# GEMM K-loop with two workgroup barriers per K-tile instead of four: leading half skips the pre-MFMA barrier, trailing half skips the post-MFMA barrier (separate loop copies per half), trailing half MF
# baseline (speedup 1.0000x reference)
.LBB0_277:
	s_lshl_b32 s10, s10, 5
	s_and_b32 s20, s10, 0x60
	s_lshl_b32 s15, s7, 13
	s_lshl_b32 s21, s20, 7
	s_add_u32 s10, s38, 0x43e00000
	s_mov_b64 s[12:13], 0x80
	s_addc_u32 s11, s39, 0
	s_add_i32 m0, s17, 0x18000
	v_lshl_add_u64 v[8:9], v[8:9], 0, s[12:13]
	s_waitcnt vmcnt(2)
	s_barrier
	global_load_lds_dwordx4 v[8:9], off
	v_lshl_add_u64 v[6:7], v[6:7], 0, s[12:13]
	s_add_i32 m0, s17, 0x1a000
	s_add_i32 s47, s17, 0x8000
	s_add_i32 s48, s17, 0xa000
	global_load_lds_dwordx4 v[6:7], off
	v_lshl_add_u64 v[2:3], v[2:3], 0, s[12:13]
	s_mov_b32 m0, s47
	s_add_u32 s18, s28, 0x100080
	global_load_lds_dwordx4 v[2:3], off
	v_lshl_add_u64 v[2:3], v[4:5], 0, s[12:13]
	s_mov_b32 m0, s48
	s_addc_u32 s19, s29, 0
	global_load_lds_dwordx4 v[2:3], off
	s_add_i32 m0, s17, 0x1c000
	v_lshl_add_u64 v[2:3], s[18:19], 0, v[134:135]
	global_load_lds_dwordx4 v[2:3], off
	v_lshl_add_u64 v[2:3], s[18:19], 0, v[136:137]
	s_add_i32 m0, s17, 0x1e000
	s_sext_i32_i8 s53, s6
	global_load_lds_dwordx4 v[2:3], off
	v_lshrrev_b32_e32 v2, 1, v0
	v_and_b32_e32 v2, 24, v2
	v_lshlrev_b32_e32 v3, 6, v146
	v_lshlrev_b32_e32 v4, 1, v2
	s_movk_i32 s6, 0x3c0
	v_and_or_b32 v3, v3, s6, v4
	v_or_b32_e32 v4, v4, v152
	v_or_b32_e32 v155, s20, v2
	v_lshlrev_b32_e32 v2, 10, v0
	v_bitop3_b32 v154, s21, v4, v151 bitop3:0xf6
	v_and_b32_e32 v2, 0x60000, v2
	v_lshlrev_b32_e32 v4, 13, v149
	v_or3_b32 v2, v147, v2, v4
	v_lshlrev_b32_e32 v5, 2, v146
	v_add_u32_e32 v138, v2, v148
	v_lshlrev_b32_e32 v2, 6, v150
	v_and_b32_e32 v5, 32, v5
	s_waitcnt vmcnt(6)
	s_cmpk_lt_u32 s14, 0x100
	v_and_b32_e32 v2, 0xe0000, v2
	v_bitop3_b32 v3, v3, s15, v5 bitop3:0xde
	s_cselect_b64 s[14:15], -1, 0
	v_or3_b32 v2, v147, v2, v4
	s_add_i32 s50, 0, 0x10000
	s_add_i32 s51, 0, 0x14000
	v_lshl_or_b32 v153, s7, 6, v146
	s_ashr_i32 s49, s44, 31
	v_mov_b32_e32 v139, v135
	v_add_u32_e32 v140, v2, v148
	v_mov_b32_e32 v141, v135
	v_mov_b64_e32 v[142:143], 0x294
	v_mov_b64_e32 v[144:145], 0x293
	v_add_u32_e32 v156, s50, v154
	v_add_u32_e32 v157, s51, v154
	v_add_u32_e32 v158, 0, v3
	s_movk_i32 s52, 0x2800
	s_branch .LBB0_280

.LBB0_287:
	s_and_b64 vcc, exec, s[14:15]
	s_cbranch_vccz .Lkt_T_0
.Lkt_L_0:
	ds_read_b128 v[160:163], v156
	ds_read_b128 v[164:167], v156 offset:1024
	ds_read_b128 v[168:171], v156 offset:2048
	ds_read_b128 v[172:175], v156 offset:3072
	ds_read_b128 v[176:179], v157
	ds_read_b128 v[180:183], v157 offset:1024
	ds_read_b128 v[184:187], v157 offset:2048
	ds_read_b128 v[188:191], v157 offset:3072
	s_add_u32 s28, s26, 0xfff00080
	s_addc_u32 s29, s27, -1
	s_cmp_eq_u32 s58, 60
	s_cselect_b32 s31, s21, s29
	s_cselect_b32 s30, s54, s28
	s_cselect_b32 s29, s19, s57
	s_cselect_b32 s28, s55, s56
	v_lshl_add_u64 v[192:193], s[26:27], 0, v[138:139]
	s_add_i32 m0, s17, 0xc000
	ds_read_b128 v[196:199], v158
	ds_read_b128 v[200:203], v158 offset:1024
	ds_read_b128 v[204:207], v158 offset:2048
	ds_read_b128 v[208:211], v158 offset:3072
	ds_read_b128 v[212:215], v158 offset:4096
	ds_read_b128 v[216:219], v158 offset:5120
	ds_read_b128 v[220:223], v158 offset:6144
	ds_read_b128 v[224:227], v158 offset:7168
	global_load_lds_dwordx4 v[192:193], off
	v_lshl_add_u64 v[192:193], s[26:27], 0, v[140:141]
	s_add_i32 m0, s17, 0xe000
	s_nop 0
	global_load_lds_dwordx4 v[192:193], off
	s_waitcnt lgkmcnt(0)
	s_setprio 1
	v_mfma_f32_16x16x32_bf16 v[126:129], v[160:163], v[196:199], v[126:129]
	v_mfma_f32_16x16x32_bf16 v[122:125], v[168:171], v[196:199], v[122:125]
	v_mfma_f32_16x16x32_bf16 v[118:121], v[160:163], v[204:207], v[118:121]
	v_mfma_f32_16x16x32_bf16 v[114:117], v[168:171], v[204:207], v[114:117]
	v_mfma_f32_16x16x32_bf16 v[102:105], v[160:163], v[212:215], v[102:105]
	v_mfma_f32_16x16x32_bf16 v[98:101], v[168:171], v[212:215], v[98:101]
	v_mfma_f32_16x16x32_bf16 v[86:89], v[160:163], v[220:223], v[86:89]
	v_mfma_f32_16x16x32_bf16 v[82:85], v[168:171], v[220:223], v[82:85]
	v_mfma_f32_16x16x32_bf16 v[126:129], v[164:167], v[200:203], v[126:129]
	v_mfma_f32_16x16x32_bf16 v[122:125], v[172:175], v[200:203], v[122:125]
	v_mfma_f32_16x16x32_bf16 v[118:121], v[164:167], v[208:211], v[118:121]
	v_mfma_f32_16x16x32_bf16 v[114:117], v[172:175], v[208:211], v[114:117]
	v_mfma_f32_16x16x32_bf16 v[102:105], v[164:167], v[216:219], v[102:105]
	v_mfma_f32_16x16x32_bf16 v[98:101], v[172:175], v[216:219], v[98:101]
	v_mfma_f32_16x16x32_bf16 v[86:89], v[164:167], v[224:227], v[86:89]
	v_mfma_f32_16x16x32_bf16 v[82:85], v[172:175], v[224:227], v[82:85]
	v_mfma_f32_16x16x32_bf16 v[110:113], v[176:179], v[196:199], v[110:113]
	v_mfma_f32_16x16x32_bf16 v[106:109], v[184:187], v[196:199], v[106:109]
	v_mfma_f32_16x16x32_bf16 v[94:97], v[176:179], v[204:207], v[94:97]
	v_mfma_f32_16x16x32_bf16 v[90:93], v[184:187], v[204:207], v[90:93]
	v_mfma_f32_16x16x32_bf16 v[78:81], v[176:179], v[212:215], v[78:81]
	v_mfma_f32_16x16x32_bf16 v[74:77], v[184:187], v[212:215], v[74:77]
	v_mfma_f32_16x16x32_bf16 v[70:73], v[176:179], v[220:223], v[70:73]
	v_mfma_f32_16x16x32_bf16 v[66:69], v[184:187], v[220:223], v[66:69]
	v_mfma_f32_16x16x32_bf16 v[110:113], v[180:183], v[200:203], v[110:113]
	v_mfma_f32_16x16x32_bf16 v[106:109], v[188:191], v[200:203], v[106:109]
	v_mfma_f32_16x16x32_bf16 v[94:97], v[180:183], v[208:211], v[94:97]
	v_mfma_f32_16x16x32_bf16 v[90:93], v[188:191], v[208:211], v[90:93]
	v_mfma_f32_16x16x32_bf16 v[78:81], v[180:183], v[216:219], v[78:81]
	v_mfma_f32_16x16x32_bf16 v[74:77], v[188:191], v[216:219], v[74:77]
	v_mfma_f32_16x16x32_bf16 v[70:73], v[180:183], v[224:227], v[70:73]
	v_mfma_f32_16x16x32_bf16 v[66:69], v[188:191], v[224:227], v[66:69]
	s_setprio 0
	s_waitcnt vmcnt(8)
	s_barrier
	s_add_i32 s59, s50, s41
	v_lshl_add_u64 v[192:193], s[28:29], 0, v[134:135]
	s_mov_b32 m0, s59
	ds_read_b128 v[196:199], v158 offset:16384
	ds_read_b128 v[200:203], v158 offset:17408
	ds_read_b128 v[204:207], v158 offset:18432
	ds_read_b128 v[208:211], v158 offset:19456
	ds_read_b128 v[212:215], v158 offset:20480
	ds_read_b128 v[216:219], v158 offset:21504
	ds_read_b128 v[220:223], v158 offset:22528
	ds_read_b128 v[224:227], v158 offset:23552
	global_load_lds_dwordx4 v[192:193], off
	s_add_i32 m0, s59, 0x2000
	s_add_u32 s60, s28, 0x100000
	v_lshl_add_u64 v[228:229], s[28:29], 0, v[136:137]
	s_addc_u32 s61, s29, 0
	s_add_i32 s59, s51, s41
	global_load_lds_dwordx4 v[228:229], off
	v_lshl_add_u64 v[230:231], s[60:61], 0, v[134:135]
	s_mov_b32 m0, s59
	v_lshl_add_u64 v[232:233], s[30:31], 0, v[132:133]
	global_load_lds_dwordx4 v[230:231], off
	v_lshl_add_u64 v[230:231], s[60:61], 0, v[136:137]
	s_add_i32 m0, s59, 0x2000
	s_nop 0
	global_load_lds_dwordx4 v[230:231], off
	v_lshl_add_u64 v[230:231], s[30:31], 0, v[130:131]
	s_mov_b32 m0, s17
	s_nop 0
	global_load_lds_dwordx4 v[230:231], off
	s_mov_b32 m0, s42
	s_nop 0
	global_load_lds_dwordx4 v[232:233], off
	s_waitcnt lgkmcnt(0)
	s_setprio 1
	v_mfma_f32_16x16x32_bf16 v[62:65], v[160:163], v[196:199], v[62:65]
	v_mfma_f32_16x16x32_bf16 v[58:61], v[168:171], v[196:199], v[58:61]
	v_mfma_f32_16x16x32_bf16 v[54:57], v[160:163], v[204:207], v[54:57]
	v_mfma_f32_16x16x32_bf16 v[50:53], v[168:171], v[204:207], v[50:53]
	v_mfma_f32_16x16x32_bf16 v[38:41], v[160:163], v[212:215], v[38:41]
	v_mfma_f32_16x16x32_bf16 v[34:37], v[168:171], v[212:215], v[34:37]
	v_mfma_f32_16x16x32_bf16 v[22:25], v[160:163], v[220:223], v[22:25]
	v_mfma_f32_16x16x32_bf16 v[18:21], v[168:171], v[220:223], v[18:21]
	v_mfma_f32_16x16x32_bf16 v[62:65], v[164:167], v[200:203], v[62:65]
	v_mfma_f32_16x16x32_bf16 v[58:61], v[172:175], v[200:203], v[58:61]
	v_mfma_f32_16x16x32_bf16 v[54:57], v[164:167], v[208:211], v[54:57]
	v_mfma_f32_16x16x32_bf16 v[50:53], v[172:175], v[208:211], v[50:53]
	v_mfma_f32_16x16x32_bf16 v[38:41], v[164:167], v[216:219], v[38:41]
	v_mfma_f32_16x16x32_bf16 v[34:37], v[172:175], v[216:219], v[34:37]
	v_mfma_f32_16x16x32_bf16 v[22:25], v[164:167], v[224:227], v[22:25]
	v_mfma_f32_16x16x32_bf16 v[18:21], v[172:175], v[224:227], v[18:21]
	v_mfma_f32_16x16x32_bf16 v[46:49], v[176:179], v[196:199], v[46:49]
	v_mfma_f32_16x16x32_bf16 v[42:45], v[184:187], v[196:199], v[42:45]
	v_mfma_f32_16x16x32_bf16 v[30:33], v[176:179], v[204:207], v[30:33]
	v_mfma_f32_16x16x32_bf16 v[26:29], v[184:187], v[204:207], v[26:29]
	v_mfma_f32_16x16x32_bf16 v[14:17], v[176:179], v[212:215], v[14:17]
	v_mfma_f32_16x16x32_bf16 v[10:13], v[184:187], v[212:215], v[10:13]
	v_mfma_f32_16x16x32_bf16 v[6:9], v[176:179], v[220:223], v[6:9]
	v_mfma_f32_16x16x32_bf16 v[2:5], v[184:187], v[220:223], v[2:5]
	v_mfma_f32_16x16x32_bf16 v[46:49], v[180:183], v[200:203], v[46:49]
	v_mfma_f32_16x16x32_bf16 v[42:45], v[188:191], v[200:203], v[42:45]
	v_mfma_f32_16x16x32_bf16 v[30:33], v[180:183], v[208:211], v[30:33]
	v_mfma_f32_16x16x32_bf16 v[26:29], v[188:191], v[208:211], v[26:29]
	v_mfma_f32_16x16x32_bf16 v[14:17], v[180:183], v[216:219], v[14:17]
	v_mfma_f32_16x16x32_bf16 v[10:13], v[188:191], v[216:219], v[10:13]
	v_mfma_f32_16x16x32_bf16 v[6:9], v[180:183], v[224:227], v[6:9]
	v_mfma_f32_16x16x32_bf16 v[2:5], v[188:191], v[224:227], v[2:5]
	s_setprio 0
	s_waitcnt vmcnt(8)
	s_barrier
	s_add_i32 s59, 0, 0x18000
	v_add_u32_e32 v159, s59, v154
	s_add_i32 s60, 0, 0x1c000
	ds_read_b128 v[160:163], v159
	ds_read_b128 v[164:167], v159 offset:1024
	ds_read_b128 v[168:171], v159 offset:2048
	ds_read_b128 v[172:175], v159 offset:3072
	v_add_u32_e32 v159, s60, v154
	ds_read_b128 v[176:179], v159
	ds_read_b128 v[180:183], v159 offset:1024
	ds_read_b128 v[184:187], v159 offset:2048
	ds_read_b128 v[188:191], v159 offset:3072
	s_add_u32 s30, s30, 0x100000
	s_addc_u32 s31, s31, 0
	s_mov_b32 m0, s43
	v_lshl_add_u64 v[234:235], s[30:31], 0, v[130:131]
	ds_read_b128 v[196:199], v158 offset:32768
	ds_read_b128 v[200:203], v158 offset:33792
	ds_read_b128 v[204:207], v158 offset:34816
	ds_read_b128 v[208:211], v158 offset:35840
	ds_read_b128 v[212:215], v158 offset:36864
	ds_read_b128 v[216:219], v158 offset:37888
	ds_read_b128 v[220:223], v158 offset:38912
	ds_read_b128 v[224:227], v158 offset:39936
	global_load_lds_dwordx4 v[234:235], off
	v_lshl_add_u64 v[234:235], s[30:31], 0, v[132:133]
	s_mov_b32 m0, s45
	s_nop 0
	global_load_lds_dwordx4 v[234:235], off
	s_waitcnt lgkmcnt(0)
	s_setprio 1
	v_mfma_f32_16x16x32_bf16 v[126:129], v[160:163], v[196:199], v[126:129]
	v_mfma_f32_16x16x32_bf16 v[122:125], v[168:171], v[196:199], v[122:125]
	v_mfma_f32_16x16x32_bf16 v[118:121], v[160:163], v[204:207], v[118:121]
	v_mfma_f32_16x16x32_bf16 v[114:117], v[168:171], v[204:207], v[114:117]
	v_mfma_f32_16x16x32_bf16 v[102:105], v[160:163], v[212:215], v[102:105]
	v_mfma_f32_16x16x32_bf16 v[98:101], v[168:171], v[212:215], v[98:101]
	v_mfma_f32_16x16x32_bf16 v[86:89], v[160:163], v[220:223], v[86:89]
	v_mfma_f32_16x16x32_bf16 v[82:85], v[168:171], v[220:223], v[82:85]
	v_mfma_f32_16x16x32_bf16 v[126:129], v[164:167], v[200:203], v[126:129]
	v_mfma_f32_16x16x32_bf16 v[122:125], v[172:175], v[200:203], v[122:125]
	v_mfma_f32_16x16x32_bf16 v[118:121], v[164:167], v[208:211], v[118:121]
	v_mfma_f32_16x16x32_bf16 v[114:117], v[172:175], v[208:211], v[114:117]
	v_mfma_f32_16x16x32_bf16 v[102:105], v[164:167], v[216:219], v[102:105]
	v_mfma_f32_16x16x32_bf16 v[98:101], v[172:175], v[216:219], v[98:101]
	v_mfma_f32_16x16x32_bf16 v[86:89], v[164:167], v[224:227], v[86:89]
	v_mfma_f32_16x16x32_bf16 v[82:85], v[172:175], v[224:227], v[82:85]
	v_mfma_f32_16x16x32_bf16 v[110:113], v[176:179], v[196:199], v[110:113]
	v_mfma_f32_16x16x32_bf16 v[106:109], v[184:187], v[196:199], v[106:109]
	v_mfma_f32_16x16x32_bf16 v[94:97], v[176:179], v[204:207], v[94:97]
	v_mfma_f32_16x16x32_bf16 v[90:93], v[184:187], v[204:207], v[90:93]
	v_mfma_f32_16x16x32_bf16 v[78:81], v[176:179], v[212:215], v[78:81]
	v_mfma_f32_16x16x32_bf16 v[74:77], v[184:187], v[212:215], v[74:77]
	v_mfma_f32_16x16x32_bf16 v[70:73], v[176:179], v[220:223], v[70:73]
	v_mfma_f32_16x16x32_bf16 v[66:69], v[184:187], v[220:223], v[66:69]
	v_mfma_f32_16x16x32_bf16 v[110:113], v[180:183], v[200:203], v[110:113]
	v_mfma_f32_16x16x32_bf16 v[106:109], v[188:191], v[200:203], v[106:109]
	v_mfma_f32_16x16x32_bf16 v[94:97], v[180:183], v[208:211], v[94:97]
	v_mfma_f32_16x16x32_bf16 v[90:93], v[188:191], v[208:211], v[90:93]
	v_mfma_f32_16x16x32_bf16 v[78:81], v[180:183], v[216:219], v[78:81]
	v_mfma_f32_16x16x32_bf16 v[74:77], v[188:191], v[216:219], v[74:77]
	v_mfma_f32_16x16x32_bf16 v[70:73], v[180:183], v[224:227], v[70:73]
	v_mfma_f32_16x16x32_bf16 v[66:69], v[188:191], v[224:227], v[66:69]
	s_setprio 0
	s_waitcnt vmcnt(8)
	s_barrier
	s_add_i32 s30, s59, s41
	v_lshl_add_u64 v[192:193], v[192:193], 0, s[12:13]
	s_mov_b32 m0, s30
	ds_read_b128 v[196:199], v158 offset:49152
	ds_read_b128 v[200:203], v158 offset:50176
	ds_read_b128 v[204:207], v158 offset:51200
	ds_read_b128 v[208:211], v158 offset:52224
	ds_read_b128 v[212:215], v158 offset:53248
	ds_read_b128 v[216:219], v158 offset:54272
	ds_read_b128 v[220:223], v158 offset:55296
	ds_read_b128 v[224:227], v158 offset:56320
	global_load_lds_dwordx4 v[192:193], off
	s_add_i32 m0, s30, 0x2000
	s_add_u32 s28, s28, 0x100080
	v_lshl_add_u64 v[192:193], v[228:229], 0, s[12:13]
	s_addc_u32 s29, s29, 0
	s_add_i32 s30, s60, s41
	global_load_lds_dwordx4 v[192:193], off
	v_lshl_add_u64 v[192:193], s[28:29], 0, v[134:135]
	s_mov_b32 m0, s30
	s_nop 0
	global_load_lds_dwordx4 v[192:193], off
	v_lshl_add_u64 v[192:193], s[28:29], 0, v[136:137]
	s_add_i32 m0, s30, 0x2000
	s_nop 0
	global_load_lds_dwordx4 v[192:193], off
	v_lshl_add_u64 v[192:193], v[230:231], 0, s[12:13]
	s_mov_b32 m0, s47
	s_nop 0
	global_load_lds_dwordx4 v[192:193], off
	v_lshl_add_u64 v[192:193], v[232:233], 0, s[12:13]
	s_mov_b32 m0, s48
	s_nop 0
	global_load_lds_dwordx4 v[192:193], off
	s_waitcnt lgkmcnt(0)
	s_setprio 1
	v_mfma_f32_16x16x32_bf16 v[62:65], v[160:163], v[196:199], v[62:65]
	v_mfma_f32_16x16x32_bf16 v[58:61], v[168:171], v[196:199], v[58:61]
	v_mfma_f32_16x16x32_bf16 v[54:57], v[160:163], v[204:207], v[54:57]
	v_mfma_f32_16x16x32_bf16 v[50:53], v[168:171], v[204:207], v[50:53]
	v_mfma_f32_16x16x32_bf16 v[38:41], v[160:163], v[212:215], v[38:41]
	v_mfma_f32_16x16x32_bf16 v[34:37], v[168:171], v[212:215], v[34:37]
	v_mfma_f32_16x16x32_bf16 v[22:25], v[160:163], v[220:223], v[22:25]
	v_mfma_f32_16x16x32_bf16 v[18:21], v[168:171], v[220:223], v[18:21]
	v_mfma_f32_16x16x32_bf16 v[62:65], v[164:167], v[200:203], v[62:65]
	v_mfma_f32_16x16x32_bf16 v[58:61], v[172:175], v[200:203], v[58:61]
	v_mfma_f32_16x16x32_bf16 v[54:57], v[164:167], v[208:211], v[54:57]
	v_mfma_f32_16x16x32_bf16 v[50:53], v[172:175], v[208:211], v[50:53]
	v_mfma_f32_16x16x32_bf16 v[38:41], v[164:167], v[216:219], v[38:41]
	v_mfma_f32_16x16x32_bf16 v[34:37], v[172:175], v[216:219], v[34:37]
	v_mfma_f32_16x16x32_bf16 v[22:25], v[164:167], v[224:227], v[22:25]
	v_mfma_f32_16x16x32_bf16 v[18:21], v[172:175], v[224:227], v[18:21]
	v_mfma_f32_16x16x32_bf16 v[46:49], v[176:179], v[196:199], v[46:49]
	v_mfma_f32_16x16x32_bf16 v[42:45], v[184:187], v[196:199], v[42:45]
	v_mfma_f32_16x16x32_bf16 v[30:33], v[176:179], v[204:207], v[30:33]
	v_mfma_f32_16x16x32_bf16 v[26:29], v[184:187], v[204:207], v[26:29]
	v_mfma_f32_16x16x32_bf16 v[14:17], v[176:179], v[212:215], v[14:17]
	v_mfma_f32_16x16x32_bf16 v[10:13], v[184:187], v[212:215], v[10:13]
	v_mfma_f32_16x16x32_bf16 v[6:9], v[176:179], v[220:223], v[6:9]
	v_mfma_f32_16x16x32_bf16 v[2:5], v[184:187], v[220:223], v[2:5]
	v_mfma_f32_16x16x32_bf16 v[46:49], v[180:183], v[200:203], v[46:49]
	v_mfma_f32_16x16x32_bf16 v[42:45], v[188:191], v[200:203], v[42:45]
	v_mfma_f32_16x16x32_bf16 v[30:33], v[180:183], v[208:211], v[30:33]
	v_mfma_f32_16x16x32_bf16 v[26:29], v[188:191], v[208:211], v[26:29]
	v_mfma_f32_16x16x32_bf16 v[14:17], v[180:183], v[216:219], v[14:17]
	v_mfma_f32_16x16x32_bf16 v[10:13], v[188:191], v[216:219], v[10:13]
	v_mfma_f32_16x16x32_bf16 v[6:9], v[180:183], v[224:227], v[6:9]
	v_mfma_f32_16x16x32_bf16 v[2:5], v[188:191], v[224:227], v[2:5]
	s_setprio 0
	s_waitcnt vmcnt(8)
	s_barrier
	s_add_i32 s58, s58, 2
	s_add_u32 s26, s26, 0x100
	s_addc_u32 s27, s27, 0
	s_add_u32 s56, s56, 0x100
	s_addc_u32 s57, s57, 0
	s_cmp_gt_u32 s58, 61
	s_cbranch_scc0 .Lkt_L_0
	s_branch .Lkt_exit_0
.Lkt_T_0:
	ds_read_b128 v[160:163], v156
	ds_read_b128 v[164:167], v156 offset:1024
	ds_read_b128 v[168:171], v156 offset:2048
	ds_read_b128 v[172:175], v156 offset:3072
	ds_read_b128 v[176:179], v157
	ds_read_b128 v[180:183], v157 offset:1024
	ds_read_b128 v[184:187], v157 offset:2048
	ds_read_b128 v[188:191], v157 offset:3072
	s_add_u32 s28, s26, 0xfff00080
	s_addc_u32 s29, s27, -1
	s_cmp_eq_u32 s58, 60
	s_cselect_b32 s31, s21, s29
	s_cselect_b32 s30, s54, s28
	s_cselect_b32 s29, s19, s57
	s_cselect_b32 s28, s55, s56
	v_lshl_add_u64 v[192:193], s[26:27], 0, v[138:139]
	s_add_i32 m0, s17, 0xc000
	ds_read_b128 v[196:199], v158
	ds_read_b128 v[200:203], v158 offset:1024
	ds_read_b128 v[204:207], v158 offset:2048
	ds_read_b128 v[208:211], v158 offset:3072
	ds_read_b128 v[212:215], v158 offset:4096
	ds_read_b128 v[216:219], v158 offset:5120
	ds_read_b128 v[220:223], v158 offset:6144
	ds_read_b128 v[224:227], v158 offset:7168
	global_load_lds_dwordx4 v[192:193], off
	v_lshl_add_u64 v[192:193], s[26:27], 0, v[140:141]
	s_add_i32 m0, s17, 0xe000
	s_nop 0
	global_load_lds_dwordx4 v[192:193], off
	s_waitcnt vmcnt(8)
	s_waitcnt lgkmcnt(0)
	s_barrier
	s_setprio 2
	v_mfma_f32_16x16x32_bf16 v[126:129], v[160:163], v[196:199], v[126:129]
	v_mfma_f32_16x16x32_bf16 v[122:125], v[168:171], v[196:199], v[122:125]
	v_mfma_f32_16x16x32_bf16 v[118:121], v[160:163], v[204:207], v[118:121]
	v_mfma_f32_16x16x32_bf16 v[114:117], v[168:171], v[204:207], v[114:117]
	v_mfma_f32_16x16x32_bf16 v[102:105], v[160:163], v[212:215], v[102:105]
	v_mfma_f32_16x16x32_bf16 v[98:101], v[168:171], v[212:215], v[98:101]
	v_mfma_f32_16x16x32_bf16 v[86:89], v[160:163], v[220:223], v[86:89]
	v_mfma_f32_16x16x32_bf16 v[82:85], v[168:171], v[220:223], v[82:85]
	v_mfma_f32_16x16x32_bf16 v[126:129], v[164:167], v[200:203], v[126:129]
	v_mfma_f32_16x16x32_bf16 v[122:125], v[172:175], v[200:203], v[122:125]
	v_mfma_f32_16x16x32_bf16 v[118:121], v[164:167], v[208:211], v[118:121]
	v_mfma_f32_16x16x32_bf16 v[114:117], v[172:175], v[208:211], v[114:117]
	v_mfma_f32_16x16x32_bf16 v[102:105], v[164:167], v[216:219], v[102:105]
	v_mfma_f32_16x16x32_bf16 v[98:101], v[172:175], v[216:219], v[98:101]
	v_mfma_f32_16x16x32_bf16 v[86:89], v[164:167], v[224:227], v[86:89]
	v_mfma_f32_16x16x32_bf16 v[82:85], v[172:175], v[224:227], v[82:85]
	v_mfma_f32_16x16x32_bf16 v[110:113], v[176:179], v[196:199], v[110:113]
	v_mfma_f32_16x16x32_bf16 v[106:109], v[184:187], v[196:199], v[106:109]
	v_mfma_f32_16x16x32_bf16 v[94:97], v[176:179], v[204:207], v[94:97]
	v_mfma_f32_16x16x32_bf16 v[90:93], v[184:187], v[204:207], v[90:93]
	v_mfma_f32_16x16x32_bf16 v[78:81], v[176:179], v[212:215], v[78:81]
	v_mfma_f32_16x16x32_bf16 v[74:77], v[184:187], v[212:215], v[74:77]
	v_mfma_f32_16x16x32_bf16 v[70:73], v[176:179], v[220:223], v[70:73]
	v_mfma_f32_16x16x32_bf16 v[66:69], v[184:187], v[220:223], v[66:69]
	v_mfma_f32_16x16x32_bf16 v[110:113], v[180:183], v[200:203], v[110:113]
	v_mfma_f32_16x16x32_bf16 v[106:109], v[188:191], v[200:203], v[106:109]
	v_mfma_f32_16x16x32_bf16 v[94:97], v[180:183], v[208:211], v[94:97]
	v_mfma_f32_16x16x32_bf16 v[90:93], v[188:191], v[208:211], v[90:93]
	v_mfma_f32_16x16x32_bf16 v[78:81], v[180:183], v[216:219], v[78:81]
	v_mfma_f32_16x16x32_bf16 v[74:77], v[188:191], v[216:219], v[74:77]
	v_mfma_f32_16x16x32_bf16 v[70:73], v[180:183], v[224:227], v[70:73]
	v_mfma_f32_16x16x32_bf16 v[66:69], v[188:191], v[224:227], v[66:69]
	s_setprio 0
	s_add_i32 s59, s50, s41
	v_lshl_add_u64 v[192:193], s[28:29], 0, v[134:135]
	s_mov_b32 m0, s59
	ds_read_b128 v[196:199], v158 offset:16384
	ds_read_b128 v[200:203], v158 offset:17408
	ds_read_b128 v[204:207], v158 offset:18432
	ds_read_b128 v[208:211], v158 offset:19456
	ds_read_b128 v[212:215], v158 offset:20480
	ds_read_b128 v[216:219], v158 offset:21504
	ds_read_b128 v[220:223], v158 offset:22528
	ds_read_b128 v[224:227], v158 offset:23552
	global_load_lds_dwordx4 v[192:193], off
	s_add_i32 m0, s59, 0x2000
	s_add_u32 s60, s28, 0x100000
	v_lshl_add_u64 v[228:229], s[28:29], 0, v[136:137]
	s_addc_u32 s61, s29, 0
	s_add_i32 s59, s51, s41
	global_load_lds_dwordx4 v[228:229], off
	v_lshl_add_u64 v[230:231], s[60:61], 0, v[134:135]
	s_mov_b32 m0, s59
	v_lshl_add_u64 v[232:233], s[30:31], 0, v[132:133]
	global_load_lds_dwordx4 v[230:231], off
	v_lshl_add_u64 v[230:231], s[60:61], 0, v[136:137]
	s_add_i32 m0, s59, 0x2000
	s_nop 0
	global_load_lds_dwordx4 v[230:231], off
	v_lshl_add_u64 v[230:231], s[30:31], 0, v[130:131]
	s_mov_b32 m0, s17
	s_nop 0
	global_load_lds_dwordx4 v[230:231], off
	s_mov_b32 m0, s42
	s_nop 0
	global_load_lds_dwordx4 v[232:233], off
	s_waitcnt vmcnt(8)
	s_waitcnt lgkmcnt(0)
	s_barrier
	s_setprio 2
	v_mfma_f32_16x16x32_bf16 v[62:65], v[160:163], v[196:199], v[62:65]
	v_mfma_f32_16x16x32_bf16 v[58:61], v[168:171], v[196:199], v[58:61]
	v_mfma_f32_16x16x32_bf16 v[54:57], v[160:163], v[204:207], v[54:57]
	v_mfma_f32_16x16x32_bf16 v[50:53], v[168:171], v[204:207], v[50:53]
	v_mfma_f32_16x16x32_bf16 v[38:41], v[160:163], v[212:215], v[38:41]
	v_mfma_f32_16x16x32_bf16 v[34:37], v[168:171], v[212:215], v[34:37]
	v_mfma_f32_16x16x32_bf16 v[22:25], v[160:163], v[220:223], v[22:25]
	v_mfma_f32_16x16x32_bf16 v[18:21], v[168:171], v[220:223], v[18:21]
	v_mfma_f32_16x16x32_bf16 v[62:65], v[164:167], v[200:203], v[62:65]
	v_mfma_f32_16x16x32_bf16 v[58:61], v[172:175], v[200:203], v[58:61]
	v_mfma_f32_16x16x32_bf16 v[54:57], v[164:167], v[208:211], v[54:57]
	v_mfma_f32_16x16x32_bf16 v[50:53], v[172:175], v[208:211], v[50:53]
	v_mfma_f32_16x16x32_bf16 v[38:41], v[164:167], v[216:219], v[38:41]
	v_mfma_f32_16x16x32_bf16 v[34:37], v[172:175], v[216:219], v[34:37]
	v_mfma_f32_16x16x32_bf16 v[22:25], v[164:167], v[224:227], v[22:25]
	v_mfma_f32_16x16x32_bf16 v[18:21], v[172:175], v[224:227], v[18:21]
	v_mfma_f32_16x16x32_bf16 v[46:49], v[176:179], v[196:199], v[46:49]
	v_mfma_f32_16x16x32_bf16 v[42:45], v[184:187], v[196:199], v[42:45]
	v_mfma_f32_16x16x32_bf16 v[30:33], v[176:179], v[204:207], v[30:33]
	v_mfma_f32_16x16x32_bf16 v[26:29], v[184:187], v[204:207], v[26:29]
	v_mfma_f32_16x16x32_bf16 v[14:17], v[176:179], v[212:215], v[14:17]
	v_mfma_f32_16x16x32_bf16 v[10:13], v[184:187], v[212:215], v[10:13]
	v_mfma_f32_16x16x32_bf16 v[6:9], v[176:179], v[220:223], v[6:9]
	v_mfma_f32_16x16x32_bf16 v[2:5], v[184:187], v[220:223], v[2:5]
	v_mfma_f32_16x16x32_bf16 v[46:49], v[180:183], v[200:203], v[46:49]
	v_mfma_f32_16x16x32_bf16 v[42:45], v[188:191], v[200:203], v[42:45]
	v_mfma_f32_16x16x32_bf16 v[30:33], v[180:183], v[208:211], v[30:33]
	v_mfma_f32_16x16x32_bf16 v[26:29], v[188:191], v[208:211], v[26:29]
	v_mfma_f32_16x16x32_bf16 v[14:17], v[180:183], v[216:219], v[14:17]
	v_mfma_f32_16x16x32_bf16 v[10:13], v[188:191], v[216:219], v[10:13]
	v_mfma_f32_16x16x32_bf16 v[6:9], v[180:183], v[224:227], v[6:9]
	v_mfma_f32_16x16x32_bf16 v[2:5], v[188:191], v[224:227], v[2:5]
	s_setprio 0
	s_add_i32 s59, 0, 0x18000
	v_add_u32_e32 v159, s59, v154
	s_add_i32 s60, 0, 0x1c000
	ds_read_b128 v[160:163], v159
	ds_read_b128 v[164:167], v159 offset:1024
	ds_read_b128 v[168:171], v159 offset:2048
	ds_read_b128 v[172:175], v159 offset:3072
	v_add_u32_e32 v159, s60, v154
	ds_read_b128 v[176:179], v159
	ds_read_b128 v[180:183], v159 offset:1024
	ds_read_b128 v[184:187], v159 offset:2048
	ds_read_b128 v[188:191], v159 offset:3072
	s_add_u32 s30, s30, 0x100000
	s_addc_u32 s31, s31, 0
	s_mov_b32 m0, s43
	v_lshl_add_u64 v[234:235], s[30:31], 0, v[130:131]
	ds_read_b128 v[196:199], v158 offset:32768
	ds_read_b128 v[200:203], v158 offset:33792
	ds_read_b128 v[204:207], v158 offset:34816
	ds_read_b128 v[208:211], v158 offset:35840
	ds_read_b128 v[212:215], v158 offset:36864
	ds_read_b128 v[216:219], v158 offset:37888
	ds_read_b128 v[220:223], v158 offset:38912
	ds_read_b128 v[224:227], v158 offset:39936
	global_load_lds_dwordx4 v[234:235], off
	v_lshl_add_u64 v[234:235], s[30:31], 0, v[132:133]
	s_mov_b32 m0, s45
	s_nop 0
	global_load_lds_dwordx4 v[234:235], off
	s_waitcnt vmcnt(8)
	s_waitcnt lgkmcnt(0)
	s_barrier
	s_setprio 2
	v_mfma_f32_16x16x32_bf16 v[126:129], v[160:163], v[196:199], v[126:129]
	v_mfma_f32_16x16x32_bf16 v[122:125], v[168:171], v[196:199], v[122:125]
	v_mfma_f32_16x16x32_bf16 v[118:121], v[160:163], v[204:207], v[118:121]
	v_mfma_f32_16x16x32_bf16 v[114:117], v[168:171], v[204:207], v[114:117]
	v_mfma_f32_16x16x32_bf16 v[102:105], v[160:163], v[212:215], v[102:105]
	v_mfma_f32_16x16x32_bf16 v[98:101], v[168:171], v[212:215], v[98:101]
	v_mfma_f32_16x16x32_bf16 v[86:89], v[160:163], v[220:223], v[86:89]
	v_mfma_f32_16x16x32_bf16 v[82:85], v[168:171], v[220:223], v[82:85]
	v_mfma_f32_16x16x32_bf16 v[126:129], v[164:167], v[200:203], v[126:129]
	v_mfma_f32_16x16x32_bf16 v[122:125], v[172:175], v[200:203], v[122:125]
	v_mfma_f32_16x16x32_bf16 v[118:121], v[164:167], v[208:211], v[118:121]
	v_mfma_f32_16x16x32_bf16 v[114:117], v[172:175], v[208:211], v[114:117]
	v_mfma_f32_16x16x32_bf16 v[102:105], v[164:167], v[216:219], v[102:105]
	v_mfma_f32_16x16x32_bf16 v[98:101], v[172:175], v[216:219], v[98:101]
	v_mfma_f32_16x16x32_bf16 v[86:89], v[164:167], v[224:227], v[86:89]
	v_mfma_f32_16x16x32_bf16 v[82:85], v[172:175], v[224:227], v[82:85]
	v_mfma_f32_16x16x32_bf16 v[110:113], v[176:179], v[196:199], v[110:113]
	v_mfma_f32_16x16x32_bf16 v[106:109], v[184:187], v[196:199], v[106:109]
	v_mfma_f32_16x16x32_bf16 v[94:97], v[176:179], v[204:207], v[94:97]
	v_mfma_f32_16x16x32_bf16 v[90:93], v[184:187], v[204:207], v[90:93]
	v_mfma_f32_16x16x32_bf16 v[78:81], v[176:179], v[212:215], v[78:81]
	v_mfma_f32_16x16x32_bf16 v[74:77], v[184:187], v[212:215], v[74:77]
	v_mfma_f32_16x16x32_bf16 v[70:73], v[176:179], v[220:223], v[70:73]
	v_mfma_f32_16x16x32_bf16 v[66:69], v[184:187], v[220:223], v[66:69]
	v_mfma_f32_16x16x32_bf16 v[110:113], v[180:183], v[200:203], v[110:113]
	v_mfma_f32_16x16x32_bf16 v[106:109], v[188:191], v[200:203], v[106:109]
	v_mfma_f32_16x16x32_bf16 v[94:97], v[180:183], v[208:211], v[94:97]
	v_mfma_f32_16x16x32_bf16 v[90:93], v[188:191], v[208:211], v[90:93]
	v_mfma_f32_16x16x32_bf16 v[78:81], v[180:183], v[216:219], v[78:81]
	v_mfma_f32_16x16x32_bf16 v[74:77], v[188:191], v[216:219], v[74:77]
	v_mfma_f32_16x16x32_bf16 v[70:73], v[180:183], v[224:227], v[70:73]
	v_mfma_f32_16x16x32_bf16 v[66:69], v[188:191], v[224:227], v[66:69]
	s_setprio 0
	s_add_i32 s30, s59, s41
	v_lshl_add_u64 v[192:193], v[192:193], 0, s[12:13]
	s_mov_b32 m0, s30
	ds_read_b128 v[196:199], v158 offset:49152
	ds_read_b128 v[200:203], v158 offset:50176
	ds_read_b128 v[204:207], v158 offset:51200
	ds_read_b128 v[208:211], v158 offset:52224
	ds_read_b128 v[212:215], v158 offset:53248
	ds_read_b128 v[216:219], v158 offset:54272
	ds_read_b128 v[220:223], v158 offset:55296
	ds_read_b128 v[224:227], v158 offset:56320
	global_load_lds_dwordx4 v[192:193], off
	s_add_i32 m0, s30, 0x2000
	s_add_u32 s28, s28, 0x100080
	v_lshl_add_u64 v[192:193], v[228:229], 0, s[12:13]
	s_addc_u32 s29, s29, 0
	s_add_i32 s30, s60, s41
	global_load_lds_dwordx4 v[192:193], off
	v_lshl_add_u64 v[192:193], s[28:29], 0, v[134:135]
	s_mov_b32 m0, s30
	s_nop 0
	global_load_lds_dwordx4 v[192:193], off
	v_lshl_add_u64 v[192:193], s[28:29], 0, v[136:137]
	s_add_i32 m0, s30, 0x2000
	s_nop 0
	global_load_lds_dwordx4 v[192:193], off
	v_lshl_add_u64 v[192:193], v[230:231], 0, s[12:13]
	s_mov_b32 m0, s47
	s_nop 0
	global_load_lds_dwordx4 v[192:193], off
	v_lshl_add_u64 v[192:193], v[232:233], 0, s[12:13]
	s_mov_b32 m0, s48
	s_nop 0
	global_load_lds_dwordx4 v[192:193], off
	s_waitcnt vmcnt(8)
	s_waitcnt lgkmcnt(0)
	s_barrier
	s_setprio 2
	v_mfma_f32_16x16x32_bf16 v[62:65], v[160:163], v[196:199], v[62:65]
	v_mfma_f32_16x16x32_bf16 v[58:61], v[168:171], v[196:199], v[58:61]
	v_mfma_f32_16x16x32_bf16 v[54:57], v[160:163], v[204:207], v[54:57]
	v_mfma_f32_16x16x32_bf16 v[50:53], v[168:171], v[204:207], v[50:53]
	v_mfma_f32_16x16x32_bf16 v[38:41], v[160:163], v[212:215], v[38:41]
	v_mfma_f32_16x16x32_bf16 v[34:37], v[168:171], v[212:215], v[34:37]
	v_mfma_f32_16x16x32_bf16 v[22:25], v[160:163], v[220:223], v[22:25]
	v_mfma_f32_16x16x32_bf16 v[18:21], v[168:171], v[220:223], v[18:21]
	v_mfma_f32_16x16x32_bf16 v[62:65], v[164:167], v[200:203], v[62:65]
	v_mfma_f32_16x16x32_bf16 v[58:61], v[172:175], v[200:203], v[58:61]
	v_mfma_f32_16x16x32_bf16 v[54:57], v[164:167], v[208:211], v[54:57]
	v_mfma_f32_16x16x32_bf16 v[50:53], v[172:175], v[208:211], v[50:53]
	v_mfma_f32_16x16x32_bf16 v[38:41], v[164:167], v[216:219], v[38:41]
	v_mfma_f32_16x16x32_bf16 v[34:37], v[172:175], v[216:219], v[34:37]
	v_mfma_f32_16x16x32_bf16 v[22:25], v[164:167], v[224:227], v[22:25]
	v_mfma_f32_16x16x32_bf16 v[18:21], v[172:175], v[224:227], v[18:21]
	v_mfma_f32_16x16x32_bf16 v[46:49], v[176:179], v[196:199], v[46:49]
	v_mfma_f32_16x16x32_bf16 v[42:45], v[184:187], v[196:199], v[42:45]
	v_mfma_f32_16x16x32_bf16 v[30:33], v[176:179], v[204:207], v[30:33]
	v_mfma_f32_16x16x32_bf16 v[26:29], v[184:187], v[204:207], v[26:29]
	v_mfma_f32_16x16x32_bf16 v[14:17], v[176:179], v[212:215], v[14:17]
	v_mfma_f32_16x16x32_bf16 v[10:13], v[184:187], v[212:215], v[10:13]
	v_mfma_f32_16x16x32_bf16 v[6:9], v[176:179], v[220:223], v[6:9]
	v_mfma_f32_16x16x32_bf16 v[2:5], v[184:187], v[220:223], v[2:5]
	v_mfma_f32_16x16x32_bf16 v[46:49], v[180:183], v[200:203], v[46:49]
	v_mfma_f32_16x16x32_bf16 v[42:45], v[188:191], v[200:203], v[42:45]
	v_mfma_f32_16x16x32_bf16 v[30:33], v[180:183], v[208:211], v[30:33]
	v_mfma_f32_16x16x32_bf16 v[26:29], v[188:191], v[208:211], v[26:29]
	v_mfma_f32_16x16x32_bf16 v[14:17], v[180:183], v[216:219], v[14:17]
	v_mfma_f32_16x16x32_bf16 v[10:13], v[188:191], v[216:219], v[10:13]
	v_mfma_f32_16x16x32_bf16 v[6:9], v[180:183], v[224:227], v[6:9]
	v_mfma_f32_16x16x32_bf16 v[2:5], v[188:191], v[224:227], v[2:5]
	s_setprio 0
	s_add_i32 s58, s58, 2
	s_add_u32 s26, s26, 0x100
	s_addc_u32 s27, s27, 0
	s_add_u32 s56, s56, 0x100
	s_addc_u32 s57, s57, 0
	s_cmp_gt_u32 s58, 61
	s_cbranch_scc0 .Lkt_T_0
	s_nop 7

.LBB0_290:
	v_lshl_add_u32 v159, s16, 8, v153
	v_lshl_or_b32 v160, s53, 8, v155
	v_ashrrev_i32_e32 v161, 31, v160
	v_mov_b64_e32 v[162:163], s[10:11]
	v_cvt_pk_bf16_f32 v70, v70, v71
	v_cvt_pk_bf16_f32 v71, v72, v73
	v_cvt_pk_bf16_f32 v72, v66, v67
	v_add_u32_e32 v66, 0x80, v159
	v_mad_i64_i32 v[164:165], s[26:27], v159, s52, v[162:163]
	v_lshlrev_b64 v[160:161], 1, v[160:161]
	v_cvt_pk_bf16_f32 v110, v110, v111
	v_cvt_pk_bf16_f32 v111, v112, v113
	v_cvt_pk_bf16_f32 v112, v106, v107
	v_or_b32_e32 v106, 16, v159
	v_mad_i64_i32 v[66:67], s[26:27], v66, s52, v[162:163]
	v_cvt_pk_bf16_f32 v46, v46, v47
	v_cvt_pk_bf16_f32 v47, v48, v49
	v_cvt_pk_bf16_f32 v48, v42, v43
	v_add_u32_e32 v42, 0x90, v159
	v_lshl_add_u64 v[164:165], v[164:165], 0, v[160:161]
	v_cvt_pk_bf16_f32 v113, v108, v109
	v_mad_i64_i32 v[106:107], s[26:27], v106, s52, v[162:163]
	v_cvt_pk_bf16_f32 v94, v94, v95
	v_cvt_pk_bf16_f32 v95, v96, v97
	v_cvt_pk_bf16_f32 v96, v90, v91
	v_or_b32_e32 v90, 32, v159
	v_lshl_add_u64 v[66:67], v[66:67], 0, v[160:161]
	v_cvt_pk_bf16_f32 v49, v44, v45
	v_mad_i64_i32 v[42:43], s[26:27], v42, s52, v[162:163]
	v_cvt_pk_bf16_f32 v30, v30, v31
	v_cvt_pk_bf16_f32 v31, v32, v33
	v_cvt_pk_bf16_f32 v32, v26, v27
	v_add_u32_e32 v26, 0xa0, v159
	global_store_dwordx4 v[164:165], v[110:113], off offset:256
	v_cvt_pk_bf16_f32 v97, v92, v93
	v_mad_i64_i32 v[90:91], s[26:27], v90, s52, v[162:163]
	v_lshl_add_u64 v[110:111], v[106:107], 0, v[160:161]
	v_cvt_pk_bf16_f32 v78, v78, v79
	v_cvt_pk_bf16_f32 v79, v80, v81
	v_cvt_pk_bf16_f32 v80, v74, v75
	v_or_b32_e32 v74, 48, v159
	global_store_dwordx4 v[66:67], v[46:49], off offset:256
	v_cvt_pk_bf16_f32 v33, v28, v29
	v_mad_i64_i32 v[26:27], s[26:27], v26, s52, v[162:163]
	v_lshl_add_u64 v[46:47], v[42:43], 0, v[160:161]
	v_cvt_pk_bf16_f32 v14, v14, v15
	v_cvt_pk_bf16_f32 v15, v16, v17
	v_cvt_pk_bf16_f32 v16, v10, v11
	v_add_u32_e32 v10, 0xb0, v159
	global_store_dwordx4 v[110:111], v[94:97], off offset:256
	v_cvt_pk_bf16_f32 v81, v76, v77
	v_mad_i64_i32 v[74:75], s[26:27], v74, s52, v[162:163]
	v_lshl_add_u64 v[94:95], v[90:91], 0, v[160:161]
	global_store_dwordx4 v[46:47], v[30:33], off offset:256
	v_cvt_pk_bf16_f32 v17, v12, v13
	v_mad_i64_i32 v[10:11], s[26:27], v10, s52, v[162:163]
	v_lshl_add_u64 v[30:31], v[26:27], 0, v[160:161]
	v_cvt_pk_bf16_f32 v126, v126, v127
	v_cvt_pk_bf16_f32 v127, v128, v129
	v_cvt_pk_bf16_f32 v128, v122, v123
	v_cvt_pk_bf16_f32 v129, v124, v125
	v_cvt_pk_bf16_f32 v106, v118, v119
	v_cvt_pk_bf16_f32 v107, v120, v121
	v_cvt_pk_bf16_f32 v108, v114, v115
	v_cvt_pk_bf16_f32 v109, v116, v117
	v_cvt_pk_bf16_f32 v90, v102, v103
	v_cvt_pk_bf16_f32 v91, v104, v105
	v_cvt_pk_bf16_f32 v92, v98, v99
	v_cvt_pk_bf16_f32 v93, v100, v101
	global_store_dwordx4 v[94:95], v[78:81], off offset:256
	v_cvt_pk_bf16_f32 v76, v82, v83
	v_cvt_pk_bf16_f32 v77, v84, v85
	v_lshl_add_u64 v[78:79], v[74:75], 0, v[160:161]
	v_cvt_pk_bf16_f32 v74, v86, v87
	v_cvt_pk_bf16_f32 v75, v88, v89
	v_cvt_pk_bf16_f32 v73, v68, v69
	v_cvt_pk_bf16_f32 v62, v62, v63
	v_cvt_pk_bf16_f32 v63, v64, v65
	v_cvt_pk_bf16_f32 v64, v58, v59
	v_cvt_pk_bf16_f32 v65, v60, v61
	v_cvt_pk_bf16_f32 v42, v54, v55
	v_cvt_pk_bf16_f32 v43, v56, v57
	v_cvt_pk_bf16_f32 v44, v50, v51
	v_cvt_pk_bf16_f32 v45, v52, v53
	v_cvt_pk_bf16_f32 v26, v38, v39
	v_cvt_pk_bf16_f32 v27, v40, v41
	v_cvt_pk_bf16_f32 v28, v34, v35
	v_cvt_pk_bf16_f32 v29, v36, v37
	global_store_dwordx4 v[30:31], v[14:17], off offset:256
	v_cvt_pk_bf16_f32 v12, v18, v19
	v_cvt_pk_bf16_f32 v13, v20, v21
	v_lshl_add_u64 v[14:15], v[10:11], 0, v[160:161]
	v_cvt_pk_bf16_f32 v10, v22, v23
	v_cvt_pk_bf16_f32 v11, v24, v25
	v_cvt_pk_bf16_f32 v6, v6, v7
	v_cvt_pk_bf16_f32 v7, v8, v9
	v_cvt_pk_bf16_f32 v8, v2, v3
	v_cvt_pk_bf16_f32 v9, v4, v5
	s_andn2_b64 vcc, exec, s[6:7]
	s_mov_b64 s[6:7], -1
	global_store_dwordx4 v[164:165], v[126:129], off
	global_store_dwordx4 v[110:111], v[106:109], off
	global_store_dwordx4 v[94:95], v[90:93], off
	global_store_dwordx4 v[78:79], v[74:77], off
	global_store_dwordx4 v[78:79], v[70:73], off offset:256
	global_store_dwordx4 v[66:67], v[62:65], off
	global_store_dwordx4 v[46:47], v[42:45], off
	global_store_dwordx4 v[30:31], v[26:29], off
	global_store_dwordx4 v[14:15], v[10:13], off
	global_store_dwordx4 v[14:15], v[6:9], off offset:256
	s_cbranch_vccnz .LBB0_279
	s_andn2_b64 vcc, exec, s[8:9]
	s_cbranch_vccnz .LBB0_278
	s_branch .LBB0_278

.LBB0_301:
	s_add_u32 s8, s38, 0x43a00000
	s_addc_u32 s9, s39, 0
	s_lshl_b32 s10, s10, 5
	s_and_b32 s18, s10, 0x60
	s_mov_b64 s[10:11], 0x80
	s_add_i32 m0, s29, 0x18000
	v_lshl_add_u64 v[8:9], v[8:9], 0, s[10:11]
	s_lshl_b32 s15, s14, 13
	s_waitcnt vmcnt(2)
	s_barrier
	global_load_lds_dwordx4 v[8:9], off
	v_lshl_add_u64 v[6:7], v[6:7], 0, s[10:11]
	s_add_i32 m0, s29, 0x1a000
	s_add_i32 s59, s29, 0x8000
	s_add_i32 s60, s29, 0xa000
	global_load_lds_dwordx4 v[6:7], off
	v_lshl_add_u64 v[2:3], v[2:3], 0, s[10:11]
	s_mov_b32 m0, s59
	s_add_u32 s16, s42, 0x100080
	global_load_lds_dwordx4 v[2:3], off
	v_lshl_add_u64 v[2:3], v[4:5], 0, s[10:11]
	s_mov_b32 m0, s60
	s_addc_u32 s17, s43, 0
	global_load_lds_dwordx4 v[2:3], off
	s_add_i32 m0, s29, 0x1c000
	v_lshl_add_u64 v[2:3], s[16:17], 0, v[130:131]
	global_load_lds_dwordx4 v[2:3], off
	v_lshl_add_u64 v[2:3], s[16:17], 0, v[132:133]
	s_add_i32 m0, s29, 0x1e000
	s_sext_i32_i8 s65, s12
	global_load_lds_dwordx4 v[2:3], off
	v_lshlrev_b32_e32 v2, 6, v146
	s_movk_i32 s12, 0x3c0
	v_lshlrev_b32_e32 v3, 2, v146
	v_and_or_b32 v2, v2, s12, v140
	v_and_b32_e32 v3, 32, v3
	v_bitop3_b32 v2, v2, s15, v3 bitop3:0xde
	v_lshlrev_b32_e32 v3, 10, v0
	v_and_b32_e32 v3, 0x60000, v3
	v_lshlrev_b32_e32 v4, 13, v149
	v_or3_b32 v3, v147, v3, v4
	v_add_u32_e32 v134, v3, v148
	v_lshlrev_b32_e32 v3, 6, v150
	s_waitcnt vmcnt(6)
	s_cmpk_lt_u32 s13, 0x100
	v_and_b32_e32 v3, 0xe0000, v3
	v_lshl_or_b32 v142, s18, 7, v139
	s_cselect_b64 s[12:13], -1, 0
	v_or3_b32 v3, v147, v3, v4
	s_add_i32 s62, 0, 0x10000
	s_add_i32 s63, 0, 0x14000
	v_lshl_or_b32 v141, s14, 6, v146
	s_ashr_i32 s61, s44, 31
	v_lshl_or_b32 v143, v138, 2, s18
	v_mov_b32_e32 v135, v131
	v_add_u32_e32 v136, v3, v148
	v_mov_b32_e32 v137, v131
	v_add_u32_e32 v144, s62, v142
	v_add_u32_e32 v145, s63, v142
	v_add_u32_e32 v151, 0, v2
	s_mov_b32 s64, 0x8200000
	s_mov_b64 s[14:15], 0x40000
	s_mov_b64 s[16:17], 0x48000
	s_mov_b64 s[18:19], 0x50000
	s_mov_b64 s[20:21], 0x58000
	s_branch .LBB0_304

.LBB0_311:
	s_and_b64 vcc, exec, s[12:13]
	s_cbranch_vccz .Lkt_T_1
.Lkt_L_1:
	ds_read_b128 v[152:155], v144
	ds_read_b128 v[156:159], v144 offset:1024
	ds_read_b128 v[160:163], v144 offset:2048
	ds_read_b128 v[164:167], v144 offset:3072
	ds_read_b128 v[168:171], v145
	ds_read_b128 v[172:175], v145 offset:1024
	ds_read_b128 v[176:179], v145 offset:2048
	ds_read_b128 v[180:183], v145 offset:3072
	s_add_u32 s42, s40, 0xfff00080
	s_addc_u32 s43, s41, -1
	s_cmp_eq_u32 s70, 60
	s_cselect_b32 s47, s27, s43
	s_cselect_b32 s46, s66, s42
	s_cselect_b32 s43, s25, s69
	s_cselect_b32 s42, s67, s68
	v_lshl_add_u64 v[192:193], s[40:41], 0, v[134:135]
	s_add_i32 m0, s29, 0xc000
	ds_read_b128 v[184:187], v151
	ds_read_b128 v[188:191], v151 offset:1024
	ds_read_b128 v[196:199], v151 offset:2048
	ds_read_b128 v[200:203], v151 offset:3072
	ds_read_b128 v[204:207], v151 offset:4096
	ds_read_b128 v[208:211], v151 offset:5120
	ds_read_b128 v[212:215], v151 offset:6144
	ds_read_b128 v[216:219], v151 offset:7168
	global_load_lds_dwordx4 v[192:193], off
	v_lshl_add_u64 v[192:193], s[40:41], 0, v[136:137]
	s_add_i32 m0, s29, 0xe000
	s_nop 0
	global_load_lds_dwordx4 v[192:193], off
	s_waitcnt lgkmcnt(0)
	s_setprio 1
	v_mfma_f32_16x16x32_bf16 v[126:129], v[152:155], v[184:187], v[126:129]
	v_mfma_f32_16x16x32_bf16 v[122:125], v[160:163], v[184:187], v[122:125]
	v_mfma_f32_16x16x32_bf16 v[118:121], v[152:155], v[196:199], v[118:121]
	v_mfma_f32_16x16x32_bf16 v[110:113], v[160:163], v[196:199], v[110:113]
	v_mfma_f32_16x16x32_bf16 v[102:105], v[152:155], v[204:207], v[102:105]
	v_mfma_f32_16x16x32_bf16 v[94:97], v[160:163], v[204:207], v[94:97]
	v_mfma_f32_16x16x32_bf16 v[86:89], v[152:155], v[212:215], v[86:89]
	v_mfma_f32_16x16x32_bf16 v[78:81], v[160:163], v[212:215], v[78:81]
	v_mfma_f32_16x16x32_bf16 v[126:129], v[156:159], v[188:191], v[126:129]
	v_mfma_f32_16x16x32_bf16 v[122:125], v[164:167], v[188:191], v[122:125]
	v_mfma_f32_16x16x32_bf16 v[118:121], v[156:159], v[200:203], v[118:121]
	v_mfma_f32_16x16x32_bf16 v[110:113], v[164:167], v[200:203], v[110:113]
	v_mfma_f32_16x16x32_bf16 v[102:105], v[156:159], v[208:211], v[102:105]
	v_mfma_f32_16x16x32_bf16 v[94:97], v[164:167], v[208:211], v[94:97]
	v_mfma_f32_16x16x32_bf16 v[86:89], v[156:159], v[216:219], v[86:89]
	v_mfma_f32_16x16x32_bf16 v[78:81], v[164:167], v[216:219], v[78:81]
	v_mfma_f32_16x16x32_bf16 v[114:117], v[168:171], v[184:187], v[114:117]
	v_mfma_f32_16x16x32_bf16 v[106:109], v[176:179], v[184:187], v[106:109]
	v_mfma_f32_16x16x32_bf16 v[98:101], v[168:171], v[196:199], v[98:101]
	v_mfma_f32_16x16x32_bf16 v[90:93], v[176:179], v[196:199], v[90:93]
	v_mfma_f32_16x16x32_bf16 v[82:85], v[168:171], v[204:207], v[82:85]
	v_mfma_f32_16x16x32_bf16 v[74:77], v[176:179], v[204:207], v[74:77]
	v_mfma_f32_16x16x32_bf16 v[70:73], v[168:171], v[212:215], v[70:73]
	v_mfma_f32_16x16x32_bf16 v[66:69], v[176:179], v[212:215], v[66:69]
	v_mfma_f32_16x16x32_bf16 v[114:117], v[172:175], v[188:191], v[114:117]
	v_mfma_f32_16x16x32_bf16 v[106:109], v[180:183], v[188:191], v[106:109]
	v_mfma_f32_16x16x32_bf16 v[98:101], v[172:175], v[200:203], v[98:101]
	v_mfma_f32_16x16x32_bf16 v[90:93], v[180:183], v[200:203], v[90:93]
	v_mfma_f32_16x16x32_bf16 v[82:85], v[172:175], v[208:211], v[82:85]
	v_mfma_f32_16x16x32_bf16 v[74:77], v[180:183], v[208:211], v[74:77]
	v_mfma_f32_16x16x32_bf16 v[70:73], v[172:175], v[216:219], v[70:73]
	v_mfma_f32_16x16x32_bf16 v[66:69], v[180:183], v[216:219], v[66:69]
	s_setprio 0
	s_waitcnt vmcnt(8)
	s_barrier
	s_add_i32 s71, s62, s54
	v_lshl_add_u64 v[192:193], s[42:43], 0, v[130:131]
	s_mov_b32 m0, s71
	ds_read_b128 v[184:187], v151 offset:16384
	ds_read_b128 v[188:191], v151 offset:17408
	ds_read_b128 v[196:199], v151 offset:18432
	ds_read_b128 v[200:203], v151 offset:19456
	ds_read_b128 v[204:207], v151 offset:20480
	ds_read_b128 v[208:211], v151 offset:21504
	ds_read_b128 v[212:215], v151 offset:22528
	ds_read_b128 v[216:219], v151 offset:23552
	global_load_lds_dwordx4 v[192:193], off
	s_add_i32 m0, s71, 0x2000
	s_add_u32 s72, s42, 0x100000
	v_lshl_add_u64 v[220:221], s[42:43], 0, v[132:133]
	s_addc_u32 s73, s43, 0
	s_add_i32 s71, s63, s54
	global_load_lds_dwordx4 v[220:221], off
	v_lshl_add_u64 v[222:223], s[72:73], 0, v[130:131]
	s_mov_b32 m0, s71
	v_lshl_add_u64 v[224:225], s[46:47], 0, v[132:133]
	global_load_lds_dwordx4 v[222:223], off
	v_lshl_add_u64 v[222:223], s[72:73], 0, v[132:133]
	s_add_i32 m0, s71, 0x2000
	s_nop 0
	global_load_lds_dwordx4 v[222:223], off
	v_lshl_add_u64 v[222:223], s[46:47], 0, v[130:131]
	s_mov_b32 m0, s29
	s_nop 0
	global_load_lds_dwordx4 v[222:223], off
	s_mov_b32 m0, s55
	s_nop 0
	global_load_lds_dwordx4 v[224:225], off
	s_waitcnt lgkmcnt(0)
	s_setprio 1
	v_mfma_f32_16x16x32_bf16 v[62:65], v[152:155], v[184:187], v[62:65]
	v_mfma_f32_16x16x32_bf16 v[58:61], v[160:163], v[184:187], v[58:61]
	v_mfma_f32_16x16x32_bf16 v[54:57], v[152:155], v[196:199], v[54:57]
	v_mfma_f32_16x16x32_bf16 v[46:49], v[160:163], v[196:199], v[46:49]
	v_mfma_f32_16x16x32_bf16 v[38:41], v[152:155], v[204:207], v[38:41]
	v_mfma_f32_16x16x32_bf16 v[30:33], v[160:163], v[204:207], v[30:33]
	v_mfma_f32_16x16x32_bf16 v[22:25], v[152:155], v[212:215], v[22:25]
	v_mfma_f32_16x16x32_bf16 v[14:17], v[160:163], v[212:215], v[14:17]
	v_mfma_f32_16x16x32_bf16 v[62:65], v[156:159], v[188:191], v[62:65]
	v_mfma_f32_16x16x32_bf16 v[58:61], v[164:167], v[188:191], v[58:61]
	v_mfma_f32_16x16x32_bf16 v[54:57], v[156:159], v[200:203], v[54:57]
	v_mfma_f32_16x16x32_bf16 v[46:49], v[164:167], v[200:203], v[46:49]
	v_mfma_f32_16x16x32_bf16 v[38:41], v[156:159], v[208:211], v[38:41]
	v_mfma_f32_16x16x32_bf16 v[30:33], v[164:167], v[208:211], v[30:33]
	v_mfma_f32_16x16x32_bf16 v[22:25], v[156:159], v[216:219], v[22:25]
	v_mfma_f32_16x16x32_bf16 v[14:17], v[164:167], v[216:219], v[14:17]
	v_mfma_f32_16x16x32_bf16 v[50:53], v[168:171], v[184:187], v[50:53]
	v_mfma_f32_16x16x32_bf16 v[42:45], v[176:179], v[184:187], v[42:45]
	v_mfma_f32_16x16x32_bf16 v[34:37], v[168:171], v[196:199], v[34:37]
	v_mfma_f32_16x16x32_bf16 v[26:29], v[176:179], v[196:199], v[26:29]
	v_mfma_f32_16x16x32_bf16 v[18:21], v[168:171], v[204:207], v[18:21]
	v_mfma_f32_16x16x32_bf16 v[10:13], v[176:179], v[204:207], v[10:13]
	v_mfma_f32_16x16x32_bf16 v[6:9], v[168:171], v[212:215], v[6:9]
	v_mfma_f32_16x16x32_bf16 v[2:5], v[176:179], v[212:215], v[2:5]
	v_mfma_f32_16x16x32_bf16 v[50:53], v[172:175], v[188:191], v[50:53]
	v_mfma_f32_16x16x32_bf16 v[42:45], v[180:183], v[188:191], v[42:45]
	v_mfma_f32_16x16x32_bf16 v[34:37], v[172:175], v[200:203], v[34:37]
	v_mfma_f32_16x16x32_bf16 v[26:29], v[180:183], v[200:203], v[26:29]
	v_mfma_f32_16x16x32_bf16 v[18:21], v[172:175], v[208:211], v[18:21]
	v_mfma_f32_16x16x32_bf16 v[10:13], v[180:183], v[208:211], v[10:13]
	v_mfma_f32_16x16x32_bf16 v[6:9], v[172:175], v[216:219], v[6:9]
	v_mfma_f32_16x16x32_bf16 v[2:5], v[180:183], v[216:219], v[2:5]
	s_setprio 0
	s_waitcnt vmcnt(8)
	s_barrier
	s_add_i32 s71, 0, 0x18000
	s_add_i32 s72, 0, 0x1c000
	v_add_u32_e32 v164, s71, v142
	v_add_u32_e32 v180, s72, v142
	ds_read_b128 v[152:155], v164
	ds_read_b128 v[156:159], v164 offset:1024
	ds_read_b128 v[160:163], v164 offset:2048
	ds_read_b128 v[164:167], v164 offset:3072
	ds_read_b128 v[168:171], v180
	ds_read_b128 v[172:175], v180 offset:1024
	ds_read_b128 v[176:179], v180 offset:2048
	ds_read_b128 v[180:183], v180 offset:3072
	s_add_u32 s46, s46, 0x100000
	s_addc_u32 s47, s47, 0
	s_mov_b32 m0, s56
	v_lshl_add_u64 v[226:227], s[46:47], 0, v[130:131]
	ds_read_b128 v[184:187], v151 offset:32768
	ds_read_b128 v[188:191], v151 offset:33792
	ds_read_b128 v[196:199], v151 offset:34816
	ds_read_b128 v[200:203], v151 offset:35840
	ds_read_b128 v[204:207], v151 offset:36864
	ds_read_b128 v[208:211], v151 offset:37888
	ds_read_b128 v[212:215], v151 offset:38912
	ds_read_b128 v[216:219], v151 offset:39936
	global_load_lds_dwordx4 v[226:227], off
	v_lshl_add_u64 v[226:227], s[46:47], 0, v[132:133]
	s_mov_b32 m0, s57
	s_nop 0
	global_load_lds_dwordx4 v[226:227], off
	s_waitcnt lgkmcnt(0)
	s_setprio 1
	v_mfma_f32_16x16x32_bf16 v[126:129], v[152:155], v[184:187], v[126:129]
	v_mfma_f32_16x16x32_bf16 v[122:125], v[160:163], v[184:187], v[122:125]
	v_mfma_f32_16x16x32_bf16 v[118:121], v[152:155], v[196:199], v[118:121]
	v_mfma_f32_16x16x32_bf16 v[110:113], v[160:163], v[196:199], v[110:113]
	v_mfma_f32_16x16x32_bf16 v[102:105], v[152:155], v[204:207], v[102:105]
	v_mfma_f32_16x16x32_bf16 v[94:97], v[160:163], v[204:207], v[94:97]
	v_mfma_f32_16x16x32_bf16 v[86:89], v[152:155], v[212:215], v[86:89]
	v_mfma_f32_16x16x32_bf16 v[78:81], v[160:163], v[212:215], v[78:81]
	v_mfma_f32_16x16x32_bf16 v[126:129], v[156:159], v[188:191], v[126:129]
	v_mfma_f32_16x16x32_bf16 v[122:125], v[164:167], v[188:191], v[122:125]
	v_mfma_f32_16x16x32_bf16 v[118:121], v[156:159], v[200:203], v[118:121]
	v_mfma_f32_16x16x32_bf16 v[110:113], v[164:167], v[200:203], v[110:113]
	v_mfma_f32_16x16x32_bf16 v[102:105], v[156:159], v[208:211], v[102:105]
	v_mfma_f32_16x16x32_bf16 v[94:97], v[164:167], v[208:211], v[94:97]
	v_mfma_f32_16x16x32_bf16 v[86:89], v[156:159], v[216:219], v[86:89]
	v_mfma_f32_16x16x32_bf16 v[78:81], v[164:167], v[216:219], v[78:81]
	v_mfma_f32_16x16x32_bf16 v[114:117], v[168:171], v[184:187], v[114:117]
	v_mfma_f32_16x16x32_bf16 v[106:109], v[176:179], v[184:187], v[106:109]
	v_mfma_f32_16x16x32_bf16 v[98:101], v[168:171], v[196:199], v[98:101]
	v_mfma_f32_16x16x32_bf16 v[90:93], v[176:179], v[196:199], v[90:93]
	v_mfma_f32_16x16x32_bf16 v[82:85], v[168:171], v[204:207], v[82:85]
	v_mfma_f32_16x16x32_bf16 v[74:77], v[176:179], v[204:207], v[74:77]
	v_mfma_f32_16x16x32_bf16 v[70:73], v[168:171], v[212:215], v[70:73]
	v_mfma_f32_16x16x32_bf16 v[66:69], v[176:179], v[212:215], v[66:69]
	v_mfma_f32_16x16x32_bf16 v[114:117], v[172:175], v[188:191], v[114:117]
	v_mfma_f32_16x16x32_bf16 v[106:109], v[180:183], v[188:191], v[106:109]
	v_mfma_f32_16x16x32_bf16 v[98:101], v[172:175], v[200:203], v[98:101]
	v_mfma_f32_16x16x32_bf16 v[90:93], v[180:183], v[200:203], v[90:93]
	v_mfma_f32_16x16x32_bf16 v[82:85], v[172:175], v[208:211], v[82:85]
	v_mfma_f32_16x16x32_bf16 v[74:77], v[180:183], v[208:211], v[74:77]
	v_mfma_f32_16x16x32_bf16 v[70:73], v[172:175], v[216:219], v[70:73]
	v_mfma_f32_16x16x32_bf16 v[66:69], v[180:183], v[216:219], v[66:69]
	s_setprio 0
	s_waitcnt vmcnt(8)
	s_barrier
	s_add_i32 s46, s71, s54
	v_lshl_add_u64 v[192:193], v[192:193], 0, s[10:11]
	s_mov_b32 m0, s46
	ds_read_b128 v[184:187], v151 offset:49152
	ds_read_b128 v[188:191], v151 offset:50176
	ds_read_b128 v[196:199], v151 offset:51200
	ds_read_b128 v[200:203], v151 offset:52224
	ds_read_b128 v[204:207], v151 offset:53248
	ds_read_b128 v[208:211], v151 offset:54272
	ds_read_b128 v[212:215], v151 offset:55296
	ds_read_b128 v[216:219], v151 offset:56320
	global_load_lds_dwordx4 v[192:193], off
	s_add_i32 m0, s46, 0x2000
	s_add_u32 s42, s42, 0x100080
	v_lshl_add_u64 v[192:193], v[220:221], 0, s[10:11]
	s_addc_u32 s43, s43, 0
	s_add_i32 s46, s72, s54
	global_load_lds_dwordx4 v[192:193], off
	v_lshl_add_u64 v[192:193], s[42:43], 0, v[130:131]
	s_mov_b32 m0, s46
	s_nop 0
	global_load_lds_dwordx4 v[192:193], off
	v_lshl_add_u64 v[192:193], s[42:43], 0, v[132:133]
	s_add_i32 m0, s46, 0x2000
	s_nop 0
	global_load_lds_dwordx4 v[192:193], off
	v_lshl_add_u64 v[192:193], v[222:223], 0, s[10:11]
	s_mov_b32 m0, s59
	s_nop 0
	global_load_lds_dwordx4 v[192:193], off
	v_lshl_add_u64 v[192:193], v[224:225], 0, s[10:11]
	s_mov_b32 m0, s60
	s_nop 0
	global_load_lds_dwordx4 v[192:193], off
	s_waitcnt lgkmcnt(0)
	s_setprio 1
	v_mfma_f32_16x16x32_bf16 v[62:65], v[152:155], v[184:187], v[62:65]
	v_mfma_f32_16x16x32_bf16 v[58:61], v[160:163], v[184:187], v[58:61]
	v_mfma_f32_16x16x32_bf16 v[54:57], v[152:155], v[196:199], v[54:57]
	v_mfma_f32_16x16x32_bf16 v[46:49], v[160:163], v[196:199], v[46:49]
	v_mfma_f32_16x16x32_bf16 v[38:41], v[152:155], v[204:207], v[38:41]
	v_mfma_f32_16x16x32_bf16 v[30:33], v[160:163], v[204:207], v[30:33]
	v_mfma_f32_16x16x32_bf16 v[22:25], v[152:155], v[212:215], v[22:25]
	v_mfma_f32_16x16x32_bf16 v[14:17], v[160:163], v[212:215], v[14:17]
	v_mfma_f32_16x16x32_bf16 v[62:65], v[156:159], v[188:191], v[62:65]
	v_mfma_f32_16x16x32_bf16 v[58:61], v[164:167], v[188:191], v[58:61]
	v_mfma_f32_16x16x32_bf16 v[54:57], v[156:159], v[200:203], v[54:57]
	v_mfma_f32_16x16x32_bf16 v[46:49], v[164:167], v[200:203], v[46:49]
	v_mfma_f32_16x16x32_bf16 v[38:41], v[156:159], v[208:211], v[38:41]
	v_mfma_f32_16x16x32_bf16 v[30:33], v[164:167], v[208:211], v[30:33]
	v_mfma_f32_16x16x32_bf16 v[22:25], v[156:159], v[216:219], v[22:25]
	v_mfma_f32_16x16x32_bf16 v[14:17], v[164:167], v[216:219], v[14:17]
	v_mfma_f32_16x16x32_bf16 v[50:53], v[168:171], v[184:187], v[50:53]
	v_mfma_f32_16x16x32_bf16 v[42:45], v[176:179], v[184:187], v[42:45]
	v_mfma_f32_16x16x32_bf16 v[34:37], v[168:171], v[196:199], v[34:37]
	v_mfma_f32_16x16x32_bf16 v[26:29], v[176:179], v[196:199], v[26:29]
	v_mfma_f32_16x16x32_bf16 v[18:21], v[168:171], v[204:207], v[18:21]
	v_mfma_f32_16x16x32_bf16 v[10:13], v[176:179], v[204:207], v[10:13]
	v_mfma_f32_16x16x32_bf16 v[6:9], v[168:171], v[212:215], v[6:9]
	v_mfma_f32_16x16x32_bf16 v[2:5], v[176:179], v[212:215], v[2:5]
	v_mfma_f32_16x16x32_bf16 v[50:53], v[172:175], v[188:191], v[50:53]
	v_mfma_f32_16x16x32_bf16 v[42:45], v[180:183], v[188:191], v[42:45]
	v_mfma_f32_16x16x32_bf16 v[34:37], v[172:175], v[200:203], v[34:37]
	v_mfma_f32_16x16x32_bf16 v[26:29], v[180:183], v[200:203], v[26:29]
	v_mfma_f32_16x16x32_bf16 v[18:21], v[172:175], v[208:211], v[18:21]
	v_mfma_f32_16x16x32_bf16 v[10:13], v[180:183], v[208:211], v[10:13]
	v_mfma_f32_16x16x32_bf16 v[6:9], v[172:175], v[216:219], v[6:9]
	v_mfma_f32_16x16x32_bf16 v[2:5], v[180:183], v[216:219], v[2:5]
	s_setprio 0
	s_waitcnt vmcnt(8)
	s_barrier
	s_add_i32 s70, s70, 2
	s_add_u32 s40, s40, 0x100
	s_addc_u32 s41, s41, 0
	s_add_u32 s68, s68, 0x100
	s_addc_u32 s69, s69, 0
	s_cmp_gt_u32 s70, 61
	s_cbranch_scc0 .Lkt_L_1
	s_branch .Lkt_exit_1
.Lkt_T_1:
	ds_read_b128 v[152:155], v144
	ds_read_b128 v[156:159], v144 offset:1024
	ds_read_b128 v[160:163], v144 offset:2048
	ds_read_b128 v[164:167], v144 offset:3072
	ds_read_b128 v[168:171], v145
	ds_read_b128 v[172:175], v145 offset:1024
	ds_read_b128 v[176:179], v145 offset:2048
	ds_read_b128 v[180:183], v145 offset:3072
	s_add_u32 s42, s40, 0xfff00080
	s_addc_u32 s43, s41, -1
	s_cmp_eq_u32 s70, 60
	s_cselect_b32 s47, s27, s43
	s_cselect_b32 s46, s66, s42
	s_cselect_b32 s43, s25, s69
	s_cselect_b32 s42, s67, s68
	v_lshl_add_u64 v[192:193], s[40:41], 0, v[134:135]
	s_add_i32 m0, s29, 0xc000
	ds_read_b128 v[184:187], v151
	ds_read_b128 v[188:191], v151 offset:1024
	ds_read_b128 v[196:199], v151 offset:2048
	ds_read_b128 v[200:203], v151 offset:3072
	ds_read_b128 v[204:207], v151 offset:4096
	ds_read_b128 v[208:211], v151 offset:5120
	ds_read_b128 v[212:215], v151 offset:6144
	ds_read_b128 v[216:219], v151 offset:7168
	global_load_lds_dwordx4 v[192:193], off
	v_lshl_add_u64 v[192:193], s[40:41], 0, v[136:137]
	s_add_i32 m0, s29, 0xe000
	s_nop 0
	global_load_lds_dwordx4 v[192:193], off
	s_waitcnt vmcnt(8)
	s_waitcnt lgkmcnt(0)
	s_barrier
	s_setprio 2
	v_mfma_f32_16x16x32_bf16 v[126:129], v[152:155], v[184:187], v[126:129]
	v_mfma_f32_16x16x32_bf16 v[122:125], v[160:163], v[184:187], v[122:125]
	v_mfma_f32_16x16x32_bf16 v[118:121], v[152:155], v[196:199], v[118:121]
	v_mfma_f32_16x16x32_bf16 v[110:113], v[160:163], v[196:199], v[110:113]
	v_mfma_f32_16x16x32_bf16 v[102:105], v[152:155], v[204:207], v[102:105]
	v_mfma_f32_16x16x32_bf16 v[94:97], v[160:163], v[204:207], v[94:97]
	v_mfma_f32_16x16x32_bf16 v[86:89], v[152:155], v[212:215], v[86:89]
	v_mfma_f32_16x16x32_bf16 v[78:81], v[160:163], v[212:215], v[78:81]
	v_mfma_f32_16x16x32_bf16 v[126:129], v[156:159], v[188:191], v[126:129]
	v_mfma_f32_16x16x32_bf16 v[122:125], v[164:167], v[188:191], v[122:125]
	v_mfma_f32_16x16x32_bf16 v[118:121], v[156:159], v[200:203], v[118:121]
	v_mfma_f32_16x16x32_bf16 v[110:113], v[164:167], v[200:203], v[110:113]
	v_mfma_f32_16x16x32_bf16 v[102:105], v[156:159], v[208:211], v[102:105]
	v_mfma_f32_16x16x32_bf16 v[94:97], v[164:167], v[208:211], v[94:97]
	v_mfma_f32_16x16x32_bf16 v[86:89], v[156:159], v[216:219], v[86:89]
	v_mfma_f32_16x16x32_bf16 v[78:81], v[164:167], v[216:219], v[78:81]
	v_mfma_f32_16x16x32_bf16 v[114:117], v[168:171], v[184:187], v[114:117]
	v_mfma_f32_16x16x32_bf16 v[106:109], v[176:179], v[184:187], v[106:109]
	v_mfma_f32_16x16x32_bf16 v[98:101], v[168:171], v[196:199], v[98:101]
	v_mfma_f32_16x16x32_bf16 v[90:93], v[176:179], v[196:199], v[90:93]
	v_mfma_f32_16x16x32_bf16 v[82:85], v[168:171], v[204:207], v[82:85]
	v_mfma_f32_16x16x32_bf16 v[74:77], v[176:179], v[204:207], v[74:77]
	v_mfma_f32_16x16x32_bf16 v[70:73], v[168:171], v[212:215], v[70:73]
	v_mfma_f32_16x16x32_bf16 v[66:69], v[176:179], v[212:215], v[66:69]
	v_mfma_f32_16x16x32_bf16 v[114:117], v[172:175], v[188:191], v[114:117]
	v_mfma_f32_16x16x32_bf16 v[106:109], v[180:183], v[188:191], v[106:109]
	v_mfma_f32_16x16x32_bf16 v[98:101], v[172:175], v[200:203], v[98:101]
	v_mfma_f32_16x16x32_bf16 v[90:93], v[180:183], v[200:203], v[90:93]
	v_mfma_f32_16x16x32_bf16 v[82:85], v[172:175], v[208:211], v[82:85]
	v_mfma_f32_16x16x32_bf16 v[74:77], v[180:183], v[208:211], v[74:77]
	v_mfma_f32_16x16x32_bf16 v[70:73], v[172:175], v[216:219], v[70:73]
	v_mfma_f32_16x16x32_bf16 v[66:69], v[180:183], v[216:219], v[66:69]
	s_setprio 0
	s_add_i32 s71, s62, s54
	v_lshl_add_u64 v[192:193], s[42:43], 0, v[130:131]
	s_mov_b32 m0, s71
	ds_read_b128 v[184:187], v151 offset:16384
	ds_read_b128 v[188:191], v151 offset:17408
	ds_read_b128 v[196:199], v151 offset:18432
	ds_read_b128 v[200:203], v151 offset:19456
	ds_read_b128 v[204:207], v151 offset:20480
	ds_read_b128 v[208:211], v151 offset:21504
	ds_read_b128 v[212:215], v151 offset:22528
	ds_read_b128 v[216:219], v151 offset:23552
	global_load_lds_dwordx4 v[192:193], off
	s_add_i32 m0, s71, 0x2000
	s_add_u32 s72, s42, 0x100000
	v_lshl_add_u64 v[220:221], s[42:43], 0, v[132:133]
	s_addc_u32 s73, s43, 0
	s_add_i32 s71, s63, s54
	global_load_lds_dwordx4 v[220:221], off
	v_lshl_add_u64 v[222:223], s[72:73], 0, v[130:131]
	s_mov_b32 m0, s71
	v_lshl_add_u64 v[224:225], s[46:47], 0, v[132:133]
	global_load_lds_dwordx4 v[222:223], off
	v_lshl_add_u64 v[222:223], s[72:73], 0, v[132:133]
	s_add_i32 m0, s71, 0x2000
	s_nop 0
	global_load_lds_dwordx4 v[222:223], off
	v_lshl_add_u64 v[222:223], s[46:47], 0, v[130:131]
	s_mov_b32 m0, s29
	s_nop 0
	global_load_lds_dwordx4 v[222:223], off
	s_mov_b32 m0, s55
	s_nop 0
	global_load_lds_dwordx4 v[224:225], off
	s_waitcnt vmcnt(8)
	s_waitcnt lgkmcnt(0)
	s_barrier
	s_setprio 2
	v_mfma_f32_16x16x32_bf16 v[62:65], v[152:155], v[184:187], v[62:65]
	v_mfma_f32_16x16x32_bf16 v[58:61], v[160:163], v[184:187], v[58:61]
	v_mfma_f32_16x16x32_bf16 v[54:57], v[152:155], v[196:199], v[54:57]
	v_mfma_f32_16x16x32_bf16 v[46:49], v[160:163], v[196:199], v[46:49]
	v_mfma_f32_16x16x32_bf16 v[38:41], v[152:155], v[204:207], v[38:41]
	v_mfma_f32_16x16x32_bf16 v[30:33], v[160:163], v[204:207], v[30:33]
	v_mfma_f32_16x16x32_bf16 v[22:25], v[152:155], v[212:215], v[22:25]
	v_mfma_f32_16x16x32_bf16 v[14:17], v[160:163], v[212:215], v[14:17]
	v_mfma_f32_16x16x32_bf16 v[62:65], v[156:159], v[188:191], v[62:65]
	v_mfma_f32_16x16x32_bf16 v[58:61], v[164:167], v[188:191], v[58:61]
	v_mfma_f32_16x16x32_bf16 v[54:57], v[156:159], v[200:203], v[54:57]
	v_mfma_f32_16x16x32_bf16 v[46:49], v[164:167], v[200:203], v[46:49]
	v_mfma_f32_16x16x32_bf16 v[38:41], v[156:159], v[208:211], v[38:41]
	v_mfma_f32_16x16x32_bf16 v[30:33], v[164:167], v[208:211], v[30:33]
	v_mfma_f32_16x16x32_bf16 v[22:25], v[156:159], v[216:219], v[22:25]
	v_mfma_f32_16x16x32_bf16 v[14:17], v[164:167], v[216:219], v[14:17]
	v_mfma_f32_16x16x32_bf16 v[50:53], v[168:171], v[184:187], v[50:53]
	v_mfma_f32_16x16x32_bf16 v[42:45], v[176:179], v[184:187], v[42:45]
	v_mfma_f32_16x16x32_bf16 v[34:37], v[168:171], v[196:199], v[34:37]
	v_mfma_f32_16x16x32_bf16 v[26:29], v[176:179], v[196:199], v[26:29]
	v_mfma_f32_16x16x32_bf16 v[18:21], v[168:171], v[204:207], v[18:21]
	v_mfma_f32_16x16x32_bf16 v[10:13], v[176:179], v[204:207], v[10:13]
	v_mfma_f32_16x16x32_bf16 v[6:9], v[168:171], v[212:215], v[6:9]
	v_mfma_f32_16x16x32_bf16 v[2:5], v[176:179], v[212:215], v[2:5]
	v_mfma_f32_16x16x32_bf16 v[50:53], v[172:175], v[188:191], v[50:53]
	v_mfma_f32_16x16x32_bf16 v[42:45], v[180:183], v[188:191], v[42:45]
	v_mfma_f32_16x16x32_bf16 v[34:37], v[172:175], v[200:203], v[34:37]
	v_mfma_f32_16x16x32_bf16 v[26:29], v[180:183], v[200:203], v[26:29]
	v_mfma_f32_16x16x32_bf16 v[18:21], v[172:175], v[208:211], v[18:21]
	v_mfma_f32_16x16x32_bf16 v[10:13], v[180:183], v[208:211], v[10:13]
	v_mfma_f32_16x16x32_bf16 v[6:9], v[172:175], v[216:219], v[6:9]
	v_mfma_f32_16x16x32_bf16 v[2:5], v[180:183], v[216:219], v[2:5]
	s_setprio 0
	s_add_i32 s71, 0, 0x18000
	s_add_i32 s72, 0, 0x1c000
	v_add_u32_e32 v164, s71, v142
	v_add_u32_e32 v180, s72, v142
	ds_read_b128 v[152:155], v164
	ds_read_b128 v[156:159], v164 offset:1024
	ds_read_b128 v[160:163], v164 offset:2048
	ds_read_b128 v[164:167], v164 offset:3072
	ds_read_b128 v[168:171], v180
	ds_read_b128 v[172:175], v180 offset:1024
	ds_read_b128 v[176:179], v180 offset:2048
	ds_read_b128 v[180:183], v180 offset:3072
	s_add_u32 s46, s46, 0x100000
	s_addc_u32 s47, s47, 0
	s_mov_b32 m0, s56
	v_lshl_add_u64 v[226:227], s[46:47], 0, v[130:131]
	ds_read_b128 v[184:187], v151 offset:32768
	ds_read_b128 v[188:191], v151 offset:33792
	ds_read_b128 v[196:199], v151 offset:34816
	ds_read_b128 v[200:203], v151 offset:35840
	ds_read_b128 v[204:207], v151 offset:36864
	ds_read_b128 v[208:211], v151 offset:37888
	ds_read_b128 v[212:215], v151 offset:38912
	ds_read_b128 v[216:219], v151 offset:39936
	global_load_lds_dwordx4 v[226:227], off
	v_lshl_add_u64 v[226:227], s[46:47], 0, v[132:133]
	s_mov_b32 m0, s57
	s_nop 0
	global_load_lds_dwordx4 v[226:227], off
	s_waitcnt vmcnt(8)
	s_waitcnt lgkmcnt(0)
	s_barrier
	s_setprio 2
	v_mfma_f32_16x16x32_bf16 v[126:129], v[152:155], v[184:187], v[126:129]
	v_mfma_f32_16x16x32_bf16 v[122:125], v[160:163], v[184:187], v[122:125]
	v_mfma_f32_16x16x32_bf16 v[118:121], v[152:155], v[196:199], v[118:121]
	v_mfma_f32_16x16x32_bf16 v[110:113], v[160:163], v[196:199], v[110:113]
	v_mfma_f32_16x16x32_bf16 v[102:105], v[152:155], v[204:207], v[102:105]
	v_mfma_f32_16x16x32_bf16 v[94:97], v[160:163], v[204:207], v[94:97]
	v_mfma_f32_16x16x32_bf16 v[86:89], v[152:155], v[212:215], v[86:89]
	v_mfma_f32_16x16x32_bf16 v[78:81], v[160:163], v[212:215], v[78:81]
	v_mfma_f32_16x16x32_bf16 v[126:129], v[156:159], v[188:191], v[126:129]
	v_mfma_f32_16x16x32_bf16 v[122:125], v[164:167], v[188:191], v[122:125]
	v_mfma_f32_16x16x32_bf16 v[118:121], v[156:159], v[200:203], v[118:121]
	v_mfma_f32_16x16x32_bf16 v[110:113], v[164:167], v[200:203], v[110:113]
	v_mfma_f32_16x16x32_bf16 v[102:105], v[156:159], v[208:211], v[102:105]
	v_mfma_f32_16x16x32_bf16 v[94:97], v[164:167], v[208:211], v[94:97]
	v_mfma_f32_16x16x32_bf16 v[86:89], v[156:159], v[216:219], v[86:89]
	v_mfma_f32_16x16x32_bf16 v[78:81], v[164:167], v[216:219], v[78:81]
	v_mfma_f32_16x16x32_bf16 v[114:117], v[168:171], v[184:187], v[114:117]
	v_mfma_f32_16x16x32_bf16 v[106:109], v[176:179], v[184:187], v[106:109]
	v_mfma_f32_16x16x32_bf16 v[98:101], v[168:171], v[196:199], v[98:101]
	v_mfma_f32_16x16x32_bf16 v[90:93], v[176:179], v[196:199], v[90:93]
	v_mfma_f32_16x16x32_bf16 v[82:85], v[168:171], v[204:207], v[82:85]
	v_mfma_f32_16x16x32_bf16 v[74:77], v[176:179], v[204:207], v[74:77]
	v_mfma_f32_16x16x32_bf16 v[70:73], v[168:171], v[212:215], v[70:73]
	v_mfma_f32_16x16x32_bf16 v[66:69], v[176:179], v[212:215], v[66:69]
	v_mfma_f32_16x16x32_bf16 v[114:117], v[172:175], v[188:191], v[114:117]
	v_mfma_f32_16x16x32_bf16 v[106:109], v[180:183], v[188:191], v[106:109]
	v_mfma_f32_16x16x32_bf16 v[98:101], v[172:175], v[200:203], v[98:101]
	v_mfma_f32_16x16x32_bf16 v[90:93], v[180:183], v[200:203], v[90:93]
	v_mfma_f32_16x16x32_bf16 v[82:85], v[172:175], v[208:211], v[82:85]
	v_mfma_f32_16x16x32_bf16 v[74:77], v[180:183], v[208:211], v[74:77]
	v_mfma_f32_16x16x32_bf16 v[70:73], v[172:175], v[216:219], v[70:73]
	v_mfma_f32_16x16x32_bf16 v[66:69], v[180:183], v[216:219], v[66:69]
	s_setprio 0
	s_add_i32 s46, s71, s54
	v_lshl_add_u64 v[192:193], v[192:193], 0, s[10:11]
	s_mov_b32 m0, s46
	ds_read_b128 v[184:187], v151 offset:49152
	ds_read_b128 v[188:191], v151 offset:50176
	ds_read_b128 v[196:199], v151 offset:51200
	ds_read_b128 v[200:203], v151 offset:52224
	ds_read_b128 v[204:207], v151 offset:53248
	ds_read_b128 v[208:211], v151 offset:54272
	ds_read_b128 v[212:215], v151 offset:55296
	ds_read_b128 v[216:219], v151 offset:56320
	global_load_lds_dwordx4 v[192:193], off
	s_add_i32 m0, s46, 0x2000
	s_add_u32 s42, s42, 0x100080
	v_lshl_add_u64 v[192:193], v[220:221], 0, s[10:11]
	s_addc_u32 s43, s43, 0
	s_add_i32 s46, s72, s54
	global_load_lds_dwordx4 v[192:193], off
	v_lshl_add_u64 v[192:193], s[42:43], 0, v[130:131]
	s_mov_b32 m0, s46
	s_nop 0
	global_load_lds_dwordx4 v[192:193], off
	v_lshl_add_u64 v[192:193], s[42:43], 0, v[132:133]
	s_add_i32 m0, s46, 0x2000
	s_nop 0
	global_load_lds_dwordx4 v[192:193], off
	v_lshl_add_u64 v[192:193], v[222:223], 0, s[10:11]
	s_mov_b32 m0, s59
	s_nop 0
	global_load_lds_dwordx4 v[192:193], off
	v_lshl_add_u64 v[192:193], v[224:225], 0, s[10:11]
	s_mov_b32 m0, s60
	s_nop 0
	global_load_lds_dwordx4 v[192:193], off
	s_waitcnt vmcnt(8)
	s_waitcnt lgkmcnt(0)
	s_barrier
	s_setprio 2
	v_mfma_f32_16x16x32_bf16 v[62:65], v[152:155], v[184:187], v[62:65]
	v_mfma_f32_16x16x32_bf16 v[58:61], v[160:163], v[184:187], v[58:61]
	v_mfma_f32_16x16x32_bf16 v[54:57], v[152:155], v[196:199], v[54:57]
	v_mfma_f32_16x16x32_bf16 v[46:49], v[160:163], v[196:199], v[46:49]
	v_mfma_f32_16x16x32_bf16 v[38:41], v[152:155], v[204:207], v[38:41]
	v_mfma_f32_16x16x32_bf16 v[30:33], v[160:163], v[204:207], v[30:33]
	v_mfma_f32_16x16x32_bf16 v[22:25], v[152:155], v[212:215], v[22:25]
	v_mfma_f32_16x16x32_bf16 v[14:17], v[160:163], v[212:215], v[14:17]
	v_mfma_f32_16x16x32_bf16 v[62:65], v[156:159], v[188:191], v[62:65]
	v_mfma_f32_16x16x32_bf16 v[58:61], v[164:167], v[188:191], v[58:61]
	v_mfma_f32_16x16x32_bf16 v[54:57], v[156:159], v[200:203], v[54:57]
	v_mfma_f32_16x16x32_bf16 v[46:49], v[164:167], v[200:203], v[46:49]
	v_mfma_f32_16x16x32_bf16 v[38:41], v[156:159], v[208:211], v[38:41]
	v_mfma_f32_16x16x32_bf16 v[30:33], v[164:167], v[208:211], v[30:33]
	v_mfma_f32_16x16x32_bf16 v[22:25], v[156:159], v[216:219], v[22:25]
	v_mfma_f32_16x16x32_bf16 v[14:17], v[164:167], v[216:219], v[14:17]
	v_mfma_f32_16x16x32_bf16 v[50:53], v[168:171], v[184:187], v[50:53]
	v_mfma_f32_16x16x32_bf16 v[42:45], v[176:179], v[184:187], v[42:45]
	v_mfma_f32_16x16x32_bf16 v[34:37], v[168:171], v[196:199], v[34:37]
	v_mfma_f32_16x16x32_bf16 v[26:29], v[176:179], v[196:199], v[26:29]
	v_mfma_f32_16x16x32_bf16 v[18:21], v[168:171], v[204:207], v[18:21]
	v_mfma_f32_16x16x32_bf16 v[10:13], v[176:179], v[204:207], v[10:13]
	v_mfma_f32_16x16x32_bf16 v[6:9], v[168:171], v[212:215], v[6:9]
	v_mfma_f32_16x16x32_bf16 v[2:5], v[176:179], v[212:215], v[2:5]
	v_mfma_f32_16x16x32_bf16 v[50:53], v[172:175], v[188:191], v[50:53]
	v_mfma_f32_16x16x32_bf16 v[42:45], v[180:183], v[188:191], v[42:45]
	v_mfma_f32_16x16x32_bf16 v[34:37], v[172:175], v[200:203], v[34:37]
	v_mfma_f32_16x16x32_bf16 v[26:29], v[180:183], v[200:203], v[26:29]
	v_mfma_f32_16x16x32_bf16 v[18:21], v[172:175], v[208:211], v[18:21]
	v_mfma_f32_16x16x32_bf16 v[10:13], v[180:183], v[208:211], v[10:13]
	v_mfma_f32_16x16x32_bf16 v[6:9], v[172:175], v[216:219], v[6:9]
	v_mfma_f32_16x16x32_bf16 v[2:5], v[180:183], v[216:219], v[2:5]
	s_setprio 0
	s_add_i32 s70, s70, 2
	s_add_u32 s40, s40, 0x100
	s_addc_u32 s41, s41, 0
	s_add_u32 s68, s68, 0x100
	s_addc_u32 s69, s69, 0
	s_cmp_gt_u32 s70, 61
	s_cbranch_scc0 .Lkt_T_1
	s_nop 7

.LBB0_314:
	s_cmp_lt_i32 s65, 2
	v_lshl_or_b32 v154, s65, 8, v143
	s_cselect_b32 s25, s64, 0x8600000
	s_cselect_b32 s27, 0, 0xfffffe00
	v_lshl_add_u32 v152, s28, 8, v141
	s_add_u32 s40, s36, s25
	v_add_u32_e32 v156, s27, v154
	s_addc_u32 s41, s37, 0
	v_ashrrev_i32_e32 v157, 31, v156
	v_ashrrev_i32_e32 v153, 31, v152
	v_lshl_add_u64 v[156:157], v[156:157], 2, s[40:41]
	v_lshlrev_b64 v[158:159], 11, v[152:153]
	v_ashrrev_i32_e32 v155, 31, v154
	v_lshl_add_u64 v[160:161], v[156:157], 0, v[158:159]
	global_store_dwordx4 v[160:161], v[126:129], off
	v_lshlrev_b64 v[154:155], 1, v[154:155]
	s_andn2_b64 vcc, exec, s[22:23]
	v_cvt_pk_bf16_f32 v126, v126, v127
	v_cvt_pk_bf16_f32 v127, v128, v129
	v_lshl_add_u64 v[128:129], s[8:9], 0, v[158:159]
	v_lshl_add_u64 v[128:129], v[128:129], 0, v[154:155]
	global_store_dwordx2 v[128:129], v[126:127], off
	global_store_dwordx4 v[160:161], v[122:125], off offset:64
	s_mov_b64 s[22:23], -1
	s_nop 0
	v_cvt_pk_bf16_f32 v122, v122, v123
	v_cvt_pk_bf16_f32 v123, v124, v125
	global_store_dwordx2 v[128:129], v[122:123], off offset:32
	global_store_dwordx4 v[160:161], v[114:117], off offset:512
	s_nop 1
	v_cvt_pk_bf16_f32 v114, v114, v115
	v_cvt_pk_bf16_f32 v115, v116, v117
	global_store_dwordx2 v[128:129], v[114:115], off offset:256
	global_store_dwordx4 v[160:161], v[106:109], off offset:576
	v_cvt_pk_bf16_f32 v114, v118, v119
	v_cvt_pk_bf16_f32 v115, v120, v121
	v_cvt_pk_bf16_f32 v106, v106, v107
	v_cvt_pk_bf16_f32 v107, v108, v109
	global_store_dwordx2 v[128:129], v[106:107], off offset:288
	v_or_b32_e32 v106, 16, v152
	v_ashrrev_i32_e32 v107, 31, v106
	v_lshlrev_b64 v[106:107], 11, v[106:107]
	v_lshl_add_u64 v[108:109], v[156:157], 0, v[106:107]
	v_lshl_add_u64 v[106:107], s[8:9], 0, v[106:107]
	v_lshl_add_u64 v[106:107], v[106:107], 0, v[154:155]
	global_store_dwordx4 v[108:109], v[118:121], off
	global_store_dwordx2 v[106:107], v[114:115], off
	global_store_dwordx4 v[108:109], v[110:113], off offset:64
	s_nop 1
	v_cvt_pk_bf16_f32 v110, v110, v111
	v_cvt_pk_bf16_f32 v111, v112, v113
	global_store_dwordx2 v[106:107], v[110:111], off offset:32
	global_store_dwordx4 v[108:109], v[98:101], off offset:512
	s_nop 1
	v_cvt_pk_bf16_f32 v98, v98, v99
	v_cvt_pk_bf16_f32 v99, v100, v101
	global_store_dwordx2 v[106:107], v[98:99], off offset:256
	global_store_dwordx4 v[108:109], v[90:93], off offset:576
	v_cvt_pk_bf16_f32 v98, v102, v103
	v_cvt_pk_bf16_f32 v99, v104, v105
	v_cvt_pk_bf16_f32 v90, v90, v91
	v_cvt_pk_bf16_f32 v91, v92, v93
	global_store_dwordx2 v[106:107], v[90:91], off offset:288
	v_or_b32_e32 v90, 32, v152
	v_ashrrev_i32_e32 v91, 31, v90
	v_lshlrev_b64 v[90:91], 11, v[90:91]
	v_lshl_add_u64 v[92:93], v[156:157], 0, v[90:91]
	v_lshl_add_u64 v[90:91], s[8:9], 0, v[90:91]
	v_lshl_add_u64 v[90:91], v[90:91], 0, v[154:155]
	global_store_dwordx4 v[92:93], v[102:105], off
	global_store_dwordx2 v[90:91], v[98:99], off
	global_store_dwordx4 v[92:93], v[94:97], off offset:64
	s_nop 1
	v_cvt_pk_bf16_f32 v94, v94, v95
	v_cvt_pk_bf16_f32 v95, v96, v97
	global_store_dwordx2 v[90:91], v[94:95], off offset:32
	global_store_dwordx4 v[92:93], v[82:85], off offset:512
	s_nop 1
	v_cvt_pk_bf16_f32 v82, v82, v83
	v_cvt_pk_bf16_f32 v83, v84, v85
	global_store_dwordx2 v[90:91], v[82:83], off offset:256
	global_store_dwordx4 v[92:93], v[74:77], off offset:576
	v_cvt_pk_bf16_f32 v82, v86, v87
	v_cvt_pk_bf16_f32 v83, v88, v89
	v_cvt_pk_bf16_f32 v74, v74, v75
	v_cvt_pk_bf16_f32 v75, v76, v77
	global_store_dwordx2 v[90:91], v[74:75], off offset:288
	v_or_b32_e32 v74, 48, v152
	v_ashrrev_i32_e32 v75, 31, v74
	v_lshlrev_b64 v[74:75], 11, v[74:75]
	v_lshl_add_u64 v[76:77], v[156:157], 0, v[74:75]
	v_lshl_add_u64 v[74:75], s[8:9], 0, v[74:75]
	v_lshl_add_u64 v[74:75], v[74:75], 0, v[154:155]
	global_store_dwordx4 v[76:77], v[86:89], off
	global_store_dwordx2 v[74:75], v[82:83], off
	global_store_dwordx4 v[76:77], v[78:81], off offset:64
	s_nop 1
	v_cvt_pk_bf16_f32 v78, v78, v79
	v_cvt_pk_bf16_f32 v79, v80, v81
	global_store_dwordx2 v[74:75], v[78:79], off offset:32
	global_store_dwordx4 v[76:77], v[70:73], off offset:512
	s_nop 1
	v_cvt_pk_bf16_f32 v70, v70, v71
	v_cvt_pk_bf16_f32 v71, v72, v73
	global_store_dwordx2 v[74:75], v[70:71], off offset:256
	global_store_dwordx4 v[76:77], v[66:69], off offset:576
	s_nop 1
	v_cvt_pk_bf16_f32 v66, v66, v67
	v_cvt_pk_bf16_f32 v67, v68, v69
	global_store_dwordx2 v[74:75], v[66:67], off offset:288
	v_lshl_add_u64 v[66:67], v[158:159], 0, s[14:15]
	v_lshl_add_u64 v[68:69], v[156:157], 0, v[66:67]
	global_store_dwordx4 v[68:69], v[62:65], off
	s_nop 1
	v_cvt_pk_bf16_f32 v62, v62, v63
	v_cvt_pk_bf16_f32 v63, v64, v65
	v_lshl_add_u64 v[64:65], s[8:9], 0, v[66:67]
	v_lshl_add_u64 v[64:65], v[64:65], 0, v[154:155]
	global_store_dwordx2 v[64:65], v[62:63], off
	global_store_dwordx4 v[68:69], v[58:61], off offset:64
	s_nop 1
	v_cvt_pk_bf16_f32 v58, v58, v59
	v_cvt_pk_bf16_f32 v59, v60, v61
	global_store_dwordx2 v[64:65], v[58:59], off offset:32
	global_store_dwordx4 v[68:69], v[50:53], off offset:512
	s_nop 1
	v_cvt_pk_bf16_f32 v50, v50, v51
	v_cvt_pk_bf16_f32 v51, v52, v53
	global_store_dwordx2 v[64:65], v[50:51], off offset:256
	global_store_dwordx4 v[68:69], v[42:45], off offset:576
	v_cvt_pk_bf16_f32 v50, v54, v55
	v_cvt_pk_bf16_f32 v51, v56, v57
	v_cvt_pk_bf16_f32 v42, v42, v43
	v_cvt_pk_bf16_f32 v43, v44, v45
	global_store_dwordx2 v[64:65], v[42:43], off offset:288
	v_lshl_add_u64 v[42:43], v[158:159], 0, s[16:17]
	v_lshl_add_u64 v[44:45], v[156:157], 0, v[42:43]
	v_lshl_add_u64 v[42:43], s[8:9], 0, v[42:43]
	v_lshl_add_u64 v[42:43], v[42:43], 0, v[154:155]
	global_store_dwordx4 v[44:45], v[54:57], off
	global_store_dwordx2 v[42:43], v[50:51], off
	global_store_dwordx4 v[44:45], v[46:49], off offset:64
	s_nop 1
	v_cvt_pk_bf16_f32 v46, v46, v47
	v_cvt_pk_bf16_f32 v47, v48, v49
	global_store_dwordx2 v[42:43], v[46:47], off offset:32
	global_store_dwordx4 v[44:45], v[34:37], off offset:512
	s_nop 1
	v_cvt_pk_bf16_f32 v34, v34, v35
	v_cvt_pk_bf16_f32 v35, v36, v37
	global_store_dwordx2 v[42:43], v[34:35], off offset:256
	global_store_dwordx4 v[44:45], v[26:29], off offset:576
	v_cvt_pk_bf16_f32 v34, v38, v39
	v_cvt_pk_bf16_f32 v35, v40, v41
	v_cvt_pk_bf16_f32 v26, v26, v27
	v_cvt_pk_bf16_f32 v27, v28, v29
	global_store_dwordx2 v[42:43], v[26:27], off offset:288
	v_lshl_add_u64 v[26:27], v[158:159], 0, s[18:19]
	v_lshl_add_u64 v[28:29], v[156:157], 0, v[26:27]
	v_lshl_add_u64 v[26:27], s[8:9], 0, v[26:27]
	v_lshl_add_u64 v[26:27], v[26:27], 0, v[154:155]
	global_store_dwordx4 v[28:29], v[38:41], off
	global_store_dwordx2 v[26:27], v[34:35], off
	global_store_dwordx4 v[28:29], v[30:33], off offset:64
	s_nop 1
	v_cvt_pk_bf16_f32 v30, v30, v31
	v_cvt_pk_bf16_f32 v31, v32, v33
	global_store_dwordx2 v[26:27], v[30:31], off offset:32
	global_store_dwordx4 v[28:29], v[18:21], off offset:512
	s_nop 1
	v_cvt_pk_bf16_f32 v18, v18, v19
	v_cvt_pk_bf16_f32 v19, v20, v21
	global_store_dwordx2 v[26:27], v[18:19], off offset:256
	global_store_dwordx4 v[28:29], v[10:13], off offset:576
	v_cvt_pk_bf16_f32 v18, v22, v23
	v_cvt_pk_bf16_f32 v19, v24, v25
	v_cvt_pk_bf16_f32 v10, v10, v11
	v_cvt_pk_bf16_f32 v11, v12, v13
	global_store_dwordx2 v[26:27], v[10:11], off offset:288
	v_lshl_add_u64 v[10:11], v[158:159], 0, s[20:21]
	v_lshl_add_u64 v[12:13], v[156:157], 0, v[10:11]
	v_lshl_add_u64 v[10:11], s[8:9], 0, v[10:11]
	v_lshl_add_u64 v[10:11], v[10:11], 0, v[154:155]
	global_store_dwordx4 v[12:13], v[22:25], off
	global_store_dwordx2 v[10:11], v[18:19], off
	global_store_dwordx4 v[12:13], v[14:17], off offset:64
	s_nop 1
	v_cvt_pk_bf16_f32 v14, v14, v15
	v_cvt_pk_bf16_f32 v15, v16, v17
	global_store_dwordx2 v[10:11], v[14:15], off offset:32
	global_store_dwordx4 v[12:13], v[6:9], off offset:512
	s_nop 1
	v_cvt_pk_bf16_f32 v6, v6, v7
	v_cvt_pk_bf16_f32 v7, v8, v9
	global_store_dwordx2 v[10:11], v[6:7], off offset:256
	global_store_dwordx4 v[12:13], v[2:5], off offset:576
	s_nop 1
	v_cvt_pk_bf16_f32 v2, v2, v3
	v_cvt_pk_bf16_f32 v3, v4, v5
	global_store_dwordx2 v[10:11], v[2:3], off offset:288
	s_cbranch_vccnz .LBB0_303
	s_andn2_b64 vcc, exec, s[6:7]
	s_cbranch_vccnz .LBB0_302
	s_branch .LBB0_302

.LBB0_325:
	s_add_u32 s8, s38, 0x43c00000
	s_addc_u32 s9, s39, 0
	s_lshl_b32 s10, s10, 5
	s_and_b32 s18, s10, 0x60
	s_mov_b64 s[10:11], 0x80
	s_add_i32 m0, s29, 0x18000
	v_lshl_add_u64 v[8:9], v[8:9], 0, s[10:11]
	s_lshl_b32 s15, s14, 13
	s_waitcnt vmcnt(2)
	s_barrier
	global_load_lds_dwordx4 v[8:9], off
	v_lshl_add_u64 v[6:7], v[6:7], 0, s[10:11]
	s_add_i32 m0, s29, 0x1a000
	s_add_i32 s56, s29, 0x8000
	s_add_i32 s57, s29, 0xa000
	global_load_lds_dwordx4 v[6:7], off
	v_lshl_add_u64 v[2:3], v[2:3], 0, s[10:11]
	s_mov_b32 m0, s56
	s_add_u32 s16, s42, 0x100080
	global_load_lds_dwordx4 v[2:3], off
	v_lshl_add_u64 v[2:3], v[4:5], 0, s[10:11]
	s_mov_b32 m0, s57
	s_addc_u32 s17, s43, 0
	global_load_lds_dwordx4 v[2:3], off
	s_add_i32 m0, s29, 0x1c000
	v_lshl_add_u64 v[2:3], s[16:17], 0, v[130:131]
	global_load_lds_dwordx4 v[2:3], off
	v_lshl_add_u64 v[2:3], s[16:17], 0, v[132:133]
	s_add_i32 m0, s29, 0x1e000
	s_sext_i32_i8 s62, s12
	global_load_lds_dwordx4 v[2:3], off
	v_lshlrev_b32_e32 v2, 6, v146
	s_movk_i32 s12, 0x3c0
	v_lshlrev_b32_e32 v3, 2, v146
	v_and_or_b32 v2, v2, s12, v140
	v_and_b32_e32 v3, 32, v3
	v_bitop3_b32 v2, v2, s15, v3 bitop3:0xde
	v_lshlrev_b32_e32 v3, 10, v0
	v_and_b32_e32 v3, 0x60000, v3
	v_lshlrev_b32_e32 v4, 13, v149
	v_or3_b32 v3, v147, v3, v4
	v_add_u32_e32 v134, v3, v148
	v_lshlrev_b32_e32 v3, 6, v150
	s_waitcnt vmcnt(6)
	s_cmpk_lt_u32 s13, 0x100
	v_and_b32_e32 v3, 0xe0000, v3
	v_lshl_or_b32 v139, s18, 7, v139
	s_cselect_b64 s[12:13], -1, 0
	v_or3_b32 v3, v147, v3, v4
	s_add_i32 s59, 0, 0x10000
	s_add_i32 s60, 0, 0x14000
	v_lshl_or_b32 v141, s14, 6, v146
	s_ashr_i32 s58, s44, 31
	v_lshl_or_b32 v138, v138, 2, s18
	v_mov_b32_e32 v135, v131
	v_add_u32_e32 v136, v3, v148
	v_mov_b32_e32 v137, v131
	v_add_u32_e32 v140, s59, v139
	v_add_u32_e32 v142, s60, v139
	v_add_u32_e32 v143, 0, v2
	s_mov_b32 s61, 0x8400000
	s_mov_b64 s[14:15], 0x40000
	s_mov_b64 s[16:17], 0x48000
	s_mov_b64 s[18:19], 0x50000
	s_mov_b64 s[20:21], 0x58000
	s_branch .LBB0_328

.Lkt_L_2:
	ds_read_b128 v[144:147], v140
	ds_read_b128 v[148:151], v140 offset:1024
	ds_read_b128 v[152:155], v140 offset:2048
	ds_read_b128 v[156:159], v140 offset:3072
	ds_read_b128 v[160:163], v142
	ds_read_b128 v[164:167], v142 offset:1024
	ds_read_b128 v[168:171], v142 offset:2048
	ds_read_b128 v[172:175], v142 offset:3072
	s_add_u32 s42, s40, 0xfff00080
	s_addc_u32 s43, s41, -1
	s_cmp_eq_u32 s67, 60
	s_cselect_b32 s47, s27, s43
	s_cselect_b32 s46, s63, s42
	s_cselect_b32 s43, s25, s66
	s_cselect_b32 s42, s64, s65
	v_lshl_add_u64 v[192:193], s[40:41], 0, v[134:135]
	s_add_i32 m0, s29, 0xc000
	ds_read_b128 v[176:179], v143
	ds_read_b128 v[180:183], v143 offset:1024
	ds_read_b128 v[184:187], v143 offset:2048
	ds_read_b128 v[188:191], v143 offset:3072
	ds_read_b128 v[196:199], v143 offset:4096
	ds_read_b128 v[200:203], v143 offset:5120
	ds_read_b128 v[204:207], v143 offset:6144
	ds_read_b128 v[208:211], v143 offset:7168
	global_load_lds_dwordx4 v[192:193], off
	v_lshl_add_u64 v[192:193], s[40:41], 0, v[136:137]
	s_add_i32 m0, s29, 0xe000
	s_nop 0
	global_load_lds_dwordx4 v[192:193], off
	s_waitcnt lgkmcnt(0)
	s_setprio 1
	v_mfma_f32_16x16x32_bf16 v[126:129], v[144:147], v[176:179], v[126:129]
	v_mfma_f32_16x16x32_bf16 v[122:125], v[152:155], v[176:179], v[122:125]
	v_mfma_f32_16x16x32_bf16 v[118:121], v[144:147], v[184:187], v[118:121]
	v_mfma_f32_16x16x32_bf16 v[110:113], v[152:155], v[184:187], v[110:113]
	v_mfma_f32_16x16x32_bf16 v[102:105], v[144:147], v[196:199], v[102:105]
	v_mfma_f32_16x16x32_bf16 v[94:97], v[152:155], v[196:199], v[94:97]
	v_mfma_f32_16x16x32_bf16 v[86:89], v[144:147], v[204:207], v[86:89]
	v_mfma_f32_16x16x32_bf16 v[78:81], v[152:155], v[204:207], v[78:81]
	v_mfma_f32_16x16x32_bf16 v[126:129], v[148:151], v[180:183], v[126:129]
	v_mfma_f32_16x16x32_bf16 v[122:125], v[156:159], v[180:183], v[122:125]
	v_mfma_f32_16x16x32_bf16 v[118:121], v[148:151], v[188:191], v[118:121]
	v_mfma_f32_16x16x32_bf16 v[110:113], v[156:159], v[188:191], v[110:113]
	v_mfma_f32_16x16x32_bf16 v[102:105], v[148:151], v[200:203], v[102:105]
	v_mfma_f32_16x16x32_bf16 v[94:97], v[156:159], v[200:203], v[94:97]
	v_mfma_f32_16x16x32_bf16 v[86:89], v[148:151], v[208:211], v[86:89]
	v_mfma_f32_16x16x32_bf16 v[78:81], v[156:159], v[208:211], v[78:81]
	v_mfma_f32_16x16x32_bf16 v[114:117], v[160:163], v[176:179], v[114:117]
	v_mfma_f32_16x16x32_bf16 v[106:109], v[168:171], v[176:179], v[106:109]
	v_mfma_f32_16x16x32_bf16 v[98:101], v[160:163], v[184:187], v[98:101]
	v_mfma_f32_16x16x32_bf16 v[90:93], v[168:171], v[184:187], v[90:93]
	v_mfma_f32_16x16x32_bf16 v[82:85], v[160:163], v[196:199], v[82:85]
	v_mfma_f32_16x16x32_bf16 v[74:77], v[168:171], v[196:199], v[74:77]
	v_mfma_f32_16x16x32_bf16 v[70:73], v[160:163], v[204:207], v[70:73]
	v_mfma_f32_16x16x32_bf16 v[66:69], v[168:171], v[204:207], v[66:69]
	v_mfma_f32_16x16x32_bf16 v[114:117], v[164:167], v[180:183], v[114:117]
	v_mfma_f32_16x16x32_bf16 v[106:109], v[172:175], v[180:183], v[106:109]
	v_mfma_f32_16x16x32_bf16 v[98:101], v[164:167], v[188:191], v[98:101]
	v_mfma_f32_16x16x32_bf16 v[90:93], v[172:175], v[188:191], v[90:93]
	v_mfma_f32_16x16x32_bf16 v[82:85], v[164:167], v[200:203], v[82:85]
	v_mfma_f32_16x16x32_bf16 v[74:77], v[172:175], v[200:203], v[74:77]
	v_mfma_f32_16x16x32_bf16 v[70:73], v[164:167], v[208:211], v[70:73]
	v_mfma_f32_16x16x32_bf16 v[66:69], v[172:175], v[208:211], v[66:69]
	s_setprio 0
	s_waitcnt vmcnt(8)
	s_barrier
	s_add_i32 s68, s59, s51
	v_lshl_add_u64 v[192:193], s[42:43], 0, v[130:131]
	s_mov_b32 m0, s68
	ds_read_b128 v[176:179], v143 offset:16384
	ds_read_b128 v[180:183], v143 offset:17408
	ds_read_b128 v[184:187], v143 offset:18432
	ds_read_b128 v[188:191], v143 offset:19456
	ds_read_b128 v[196:199], v143 offset:20480
	ds_read_b128 v[200:203], v143 offset:21504
	ds_read_b128 v[204:207], v143 offset:22528
	ds_read_b128 v[208:211], v143 offset:23552
	global_load_lds_dwordx4 v[192:193], off
	s_add_i32 m0, s68, 0x2000
	s_add_u32 s68, s42, 0x100000
	v_lshl_add_u64 v[212:213], s[42:43], 0, v[132:133]
	s_addc_u32 s69, s43, 0
	s_add_i32 s70, s60, s51
	global_load_lds_dwordx4 v[212:213], off
	v_lshl_add_u64 v[214:215], s[68:69], 0, v[130:131]
	s_mov_b32 m0, s70
	v_lshl_add_u64 v[216:217], s[46:47], 0, v[132:133]
	global_load_lds_dwordx4 v[214:215], off
	v_lshl_add_u64 v[214:215], s[68:69], 0, v[132:133]
	s_add_i32 m0, s70, 0x2000
	s_nop 0
	global_load_lds_dwordx4 v[214:215], off
	v_lshl_add_u64 v[214:215], s[46:47], 0, v[130:131]
	s_mov_b32 m0, s29
	s_nop 0
	global_load_lds_dwordx4 v[214:215], off
	s_mov_b32 m0, s52
	s_nop 0
	global_load_lds_dwordx4 v[216:217], off
	s_waitcnt lgkmcnt(0)
	s_setprio 1
	v_mfma_f32_16x16x32_bf16 v[62:65], v[144:147], v[176:179], v[62:65]
	v_mfma_f32_16x16x32_bf16 v[58:61], v[152:155], v[176:179], v[58:61]
	v_mfma_f32_16x16x32_bf16 v[54:57], v[144:147], v[184:187], v[54:57]
	v_mfma_f32_16x16x32_bf16 v[46:49], v[152:155], v[184:187], v[46:49]
	v_mfma_f32_16x16x32_bf16 v[38:41], v[144:147], v[196:199], v[38:41]
	v_mfma_f32_16x16x32_bf16 v[30:33], v[152:155], v[196:199], v[30:33]
	v_mfma_f32_16x16x32_bf16 v[22:25], v[144:147], v[204:207], v[22:25]
	v_mfma_f32_16x16x32_bf16 v[14:17], v[152:155], v[204:207], v[14:17]
	v_mfma_f32_16x16x32_bf16 v[62:65], v[148:151], v[180:183], v[62:65]
	v_mfma_f32_16x16x32_bf16 v[58:61], v[156:159], v[180:183], v[58:61]
	v_mfma_f32_16x16x32_bf16 v[54:57], v[148:151], v[188:191], v[54:57]
	v_mfma_f32_16x16x32_bf16 v[46:49], v[156:159], v[188:191], v[46:49]
	v_mfma_f32_16x16x32_bf16 v[38:41], v[148:151], v[200:203], v[38:41]
	v_mfma_f32_16x16x32_bf16 v[30:33], v[156:159], v[200:203], v[30:33]
	v_mfma_f32_16x16x32_bf16 v[22:25], v[148:151], v[208:211], v[22:25]
	v_mfma_f32_16x16x32_bf16 v[14:17], v[156:159], v[208:211], v[14:17]
	v_mfma_f32_16x16x32_bf16 v[50:53], v[160:163], v[176:179], v[50:53]
	v_mfma_f32_16x16x32_bf16 v[42:45], v[168:171], v[176:179], v[42:45]
	v_mfma_f32_16x16x32_bf16 v[34:37], v[160:163], v[184:187], v[34:37]
	v_mfma_f32_16x16x32_bf16 v[26:29], v[168:171], v[184:187], v[26:29]
	v_mfma_f32_16x16x32_bf16 v[18:21], v[160:163], v[196:199], v[18:21]
	v_mfma_f32_16x16x32_bf16 v[10:13], v[168:171], v[196:199], v[10:13]
	v_mfma_f32_16x16x32_bf16 v[6:9], v[160:163], v[204:207], v[6:9]
	v_mfma_f32_16x16x32_bf16 v[2:5], v[168:171], v[204:207], v[2:5]
	v_mfma_f32_16x16x32_bf16 v[50:53], v[164:167], v[180:183], v[50:53]
	v_mfma_f32_16x16x32_bf16 v[42:45], v[172:175], v[180:183], v[42:45]
	v_mfma_f32_16x16x32_bf16 v[34:37], v[164:167], v[188:191], v[34:37]
	v_mfma_f32_16x16x32_bf16 v[26:29], v[172:175], v[188:191], v[26:29]
	v_mfma_f32_16x16x32_bf16 v[18:21], v[164:167], v[200:203], v[18:21]
	v_mfma_f32_16x16x32_bf16 v[10:13], v[172:175], v[200:203], v[10:13]
	v_mfma_f32_16x16x32_bf16 v[6:9], v[164:167], v[208:211], v[6:9]
	v_mfma_f32_16x16x32_bf16 v[2:5], v[172:175], v[208:211], v[2:5]
	s_setprio 0
	s_waitcnt vmcnt(8)
	s_barrier
	s_add_i32 s68, 0, 0x18000
	s_add_i32 s69, 0, 0x1c000
	v_add_u32_e32 v156, s68, v139
	v_add_u32_e32 v172, s69, v139
	ds_read_b128 v[144:147], v156
	ds_read_b128 v[148:151], v156 offset:1024
	ds_read_b128 v[152:155], v156 offset:2048
	ds_read_b128 v[156:159], v156 offset:3072
	ds_read_b128 v[160:163], v172
	ds_read_b128 v[164:167], v172 offset:1024
	ds_read_b128 v[168:171], v172 offset:2048
	ds_read_b128 v[172:175], v172 offset:3072
	s_add_u32 s46, s46, 0x100000
	s_addc_u32 s47, s47, 0
	s_mov_b32 m0, s53
	v_lshl_add_u64 v[218:219], s[46:47], 0, v[130:131]
	ds_read_b128 v[176:179], v143 offset:32768
	ds_read_b128 v[180:183], v143 offset:33792
	ds_read_b128 v[184:187], v143 offset:34816
	ds_read_b128 v[188:191], v143 offset:35840
	ds_read_b128 v[196:199], v143 offset:36864
	ds_read_b128 v[200:203], v143 offset:37888
	ds_read_b128 v[204:207], v143 offset:38912
	ds_read_b128 v[208:211], v143 offset:39936
	global_load_lds_dwordx4 v[218:219], off
	v_lshl_add_u64 v[218:219], s[46:47], 0, v[132:133]
	s_mov_b32 m0, s54
	s_nop 0
	global_load_lds_dwordx4 v[218:219], off
	s_waitcnt lgkmcnt(0)
	s_setprio 1
	v_mfma_f32_16x16x32_bf16 v[126:129], v[144:147], v[176:179], v[126:129]
	v_mfma_f32_16x16x32_bf16 v[122:125], v[152:155], v[176:179], v[122:125]
	v_mfma_f32_16x16x32_bf16 v[118:121], v[144:147], v[184:187], v[118:121]
	v_mfma_f32_16x16x32_bf16 v[110:113], v[152:155], v[184:187], v[110:113]
	v_mfma_f32_16x16x32_bf16 v[102:105], v[144:147], v[196:199], v[102:105]
	v_mfma_f32_16x16x32_bf16 v[94:97], v[152:155], v[196:199], v[94:97]
	v_mfma_f32_16x16x32_bf16 v[86:89], v[144:147], v[204:207], v[86:89]
	v_mfma_f32_16x16x32_bf16 v[78:81], v[152:155], v[204:207], v[78:81]
	v_mfma_f32_16x16x32_bf16 v[126:129], v[148:151], v[180:183], v[126:129]
	v_mfma_f32_16x16x32_bf16 v[122:125], v[156:159], v[180:183], v[122:125]
	v_mfma_f32_16x16x32_bf16 v[118:121], v[148:151], v[188:191], v[118:121]
	v_mfma_f32_16x16x32_bf16 v[110:113], v[156:159], v[188:191], v[110:113]
	v_mfma_f32_16x16x32_bf16 v[102:105], v[148:151], v[200:203], v[102:105]
	v_mfma_f32_16x16x32_bf16 v[94:97], v[156:159], v[200:203], v[94:97]
	v_mfma_f32_16x16x32_bf16 v[86:89], v[148:151], v[208:211], v[86:89]
	v_mfma_f32_16x16x32_bf16 v[78:81], v[156:159], v[208:211], v[78:81]
	v_mfma_f32_16x16x32_bf16 v[114:117], v[160:163], v[176:179], v[114:117]
	v_mfma_f32_16x16x32_bf16 v[106:109], v[168:171], v[176:179], v[106:109]
	v_mfma_f32_16x16x32_bf16 v[98:101], v[160:163], v[184:187], v[98:101]
	v_mfma_f32_16x16x32_bf16 v[90:93], v[168:171], v[184:187], v[90:93]
	v_mfma_f32_16x16x32_bf16 v[82:85], v[160:163], v[196:199], v[82:85]
	v_mfma_f32_16x16x32_bf16 v[74:77], v[168:171], v[196:199], v[74:77]
	v_mfma_f32_16x16x32_bf16 v[70:73], v[160:163], v[204:207], v[70:73]
	v_mfma_f32_16x16x32_bf16 v[66:69], v[168:171], v[204:207], v[66:69]
	v_mfma_f32_16x16x32_bf16 v[114:117], v[164:167], v[180:183], v[114:117]
	v_mfma_f32_16x16x32_bf16 v[106:109], v[172:175], v[180:183], v[106:109]
	v_mfma_f32_16x16x32_bf16 v[98:101], v[164:167], v[188:191], v[98:101]
	v_mfma_f32_16x16x32_bf16 v[90:93], v[172:175], v[188:191], v[90:93]
	v_mfma_f32_16x16x32_bf16 v[82:85], v[164:167], v[200:203], v[82:85]
	v_mfma_f32_16x16x32_bf16 v[74:77], v[172:175], v[200:203], v[74:77]
	v_mfma_f32_16x16x32_bf16 v[70:73], v[164:167], v[208:211], v[70:73]
	v_mfma_f32_16x16x32_bf16 v[66:69], v[172:175], v[208:211], v[66:69]
	s_setprio 0
	s_waitcnt vmcnt(8)
	s_barrier
	s_add_i32 s46, s68, s51
	v_lshl_add_u64 v[192:193], v[192:193], 0, s[10:11]
	s_mov_b32 m0, s46
	ds_read_b128 v[176:179], v143 offset:49152
	ds_read_b128 v[180:183], v143 offset:50176
	ds_read_b128 v[184:187], v143 offset:51200
	ds_read_b128 v[188:191], v143 offset:52224
	ds_read_b128 v[196:199], v143 offset:53248
	ds_read_b128 v[200:203], v143 offset:54272
	ds_read_b128 v[204:207], v143 offset:55296
	ds_read_b128 v[208:211], v143 offset:56320
	global_load_lds_dwordx4 v[192:193], off
	s_add_i32 m0, s46, 0x2000
	s_add_u32 s42, s42, 0x100080
	v_lshl_add_u64 v[192:193], v[212:213], 0, s[10:11]
	s_addc_u32 s43, s43, 0
	s_add_i32 s46, s69, s51
	global_load_lds_dwordx4 v[192:193], off
	v_lshl_add_u64 v[192:193], s[42:43], 0, v[130:131]
	s_mov_b32 m0, s46
	s_nop 0
	global_load_lds_dwordx4 v[192:193], off
	v_lshl_add_u64 v[192:193], s[42:43], 0, v[132:133]
	s_add_i32 m0, s46, 0x2000
	s_nop 0
	global_load_lds_dwordx4 v[192:193], off
	v_lshl_add_u64 v[192:193], v[214:215], 0, s[10:11]
	s_mov_b32 m0, s56
	s_nop 0
	global_load_lds_dwordx4 v[192:193], off
	v_lshl_add_u64 v[192:193], v[216:217], 0, s[10:11]
	s_mov_b32 m0, s57
	s_nop 0
	global_load_lds_dwordx4 v[192:193], off
	s_waitcnt lgkmcnt(0)
	s_setprio 1
	v_mfma_f32_16x16x32_bf16 v[62:65], v[144:147], v[176:179], v[62:65]
	v_mfma_f32_16x16x32_bf16 v[58:61], v[152:155], v[176:179], v[58:61]
	v_mfma_f32_16x16x32_bf16 v[54:57], v[144:147], v[184:187], v[54:57]
	v_mfma_f32_16x16x32_bf16 v[46:49], v[152:155], v[184:187], v[46:49]
	v_mfma_f32_16x16x32_bf16 v[38:41], v[144:147], v[196:199], v[38:41]
	v_mfma_f32_16x16x32_bf16 v[30:33], v[152:155], v[196:199], v[30:33]
	v_mfma_f32_16x16x32_bf16 v[22:25], v[144:147], v[204:207], v[22:25]
	v_mfma_f32_16x16x32_bf16 v[14:17], v[152:155], v[204:207], v[14:17]
	v_mfma_f32_16x16x32_bf16 v[62:65], v[148:151], v[180:183], v[62:65]
	v_mfma_f32_16x16x32_bf16 v[58:61], v[156:159], v[180:183], v[58:61]
	v_mfma_f32_16x16x32_bf16 v[54:57], v[148:151], v[188:191], v[54:57]
	v_mfma_f32_16x16x32_bf16 v[46:49], v[156:159], v[188:191], v[46:49]
	v_mfma_f32_16x16x32_bf16 v[38:41], v[148:151], v[200:203], v[38:41]
	v_mfma_f32_16x16x32_bf16 v[30:33], v[156:159], v[200:203], v[30:33]
	v_mfma_f32_16x16x32_bf16 v[22:25], v[148:151], v[208:211], v[22:25]
	v_mfma_f32_16x16x32_bf16 v[14:17], v[156:159], v[208:211], v[14:17]
	v_mfma_f32_16x16x32_bf16 v[50:53], v[160:163], v[176:179], v[50:53]
	v_mfma_f32_16x16x32_bf16 v[42:45], v[168:171], v[176:179], v[42:45]
	v_mfma_f32_16x16x32_bf16 v[34:37], v[160:163], v[184:187], v[34:37]
	v_mfma_f32_16x16x32_bf16 v[26:29], v[168:171], v[184:187], v[26:29]
	v_mfma_f32_16x16x32_bf16 v[18:21], v[160:163], v[196:199], v[18:21]
	v_mfma_f32_16x16x32_bf16 v[10:13], v[168:171], v[196:199], v[10:13]
	v_mfma_f32_16x16x32_bf16 v[6:9], v[160:163], v[204:207], v[6:9]
	v_mfma_f32_16x16x32_bf16 v[2:5], v[168:171], v[204:207], v[2:5]
	v_mfma_f32_16x16x32_bf16 v[50:53], v[164:167], v[180:183], v[50:53]
	v_mfma_f32_16x16x32_bf16 v[42:45], v[172:175], v[180:183], v[42:45]
	v_mfma_f32_16x16x32_bf16 v[34:37], v[164:167], v[188:191], v[34:37]
	v_mfma_f32_16x16x32_bf16 v[26:29], v[172:175], v[188:191], v[26:29]
	v_mfma_f32_16x16x32_bf16 v[18:21], v[164:167], v[200:203], v[18:21]
	v_mfma_f32_16x16x32_bf16 v[10:13], v[172:175], v[200:203], v[10:13]
	v_mfma_f32_16x16x32_bf16 v[6:9], v[164:167], v[208:211], v[6:9]
	v_mfma_f32_16x16x32_bf16 v[2:5], v[172:175], v[208:211], v[2:5]
	s_setprio 0
	s_waitcnt vmcnt(8)
	s_barrier
	s_add_i32 s67, s67, 2
	s_add_u32 s40, s40, 0x100
	s_addc_u32 s41, s41, 0
	s_add_u32 s65, s65, 0x100
	s_addc_u32 s66, s66, 0
	s_cmp_gt_u32 s67, 61
	s_cbranch_scc0 .Lkt_L_2
	s_branch .Lkt_exit_2
.Lkt_T_2:
	ds_read_b128 v[144:147], v140
	ds_read_b128 v[148:151], v140 offset:1024
	ds_read_b128 v[152:155], v140 offset:2048
	ds_read_b128 v[156:159], v140 offset:3072
	ds_read_b128 v[160:163], v142
	ds_read_b128 v[164:167], v142 offset:1024
	ds_read_b128 v[168:171], v142 offset:2048
	ds_read_b128 v[172:175], v142 offset:3072
	s_add_u32 s42, s40, 0xfff00080
	s_addc_u32 s43, s41, -1
	s_cmp_eq_u32 s67, 60
	s_cselect_b32 s47, s27, s43
	s_cselect_b32 s46, s63, s42
	s_cselect_b32 s43, s25, s66
	s_cselect_b32 s42, s64, s65
	v_lshl_add_u64 v[192:193], s[40:41], 0, v[134:135]
	s_add_i32 m0, s29, 0xc000
	ds_read_b128 v[176:179], v143
	ds_read_b128 v[180:183], v143 offset:1024
	ds_read_b128 v[184:187], v143 offset:2048
	ds_read_b128 v[188:191], v143 offset:3072
	ds_read_b128 v[196:199], v143 offset:4096
	ds_read_b128 v[200:203], v143 offset:5120
	ds_read_b128 v[204:207], v143 offset:6144
	ds_read_b128 v[208:211], v143 offset:7168
	global_load_lds_dwordx4 v[192:193], off
	v_lshl_add_u64 v[192:193], s[40:41], 0, v[136:137]
	s_add_i32 m0, s29, 0xe000
	s_nop 0
	global_load_lds_dwordx4 v[192:193], off
	s_waitcnt vmcnt(8)
	s_waitcnt lgkmcnt(0)
	s_barrier
	s_setprio 2
	v_mfma_f32_16x16x32_bf16 v[126:129], v[144:147], v[176:179], v[126:129]
	v_mfma_f32_16x16x32_bf16 v[122:125], v[152:155], v[176:179], v[122:125]
	v_mfma_f32_16x16x32_bf16 v[118:121], v[144:147], v[184:187], v[118:121]
	v_mfma_f32_16x16x32_bf16 v[110:113], v[152:155], v[184:187], v[110:113]
	v_mfma_f32_16x16x32_bf16 v[102:105], v[144:147], v[196:199], v[102:105]
	v_mfma_f32_16x16x32_bf16 v[94:97], v[152:155], v[196:199], v[94:97]
	v_mfma_f32_16x16x32_bf16 v[86:89], v[144:147], v[204:207], v[86:89]
	v_mfma_f32_16x16x32_bf16 v[78:81], v[152:155], v[204:207], v[78:81]
	v_mfma_f32_16x16x32_bf16 v[126:129], v[148:151], v[180:183], v[126:129]
	v_mfma_f32_16x16x32_bf16 v[122:125], v[156:159], v[180:183], v[122:125]
	v_mfma_f32_16x16x32_bf16 v[118:121], v[148:151], v[188:191], v[118:121]
	v_mfma_f32_16x16x32_bf16 v[110:113], v[156:159], v[188:191], v[110:113]
	v_mfma_f32_16x16x32_bf16 v[102:105], v[148:151], v[200:203], v[102:105]
	v_mfma_f32_16x16x32_bf16 v[94:97], v[156:159], v[200:203], v[94:97]
	v_mfma_f32_16x16x32_bf16 v[86:89], v[148:151], v[208:211], v[86:89]
	v_mfma_f32_16x16x32_bf16 v[78:81], v[156:159], v[208:211], v[78:81]
	v_mfma_f32_16x16x32_bf16 v[114:117], v[160:163], v[176:179], v[114:117]
	v_mfma_f32_16x16x32_bf16 v[106:109], v[168:171], v[176:179], v[106:109]
	v_mfma_f32_16x16x32_bf16 v[98:101], v[160:163], v[184:187], v[98:101]
	v_mfma_f32_16x16x32_bf16 v[90:93], v[168:171], v[184:187], v[90:93]
	v_mfma_f32_16x16x32_bf16 v[82:85], v[160:163], v[196:199], v[82:85]
	v_mfma_f32_16x16x32_bf16 v[74:77], v[168:171], v[196:199], v[74:77]
	v_mfma_f32_16x16x32_bf16 v[70:73], v[160:163], v[204:207], v[70:73]
	v_mfma_f32_16x16x32_bf16 v[66:69], v[168:171], v[204:207], v[66:69]
	v_mfma_f32_16x16x32_bf16 v[114:117], v[164:167], v[180:183], v[114:117]
	v_mfma_f32_16x16x32_bf16 v[106:109], v[172:175], v[180:183], v[106:109]
	v_mfma_f32_16x16x32_bf16 v[98:101], v[164:167], v[188:191], v[98:101]
	v_mfma_f32_16x16x32_bf16 v[90:93], v[172:175], v[188:191], v[90:93]
	v_mfma_f32_16x16x32_bf16 v[82:85], v[164:167], v[200:203], v[82:85]
	v_mfma_f32_16x16x32_bf16 v[74:77], v[172:175], v[200:203], v[74:77]
	v_mfma_f32_16x16x32_bf16 v[70:73], v[164:167], v[208:211], v[70:73]
	v_mfma_f32_16x16x32_bf16 v[66:69], v[172:175], v[208:211], v[66:69]
	s_setprio 0
	s_add_i32 s68, s59, s51
	v_lshl_add_u64 v[192:193], s[42:43], 0, v[130:131]
	s_mov_b32 m0, s68
	ds_read_b128 v[176:179], v143 offset:16384
	ds_read_b128 v[180:183], v143 offset:17408
	ds_read_b128 v[184:187], v143 offset:18432
	ds_read_b128 v[188:191], v143 offset:19456
	ds_read_b128 v[196:199], v143 offset:20480
	ds_read_b128 v[200:203], v143 offset:21504
	ds_read_b128 v[204:207], v143 offset:22528
	ds_read_b128 v[208:211], v143 offset:23552
	global_load_lds_dwordx4 v[192:193], off
	s_add_i32 m0, s68, 0x2000
	s_add_u32 s68, s42, 0x100000
	v_lshl_add_u64 v[212:213], s[42:43], 0, v[132:133]
	s_addc_u32 s69, s43, 0
	s_add_i32 s70, s60, s51
	global_load_lds_dwordx4 v[212:213], off
	v_lshl_add_u64 v[214:215], s[68:69], 0, v[130:131]
	s_mov_b32 m0, s70
	v_lshl_add_u64 v[216:217], s[46:47], 0, v[132:133]
	global_load_lds_dwordx4 v[214:215], off
	v_lshl_add_u64 v[214:215], s[68:69], 0, v[132:133]
	s_add_i32 m0, s70, 0x2000
	s_nop 0
	global_load_lds_dwordx4 v[214:215], off
	v_lshl_add_u64 v[214:215], s[46:47], 0, v[130:131]
	s_mov_b32 m0, s29
	s_nop 0
	global_load_lds_dwordx4 v[214:215], off
	s_mov_b32 m0, s52
	s_nop 0
	global_load_lds_dwordx4 v[216:217], off
	s_waitcnt vmcnt(8)
	s_waitcnt lgkmcnt(0)
	s_barrier
	s_setprio 2
	v_mfma_f32_16x16x32_bf16 v[62:65], v[144:147], v[176:179], v[62:65]
	v_mfma_f32_16x16x32_bf16 v[58:61], v[152:155], v[176:179], v[58:61]
	v_mfma_f32_16x16x32_bf16 v[54:57], v[144:147], v[184:187], v[54:57]
	v_mfma_f32_16x16x32_bf16 v[46:49], v[152:155], v[184:187], v[46:49]
	v_mfma_f32_16x16x32_bf16 v[38:41], v[144:147], v[196:199], v[38:41]
	v_mfma_f32_16x16x32_bf16 v[30:33], v[152:155], v[196:199], v[30:33]
	v_mfma_f32_16x16x32_bf16 v[22:25], v[144:147], v[204:207], v[22:25]
	v_mfma_f32_16x16x32_bf16 v[14:17], v[152:155], v[204:207], v[14:17]
	v_mfma_f32_16x16x32_bf16 v[62:65], v[148:151], v[180:183], v[62:65]
	v_mfma_f32_16x16x32_bf16 v[58:61], v[156:159], v[180:183], v[58:61]
	v_mfma_f32_16x16x32_bf16 v[54:57], v[148:151], v[188:191], v[54:57]
	v_mfma_f32_16x16x32_bf16 v[46:49], v[156:159], v[188:191], v[46:49]
	v_mfma_f32_16x16x32_bf16 v[38:41], v[148:151], v[200:203], v[38:41]
	v_mfma_f32_16x16x32_bf16 v[30:33], v[156:159], v[200:203], v[30:33]
	v_mfma_f32_16x16x32_bf16 v[22:25], v[148:151], v[208:211], v[22:25]
	v_mfma_f32_16x16x32_bf16 v[14:17], v[156:159], v[208:211], v[14:17]
	v_mfma_f32_16x16x32_bf16 v[50:53], v[160:163], v[176:179], v[50:53]
	v_mfma_f32_16x16x32_bf16 v[42:45], v[168:171], v[176:179], v[42:45]
	v_mfma_f32_16x16x32_bf16 v[34:37], v[160:163], v[184:187], v[34:37]
	v_mfma_f32_16x16x32_bf16 v[26:29], v[168:171], v[184:187], v[26:29]
	v_mfma_f32_16x16x32_bf16 v[18:21], v[160:163], v[196:199], v[18:21]
	v_mfma_f32_16x16x32_bf16 v[10:13], v[168:171], v[196:199], v[10:13]
	v_mfma_f32_16x16x32_bf16 v[6:9], v[160:163], v[204:207], v[6:9]
	v_mfma_f32_16x16x32_bf16 v[2:5], v[168:171], v[204:207], v[2:5]
	v_mfma_f32_16x16x32_bf16 v[50:53], v[164:167], v[180:183], v[50:53]
	v_mfma_f32_16x16x32_bf16 v[42:45], v[172:175], v[180:183], v[42:45]
	v_mfma_f32_16x16x32_bf16 v[34:37], v[164:167], v[188:191], v[34:37]
	v_mfma_f32_16x16x32_bf16 v[26:29], v[172:175], v[188:191], v[26:29]
	v_mfma_f32_16x16x32_bf16 v[18:21], v[164:167], v[200:203], v[18:21]
	v_mfma_f32_16x16x32_bf16 v[10:13], v[172:175], v[200:203], v[10:13]
	v_mfma_f32_16x16x32_bf16 v[6:9], v[164:167], v[208:211], v[6:9]
	v_mfma_f32_16x16x32_bf16 v[2:5], v[172:175], v[208:211], v[2:5]
	s_setprio 0
	s_add_i32 s68, 0, 0x18000
	s_add_i32 s69, 0, 0x1c000
	v_add_u32_e32 v156, s68, v139
	v_add_u32_e32 v172, s69, v139
	ds_read_b128 v[144:147], v156
	ds_read_b128 v[148:151], v156 offset:1024
	ds_read_b128 v[152:155], v156 offset:2048
	ds_read_b128 v[156:159], v156 offset:3072
	ds_read_b128 v[160:163], v172
	ds_read_b128 v[164:167], v172 offset:1024
	ds_read_b128 v[168:171], v172 offset:2048
	ds_read_b128 v[172:175], v172 offset:3072
	s_add_u32 s46, s46, 0x100000
	s_addc_u32 s47, s47, 0
	s_mov_b32 m0, s53
	v_lshl_add_u64 v[218:219], s[46:47], 0, v[130:131]
	ds_read_b128 v[176:179], v143 offset:32768
	ds_read_b128 v[180:183], v143 offset:33792
	ds_read_b128 v[184:187], v143 offset:34816
	ds_read_b128 v[188:191], v143 offset:35840
	ds_read_b128 v[196:199], v143 offset:36864
	ds_read_b128 v[200:203], v143 offset:37888
	ds_read_b128 v[204:207], v143 offset:38912
	ds_read_b128 v[208:211], v143 offset:39936
	global_load_lds_dwordx4 v[218:219], off
	v_lshl_add_u64 v[218:219], s[46:47], 0, v[132:133]
	s_mov_b32 m0, s54
	s_nop 0
	global_load_lds_dwordx4 v[218:219], off
	s_waitcnt vmcnt(8)
	s_waitcnt lgkmcnt(0)
	s_barrier
	s_setprio 2
	v_mfma_f32_16x16x32_bf16 v[126:129], v[144:147], v[176:179], v[126:129]
	v_mfma_f32_16x16x32_bf16 v[122:125], v[152:155], v[176:179], v[122:125]
	v_mfma_f32_16x16x32_bf16 v[118:121], v[144:147], v[184:187], v[118:121]
	v_mfma_f32_16x16x32_bf16 v[110:113], v[152:155], v[184:187], v[110:113]
	v_mfma_f32_16x16x32_bf16 v[102:105], v[144:147], v[196:199], v[102:105]
	v_mfma_f32_16x16x32_bf16 v[94:97], v[152:155], v[196:199], v[94:97]
	v_mfma_f32_16x16x32_bf16 v[86:89], v[144:147], v[204:207], v[86:89]
	v_mfma_f32_16x16x32_bf16 v[78:81], v[152:155], v[204:207], v[78:81]
	v_mfma_f32_16x16x32_bf16 v[126:129], v[148:151], v[180:183], v[126:129]
	v_mfma_f32_16x16x32_bf16 v[122:125], v[156:159], v[180:183], v[122:125]
	v_mfma_f32_16x16x32_bf16 v[118:121], v[148:151], v[188:191], v[118:121]
	v_mfma_f32_16x16x32_bf16 v[110:113], v[156:159], v[188:191], v[110:113]
	v_mfma_f32_16x16x32_bf16 v[102:105], v[148:151], v[200:203], v[102:105]
	v_mfma_f32_16x16x32_bf16 v[94:97], v[156:159], v[200:203], v[94:97]
	v_mfma_f32_16x16x32_bf16 v[86:89], v[148:151], v[208:211], v[86:89]
	v_mfma_f32_16x16x32_bf16 v[78:81], v[156:159], v[208:211], v[78:81]
	v_mfma_f32_16x16x32_bf16 v[114:117], v[160:163], v[176:179], v[114:117]
	v_mfma_f32_16x16x32_bf16 v[106:109], v[168:171], v[176:179], v[106:109]
	v_mfma_f32_16x16x32_bf16 v[98:101], v[160:163], v[184:187], v[98:101]
	v_mfma_f32_16x16x32_bf16 v[90:93], v[168:171], v[184:187], v[90:93]
	v_mfma_f32_16x16x32_bf16 v[82:85], v[160:163], v[196:199], v[82:85]
	v_mfma_f32_16x16x32_bf16 v[74:77], v[168:171], v[196:199], v[74:77]
	v_mfma_f32_16x16x32_bf16 v[70:73], v[160:163], v[204:207], v[70:73]
	v_mfma_f32_16x16x32_bf16 v[66:69], v[168:171], v[204:207], v[66:69]
	v_mfma_f32_16x16x32_bf16 v[114:117], v[164:167], v[180:183], v[114:117]
	v_mfma_f32_16x16x32_bf16 v[106:109], v[172:175], v[180:183], v[106:109]
	v_mfma_f32_16x16x32_bf16 v[98:101], v[164:167], v[188:191], v[98:101]
	v_mfma_f32_16x16x32_bf16 v[90:93], v[172:175], v[188:191], v[90:93]
	v_mfma_f32_16x16x32_bf16 v[82:85], v[164:167], v[200:203], v[82:85]
	v_mfma_f32_16x16x32_bf16 v[74:77], v[172:175], v[200:203], v[74:77]
	v_mfma_f32_16x16x32_bf16 v[70:73], v[164:167], v[208:211], v[70:73]
	v_mfma_f32_16x16x32_bf16 v[66:69], v[172:175], v[208:211], v[66:69]
	s_setprio 0
	s_add_i32 s46, s68, s51
	v_lshl_add_u64 v[192:193], v[192:193], 0, s[10:11]
	s_mov_b32 m0, s46
	ds_read_b128 v[176:179], v143 offset:49152
	ds_read_b128 v[180:183], v143 offset:50176
	ds_read_b128 v[184:187], v143 offset:51200
	ds_read_b128 v[188:191], v143 offset:52224
	ds_read_b128 v[196:199], v143 offset:53248
	ds_read_b128 v[200:203], v143 offset:54272
	ds_read_b128 v[204:207], v143 offset:55296
	ds_read_b128 v[208:211], v143 offset:56320
	global_load_lds_dwordx4 v[192:193], off
	s_add_i32 m0, s46, 0x2000
	s_add_u32 s42, s42, 0x100080
	v_lshl_add_u64 v[192:193], v[212:213], 0, s[10:11]
	s_addc_u32 s43, s43, 0
	s_add_i32 s46, s69, s51
	global_load_lds_dwordx4 v[192:193], off
	v_lshl_add_u64 v[192:193], s[42:43], 0, v[130:131]
	s_mov_b32 m0, s46
	s_nop 0
	global_load_lds_dwordx4 v[192:193], off
	v_lshl_add_u64 v[192:193], s[42:43], 0, v[132:133]
	s_add_i32 m0, s46, 0x2000
	s_nop 0
	global_load_lds_dwordx4 v[192:193], off
	v_lshl_add_u64 v[192:193], v[214:215], 0, s[10:11]
	s_mov_b32 m0, s56
	s_nop 0
	global_load_lds_dwordx4 v[192:193], off
	v_lshl_add_u64 v[192:193], v[216:217], 0, s[10:11]
	s_mov_b32 m0, s57
	s_nop 0
	global_load_lds_dwordx4 v[192:193], off
	s_waitcnt vmcnt(8)
	s_waitcnt lgkmcnt(0)
	s_barrier
	s_setprio 2
	v_mfma_f32_16x16x32_bf16 v[62:65], v[144:147], v[176:179], v[62:65]
	v_mfma_f32_16x16x32_bf16 v[58:61], v[152:155], v[176:179], v[58:61]
	v_mfma_f32_16x16x32_bf16 v[54:57], v[144:147], v[184:187], v[54:57]
	v_mfma_f32_16x16x32_bf16 v[46:49], v[152:155], v[184:187], v[46:49]
	v_mfma_f32_16x16x32_bf16 v[38:41], v[144:147], v[196:199], v[38:41]
	v_mfma_f32_16x16x32_bf16 v[30:33], v[152:155], v[196:199], v[30:33]
	v_mfma_f32_16x16x32_bf16 v[22:25], v[144:147], v[204:207], v[22:25]
	v_mfma_f32_16x16x32_bf16 v[14:17], v[152:155], v[204:207], v[14:17]
	v_mfma_f32_16x16x32_bf16 v[62:65], v[148:151], v[180:183], v[62:65]
	v_mfma_f32_16x16x32_bf16 v[58:61], v[156:159], v[180:183], v[58:61]
	v_mfma_f32_16x16x32_bf16 v[54:57], v[148:151], v[188:191], v[54:57]
	v_mfma_f32_16x16x32_bf16 v[46:49], v[156:159], v[188:191], v[46:49]
	v_mfma_f32_16x16x32_bf16 v[38:41], v[148:151], v[200:203], v[38:41]
	v_mfma_f32_16x16x32_bf16 v[30:33], v[156:159], v[200:203], v[30:33]
	v_mfma_f32_16x16x32_bf16 v[22:25], v[148:151], v[208:211], v[22:25]
	v_mfma_f32_16x16x32_bf16 v[14:17], v[156:159], v[208:211], v[14:17]
	v_mfma_f32_16x16x32_bf16 v[50:53], v[160:163], v[176:179], v[50:53]
	v_mfma_f32_16x16x32_bf16 v[42:45], v[168:171], v[176:179], v[42:45]
	v_mfma_f32_16x16x32_bf16 v[34:37], v[160:163], v[184:187], v[34:37]
	v_mfma_f32_16x16x32_bf16 v[26:29], v[168:171], v[184:187], v[26:29]
	v_mfma_f32_16x16x32_bf16 v[18:21], v[160:163], v[196:199], v[18:21]
	v_mfma_f32_16x16x32_bf16 v[10:13], v[168:171], v[196:199], v[10:13]
	v_mfma_f32_16x16x32_bf16 v[6:9], v[160:163], v[204:207], v[6:9]
	v_mfma_f32_16x16x32_bf16 v[2:5], v[168:171], v[204:207], v[2:5]
	v_mfma_f32_16x16x32_bf16 v[50:53], v[164:167], v[180:183], v[50:53]
	v_mfma_f32_16x16x32_bf16 v[42:45], v[172:175], v[180:183], v[42:45]
	v_mfma_f32_16x16x32_bf16 v[34:37], v[164:167], v[188:191], v[34:37]
	v_mfma_f32_16x16x32_bf16 v[26:29], v[172:175], v[188:191], v[26:29]
	v_mfma_f32_16x16x32_bf16 v[18:21], v[164:167], v[200:203], v[18:21]
	v_mfma_f32_16x16x32_bf16 v[10:13], v[172:175], v[200:203], v[10:13]
	v_mfma_f32_16x16x32_bf16 v[6:9], v[164:167], v[208:211], v[6:9]
	v_mfma_f32_16x16x32_bf16 v[2:5], v[172:175], v[208:211], v[2:5]
	s_setprio 0
	s_add_i32 s67, s67, 2
	s_add_u32 s40, s40, 0x100
	s_addc_u32 s41, s41, 0
	s_add_u32 s65, s65, 0x100
	s_addc_u32 s66, s66, 0
	s_cmp_gt_u32 s67, 61
	s_cbranch_scc0 .Lkt_T_2
	s_nop 7

.LBB0_338:
	s_cmp_lt_i32 s62, 2
	v_lshl_or_b32 v146, s62, 8, v138
	s_cselect_b32 s25, s61, 0x8800000
	s_cselect_b32 s27, 0, 0xfffffe00
	v_lshl_add_u32 v144, s28, 8, v141
	s_add_u32 s40, s36, s25
	v_add_u32_e32 v148, s27, v146
	s_addc_u32 s41, s37, 0
	v_ashrrev_i32_e32 v149, 31, v148
	v_ashrrev_i32_e32 v145, 31, v144
	v_lshl_add_u64 v[148:149], v[148:149], 2, s[40:41]
	v_lshlrev_b64 v[150:151], 11, v[144:145]
	v_ashrrev_i32_e32 v147, 31, v146
	v_lshl_add_u64 v[152:153], v[148:149], 0, v[150:151]
	global_store_dwordx4 v[152:153], v[126:129], off
	v_lshlrev_b64 v[146:147], 1, v[146:147]
	s_andn2_b64 vcc, exec, s[22:23]
	v_cvt_pk_bf16_f32 v126, v126, v127
	v_cvt_pk_bf16_f32 v127, v128, v129
	v_lshl_add_u64 v[128:129], s[8:9], 0, v[150:151]
	v_lshl_add_u64 v[128:129], v[128:129], 0, v[146:147]
	global_store_dwordx2 v[128:129], v[126:127], off
	global_store_dwordx4 v[152:153], v[122:125], off offset:64
	s_mov_b64 s[22:23], -1
	s_nop 0
	v_cvt_pk_bf16_f32 v122, v122, v123
	v_cvt_pk_bf16_f32 v123, v124, v125
	global_store_dwordx2 v[128:129], v[122:123], off offset:32
	global_store_dwordx4 v[152:153], v[114:117], off offset:512
	s_nop 1
	v_cvt_pk_bf16_f32 v114, v114, v115
	v_cvt_pk_bf16_f32 v115, v116, v117
	global_store_dwordx2 v[128:129], v[114:115], off offset:256
	global_store_dwordx4 v[152:153], v[106:109], off offset:576
	v_cvt_pk_bf16_f32 v114, v118, v119
	v_cvt_pk_bf16_f32 v115, v120, v121
	v_cvt_pk_bf16_f32 v106, v106, v107
	v_cvt_pk_bf16_f32 v107, v108, v109
	global_store_dwordx2 v[128:129], v[106:107], off offset:288
	v_or_b32_e32 v106, 16, v144
	v_ashrrev_i32_e32 v107, 31, v106
	v_lshlrev_b64 v[106:107], 11, v[106:107]
	v_lshl_add_u64 v[108:109], v[148:149], 0, v[106:107]
	v_lshl_add_u64 v[106:107], s[8:9], 0, v[106:107]
	v_lshl_add_u64 v[106:107], v[106:107], 0, v[146:147]
	global_store_dwordx4 v[108:109], v[118:121], off
	global_store_dwordx2 v[106:107], v[114:115], off
	global_store_dwordx4 v[108:109], v[110:113], off offset:64
	s_nop 1
	v_cvt_pk_bf16_f32 v110, v110, v111
	v_cvt_pk_bf16_f32 v111, v112, v113
	global_store_dwordx2 v[106:107], v[110:111], off offset:32
	global_store_dwordx4 v[108:109], v[98:101], off offset:512
	s_nop 1
	v_cvt_pk_bf16_f32 v98, v98, v99
	v_cvt_pk_bf16_f32 v99, v100, v101
	global_store_dwordx2 v[106:107], v[98:99], off offset:256
	global_store_dwordx4 v[108:109], v[90:93], off offset:576
	v_cvt_pk_bf16_f32 v98, v102, v103
	v_cvt_pk_bf16_f32 v99, v104, v105
	v_cvt_pk_bf16_f32 v90, v90, v91
	v_cvt_pk_bf16_f32 v91, v92, v93
	global_store_dwordx2 v[106:107], v[90:91], off offset:288
	v_or_b32_e32 v90, 32, v144
	v_ashrrev_i32_e32 v91, 31, v90
	v_lshlrev_b64 v[90:91], 11, v[90:91]
	v_lshl_add_u64 v[92:93], v[148:149], 0, v[90:91]
	v_lshl_add_u64 v[90:91], s[8:9], 0, v[90:91]
	v_lshl_add_u64 v[90:91], v[90:91], 0, v[146:147]
	global_store_dwordx4 v[92:93], v[102:105], off
	global_store_dwordx2 v[90:91], v[98:99], off
	global_store_dwordx4 v[92:93], v[94:97], off offset:64
	s_nop 1
	v_cvt_pk_bf16_f32 v94, v94, v95
	v_cvt_pk_bf16_f32 v95, v96, v97
	global_store_dwordx2 v[90:91], v[94:95], off offset:32
	global_store_dwordx4 v[92:93], v[82:85], off offset:512
	s_nop 1
	v_cvt_pk_bf16_f32 v82, v82, v83
	v_cvt_pk_bf16_f32 v83, v84, v85
	global_store_dwordx2 v[90:91], v[82:83], off offset:256
	global_store_dwordx4 v[92:93], v[74:77], off offset:576
	v_cvt_pk_bf16_f32 v82, v86, v87
	v_cvt_pk_bf16_f32 v83, v88, v89
	v_cvt_pk_bf16_f32 v74, v74, v75
	v_cvt_pk_bf16_f32 v75, v76, v77
	global_store_dwordx2 v[90:91], v[74:75], off offset:288
	v_or_b32_e32 v74, 48, v144
	v_ashrrev_i32_e32 v75, 31, v74
	v_lshlrev_b64 v[74:75], 11, v[74:75]
	v_lshl_add_u64 v[76:77], v[148:149], 0, v[74:75]
	v_lshl_add_u64 v[74:75], s[8:9], 0, v[74:75]
	v_lshl_add_u64 v[74:75], v[74:75], 0, v[146:147]
	global_store_dwordx4 v[76:77], v[86:89], off
	global_store_dwordx2 v[74:75], v[82:83], off
	global_store_dwordx4 v[76:77], v[78:81], off offset:64
	s_nop 1
	v_cvt_pk_bf16_f32 v78, v78, v79
	v_cvt_pk_bf16_f32 v79, v80, v81
	global_store_dwordx2 v[74:75], v[78:79], off offset:32
	global_store_dwordx4 v[76:77], v[70:73], off offset:512
	s_nop 1
	v_cvt_pk_bf16_f32 v70, v70, v71
	v_cvt_pk_bf16_f32 v71, v72, v73
	global_store_dwordx2 v[74:75], v[70:71], off offset:256
	global_store_dwordx4 v[76:77], v[66:69], off offset:576
	s_nop 1
	v_cvt_pk_bf16_f32 v66, v66, v67
	v_cvt_pk_bf16_f32 v67, v68, v69
	global_store_dwordx2 v[74:75], v[66:67], off offset:288
	v_lshl_add_u64 v[66:67], v[150:151], 0, s[14:15]
	v_lshl_add_u64 v[68:69], v[148:149], 0, v[66:67]
	global_store_dwordx4 v[68:69], v[62:65], off
	s_nop 1
	v_cvt_pk_bf16_f32 v62, v62, v63
	v_cvt_pk_bf16_f32 v63, v64, v65
	v_lshl_add_u64 v[64:65], s[8:9], 0, v[66:67]
	v_lshl_add_u64 v[64:65], v[64:65], 0, v[146:147]
	global_store_dwordx2 v[64:65], v[62:63], off
	global_store_dwordx4 v[68:69], v[58:61], off offset:64
	s_nop 1
	v_cvt_pk_bf16_f32 v58, v58, v59
	v_cvt_pk_bf16_f32 v59, v60, v61
	global_store_dwordx2 v[64:65], v[58:59], off offset:32
	global_store_dwordx4 v[68:69], v[50:53], off offset:512
	s_nop 1
	v_cvt_pk_bf16_f32 v50, v50, v51
	v_cvt_pk_bf16_f32 v51, v52, v53
	global_store_dwordx2 v[64:65], v[50:51], off offset:256
	global_store_dwordx4 v[68:69], v[42:45], off offset:576
	v_cvt_pk_bf16_f32 v50, v54, v55
	v_cvt_pk_bf16_f32 v51, v56, v57
	v_cvt_pk_bf16_f32 v42, v42, v43
	v_cvt_pk_bf16_f32 v43, v44, v45
	global_store_dwordx2 v[64:65], v[42:43], off offset:288
	v_lshl_add_u64 v[42:43], v[150:151], 0, s[16:17]
	v_lshl_add_u64 v[44:45], v[148:149], 0, v[42:43]
	v_lshl_add_u64 v[42:43], s[8:9], 0, v[42:43]
	v_lshl_add_u64 v[42:43], v[42:43], 0, v[146:147]
	global_store_dwordx4 v[44:45], v[54:57], off
	global_store_dwordx2 v[42:43], v[50:51], off
	global_store_dwordx4 v[44:45], v[46:49], off offset:64
	s_nop 1
	v_cvt_pk_bf16_f32 v46, v46, v47
	v_cvt_pk_bf16_f32 v47, v48, v49
	global_store_dwordx2 v[42:43], v[46:47], off offset:32
	global_store_dwordx4 v[44:45], v[34:37], off offset:512
	s_nop 1
	v_cvt_pk_bf16_f32 v34, v34, v35
	v_cvt_pk_bf16_f32 v35, v36, v37
	global_store_dwordx2 v[42:43], v[34:35], off offset:256
	global_store_dwordx4 v[44:45], v[26:29], off offset:576
	v_cvt_pk_bf16_f32 v34, v38, v39
	v_cvt_pk_bf16_f32 v35, v40, v41
	v_cvt_pk_bf16_f32 v26, v26, v27
	v_cvt_pk_bf16_f32 v27, v28, v29
	global_store_dwordx2 v[42:43], v[26:27], off offset:288
	v_lshl_add_u64 v[26:27], v[150:151], 0, s[18:19]
	v_lshl_add_u64 v[28:29], v[148:149], 0, v[26:27]
	v_lshl_add_u64 v[26:27], s[8:9], 0, v[26:27]
	v_lshl_add_u64 v[26:27], v[26:27], 0, v[146:147]
	global_store_dwordx4 v[28:29], v[38:41], off
	global_store_dwordx2 v[26:27], v[34:35], off
	global_store_dwordx4 v[28:29], v[30:33], off offset:64
	s_nop 1
	v_cvt_pk_bf16_f32 v30, v30, v31
	v_cvt_pk_bf16_f32 v31, v32, v33
	global_store_dwordx2 v[26:27], v[30:31], off offset:32
	global_store_dwordx4 v[28:29], v[18:21], off offset:512
	s_nop 1
	v_cvt_pk_bf16_f32 v18, v18, v19
	v_cvt_pk_bf16_f32 v19, v20, v21
	global_store_dwordx2 v[26:27], v[18:19], off offset:256
	global_store_dwordx4 v[28:29], v[10:13], off offset:576
	v_cvt_pk_bf16_f32 v18, v22, v23
	v_cvt_pk_bf16_f32 v19, v24, v25
	v_cvt_pk_bf16_f32 v10, v10, v11
	v_cvt_pk_bf16_f32 v11, v12, v13
	global_store_dwordx2 v[26:27], v[10:11], off offset:288
	v_lshl_add_u64 v[10:11], v[150:151], 0, s[20:21]
	v_lshl_add_u64 v[12:13], v[148:149], 0, v[10:11]
	v_lshl_add_u64 v[10:11], s[8:9], 0, v[10:11]
	v_lshl_add_u64 v[10:11], v[10:11], 0, v[146:147]
	global_store_dwordx4 v[12:13], v[22:25], off
	global_store_dwordx2 v[10:11], v[18:19], off
	global_store_dwordx4 v[12:13], v[14:17], off offset:64
	s_nop 1
	v_cvt_pk_bf16_f32 v14, v14, v15
	v_cvt_pk_bf16_f32 v15, v16, v17
	global_store_dwordx2 v[10:11], v[14:15], off offset:32
	global_store_dwordx4 v[12:13], v[6:9], off offset:512
	s_nop 1
	v_cvt_pk_bf16_f32 v6, v6, v7
	v_cvt_pk_bf16_f32 v7, v8, v9
	global_store_dwordx2 v[10:11], v[6:7], off offset:256
	global_store_dwordx4 v[12:13], v[2:5], off offset:576
	s_nop 1
	v_cvt_pk_bf16_f32 v2, v2, v3
	v_cvt_pk_bf16_f32 v3, v4, v5
	global_store_dwordx2 v[10:11], v[2:3], off offset:288
	s_cbranch_vccnz .LBB0_327
	s_andn2_b64 vcc, exec, s[6:7]
	s_cbranch_vccnz .LBB0_326
	s_branch .LBB0_326

.LBB0_647:
	s_lshl_b32 s10, s10, 5
	s_and_b32 s20, s10, 0x60
	s_lshl_b32 s15, s7, 13
	s_lshl_b32 s21, s20, 7
	s_add_u32 s10, s38, 0x43e00000
	s_mov_b64 s[12:13], 0x80
	s_addc_u32 s11, s39, 0
	s_add_i32 m0, s17, 0x18000
	v_lshl_add_u64 v[8:9], v[8:9], 0, s[12:13]
	s_waitcnt vmcnt(2)
	s_barrier
	global_load_lds_dwordx4 v[8:9], off
	v_lshl_add_u64 v[6:7], v[6:7], 0, s[12:13]
	s_add_i32 m0, s17, 0x1a000
	s_add_i32 s47, s17, 0x8000
	s_add_i32 s48, s17, 0xa000
	global_load_lds_dwordx4 v[6:7], off
	v_lshl_add_u64 v[2:3], v[2:3], 0, s[12:13]
	s_mov_b32 m0, s47
	s_add_u32 s18, s28, 0x100080
	global_load_lds_dwordx4 v[2:3], off
	v_lshl_add_u64 v[2:3], v[4:5], 0, s[12:13]
	s_mov_b32 m0, s48
	s_addc_u32 s19, s29, 0
	global_load_lds_dwordx4 v[2:3], off
	s_add_i32 m0, s17, 0x1c000
	v_lshl_add_u64 v[2:3], s[18:19], 0, v[134:135]
	global_load_lds_dwordx4 v[2:3], off
	v_lshl_add_u64 v[2:3], s[18:19], 0, v[136:137]
	s_add_i32 m0, s17, 0x1e000
	s_sext_i32_i8 s53, s6
	global_load_lds_dwordx4 v[2:3], off
	v_lshrrev_b32_e32 v2, 1, v0
	v_and_b32_e32 v2, 24, v2
	v_lshlrev_b32_e32 v3, 6, v1
	v_lshlrev_b32_e32 v4, 1, v2
	s_movk_i32 s6, 0x3c0
	v_and_or_b32 v3, v3, s6, v4
	v_or_b32_e32 v4, v4, v151
	v_or_b32_e32 v154, s20, v2
	v_lshlrev_b32_e32 v2, 10, v0
	v_bitop3_b32 v153, s21, v4, v150 bitop3:0xf6
	v_and_b32_e32 v2, 0x60000, v2
	v_lshlrev_b32_e32 v4, 13, v148
	v_or3_b32 v2, v146, v2, v4
	v_lshlrev_b32_e32 v5, 2, v1
	v_add_u32_e32 v138, v2, v147
	v_lshlrev_b32_e32 v2, 6, v149
	v_and_b32_e32 v5, 32, v5
	s_waitcnt vmcnt(6)
	s_cmpk_lt_u32 s14, 0x100
	v_and_b32_e32 v2, 0xe0000, v2
	v_bitop3_b32 v3, v3, s15, v5 bitop3:0xde
	s_cselect_b64 s[14:15], -1, 0
	v_or3_b32 v2, v146, v2, v4
	s_add_i32 s50, 0, 0x10000
	s_add_i32 s51, 0, 0x14000
	v_lshl_or_b32 v152, s7, 6, v1
	s_ashr_i32 s49, s44, 31
	v_mov_b32_e32 v139, v135
	v_add_u32_e32 v140, v2, v147
	v_mov_b32_e32 v141, v135
	v_mov_b64_e32 v[142:143], 0x294
	v_mov_b64_e32 v[144:145], 0x293
	v_add_u32_e32 v155, s50, v153
	v_add_u32_e32 v156, s51, v153
	v_add_u32_e32 v157, 0, v3
	s_movk_i32 s52, 0x2800
	s_waitcnt vmcnt(0)
	s_branch .LBB0_650

.Lkt_L_3:
	ds_read_b128 v[158:161], v155
	ds_read_b128 v[162:165], v155 offset:1024
	ds_read_b128 v[166:169], v155 offset:2048
	ds_read_b128 v[170:173], v155 offset:3072
	ds_read_b128 v[174:177], v156
	ds_read_b128 v[178:181], v156 offset:1024
	ds_read_b128 v[182:185], v156 offset:2048
	ds_read_b128 v[186:189], v156 offset:3072
	s_add_u32 s28, s26, 0xfff00080
	s_addc_u32 s29, s27, -1
	s_cmp_eq_u32 s58, 60
	s_cselect_b32 s31, s21, s29
	s_cselect_b32 s30, s54, s28
	s_cselect_b32 s29, s19, s57
	s_cselect_b32 s28, s55, s56
	v_lshl_add_u64 v[224:225], s[26:27], 0, v[138:139]
	s_add_i32 m0, s17, 0xc000
	ds_read_b128 v[190:193], v157
	ds_read_b128 v[196:199], v157 offset:1024
	ds_read_b128 v[200:203], v157 offset:2048
	ds_read_b128 v[204:207], v157 offset:3072
	ds_read_b128 v[208:211], v157 offset:4096
	ds_read_b128 v[212:215], v157 offset:5120
	ds_read_b128 v[216:219], v157 offset:6144
	ds_read_b128 v[220:223], v157 offset:7168
	global_load_lds_dwordx4 v[224:225], off
	v_lshl_add_u64 v[224:225], s[26:27], 0, v[140:141]
	s_add_i32 m0, s17, 0xe000
	s_nop 0
	global_load_lds_dwordx4 v[224:225], off
	s_waitcnt lgkmcnt(0)
	s_setprio 1
	v_mfma_f32_16x16x32_bf16 v[126:129], v[158:161], v[190:193], v[126:129]
	v_mfma_f32_16x16x32_bf16 v[122:125], v[166:169], v[190:193], v[122:125]
	v_mfma_f32_16x16x32_bf16 v[118:121], v[158:161], v[200:203], v[118:121]
	v_mfma_f32_16x16x32_bf16 v[114:117], v[166:169], v[200:203], v[114:117]
	v_mfma_f32_16x16x32_bf16 v[102:105], v[158:161], v[208:211], v[102:105]
	v_mfma_f32_16x16x32_bf16 v[98:101], v[166:169], v[208:211], v[98:101]
	v_mfma_f32_16x16x32_bf16 v[86:89], v[158:161], v[216:219], v[86:89]
	v_mfma_f32_16x16x32_bf16 v[82:85], v[166:169], v[216:219], v[82:85]
	v_mfma_f32_16x16x32_bf16 v[126:129], v[162:165], v[196:199], v[126:129]
	v_mfma_f32_16x16x32_bf16 v[122:125], v[170:173], v[196:199], v[122:125]
	v_mfma_f32_16x16x32_bf16 v[118:121], v[162:165], v[204:207], v[118:121]
	v_mfma_f32_16x16x32_bf16 v[114:117], v[170:173], v[204:207], v[114:117]
	v_mfma_f32_16x16x32_bf16 v[102:105], v[162:165], v[212:215], v[102:105]
	v_mfma_f32_16x16x32_bf16 v[98:101], v[170:173], v[212:215], v[98:101]
	v_mfma_f32_16x16x32_bf16 v[86:89], v[162:165], v[220:223], v[86:89]
	v_mfma_f32_16x16x32_bf16 v[82:85], v[170:173], v[220:223], v[82:85]
	v_mfma_f32_16x16x32_bf16 v[110:113], v[174:177], v[190:193], v[110:113]
	v_mfma_f32_16x16x32_bf16 v[106:109], v[182:185], v[190:193], v[106:109]
	v_mfma_f32_16x16x32_bf16 v[94:97], v[174:177], v[200:203], v[94:97]
	v_mfma_f32_16x16x32_bf16 v[90:93], v[182:185], v[200:203], v[90:93]
	v_mfma_f32_16x16x32_bf16 v[78:81], v[174:177], v[208:211], v[78:81]
	v_mfma_f32_16x16x32_bf16 v[74:77], v[182:185], v[208:211], v[74:77]
	v_mfma_f32_16x16x32_bf16 v[70:73], v[174:177], v[216:219], v[70:73]
	v_mfma_f32_16x16x32_bf16 v[66:69], v[182:185], v[216:219], v[66:69]
	v_mfma_f32_16x16x32_bf16 v[110:113], v[178:181], v[196:199], v[110:113]
	v_mfma_f32_16x16x32_bf16 v[106:109], v[186:189], v[196:199], v[106:109]
	v_mfma_f32_16x16x32_bf16 v[94:97], v[178:181], v[204:207], v[94:97]
	v_mfma_f32_16x16x32_bf16 v[90:93], v[186:189], v[204:207], v[90:93]
	v_mfma_f32_16x16x32_bf16 v[78:81], v[178:181], v[212:215], v[78:81]
	v_mfma_f32_16x16x32_bf16 v[74:77], v[186:189], v[212:215], v[74:77]
	v_mfma_f32_16x16x32_bf16 v[70:73], v[178:181], v[220:223], v[70:73]
	v_mfma_f32_16x16x32_bf16 v[66:69], v[186:189], v[220:223], v[66:69]
	s_setprio 0
	s_waitcnt vmcnt(8)
	s_barrier
	s_add_i32 s59, s50, s41
	v_lshl_add_u64 v[224:225], s[28:29], 0, v[134:135]
	s_mov_b32 m0, s59
	ds_read_b128 v[190:193], v157 offset:16384
	ds_read_b128 v[196:199], v157 offset:17408
	ds_read_b128 v[200:203], v157 offset:18432
	ds_read_b128 v[204:207], v157 offset:19456
	ds_read_b128 v[208:211], v157 offset:20480
	ds_read_b128 v[212:215], v157 offset:21504
	ds_read_b128 v[216:219], v157 offset:22528
	ds_read_b128 v[220:223], v157 offset:23552
	global_load_lds_dwordx4 v[224:225], off
	s_add_i32 m0, s59, 0x2000
	s_add_u32 s60, s28, 0x100000
	v_lshl_add_u64 v[226:227], s[28:29], 0, v[136:137]
	s_addc_u32 s61, s29, 0
	s_add_i32 s59, s51, s41
	global_load_lds_dwordx4 v[226:227], off
	v_lshl_add_u64 v[228:229], s[60:61], 0, v[134:135]
	s_mov_b32 m0, s59
	v_lshl_add_u64 v[230:231], s[30:31], 0, v[132:133]
	global_load_lds_dwordx4 v[228:229], off
	v_lshl_add_u64 v[228:229], s[60:61], 0, v[136:137]
	s_add_i32 m0, s59, 0x2000
	s_nop 0
	global_load_lds_dwordx4 v[228:229], off
	v_lshl_add_u64 v[228:229], s[30:31], 0, v[130:131]
	s_mov_b32 m0, s17
	s_nop 0
	global_load_lds_dwordx4 v[228:229], off
	s_mov_b32 m0, s42
	s_nop 0
	global_load_lds_dwordx4 v[230:231], off
	s_waitcnt lgkmcnt(0)
	s_setprio 1
	v_mfma_f32_16x16x32_bf16 v[62:65], v[158:161], v[190:193], v[62:65]
	v_mfma_f32_16x16x32_bf16 v[58:61], v[166:169], v[190:193], v[58:61]
	v_mfma_f32_16x16x32_bf16 v[54:57], v[158:161], v[200:203], v[54:57]
	v_mfma_f32_16x16x32_bf16 v[50:53], v[166:169], v[200:203], v[50:53]
	v_mfma_f32_16x16x32_bf16 v[38:41], v[158:161], v[208:211], v[38:41]
	v_mfma_f32_16x16x32_bf16 v[34:37], v[166:169], v[208:211], v[34:37]
	v_mfma_f32_16x16x32_bf16 v[22:25], v[158:161], v[216:219], v[22:25]
	v_mfma_f32_16x16x32_bf16 v[18:21], v[166:169], v[216:219], v[18:21]
	v_mfma_f32_16x16x32_bf16 v[62:65], v[162:165], v[196:199], v[62:65]
	v_mfma_f32_16x16x32_bf16 v[58:61], v[170:173], v[196:199], v[58:61]
	v_mfma_f32_16x16x32_bf16 v[54:57], v[162:165], v[204:207], v[54:57]
	v_mfma_f32_16x16x32_bf16 v[50:53], v[170:173], v[204:207], v[50:53]
	v_mfma_f32_16x16x32_bf16 v[38:41], v[162:165], v[212:215], v[38:41]
	v_mfma_f32_16x16x32_bf16 v[34:37], v[170:173], v[212:215], v[34:37]
	v_mfma_f32_16x16x32_bf16 v[22:25], v[162:165], v[220:223], v[22:25]
	v_mfma_f32_16x16x32_bf16 v[18:21], v[170:173], v[220:223], v[18:21]
	v_mfma_f32_16x16x32_bf16 v[46:49], v[174:177], v[190:193], v[46:49]
	v_mfma_f32_16x16x32_bf16 v[42:45], v[182:185], v[190:193], v[42:45]
	v_mfma_f32_16x16x32_bf16 v[30:33], v[174:177], v[200:203], v[30:33]
	v_mfma_f32_16x16x32_bf16 v[26:29], v[182:185], v[200:203], v[26:29]
	v_mfma_f32_16x16x32_bf16 v[14:17], v[174:177], v[208:211], v[14:17]
	v_mfma_f32_16x16x32_bf16 v[10:13], v[182:185], v[208:211], v[10:13]
	v_mfma_f32_16x16x32_bf16 v[6:9], v[174:177], v[216:219], v[6:9]
	v_mfma_f32_16x16x32_bf16 v[2:5], v[182:185], v[216:219], v[2:5]
	v_mfma_f32_16x16x32_bf16 v[46:49], v[178:181], v[196:199], v[46:49]
	v_mfma_f32_16x16x32_bf16 v[42:45], v[186:189], v[196:199], v[42:45]
	v_mfma_f32_16x16x32_bf16 v[30:33], v[178:181], v[204:207], v[30:33]
	v_mfma_f32_16x16x32_bf16 v[26:29], v[186:189], v[204:207], v[26:29]
	v_mfma_f32_16x16x32_bf16 v[14:17], v[178:181], v[212:215], v[14:17]
	v_mfma_f32_16x16x32_bf16 v[10:13], v[186:189], v[212:215], v[10:13]
	v_mfma_f32_16x16x32_bf16 v[6:9], v[178:181], v[220:223], v[6:9]
	v_mfma_f32_16x16x32_bf16 v[2:5], v[186:189], v[220:223], v[2:5]
	s_setprio 0
	s_waitcnt vmcnt(8)
	s_barrier
	s_add_i32 s59, 0, 0x18000
	s_add_i32 s60, 0, 0x1c000
	v_add_u32_e32 v170, s59, v153
	v_add_u32_e32 v186, s60, v153
	ds_read_b128 v[158:161], v170
	ds_read_b128 v[162:165], v170 offset:1024
	ds_read_b128 v[166:169], v170 offset:2048
	ds_read_b128 v[170:173], v170 offset:3072
	ds_read_b128 v[174:177], v186
	ds_read_b128 v[178:181], v186 offset:1024
	ds_read_b128 v[182:185], v186 offset:2048
	ds_read_b128 v[186:189], v186 offset:3072
	s_add_u32 s30, s30, 0x100000
	s_addc_u32 s31, s31, 0
	s_mov_b32 m0, s43
	v_lshl_add_u64 v[232:233], s[30:31], 0, v[130:131]
	ds_read_b128 v[190:193], v157 offset:32768
	ds_read_b128 v[196:199], v157 offset:33792
	ds_read_b128 v[200:203], v157 offset:34816
	ds_read_b128 v[204:207], v157 offset:35840
	ds_read_b128 v[208:211], v157 offset:36864
	ds_read_b128 v[212:215], v157 offset:37888
	ds_read_b128 v[216:219], v157 offset:38912
	ds_read_b128 v[220:223], v157 offset:39936
	global_load_lds_dwordx4 v[232:233], off
	v_lshl_add_u64 v[232:233], s[30:31], 0, v[132:133]
	s_mov_b32 m0, s45
	s_nop 0
	global_load_lds_dwordx4 v[232:233], off
	s_waitcnt lgkmcnt(0)
	s_setprio 1
	v_mfma_f32_16x16x32_bf16 v[126:129], v[158:161], v[190:193], v[126:129]
	v_mfma_f32_16x16x32_bf16 v[122:125], v[166:169], v[190:193], v[122:125]
	v_mfma_f32_16x16x32_bf16 v[118:121], v[158:161], v[200:203], v[118:121]
	v_mfma_f32_16x16x32_bf16 v[114:117], v[166:169], v[200:203], v[114:117]
	v_mfma_f32_16x16x32_bf16 v[102:105], v[158:161], v[208:211], v[102:105]
	v_mfma_f32_16x16x32_bf16 v[98:101], v[166:169], v[208:211], v[98:101]
	v_mfma_f32_16x16x32_bf16 v[86:89], v[158:161], v[216:219], v[86:89]
	v_mfma_f32_16x16x32_bf16 v[82:85], v[166:169], v[216:219], v[82:85]
	v_mfma_f32_16x16x32_bf16 v[126:129], v[162:165], v[196:199], v[126:129]
	v_mfma_f32_16x16x32_bf16 v[122:125], v[170:173], v[196:199], v[122:125]
	v_mfma_f32_16x16x32_bf16 v[118:121], v[162:165], v[204:207], v[118:121]
	v_mfma_f32_16x16x32_bf16 v[114:117], v[170:173], v[204:207], v[114:117]
	v_mfma_f32_16x16x32_bf16 v[102:105], v[162:165], v[212:215], v[102:105]
	v_mfma_f32_16x16x32_bf16 v[98:101], v[170:173], v[212:215], v[98:101]
	v_mfma_f32_16x16x32_bf16 v[86:89], v[162:165], v[220:223], v[86:89]
	v_mfma_f32_16x16x32_bf16 v[82:85], v[170:173], v[220:223], v[82:85]
	v_mfma_f32_16x16x32_bf16 v[110:113], v[174:177], v[190:193], v[110:113]
	v_mfma_f32_16x16x32_bf16 v[106:109], v[182:185], v[190:193], v[106:109]
	v_mfma_f32_16x16x32_bf16 v[94:97], v[174:177], v[200:203], v[94:97]
	v_mfma_f32_16x16x32_bf16 v[90:93], v[182:185], v[200:203], v[90:93]
	v_mfma_f32_16x16x32_bf16 v[78:81], v[174:177], v[208:211], v[78:81]
	v_mfma_f32_16x16x32_bf16 v[74:77], v[182:185], v[208:211], v[74:77]
	v_mfma_f32_16x16x32_bf16 v[70:73], v[174:177], v[216:219], v[70:73]
	v_mfma_f32_16x16x32_bf16 v[66:69], v[182:185], v[216:219], v[66:69]
	v_mfma_f32_16x16x32_bf16 v[110:113], v[178:181], v[196:199], v[110:113]
	v_mfma_f32_16x16x32_bf16 v[106:109], v[186:189], v[196:199], v[106:109]
	v_mfma_f32_16x16x32_bf16 v[94:97], v[178:181], v[204:207], v[94:97]
	v_mfma_f32_16x16x32_bf16 v[90:93], v[186:189], v[204:207], v[90:93]
	v_mfma_f32_16x16x32_bf16 v[78:81], v[178:181], v[212:215], v[78:81]
	v_mfma_f32_16x16x32_bf16 v[74:77], v[186:189], v[212:215], v[74:77]
	v_mfma_f32_16x16x32_bf16 v[70:73], v[178:181], v[220:223], v[70:73]
	v_mfma_f32_16x16x32_bf16 v[66:69], v[186:189], v[220:223], v[66:69]
	s_setprio 0
	s_waitcnt vmcnt(8)
	s_barrier
	s_add_i32 s30, s59, s41
	v_lshl_add_u64 v[224:225], v[224:225], 0, s[12:13]
	s_mov_b32 m0, s30
	ds_read_b128 v[190:193], v157 offset:49152
	ds_read_b128 v[196:199], v157 offset:50176
	ds_read_b128 v[200:203], v157 offset:51200
	ds_read_b128 v[204:207], v157 offset:52224
	ds_read_b128 v[208:211], v157 offset:53248
	ds_read_b128 v[212:215], v157 offset:54272
	ds_read_b128 v[216:219], v157 offset:55296
	ds_read_b128 v[220:223], v157 offset:56320
	global_load_lds_dwordx4 v[224:225], off
	s_add_i32 m0, s30, 0x2000
	s_add_u32 s28, s28, 0x100080
	v_lshl_add_u64 v[224:225], v[226:227], 0, s[12:13]
	s_addc_u32 s29, s29, 0
	s_add_i32 s30, s60, s41
	global_load_lds_dwordx4 v[224:225], off
	v_lshl_add_u64 v[224:225], s[28:29], 0, v[134:135]
	s_mov_b32 m0, s30
	s_nop 0
	global_load_lds_dwordx4 v[224:225], off
	v_lshl_add_u64 v[224:225], s[28:29], 0, v[136:137]
	s_add_i32 m0, s30, 0x2000
	s_nop 0
	global_load_lds_dwordx4 v[224:225], off
	v_lshl_add_u64 v[224:225], v[228:229], 0, s[12:13]
	s_mov_b32 m0, s47
	s_nop 0
	global_load_lds_dwordx4 v[224:225], off
	v_lshl_add_u64 v[224:225], v[230:231], 0, s[12:13]
	s_mov_b32 m0, s48
	s_nop 0
	global_load_lds_dwordx4 v[224:225], off
	s_waitcnt lgkmcnt(0)
	s_setprio 1
	v_mfma_f32_16x16x32_bf16 v[62:65], v[158:161], v[190:193], v[62:65]
	v_mfma_f32_16x16x32_bf16 v[58:61], v[166:169], v[190:193], v[58:61]
	v_mfma_f32_16x16x32_bf16 v[54:57], v[158:161], v[200:203], v[54:57]
	v_mfma_f32_16x16x32_bf16 v[50:53], v[166:169], v[200:203], v[50:53]
	v_mfma_f32_16x16x32_bf16 v[38:41], v[158:161], v[208:211], v[38:41]
	v_mfma_f32_16x16x32_bf16 v[34:37], v[166:169], v[208:211], v[34:37]
	v_mfma_f32_16x16x32_bf16 v[22:25], v[158:161], v[216:219], v[22:25]
	v_mfma_f32_16x16x32_bf16 v[18:21], v[166:169], v[216:219], v[18:21]
	v_mfma_f32_16x16x32_bf16 v[62:65], v[162:165], v[196:199], v[62:65]
	v_mfma_f32_16x16x32_bf16 v[58:61], v[170:173], v[196:199], v[58:61]
	v_mfma_f32_16x16x32_bf16 v[54:57], v[162:165], v[204:207], v[54:57]
	v_mfma_f32_16x16x32_bf16 v[50:53], v[170:173], v[204:207], v[50:53]
	v_mfma_f32_16x16x32_bf16 v[38:41], v[162:165], v[212:215], v[38:41]
	v_mfma_f32_16x16x32_bf16 v[34:37], v[170:173], v[212:215], v[34:37]
	v_mfma_f32_16x16x32_bf16 v[22:25], v[162:165], v[220:223], v[22:25]
	v_mfma_f32_16x16x32_bf16 v[18:21], v[170:173], v[220:223], v[18:21]
	v_mfma_f32_16x16x32_bf16 v[46:49], v[174:177], v[190:193], v[46:49]
	v_mfma_f32_16x16x32_bf16 v[42:45], v[182:185], v[190:193], v[42:45]
	v_mfma_f32_16x16x32_bf16 v[30:33], v[174:177], v[200:203], v[30:33]
	v_mfma_f32_16x16x32_bf16 v[26:29], v[182:185], v[200:203], v[26:29]
	v_mfma_f32_16x16x32_bf16 v[14:17], v[174:177], v[208:211], v[14:17]
	v_mfma_f32_16x16x32_bf16 v[10:13], v[182:185], v[208:211], v[10:13]
	v_mfma_f32_16x16x32_bf16 v[6:9], v[174:177], v[216:219], v[6:9]
	v_mfma_f32_16x16x32_bf16 v[2:5], v[182:185], v[216:219], v[2:5]
	v_mfma_f32_16x16x32_bf16 v[46:49], v[178:181], v[196:199], v[46:49]
	v_mfma_f32_16x16x32_bf16 v[42:45], v[186:189], v[196:199], v[42:45]
	v_mfma_f32_16x16x32_bf16 v[30:33], v[178:181], v[204:207], v[30:33]
	v_mfma_f32_16x16x32_bf16 v[26:29], v[186:189], v[204:207], v[26:29]
	v_mfma_f32_16x16x32_bf16 v[14:17], v[178:181], v[212:215], v[14:17]
	v_mfma_f32_16x16x32_bf16 v[10:13], v[186:189], v[212:215], v[10:13]
	v_mfma_f32_16x16x32_bf16 v[6:9], v[178:181], v[220:223], v[6:9]
	v_mfma_f32_16x16x32_bf16 v[2:5], v[186:189], v[220:223], v[2:5]
	s_setprio 0
	s_waitcnt vmcnt(8)
	s_barrier
	s_add_i32 s58, s58, 2
	s_add_u32 s26, s26, 0x100
	s_addc_u32 s27, s27, 0
	s_add_u32 s56, s56, 0x100
	s_addc_u32 s57, s57, 0
	s_cmp_gt_u32 s58, 61
	s_cbranch_scc0 .Lkt_L_3
	s_branch .Lkt_exit_3
.Lkt_T_3:
	ds_read_b128 v[158:161], v155
	ds_read_b128 v[162:165], v155 offset:1024
	ds_read_b128 v[166:169], v155 offset:2048
	ds_read_b128 v[170:173], v155 offset:3072
	ds_read_b128 v[174:177], v156
	ds_read_b128 v[178:181], v156 offset:1024
	ds_read_b128 v[182:185], v156 offset:2048
	ds_read_b128 v[186:189], v156 offset:3072
	s_add_u32 s28, s26, 0xfff00080
	s_addc_u32 s29, s27, -1
	s_cmp_eq_u32 s58, 60
	s_cselect_b32 s31, s21, s29
	s_cselect_b32 s30, s54, s28
	s_cselect_b32 s29, s19, s57
	s_cselect_b32 s28, s55, s56
	v_lshl_add_u64 v[224:225], s[26:27], 0, v[138:139]
	s_add_i32 m0, s17, 0xc000
	ds_read_b128 v[190:193], v157
	ds_read_b128 v[196:199], v157 offset:1024
	ds_read_b128 v[200:203], v157 offset:2048
	ds_read_b128 v[204:207], v157 offset:3072
	ds_read_b128 v[208:211], v157 offset:4096
	ds_read_b128 v[212:215], v157 offset:5120
	ds_read_b128 v[216:219], v157 offset:6144
	ds_read_b128 v[220:223], v157 offset:7168
	global_load_lds_dwordx4 v[224:225], off
	v_lshl_add_u64 v[224:225], s[26:27], 0, v[140:141]
	s_add_i32 m0, s17, 0xe000
	s_nop 0
	global_load_lds_dwordx4 v[224:225], off
	s_waitcnt vmcnt(8)
	s_waitcnt lgkmcnt(0)
	s_barrier
	s_setprio 2
	v_mfma_f32_16x16x32_bf16 v[126:129], v[158:161], v[190:193], v[126:129]
	v_mfma_f32_16x16x32_bf16 v[122:125], v[166:169], v[190:193], v[122:125]
	v_mfma_f32_16x16x32_bf16 v[118:121], v[158:161], v[200:203], v[118:121]
	v_mfma_f32_16x16x32_bf16 v[114:117], v[166:169], v[200:203], v[114:117]
	v_mfma_f32_16x16x32_bf16 v[102:105], v[158:161], v[208:211], v[102:105]
	v_mfma_f32_16x16x32_bf16 v[98:101], v[166:169], v[208:211], v[98:101]
	v_mfma_f32_16x16x32_bf16 v[86:89], v[158:161], v[216:219], v[86:89]
	v_mfma_f32_16x16x32_bf16 v[82:85], v[166:169], v[216:219], v[82:85]
	v_mfma_f32_16x16x32_bf16 v[126:129], v[162:165], v[196:199], v[126:129]
	v_mfma_f32_16x16x32_bf16 v[122:125], v[170:173], v[196:199], v[122:125]
	v_mfma_f32_16x16x32_bf16 v[118:121], v[162:165], v[204:207], v[118:121]
	v_mfma_f32_16x16x32_bf16 v[114:117], v[170:173], v[204:207], v[114:117]
	v_mfma_f32_16x16x32_bf16 v[102:105], v[162:165], v[212:215], v[102:105]
	v_mfma_f32_16x16x32_bf16 v[98:101], v[170:173], v[212:215], v[98:101]
	v_mfma_f32_16x16x32_bf16 v[86:89], v[162:165], v[220:223], v[86:89]
	v_mfma_f32_16x16x32_bf16 v[82:85], v[170:173], v[220:223], v[82:85]
	v_mfma_f32_16x16x32_bf16 v[110:113], v[174:177], v[190:193], v[110:113]
	v_mfma_f32_16x16x32_bf16 v[106:109], v[182:185], v[190:193], v[106:109]
	v_mfma_f32_16x16x32_bf16 v[94:97], v[174:177], v[200:203], v[94:97]
	v_mfma_f32_16x16x32_bf16 v[90:93], v[182:185], v[200:203], v[90:93]
	v_mfma_f32_16x16x32_bf16 v[78:81], v[174:177], v[208:211], v[78:81]
	v_mfma_f32_16x16x32_bf16 v[74:77], v[182:185], v[208:211], v[74:77]
	v_mfma_f32_16x16x32_bf16 v[70:73], v[174:177], v[216:219], v[70:73]
	v_mfma_f32_16x16x32_bf16 v[66:69], v[182:185], v[216:219], v[66:69]
	v_mfma_f32_16x16x32_bf16 v[110:113], v[178:181], v[196:199], v[110:113]
	v_mfma_f32_16x16x32_bf16 v[106:109], v[186:189], v[196:199], v[106:109]
	v_mfma_f32_16x16x32_bf16 v[94:97], v[178:181], v[204:207], v[94:97]
	v_mfma_f32_16x16x32_bf16 v[90:93], v[186:189], v[204:207], v[90:93]
	v_mfma_f32_16x16x32_bf16 v[78:81], v[178:181], v[212:215], v[78:81]
	v_mfma_f32_16x16x32_bf16 v[74:77], v[186:189], v[212:215], v[74:77]
	v_mfma_f32_16x16x32_bf16 v[70:73], v[178:181], v[220:223], v[70:73]
	v_mfma_f32_16x16x32_bf16 v[66:69], v[186:189], v[220:223], v[66:69]
	s_setprio 0
	s_add_i32 s59, s50, s41
	v_lshl_add_u64 v[224:225], s[28:29], 0, v[134:135]
	s_mov_b32 m0, s59
	ds_read_b128 v[190:193], v157 offset:16384
	ds_read_b128 v[196:199], v157 offset:17408
	ds_read_b128 v[200:203], v157 offset:18432
	ds_read_b128 v[204:207], v157 offset:19456
	ds_read_b128 v[208:211], v157 offset:20480
	ds_read_b128 v[212:215], v157 offset:21504
	ds_read_b128 v[216:219], v157 offset:22528
	ds_read_b128 v[220:223], v157 offset:23552
	global_load_lds_dwordx4 v[224:225], off
	s_add_i32 m0, s59, 0x2000
	s_add_u32 s60, s28, 0x100000
	v_lshl_add_u64 v[226:227], s[28:29], 0, v[136:137]
	s_addc_u32 s61, s29, 0
	s_add_i32 s59, s51, s41
	global_load_lds_dwordx4 v[226:227], off
	v_lshl_add_u64 v[228:229], s[60:61], 0, v[134:135]
	s_mov_b32 m0, s59
	v_lshl_add_u64 v[230:231], s[30:31], 0, v[132:133]
	global_load_lds_dwordx4 v[228:229], off
	v_lshl_add_u64 v[228:229], s[60:61], 0, v[136:137]
	s_add_i32 m0, s59, 0x2000
	s_nop 0
	global_load_lds_dwordx4 v[228:229], off
	v_lshl_add_u64 v[228:229], s[30:31], 0, v[130:131]
	s_mov_b32 m0, s17
	s_nop 0
	global_load_lds_dwordx4 v[228:229], off
	s_mov_b32 m0, s42
	s_nop 0
	global_load_lds_dwordx4 v[230:231], off
	s_waitcnt vmcnt(8)
	s_waitcnt lgkmcnt(0)
	s_barrier
	s_setprio 2
	v_mfma_f32_16x16x32_bf16 v[62:65], v[158:161], v[190:193], v[62:65]
	v_mfma_f32_16x16x32_bf16 v[58:61], v[166:169], v[190:193], v[58:61]
	v_mfma_f32_16x16x32_bf16 v[54:57], v[158:161], v[200:203], v[54:57]
	v_mfma_f32_16x16x32_bf16 v[50:53], v[166:169], v[200:203], v[50:53]
	v_mfma_f32_16x16x32_bf16 v[38:41], v[158:161], v[208:211], v[38:41]
	v_mfma_f32_16x16x32_bf16 v[34:37], v[166:169], v[208:211], v[34:37]
	v_mfma_f32_16x16x32_bf16 v[22:25], v[158:161], v[216:219], v[22:25]
	v_mfma_f32_16x16x32_bf16 v[18:21], v[166:169], v[216:219], v[18:21]
	v_mfma_f32_16x16x32_bf16 v[62:65], v[162:165], v[196:199], v[62:65]
	v_mfma_f32_16x16x32_bf16 v[58:61], v[170:173], v[196:199], v[58:61]
	v_mfma_f32_16x16x32_bf16 v[54:57], v[162:165], v[204:207], v[54:57]
	v_mfma_f32_16x16x32_bf16 v[50:53], v[170:173], v[204:207], v[50:53]
	v_mfma_f32_16x16x32_bf16 v[38:41], v[162:165], v[212:215], v[38:41]
	v_mfma_f32_16x16x32_bf16 v[34:37], v[170:173], v[212:215], v[34:37]
	v_mfma_f32_16x16x32_bf16 v[22:25], v[162:165], v[220:223], v[22:25]
	v_mfma_f32_16x16x32_bf16 v[18:21], v[170:173], v[220:223], v[18:21]
	v_mfma_f32_16x16x32_bf16 v[46:49], v[174:177], v[190:193], v[46:49]
	v_mfma_f32_16x16x32_bf16 v[42:45], v[182:185], v[190:193], v[42:45]
	v_mfma_f32_16x16x32_bf16 v[30:33], v[174:177], v[200:203], v[30:33]
	v_mfma_f32_16x16x32_bf16 v[26:29], v[182:185], v[200:203], v[26:29]
	v_mfma_f32_16x16x32_bf16 v[14:17], v[174:177], v[208:211], v[14:17]
	v_mfma_f32_16x16x32_bf16 v[10:13], v[182:185], v[208:211], v[10:13]
	v_mfma_f32_16x16x32_bf16 v[6:9], v[174:177], v[216:219], v[6:9]
	v_mfma_f32_16x16x32_bf16 v[2:5], v[182:185], v[216:219], v[2:5]
	v_mfma_f32_16x16x32_bf16 v[46:49], v[178:181], v[196:199], v[46:49]
	v_mfma_f32_16x16x32_bf16 v[42:45], v[186:189], v[196:199], v[42:45]
	v_mfma_f32_16x16x32_bf16 v[30:33], v[178:181], v[204:207], v[30:33]
	v_mfma_f32_16x16x32_bf16 v[26:29], v[186:189], v[204:207], v[26:29]
	v_mfma_f32_16x16x32_bf16 v[14:17], v[178:181], v[212:215], v[14:17]
	v_mfma_f32_16x16x32_bf16 v[10:13], v[186:189], v[212:215], v[10:13]
	v_mfma_f32_16x16x32_bf16 v[6:9], v[178:181], v[220:223], v[6:9]
	v_mfma_f32_16x16x32_bf16 v[2:5], v[186:189], v[220:223], v[2:5]
	s_setprio 0
	s_add_i32 s59, 0, 0x18000
	s_add_i32 s60, 0, 0x1c000
	v_add_u32_e32 v170, s59, v153
	v_add_u32_e32 v186, s60, v153
	ds_read_b128 v[158:161], v170
	ds_read_b128 v[162:165], v170 offset:1024
	ds_read_b128 v[166:169], v170 offset:2048
	ds_read_b128 v[170:173], v170 offset:3072
	ds_read_b128 v[174:177], v186
	ds_read_b128 v[178:181], v186 offset:1024
	ds_read_b128 v[182:185], v186 offset:2048
	ds_read_b128 v[186:189], v186 offset:3072
	s_add_u32 s30, s30, 0x100000
	s_addc_u32 s31, s31, 0
	s_mov_b32 m0, s43
	v_lshl_add_u64 v[232:233], s[30:31], 0, v[130:131]
	ds_read_b128 v[190:193], v157 offset:32768
	ds_read_b128 v[196:199], v157 offset:33792
	ds_read_b128 v[200:203], v157 offset:34816
	ds_read_b128 v[204:207], v157 offset:35840
	ds_read_b128 v[208:211], v157 offset:36864
	ds_read_b128 v[212:215], v157 offset:37888
	ds_read_b128 v[216:219], v157 offset:38912
	ds_read_b128 v[220:223], v157 offset:39936
	global_load_lds_dwordx4 v[232:233], off
	v_lshl_add_u64 v[232:233], s[30:31], 0, v[132:133]
	s_mov_b32 m0, s45
	s_nop 0
	global_load_lds_dwordx4 v[232:233], off
	s_waitcnt vmcnt(8)
	s_waitcnt lgkmcnt(0)
	s_barrier
	s_setprio 2
	v_mfma_f32_16x16x32_bf16 v[126:129], v[158:161], v[190:193], v[126:129]
	v_mfma_f32_16x16x32_bf16 v[122:125], v[166:169], v[190:193], v[122:125]
	v_mfma_f32_16x16x32_bf16 v[118:121], v[158:161], v[200:203], v[118:121]
	v_mfma_f32_16x16x32_bf16 v[114:117], v[166:169], v[200:203], v[114:117]
	v_mfma_f32_16x16x32_bf16 v[102:105], v[158:161], v[208:211], v[102:105]
	v_mfma_f32_16x16x32_bf16 v[98:101], v[166:169], v[208:211], v[98:101]
	v_mfma_f32_16x16x32_bf16 v[86:89], v[158:161], v[216:219], v[86:89]
	v_mfma_f32_16x16x32_bf16 v[82:85], v[166:169], v[216:219], v[82:85]
	v_mfma_f32_16x16x32_bf16 v[126:129], v[162:165], v[196:199], v[126:129]
	v_mfma_f32_16x16x32_bf16 v[122:125], v[170:173], v[196:199], v[122:125]
	v_mfma_f32_16x16x32_bf16 v[118:121], v[162:165], v[204:207], v[118:121]
	v_mfma_f32_16x16x32_bf16 v[114:117], v[170:173], v[204:207], v[114:117]
	v_mfma_f32_16x16x32_bf16 v[102:105], v[162:165], v[212:215], v[102:105]
	v_mfma_f32_16x16x32_bf16 v[98:101], v[170:173], v[212:215], v[98:101]
	v_mfma_f32_16x16x32_bf16 v[86:89], v[162:165], v[220:223], v[86:89]
	v_mfma_f32_16x16x32_bf16 v[82:85], v[170:173], v[220:223], v[82:85]
	v_mfma_f32_16x16x32_bf16 v[110:113], v[174:177], v[190:193], v[110:113]
	v_mfma_f32_16x16x32_bf16 v[106:109], v[182:185], v[190:193], v[106:109]
	v_mfma_f32_16x16x32_bf16 v[94:97], v[174:177], v[200:203], v[94:97]
	v_mfma_f32_16x16x32_bf16 v[90:93], v[182:185], v[200:203], v[90:93]
	v_mfma_f32_16x16x32_bf16 v[78:81], v[174:177], v[208:211], v[78:81]
	v_mfma_f32_16x16x32_bf16 v[74:77], v[182:185], v[208:211], v[74:77]
	v_mfma_f32_16x16x32_bf16 v[70:73], v[174:177], v[216:219], v[70:73]
	v_mfma_f32_16x16x32_bf16 v[66:69], v[182:185], v[216:219], v[66:69]
	v_mfma_f32_16x16x32_bf16 v[110:113], v[178:181], v[196:199], v[110:113]
	v_mfma_f32_16x16x32_bf16 v[106:109], v[186:189], v[196:199], v[106:109]
	v_mfma_f32_16x16x32_bf16 v[94:97], v[178:181], v[204:207], v[94:97]
	v_mfma_f32_16x16x32_bf16 v[90:93], v[186:189], v[204:207], v[90:93]
	v_mfma_f32_16x16x32_bf16 v[78:81], v[178:181], v[212:215], v[78:81]
	v_mfma_f32_16x16x32_bf16 v[74:77], v[186:189], v[212:215], v[74:77]
	v_mfma_f32_16x16x32_bf16 v[70:73], v[178:181], v[220:223], v[70:73]
	v_mfma_f32_16x16x32_bf16 v[66:69], v[186:189], v[220:223], v[66:69]
	s_setprio 0
	s_add_i32 s30, s59, s41
	v_lshl_add_u64 v[224:225], v[224:225], 0, s[12:13]
	s_mov_b32 m0, s30
	ds_read_b128 v[190:193], v157 offset:49152
	ds_read_b128 v[196:199], v157 offset:50176
	ds_read_b128 v[200:203], v157 offset:51200
	ds_read_b128 v[204:207], v157 offset:52224
	ds_read_b128 v[208:211], v157 offset:53248
	ds_read_b128 v[212:215], v157 offset:54272
	ds_read_b128 v[216:219], v157 offset:55296
	ds_read_b128 v[220:223], v157 offset:56320
	global_load_lds_dwordx4 v[224:225], off
	s_add_i32 m0, s30, 0x2000
	s_add_u32 s28, s28, 0x100080
	v_lshl_add_u64 v[224:225], v[226:227], 0, s[12:13]
	s_addc_u32 s29, s29, 0
	s_add_i32 s30, s60, s41
	global_load_lds_dwordx4 v[224:225], off
	v_lshl_add_u64 v[224:225], s[28:29], 0, v[134:135]
	s_mov_b32 m0, s30
	s_nop 0
	global_load_lds_dwordx4 v[224:225], off
	v_lshl_add_u64 v[224:225], s[28:29], 0, v[136:137]
	s_add_i32 m0, s30, 0x2000
	s_nop 0
	global_load_lds_dwordx4 v[224:225], off
	v_lshl_add_u64 v[224:225], v[228:229], 0, s[12:13]
	s_mov_b32 m0, s47
	s_nop 0
	global_load_lds_dwordx4 v[224:225], off
	v_lshl_add_u64 v[224:225], v[230:231], 0, s[12:13]
	s_mov_b32 m0, s48
	s_nop 0
	global_load_lds_dwordx4 v[224:225], off
	s_waitcnt vmcnt(8)
	s_waitcnt lgkmcnt(0)
	s_barrier
	s_setprio 2
	v_mfma_f32_16x16x32_bf16 v[62:65], v[158:161], v[190:193], v[62:65]
	v_mfma_f32_16x16x32_bf16 v[58:61], v[166:169], v[190:193], v[58:61]
	v_mfma_f32_16x16x32_bf16 v[54:57], v[158:161], v[200:203], v[54:57]
	v_mfma_f32_16x16x32_bf16 v[50:53], v[166:169], v[200:203], v[50:53]
	v_mfma_f32_16x16x32_bf16 v[38:41], v[158:161], v[208:211], v[38:41]
	v_mfma_f32_16x16x32_bf16 v[34:37], v[166:169], v[208:211], v[34:37]
	v_mfma_f32_16x16x32_bf16 v[22:25], v[158:161], v[216:219], v[22:25]
	v_mfma_f32_16x16x32_bf16 v[18:21], v[166:169], v[216:219], v[18:21]
	v_mfma_f32_16x16x32_bf16 v[62:65], v[162:165], v[196:199], v[62:65]
	v_mfma_f32_16x16x32_bf16 v[58:61], v[170:173], v[196:199], v[58:61]
	v_mfma_f32_16x16x32_bf16 v[54:57], v[162:165], v[204:207], v[54:57]
	v_mfma_f32_16x16x32_bf16 v[50:53], v[170:173], v[204:207], v[50:53]
	v_mfma_f32_16x16x32_bf16 v[38:41], v[162:165], v[212:215], v[38:41]
	v_mfma_f32_16x16x32_bf16 v[34:37], v[170:173], v[212:215], v[34:37]
	v_mfma_f32_16x16x32_bf16 v[22:25], v[162:165], v[220:223], v[22:25]
	v_mfma_f32_16x16x32_bf16 v[18:21], v[170:173], v[220:223], v[18:21]
	v_mfma_f32_16x16x32_bf16 v[46:49], v[174:177], v[190:193], v[46:49]
	v_mfma_f32_16x16x32_bf16 v[42:45], v[182:185], v[190:193], v[42:45]
	v_mfma_f32_16x16x32_bf16 v[30:33], v[174:177], v[200:203], v[30:33]
	v_mfma_f32_16x16x32_bf16 v[26:29], v[182:185], v[200:203], v[26:29]
	v_mfma_f32_16x16x32_bf16 v[14:17], v[174:177], v[208:211], v[14:17]
	v_mfma_f32_16x16x32_bf16 v[10:13], v[182:185], v[208:211], v[10:13]
	v_mfma_f32_16x16x32_bf16 v[6:9], v[174:177], v[216:219], v[6:9]
	v_mfma_f32_16x16x32_bf16 v[2:5], v[182:185], v[216:219], v[2:5]
	v_mfma_f32_16x16x32_bf16 v[46:49], v[178:181], v[196:199], v[46:49]
	v_mfma_f32_16x16x32_bf16 v[42:45], v[186:189], v[196:199], v[42:45]
	v_mfma_f32_16x16x32_bf16 v[30:33], v[178:181], v[204:207], v[30:33]
	v_mfma_f32_16x16x32_bf16 v[26:29], v[186:189], v[204:207], v[26:29]
	v_mfma_f32_16x16x32_bf16 v[14:17], v[178:181], v[212:215], v[14:17]
	v_mfma_f32_16x16x32_bf16 v[10:13], v[186:189], v[212:215], v[10:13]
	v_mfma_f32_16x16x32_bf16 v[6:9], v[178:181], v[220:223], v[6:9]
	v_mfma_f32_16x16x32_bf16 v[2:5], v[186:189], v[220:223], v[2:5]
	s_setprio 0
	s_add_i32 s58, s58, 2
	s_add_u32 s26, s26, 0x100
	s_addc_u32 s27, s27, 0
	s_add_u32 s56, s56, 0x100
	s_addc_u32 s57, s57, 0
	s_cmp_gt_u32 s58, 61
	s_cbranch_scc0 .Lkt_T_3
	s_nop 7

.LBB0_660:
	v_lshl_add_u32 v164, s16, 8, v152
	v_lshl_or_b32 v158, s53, 8, v154
	v_ashrrev_i32_e32 v159, 31, v158
	v_mov_b64_e32 v[160:161], s[10:11]
	v_cvt_pk_bf16_f32 v70, v70, v71
	v_cvt_pk_bf16_f32 v71, v72, v73
	v_cvt_pk_bf16_f32 v72, v66, v67
	v_add_u32_e32 v66, 0x80, v164
	v_mad_i64_i32 v[162:163], s[26:27], v164, s52, v[160:161]
	v_lshlrev_b64 v[158:159], 1, v[158:159]
	v_cvt_pk_bf16_f32 v110, v110, v111
	v_cvt_pk_bf16_f32 v111, v112, v113
	v_cvt_pk_bf16_f32 v112, v106, v107
	v_or_b32_e32 v106, 16, v164
	v_mad_i64_i32 v[66:67], s[26:27], v66, s52, v[160:161]
	v_cvt_pk_bf16_f32 v46, v46, v47
	v_cvt_pk_bf16_f32 v47, v48, v49
	v_cvt_pk_bf16_f32 v48, v42, v43
	v_add_u32_e32 v42, 0x90, v164
	v_lshl_add_u64 v[162:163], v[162:163], 0, v[158:159]
	v_cvt_pk_bf16_f32 v113, v108, v109
	v_mad_i64_i32 v[106:107], s[26:27], v106, s52, v[160:161]
	v_cvt_pk_bf16_f32 v94, v94, v95
	v_cvt_pk_bf16_f32 v95, v96, v97
	v_cvt_pk_bf16_f32 v96, v90, v91
	v_or_b32_e32 v90, 32, v164
	v_lshl_add_u64 v[66:67], v[66:67], 0, v[158:159]
	v_cvt_pk_bf16_f32 v49, v44, v45
	v_mad_i64_i32 v[42:43], s[26:27], v42, s52, v[160:161]
	v_cvt_pk_bf16_f32 v30, v30, v31
	v_cvt_pk_bf16_f32 v31, v32, v33
	v_cvt_pk_bf16_f32 v32, v26, v27
	v_add_u32_e32 v26, 0xa0, v164
	global_store_dwordx4 v[162:163], v[110:113], off offset:256
	v_cvt_pk_bf16_f32 v97, v92, v93
	v_mad_i64_i32 v[90:91], s[26:27], v90, s52, v[160:161]
	v_lshl_add_u64 v[110:111], v[106:107], 0, v[158:159]
	v_cvt_pk_bf16_f32 v78, v78, v79
	v_cvt_pk_bf16_f32 v79, v80, v81
	v_cvt_pk_bf16_f32 v80, v74, v75
	v_or_b32_e32 v74, 48, v164
	global_store_dwordx4 v[66:67], v[46:49], off offset:256
	v_cvt_pk_bf16_f32 v33, v28, v29
	v_mad_i64_i32 v[26:27], s[26:27], v26, s52, v[160:161]
	v_lshl_add_u64 v[46:47], v[42:43], 0, v[158:159]
	v_cvt_pk_bf16_f32 v14, v14, v15
	v_cvt_pk_bf16_f32 v15, v16, v17
	v_cvt_pk_bf16_f32 v16, v10, v11
	v_add_u32_e32 v10, 0xb0, v164
	global_store_dwordx4 v[110:111], v[94:97], off offset:256
	v_cvt_pk_bf16_f32 v81, v76, v77
	v_mad_i64_i32 v[74:75], s[26:27], v74, s52, v[160:161]
	v_lshl_add_u64 v[94:95], v[90:91], 0, v[158:159]
	global_store_dwordx4 v[46:47], v[30:33], off offset:256
	v_cvt_pk_bf16_f32 v17, v12, v13
	v_mad_i64_i32 v[10:11], s[26:27], v10, s52, v[160:161]
	v_lshl_add_u64 v[30:31], v[26:27], 0, v[158:159]
	v_cvt_pk_bf16_f32 v126, v126, v127
	v_cvt_pk_bf16_f32 v127, v128, v129
	v_cvt_pk_bf16_f32 v128, v122, v123
	v_cvt_pk_bf16_f32 v129, v124, v125
	v_cvt_pk_bf16_f32 v106, v118, v119
	v_cvt_pk_bf16_f32 v107, v120, v121
	v_cvt_pk_bf16_f32 v108, v114, v115
	v_cvt_pk_bf16_f32 v109, v116, v117
	v_cvt_pk_bf16_f32 v90, v102, v103
	v_cvt_pk_bf16_f32 v91, v104, v105
	v_cvt_pk_bf16_f32 v92, v98, v99
	v_cvt_pk_bf16_f32 v93, v100, v101
	global_store_dwordx4 v[94:95], v[78:81], off offset:256
	v_cvt_pk_bf16_f32 v76, v82, v83
	v_cvt_pk_bf16_f32 v77, v84, v85
	v_lshl_add_u64 v[78:79], v[74:75], 0, v[158:159]
	v_cvt_pk_bf16_f32 v74, v86, v87
	v_cvt_pk_bf16_f32 v75, v88, v89
	v_cvt_pk_bf16_f32 v73, v68, v69
	v_cvt_pk_bf16_f32 v62, v62, v63
	v_cvt_pk_bf16_f32 v63, v64, v65
	v_cvt_pk_bf16_f32 v64, v58, v59
	v_cvt_pk_bf16_f32 v65, v60, v61
	v_cvt_pk_bf16_f32 v42, v54, v55
	v_cvt_pk_bf16_f32 v43, v56, v57
	v_cvt_pk_bf16_f32 v44, v50, v51
	v_cvt_pk_bf16_f32 v45, v52, v53
	v_cvt_pk_bf16_f32 v26, v38, v39
	v_cvt_pk_bf16_f32 v27, v40, v41
	v_cvt_pk_bf16_f32 v28, v34, v35
	v_cvt_pk_bf16_f32 v29, v36, v37
	global_store_dwordx4 v[30:31], v[14:17], off offset:256
	v_cvt_pk_bf16_f32 v12, v18, v19
	v_cvt_pk_bf16_f32 v13, v20, v21
	v_lshl_add_u64 v[14:15], v[10:11], 0, v[158:159]
	v_cvt_pk_bf16_f32 v10, v22, v23
	v_cvt_pk_bf16_f32 v11, v24, v25
	v_cvt_pk_bf16_f32 v6, v6, v7
	v_cvt_pk_bf16_f32 v7, v8, v9
	v_cvt_pk_bf16_f32 v8, v2, v3
	v_cvt_pk_bf16_f32 v9, v4, v5
	s_andn2_b64 vcc, exec, s[6:7]
	s_mov_b64 s[6:7], -1
	global_store_dwordx4 v[162:163], v[126:129], off
	global_store_dwordx4 v[110:111], v[106:109], off
	global_store_dwordx4 v[94:95], v[90:93], off
	global_store_dwordx4 v[78:79], v[74:77], off
	global_store_dwordx4 v[78:79], v[70:73], off offset:256
	global_store_dwordx4 v[66:67], v[62:65], off
	global_store_dwordx4 v[46:47], v[42:45], off
	global_store_dwordx4 v[30:31], v[26:29], off
	global_store_dwordx4 v[14:15], v[10:13], off
	global_store_dwordx4 v[14:15], v[6:9], off offset:256
	s_cbranch_vccnz .LBB0_649
	s_andn2_b64 vcc, exec, s[8:9]
	s_cbranch_vccnz .LBB0_648
	s_branch .LBB0_648

.LBB0_671:
	s_add_u32 s8, s38, 0x43a00000
	s_addc_u32 s9, s39, 0
	s_lshl_b32 s10, s10, 5
	s_and_b32 s18, s10, 0x60
	s_mov_b64 s[10:11], 0x80
	s_add_i32 m0, s29, 0x18000
	v_lshl_add_u64 v[8:9], v[8:9], 0, s[10:11]
	s_lshl_b32 s15, s14, 13
	s_waitcnt vmcnt(2)
	s_barrier
	global_load_lds_dwordx4 v[8:9], off
	v_lshl_add_u64 v[6:7], v[6:7], 0, s[10:11]
	s_add_i32 m0, s29, 0x1a000
	s_add_i32 s59, s29, 0x8000
	s_add_i32 s60, s29, 0xa000
	global_load_lds_dwordx4 v[6:7], off
	v_lshl_add_u64 v[2:3], v[2:3], 0, s[10:11]
	s_mov_b32 m0, s59
	s_add_u32 s16, s42, 0x100080
	global_load_lds_dwordx4 v[2:3], off
	v_lshl_add_u64 v[2:3], v[4:5], 0, s[10:11]
	s_mov_b32 m0, s60
	s_addc_u32 s17, s43, 0
	global_load_lds_dwordx4 v[2:3], off
	s_add_i32 m0, s29, 0x1c000
	v_lshl_add_u64 v[2:3], s[16:17], 0, v[130:131]
	global_load_lds_dwordx4 v[2:3], off
	v_lshl_add_u64 v[2:3], s[16:17], 0, v[132:133]
	s_add_i32 m0, s29, 0x1e000
	s_sext_i32_i8 s65, s12
	global_load_lds_dwordx4 v[2:3], off
	v_lshlrev_b32_e32 v2, 6, v1
	s_movk_i32 s12, 0x3c0
	v_lshlrev_b32_e32 v3, 2, v1
	v_and_or_b32 v2, v2, s12, v140
	v_and_b32_e32 v3, 32, v3
	v_bitop3_b32 v2, v2, s15, v3 bitop3:0xde
	v_lshlrev_b32_e32 v3, 10, v0
	v_and_b32_e32 v3, 0x60000, v3
	v_lshlrev_b32_e32 v4, 13, v148
	v_or3_b32 v3, v146, v3, v4
	v_add_u32_e32 v134, v3, v147
	v_lshlrev_b32_e32 v3, 6, v149
	s_waitcnt vmcnt(6)
	s_cmpk_lt_u32 s13, 0x100
	v_and_b32_e32 v3, 0xe0000, v3
	v_lshl_or_b32 v142, s18, 7, v139
	s_cselect_b64 s[12:13], -1, 0
	v_or3_b32 v3, v146, v3, v4
	s_add_i32 s62, 0, 0x10000
	s_add_i32 s63, 0, 0x14000
	v_lshl_or_b32 v141, s14, 6, v1
	s_ashr_i32 s61, s44, 31
	v_lshl_or_b32 v143, v138, 2, s18
	v_mov_b32_e32 v135, v131
	v_add_u32_e32 v136, v3, v147
	v_mov_b32_e32 v137, v131
	v_add_u32_e32 v144, s62, v142
	v_add_u32_e32 v145, s63, v142
	v_add_u32_e32 v150, 0, v2
	s_mov_b32 s64, 0x8200000
	s_mov_b64 s[14:15], 0x40000
	s_mov_b64 s[16:17], 0x48000
	s_mov_b64 s[18:19], 0x50000
	s_mov_b64 s[20:21], 0x58000
	s_waitcnt vmcnt(0)
	s_branch .LBB0_674

.Lkt_L_4:
	ds_read_b128 v[152:155], v144
	ds_read_b128 v[156:159], v144 offset:1024
	ds_read_b128 v[160:163], v144 offset:2048
	ds_read_b128 v[164:167], v144 offset:3072
	ds_read_b128 v[168:171], v145
	ds_read_b128 v[172:175], v145 offset:1024
	ds_read_b128 v[176:179], v145 offset:2048
	ds_read_b128 v[180:183], v145 offset:3072
	s_add_u32 s42, s40, 0xfff00080
	s_addc_u32 s43, s41, -1
	s_cmp_eq_u32 s70, 60
	s_cselect_b32 s47, s27, s43
	s_cselect_b32 s46, s66, s42
	s_cselect_b32 s43, s25, s69
	s_cselect_b32 s42, s67, s68
	v_lshl_add_u64 v[192:193], s[40:41], 0, v[134:135]
	s_add_i32 m0, s29, 0xc000
	ds_read_b128 v[184:187], v150
	ds_read_b128 v[188:191], v150 offset:1024
	ds_read_b128 v[196:199], v150 offset:2048
	ds_read_b128 v[200:203], v150 offset:3072
	ds_read_b128 v[204:207], v150 offset:4096
	ds_read_b128 v[208:211], v150 offset:5120
	ds_read_b128 v[212:215], v150 offset:6144
	ds_read_b128 v[216:219], v150 offset:7168
	global_load_lds_dwordx4 v[192:193], off
	v_lshl_add_u64 v[192:193], s[40:41], 0, v[136:137]
	s_add_i32 m0, s29, 0xe000
	s_nop 0
	global_load_lds_dwordx4 v[192:193], off
	s_waitcnt lgkmcnt(0)
	s_setprio 1
	v_mfma_f32_16x16x32_bf16 v[126:129], v[152:155], v[184:187], v[126:129]
	v_mfma_f32_16x16x32_bf16 v[122:125], v[160:163], v[184:187], v[122:125]
	v_mfma_f32_16x16x32_bf16 v[118:121], v[152:155], v[196:199], v[118:121]
	v_mfma_f32_16x16x32_bf16 v[110:113], v[160:163], v[196:199], v[110:113]
	v_mfma_f32_16x16x32_bf16 v[102:105], v[152:155], v[204:207], v[102:105]
	v_mfma_f32_16x16x32_bf16 v[94:97], v[160:163], v[204:207], v[94:97]
	v_mfma_f32_16x16x32_bf16 v[86:89], v[152:155], v[212:215], v[86:89]
	v_mfma_f32_16x16x32_bf16 v[78:81], v[160:163], v[212:215], v[78:81]
	v_mfma_f32_16x16x32_bf16 v[126:129], v[156:159], v[188:191], v[126:129]
	v_mfma_f32_16x16x32_bf16 v[122:125], v[164:167], v[188:191], v[122:125]
	v_mfma_f32_16x16x32_bf16 v[118:121], v[156:159], v[200:203], v[118:121]
	v_mfma_f32_16x16x32_bf16 v[110:113], v[164:167], v[200:203], v[110:113]
	v_mfma_f32_16x16x32_bf16 v[102:105], v[156:159], v[208:211], v[102:105]
	v_mfma_f32_16x16x32_bf16 v[94:97], v[164:167], v[208:211], v[94:97]
	v_mfma_f32_16x16x32_bf16 v[86:89], v[156:159], v[216:219], v[86:89]
	v_mfma_f32_16x16x32_bf16 v[78:81], v[164:167], v[216:219], v[78:81]
	v_mfma_f32_16x16x32_bf16 v[114:117], v[168:171], v[184:187], v[114:117]
	v_mfma_f32_16x16x32_bf16 v[106:109], v[176:179], v[184:187], v[106:109]
	v_mfma_f32_16x16x32_bf16 v[98:101], v[168:171], v[196:199], v[98:101]
	v_mfma_f32_16x16x32_bf16 v[90:93], v[176:179], v[196:199], v[90:93]
	v_mfma_f32_16x16x32_bf16 v[82:85], v[168:171], v[204:207], v[82:85]
	v_mfma_f32_16x16x32_bf16 v[74:77], v[176:179], v[204:207], v[74:77]
	v_mfma_f32_16x16x32_bf16 v[70:73], v[168:171], v[212:215], v[70:73]
	v_mfma_f32_16x16x32_bf16 v[66:69], v[176:179], v[212:215], v[66:69]
	v_mfma_f32_16x16x32_bf16 v[114:117], v[172:175], v[188:191], v[114:117]
	v_mfma_f32_16x16x32_bf16 v[106:109], v[180:183], v[188:191], v[106:109]
	v_mfma_f32_16x16x32_bf16 v[98:101], v[172:175], v[200:203], v[98:101]
	v_mfma_f32_16x16x32_bf16 v[90:93], v[180:183], v[200:203], v[90:93]
	v_mfma_f32_16x16x32_bf16 v[82:85], v[172:175], v[208:211], v[82:85]
	v_mfma_f32_16x16x32_bf16 v[74:77], v[180:183], v[208:211], v[74:77]
	v_mfma_f32_16x16x32_bf16 v[70:73], v[172:175], v[216:219], v[70:73]
	v_mfma_f32_16x16x32_bf16 v[66:69], v[180:183], v[216:219], v[66:69]
	s_setprio 0
	s_waitcnt vmcnt(8)
	s_barrier
	s_add_i32 s71, s62, s54
	v_lshl_add_u64 v[192:193], s[42:43], 0, v[130:131]
	s_mov_b32 m0, s71
	ds_read_b128 v[184:187], v150 offset:16384
	ds_read_b128 v[188:191], v150 offset:17408
	ds_read_b128 v[196:199], v150 offset:18432
	ds_read_b128 v[200:203], v150 offset:19456
	ds_read_b128 v[204:207], v150 offset:20480
	ds_read_b128 v[208:211], v150 offset:21504
	ds_read_b128 v[212:215], v150 offset:22528
	ds_read_b128 v[216:219], v150 offset:23552
	global_load_lds_dwordx4 v[192:193], off
	s_add_i32 m0, s71, 0x2000
	s_add_u32 s72, s42, 0x100000
	v_lshl_add_u64 v[220:221], s[42:43], 0, v[132:133]
	s_addc_u32 s73, s43, 0
	s_add_i32 s71, s63, s54
	global_load_lds_dwordx4 v[220:221], off
	v_lshl_add_u64 v[222:223], s[72:73], 0, v[130:131]
	s_mov_b32 m0, s71
	v_lshl_add_u64 v[224:225], s[46:47], 0, v[132:133]
	global_load_lds_dwordx4 v[222:223], off
	v_lshl_add_u64 v[222:223], s[72:73], 0, v[132:133]
	s_add_i32 m0, s71, 0x2000
	s_nop 0
	global_load_lds_dwordx4 v[222:223], off
	v_lshl_add_u64 v[222:223], s[46:47], 0, v[130:131]
	s_mov_b32 m0, s29
	s_nop 0
	global_load_lds_dwordx4 v[222:223], off
	s_mov_b32 m0, s55
	s_nop 0
	global_load_lds_dwordx4 v[224:225], off
	s_waitcnt lgkmcnt(0)
	s_setprio 1
	v_mfma_f32_16x16x32_bf16 v[62:65], v[152:155], v[184:187], v[62:65]
	v_mfma_f32_16x16x32_bf16 v[58:61], v[160:163], v[184:187], v[58:61]
	v_mfma_f32_16x16x32_bf16 v[54:57], v[152:155], v[196:199], v[54:57]
	v_mfma_f32_16x16x32_bf16 v[46:49], v[160:163], v[196:199], v[46:49]
	v_mfma_f32_16x16x32_bf16 v[38:41], v[152:155], v[204:207], v[38:41]
	v_mfma_f32_16x16x32_bf16 v[30:33], v[160:163], v[204:207], v[30:33]
	v_mfma_f32_16x16x32_bf16 v[22:25], v[152:155], v[212:215], v[22:25]
	v_mfma_f32_16x16x32_bf16 v[14:17], v[160:163], v[212:215], v[14:17]
	v_mfma_f32_16x16x32_bf16 v[62:65], v[156:159], v[188:191], v[62:65]
	v_mfma_f32_16x16x32_bf16 v[58:61], v[164:167], v[188:191], v[58:61]
	v_mfma_f32_16x16x32_bf16 v[54:57], v[156:159], v[200:203], v[54:57]
	v_mfma_f32_16x16x32_bf16 v[46:49], v[164:167], v[200:203], v[46:49]
	v_mfma_f32_16x16x32_bf16 v[38:41], v[156:159], v[208:211], v[38:41]
	v_mfma_f32_16x16x32_bf16 v[30:33], v[164:167], v[208:211], v[30:33]
	v_mfma_f32_16x16x32_bf16 v[22:25], v[156:159], v[216:219], v[22:25]
	v_mfma_f32_16x16x32_bf16 v[14:17], v[164:167], v[216:219], v[14:17]
	v_mfma_f32_16x16x32_bf16 v[50:53], v[168:171], v[184:187], v[50:53]
	v_mfma_f32_16x16x32_bf16 v[42:45], v[176:179], v[184:187], v[42:45]
	v_mfma_f32_16x16x32_bf16 v[34:37], v[168:171], v[196:199], v[34:37]
	v_mfma_f32_16x16x32_bf16 v[26:29], v[176:179], v[196:199], v[26:29]
	v_mfma_f32_16x16x32_bf16 v[18:21], v[168:171], v[204:207], v[18:21]
	v_mfma_f32_16x16x32_bf16 v[10:13], v[176:179], v[204:207], v[10:13]
	v_mfma_f32_16x16x32_bf16 v[6:9], v[168:171], v[212:215], v[6:9]
	v_mfma_f32_16x16x32_bf16 v[2:5], v[176:179], v[212:215], v[2:5]
	v_mfma_f32_16x16x32_bf16 v[50:53], v[172:175], v[188:191], v[50:53]
	v_mfma_f32_16x16x32_bf16 v[42:45], v[180:183], v[188:191], v[42:45]
	v_mfma_f32_16x16x32_bf16 v[34:37], v[172:175], v[200:203], v[34:37]
	v_mfma_f32_16x16x32_bf16 v[26:29], v[180:183], v[200:203], v[26:29]
	v_mfma_f32_16x16x32_bf16 v[18:21], v[172:175], v[208:211], v[18:21]
	v_mfma_f32_16x16x32_bf16 v[10:13], v[180:183], v[208:211], v[10:13]
	v_mfma_f32_16x16x32_bf16 v[6:9], v[172:175], v[216:219], v[6:9]
	v_mfma_f32_16x16x32_bf16 v[2:5], v[180:183], v[216:219], v[2:5]
	s_setprio 0
	s_waitcnt vmcnt(8)
	s_barrier
	s_add_i32 s71, 0, 0x18000
	v_add_u32_e32 v151, s71, v142
	s_add_i32 s72, 0, 0x1c000
	ds_read_b128 v[152:155], v151
	ds_read_b128 v[156:159], v151 offset:1024
	ds_read_b128 v[160:163], v151 offset:2048
	ds_read_b128 v[164:167], v151 offset:3072
	v_add_u32_e32 v151, s72, v142
	ds_read_b128 v[168:171], v151
	ds_read_b128 v[172:175], v151 offset:1024
	ds_read_b128 v[176:179], v151 offset:2048
	ds_read_b128 v[180:183], v151 offset:3072
	s_add_u32 s46, s46, 0x100000
	s_addc_u32 s47, s47, 0
	s_mov_b32 m0, s56
	v_lshl_add_u64 v[226:227], s[46:47], 0, v[130:131]
	ds_read_b128 v[184:187], v150 offset:32768
	ds_read_b128 v[188:191], v150 offset:33792
	ds_read_b128 v[196:199], v150 offset:34816
	ds_read_b128 v[200:203], v150 offset:35840
	ds_read_b128 v[204:207], v150 offset:36864
	ds_read_b128 v[208:211], v150 offset:37888
	ds_read_b128 v[212:215], v150 offset:38912
	ds_read_b128 v[216:219], v150 offset:39936
	global_load_lds_dwordx4 v[226:227], off
	v_lshl_add_u64 v[226:227], s[46:47], 0, v[132:133]
	s_mov_b32 m0, s57
	s_nop 0
	global_load_lds_dwordx4 v[226:227], off
	s_waitcnt lgkmcnt(0)
	s_setprio 1
	v_mfma_f32_16x16x32_bf16 v[126:129], v[152:155], v[184:187], v[126:129]
	v_mfma_f32_16x16x32_bf16 v[122:125], v[160:163], v[184:187], v[122:125]
	v_mfma_f32_16x16x32_bf16 v[118:121], v[152:155], v[196:199], v[118:121]
	v_mfma_f32_16x16x32_bf16 v[110:113], v[160:163], v[196:199], v[110:113]
	v_mfma_f32_16x16x32_bf16 v[102:105], v[152:155], v[204:207], v[102:105]
	v_mfma_f32_16x16x32_bf16 v[94:97], v[160:163], v[204:207], v[94:97]
	v_mfma_f32_16x16x32_bf16 v[86:89], v[152:155], v[212:215], v[86:89]
	v_mfma_f32_16x16x32_bf16 v[78:81], v[160:163], v[212:215], v[78:81]
	v_mfma_f32_16x16x32_bf16 v[126:129], v[156:159], v[188:191], v[126:129]
	v_mfma_f32_16x16x32_bf16 v[122:125], v[164:167], v[188:191], v[122:125]
	v_mfma_f32_16x16x32_bf16 v[118:121], v[156:159], v[200:203], v[118:121]
	v_mfma_f32_16x16x32_bf16 v[110:113], v[164:167], v[200:203], v[110:113]
	v_mfma_f32_16x16x32_bf16 v[102:105], v[156:159], v[208:211], v[102:105]
	v_mfma_f32_16x16x32_bf16 v[94:97], v[164:167], v[208:211], v[94:97]
	v_mfma_f32_16x16x32_bf16 v[86:89], v[156:159], v[216:219], v[86:89]
	v_mfma_f32_16x16x32_bf16 v[78:81], v[164:167], v[216:219], v[78:81]
	v_mfma_f32_16x16x32_bf16 v[114:117], v[168:171], v[184:187], v[114:117]
	v_mfma_f32_16x16x32_bf16 v[106:109], v[176:179], v[184:187], v[106:109]
	v_mfma_f32_16x16x32_bf16 v[98:101], v[168:171], v[196:199], v[98:101]
	v_mfma_f32_16x16x32_bf16 v[90:93], v[176:179], v[196:199], v[90:93]
	v_mfma_f32_16x16x32_bf16 v[82:85], v[168:171], v[204:207], v[82:85]
	v_mfma_f32_16x16x32_bf16 v[74:77], v[176:179], v[204:207], v[74:77]
	v_mfma_f32_16x16x32_bf16 v[70:73], v[168:171], v[212:215], v[70:73]
	v_mfma_f32_16x16x32_bf16 v[66:69], v[176:179], v[212:215], v[66:69]
	v_mfma_f32_16x16x32_bf16 v[114:117], v[172:175], v[188:191], v[114:117]
	v_mfma_f32_16x16x32_bf16 v[106:109], v[180:183], v[188:191], v[106:109]
	v_mfma_f32_16x16x32_bf16 v[98:101], v[172:175], v[200:203], v[98:101]
	v_mfma_f32_16x16x32_bf16 v[90:93], v[180:183], v[200:203], v[90:93]
	v_mfma_f32_16x16x32_bf16 v[82:85], v[172:175], v[208:211], v[82:85]
	v_mfma_f32_16x16x32_bf16 v[74:77], v[180:183], v[208:211], v[74:77]
	v_mfma_f32_16x16x32_bf16 v[70:73], v[172:175], v[216:219], v[70:73]
	v_mfma_f32_16x16x32_bf16 v[66:69], v[180:183], v[216:219], v[66:69]
	s_setprio 0
	s_waitcnt vmcnt(8)
	s_barrier
	s_add_i32 s46, s71, s54
	v_lshl_add_u64 v[192:193], v[192:193], 0, s[10:11]
	s_mov_b32 m0, s46
	ds_read_b128 v[184:187], v150 offset:49152
	ds_read_b128 v[188:191], v150 offset:50176
	ds_read_b128 v[196:199], v150 offset:51200
	ds_read_b128 v[200:203], v150 offset:52224
	ds_read_b128 v[204:207], v150 offset:53248
	ds_read_b128 v[208:211], v150 offset:54272
	ds_read_b128 v[212:215], v150 offset:55296
	ds_read_b128 v[216:219], v150 offset:56320
	global_load_lds_dwordx4 v[192:193], off
	s_add_i32 m0, s46, 0x2000
	s_add_u32 s42, s42, 0x100080
	v_lshl_add_u64 v[192:193], v[220:221], 0, s[10:11]
	s_addc_u32 s43, s43, 0
	s_add_i32 s46, s72, s54
	global_load_lds_dwordx4 v[192:193], off
	v_lshl_add_u64 v[192:193], s[42:43], 0, v[130:131]
	s_mov_b32 m0, s46
	s_nop 0
	global_load_lds_dwordx4 v[192:193], off
	v_lshl_add_u64 v[192:193], s[42:43], 0, v[132:133]
	s_add_i32 m0, s46, 0x2000
	s_nop 0
	global_load_lds_dwordx4 v[192:193], off
	v_lshl_add_u64 v[192:193], v[222:223], 0, s[10:11]
	s_mov_b32 m0, s59
	s_nop 0
	global_load_lds_dwordx4 v[192:193], off
	v_lshl_add_u64 v[192:193], v[224:225], 0, s[10:11]
	s_mov_b32 m0, s60
	s_nop 0
	global_load_lds_dwordx4 v[192:193], off
	s_waitcnt lgkmcnt(0)
	s_setprio 1
	v_mfma_f32_16x16x32_bf16 v[62:65], v[152:155], v[184:187], v[62:65]
	v_mfma_f32_16x16x32_bf16 v[58:61], v[160:163], v[184:187], v[58:61]
	v_mfma_f32_16x16x32_bf16 v[54:57], v[152:155], v[196:199], v[54:57]
	v_mfma_f32_16x16x32_bf16 v[46:49], v[160:163], v[196:199], v[46:49]
	v_mfma_f32_16x16x32_bf16 v[38:41], v[152:155], v[204:207], v[38:41]
	v_mfma_f32_16x16x32_bf16 v[30:33], v[160:163], v[204:207], v[30:33]
	v_mfma_f32_16x16x32_bf16 v[22:25], v[152:155], v[212:215], v[22:25]
	v_mfma_f32_16x16x32_bf16 v[14:17], v[160:163], v[212:215], v[14:17]
	v_mfma_f32_16x16x32_bf16 v[62:65], v[156:159], v[188:191], v[62:65]
	v_mfma_f32_16x16x32_bf16 v[58:61], v[164:167], v[188:191], v[58:61]
	v_mfma_f32_16x16x32_bf16 v[54:57], v[156:159], v[200:203], v[54:57]
	v_mfma_f32_16x16x32_bf16 v[46:49], v[164:167], v[200:203], v[46:49]
	v_mfma_f32_16x16x32_bf16 v[38:41], v[156:159], v[208:211], v[38:41]
	v_mfma_f32_16x16x32_bf16 v[30:33], v[164:167], v[208:211], v[30:33]
	v_mfma_f32_16x16x32_bf16 v[22:25], v[156:159], v[216:219], v[22:25]
	v_mfma_f32_16x16x32_bf16 v[14:17], v[164:167], v[216:219], v[14:17]
	v_mfma_f32_16x16x32_bf16 v[50:53], v[168:171], v[184:187], v[50:53]
	v_mfma_f32_16x16x32_bf16 v[42:45], v[176:179], v[184:187], v[42:45]
	v_mfma_f32_16x16x32_bf16 v[34:37], v[168:171], v[196:199], v[34:37]
	v_mfma_f32_16x16x32_bf16 v[26:29], v[176:179], v[196:199], v[26:29]
	v_mfma_f32_16x16x32_bf16 v[18:21], v[168:171], v[204:207], v[18:21]
	v_mfma_f32_16x16x32_bf16 v[10:13], v[176:179], v[204:207], v[10:13]
	v_mfma_f32_16x16x32_bf16 v[6:9], v[168:171], v[212:215], v[6:9]
	v_mfma_f32_16x16x32_bf16 v[2:5], v[176:179], v[212:215], v[2:5]
	v_mfma_f32_16x16x32_bf16 v[50:53], v[172:175], v[188:191], v[50:53]
	v_mfma_f32_16x16x32_bf16 v[42:45], v[180:183], v[188:191], v[42:45]
	v_mfma_f32_16x16x32_bf16 v[34:37], v[172:175], v[200:203], v[34:37]
	v_mfma_f32_16x16x32_bf16 v[26:29], v[180:183], v[200:203], v[26:29]
	v_mfma_f32_16x16x32_bf16 v[18:21], v[172:175], v[208:211], v[18:21]
	v_mfma_f32_16x16x32_bf16 v[10:13], v[180:183], v[208:211], v[10:13]
	v_mfma_f32_16x16x32_bf16 v[6:9], v[172:175], v[216:219], v[6:9]
	v_mfma_f32_16x16x32_bf16 v[2:5], v[180:183], v[216:219], v[2:5]
	s_setprio 0
	s_waitcnt vmcnt(8)
	s_barrier
	s_add_i32 s70, s70, 2
	s_add_u32 s40, s40, 0x100
	s_addc_u32 s41, s41, 0
	s_add_u32 s68, s68, 0x100
	s_addc_u32 s69, s69, 0
	s_cmp_gt_u32 s70, 61
	s_cbranch_scc0 .Lkt_L_4
	s_branch .Lkt_exit_4
.Lkt_T_4:
	ds_read_b128 v[152:155], v144
	ds_read_b128 v[156:159], v144 offset:1024
	ds_read_b128 v[160:163], v144 offset:2048
	ds_read_b128 v[164:167], v144 offset:3072
	ds_read_b128 v[168:171], v145
	ds_read_b128 v[172:175], v145 offset:1024
	ds_read_b128 v[176:179], v145 offset:2048
	ds_read_b128 v[180:183], v145 offset:3072
	s_add_u32 s42, s40, 0xfff00080
	s_addc_u32 s43, s41, -1
	s_cmp_eq_u32 s70, 60
	s_cselect_b32 s47, s27, s43
	s_cselect_b32 s46, s66, s42
	s_cselect_b32 s43, s25, s69
	s_cselect_b32 s42, s67, s68
	v_lshl_add_u64 v[192:193], s[40:41], 0, v[134:135]
	s_add_i32 m0, s29, 0xc000
	ds_read_b128 v[184:187], v150
	ds_read_b128 v[188:191], v150 offset:1024
	ds_read_b128 v[196:199], v150 offset:2048
	ds_read_b128 v[200:203], v150 offset:3072
	ds_read_b128 v[204:207], v150 offset:4096
	ds_read_b128 v[208:211], v150 offset:5120
	ds_read_b128 v[212:215], v150 offset:6144
	ds_read_b128 v[216:219], v150 offset:7168
	global_load_lds_dwordx4 v[192:193], off
	v_lshl_add_u64 v[192:193], s[40:41], 0, v[136:137]
	s_add_i32 m0, s29, 0xe000
	s_nop 0
	global_load_lds_dwordx4 v[192:193], off
	s_waitcnt vmcnt(8)
	s_waitcnt lgkmcnt(0)
	s_barrier
	s_setprio 2
	v_mfma_f32_16x16x32_bf16 v[126:129], v[152:155], v[184:187], v[126:129]
	v_mfma_f32_16x16x32_bf16 v[122:125], v[160:163], v[184:187], v[122:125]
	v_mfma_f32_16x16x32_bf16 v[118:121], v[152:155], v[196:199], v[118:121]
	v_mfma_f32_16x16x32_bf16 v[110:113], v[160:163], v[196:199], v[110:113]
	v_mfma_f32_16x16x32_bf16 v[102:105], v[152:155], v[204:207], v[102:105]
	v_mfma_f32_16x16x32_bf16 v[94:97], v[160:163], v[204:207], v[94:97]
	v_mfma_f32_16x16x32_bf16 v[86:89], v[152:155], v[212:215], v[86:89]
	v_mfma_f32_16x16x32_bf16 v[78:81], v[160:163], v[212:215], v[78:81]
	v_mfma_f32_16x16x32_bf16 v[126:129], v[156:159], v[188:191], v[126:129]
	v_mfma_f32_16x16x32_bf16 v[122:125], v[164:167], v[188:191], v[122:125]
	v_mfma_f32_16x16x32_bf16 v[118:121], v[156:159], v[200:203], v[118:121]
	v_mfma_f32_16x16x32_bf16 v[110:113], v[164:167], v[200:203], v[110:113]
	v_mfma_f32_16x16x32_bf16 v[102:105], v[156:159], v[208:211], v[102:105]
	v_mfma_f32_16x16x32_bf16 v[94:97], v[164:167], v[208:211], v[94:97]
	v_mfma_f32_16x16x32_bf16 v[86:89], v[156:159], v[216:219], v[86:89]
	v_mfma_f32_16x16x32_bf16 v[78:81], v[164:167], v[216:219], v[78:81]
	v_mfma_f32_16x16x32_bf16 v[114:117], v[168:171], v[184:187], v[114:117]
	v_mfma_f32_16x16x32_bf16 v[106:109], v[176:179], v[184:187], v[106:109]
	v_mfma_f32_16x16x32_bf16 v[98:101], v[168:171], v[196:199], v[98:101]
	v_mfma_f32_16x16x32_bf16 v[90:93], v[176:179], v[196:199], v[90:93]
	v_mfma_f32_16x16x32_bf16 v[82:85], v[168:171], v[204:207], v[82:85]
	v_mfma_f32_16x16x32_bf16 v[74:77], v[176:179], v[204:207], v[74:77]
	v_mfma_f32_16x16x32_bf16 v[70:73], v[168:171], v[212:215], v[70:73]
	v_mfma_f32_16x16x32_bf16 v[66:69], v[176:179], v[212:215], v[66:69]
	v_mfma_f32_16x16x32_bf16 v[114:117], v[172:175], v[188:191], v[114:117]
	v_mfma_f32_16x16x32_bf16 v[106:109], v[180:183], v[188:191], v[106:109]
	v_mfma_f32_16x16x32_bf16 v[98:101], v[172:175], v[200:203], v[98:101]
	v_mfma_f32_16x16x32_bf16 v[90:93], v[180:183], v[200:203], v[90:93]
	v_mfma_f32_16x16x32_bf16 v[82:85], v[172:175], v[208:211], v[82:85]
	v_mfma_f32_16x16x32_bf16 v[74:77], v[180:183], v[208:211], v[74:77]
	v_mfma_f32_16x16x32_bf16 v[70:73], v[172:175], v[216:219], v[70:73]
	v_mfma_f32_16x16x32_bf16 v[66:69], v[180:183], v[216:219], v[66:69]
	s_setprio 0
	s_add_i32 s71, s62, s54
	v_lshl_add_u64 v[192:193], s[42:43], 0, v[130:131]
	s_mov_b32 m0, s71
	ds_read_b128 v[184:187], v150 offset:16384
	ds_read_b128 v[188:191], v150 offset:17408
	ds_read_b128 v[196:199], v150 offset:18432
	ds_read_b128 v[200:203], v150 offset:19456
	ds_read_b128 v[204:207], v150 offset:20480
	ds_read_b128 v[208:211], v150 offset:21504
	ds_read_b128 v[212:215], v150 offset:22528
	ds_read_b128 v[216:219], v150 offset:23552
	global_load_lds_dwordx4 v[192:193], off
	s_add_i32 m0, s71, 0x2000
	s_add_u32 s72, s42, 0x100000
	v_lshl_add_u64 v[220:221], s[42:43], 0, v[132:133]
	s_addc_u32 s73, s43, 0
	s_add_i32 s71, s63, s54
	global_load_lds_dwordx4 v[220:221], off
	v_lshl_add_u64 v[222:223], s[72:73], 0, v[130:131]
	s_mov_b32 m0, s71
	v_lshl_add_u64 v[224:225], s[46:47], 0, v[132:133]
	global_load_lds_dwordx4 v[222:223], off
	v_lshl_add_u64 v[222:223], s[72:73], 0, v[132:133]
	s_add_i32 m0, s71, 0x2000
	s_nop 0
	global_load_lds_dwordx4 v[222:223], off
	v_lshl_add_u64 v[222:223], s[46:47], 0, v[130:131]
	s_mov_b32 m0, s29
	s_nop 0
	global_load_lds_dwordx4 v[222:223], off
	s_mov_b32 m0, s55
	s_nop 0
	global_load_lds_dwordx4 v[224:225], off
	s_waitcnt vmcnt(8)
	s_waitcnt lgkmcnt(0)
	s_barrier
	s_setprio 2
	v_mfma_f32_16x16x32_bf16 v[62:65], v[152:155], v[184:187], v[62:65]
	v_mfma_f32_16x16x32_bf16 v[58:61], v[160:163], v[184:187], v[58:61]
	v_mfma_f32_16x16x32_bf16 v[54:57], v[152:155], v[196:199], v[54:57]
	v_mfma_f32_16x16x32_bf16 v[46:49], v[160:163], v[196:199], v[46:49]
	v_mfma_f32_16x16x32_bf16 v[38:41], v[152:155], v[204:207], v[38:41]
	v_mfma_f32_16x16x32_bf16 v[30:33], v[160:163], v[204:207], v[30:33]
	v_mfma_f32_16x16x32_bf16 v[22:25], v[152:155], v[212:215], v[22:25]
	v_mfma_f32_16x16x32_bf16 v[14:17], v[160:163], v[212:215], v[14:17]
	v_mfma_f32_16x16x32_bf16 v[62:65], v[156:159], v[188:191], v[62:65]
	v_mfma_f32_16x16x32_bf16 v[58:61], v[164:167], v[188:191], v[58:61]
	v_mfma_f32_16x16x32_bf16 v[54:57], v[156:159], v[200:203], v[54:57]
	v_mfma_f32_16x16x32_bf16 v[46:49], v[164:167], v[200:203], v[46:49]
	v_mfma_f32_16x16x32_bf16 v[38:41], v[156:159], v[208:211], v[38:41]
	v_mfma_f32_16x16x32_bf16 v[30:33], v[164:167], v[208:211], v[30:33]
	v_mfma_f32_16x16x32_bf16 v[22:25], v[156:159], v[216:219], v[22:25]
	v_mfma_f32_16x16x32_bf16 v[14:17], v[164:167], v[216:219], v[14:17]
	v_mfma_f32_16x16x32_bf16 v[50:53], v[168:171], v[184:187], v[50:53]
	v_mfma_f32_16x16x32_bf16 v[42:45], v[176:179], v[184:187], v[42:45]
	v_mfma_f32_16x16x32_bf16 v[34:37], v[168:171], v[196:199], v[34:37]
	v_mfma_f32_16x16x32_bf16 v[26:29], v[176:179], v[196:199], v[26:29]
	v_mfma_f32_16x16x32_bf16 v[18:21], v[168:171], v[204:207], v[18:21]
	v_mfma_f32_16x16x32_bf16 v[10:13], v[176:179], v[204:207], v[10:13]
	v_mfma_f32_16x16x32_bf16 v[6:9], v[168:171], v[212:215], v[6:9]
	v_mfma_f32_16x16x32_bf16 v[2:5], v[176:179], v[212:215], v[2:5]
	v_mfma_f32_16x16x32_bf16 v[50:53], v[172:175], v[188:191], v[50:53]
	v_mfma_f32_16x16x32_bf16 v[42:45], v[180:183], v[188:191], v[42:45]
	v_mfma_f32_16x16x32_bf16 v[34:37], v[172:175], v[200:203], v[34:37]
	v_mfma_f32_16x16x32_bf16 v[26:29], v[180:183], v[200:203], v[26:29]
	v_mfma_f32_16x16x32_bf16 v[18:21], v[172:175], v[208:211], v[18:21]
	v_mfma_f32_16x16x32_bf16 v[10:13], v[180:183], v[208:211], v[10:13]
	v_mfma_f32_16x16x32_bf16 v[6:9], v[172:175], v[216:219], v[6:9]
	v_mfma_f32_16x16x32_bf16 v[2:5], v[180:183], v[216:219], v[2:5]
	s_setprio 0
	s_add_i32 s71, 0, 0x18000
	v_add_u32_e32 v151, s71, v142
	s_add_i32 s72, 0, 0x1c000
	ds_read_b128 v[152:155], v151
	ds_read_b128 v[156:159], v151 offset:1024
	ds_read_b128 v[160:163], v151 offset:2048
	ds_read_b128 v[164:167], v151 offset:3072
	v_add_u32_e32 v151, s72, v142
	ds_read_b128 v[168:171], v151
	ds_read_b128 v[172:175], v151 offset:1024
	ds_read_b128 v[176:179], v151 offset:2048
	ds_read_b128 v[180:183], v151 offset:3072
	s_add_u32 s46, s46, 0x100000
	s_addc_u32 s47, s47, 0
	s_mov_b32 m0, s56
	v_lshl_add_u64 v[226:227], s[46:47], 0, v[130:131]
	ds_read_b128 v[184:187], v150 offset:32768
	ds_read_b128 v[188:191], v150 offset:33792
	ds_read_b128 v[196:199], v150 offset:34816
	ds_read_b128 v[200:203], v150 offset:35840
	ds_read_b128 v[204:207], v150 offset:36864
	ds_read_b128 v[208:211], v150 offset:37888
	ds_read_b128 v[212:215], v150 offset:38912
	ds_read_b128 v[216:219], v150 offset:39936
	global_load_lds_dwordx4 v[226:227], off
	v_lshl_add_u64 v[226:227], s[46:47], 0, v[132:133]
	s_mov_b32 m0, s57
	s_nop 0
	global_load_lds_dwordx4 v[226:227], off
	s_waitcnt vmcnt(8)
	s_waitcnt lgkmcnt(0)
	s_barrier
	s_setprio 2
	v_mfma_f32_16x16x32_bf16 v[126:129], v[152:155], v[184:187], v[126:129]
	v_mfma_f32_16x16x32_bf16 v[122:125], v[160:163], v[184:187], v[122:125]
	v_mfma_f32_16x16x32_bf16 v[118:121], v[152:155], v[196:199], v[118:121]
	v_mfma_f32_16x16x32_bf16 v[110:113], v[160:163], v[196:199], v[110:113]
	v_mfma_f32_16x16x32_bf16 v[102:105], v[152:155], v[204:207], v[102:105]
	v_mfma_f32_16x16x32_bf16 v[94:97], v[160:163], v[204:207], v[94:97]
	v_mfma_f32_16x16x32_bf16 v[86:89], v[152:155], v[212:215], v[86:89]
	v_mfma_f32_16x16x32_bf16 v[78:81], v[160:163], v[212:215], v[78:81]
	v_mfma_f32_16x16x32_bf16 v[126:129], v[156:159], v[188:191], v[126:129]
	v_mfma_f32_16x16x32_bf16 v[122:125], v[164:167], v[188:191], v[122:125]
	v_mfma_f32_16x16x32_bf16 v[118:121], v[156:159], v[200:203], v[118:121]
	v_mfma_f32_16x16x32_bf16 v[110:113], v[164:167], v[200:203], v[110:113]
	v_mfma_f32_16x16x32_bf16 v[102:105], v[156:159], v[208:211], v[102:105]
	v_mfma_f32_16x16x32_bf16 v[94:97], v[164:167], v[208:211], v[94:97]
	v_mfma_f32_16x16x32_bf16 v[86:89], v[156:159], v[216:219], v[86:89]
	v_mfma_f32_16x16x32_bf16 v[78:81], v[164:167], v[216:219], v[78:81]
	v_mfma_f32_16x16x32_bf16 v[114:117], v[168:171], v[184:187], v[114:117]
	v_mfma_f32_16x16x32_bf16 v[106:109], v[176:179], v[184:187], v[106:109]
	v_mfma_f32_16x16x32_bf16 v[98:101], v[168:171], v[196:199], v[98:101]
	v_mfma_f32_16x16x32_bf16 v[90:93], v[176:179], v[196:199], v[90:93]
	v_mfma_f32_16x16x32_bf16 v[82:85], v[168:171], v[204:207], v[82:85]
	v_mfma_f32_16x16x32_bf16 v[74:77], v[176:179], v[204:207], v[74:77]
	v_mfma_f32_16x16x32_bf16 v[70:73], v[168:171], v[212:215], v[70:73]
	v_mfma_f32_16x16x32_bf16 v[66:69], v[176:179], v[212:215], v[66:69]
	v_mfma_f32_16x16x32_bf16 v[114:117], v[172:175], v[188:191], v[114:117]
	v_mfma_f32_16x16x32_bf16 v[106:109], v[180:183], v[188:191], v[106:109]
	v_mfma_f32_16x16x32_bf16 v[98:101], v[172:175], v[200:203], v[98:101]
	v_mfma_f32_16x16x32_bf16 v[90:93], v[180:183], v[200:203], v[90:93]
	v_mfma_f32_16x16x32_bf16 v[82:85], v[172:175], v[208:211], v[82:85]
	v_mfma_f32_16x16x32_bf16 v[74:77], v[180:183], v[208:211], v[74:77]
	v_mfma_f32_16x16x32_bf16 v[70:73], v[172:175], v[216:219], v[70:73]
	v_mfma_f32_16x16x32_bf16 v[66:69], v[180:183], v[216:219], v[66:69]
	s_setprio 0
	s_add_i32 s46, s71, s54
	v_lshl_add_u64 v[192:193], v[192:193], 0, s[10:11]
	s_mov_b32 m0, s46
	ds_read_b128 v[184:187], v150 offset:49152
	ds_read_b128 v[188:191], v150 offset:50176
	ds_read_b128 v[196:199], v150 offset:51200
	ds_read_b128 v[200:203], v150 offset:52224
	ds_read_b128 v[204:207], v150 offset:53248
	ds_read_b128 v[208:211], v150 offset:54272
	ds_read_b128 v[212:215], v150 offset:55296
	ds_read_b128 v[216:219], v150 offset:56320
	global_load_lds_dwordx4 v[192:193], off
	s_add_i32 m0, s46, 0x2000
	s_add_u32 s42, s42, 0x100080
	v_lshl_add_u64 v[192:193], v[220:221], 0, s[10:11]
	s_addc_u32 s43, s43, 0
	s_add_i32 s46, s72, s54
	global_load_lds_dwordx4 v[192:193], off
	v_lshl_add_u64 v[192:193], s[42:43], 0, v[130:131]
	s_mov_b32 m0, s46
	s_nop 0
	global_load_lds_dwordx4 v[192:193], off
	v_lshl_add_u64 v[192:193], s[42:43], 0, v[132:133]
	s_add_i32 m0, s46, 0x2000
	s_nop 0
	global_load_lds_dwordx4 v[192:193], off
	v_lshl_add_u64 v[192:193], v[222:223], 0, s[10:11]
	s_mov_b32 m0, s59
	s_nop 0
	global_load_lds_dwordx4 v[192:193], off
	v_lshl_add_u64 v[192:193], v[224:225], 0, s[10:11]
	s_mov_b32 m0, s60
	s_nop 0
	global_load_lds_dwordx4 v[192:193], off
	s_waitcnt vmcnt(8)
	s_waitcnt lgkmcnt(0)
	s_barrier
	s_setprio 2
	v_mfma_f32_16x16x32_bf16 v[62:65], v[152:155], v[184:187], v[62:65]
	v_mfma_f32_16x16x32_bf16 v[58:61], v[160:163], v[184:187], v[58:61]
	v_mfma_f32_16x16x32_bf16 v[54:57], v[152:155], v[196:199], v[54:57]
	v_mfma_f32_16x16x32_bf16 v[46:49], v[160:163], v[196:199], v[46:49]
	v_mfma_f32_16x16x32_bf16 v[38:41], v[152:155], v[204:207], v[38:41]
	v_mfma_f32_16x16x32_bf16 v[30:33], v[160:163], v[204:207], v[30:33]
	v_mfma_f32_16x16x32_bf16 v[22:25], v[152:155], v[212:215], v[22:25]
	v_mfma_f32_16x16x32_bf16 v[14:17], v[160:163], v[212:215], v[14:17]
	v_mfma_f32_16x16x32_bf16 v[62:65], v[156:159], v[188:191], v[62:65]
	v_mfma_f32_16x16x32_bf16 v[58:61], v[164:167], v[188:191], v[58:61]
	v_mfma_f32_16x16x32_bf16 v[54:57], v[156:159], v[200:203], v[54:57]
	v_mfma_f32_16x16x32_bf16 v[46:49], v[164:167], v[200:203], v[46:49]
	v_mfma_f32_16x16x32_bf16 v[38:41], v[156:159], v[208:211], v[38:41]
	v_mfma_f32_16x16x32_bf16 v[30:33], v[164:167], v[208:211], v[30:33]
	v_mfma_f32_16x16x32_bf16 v[22:25], v[156:159], v[216:219], v[22:25]
	v_mfma_f32_16x16x32_bf16 v[14:17], v[164:167], v[216:219], v[14:17]
	v_mfma_f32_16x16x32_bf16 v[50:53], v[168:171], v[184:187], v[50:53]
	v_mfma_f32_16x16x32_bf16 v[42:45], v[176:179], v[184:187], v[42:45]
	v_mfma_f32_16x16x32_bf16 v[34:37], v[168:171], v[196:199], v[34:37]
	v_mfma_f32_16x16x32_bf16 v[26:29], v[176:179], v[196:199], v[26:29]
	v_mfma_f32_16x16x32_bf16 v[18:21], v[168:171], v[204:207], v[18:21]
	v_mfma_f32_16x16x32_bf16 v[10:13], v[176:179], v[204:207], v[10:13]
	v_mfma_f32_16x16x32_bf16 v[6:9], v[168:171], v[212:215], v[6:9]
	v_mfma_f32_16x16x32_bf16 v[2:5], v[176:179], v[212:215], v[2:5]
	v_mfma_f32_16x16x32_bf16 v[50:53], v[172:175], v[188:191], v[50:53]
	v_mfma_f32_16x16x32_bf16 v[42:45], v[180:183], v[188:191], v[42:45]
	v_mfma_f32_16x16x32_bf16 v[34:37], v[172:175], v[200:203], v[34:37]
	v_mfma_f32_16x16x32_bf16 v[26:29], v[180:183], v[200:203], v[26:29]
	v_mfma_f32_16x16x32_bf16 v[18:21], v[172:175], v[208:211], v[18:21]
	v_mfma_f32_16x16x32_bf16 v[10:13], v[180:183], v[208:211], v[10:13]
	v_mfma_f32_16x16x32_bf16 v[6:9], v[172:175], v[216:219], v[6:9]
	v_mfma_f32_16x16x32_bf16 v[2:5], v[180:183], v[216:219], v[2:5]
	s_setprio 0
	s_add_i32 s70, s70, 2
	s_add_u32 s40, s40, 0x100
	s_addc_u32 s41, s41, 0
	s_add_u32 s68, s68, 0x100
	s_addc_u32 s69, s69, 0
	s_cmp_gt_u32 s70, 61
	s_cbranch_scc0 .Lkt_T_4
	s_nop 7

.LBB0_695:
	s_add_u32 s8, s38, 0x43c00000
	s_addc_u32 s9, s39, 0
	s_lshl_b32 s10, s10, 5
	s_and_b32 s18, s10, 0x60
	s_mov_b64 s[10:11], 0x80
	s_add_i32 m0, s29, 0x18000
	v_lshl_add_u64 v[8:9], v[8:9], 0, s[10:11]
	s_lshl_b32 s15, s14, 13
	s_waitcnt vmcnt(2)
	s_barrier
	global_load_lds_dwordx4 v[8:9], off
	v_lshl_add_u64 v[6:7], v[6:7], 0, s[10:11]
	s_add_i32 m0, s29, 0x1a000
	s_add_i32 s56, s29, 0x8000
	s_add_i32 s57, s29, 0xa000
	global_load_lds_dwordx4 v[6:7], off
	v_lshl_add_u64 v[2:3], v[2:3], 0, s[10:11]
	s_mov_b32 m0, s56
	s_add_u32 s16, s42, 0x100080
	global_load_lds_dwordx4 v[2:3], off
	v_lshl_add_u64 v[2:3], v[4:5], 0, s[10:11]
	s_mov_b32 m0, s57
	s_addc_u32 s17, s43, 0
	global_load_lds_dwordx4 v[2:3], off
	s_add_i32 m0, s29, 0x1c000
	v_lshl_add_u64 v[2:3], s[16:17], 0, v[130:131]
	global_load_lds_dwordx4 v[2:3], off
	v_lshl_add_u64 v[2:3], s[16:17], 0, v[132:133]
	s_add_i32 m0, s29, 0x1e000
	v_lshlrev_b32_e32 v4, 13, v148
	global_load_lds_dwordx4 v[2:3], off
	v_lshlrev_b32_e32 v3, 10, v0
	v_and_b32_e32 v3, 0x60000, v3
	v_or3_b32 v3, v146, v3, v4
	s_sext_i32_i8 s62, s12
	v_lshl_or_b32 v141, s14, 6, v1
	v_lshlrev_b32_e32 v2, 6, v1
	s_movk_i32 s12, 0x3c0
	v_lshlrev_b32_e32 v1, 2, v1
	v_add_u32_e32 v134, v3, v147
	v_lshlrev_b32_e32 v3, 6, v149
	v_and_or_b32 v2, v2, s12, v140
	v_and_b32_e32 v1, 32, v1
	s_waitcnt vmcnt(6)
	s_cmpk_lt_u32 s13, 0x100
	v_and_b32_e32 v3, 0xe0000, v3
	v_bitop3_b32 v2, v2, s15, v1 bitop3:0xde
	v_lshl_or_b32 v1, s18, 7, v139
	s_cselect_b64 s[12:13], -1, 0
	v_or3_b32 v3, v146, v3, v4
	s_add_i32 s59, 0, 0x10000
	s_add_i32 s60, 0, 0x14000
	s_ashr_i32 s58, s44, 31
	v_lshl_or_b32 v138, v138, 2, s18
	v_mov_b32_e32 v135, v131
	v_add_u32_e32 v136, v3, v147
	v_mov_b32_e32 v137, v131
	v_add_u32_e32 v139, s59, v1
	v_add_u32_e32 v140, s60, v1
	v_add_u32_e32 v142, 0, v2
	s_mov_b32 s61, 0x8400000
	s_mov_b64 s[14:15], 0x40000
	s_mov_b64 s[16:17], 0x48000
	s_mov_b64 s[18:19], 0x50000
	s_mov_b64 s[20:21], 0x58000
	s_waitcnt vmcnt(0)
	s_branch .LBB0_698

.Lkt_L_5:
	ds_read_b128 v[144:147], v139
	ds_read_b128 v[148:151], v139 offset:1024
	ds_read_b128 v[152:155], v139 offset:2048
	ds_read_b128 v[156:159], v139 offset:3072
	ds_read_b128 v[160:163], v140
	ds_read_b128 v[164:167], v140 offset:1024
	ds_read_b128 v[168:171], v140 offset:2048
	ds_read_b128 v[172:175], v140 offset:3072
	s_add_u32 s42, s40, 0xfff00080
	s_addc_u32 s43, s41, -1
	s_cmp_eq_u32 s67, 60
	s_cselect_b32 s47, s27, s43
	s_cselect_b32 s46, s63, s42
	s_cselect_b32 s43, s25, s66
	s_cselect_b32 s42, s64, s65
	v_lshl_add_u64 v[192:193], s[40:41], 0, v[134:135]
	s_add_i32 m0, s29, 0xc000
	ds_read_b128 v[176:179], v142
	ds_read_b128 v[180:183], v142 offset:1024
	ds_read_b128 v[184:187], v142 offset:2048
	ds_read_b128 v[188:191], v142 offset:3072
	ds_read_b128 v[196:199], v142 offset:4096
	ds_read_b128 v[200:203], v142 offset:5120
	ds_read_b128 v[204:207], v142 offset:6144
	ds_read_b128 v[208:211], v142 offset:7168
	global_load_lds_dwordx4 v[192:193], off
	v_lshl_add_u64 v[192:193], s[40:41], 0, v[136:137]
	s_add_i32 m0, s29, 0xe000
	s_nop 0
	global_load_lds_dwordx4 v[192:193], off
	s_waitcnt lgkmcnt(0)
	s_setprio 1
	v_mfma_f32_16x16x32_bf16 v[126:129], v[144:147], v[176:179], v[126:129]
	v_mfma_f32_16x16x32_bf16 v[122:125], v[152:155], v[176:179], v[122:125]
	v_mfma_f32_16x16x32_bf16 v[118:121], v[144:147], v[184:187], v[118:121]
	v_mfma_f32_16x16x32_bf16 v[110:113], v[152:155], v[184:187], v[110:113]
	v_mfma_f32_16x16x32_bf16 v[102:105], v[144:147], v[196:199], v[102:105]
	v_mfma_f32_16x16x32_bf16 v[94:97], v[152:155], v[196:199], v[94:97]
	v_mfma_f32_16x16x32_bf16 v[86:89], v[144:147], v[204:207], v[86:89]
	v_mfma_f32_16x16x32_bf16 v[78:81], v[152:155], v[204:207], v[78:81]
	v_mfma_f32_16x16x32_bf16 v[126:129], v[148:151], v[180:183], v[126:129]
	v_mfma_f32_16x16x32_bf16 v[122:125], v[156:159], v[180:183], v[122:125]
	v_mfma_f32_16x16x32_bf16 v[118:121], v[148:151], v[188:191], v[118:121]
	v_mfma_f32_16x16x32_bf16 v[110:113], v[156:159], v[188:191], v[110:113]
	v_mfma_f32_16x16x32_bf16 v[102:105], v[148:151], v[200:203], v[102:105]
	v_mfma_f32_16x16x32_bf16 v[94:97], v[156:159], v[200:203], v[94:97]
	v_mfma_f32_16x16x32_bf16 v[86:89], v[148:151], v[208:211], v[86:89]
	v_mfma_f32_16x16x32_bf16 v[78:81], v[156:159], v[208:211], v[78:81]
	v_mfma_f32_16x16x32_bf16 v[114:117], v[160:163], v[176:179], v[114:117]
	v_mfma_f32_16x16x32_bf16 v[106:109], v[168:171], v[176:179], v[106:109]
	v_mfma_f32_16x16x32_bf16 v[98:101], v[160:163], v[184:187], v[98:101]
	v_mfma_f32_16x16x32_bf16 v[90:93], v[168:171], v[184:187], v[90:93]
	v_mfma_f32_16x16x32_bf16 v[82:85], v[160:163], v[196:199], v[82:85]
	v_mfma_f32_16x16x32_bf16 v[74:77], v[168:171], v[196:199], v[74:77]
	v_mfma_f32_16x16x32_bf16 v[70:73], v[160:163], v[204:207], v[70:73]
	v_mfma_f32_16x16x32_bf16 v[66:69], v[168:171], v[204:207], v[66:69]
	v_mfma_f32_16x16x32_bf16 v[114:117], v[164:167], v[180:183], v[114:117]
	v_mfma_f32_16x16x32_bf16 v[106:109], v[172:175], v[180:183], v[106:109]
	v_mfma_f32_16x16x32_bf16 v[98:101], v[164:167], v[188:191], v[98:101]
	v_mfma_f32_16x16x32_bf16 v[90:93], v[172:175], v[188:191], v[90:93]
	v_mfma_f32_16x16x32_bf16 v[82:85], v[164:167], v[200:203], v[82:85]
	v_mfma_f32_16x16x32_bf16 v[74:77], v[172:175], v[200:203], v[74:77]
	v_mfma_f32_16x16x32_bf16 v[70:73], v[164:167], v[208:211], v[70:73]
	v_mfma_f32_16x16x32_bf16 v[66:69], v[172:175], v[208:211], v[66:69]
	s_setprio 0
	s_waitcnt vmcnt(8)
	s_barrier
	s_add_i32 s68, s59, s51
	v_lshl_add_u64 v[192:193], s[42:43], 0, v[130:131]
	s_mov_b32 m0, s68
	ds_read_b128 v[176:179], v142 offset:16384
	ds_read_b128 v[180:183], v142 offset:17408
	ds_read_b128 v[184:187], v142 offset:18432
	ds_read_b128 v[188:191], v142 offset:19456
	ds_read_b128 v[196:199], v142 offset:20480
	ds_read_b128 v[200:203], v142 offset:21504
	ds_read_b128 v[204:207], v142 offset:22528
	ds_read_b128 v[208:211], v142 offset:23552
	global_load_lds_dwordx4 v[192:193], off
	s_add_i32 m0, s68, 0x2000
	s_add_u32 s68, s42, 0x100000
	v_lshl_add_u64 v[212:213], s[42:43], 0, v[132:133]
	s_addc_u32 s69, s43, 0
	s_add_i32 s70, s60, s51
	global_load_lds_dwordx4 v[212:213], off
	v_lshl_add_u64 v[214:215], s[68:69], 0, v[130:131]
	s_mov_b32 m0, s70
	v_lshl_add_u64 v[216:217], s[46:47], 0, v[132:133]
	global_load_lds_dwordx4 v[214:215], off
	v_lshl_add_u64 v[214:215], s[68:69], 0, v[132:133]
	s_add_i32 m0, s70, 0x2000
	s_nop 0
	global_load_lds_dwordx4 v[214:215], off
	v_lshl_add_u64 v[214:215], s[46:47], 0, v[130:131]
	s_mov_b32 m0, s29
	s_nop 0
	global_load_lds_dwordx4 v[214:215], off
	s_mov_b32 m0, s52
	s_nop 0
	global_load_lds_dwordx4 v[216:217], off
	s_waitcnt lgkmcnt(0)
	s_setprio 1
	v_mfma_f32_16x16x32_bf16 v[62:65], v[144:147], v[176:179], v[62:65]
	v_mfma_f32_16x16x32_bf16 v[58:61], v[152:155], v[176:179], v[58:61]
	v_mfma_f32_16x16x32_bf16 v[54:57], v[144:147], v[184:187], v[54:57]
	v_mfma_f32_16x16x32_bf16 v[46:49], v[152:155], v[184:187], v[46:49]
	v_mfma_f32_16x16x32_bf16 v[38:41], v[144:147], v[196:199], v[38:41]
	v_mfma_f32_16x16x32_bf16 v[30:33], v[152:155], v[196:199], v[30:33]
	v_mfma_f32_16x16x32_bf16 v[22:25], v[144:147], v[204:207], v[22:25]
	v_mfma_f32_16x16x32_bf16 v[14:17], v[152:155], v[204:207], v[14:17]
	v_mfma_f32_16x16x32_bf16 v[62:65], v[148:151], v[180:183], v[62:65]
	v_mfma_f32_16x16x32_bf16 v[58:61], v[156:159], v[180:183], v[58:61]
	v_mfma_f32_16x16x32_bf16 v[54:57], v[148:151], v[188:191], v[54:57]
	v_mfma_f32_16x16x32_bf16 v[46:49], v[156:159], v[188:191], v[46:49]
	v_mfma_f32_16x16x32_bf16 v[38:41], v[148:151], v[200:203], v[38:41]
	v_mfma_f32_16x16x32_bf16 v[30:33], v[156:159], v[200:203], v[30:33]
	v_mfma_f32_16x16x32_bf16 v[22:25], v[148:151], v[208:211], v[22:25]
	v_mfma_f32_16x16x32_bf16 v[14:17], v[156:159], v[208:211], v[14:17]
	v_mfma_f32_16x16x32_bf16 v[50:53], v[160:163], v[176:179], v[50:53]
	v_mfma_f32_16x16x32_bf16 v[42:45], v[168:171], v[176:179], v[42:45]
	v_mfma_f32_16x16x32_bf16 v[34:37], v[160:163], v[184:187], v[34:37]
	v_mfma_f32_16x16x32_bf16 v[26:29], v[168:171], v[184:187], v[26:29]
	v_mfma_f32_16x16x32_bf16 v[18:21], v[160:163], v[196:199], v[18:21]
	v_mfma_f32_16x16x32_bf16 v[10:13], v[168:171], v[196:199], v[10:13]
	v_mfma_f32_16x16x32_bf16 v[6:9], v[160:163], v[204:207], v[6:9]
	v_mfma_f32_16x16x32_bf16 v[2:5], v[168:171], v[204:207], v[2:5]
	v_mfma_f32_16x16x32_bf16 v[50:53], v[164:167], v[180:183], v[50:53]
	v_mfma_f32_16x16x32_bf16 v[42:45], v[172:175], v[180:183], v[42:45]
	v_mfma_f32_16x16x32_bf16 v[34:37], v[164:167], v[188:191], v[34:37]
	v_mfma_f32_16x16x32_bf16 v[26:29], v[172:175], v[188:191], v[26:29]
	v_mfma_f32_16x16x32_bf16 v[18:21], v[164:167], v[200:203], v[18:21]
	v_mfma_f32_16x16x32_bf16 v[10:13], v[172:175], v[200:203], v[10:13]
	v_mfma_f32_16x16x32_bf16 v[6:9], v[164:167], v[208:211], v[6:9]
	v_mfma_f32_16x16x32_bf16 v[2:5], v[172:175], v[208:211], v[2:5]
	s_setprio 0
	s_waitcnt vmcnt(8)
	s_barrier
	s_add_i32 s68, 0, 0x18000
	v_add_u32_e32 v143, s68, v1
	s_add_i32 s69, 0, 0x1c000
	ds_read_b128 v[144:147], v143
	ds_read_b128 v[148:151], v143 offset:1024
	ds_read_b128 v[152:155], v143 offset:2048
	ds_read_b128 v[156:159], v143 offset:3072
	v_add_u32_e32 v143, s69, v1
	ds_read_b128 v[160:163], v143
	ds_read_b128 v[164:167], v143 offset:1024
	ds_read_b128 v[168:171], v143 offset:2048
	ds_read_b128 v[172:175], v143 offset:3072
	s_add_u32 s46, s46, 0x100000
	s_addc_u32 s47, s47, 0
	s_mov_b32 m0, s53
	v_lshl_add_u64 v[218:219], s[46:47], 0, v[130:131]
	ds_read_b128 v[176:179], v142 offset:32768
	ds_read_b128 v[180:183], v142 offset:33792
	ds_read_b128 v[184:187], v142 offset:34816
	ds_read_b128 v[188:191], v142 offset:35840
	ds_read_b128 v[196:199], v142 offset:36864
	ds_read_b128 v[200:203], v142 offset:37888
	ds_read_b128 v[204:207], v142 offset:38912
	ds_read_b128 v[208:211], v142 offset:39936
	global_load_lds_dwordx4 v[218:219], off
	v_lshl_add_u64 v[218:219], s[46:47], 0, v[132:133]
	s_mov_b32 m0, s54
	s_nop 0
	global_load_lds_dwordx4 v[218:219], off
	s_waitcnt lgkmcnt(0)
	s_setprio 1
	v_mfma_f32_16x16x32_bf16 v[126:129], v[144:147], v[176:179], v[126:129]
	v_mfma_f32_16x16x32_bf16 v[122:125], v[152:155], v[176:179], v[122:125]
	v_mfma_f32_16x16x32_bf16 v[118:121], v[144:147], v[184:187], v[118:121]
	v_mfma_f32_16x16x32_bf16 v[110:113], v[152:155], v[184:187], v[110:113]
	v_mfma_f32_16x16x32_bf16 v[102:105], v[144:147], v[196:199], v[102:105]
	v_mfma_f32_16x16x32_bf16 v[94:97], v[152:155], v[196:199], v[94:97]
	v_mfma_f32_16x16x32_bf16 v[86:89], v[144:147], v[204:207], v[86:89]
	v_mfma_f32_16x16x32_bf16 v[78:81], v[152:155], v[204:207], v[78:81]
	v_mfma_f32_16x16x32_bf16 v[126:129], v[148:151], v[180:183], v[126:129]
	v_mfma_f32_16x16x32_bf16 v[122:125], v[156:159], v[180:183], v[122:125]
	v_mfma_f32_16x16x32_bf16 v[118:121], v[148:151], v[188:191], v[118:121]
	v_mfma_f32_16x16x32_bf16 v[110:113], v[156:159], v[188:191], v[110:113]
	v_mfma_f32_16x16x32_bf16 v[102:105], v[148:151], v[200:203], v[102:105]
	v_mfma_f32_16x16x32_bf16 v[94:97], v[156:159], v[200:203], v[94:97]
	v_mfma_f32_16x16x32_bf16 v[86:89], v[148:151], v[208:211], v[86:89]
	v_mfma_f32_16x16x32_bf16 v[78:81], v[156:159], v[208:211], v[78:81]
	v_mfma_f32_16x16x32_bf16 v[114:117], v[160:163], v[176:179], v[114:117]
	v_mfma_f32_16x16x32_bf16 v[106:109], v[168:171], v[176:179], v[106:109]
	v_mfma_f32_16x16x32_bf16 v[98:101], v[160:163], v[184:187], v[98:101]
	v_mfma_f32_16x16x32_bf16 v[90:93], v[168:171], v[184:187], v[90:93]
	v_mfma_f32_16x16x32_bf16 v[82:85], v[160:163], v[196:199], v[82:85]
	v_mfma_f32_16x16x32_bf16 v[74:77], v[168:171], v[196:199], v[74:77]
	v_mfma_f32_16x16x32_bf16 v[70:73], v[160:163], v[204:207], v[70:73]
	v_mfma_f32_16x16x32_bf16 v[66:69], v[168:171], v[204:207], v[66:69]
	v_mfma_f32_16x16x32_bf16 v[114:117], v[164:167], v[180:183], v[114:117]
	v_mfma_f32_16x16x32_bf16 v[106:109], v[172:175], v[180:183], v[106:109]
	v_mfma_f32_16x16x32_bf16 v[98:101], v[164:167], v[188:191], v[98:101]
	v_mfma_f32_16x16x32_bf16 v[90:93], v[172:175], v[188:191], v[90:93]
	v_mfma_f32_16x16x32_bf16 v[82:85], v[164:167], v[200:203], v[82:85]
	v_mfma_f32_16x16x32_bf16 v[74:77], v[172:175], v[200:203], v[74:77]
	v_mfma_f32_16x16x32_bf16 v[70:73], v[164:167], v[208:211], v[70:73]
	v_mfma_f32_16x16x32_bf16 v[66:69], v[172:175], v[208:211], v[66:69]
	s_setprio 0
	s_waitcnt vmcnt(8)
	s_barrier
	s_add_i32 s46, s68, s51
	v_lshl_add_u64 v[192:193], v[192:193], 0, s[10:11]
	s_mov_b32 m0, s46
	ds_read_b128 v[176:179], v142 offset:49152
	ds_read_b128 v[180:183], v142 offset:50176
	ds_read_b128 v[184:187], v142 offset:51200
	ds_read_b128 v[188:191], v142 offset:52224
	ds_read_b128 v[196:199], v142 offset:53248
	ds_read_b128 v[200:203], v142 offset:54272
	ds_read_b128 v[204:207], v142 offset:55296
	ds_read_b128 v[208:211], v142 offset:56320
	global_load_lds_dwordx4 v[192:193], off
	s_add_i32 m0, s46, 0x2000
	s_add_u32 s42, s42, 0x100080
	v_lshl_add_u64 v[192:193], v[212:213], 0, s[10:11]
	s_addc_u32 s43, s43, 0
	s_add_i32 s46, s69, s51
	global_load_lds_dwordx4 v[192:193], off
	v_lshl_add_u64 v[192:193], s[42:43], 0, v[130:131]
	s_mov_b32 m0, s46
	s_nop 0
	global_load_lds_dwordx4 v[192:193], off
	v_lshl_add_u64 v[192:193], s[42:43], 0, v[132:133]
	s_add_i32 m0, s46, 0x2000
	s_nop 0
	global_load_lds_dwordx4 v[192:193], off
	v_lshl_add_u64 v[192:193], v[214:215], 0, s[10:11]
	s_mov_b32 m0, s56
	s_nop 0
	global_load_lds_dwordx4 v[192:193], off
	v_lshl_add_u64 v[192:193], v[216:217], 0, s[10:11]
	s_mov_b32 m0, s57
	s_nop 0
	global_load_lds_dwordx4 v[192:193], off
	s_waitcnt lgkmcnt(0)
	s_setprio 1
	v_mfma_f32_16x16x32_bf16 v[62:65], v[144:147], v[176:179], v[62:65]
	v_mfma_f32_16x16x32_bf16 v[58:61], v[152:155], v[176:179], v[58:61]
	v_mfma_f32_16x16x32_bf16 v[54:57], v[144:147], v[184:187], v[54:57]
	v_mfma_f32_16x16x32_bf16 v[46:49], v[152:155], v[184:187], v[46:49]
	v_mfma_f32_16x16x32_bf16 v[38:41], v[144:147], v[196:199], v[38:41]
	v_mfma_f32_16x16x32_bf16 v[30:33], v[152:155], v[196:199], v[30:33]
	v_mfma_f32_16x16x32_bf16 v[22:25], v[144:147], v[204:207], v[22:25]
	v_mfma_f32_16x16x32_bf16 v[14:17], v[152:155], v[204:207], v[14:17]
	v_mfma_f32_16x16x32_bf16 v[62:65], v[148:151], v[180:183], v[62:65]
	v_mfma_f32_16x16x32_bf16 v[58:61], v[156:159], v[180:183], v[58:61]
	v_mfma_f32_16x16x32_bf16 v[54:57], v[148:151], v[188:191], v[54:57]
	v_mfma_f32_16x16x32_bf16 v[46:49], v[156:159], v[188:191], v[46:49]
	v_mfma_f32_16x16x32_bf16 v[38:41], v[148:151], v[200:203], v[38:41]
	v_mfma_f32_16x16x32_bf16 v[30:33], v[156:159], v[200:203], v[30:33]
	v_mfma_f32_16x16x32_bf16 v[22:25], v[148:151], v[208:211], v[22:25]
	v_mfma_f32_16x16x32_bf16 v[14:17], v[156:159], v[208:211], v[14:17]
	v_mfma_f32_16x16x32_bf16 v[50:53], v[160:163], v[176:179], v[50:53]
	v_mfma_f32_16x16x32_bf16 v[42:45], v[168:171], v[176:179], v[42:45]
	v_mfma_f32_16x16x32_bf16 v[34:37], v[160:163], v[184:187], v[34:37]
	v_mfma_f32_16x16x32_bf16 v[26:29], v[168:171], v[184:187], v[26:29]
	v_mfma_f32_16x16x32_bf16 v[18:21], v[160:163], v[196:199], v[18:21]
	v_mfma_f32_16x16x32_bf16 v[10:13], v[168:171], v[196:199], v[10:13]
	v_mfma_f32_16x16x32_bf16 v[6:9], v[160:163], v[204:207], v[6:9]
	v_mfma_f32_16x16x32_bf16 v[2:5], v[168:171], v[204:207], v[2:5]
	v_mfma_f32_16x16x32_bf16 v[50:53], v[164:167], v[180:183], v[50:53]
	v_mfma_f32_16x16x32_bf16 v[42:45], v[172:175], v[180:183], v[42:45]
	v_mfma_f32_16x16x32_bf16 v[34:37], v[164:167], v[188:191], v[34:37]
	v_mfma_f32_16x16x32_bf16 v[26:29], v[172:175], v[188:191], v[26:29]
	v_mfma_f32_16x16x32_bf16 v[18:21], v[164:167], v[200:203], v[18:21]
	v_mfma_f32_16x16x32_bf16 v[10:13], v[172:175], v[200:203], v[10:13]
	v_mfma_f32_16x16x32_bf16 v[6:9], v[164:167], v[208:211], v[6:9]
	v_mfma_f32_16x16x32_bf16 v[2:5], v[172:175], v[208:211], v[2:5]
	s_setprio 0
	s_waitcnt vmcnt(8)
	s_barrier
	s_add_i32 s67, s67, 2
	s_add_u32 s40, s40, 0x100
	s_addc_u32 s41, s41, 0
	s_add_u32 s65, s65, 0x100
	s_addc_u32 s66, s66, 0
	s_cmp_gt_u32 s67, 61
	s_cbranch_scc0 .Lkt_L_5
	s_branch .Lkt_exit_5
.Lkt_T_5:
	ds_read_b128 v[144:147], v139
	ds_read_b128 v[148:151], v139 offset:1024
	ds_read_b128 v[152:155], v139 offset:2048
	ds_read_b128 v[156:159], v139 offset:3072
	ds_read_b128 v[160:163], v140
	ds_read_b128 v[164:167], v140 offset:1024
	ds_read_b128 v[168:171], v140 offset:2048
	ds_read_b128 v[172:175], v140 offset:3072
	s_add_u32 s42, s40, 0xfff00080
	s_addc_u32 s43, s41, -1
	s_cmp_eq_u32 s67, 60
	s_cselect_b32 s47, s27, s43
	s_cselect_b32 s46, s63, s42
	s_cselect_b32 s43, s25, s66
	s_cselect_b32 s42, s64, s65
	v_lshl_add_u64 v[192:193], s[40:41], 0, v[134:135]
	s_add_i32 m0, s29, 0xc000
	ds_read_b128 v[176:179], v142
	ds_read_b128 v[180:183], v142 offset:1024
	ds_read_b128 v[184:187], v142 offset:2048
	ds_read_b128 v[188:191], v142 offset:3072
	ds_read_b128 v[196:199], v142 offset:4096
	ds_read_b128 v[200:203], v142 offset:5120
	ds_read_b128 v[204:207], v142 offset:6144
	ds_read_b128 v[208:211], v142 offset:7168
	global_load_lds_dwordx4 v[192:193], off
	v_lshl_add_u64 v[192:193], s[40:41], 0, v[136:137]
	s_add_i32 m0, s29, 0xe000
	s_nop 0
	global_load_lds_dwordx4 v[192:193], off
	s_waitcnt vmcnt(8)
	s_waitcnt lgkmcnt(0)
	s_barrier
	s_setprio 2
	v_mfma_f32_16x16x32_bf16 v[126:129], v[144:147], v[176:179], v[126:129]
	v_mfma_f32_16x16x32_bf16 v[122:125], v[152:155], v[176:179], v[122:125]
	v_mfma_f32_16x16x32_bf16 v[118:121], v[144:147], v[184:187], v[118:121]
	v_mfma_f32_16x16x32_bf16 v[110:113], v[152:155], v[184:187], v[110:113]
	v_mfma_f32_16x16x32_bf16 v[102:105], v[144:147], v[196:199], v[102:105]
	v_mfma_f32_16x16x32_bf16 v[94:97], v[152:155], v[196:199], v[94:97]
	v_mfma_f32_16x16x32_bf16 v[86:89], v[144:147], v[204:207], v[86:89]
	v_mfma_f32_16x16x32_bf16 v[78:81], v[152:155], v[204:207], v[78:81]
	v_mfma_f32_16x16x32_bf16 v[126:129], v[148:151], v[180:183], v[126:129]
	v_mfma_f32_16x16x32_bf16 v[122:125], v[156:159], v[180:183], v[122:125]
	v_mfma_f32_16x16x32_bf16 v[118:121], v[148:151], v[188:191], v[118:121]
	v_mfma_f32_16x16x32_bf16 v[110:113], v[156:159], v[188:191], v[110:113]
	v_mfma_f32_16x16x32_bf16 v[102:105], v[148:151], v[200:203], v[102:105]
	v_mfma_f32_16x16x32_bf16 v[94:97], v[156:159], v[200:203], v[94:97]
	v_mfma_f32_16x16x32_bf16 v[86:89], v[148:151], v[208:211], v[86:89]
	v_mfma_f32_16x16x32_bf16 v[78:81], v[156:159], v[208:211], v[78:81]
	v_mfma_f32_16x16x32_bf16 v[114:117], v[160:163], v[176:179], v[114:117]
	v_mfma_f32_16x16x32_bf16 v[106:109], v[168:171], v[176:179], v[106:109]
	v_mfma_f32_16x16x32_bf16 v[98:101], v[160:163], v[184:187], v[98:101]
	v_mfma_f32_16x16x32_bf16 v[90:93], v[168:171], v[184:187], v[90:93]
	v_mfma_f32_16x16x32_bf16 v[82:85], v[160:163], v[196:199], v[82:85]
	v_mfma_f32_16x16x32_bf16 v[74:77], v[168:171], v[196:199], v[74:77]
	v_mfma_f32_16x16x32_bf16 v[70:73], v[160:163], v[204:207], v[70:73]
	v_mfma_f32_16x16x32_bf16 v[66:69], v[168:171], v[204:207], v[66:69]
	v_mfma_f32_16x16x32_bf16 v[114:117], v[164:167], v[180:183], v[114:117]
	v_mfma_f32_16x16x32_bf16 v[106:109], v[172:175], v[180:183], v[106:109]
	v_mfma_f32_16x16x32_bf16 v[98:101], v[164:167], v[188:191], v[98:101]
	v_mfma_f32_16x16x32_bf16 v[90:93], v[172:175], v[188:191], v[90:93]
	v_mfma_f32_16x16x32_bf16 v[82:85], v[164:167], v[200:203], v[82:85]
	v_mfma_f32_16x16x32_bf16 v[74:77], v[172:175], v[200:203], v[74:77]
	v_mfma_f32_16x16x32_bf16 v[70:73], v[164:167], v[208:211], v[70:73]
	v_mfma_f32_16x16x32_bf16 v[66:69], v[172:175], v[208:211], v[66:69]
	s_setprio 0
	s_add_i32 s68, s59, s51
	v_lshl_add_u64 v[192:193], s[42:43], 0, v[130:131]
	s_mov_b32 m0, s68
	ds_read_b128 v[176:179], v142 offset:16384
	ds_read_b128 v[180:183], v142 offset:17408
	ds_read_b128 v[184:187], v142 offset:18432
	ds_read_b128 v[188:191], v142 offset:19456
	ds_read_b128 v[196:199], v142 offset:20480
	ds_read_b128 v[200:203], v142 offset:21504
	ds_read_b128 v[204:207], v142 offset:22528
	ds_read_b128 v[208:211], v142 offset:23552
	global_load_lds_dwordx4 v[192:193], off
	s_add_i32 m0, s68, 0x2000
	s_add_u32 s68, s42, 0x100000
	v_lshl_add_u64 v[212:213], s[42:43], 0, v[132:133]
	s_addc_u32 s69, s43, 0
	s_add_i32 s70, s60, s51
	global_load_lds_dwordx4 v[212:213], off
	v_lshl_add_u64 v[214:215], s[68:69], 0, v[130:131]
	s_mov_b32 m0, s70
	v_lshl_add_u64 v[216:217], s[46:47], 0, v[132:133]
	global_load_lds_dwordx4 v[214:215], off
	v_lshl_add_u64 v[214:215], s[68:69], 0, v[132:133]
	s_add_i32 m0, s70, 0x2000
	s_nop 0
	global_load_lds_dwordx4 v[214:215], off
	v_lshl_add_u64 v[214:215], s[46:47], 0, v[130:131]
	s_mov_b32 m0, s29
	s_nop 0
	global_load_lds_dwordx4 v[214:215], off
	s_mov_b32 m0, s52
	s_nop 0
	global_load_lds_dwordx4 v[216:217], off
	s_waitcnt vmcnt(8)
	s_waitcnt lgkmcnt(0)
	s_barrier
	s_setprio 2
	v_mfma_f32_16x16x32_bf16 v[62:65], v[144:147], v[176:179], v[62:65]
	v_mfma_f32_16x16x32_bf16 v[58:61], v[152:155], v[176:179], v[58:61]
	v_mfma_f32_16x16x32_bf16 v[54:57], v[144:147], v[184:187], v[54:57]
	v_mfma_f32_16x16x32_bf16 v[46:49], v[152:155], v[184:187], v[46:49]
	v_mfma_f32_16x16x32_bf16 v[38:41], v[144:147], v[196:199], v[38:41]
	v_mfma_f32_16x16x32_bf16 v[30:33], v[152:155], v[196:199], v[30:33]
	v_mfma_f32_16x16x32_bf16 v[22:25], v[144:147], v[204:207], v[22:25]
	v_mfma_f32_16x16x32_bf16 v[14:17], v[152:155], v[204:207], v[14:17]
	v_mfma_f32_16x16x32_bf16 v[62:65], v[148:151], v[180:183], v[62:65]
	v_mfma_f32_16x16x32_bf16 v[58:61], v[156:159], v[180:183], v[58:61]
	v_mfma_f32_16x16x32_bf16 v[54:57], v[148:151], v[188:191], v[54:57]
	v_mfma_f32_16x16x32_bf16 v[46:49], v[156:159], v[188:191], v[46:49]
	v_mfma_f32_16x16x32_bf16 v[38:41], v[148:151], v[200:203], v[38:41]
	v_mfma_f32_16x16x32_bf16 v[30:33], v[156:159], v[200:203], v[30:33]
	v_mfma_f32_16x16x32_bf16 v[22:25], v[148:151], v[208:211], v[22:25]
	v_mfma_f32_16x16x32_bf16 v[14:17], v[156:159], v[208:211], v[14:17]
	v_mfma_f32_16x16x32_bf16 v[50:53], v[160:163], v[176:179], v[50:53]
	v_mfma_f32_16x16x32_bf16 v[42:45], v[168:171], v[176:179], v[42:45]
	v_mfma_f32_16x16x32_bf16 v[34:37], v[160:163], v[184:187], v[34:37]
	v_mfma_f32_16x16x32_bf16 v[26:29], v[168:171], v[184:187], v[26:29]
	v_mfma_f32_16x16x32_bf16 v[18:21], v[160:163], v[196:199], v[18:21]
	v_mfma_f32_16x16x32_bf16 v[10:13], v[168:171], v[196:199], v[10:13]
	v_mfma_f32_16x16x32_bf16 v[6:9], v[160:163], v[204:207], v[6:9]
	v_mfma_f32_16x16x32_bf16 v[2:5], v[168:171], v[204:207], v[2:5]
	v_mfma_f32_16x16x32_bf16 v[50:53], v[164:167], v[180:183], v[50:53]
	v_mfma_f32_16x16x32_bf16 v[42:45], v[172:175], v[180:183], v[42:45]
	v_mfma_f32_16x16x32_bf16 v[34:37], v[164:167], v[188:191], v[34:37]
	v_mfma_f32_16x16x32_bf16 v[26:29], v[172:175], v[188:191], v[26:29]
	v_mfma_f32_16x16x32_bf16 v[18:21], v[164:167], v[200:203], v[18:21]
	v_mfma_f32_16x16x32_bf16 v[10:13], v[172:175], v[200:203], v[10:13]
	v_mfma_f32_16x16x32_bf16 v[6:9], v[164:167], v[208:211], v[6:9]
	v_mfma_f32_16x16x32_bf16 v[2:5], v[172:175], v[208:211], v[2:5]
	s_setprio 0
	s_add_i32 s68, 0, 0x18000
	v_add_u32_e32 v143, s68, v1
	s_add_i32 s69, 0, 0x1c000
	ds_read_b128 v[144:147], v143
	ds_read_b128 v[148:151], v143 offset:1024
	ds_read_b128 v[152:155], v143 offset:2048
	ds_read_b128 v[156:159], v143 offset:3072
	v_add_u32_e32 v143, s69, v1
	ds_read_b128 v[160:163], v143
	ds_read_b128 v[164:167], v143 offset:1024
	ds_read_b128 v[168:171], v143 offset:2048
	ds_read_b128 v[172:175], v143 offset:3072
	s_add_u32 s46, s46, 0x100000
	s_addc_u32 s47, s47, 0
	s_mov_b32 m0, s53
	v_lshl_add_u64 v[218:219], s[46:47], 0, v[130:131]
	ds_read_b128 v[176:179], v142 offset:32768
	ds_read_b128 v[180:183], v142 offset:33792
	ds_read_b128 v[184:187], v142 offset:34816
	ds_read_b128 v[188:191], v142 offset:35840
	ds_read_b128 v[196:199], v142 offset:36864
	ds_read_b128 v[200:203], v142 offset:37888
	ds_read_b128 v[204:207], v142 offset:38912
	ds_read_b128 v[208:211], v142 offset:39936
	global_load_lds_dwordx4 v[218:219], off
	v_lshl_add_u64 v[218:219], s[46:47], 0, v[132:133]
	s_mov_b32 m0, s54
	s_nop 0
	global_load_lds_dwordx4 v[218:219], off
	s_waitcnt vmcnt(8)
	s_waitcnt lgkmcnt(0)
	s_barrier
	s_setprio 2
	v_mfma_f32_16x16x32_bf16 v[126:129], v[144:147], v[176:179], v[126:129]
	v_mfma_f32_16x16x32_bf16 v[122:125], v[152:155], v[176:179], v[122:125]
	v_mfma_f32_16x16x32_bf16 v[118:121], v[144:147], v[184:187], v[118:121]
	v_mfma_f32_16x16x32_bf16 v[110:113], v[152:155], v[184:187], v[110:113]
	v_mfma_f32_16x16x32_bf16 v[102:105], v[144:147], v[196:199], v[102:105]
	v_mfma_f32_16x16x32_bf16 v[94:97], v[152:155], v[196:199], v[94:97]
	v_mfma_f32_16x16x32_bf16 v[86:89], v[144:147], v[204:207], v[86:89]
	v_mfma_f32_16x16x32_bf16 v[78:81], v[152:155], v[204:207], v[78:81]
	v_mfma_f32_16x16x32_bf16 v[126:129], v[148:151], v[180:183], v[126:129]
	v_mfma_f32_16x16x32_bf16 v[122:125], v[156:159], v[180:183], v[122:125]
	v_mfma_f32_16x16x32_bf16 v[118:121], v[148:151], v[188:191], v[118:121]
	v_mfma_f32_16x16x32_bf16 v[110:113], v[156:159], v[188:191], v[110:113]
	v_mfma_f32_16x16x32_bf16 v[102:105], v[148:151], v[200:203], v[102:105]
	v_mfma_f32_16x16x32_bf16 v[94:97], v[156:159], v[200:203], v[94:97]
	v_mfma_f32_16x16x32_bf16 v[86:89], v[148:151], v[208:211], v[86:89]
	v_mfma_f32_16x16x32_bf16 v[78:81], v[156:159], v[208:211], v[78:81]
	v_mfma_f32_16x16x32_bf16 v[114:117], v[160:163], v[176:179], v[114:117]
	v_mfma_f32_16x16x32_bf16 v[106:109], v[168:171], v[176:179], v[106:109]
	v_mfma_f32_16x16x32_bf16 v[98:101], v[160:163], v[184:187], v[98:101]
	v_mfma_f32_16x16x32_bf16 v[90:93], v[168:171], v[184:187], v[90:93]
	v_mfma_f32_16x16x32_bf16 v[82:85], v[160:163], v[196:199], v[82:85]
	v_mfma_f32_16x16x32_bf16 v[74:77], v[168:171], v[196:199], v[74:77]
	v_mfma_f32_16x16x32_bf16 v[70:73], v[160:163], v[204:207], v[70:73]
	v_mfma_f32_16x16x32_bf16 v[66:69], v[168:171], v[204:207], v[66:69]
	v_mfma_f32_16x16x32_bf16 v[114:117], v[164:167], v[180:183], v[114:117]
	v_mfma_f32_16x16x32_bf16 v[106:109], v[172:175], v[180:183], v[106:109]
	v_mfma_f32_16x16x32_bf16 v[98:101], v[164:167], v[188:191], v[98:101]
	v_mfma_f32_16x16x32_bf16 v[90:93], v[172:175], v[188:191], v[90:93]
	v_mfma_f32_16x16x32_bf16 v[82:85], v[164:167], v[200:203], v[82:85]
	v_mfma_f32_16x16x32_bf16 v[74:77], v[172:175], v[200:203], v[74:77]
	v_mfma_f32_16x16x32_bf16 v[70:73], v[164:167], v[208:211], v[70:73]
	v_mfma_f32_16x16x32_bf16 v[66:69], v[172:175], v[208:211], v[66:69]
	s_setprio 0
	s_add_i32 s46, s68, s51
	v_lshl_add_u64 v[192:193], v[192:193], 0, s[10:11]
	s_mov_b32 m0, s46
	ds_read_b128 v[176:179], v142 offset:49152
	ds_read_b128 v[180:183], v142 offset:50176
	ds_read_b128 v[184:187], v142 offset:51200
	ds_read_b128 v[188:191], v142 offset:52224
	ds_read_b128 v[196:199], v142 offset:53248
	ds_read_b128 v[200:203], v142 offset:54272
	ds_read_b128 v[204:207], v142 offset:55296
	ds_read_b128 v[208:211], v142 offset:56320
	global_load_lds_dwordx4 v[192:193], off
	s_add_i32 m0, s46, 0x2000
	s_add_u32 s42, s42, 0x100080
	v_lshl_add_u64 v[192:193], v[212:213], 0, s[10:11]
	s_addc_u32 s43, s43, 0
	s_add_i32 s46, s69, s51
	global_load_lds_dwordx4 v[192:193], off
	v_lshl_add_u64 v[192:193], s[42:43], 0, v[130:131]
	s_mov_b32 m0, s46
	s_nop 0
	global_load_lds_dwordx4 v[192:193], off
	v_lshl_add_u64 v[192:193], s[42:43], 0, v[132:133]
	s_add_i32 m0, s46, 0x2000
	s_nop 0
	global_load_lds_dwordx4 v[192:193], off
	v_lshl_add_u64 v[192:193], v[214:215], 0, s[10:11]
	s_mov_b32 m0, s56
	s_nop 0
	global_load_lds_dwordx4 v[192:193], off
	v_lshl_add_u64 v[192:193], v[216:217], 0, s[10:11]
	s_mov_b32 m0, s57
	s_nop 0
	global_load_lds_dwordx4 v[192:193], off
	s_waitcnt vmcnt(8)
	s_waitcnt lgkmcnt(0)
	s_barrier
	s_setprio 2
	v_mfma_f32_16x16x32_bf16 v[62:65], v[144:147], v[176:179], v[62:65]
	v_mfma_f32_16x16x32_bf16 v[58:61], v[152:155], v[176:179], v[58:61]
	v_mfma_f32_16x16x32_bf16 v[54:57], v[144:147], v[184:187], v[54:57]
	v_mfma_f32_16x16x32_bf16 v[46:49], v[152:155], v[184:187], v[46:49]
	v_mfma_f32_16x16x32_bf16 v[38:41], v[144:147], v[196:199], v[38:41]
	v_mfma_f32_16x16x32_bf16 v[30:33], v[152:155], v[196:199], v[30:33]
	v_mfma_f32_16x16x32_bf16 v[22:25], v[144:147], v[204:207], v[22:25]
	v_mfma_f32_16x16x32_bf16 v[14:17], v[152:155], v[204:207], v[14:17]
	v_mfma_f32_16x16x32_bf16 v[62:65], v[148:151], v[180:183], v[62:65]
	v_mfma_f32_16x16x32_bf16 v[58:61], v[156:159], v[180:183], v[58:61]
	v_mfma_f32_16x16x32_bf16 v[54:57], v[148:151], v[188:191], v[54:57]
	v_mfma_f32_16x16x32_bf16 v[46:49], v[156:159], v[188:191], v[46:49]
	v_mfma_f32_16x16x32_bf16 v[38:41], v[148:151], v[200:203], v[38:41]
	v_mfma_f32_16x16x32_bf16 v[30:33], v[156:159], v[200:203], v[30:33]
	v_mfma_f32_16x16x32_bf16 v[22:25], v[148:151], v[208:211], v[22:25]
	v_mfma_f32_16x16x32_bf16 v[14:17], v[156:159], v[208:211], v[14:17]
	v_mfma_f32_16x16x32_bf16 v[50:53], v[160:163], v[176:179], v[50:53]
	v_mfma_f32_16x16x32_bf16 v[42:45], v[168:171], v[176:179], v[42:45]
	v_mfma_f32_16x16x32_bf16 v[34:37], v[160:163], v[184:187], v[34:37]
	v_mfma_f32_16x16x32_bf16 v[26:29], v[168:171], v[184:187], v[26:29]
	v_mfma_f32_16x16x32_bf16 v[18:21], v[160:163], v[196:199], v[18:21]
	v_mfma_f32_16x16x32_bf16 v[10:13], v[168:171], v[196:199], v[10:13]
	v_mfma_f32_16x16x32_bf16 v[6:9], v[160:163], v[204:207], v[6:9]
	v_mfma_f32_16x16x32_bf16 v[2:5], v[168:171], v[204:207], v[2:5]
	v_mfma_f32_16x16x32_bf16 v[50:53], v[164:167], v[180:183], v[50:53]
	v_mfma_f32_16x16x32_bf16 v[42:45], v[172:175], v[180:183], v[42:45]
	v_mfma_f32_16x16x32_bf16 v[34:37], v[164:167], v[188:191], v[34:37]
	v_mfma_f32_16x16x32_bf16 v[26:29], v[172:175], v[188:191], v[26:29]
	v_mfma_f32_16x16x32_bf16 v[18:21], v[164:167], v[200:203], v[18:21]
	v_mfma_f32_16x16x32_bf16 v[10:13], v[172:175], v[200:203], v[10:13]
	v_mfma_f32_16x16x32_bf16 v[6:9], v[164:167], v[208:211], v[6:9]
	v_mfma_f32_16x16x32_bf16 v[2:5], v[172:175], v[208:211], v[2:5]
	s_setprio 0
	s_add_i32 s67, s67, 2
	s_add_u32 s40, s40, 0x100
	s_addc_u32 s41, s41, 0
	s_add_u32 s65, s65, 0x100
	s_addc_u32 s66, s66, 0
	s_cmp_gt_u32 s67, 61
	s_cbranch_scc0 .Lkt_T_5
	s_nop 7

.LBB0_961:
	s_add_u32 s12, s38, 0x3de00000
	s_addc_u32 s13, s39, 0
	s_lshl_b32 s14, s14, 5
	s_and_b32 s20, s14, 0x60
	s_mov_b64 s[14:15], 0x80
	s_add_i32 m0, s27, 0x18000
	v_lshl_add_u64 v[8:9], v[8:9], 0, s[14:15]
	s_lshl_b32 s17, s16, 13
	s_lshl_b32 s21, s20, 7
	s_waitcnt vmcnt(2)
	s_barrier
	global_load_lds_dwordx4 v[8:9], off
	v_lshl_add_u64 v[6:7], v[6:7], 0, s[14:15]
	s_add_i32 m0, s27, 0x1a000
	s_add_i32 s47, s27, 0x8000
	s_add_i32 s48, s27, 0xa000
	global_load_lds_dwordx4 v[6:7], off
	v_lshl_add_u64 v[2:3], v[2:3], 0, s[14:15]
	s_mov_b32 m0, s47
	s_add_u32 s18, s30, 0x80080
	global_load_lds_dwordx4 v[2:3], off
	v_lshl_add_u64 v[2:3], v[4:5], 0, s[14:15]
	s_mov_b32 m0, s48
	s_addc_u32 s19, s31, 0
	global_load_lds_dwordx4 v[2:3], off
	s_add_i32 m0, s27, 0x1c000
	v_lshl_add_u64 v[2:3], s[18:19], 0, v[134:135]
	global_load_lds_dwordx4 v[2:3], off
	v_lshl_add_u64 v[2:3], s[18:19], 0, v[130:131]
	s_add_i32 m0, s27, 0x1e000
	s_sext_i32_i8 s52, s6
	global_load_lds_dwordx4 v[2:3], off
	v_and_b32_e32 v2, 15, v0
	v_lshlrev_b32_e32 v3, 1, v13
	v_lshlrev_b32_e32 v4, 2, v0
	v_lshlrev_b32_e32 v5, 6, v0
	s_movk_i32 s6, 0x3c0
	v_lshl_or_b32 v1, s16, 6, v2
	v_lshl_or_b32 v2, v2, 6, v3
	v_and_b32_e32 v4, 32, v4
	v_and_or_b32 v3, v5, s6, v3
	v_bitop3_b32 v150, s21, v3, v4 bitop3:0xf6
	v_lshlrev_b32_e32 v3, 9, v0
	v_bitop3_b32 v2, v2, s17, v4 bitop3:0xde
	v_and_b32_e32 v3, 0x30000, v3
	v_lshlrev_b32_e32 v4, 12, v14
	v_or3_b32 v3, v11, v3, v4
	v_add_u32_e32 v138, v3, v12
	v_lshlrev_b32_e32 v3, 5, v10
	s_waitcnt vmcnt(6)
	s_cmpk_lt_u32 s7, 0x100
	v_and_b32_e32 v3, 0x70000, v3
	s_cselect_b64 s[16:17], -1, 0
	v_or3_b32 v3, v11, v3, v4
	s_add_i32 s50, 0, 0x10000
	s_add_i32 s51, 0, 0x14000
	s_ashr_i32 s49, s44, 31
	v_or_b32_e32 v151, s20, v13
	v_mov_b32_e32 v139, v135
	v_add_u32_e32 v140, v3, v12
	v_mov_b32_e32 v141, v135
	v_mov_b64_e32 v[142:143], 0x108
	v_mov_b64_e32 v[144:145], 0x107
	v_add_u32_e32 v152, s50, v150
	v_add_u32_e32 v153, s51, v150
	v_add_u32_e32 v154, 0, v2
	s_branch .LBB0_964

.LBB0_967:
	s_and_b64 vcc, exec, s[16:17]
	s_cbranch_vccz .Lkt_T_6
.Lkt_L_6:
	ds_read_b128 v[146:149], v152
	ds_read_b128 v[156:159], v152 offset:1024
	ds_read_b128 v[160:163], v152 offset:2048
	ds_read_b128 v[164:167], v152 offset:3072
	ds_read_b128 v[168:171], v153
	ds_read_b128 v[172:175], v153 offset:1024
	ds_read_b128 v[176:179], v153 offset:2048
	ds_read_b128 v[180:183], v153 offset:3072
	s_add_u32 s30, s28, 0xfff80080
	s_addc_u32 s31, s29, -1
	s_cmp_eq_u32 s57, 28
	s_cselect_b32 s35, s21, s31
	s_cselect_b32 s34, s53, s30
	s_cselect_b32 s31, s19, s56
	s_cselect_b32 s30, s54, s55
	v_lshl_add_u64 v[192:193], s[28:29], 0, v[138:139]
	s_add_i32 m0, s27, 0xc000
	ds_read_b128 v[184:187], v154
	ds_read_b128 v[188:191], v154 offset:1024
	ds_read_b128 v[196:199], v154 offset:2048
	ds_read_b128 v[200:203], v154 offset:3072
	ds_read_b128 v[206:209], v154 offset:4096
	ds_read_b128 v[210:213], v154 offset:5120
	ds_read_b128 v[214:217], v154 offset:6144
	ds_read_b128 v[218:221], v154 offset:7168
	global_load_lds_dwordx4 v[192:193], off
	v_lshl_add_u64 v[192:193], s[28:29], 0, v[140:141]
	s_add_i32 m0, s27, 0xe000
	s_nop 0
	global_load_lds_dwordx4 v[192:193], off
	s_waitcnt lgkmcnt(0)
	s_setprio 1
	v_mfma_f32_16x16x32_bf16 v[126:129], v[146:149], v[184:187], v[126:129]
	v_mfma_f32_16x16x32_bf16 v[122:125], v[160:163], v[184:187], v[122:125]
	v_mfma_f32_16x16x32_bf16 v[110:113], v[146:149], v[196:199], v[110:113]
	v_mfma_f32_16x16x32_bf16 v[106:109], v[160:163], v[196:199], v[106:109]
	v_mfma_f32_16x16x32_bf16 v[98:101], v[146:149], v[206:209], v[98:101]
	v_mfma_f32_16x16x32_bf16 v[90:93], v[160:163], v[206:209], v[90:93]
	v_mfma_f32_16x16x32_bf16 v[78:81], v[146:149], v[214:217], v[78:81]
	v_mfma_f32_16x16x32_bf16 v[74:77], v[160:163], v[214:217], v[74:77]
	v_mfma_f32_16x16x32_bf16 v[126:129], v[156:159], v[188:191], v[126:129]
	v_mfma_f32_16x16x32_bf16 v[122:125], v[164:167], v[188:191], v[122:125]
	v_mfma_f32_16x16x32_bf16 v[110:113], v[156:159], v[200:203], v[110:113]
	v_mfma_f32_16x16x32_bf16 v[106:109], v[164:167], v[200:203], v[106:109]
	v_mfma_f32_16x16x32_bf16 v[98:101], v[156:159], v[210:213], v[98:101]
	v_mfma_f32_16x16x32_bf16 v[90:93], v[164:167], v[210:213], v[90:93]
	v_mfma_f32_16x16x32_bf16 v[78:81], v[156:159], v[218:221], v[78:81]
	v_mfma_f32_16x16x32_bf16 v[74:77], v[164:167], v[218:221], v[74:77]
	v_mfma_f32_16x16x32_bf16 v[118:121], v[168:171], v[184:187], v[118:121]
	v_mfma_f32_16x16x32_bf16 v[114:117], v[176:179], v[184:187], v[114:117]
	v_mfma_f32_16x16x32_bf16 v[102:105], v[168:171], v[196:199], v[102:105]
	v_mfma_f32_16x16x32_bf16 v[94:97], v[176:179], v[196:199], v[94:97]
	v_mfma_f32_16x16x32_bf16 v[86:89], v[168:171], v[206:209], v[86:89]
	v_mfma_f32_16x16x32_bf16 v[82:85], v[176:179], v[206:209], v[82:85]
	v_mfma_f32_16x16x32_bf16 v[70:73], v[168:171], v[214:217], v[70:73]
	v_mfma_f32_16x16x32_bf16 v[66:69], v[176:179], v[214:217], v[66:69]
	v_mfma_f32_16x16x32_bf16 v[118:121], v[172:175], v[188:191], v[118:121]
	v_mfma_f32_16x16x32_bf16 v[114:117], v[180:183], v[188:191], v[114:117]
	v_mfma_f32_16x16x32_bf16 v[102:105], v[172:175], v[200:203], v[102:105]
	v_mfma_f32_16x16x32_bf16 v[94:97], v[180:183], v[200:203], v[94:97]
	v_mfma_f32_16x16x32_bf16 v[86:89], v[172:175], v[210:213], v[86:89]
	v_mfma_f32_16x16x32_bf16 v[82:85], v[180:183], v[210:213], v[82:85]
	v_mfma_f32_16x16x32_bf16 v[70:73], v[172:175], v[218:221], v[70:73]
	v_mfma_f32_16x16x32_bf16 v[66:69], v[180:183], v[218:221], v[66:69]
	s_setprio 0
	s_waitcnt vmcnt(8)
	s_barrier
	s_add_i32 s58, s50, s40
	v_lshl_add_u64 v[192:193], s[30:31], 0, v[134:135]
	s_mov_b32 m0, s58
	ds_read_b128 v[184:187], v154 offset:16384
	ds_read_b128 v[188:191], v154 offset:17408
	ds_read_b128 v[196:199], v154 offset:18432
	ds_read_b128 v[200:203], v154 offset:19456
	ds_read_b128 v[206:209], v154 offset:20480
	ds_read_b128 v[210:213], v154 offset:21504
	ds_read_b128 v[214:217], v154 offset:22528
	ds_read_b128 v[218:221], v154 offset:23552
	global_load_lds_dwordx4 v[192:193], off
	s_add_i32 m0, s58, 0x2000
	s_add_u32 s58, s30, 0x80000
	v_lshl_add_u64 v[222:223], s[30:31], 0, v[130:131]
	s_addc_u32 s59, s31, 0
	s_add_i32 s60, s51, s40
	global_load_lds_dwordx4 v[222:223], off
	v_lshl_add_u64 v[224:225], s[58:59], 0, v[134:135]
	s_mov_b32 m0, s60
	v_lshl_add_u64 v[226:227], s[34:35], 0, v[132:133]
	global_load_lds_dwordx4 v[224:225], off
	v_lshl_add_u64 v[224:225], s[58:59], 0, v[130:131]
	s_add_i32 m0, s60, 0x2000
	s_nop 0
	global_load_lds_dwordx4 v[224:225], off
	v_lshl_add_u64 v[224:225], s[34:35], 0, v[136:137]
	s_mov_b32 m0, s27
	s_nop 0
	global_load_lds_dwordx4 v[224:225], off
	s_mov_b32 m0, s42
	s_nop 0
	global_load_lds_dwordx4 v[226:227], off
	s_waitcnt lgkmcnt(0)
	s_setprio 1
	v_mfma_f32_16x16x32_bf16 v[62:65], v[146:149], v[184:187], v[62:65]
	v_mfma_f32_16x16x32_bf16 v[58:61], v[160:163], v[184:187], v[58:61]
	v_mfma_f32_16x16x32_bf16 v[46:49], v[146:149], v[196:199], v[46:49]
	v_mfma_f32_16x16x32_bf16 v[42:45], v[160:163], v[196:199], v[42:45]
	v_mfma_f32_16x16x32_bf16 v[30:33], v[146:149], v[206:209], v[30:33]
	v_mfma_f32_16x16x32_bf16 v[26:29], v[160:163], v[206:209], v[26:29]
	v_mfma_f32_16x16x32_bf16 v[14:17], v[146:149], v[214:217], v[14:17]
	v_mfma_f32_16x16x32_bf16 v[10:13], v[160:163], v[214:217], v[10:13]
	v_mfma_f32_16x16x32_bf16 v[62:65], v[156:159], v[188:191], v[62:65]
	v_mfma_f32_16x16x32_bf16 v[58:61], v[164:167], v[188:191], v[58:61]
	v_mfma_f32_16x16x32_bf16 v[46:49], v[156:159], v[200:203], v[46:49]
	v_mfma_f32_16x16x32_bf16 v[42:45], v[164:167], v[200:203], v[42:45]
	v_mfma_f32_16x16x32_bf16 v[30:33], v[156:159], v[210:213], v[30:33]
	v_mfma_f32_16x16x32_bf16 v[26:29], v[164:167], v[210:213], v[26:29]
	v_mfma_f32_16x16x32_bf16 v[14:17], v[156:159], v[218:221], v[14:17]
	v_mfma_f32_16x16x32_bf16 v[10:13], v[164:167], v[218:221], v[10:13]
	v_mfma_f32_16x16x32_bf16 v[54:57], v[168:171], v[184:187], v[54:57]
	v_mfma_f32_16x16x32_bf16 v[50:53], v[176:179], v[184:187], v[50:53]
	v_mfma_f32_16x16x32_bf16 v[38:41], v[168:171], v[196:199], v[38:41]
	v_mfma_f32_16x16x32_bf16 v[34:37], v[176:179], v[196:199], v[34:37]
	v_mfma_f32_16x16x32_bf16 v[22:25], v[168:171], v[206:209], v[22:25]
	v_mfma_f32_16x16x32_bf16 v[18:21], v[176:179], v[206:209], v[18:21]
	v_mfma_f32_16x16x32_bf16 v[6:9], v[168:171], v[214:217], v[6:9]
	v_mfma_f32_16x16x32_bf16 v[2:5], v[176:179], v[214:217], v[2:5]
	v_mfma_f32_16x16x32_bf16 v[54:57], v[172:175], v[188:191], v[54:57]
	v_mfma_f32_16x16x32_bf16 v[50:53], v[180:183], v[188:191], v[50:53]
	v_mfma_f32_16x16x32_bf16 v[38:41], v[172:175], v[200:203], v[38:41]
	v_mfma_f32_16x16x32_bf16 v[34:37], v[180:183], v[200:203], v[34:37]
	v_mfma_f32_16x16x32_bf16 v[22:25], v[172:175], v[210:213], v[22:25]
	v_mfma_f32_16x16x32_bf16 v[18:21], v[180:183], v[210:213], v[18:21]
	v_mfma_f32_16x16x32_bf16 v[6:9], v[172:175], v[218:221], v[6:9]
	v_mfma_f32_16x16x32_bf16 v[2:5], v[180:183], v[218:221], v[2:5]
	s_setprio 0
	s_waitcnt vmcnt(8)
	s_barrier
	s_add_i32 s58, 0, 0x18000
	v_add_u32_e32 v155, s58, v150
	s_add_i32 s59, 0, 0x1c000
	ds_read_b128 v[146:149], v155
	ds_read_b128 v[156:159], v155 offset:1024
	ds_read_b128 v[160:163], v155 offset:2048
	ds_read_b128 v[164:167], v155 offset:3072
	v_add_u32_e32 v155, s59, v150
	ds_read_b128 v[168:171], v155
	ds_read_b128 v[172:175], v155 offset:1024
	ds_read_b128 v[176:179], v155 offset:2048
	ds_read_b128 v[180:183], v155 offset:3072
	s_add_u32 s34, s34, 0x80000
	s_addc_u32 s35, s35, 0
	s_mov_b32 m0, s43
	v_lshl_add_u64 v[228:229], s[34:35], 0, v[136:137]
	ds_read_b128 v[184:187], v154 offset:32768
	ds_read_b128 v[188:191], v154 offset:33792
	ds_read_b128 v[196:199], v154 offset:34816
	ds_read_b128 v[200:203], v154 offset:35840
	ds_read_b128 v[206:209], v154 offset:36864
	ds_read_b128 v[210:213], v154 offset:37888
	ds_read_b128 v[214:217], v154 offset:38912
	ds_read_b128 v[218:221], v154 offset:39936
	global_load_lds_dwordx4 v[228:229], off
	v_lshl_add_u64 v[228:229], s[34:35], 0, v[132:133]
	s_mov_b32 m0, s45
	s_nop 0
	global_load_lds_dwordx4 v[228:229], off
	s_waitcnt lgkmcnt(0)
	s_setprio 1
	v_mfma_f32_16x16x32_bf16 v[126:129], v[146:149], v[184:187], v[126:129]
	v_mfma_f32_16x16x32_bf16 v[122:125], v[160:163], v[184:187], v[122:125]
	v_mfma_f32_16x16x32_bf16 v[110:113], v[146:149], v[196:199], v[110:113]
	v_mfma_f32_16x16x32_bf16 v[106:109], v[160:163], v[196:199], v[106:109]
	v_mfma_f32_16x16x32_bf16 v[98:101], v[146:149], v[206:209], v[98:101]
	v_mfma_f32_16x16x32_bf16 v[90:93], v[160:163], v[206:209], v[90:93]
	v_mfma_f32_16x16x32_bf16 v[78:81], v[146:149], v[214:217], v[78:81]
	v_mfma_f32_16x16x32_bf16 v[74:77], v[160:163], v[214:217], v[74:77]
	v_mfma_f32_16x16x32_bf16 v[126:129], v[156:159], v[188:191], v[126:129]
	v_mfma_f32_16x16x32_bf16 v[122:125], v[164:167], v[188:191], v[122:125]
	v_mfma_f32_16x16x32_bf16 v[110:113], v[156:159], v[200:203], v[110:113]
	v_mfma_f32_16x16x32_bf16 v[106:109], v[164:167], v[200:203], v[106:109]
	v_mfma_f32_16x16x32_bf16 v[98:101], v[156:159], v[210:213], v[98:101]
	v_mfma_f32_16x16x32_bf16 v[90:93], v[164:167], v[210:213], v[90:93]
	v_mfma_f32_16x16x32_bf16 v[78:81], v[156:159], v[218:221], v[78:81]
	v_mfma_f32_16x16x32_bf16 v[74:77], v[164:167], v[218:221], v[74:77]
	v_mfma_f32_16x16x32_bf16 v[118:121], v[168:171], v[184:187], v[118:121]
	v_mfma_f32_16x16x32_bf16 v[114:117], v[176:179], v[184:187], v[114:117]
	v_mfma_f32_16x16x32_bf16 v[102:105], v[168:171], v[196:199], v[102:105]
	v_mfma_f32_16x16x32_bf16 v[94:97], v[176:179], v[196:199], v[94:97]
	v_mfma_f32_16x16x32_bf16 v[86:89], v[168:171], v[206:209], v[86:89]
	v_mfma_f32_16x16x32_bf16 v[82:85], v[176:179], v[206:209], v[82:85]
	v_mfma_f32_16x16x32_bf16 v[70:73], v[168:171], v[214:217], v[70:73]
	v_mfma_f32_16x16x32_bf16 v[66:69], v[176:179], v[214:217], v[66:69]
	v_mfma_f32_16x16x32_bf16 v[118:121], v[172:175], v[188:191], v[118:121]
	v_mfma_f32_16x16x32_bf16 v[114:117], v[180:183], v[188:191], v[114:117]
	v_mfma_f32_16x16x32_bf16 v[102:105], v[172:175], v[200:203], v[102:105]
	v_mfma_f32_16x16x32_bf16 v[94:97], v[180:183], v[200:203], v[94:97]
	v_mfma_f32_16x16x32_bf16 v[86:89], v[172:175], v[210:213], v[86:89]
	v_mfma_f32_16x16x32_bf16 v[82:85], v[180:183], v[210:213], v[82:85]
	v_mfma_f32_16x16x32_bf16 v[70:73], v[172:175], v[218:221], v[70:73]
	v_mfma_f32_16x16x32_bf16 v[66:69], v[180:183], v[218:221], v[66:69]
	s_setprio 0
	s_waitcnt vmcnt(8)
	s_barrier
	s_add_i32 s34, s58, s40
	v_lshl_add_u64 v[192:193], v[192:193], 0, s[14:15]
	s_mov_b32 m0, s34
	ds_read_b128 v[184:187], v154 offset:49152
	ds_read_b128 v[188:191], v154 offset:50176
	ds_read_b128 v[196:199], v154 offset:51200
	ds_read_b128 v[200:203], v154 offset:52224
	ds_read_b128 v[206:209], v154 offset:53248
	ds_read_b128 v[210:213], v154 offset:54272
	ds_read_b128 v[214:217], v154 offset:55296
	ds_read_b128 v[218:221], v154 offset:56320
	global_load_lds_dwordx4 v[192:193], off
	s_add_i32 m0, s34, 0x2000
	s_add_u32 s30, s30, 0x80080
	v_lshl_add_u64 v[192:193], v[222:223], 0, s[14:15]
	s_addc_u32 s31, s31, 0
	s_add_i32 s34, s59, s40
	global_load_lds_dwordx4 v[192:193], off
	v_lshl_add_u64 v[192:193], s[30:31], 0, v[134:135]
	s_mov_b32 m0, s34
	s_nop 0
	global_load_lds_dwordx4 v[192:193], off
	v_lshl_add_u64 v[192:193], s[30:31], 0, v[130:131]
	s_add_i32 m0, s34, 0x2000
	s_nop 0
	global_load_lds_dwordx4 v[192:193], off
	v_lshl_add_u64 v[192:193], v[224:225], 0, s[14:15]
	s_mov_b32 m0, s47
	s_nop 0
	global_load_lds_dwordx4 v[192:193], off
	v_lshl_add_u64 v[192:193], v[226:227], 0, s[14:15]
	s_mov_b32 m0, s48
	s_nop 0
	global_load_lds_dwordx4 v[192:193], off
	s_waitcnt lgkmcnt(0)
	s_setprio 1
	v_mfma_f32_16x16x32_bf16 v[62:65], v[146:149], v[184:187], v[62:65]
	v_mfma_f32_16x16x32_bf16 v[58:61], v[160:163], v[184:187], v[58:61]
	v_mfma_f32_16x16x32_bf16 v[46:49], v[146:149], v[196:199], v[46:49]
	v_mfma_f32_16x16x32_bf16 v[42:45], v[160:163], v[196:199], v[42:45]
	v_mfma_f32_16x16x32_bf16 v[30:33], v[146:149], v[206:209], v[30:33]
	v_mfma_f32_16x16x32_bf16 v[26:29], v[160:163], v[206:209], v[26:29]
	v_mfma_f32_16x16x32_bf16 v[14:17], v[146:149], v[214:217], v[14:17]
	v_mfma_f32_16x16x32_bf16 v[10:13], v[160:163], v[214:217], v[10:13]
	v_mfma_f32_16x16x32_bf16 v[62:65], v[156:159], v[188:191], v[62:65]
	v_mfma_f32_16x16x32_bf16 v[58:61], v[164:167], v[188:191], v[58:61]
	v_mfma_f32_16x16x32_bf16 v[46:49], v[156:159], v[200:203], v[46:49]
	v_mfma_f32_16x16x32_bf16 v[42:45], v[164:167], v[200:203], v[42:45]
	v_mfma_f32_16x16x32_bf16 v[30:33], v[156:159], v[210:213], v[30:33]
	v_mfma_f32_16x16x32_bf16 v[26:29], v[164:167], v[210:213], v[26:29]
	v_mfma_f32_16x16x32_bf16 v[14:17], v[156:159], v[218:221], v[14:17]
	v_mfma_f32_16x16x32_bf16 v[10:13], v[164:167], v[218:221], v[10:13]
	v_mfma_f32_16x16x32_bf16 v[54:57], v[168:171], v[184:187], v[54:57]
	v_mfma_f32_16x16x32_bf16 v[50:53], v[176:179], v[184:187], v[50:53]
	v_mfma_f32_16x16x32_bf16 v[38:41], v[168:171], v[196:199], v[38:41]
	v_mfma_f32_16x16x32_bf16 v[34:37], v[176:179], v[196:199], v[34:37]
	v_mfma_f32_16x16x32_bf16 v[22:25], v[168:171], v[206:209], v[22:25]
	v_mfma_f32_16x16x32_bf16 v[18:21], v[176:179], v[206:209], v[18:21]
	v_mfma_f32_16x16x32_bf16 v[6:9], v[168:171], v[214:217], v[6:9]
	v_mfma_f32_16x16x32_bf16 v[2:5], v[176:179], v[214:217], v[2:5]
	v_mfma_f32_16x16x32_bf16 v[54:57], v[172:175], v[188:191], v[54:57]
	v_mfma_f32_16x16x32_bf16 v[50:53], v[180:183], v[188:191], v[50:53]
	v_mfma_f32_16x16x32_bf16 v[38:41], v[172:175], v[200:203], v[38:41]
	v_mfma_f32_16x16x32_bf16 v[34:37], v[180:183], v[200:203], v[34:37]
	v_mfma_f32_16x16x32_bf16 v[22:25], v[172:175], v[210:213], v[22:25]
	v_mfma_f32_16x16x32_bf16 v[18:21], v[180:183], v[210:213], v[18:21]
	v_mfma_f32_16x16x32_bf16 v[6:9], v[172:175], v[218:221], v[6:9]
	v_mfma_f32_16x16x32_bf16 v[2:5], v[180:183], v[218:221], v[2:5]
	s_setprio 0
	s_waitcnt vmcnt(8)
	s_barrier
	s_add_i32 s57, s57, 2
	s_add_u32 s28, s28, 0x100
	s_addc_u32 s29, s29, 0
	s_add_u32 s55, s55, 0x100
	s_addc_u32 s56, s56, 0
	s_cmp_gt_u32 s57, 29
	s_cbranch_scc0 .Lkt_L_6
	s_branch .Lkt_exit_6
.Lkt_T_6:
	ds_read_b128 v[146:149], v152
	ds_read_b128 v[156:159], v152 offset:1024
	ds_read_b128 v[160:163], v152 offset:2048
	ds_read_b128 v[164:167], v152 offset:3072
	ds_read_b128 v[168:171], v153
	ds_read_b128 v[172:175], v153 offset:1024
	ds_read_b128 v[176:179], v153 offset:2048
	ds_read_b128 v[180:183], v153 offset:3072
	s_add_u32 s30, s28, 0xfff80080
	s_addc_u32 s31, s29, -1
	s_cmp_eq_u32 s57, 28
	s_cselect_b32 s35, s21, s31
	s_cselect_b32 s34, s53, s30
	s_cselect_b32 s31, s19, s56
	s_cselect_b32 s30, s54, s55
	v_lshl_add_u64 v[192:193], s[28:29], 0, v[138:139]
	s_add_i32 m0, s27, 0xc000
	ds_read_b128 v[184:187], v154
	ds_read_b128 v[188:191], v154 offset:1024
	ds_read_b128 v[196:199], v154 offset:2048
	ds_read_b128 v[200:203], v154 offset:3072
	ds_read_b128 v[206:209], v154 offset:4096
	ds_read_b128 v[210:213], v154 offset:5120
	ds_read_b128 v[214:217], v154 offset:6144
	ds_read_b128 v[218:221], v154 offset:7168
	global_load_lds_dwordx4 v[192:193], off
	v_lshl_add_u64 v[192:193], s[28:29], 0, v[140:141]
	s_add_i32 m0, s27, 0xe000
	s_nop 0
	global_load_lds_dwordx4 v[192:193], off
	s_waitcnt vmcnt(8)
	s_waitcnt lgkmcnt(0)
	s_barrier
	s_setprio 2
	v_mfma_f32_16x16x32_bf16 v[126:129], v[146:149], v[184:187], v[126:129]
	v_mfma_f32_16x16x32_bf16 v[122:125], v[160:163], v[184:187], v[122:125]
	v_mfma_f32_16x16x32_bf16 v[110:113], v[146:149], v[196:199], v[110:113]
	v_mfma_f32_16x16x32_bf16 v[106:109], v[160:163], v[196:199], v[106:109]
	v_mfma_f32_16x16x32_bf16 v[98:101], v[146:149], v[206:209], v[98:101]
	v_mfma_f32_16x16x32_bf16 v[90:93], v[160:163], v[206:209], v[90:93]
	v_mfma_f32_16x16x32_bf16 v[78:81], v[146:149], v[214:217], v[78:81]
	v_mfma_f32_16x16x32_bf16 v[74:77], v[160:163], v[214:217], v[74:77]
	v_mfma_f32_16x16x32_bf16 v[126:129], v[156:159], v[188:191], v[126:129]
	v_mfma_f32_16x16x32_bf16 v[122:125], v[164:167], v[188:191], v[122:125]
	v_mfma_f32_16x16x32_bf16 v[110:113], v[156:159], v[200:203], v[110:113]
	v_mfma_f32_16x16x32_bf16 v[106:109], v[164:167], v[200:203], v[106:109]
	v_mfma_f32_16x16x32_bf16 v[98:101], v[156:159], v[210:213], v[98:101]
	v_mfma_f32_16x16x32_bf16 v[90:93], v[164:167], v[210:213], v[90:93]
	v_mfma_f32_16x16x32_bf16 v[78:81], v[156:159], v[218:221], v[78:81]
	v_mfma_f32_16x16x32_bf16 v[74:77], v[164:167], v[218:221], v[74:77]
	v_mfma_f32_16x16x32_bf16 v[118:121], v[168:171], v[184:187], v[118:121]
	v_mfma_f32_16x16x32_bf16 v[114:117], v[176:179], v[184:187], v[114:117]
	v_mfma_f32_16x16x32_bf16 v[102:105], v[168:171], v[196:199], v[102:105]
	v_mfma_f32_16x16x32_bf16 v[94:97], v[176:179], v[196:199], v[94:97]
	v_mfma_f32_16x16x32_bf16 v[86:89], v[168:171], v[206:209], v[86:89]
	v_mfma_f32_16x16x32_bf16 v[82:85], v[176:179], v[206:209], v[82:85]
	v_mfma_f32_16x16x32_bf16 v[70:73], v[168:171], v[214:217], v[70:73]
	v_mfma_f32_16x16x32_bf16 v[66:69], v[176:179], v[214:217], v[66:69]
	v_mfma_f32_16x16x32_bf16 v[118:121], v[172:175], v[188:191], v[118:121]
	v_mfma_f32_16x16x32_bf16 v[114:117], v[180:183], v[188:191], v[114:117]
	v_mfma_f32_16x16x32_bf16 v[102:105], v[172:175], v[200:203], v[102:105]
	v_mfma_f32_16x16x32_bf16 v[94:97], v[180:183], v[200:203], v[94:97]
	v_mfma_f32_16x16x32_bf16 v[86:89], v[172:175], v[210:213], v[86:89]
	v_mfma_f32_16x16x32_bf16 v[82:85], v[180:183], v[210:213], v[82:85]
	v_mfma_f32_16x16x32_bf16 v[70:73], v[172:175], v[218:221], v[70:73]
	v_mfma_f32_16x16x32_bf16 v[66:69], v[180:183], v[218:221], v[66:69]
	s_setprio 0
	s_add_i32 s58, s50, s40
	v_lshl_add_u64 v[192:193], s[30:31], 0, v[134:135]
	s_mov_b32 m0, s58
	ds_read_b128 v[184:187], v154 offset:16384
	ds_read_b128 v[188:191], v154 offset:17408
	ds_read_b128 v[196:199], v154 offset:18432
	ds_read_b128 v[200:203], v154 offset:19456
	ds_read_b128 v[206:209], v154 offset:20480
	ds_read_b128 v[210:213], v154 offset:21504
	ds_read_b128 v[214:217], v154 offset:22528
	ds_read_b128 v[218:221], v154 offset:23552
	global_load_lds_dwordx4 v[192:193], off
	s_add_i32 m0, s58, 0x2000
	s_add_u32 s58, s30, 0x80000
	v_lshl_add_u64 v[222:223], s[30:31], 0, v[130:131]
	s_addc_u32 s59, s31, 0
	s_add_i32 s60, s51, s40
	global_load_lds_dwordx4 v[222:223], off
	v_lshl_add_u64 v[224:225], s[58:59], 0, v[134:135]
	s_mov_b32 m0, s60
	v_lshl_add_u64 v[226:227], s[34:35], 0, v[132:133]
	global_load_lds_dwordx4 v[224:225], off
	v_lshl_add_u64 v[224:225], s[58:59], 0, v[130:131]
	s_add_i32 m0, s60, 0x2000
	s_nop 0
	global_load_lds_dwordx4 v[224:225], off
	v_lshl_add_u64 v[224:225], s[34:35], 0, v[136:137]
	s_mov_b32 m0, s27
	s_nop 0
	global_load_lds_dwordx4 v[224:225], off
	s_mov_b32 m0, s42
	s_nop 0
	global_load_lds_dwordx4 v[226:227], off
	s_waitcnt vmcnt(8)
	s_waitcnt lgkmcnt(0)
	s_barrier
	s_setprio 2
	v_mfma_f32_16x16x32_bf16 v[62:65], v[146:149], v[184:187], v[62:65]
	v_mfma_f32_16x16x32_bf16 v[58:61], v[160:163], v[184:187], v[58:61]
	v_mfma_f32_16x16x32_bf16 v[46:49], v[146:149], v[196:199], v[46:49]
	v_mfma_f32_16x16x32_bf16 v[42:45], v[160:163], v[196:199], v[42:45]
	v_mfma_f32_16x16x32_bf16 v[30:33], v[146:149], v[206:209], v[30:33]
	v_mfma_f32_16x16x32_bf16 v[26:29], v[160:163], v[206:209], v[26:29]
	v_mfma_f32_16x16x32_bf16 v[14:17], v[146:149], v[214:217], v[14:17]
	v_mfma_f32_16x16x32_bf16 v[10:13], v[160:163], v[214:217], v[10:13]
	v_mfma_f32_16x16x32_bf16 v[62:65], v[156:159], v[188:191], v[62:65]
	v_mfma_f32_16x16x32_bf16 v[58:61], v[164:167], v[188:191], v[58:61]
	v_mfma_f32_16x16x32_bf16 v[46:49], v[156:159], v[200:203], v[46:49]
	v_mfma_f32_16x16x32_bf16 v[42:45], v[164:167], v[200:203], v[42:45]
	v_mfma_f32_16x16x32_bf16 v[30:33], v[156:159], v[210:213], v[30:33]
	v_mfma_f32_16x16x32_bf16 v[26:29], v[164:167], v[210:213], v[26:29]
	v_mfma_f32_16x16x32_bf16 v[14:17], v[156:159], v[218:221], v[14:17]
	v_mfma_f32_16x16x32_bf16 v[10:13], v[164:167], v[218:221], v[10:13]
	v_mfma_f32_16x16x32_bf16 v[54:57], v[168:171], v[184:187], v[54:57]
	v_mfma_f32_16x16x32_bf16 v[50:53], v[176:179], v[184:187], v[50:53]
	v_mfma_f32_16x16x32_bf16 v[38:41], v[168:171], v[196:199], v[38:41]
	v_mfma_f32_16x16x32_bf16 v[34:37], v[176:179], v[196:199], v[34:37]
	v_mfma_f32_16x16x32_bf16 v[22:25], v[168:171], v[206:209], v[22:25]
	v_mfma_f32_16x16x32_bf16 v[18:21], v[176:179], v[206:209], v[18:21]
	v_mfma_f32_16x16x32_bf16 v[6:9], v[168:171], v[214:217], v[6:9]
	v_mfma_f32_16x16x32_bf16 v[2:5], v[176:179], v[214:217], v[2:5]
	v_mfma_f32_16x16x32_bf16 v[54:57], v[172:175], v[188:191], v[54:57]
	v_mfma_f32_16x16x32_bf16 v[50:53], v[180:183], v[188:191], v[50:53]
	v_mfma_f32_16x16x32_bf16 v[38:41], v[172:175], v[200:203], v[38:41]
	v_mfma_f32_16x16x32_bf16 v[34:37], v[180:183], v[200:203], v[34:37]
	v_mfma_f32_16x16x32_bf16 v[22:25], v[172:175], v[210:213], v[22:25]
	v_mfma_f32_16x16x32_bf16 v[18:21], v[180:183], v[210:213], v[18:21]
	v_mfma_f32_16x16x32_bf16 v[6:9], v[172:175], v[218:221], v[6:9]
	v_mfma_f32_16x16x32_bf16 v[2:5], v[180:183], v[218:221], v[2:5]
	s_setprio 0
	s_add_i32 s58, 0, 0x18000
	v_add_u32_e32 v155, s58, v150
	s_add_i32 s59, 0, 0x1c000
	ds_read_b128 v[146:149], v155
	ds_read_b128 v[156:159], v155 offset:1024
	ds_read_b128 v[160:163], v155 offset:2048
	ds_read_b128 v[164:167], v155 offset:3072
	v_add_u32_e32 v155, s59, v150
	ds_read_b128 v[168:171], v155
	ds_read_b128 v[172:175], v155 offset:1024
	ds_read_b128 v[176:179], v155 offset:2048
	ds_read_b128 v[180:183], v155 offset:3072
	s_add_u32 s34, s34, 0x80000
	s_addc_u32 s35, s35, 0
	s_mov_b32 m0, s43
	v_lshl_add_u64 v[228:229], s[34:35], 0, v[136:137]
	ds_read_b128 v[184:187], v154 offset:32768
	ds_read_b128 v[188:191], v154 offset:33792
	ds_read_b128 v[196:199], v154 offset:34816
	ds_read_b128 v[200:203], v154 offset:35840
	ds_read_b128 v[206:209], v154 offset:36864
	ds_read_b128 v[210:213], v154 offset:37888
	ds_read_b128 v[214:217], v154 offset:38912
	ds_read_b128 v[218:221], v154 offset:39936
	global_load_lds_dwordx4 v[228:229], off
	v_lshl_add_u64 v[228:229], s[34:35], 0, v[132:133]
	s_mov_b32 m0, s45
	s_nop 0
	global_load_lds_dwordx4 v[228:229], off
	s_waitcnt vmcnt(8)
	s_waitcnt lgkmcnt(0)
	s_barrier
	s_setprio 2
	v_mfma_f32_16x16x32_bf16 v[126:129], v[146:149], v[184:187], v[126:129]
	v_mfma_f32_16x16x32_bf16 v[122:125], v[160:163], v[184:187], v[122:125]
	v_mfma_f32_16x16x32_bf16 v[110:113], v[146:149], v[196:199], v[110:113]
	v_mfma_f32_16x16x32_bf16 v[106:109], v[160:163], v[196:199], v[106:109]
	v_mfma_f32_16x16x32_bf16 v[98:101], v[146:149], v[206:209], v[98:101]
	v_mfma_f32_16x16x32_bf16 v[90:93], v[160:163], v[206:209], v[90:93]
	v_mfma_f32_16x16x32_bf16 v[78:81], v[146:149], v[214:217], v[78:81]
	v_mfma_f32_16x16x32_bf16 v[74:77], v[160:163], v[214:217], v[74:77]
	v_mfma_f32_16x16x32_bf16 v[126:129], v[156:159], v[188:191], v[126:129]
	v_mfma_f32_16x16x32_bf16 v[122:125], v[164:167], v[188:191], v[122:125]
	v_mfma_f32_16x16x32_bf16 v[110:113], v[156:159], v[200:203], v[110:113]
	v_mfma_f32_16x16x32_bf16 v[106:109], v[164:167], v[200:203], v[106:109]
	v_mfma_f32_16x16x32_bf16 v[98:101], v[156:159], v[210:213], v[98:101]
	v_mfma_f32_16x16x32_bf16 v[90:93], v[164:167], v[210:213], v[90:93]
	v_mfma_f32_16x16x32_bf16 v[78:81], v[156:159], v[218:221], v[78:81]
	v_mfma_f32_16x16x32_bf16 v[74:77], v[164:167], v[218:221], v[74:77]
	v_mfma_f32_16x16x32_bf16 v[118:121], v[168:171], v[184:187], v[118:121]
	v_mfma_f32_16x16x32_bf16 v[114:117], v[176:179], v[184:187], v[114:117]
	v_mfma_f32_16x16x32_bf16 v[102:105], v[168:171], v[196:199], v[102:105]
	v_mfma_f32_16x16x32_bf16 v[94:97], v[176:179], v[196:199], v[94:97]
	v_mfma_f32_16x16x32_bf16 v[86:89], v[168:171], v[206:209], v[86:89]
	v_mfma_f32_16x16x32_bf16 v[82:85], v[176:179], v[206:209], v[82:85]
	v_mfma_f32_16x16x32_bf16 v[70:73], v[168:171], v[214:217], v[70:73]
	v_mfma_f32_16x16x32_bf16 v[66:69], v[176:179], v[214:217], v[66:69]
	v_mfma_f32_16x16x32_bf16 v[118:121], v[172:175], v[188:191], v[118:121]
	v_mfma_f32_16x16x32_bf16 v[114:117], v[180:183], v[188:191], v[114:117]
	v_mfma_f32_16x16x32_bf16 v[102:105], v[172:175], v[200:203], v[102:105]
	v_mfma_f32_16x16x32_bf16 v[94:97], v[180:183], v[200:203], v[94:97]
	v_mfma_f32_16x16x32_bf16 v[86:89], v[172:175], v[210:213], v[86:89]
	v_mfma_f32_16x16x32_bf16 v[82:85], v[180:183], v[210:213], v[82:85]
	v_mfma_f32_16x16x32_bf16 v[70:73], v[172:175], v[218:221], v[70:73]
	v_mfma_f32_16x16x32_bf16 v[66:69], v[180:183], v[218:221], v[66:69]
	s_setprio 0
	s_add_i32 s34, s58, s40
	v_lshl_add_u64 v[192:193], v[192:193], 0, s[14:15]
	s_mov_b32 m0, s34
	ds_read_b128 v[184:187], v154 offset:49152
	ds_read_b128 v[188:191], v154 offset:50176
	ds_read_b128 v[196:199], v154 offset:51200
	ds_read_b128 v[200:203], v154 offset:52224
	ds_read_b128 v[206:209], v154 offset:53248
	ds_read_b128 v[210:213], v154 offset:54272
	ds_read_b128 v[214:217], v154 offset:55296
	ds_read_b128 v[218:221], v154 offset:56320
	global_load_lds_dwordx4 v[192:193], off
	s_add_i32 m0, s34, 0x2000
	s_add_u32 s30, s30, 0x80080
	v_lshl_add_u64 v[192:193], v[222:223], 0, s[14:15]
	s_addc_u32 s31, s31, 0
	s_add_i32 s34, s59, s40
	global_load_lds_dwordx4 v[192:193], off
	v_lshl_add_u64 v[192:193], s[30:31], 0, v[134:135]
	s_mov_b32 m0, s34
	s_nop 0
	global_load_lds_dwordx4 v[192:193], off
	v_lshl_add_u64 v[192:193], s[30:31], 0, v[130:131]
	s_add_i32 m0, s34, 0x2000
	s_nop 0
	global_load_lds_dwordx4 v[192:193], off
	v_lshl_add_u64 v[192:193], v[224:225], 0, s[14:15]
	s_mov_b32 m0, s47
	s_nop 0
	global_load_lds_dwordx4 v[192:193], off
	v_lshl_add_u64 v[192:193], v[226:227], 0, s[14:15]
	s_mov_b32 m0, s48
	s_nop 0
	global_load_lds_dwordx4 v[192:193], off
	s_waitcnt vmcnt(8)
	s_waitcnt lgkmcnt(0)
	s_barrier
	s_setprio 2
	v_mfma_f32_16x16x32_bf16 v[62:65], v[146:149], v[184:187], v[62:65]
	v_mfma_f32_16x16x32_bf16 v[58:61], v[160:163], v[184:187], v[58:61]
	v_mfma_f32_16x16x32_bf16 v[46:49], v[146:149], v[196:199], v[46:49]
	v_mfma_f32_16x16x32_bf16 v[42:45], v[160:163], v[196:199], v[42:45]
	v_mfma_f32_16x16x32_bf16 v[30:33], v[146:149], v[206:209], v[30:33]
	v_mfma_f32_16x16x32_bf16 v[26:29], v[160:163], v[206:209], v[26:29]
	v_mfma_f32_16x16x32_bf16 v[14:17], v[146:149], v[214:217], v[14:17]
	v_mfma_f32_16x16x32_bf16 v[10:13], v[160:163], v[214:217], v[10:13]
	v_mfma_f32_16x16x32_bf16 v[62:65], v[156:159], v[188:191], v[62:65]
	v_mfma_f32_16x16x32_bf16 v[58:61], v[164:167], v[188:191], v[58:61]
	v_mfma_f32_16x16x32_bf16 v[46:49], v[156:159], v[200:203], v[46:49]
	v_mfma_f32_16x16x32_bf16 v[42:45], v[164:167], v[200:203], v[42:45]
	v_mfma_f32_16x16x32_bf16 v[30:33], v[156:159], v[210:213], v[30:33]
	v_mfma_f32_16x16x32_bf16 v[26:29], v[164:167], v[210:213], v[26:29]
	v_mfma_f32_16x16x32_bf16 v[14:17], v[156:159], v[218:221], v[14:17]
	v_mfma_f32_16x16x32_bf16 v[10:13], v[164:167], v[218:221], v[10:13]
	v_mfma_f32_16x16x32_bf16 v[54:57], v[168:171], v[184:187], v[54:57]
	v_mfma_f32_16x16x32_bf16 v[50:53], v[176:179], v[184:187], v[50:53]
	v_mfma_f32_16x16x32_bf16 v[38:41], v[168:171], v[196:199], v[38:41]
	v_mfma_f32_16x16x32_bf16 v[34:37], v[176:179], v[196:199], v[34:37]
	v_mfma_f32_16x16x32_bf16 v[22:25], v[168:171], v[206:209], v[22:25]
	v_mfma_f32_16x16x32_bf16 v[18:21], v[176:179], v[206:209], v[18:21]
	v_mfma_f32_16x16x32_bf16 v[6:9], v[168:171], v[214:217], v[6:9]
	v_mfma_f32_16x16x32_bf16 v[2:5], v[176:179], v[214:217], v[2:5]
	v_mfma_f32_16x16x32_bf16 v[54:57], v[172:175], v[188:191], v[54:57]
	v_mfma_f32_16x16x32_bf16 v[50:53], v[180:183], v[188:191], v[50:53]
	v_mfma_f32_16x16x32_bf16 v[38:41], v[172:175], v[200:203], v[38:41]
	v_mfma_f32_16x16x32_bf16 v[34:37], v[180:183], v[200:203], v[34:37]
	v_mfma_f32_16x16x32_bf16 v[22:25], v[172:175], v[210:213], v[22:25]
	v_mfma_f32_16x16x32_bf16 v[18:21], v[180:183], v[210:213], v[18:21]
	v_mfma_f32_16x16x32_bf16 v[6:9], v[172:175], v[218:221], v[6:9]
	v_mfma_f32_16x16x32_bf16 v[2:5], v[180:183], v[218:221], v[2:5]
	s_setprio 0
	s_add_i32 s57, s57, 2
	s_add_u32 s28, s28, 0x100
	s_addc_u32 s29, s29, 0
	s_add_u32 s55, s55, 0x100
	s_addc_u32 s56, s56, 0
	s_cmp_gt_u32 s57, 29
	s_cbranch_scc0 .Lkt_T_6
	s_nop 7

.LBB0_970:
	v_lshl_add_u32 v148, s26, 8, v1
	v_lshl_or_b32 v146, s52, 8, v151
	v_ashrrev_i32_e32 v149, 31, v148
	v_ashrrev_i32_e32 v147, 31, v146
	v_lshlrev_b64 v[156:157], 12, v[148:149]
	v_lshl_add_u64 v[156:157], s[8:9], 0, v[156:157]
	v_lshlrev_b64 v[146:147], 1, v[146:147]
	v_lshl_add_u64 v[160:161], v[156:157], 0, v[146:147]
	global_load_dwordx4 v[156:159], v[160:161], off
	v_mul_f32_e32 v126, 0xbfb8aa3b, v126
	v_mul_f32_e32 v128, 0xbfb8aa3b, v128
	v_mul_f32_e32 v122, 0xbfb8aa3b, v122
	v_mul_f32_e32 v127, 0xbfb8aa3b, v127
	v_mul_f32_e32 v129, 0xbfb8aa3b, v129
	v_mul_f32_e32 v123, 0xbfb8aa3b, v123
	v_mul_f32_e32 v167, 0xbfb8aa3b, v120
	v_exp_f32_e32 v120, v126
	v_exp_f32_e32 v126, v128
	v_exp_f32_e32 v128, v122
	v_or_b32_e32 v122, 16, v148
	v_mul_f32_e32 v168, 0xbfb8aa3b, v121
	v_mul_f32_e32 v169, 0xbfb8aa3b, v114
	v_mul_f32_e32 v170, 0xbfb8aa3b, v115
	v_exp_f32_e32 v121, v127
	v_exp_f32_e32 v127, v129
	v_exp_f32_e32 v129, v123
	v_lshlrev_b64 v[114:115], 13, v[148:149]
	v_ashrrev_i32_e32 v123, 31, v122
	v_mul_f32_e32 v124, 0xbfb8aa3b, v124
	v_mul_f32_e32 v125, 0xbfb8aa3b, v125
	v_mul_f32_e32 v171, 0xbfb8aa3b, v116
	v_mul_f32_e32 v172, 0xbfb8aa3b, v117
	v_lshl_add_u64 v[114:115], s[12:13], 0, v[114:115]
	v_lshlrev_b64 v[116:117], 12, v[122:123]
	v_mul_f32_e32 v155, 0xbfb8aa3b, v118
	v_mul_f32_e32 v166, 0xbfb8aa3b, v119
	v_exp_f32_e32 v162, v124
	v_exp_f32_e32 v163, v125
	v_lshl_add_u64 v[124:125], v[114:115], 0, v[146:147]
	v_lshl_add_u64 v[118:119], s[8:9], 0, v[116:117]
	global_load_dwordx4 v[114:117], v[160:161], off offset:256
	v_add_f32_e32 v120, 1.0, v120
	v_add_f32_e32 v121, 1.0, v121
	v_add_f32_e32 v149, 1.0, v126
	v_add_f32_e32 v164, 1.0, v127
	v_add_f32_e32 v128, 1.0, v128
	v_add_f32_e32 v129, 1.0, v129
	v_add_f32_e32 v160, 1.0, v162
	v_add_f32_e32 v161, 1.0, v163
	v_lshl_add_u64 v[126:127], v[118:119], 0, v[146:147]
	v_rcp_f32_e32 v118, v120
	v_rcp_f32_e32 v119, v121
	v_rcp_f32_e32 v120, v149
	v_rcp_f32_e32 v121, v164
	v_rcp_f32_e32 v128, v128
	v_rcp_f32_e32 v129, v129
	v_rcp_f32_e32 v160, v160
	v_rcp_f32_e32 v161, v161
	v_mul_f32_e32 v112, 0xbfb8aa3b, v112
	v_mul_f32_e32 v113, 0xbfb8aa3b, v113
	v_exp_f32_e32 v149, v155
	v_exp_f32_e32 v155, v166
	v_exp_f32_e32 v112, v112
	v_exp_f32_e32 v113, v113
	v_mul_f32_e32 v106, 0xbfb8aa3b, v106
	v_mul_f32_e32 v107, 0xbfb8aa3b, v107
	v_mul_f32_e32 v110, 0xbfb8aa3b, v110
	v_mul_f32_e32 v111, 0xbfb8aa3b, v111
	v_mul_f32_e32 v108, 0xbfb8aa3b, v108
	v_mul_f32_e32 v109, 0xbfb8aa3b, v109
	v_exp_f32_e32 v166, v108
	v_mul_f32_e32 v102, 0xbfb8aa3b, v102
	v_mul_f32_e32 v103, 0xbfb8aa3b, v103
	v_mul_f32_e32 v104, 0xbfb8aa3b, v104
	v_mul_f32_e32 v105, 0xbfb8aa3b, v105
	v_mul_f32_e32 v94, 0xbfb8aa3b, v94
	v_mul_f32_e32 v95, 0xbfb8aa3b, v95
	v_mul_f32_e32 v96, 0xbfb8aa3b, v96
	v_mul_f32_e32 v97, 0xbfb8aa3b, v97
	v_exp_f32_e32 v94, v94
	v_exp_f32_e32 v95, v95
	v_exp_f32_e32 v96, v96
	v_exp_f32_e32 v97, v97
	v_mul_f32_e32 v98, 0xbfb8aa3b, v98
	v_mul_f32_e32 v92, 0xbfb8aa3b, v92
	v_mul_f32_e32 v86, 0xbfb8aa3b, v86
	v_mul_f32_e32 v87, 0xbfb8aa3b, v87
	v_mul_f32_e32 v88, 0xbfb8aa3b, v88
	s_waitcnt vmcnt(0)
	v_lshlrev_b32_e32 v162, 16, v156
	v_and_b32_e32 v163, 0xffff0000, v156
	v_lshlrev_b32_e32 v156, 16, v157
	v_and_b32_e32 v157, 0xffff0000, v157
	v_lshlrev_b32_e32 v164, 16, v158
	v_and_b32_e32 v165, 0xffff0000, v158
	v_lshlrev_b32_e32 v158, 16, v159
	v_and_b32_e32 v159, 0xffff0000, v159
	v_pk_mul_f32 v[118:119], v[118:119], v[162:163]
	v_pk_mul_f32 v[120:121], v[120:121], v[156:157]
	v_pk_mul_f32 v[128:129], v[128:129], v[164:165]
	v_pk_mul_f32 v[156:157], v[160:161], v[158:159]
	v_cvt_pk_bf16_f32 v118, v118, v119
	v_cvt_pk_bf16_f32 v119, v120, v121
	v_cvt_pk_bf16_f32 v120, v128, v129
	v_cvt_pk_bf16_f32 v121, v156, v157
	global_store_dwordx4 v[124:125], v[118:121], off
	global_load_dwordx4 v[118:121], v[126:127], off
	v_exp_f32_e32 v156, v167
	v_exp_f32_e32 v157, v168
	v_exp_f32_e32 v158, v169
	v_exp_f32_e32 v159, v170
	v_exp_f32_e32 v160, v171
	v_exp_f32_e32 v161, v172
	v_exp_f32_e32 v164, v106
	v_exp_f32_e32 v165, v107
	v_lshlrev_b64 v[106:107], 13, v[122:123]
	v_exp_f32_e32 v162, v110
	v_exp_f32_e32 v163, v111
	v_exp_f32_e32 v167, v109
	v_lshl_add_u64 v[110:111], s[12:13], 0, v[106:107]
	v_add_f32_e32 v106, 1.0, v149
	v_add_f32_e32 v107, 1.0, v155
	v_add_f32_e32 v108, 1.0, v156
	v_add_f32_e32 v109, 1.0, v157
	v_add_f32_e32 v149, 1.0, v158
	v_add_f32_e32 v155, 1.0, v159
	v_add_f32_e32 v156, 1.0, v160
	v_add_f32_e32 v157, 1.0, v161
	v_add_f32_e32 v168, 1.0, v112
	v_add_f32_e32 v169, 1.0, v113
	v_rcp_f32_e32 v106, v106
	v_rcp_f32_e32 v107, v107
	v_rcp_f32_e32 v108, v108
	v_rcp_f32_e32 v109, v109
	v_rcp_f32_e32 v112, v149
	v_rcp_f32_e32 v113, v155
	v_rcp_f32_e32 v156, v156
	v_rcp_f32_e32 v157, v157
	v_lshlrev_b32_e32 v158, 16, v114
	v_and_b32_e32 v159, 0xffff0000, v114
	v_lshlrev_b32_e32 v114, 16, v115
	v_and_b32_e32 v115, 0xffff0000, v115
	v_lshlrev_b32_e32 v160, 16, v116
	v_and_b32_e32 v161, 0xffff0000, v116
	v_lshlrev_b32_e32 v116, 16, v117
	v_and_b32_e32 v117, 0xffff0000, v117
	v_pk_mul_f32 v[106:107], v[106:107], v[158:159]
	v_pk_mul_f32 v[108:109], v[108:109], v[114:115]
	v_pk_mul_f32 v[112:113], v[112:113], v[160:161]
	v_pk_mul_f32 v[114:115], v[156:157], v[116:117]
	v_cvt_pk_bf16_f32 v106, v106, v107
	v_cvt_pk_bf16_f32 v107, v108, v109
	v_cvt_pk_bf16_f32 v108, v112, v113
	v_cvt_pk_bf16_f32 v109, v114, v115
	global_store_dwordx4 v[124:125], v[106:109], off offset:256
	global_load_dwordx4 v[106:109], v[126:127], off offset:256
	v_add_f32_e32 v162, 1.0, v162
	v_add_f32_e32 v163, 1.0, v163
	v_add_f32_e32 v116, 1.0, v164
	v_add_f32_e32 v117, 1.0, v165
	v_add_f32_e32 v124, 1.0, v166
	v_add_f32_e32 v125, 1.0, v167
	v_lshl_add_u64 v[114:115], v[110:111], 0, v[146:147]
	v_rcp_f32_e32 v110, v162
	v_rcp_f32_e32 v111, v163
	v_rcp_f32_e32 v112, v168
	v_rcp_f32_e32 v113, v169
	v_rcp_f32_e32 v116, v116
	v_rcp_f32_e32 v117, v117
	v_rcp_f32_e32 v124, v124
	v_rcp_f32_e32 v125, v125
	v_or_b32_e32 v128, 32, v148
	v_ashrrev_i32_e32 v129, 31, v128
	v_lshlrev_b64 v[122:123], 12, v[128:129]
	v_mul_f32_e32 v89, 0xbfb8aa3b, v89
	v_exp_f32_e32 v86, v86
	v_exp_f32_e32 v87, v87
	v_exp_f32_e32 v88, v88
	v_exp_f32_e32 v89, v89
	v_mul_f32_e32 v82, 0xbfb8aa3b, v82
	v_mul_f32_e32 v83, 0xbfb8aa3b, v83
	v_exp_f32_e32 v82, v82
	v_exp_f32_e32 v83, v83
	v_mul_f32_e32 v84, 0xbfb8aa3b, v84
	v_mul_f32_e32 v85, 0xbfb8aa3b, v85
	v_add_f32_e32 v86, 1.0, v86
	s_waitcnt vmcnt(2)
	v_lshlrev_b32_e32 v126, 16, v118
	v_and_b32_e32 v127, 0xffff0000, v118
	v_lshlrev_b32_e32 v118, 16, v119
	v_and_b32_e32 v119, 0xffff0000, v119
	v_lshlrev_b32_e32 v156, 16, v120
	v_and_b32_e32 v157, 0xffff0000, v120
	v_lshlrev_b32_e32 v120, 16, v121
	v_and_b32_e32 v121, 0xffff0000, v121
	v_pk_mul_f32 v[110:111], v[110:111], v[126:127]
	v_pk_mul_f32 v[112:113], v[112:113], v[118:119]
	v_pk_mul_f32 v[116:117], v[116:117], v[156:157]
	v_pk_mul_f32 v[118:119], v[124:125], v[120:121]
	v_cvt_pk_bf16_f32 v110, v110, v111
	v_cvt_pk_bf16_f32 v111, v112, v113
	v_cvt_pk_bf16_f32 v112, v116, v117
	v_cvt_pk_bf16_f32 v113, v118, v119
	global_store_dwordx4 v[114:115], v[110:113], off
	v_mul_f32_e32 v118, 0xbfb8aa3b, v99
	v_mul_f32_e32 v119, 0xbfb8aa3b, v100
	v_lshl_add_u64 v[110:111], s[8:9], 0, v[122:123]
	v_lshl_add_u64 v[116:117], v[110:111], 0, v[146:147]
	global_load_dwordx4 v[110:113], v[116:117], off
	v_mul_f32_e32 v121, 0xbfb8aa3b, v90
	v_mul_f32_e32 v122, 0xbfb8aa3b, v91
	v_exp_f32_e32 v90, v102
	v_exp_f32_e32 v91, v103
	v_exp_f32_e32 v99, v104
	v_exp_f32_e32 v100, v105
	v_mul_f32_e32 v120, 0xbfb8aa3b, v101
	v_exp_f32_e32 v123, v98
	v_add_f32_e32 v90, 1.0, v90
	v_add_f32_e32 v91, 1.0, v91
	v_add_f32_e32 v98, 1.0, v99
	v_add_f32_e32 v99, 1.0, v100
	v_add_f32_e32 v100, 1.0, v94
	v_add_f32_e32 v101, 1.0, v95
	v_add_f32_e32 v102, 1.0, v96
	v_add_f32_e32 v103, 1.0, v97
	v_rcp_f32_e32 v90, v90
	v_rcp_f32_e32 v91, v91
	v_rcp_f32_e32 v94, v98
	v_rcp_f32_e32 v95, v99
	v_rcp_f32_e32 v96, v100
	v_rcp_f32_e32 v97, v101
	v_rcp_f32_e32 v98, v102
	v_rcp_f32_e32 v99, v103
	v_add_f32_e32 v87, 1.0, v87
	v_add_f32_e32 v88, 1.0, v88
	v_add_f32_e32 v89, 1.0, v89
	s_waitcnt vmcnt(2)
	v_lshlrev_b32_e32 v100, 16, v106
	v_and_b32_e32 v101, 0xffff0000, v106
	v_lshlrev_b32_e32 v102, 16, v107
	v_and_b32_e32 v103, 0xffff0000, v107
	v_lshlrev_b32_e32 v104, 16, v108
	v_and_b32_e32 v105, 0xffff0000, v108
	v_lshlrev_b32_e32 v106, 16, v109
	v_and_b32_e32 v107, 0xffff0000, v109
	v_pk_mul_f32 v[90:91], v[90:91], v[100:101]
	v_pk_mul_f32 v[100:101], v[94:95], v[102:103]
	v_pk_mul_f32 v[96:97], v[96:97], v[104:105]
	v_pk_mul_f32 v[98:99], v[98:99], v[106:107]
	v_cvt_pk_bf16_f32 v94, v90, v91
	v_cvt_pk_bf16_f32 v95, v100, v101
	v_cvt_pk_bf16_f32 v96, v96, v97
	v_cvt_pk_bf16_f32 v97, v98, v99
	global_store_dwordx4 v[114:115], v[94:97], off offset:256
	global_load_dwordx4 v[94:97], v[116:117], off offset:256
	v_exp_f32_e32 v90, v118
	v_exp_f32_e32 v91, v119
	v_exp_f32_e32 v100, v120
	v_exp_f32_e32 v101, v121
	v_add_f32_e32 v102, 1.0, v123
	v_add_f32_e32 v103, 1.0, v90
	v_add_f32_e32 v104, 1.0, v91
	v_add_f32_e32 v105, 1.0, v100
	v_add_f32_e32 v107, 1.0, v101
	v_rcp_f32_e32 v90, v102
	v_rcp_f32_e32 v91, v103
	v_rcp_f32_e32 v100, v104
	v_rcp_f32_e32 v101, v105
	v_exp_f32_e32 v106, v122
	v_lshlrev_b64 v[98:99], 13, v[128:129]
	v_lshl_add_u64 v[98:99], s[12:13], 0, v[98:99]
	v_lshl_add_u64 v[98:99], v[98:99], 0, v[146:147]
	v_exp_f32_e32 v84, v84
	v_exp_f32_e32 v85, v85
	v_rcp_f32_e32 v86, v86
	v_rcp_f32_e32 v87, v87
	v_rcp_f32_e32 v88, v88
	v_rcp_f32_e32 v89, v89
	v_add_f32_e32 v82, 1.0, v82
	v_add_f32_e32 v83, 1.0, v83
	v_rcp_f32_e32 v82, v82
	v_rcp_f32_e32 v83, v83
	v_add_f32_e32 v84, 1.0, v84
	v_add_f32_e32 v85, 1.0, v85
	v_rcp_f32_e32 v84, v84
	v_rcp_f32_e32 v85, v85
	v_mul_f32_e32 v78, 0xbfb8aa3b, v78
	v_mul_f32_e32 v79, 0xbfb8aa3b, v79
	v_exp_f32_e32 v78, v78
	s_waitcnt vmcnt(2)
	v_lshlrev_b32_e32 v102, 16, v110
	v_and_b32_e32 v103, 0xffff0000, v110
	v_lshlrev_b32_e32 v104, 16, v111
	v_and_b32_e32 v105, 0xffff0000, v111
	v_pk_mul_f32 v[90:91], v[90:91], v[102:103]
	v_pk_mul_f32 v[100:101], v[100:101], v[104:105]
	v_cvt_pk_bf16_f32 v90, v90, v91
	v_cvt_pk_bf16_f32 v91, v100, v101
	v_add_f32_e32 v101, 1.0, v106
	v_exp_f32_e32 v104, v92
	v_mul_f32_e32 v92, 0xbfb8aa3b, v93
	v_rcp_f32_e32 v100, v107
	v_rcp_f32_e32 v101, v101
	v_exp_f32_e32 v105, v92
	v_lshlrev_b32_e32 v102, 16, v112
	v_and_b32_e32 v103, 0xffff0000, v112
	v_pk_mul_f32 v[92:93], v[100:101], v[102:103]
	v_add_f32_e32 v100, 1.0, v104
	v_add_f32_e32 v101, 1.0, v105
	v_rcp_f32_e32 v100, v100
	v_rcp_f32_e32 v101, v101
	v_lshlrev_b32_e32 v102, 16, v113
	v_and_b32_e32 v103, 0xffff0000, v113
	v_cvt_pk_bf16_f32 v92, v92, v93
	v_pk_mul_f32 v[100:101], v[100:101], v[102:103]
	v_exp_f32_e32 v79, v79
	v_cvt_pk_bf16_f32 v93, v100, v101
	v_or_b32_e32 v100, 48, v148
	v_ashrrev_i32_e32 v101, 31, v100
	global_store_dwordx4 v[98:99], v[90:93], off
	v_mul_f32_e32 v80, 0xbfb8aa3b, v80
	v_mul_f32_e32 v81, 0xbfb8aa3b, v81
	v_lshlrev_b64 v[90:91], 12, v[100:101]
	v_lshl_add_u64 v[90:91], s[8:9], 0, v[90:91]
	v_lshl_add_u64 v[102:103], v[90:91], 0, v[146:147]
	global_load_dwordx4 v[90:93], v[102:103], off
	v_exp_f32_e32 v80, v80
	v_exp_f32_e32 v81, v81
	v_mul_f32_e32 v74, 0xbfb8aa3b, v74
	v_mul_f32_e32 v75, 0xbfb8aa3b, v75
	v_exp_f32_e32 v74, v74
	v_exp_f32_e32 v75, v75
	v_add_f32_e32 v78, 1.0, v78
	v_add_f32_e32 v79, 1.0, v79
	v_mul_f32_e32 v76, 0xbfb8aa3b, v76
	s_waitcnt vmcnt(2)
	v_lshlrev_b32_e32 v104, 16, v94
	v_and_b32_e32 v105, 0xffff0000, v94
	v_lshlrev_b32_e32 v94, 16, v95
	v_and_b32_e32 v95, 0xffff0000, v95
	v_pk_mul_f32 v[86:87], v[86:87], v[104:105]
	v_pk_mul_f32 v[88:89], v[88:89], v[94:95]
	v_cvt_pk_bf16_f32 v86, v86, v87
	v_cvt_pk_bf16_f32 v87, v88, v89
	v_lshlrev_b32_e32 v88, 16, v96
	v_and_b32_e32 v89, 0xffff0000, v96
	v_pk_mul_f32 v[82:83], v[82:83], v[88:89]
	v_mul_f32_e32 v77, 0xbfb8aa3b, v77
	v_cvt_pk_bf16_f32 v88, v82, v83
	v_lshlrev_b32_e32 v82, 16, v97
	v_and_b32_e32 v83, 0xffff0000, v97
	v_pk_mul_f32 v[82:83], v[84:85], v[82:83]
	v_rcp_f32_e32 v78, v78
	v_cvt_pk_bf16_f32 v89, v82, v83
	global_store_dwordx4 v[98:99], v[86:89], off offset:256
	global_load_dwordx4 v[82:85], v[102:103], off offset:256
	v_rcp_f32_e32 v79, v79
	v_add_f32_e32 v80, 1.0, v80
	v_add_f32_e32 v81, 1.0, v81
	v_exp_f32_e32 v76, v76
	v_exp_f32_e32 v77, v77
	v_rcp_f32_e32 v80, v80
	v_rcp_f32_e32 v81, v81
	v_add_f32_e32 v74, 1.0, v74
	v_add_f32_e32 v75, 1.0, v75
	v_rcp_f32_e32 v74, v74
	v_rcp_f32_e32 v75, v75
	v_add_f32_e32 v76, 1.0, v76
	v_add_f32_e32 v77, 1.0, v77
	v_rcp_f32_e32 v76, v76
	v_rcp_f32_e32 v77, v77
	v_lshlrev_b64 v[86:87], 13, v[100:101]
	v_mul_f32_e32 v70, 0xbfb8aa3b, v70
	v_mul_f32_e32 v71, 0xbfb8aa3b, v71
	v_mul_f32_e32 v72, 0xbfb8aa3b, v72
	v_mul_f32_e32 v73, 0xbfb8aa3b, v73
	v_exp_f32_e32 v70, v70
	v_exp_f32_e32 v71, v71
	v_exp_f32_e32 v72, v72
	v_exp_f32_e32 v73, v73
	v_mul_f32_e32 v66, 0xbfb8aa3b, v66
	v_mul_f32_e32 v67, 0xbfb8aa3b, v67
	v_exp_f32_e32 v66, v66
	v_exp_f32_e32 v67, v67
	v_mul_f32_e32 v68, 0xbfb8aa3b, v68
	v_mul_f32_e32 v69, 0xbfb8aa3b, v69
	v_add_f32_e32 v70, 1.0, v70
	v_add_f32_e32 v71, 1.0, v71
	v_add_f32_e32 v72, 1.0, v72
	v_add_f32_e32 v73, 1.0, v73
	v_exp_f32_e32 v68, v68
	v_exp_f32_e32 v69, v69
	v_rcp_f32_e32 v70, v70
	v_rcp_f32_e32 v71, v71
	v_rcp_f32_e32 v72, v72
	v_rcp_f32_e32 v73, v73
	v_add_f32_e32 v66, 1.0, v66
	v_add_f32_e32 v67, 1.0, v67
	v_rcp_f32_e32 v66, v66
	v_rcp_f32_e32 v67, v67
	v_add_f32_e32 v68, 1.0, v68
	v_add_f32_e32 v69, 1.0, v69
	v_rcp_f32_e32 v68, v68
	v_rcp_f32_e32 v69, v69
	v_mul_f32_e32 v62, 0xbfb8aa3b, v62
	v_mul_f32_e32 v63, 0xbfb8aa3b, v63
	s_waitcnt vmcnt(2)
	v_lshlrev_b32_e32 v88, 16, v90
	v_and_b32_e32 v89, 0xffff0000, v90
	v_pk_mul_f32 v[78:79], v[78:79], v[88:89]
	v_lshlrev_b32_e32 v88, 16, v91
	v_and_b32_e32 v89, 0xffff0000, v91
	v_pk_mul_f32 v[80:81], v[80:81], v[88:89]
	v_cvt_pk_bf16_f32 v78, v78, v79
	v_cvt_pk_bf16_f32 v79, v80, v81
	v_lshlrev_b32_e32 v80, 16, v92
	v_and_b32_e32 v81, 0xffff0000, v92
	v_pk_mul_f32 v[74:75], v[74:75], v[80:81]
	v_exp_f32_e32 v62, v62
	v_cvt_pk_bf16_f32 v80, v74, v75
	v_lshlrev_b32_e32 v74, 16, v93
	v_and_b32_e32 v75, 0xffff0000, v93
	v_pk_mul_f32 v[74:75], v[76:77], v[74:75]
	v_exp_f32_e32 v63, v63
	v_cvt_pk_bf16_f32 v81, v74, v75
	v_lshl_add_u64 v[74:75], s[12:13], 0, v[86:87]
	v_lshl_add_u64 v[86:87], v[74:75], 0, v[146:147]
	global_store_dwordx4 v[86:87], v[78:81], off
	v_mul_f32_e32 v64, 0xbfb8aa3b, v64
	v_mul_f32_e32 v65, 0xbfb8aa3b, v65
	v_add_u32_e32 v78, 0x80, v148
	v_ashrrev_i32_e32 v79, 31, v78
	v_lshlrev_b64 v[74:75], 12, v[78:79]
	v_lshl_add_u64 v[74:75], s[8:9], 0, v[74:75]
	v_lshl_add_u64 v[80:81], v[74:75], 0, v[146:147]
	global_load_dwordx4 v[74:77], v[80:81], off
	s_waitcnt vmcnt(2)
	v_lshlrev_b32_e32 v88, 16, v82
	v_and_b32_e32 v89, 0xffff0000, v82
	v_lshlrev_b32_e32 v82, 16, v83
	v_and_b32_e32 v83, 0xffff0000, v83
	v_pk_mul_f32 v[70:71], v[70:71], v[88:89]
	v_pk_mul_f32 v[72:73], v[72:73], v[82:83]
	v_cvt_pk_bf16_f32 v70, v70, v71
	v_cvt_pk_bf16_f32 v71, v72, v73
	v_lshlrev_b32_e32 v72, 16, v84
	v_and_b32_e32 v73, 0xffff0000, v84
	v_pk_mul_f32 v[66:67], v[66:67], v[72:73]
	v_exp_f32_e32 v64, v64
	v_cvt_pk_bf16_f32 v72, v66, v67
	v_lshlrev_b32_e32 v66, 16, v85
	v_and_b32_e32 v67, 0xffff0000, v85
	v_pk_mul_f32 v[66:67], v[68:69], v[66:67]
	v_exp_f32_e32 v65, v65
	v_cvt_pk_bf16_f32 v73, v66, v67
	global_store_dwordx4 v[86:87], v[70:73], off offset:256
	global_load_dwordx4 v[66:69], v[80:81], off offset:256
	v_mul_f32_e32 v58, 0xbfb8aa3b, v58
	v_mul_f32_e32 v59, 0xbfb8aa3b, v59
	v_exp_f32_e32 v58, v58
	v_exp_f32_e32 v59, v59
	v_add_f32_e32 v62, 1.0, v62
	v_add_f32_e32 v63, 1.0, v63
	v_mul_f32_e32 v60, 0xbfb8aa3b, v60
	v_mul_f32_e32 v61, 0xbfb8aa3b, v61
	v_rcp_f32_e32 v62, v62
	v_rcp_f32_e32 v63, v63
	v_add_f32_e32 v64, 1.0, v64
	v_add_f32_e32 v65, 1.0, v65
	v_exp_f32_e32 v60, v60
	v_exp_f32_e32 v61, v61
	v_rcp_f32_e32 v64, v64
	v_rcp_f32_e32 v65, v65
	v_add_f32_e32 v58, 1.0, v58
	v_add_f32_e32 v59, 1.0, v59
	v_rcp_f32_e32 v58, v58
	v_rcp_f32_e32 v59, v59
	v_add_f32_e32 v60, 1.0, v60
	v_add_f32_e32 v61, 1.0, v61
	v_rcp_f32_e32 v60, v60
	v_rcp_f32_e32 v61, v61
	v_lshlrev_b64 v[70:71], 13, v[78:79]
	v_mul_f32_e32 v54, 0xbfb8aa3b, v54
	v_mul_f32_e32 v55, 0xbfb8aa3b, v55
	v_mul_f32_e32 v56, 0xbfb8aa3b, v56
	v_mul_f32_e32 v57, 0xbfb8aa3b, v57
	v_exp_f32_e32 v54, v54
	v_exp_f32_e32 v55, v55
	v_exp_f32_e32 v56, v56
	v_exp_f32_e32 v57, v57
	v_mul_f32_e32 v50, 0xbfb8aa3b, v50
	v_mul_f32_e32 v51, 0xbfb8aa3b, v51
	v_exp_f32_e32 v50, v50
	v_exp_f32_e32 v51, v51
	v_mul_f32_e32 v52, 0xbfb8aa3b, v52
	v_mul_f32_e32 v53, 0xbfb8aa3b, v53
	v_add_f32_e32 v54, 1.0, v54
	v_add_f32_e32 v55, 1.0, v55
	v_add_f32_e32 v56, 1.0, v56
	v_add_f32_e32 v57, 1.0, v57
	v_exp_f32_e32 v52, v52
	v_exp_f32_e32 v53, v53
	v_rcp_f32_e32 v54, v54
	v_rcp_f32_e32 v55, v55
	v_rcp_f32_e32 v56, v56
	v_rcp_f32_e32 v57, v57
	v_add_f32_e32 v50, 1.0, v50
	v_add_f32_e32 v51, 1.0, v51
	v_rcp_f32_e32 v50, v50
	v_rcp_f32_e32 v51, v51
	v_add_f32_e32 v52, 1.0, v52
	v_add_f32_e32 v53, 1.0, v53
	v_rcp_f32_e32 v52, v52
	v_rcp_f32_e32 v53, v53
	v_mul_f32_e32 v46, 0xbfb8aa3b, v46
	v_mul_f32_e32 v47, 0xbfb8aa3b, v47
	s_waitcnt vmcnt(2)
	v_lshlrev_b32_e32 v72, 16, v74
	v_and_b32_e32 v73, 0xffff0000, v74
	v_pk_mul_f32 v[62:63], v[62:63], v[72:73]
	v_lshlrev_b32_e32 v72, 16, v75
	v_and_b32_e32 v73, 0xffff0000, v75
	v_pk_mul_f32 v[64:65], v[64:65], v[72:73]
	v_cvt_pk_bf16_f32 v62, v62, v63
	v_cvt_pk_bf16_f32 v63, v64, v65
	v_lshlrev_b32_e32 v64, 16, v76
	v_and_b32_e32 v65, 0xffff0000, v76
	v_pk_mul_f32 v[58:59], v[58:59], v[64:65]
	v_exp_f32_e32 v46, v46
	v_cvt_pk_bf16_f32 v64, v58, v59
	v_lshlrev_b32_e32 v58, 16, v77
	v_and_b32_e32 v59, 0xffff0000, v77
	v_pk_mul_f32 v[58:59], v[60:61], v[58:59]
	v_exp_f32_e32 v47, v47
	v_cvt_pk_bf16_f32 v65, v58, v59
	v_lshl_add_u64 v[58:59], s[12:13], 0, v[70:71]
	v_lshl_add_u64 v[70:71], v[58:59], 0, v[146:147]
	global_store_dwordx4 v[70:71], v[62:65], off
	s_waitcnt vmcnt(1)
	v_lshlrev_b32_e32 v72, 16, v66
	v_and_b32_e32 v73, 0xffff0000, v66
	v_add_u32_e32 v62, 0x90, v148
	v_ashrrev_i32_e32 v63, 31, v62
	v_lshlrev_b64 v[58:59], 12, v[62:63]
	v_lshl_add_u64 v[58:59], s[8:9], 0, v[58:59]
	v_lshl_add_u64 v[64:65], v[58:59], 0, v[146:147]
	global_load_dwordx4 v[58:61], v[64:65], off
	v_lshlrev_b32_e32 v66, 16, v67
	v_and_b32_e32 v67, 0xffff0000, v67
	v_pk_mul_f32 v[54:55], v[54:55], v[72:73]
	v_pk_mul_f32 v[56:57], v[56:57], v[66:67]
	v_cvt_pk_bf16_f32 v54, v54, v55
	v_cvt_pk_bf16_f32 v55, v56, v57
	v_lshlrev_b32_e32 v56, 16, v68
	v_and_b32_e32 v57, 0xffff0000, v68
	v_pk_mul_f32 v[50:51], v[50:51], v[56:57]
	v_mul_f32_e32 v48, 0xbfb8aa3b, v48
	v_cvt_pk_bf16_f32 v56, v50, v51
	v_lshlrev_b32_e32 v50, 16, v69
	v_and_b32_e32 v51, 0xffff0000, v69
	v_pk_mul_f32 v[50:51], v[52:53], v[50:51]
	v_mul_f32_e32 v49, 0xbfb8aa3b, v49
	v_cvt_pk_bf16_f32 v57, v50, v51
	global_store_dwordx4 v[70:71], v[54:57], off offset:256
	global_load_dwordx4 v[50:53], v[64:65], off offset:256
	v_exp_f32_e32 v48, v48
	v_exp_f32_e32 v49, v49
	v_mul_f32_e32 v42, 0xbfb8aa3b, v42
	v_mul_f32_e32 v43, 0xbfb8aa3b, v43
	v_exp_f32_e32 v42, v42
	v_exp_f32_e32 v43, v43
	v_add_f32_e32 v46, 1.0, v46
	v_add_f32_e32 v47, 1.0, v47
	v_mul_f32_e32 v44, 0xbfb8aa3b, v44
	v_mul_f32_e32 v45, 0xbfb8aa3b, v45
	v_rcp_f32_e32 v46, v46
	v_rcp_f32_e32 v47, v47
	v_add_f32_e32 v48, 1.0, v48
	v_add_f32_e32 v49, 1.0, v49
	v_exp_f32_e32 v44, v44
	v_exp_f32_e32 v45, v45
	v_rcp_f32_e32 v48, v48
	v_rcp_f32_e32 v49, v49
	v_add_f32_e32 v42, 1.0, v42
	v_add_f32_e32 v43, 1.0, v43
	v_rcp_f32_e32 v42, v42
	v_rcp_f32_e32 v43, v43
	v_add_f32_e32 v44, 1.0, v44
	v_add_f32_e32 v45, 1.0, v45
	v_rcp_f32_e32 v44, v44
	v_rcp_f32_e32 v45, v45
	v_lshlrev_b64 v[54:55], 13, v[62:63]
	v_mul_f32_e32 v38, 0xbfb8aa3b, v38
	v_mul_f32_e32 v39, 0xbfb8aa3b, v39
	v_mul_f32_e32 v40, 0xbfb8aa3b, v40
	v_mul_f32_e32 v41, 0xbfb8aa3b, v41
	v_exp_f32_e32 v38, v38
	v_exp_f32_e32 v39, v39
	v_exp_f32_e32 v40, v40
	v_exp_f32_e32 v41, v41
	v_mul_f32_e32 v34, 0xbfb8aa3b, v34
	v_mul_f32_e32 v35, 0xbfb8aa3b, v35
	v_exp_f32_e32 v34, v34
	v_exp_f32_e32 v35, v35
	v_mul_f32_e32 v36, 0xbfb8aa3b, v36
	v_mul_f32_e32 v37, 0xbfb8aa3b, v37
	v_add_f32_e32 v38, 1.0, v38
	v_add_f32_e32 v39, 1.0, v39
	v_add_f32_e32 v40, 1.0, v40
	v_add_f32_e32 v41, 1.0, v41
	v_exp_f32_e32 v36, v36
	v_exp_f32_e32 v37, v37
	v_rcp_f32_e32 v38, v38
	v_rcp_f32_e32 v39, v39
	v_rcp_f32_e32 v40, v40
	v_rcp_f32_e32 v41, v41
	v_add_f32_e32 v34, 1.0, v34
	v_add_f32_e32 v35, 1.0, v35
	v_rcp_f32_e32 v34, v34
	v_rcp_f32_e32 v35, v35
	v_add_f32_e32 v36, 1.0, v36
	v_add_f32_e32 v37, 1.0, v37
	v_rcp_f32_e32 v36, v36
	v_rcp_f32_e32 v37, v37
	v_mul_f32_e32 v30, 0xbfb8aa3b, v30
	v_mul_f32_e32 v31, 0xbfb8aa3b, v31
	s_waitcnt vmcnt(2)
	v_lshlrev_b32_e32 v56, 16, v58
	v_and_b32_e32 v57, 0xffff0000, v58
	v_pk_mul_f32 v[46:47], v[46:47], v[56:57]
	v_lshlrev_b32_e32 v56, 16, v59
	v_and_b32_e32 v57, 0xffff0000, v59
	v_pk_mul_f32 v[48:49], v[48:49], v[56:57]
	v_cvt_pk_bf16_f32 v46, v46, v47
	v_cvt_pk_bf16_f32 v47, v48, v49
	v_lshlrev_b32_e32 v48, 16, v60
	v_and_b32_e32 v49, 0xffff0000, v60
	v_pk_mul_f32 v[42:43], v[42:43], v[48:49]
	v_exp_f32_e32 v30, v30
	v_cvt_pk_bf16_f32 v48, v42, v43
	v_lshlrev_b32_e32 v42, 16, v61
	v_and_b32_e32 v43, 0xffff0000, v61
	v_pk_mul_f32 v[42:43], v[44:45], v[42:43]
	v_exp_f32_e32 v31, v31
	v_cvt_pk_bf16_f32 v49, v42, v43
	v_lshl_add_u64 v[42:43], s[12:13], 0, v[54:55]
	v_lshl_add_u64 v[54:55], v[42:43], 0, v[146:147]
	global_store_dwordx4 v[54:55], v[46:49], off
	s_waitcnt vmcnt(1)
	v_lshlrev_b32_e32 v56, 16, v50
	v_and_b32_e32 v57, 0xffff0000, v50
	v_add_u32_e32 v46, 0xa0, v148
	v_ashrrev_i32_e32 v47, 31, v46
	v_lshlrev_b64 v[42:43], 12, v[46:47]
	v_lshl_add_u64 v[42:43], s[8:9], 0, v[42:43]
	v_lshl_add_u64 v[48:49], v[42:43], 0, v[146:147]
	global_load_dwordx4 v[42:45], v[48:49], off
	v_lshlrev_b32_e32 v50, 16, v51
	v_and_b32_e32 v51, 0xffff0000, v51
	v_pk_mul_f32 v[38:39], v[38:39], v[56:57]
	v_pk_mul_f32 v[40:41], v[40:41], v[50:51]
	v_cvt_pk_bf16_f32 v38, v38, v39
	v_cvt_pk_bf16_f32 v39, v40, v41
	v_lshlrev_b32_e32 v40, 16, v52
	v_and_b32_e32 v41, 0xffff0000, v52
	v_pk_mul_f32 v[34:35], v[34:35], v[40:41]
	v_mul_f32_e32 v32, 0xbfb8aa3b, v32
	v_cvt_pk_bf16_f32 v40, v34, v35
	v_lshlrev_b32_e32 v34, 16, v53
	v_and_b32_e32 v35, 0xffff0000, v53
	v_pk_mul_f32 v[34:35], v[36:37], v[34:35]
	v_mul_f32_e32 v33, 0xbfb8aa3b, v33
	v_cvt_pk_bf16_f32 v41, v34, v35
	global_store_dwordx4 v[54:55], v[38:41], off offset:256
	global_load_dwordx4 v[34:37], v[48:49], off offset:256
	v_exp_f32_e32 v32, v32
	v_exp_f32_e32 v33, v33
	v_mul_f32_e32 v26, 0xbfb8aa3b, v26
	v_mul_f32_e32 v27, 0xbfb8aa3b, v27
	v_exp_f32_e32 v26, v26
	v_exp_f32_e32 v27, v27
	v_add_f32_e32 v30, 1.0, v30
	v_add_f32_e32 v31, 1.0, v31
	v_mul_f32_e32 v28, 0xbfb8aa3b, v28
	v_mul_f32_e32 v29, 0xbfb8aa3b, v29
	v_rcp_f32_e32 v30, v30
	v_rcp_f32_e32 v31, v31
	v_add_f32_e32 v32, 1.0, v32
	v_add_f32_e32 v33, 1.0, v33
	v_exp_f32_e32 v28, v28
	v_exp_f32_e32 v29, v29
	v_rcp_f32_e32 v32, v32
	v_rcp_f32_e32 v33, v33
	v_add_f32_e32 v26, 1.0, v26
	v_add_f32_e32 v27, 1.0, v27
	v_rcp_f32_e32 v26, v26
	v_rcp_f32_e32 v27, v27
	v_add_f32_e32 v28, 1.0, v28
	v_add_f32_e32 v29, 1.0, v29
	v_rcp_f32_e32 v28, v28
	v_rcp_f32_e32 v29, v29
	v_mul_f32_e32 v22, 0xbfb8aa3b, v22
	v_mul_f32_e32 v23, 0xbfb8aa3b, v23
	v_mul_f32_e32 v24, 0xbfb8aa3b, v24
	v_mul_f32_e32 v25, 0xbfb8aa3b, v25
	v_exp_f32_e32 v22, v22
	v_exp_f32_e32 v23, v23
	v_exp_f32_e32 v24, v24
	v_exp_f32_e32 v25, v25
	v_mul_f32_e32 v18, 0xbfb8aa3b, v18
	v_mul_f32_e32 v19, 0xbfb8aa3b, v19
	v_lshlrev_b64 v[38:39], 13, v[46:47]
	v_exp_f32_e32 v18, v18
	v_exp_f32_e32 v19, v19
	v_mul_f32_e32 v20, 0xbfb8aa3b, v20
	v_mul_f32_e32 v21, 0xbfb8aa3b, v21
	v_add_f32_e32 v22, 1.0, v22
	v_add_f32_e32 v23, 1.0, v23
	v_add_f32_e32 v24, 1.0, v24
	v_add_f32_e32 v25, 1.0, v25
	v_exp_f32_e32 v20, v20
	v_exp_f32_e32 v21, v21
	v_rcp_f32_e32 v22, v22
	v_rcp_f32_e32 v23, v23
	v_rcp_f32_e32 v24, v24
	v_rcp_f32_e32 v25, v25
	v_add_f32_e32 v18, 1.0, v18
	v_add_f32_e32 v19, 1.0, v19
	v_rcp_f32_e32 v18, v18
	v_rcp_f32_e32 v19, v19
	v_add_f32_e32 v20, 1.0, v20
	v_add_f32_e32 v21, 1.0, v21
	v_rcp_f32_e32 v20, v20
	v_rcp_f32_e32 v21, v21
	v_mul_f32_e32 v14, 0xbfb8aa3b, v14
	v_mul_f32_e32 v15, 0xbfb8aa3b, v15
	s_waitcnt vmcnt(2)
	v_lshlrev_b32_e32 v40, 16, v42
	v_and_b32_e32 v41, 0xffff0000, v42
	v_pk_mul_f32 v[30:31], v[30:31], v[40:41]
	v_lshlrev_b32_e32 v40, 16, v43
	v_and_b32_e32 v41, 0xffff0000, v43
	v_pk_mul_f32 v[32:33], v[32:33], v[40:41]
	v_cvt_pk_bf16_f32 v30, v30, v31
	v_cvt_pk_bf16_f32 v31, v32, v33
	v_lshlrev_b32_e32 v32, 16, v44
	v_and_b32_e32 v33, 0xffff0000, v44
	v_pk_mul_f32 v[26:27], v[26:27], v[32:33]
	v_exp_f32_e32 v14, v14
	v_cvt_pk_bf16_f32 v32, v26, v27
	v_lshlrev_b32_e32 v26, 16, v45
	v_and_b32_e32 v27, 0xffff0000, v45
	v_pk_mul_f32 v[26:27], v[28:29], v[26:27]
	v_exp_f32_e32 v15, v15
	v_cvt_pk_bf16_f32 v33, v26, v27
	v_lshl_add_u64 v[26:27], s[12:13], 0, v[38:39]
	v_lshl_add_u64 v[38:39], v[26:27], 0, v[146:147]
	global_store_dwordx4 v[38:39], v[30:33], off
	s_waitcnt vmcnt(1)
	v_lshlrev_b32_e32 v40, 16, v34
	v_and_b32_e32 v41, 0xffff0000, v34
	v_add_u32_e32 v30, 0xb0, v148
	v_ashrrev_i32_e32 v31, 31, v30
	v_lshlrev_b64 v[26:27], 12, v[30:31]
	v_lshl_add_u64 v[26:27], s[8:9], 0, v[26:27]
	v_lshlrev_b32_e32 v34, 16, v35
	v_and_b32_e32 v35, 0xffff0000, v35
	v_lshl_add_u64 v[32:33], v[26:27], 0, v[146:147]
	v_pk_mul_f32 v[22:23], v[22:23], v[40:41]
	v_pk_mul_f32 v[24:25], v[24:25], v[34:35]
	global_load_dwordx4 v[26:29], v[32:33], off
	v_cvt_pk_bf16_f32 v22, v22, v23
	v_cvt_pk_bf16_f32 v23, v24, v25
	v_lshlrev_b32_e32 v24, 16, v36
	v_and_b32_e32 v25, 0xffff0000, v36
	v_pk_mul_f32 v[18:19], v[18:19], v[24:25]
	v_mul_f32_e32 v16, 0xbfb8aa3b, v16
	v_cvt_pk_bf16_f32 v24, v18, v19
	v_lshlrev_b32_e32 v18, 16, v37
	v_and_b32_e32 v19, 0xffff0000, v37
	v_pk_mul_f32 v[18:19], v[20:21], v[18:19]
	v_mul_f32_e32 v17, 0xbfb8aa3b, v17
	v_cvt_pk_bf16_f32 v25, v18, v19
	global_store_dwordx4 v[38:39], v[22:25], off offset:256
	global_load_dwordx4 v[18:21], v[32:33], off offset:256
	v_exp_f32_e32 v16, v16
	v_exp_f32_e32 v17, v17
	v_mul_f32_e32 v10, 0xbfb8aa3b, v10
	v_mul_f32_e32 v11, 0xbfb8aa3b, v11
	v_exp_f32_e32 v10, v10
	v_exp_f32_e32 v11, v11
	v_add_f32_e32 v14, 1.0, v14
	v_add_f32_e32 v15, 1.0, v15
	v_mul_f32_e32 v12, 0xbfb8aa3b, v12
	v_mul_f32_e32 v13, 0xbfb8aa3b, v13
	v_rcp_f32_e32 v14, v14
	v_rcp_f32_e32 v15, v15
	v_add_f32_e32 v16, 1.0, v16
	v_add_f32_e32 v17, 1.0, v17
	v_exp_f32_e32 v12, v12
	v_exp_f32_e32 v13, v13
	v_mul_f32_e32 v6, 0xbfb8aa3b, v6
	v_mul_f32_e32 v7, 0xbfb8aa3b, v7
	v_rcp_f32_e32 v16, v16
	v_rcp_f32_e32 v17, v17
	v_exp_f32_e32 v6, v6
	v_exp_f32_e32 v7, v7
	v_mul_f32_e32 v8, 0xbfb8aa3b, v8
	v_mul_f32_e32 v9, 0xbfb8aa3b, v9
	v_add_f32_e32 v10, 1.0, v10
	v_add_f32_e32 v11, 1.0, v11
	v_exp_f32_e32 v8, v8
	v_exp_f32_e32 v9, v9
	v_rcp_f32_e32 v10, v10
	v_rcp_f32_e32 v11, v11
	v_mul_f32_e32 v2, 0xbfb8aa3b, v2
	v_mul_f32_e32 v3, 0xbfb8aa3b, v3
	v_add_f32_e32 v12, 1.0, v12
	v_add_f32_e32 v13, 1.0, v13
	v_exp_f32_e32 v2, v2
	v_exp_f32_e32 v3, v3
	v_rcp_f32_e32 v12, v12
	v_rcp_f32_e32 v13, v13
	v_add_f32_e32 v6, 1.0, v6
	v_add_f32_e32 v7, 1.0, v7
	v_mul_f32_e32 v4, 0xbfb8aa3b, v4
	v_mul_f32_e32 v5, 0xbfb8aa3b, v5
	v_rcp_f32_e32 v6, v6
	v_rcp_f32_e32 v7, v7
	v_add_f32_e32 v8, 1.0, v8
	v_add_f32_e32 v9, 1.0, v9
	v_exp_f32_e32 v4, v4
	v_exp_f32_e32 v5, v5
	v_rcp_f32_e32 v8, v8
	v_rcp_f32_e32 v9, v9
	v_add_f32_e32 v2, 1.0, v2
	v_add_f32_e32 v3, 1.0, v3
	v_rcp_f32_e32 v2, v2
	v_rcp_f32_e32 v3, v3
	v_add_f32_e32 v4, 1.0, v4
	v_add_f32_e32 v5, 1.0, v5
	v_rcp_f32_e32 v4, v4
	v_rcp_f32_e32 v5, v5
	v_lshlrev_b64 v[22:23], 13, v[30:31]
	s_andn2_b64 vcc, exec, s[6:7]
	s_mov_b64 s[6:7], -1
	s_waitcnt vmcnt(2)
	v_lshlrev_b32_e32 v24, 16, v26
	v_and_b32_e32 v25, 0xffff0000, v26
	v_pk_mul_f32 v[14:15], v[14:15], v[24:25]
	v_lshlrev_b32_e32 v24, 16, v27
	v_and_b32_e32 v25, 0xffff0000, v27
	v_pk_mul_f32 v[16:17], v[16:17], v[24:25]
	v_cvt_pk_bf16_f32 v14, v14, v15
	v_cvt_pk_bf16_f32 v15, v16, v17
	v_lshlrev_b32_e32 v16, 16, v28
	v_and_b32_e32 v17, 0xffff0000, v28
	v_pk_mul_f32 v[10:11], v[10:11], v[16:17]
	s_nop 0
	v_cvt_pk_bf16_f32 v16, v10, v11
	v_lshlrev_b32_e32 v10, 16, v29
	v_and_b32_e32 v11, 0xffff0000, v29
	v_pk_mul_f32 v[10:11], v[12:13], v[10:11]
	s_waitcnt vmcnt(0)
	v_lshlrev_b32_e32 v12, 16, v18
	v_and_b32_e32 v13, 0xffff0000, v18
	v_pk_mul_f32 v[6:7], v[6:7], v[12:13]
	v_lshlrev_b32_e32 v12, 16, v19
	v_and_b32_e32 v13, 0xffff0000, v19
	v_pk_mul_f32 v[8:9], v[8:9], v[12:13]
	v_cvt_pk_bf16_f32 v6, v6, v7
	v_cvt_pk_bf16_f32 v7, v8, v9
	v_lshlrev_b32_e32 v8, 16, v20
	v_and_b32_e32 v9, 0xffff0000, v20
	v_pk_mul_f32 v[2:3], v[2:3], v[8:9]
	v_cvt_pk_bf16_f32 v17, v10, v11
	v_cvt_pk_bf16_f32 v8, v2, v3
	v_lshlrev_b32_e32 v2, 16, v21
	v_and_b32_e32 v3, 0xffff0000, v21
	v_lshl_add_u64 v[10:11], s[12:13], 0, v[22:23]
	v_pk_mul_f32 v[2:3], v[4:5], v[2:3]
	v_lshl_add_u64 v[10:11], v[10:11], 0, v[146:147]
	v_cvt_pk_bf16_f32 v9, v2, v3
	global_store_dwordx4 v[10:11], v[14:17], off
	global_store_dwordx4 v[10:11], v[6:9], off offset:256
	s_cbranch_vccnz .LBB0_963
	s_andn2_b64 vcc, exec, s[10:11]
	s_cbranch_vccnz .LBB0_962
	s_branch .LBB0_962

.LBB0_1040:
	s_add_u32 s16, s38, 0x31800000
	s_addc_u32 s17, s39, 0
	s_add_u32 s18, s38, 0x39c00000
	s_addc_u32 s19, s39, 0
	s_add_u32 s69, s38, 0x50600000
	s_addc_u32 s70, s39, 0
	s_lshl_b32 s6, s9, 5
	s_mov_b64 s[20:21], 0x80
	s_and_b32 s9, s6, 0x60
	s_add_i32 m0, s59, 0x18000
	v_lshl_add_u64 v[8:9], v[8:9], 0, s[20:21]
	s_lshl_b32 s23, s8, 13
	s_lshl_b32 s24, s9, 7
	s_ashr_i32 s71, s2, 31
	s_waitcnt vmcnt(2)
	s_barrier
	global_load_lds_dwordx4 v[8:9], off
	v_lshl_add_u64 v[4:5], v[4:5], 0, s[20:21]
	s_add_i32 m0, s59, 0x1a000
	s_add_i32 s72, s59, 0x8000
	s_add_i32 s73, s59, 0xa000
	global_load_lds_dwordx4 v[4:5], off
	v_lshl_add_u64 v[2:3], v[2:3], 0, s[20:21]
	s_mov_b32 m0, s72
	s_add_u32 s6, s48, 0x100080
	global_load_lds_dwordx4 v[2:3], off
	v_lshl_add_u64 v[2:3], v[6:7], 0, s[20:21]
	s_mov_b32 m0, s73
	s_addc_u32 s7, s49, 0
	global_load_lds_dwordx4 v[2:3], off
	s_add_i32 m0, s59, 0x1c000
	v_lshl_add_u64 v[2:3], s[6:7], 0, v[132:133]
	global_load_lds_dwordx4 v[2:3], off
	v_lshl_add_u64 v[2:3], s[6:7], 0, v[136:137]
	s_add_i32 m0, s59, 0x1e000
	v_lshlrev_b32_e32 v4, 2, v0
	global_load_lds_dwordx4 v[2:3], off
	v_and_b32_e32 v2, 15, v0
	v_lshlrev_b32_e32 v3, 1, v13
	v_lshlrev_b32_e32 v5, 6, v0
	s_movk_i32 s6, 0x3c0
	v_lshl_or_b32 v1, s8, 6, v2
	v_lshl_or_b32 v2, v2, 6, v3
	v_and_b32_e32 v4, 32, v4
	v_and_or_b32 v3, v5, s6, v3
	v_bitop3_b32 v156, s24, v3, v4 bitop3:0xf6
	v_lshlrev_b32_e32 v3, 10, v0
	v_bitop3_b32 v2, v2, s23, v4 bitop3:0xde
	v_and_b32_e32 v3, 0x60000, v3
	v_lshlrev_b32_e32 v4, 13, v12
	v_or3_b32 v3, v10, v3, v4
	v_add_u32_e32 v138, v3, v11
	v_lshlrev_b32_e32 v3, 6, v14
	s_waitcnt vmcnt(6)
	s_cmpk_lt_u32 s22, 0x100
	v_and_b32_e32 v3, 0xe0000, v3
	s_cselect_b64 s[22:23], -1, 0
	v_or3_b32 v3, v10, v3, v4
	s_add_i32 s75, 0, 0x10000
	s_add_i32 s76, 0, 0x14000
	s_brev_b32 s24, 31
	s_mov_b32 s26, 0xf8040000
	s_mov_b32 s28, 0xf8080000
	s_mov_b32 s30, 0xf80c0000
	s_ashr_i32 s74, s44, 31
	v_or_b32_e32 v157, s9, v13
	v_mov_b32_e32 v139, v133
	v_add_u32_e32 v140, v3, v11
	v_mov_b32_e32 v141, v133
	v_mov_b64_e32 v[142:143], 0x300
	v_mov_b64_e32 v[144:145], 0x2ff
	v_add_u32_e32 v158, s75, v156
	v_add_u32_e32 v159, s76, v156
	v_add_u32_e32 v160, 0, v2
	s_mov_b32 s25, -1
	s_brev_b32 s77, 31
	s_mov_b32 s27, -1
	s_mov_b32 s78, 0xf8040000
	s_mov_b32 s29, -1
	s_mov_b32 s79, 0xf8080000
	s_mov_b32 s31, -1
	s_mov_b32 s34, 0x3fb504f3
	s_mov_b64 s[40:41], 0x120000
	s_mov_b64 s[42:43], 0x140000
	s_mov_b64 s[46:47], 0x160000
	v_mov_b64_e32 v[146:147], 0x1ff
	v_mov_b64_e32 v[148:149], 0x200
	s_mov_b32 s80, s11
	s_branch .LBB0_1043

.LBB0_1057:
	s_and_b64 vcc, exec, s[22:23]
	s_cbranch_vccz .Lkt_T_7
.Lkt_L_7:
	ds_read_b128 v[150:153], v158
	ds_read_b128 v[162:165], v158 offset:1024
	ds_read_b128 v[166:169], v158 offset:2048
	ds_read_b128 v[170:173], v158 offset:3072
	ds_read_b128 v[174:177], v159
	ds_read_b128 v[178:181], v159 offset:1024
	ds_read_b128 v[182:185], v159 offset:2048
	ds_read_b128 v[186:189], v159 offset:3072
	s_add_i32 s84, s48, 2
	s_add_u32 s49, s62, 0xfff00080
	s_addc_u32 s64, s63, -1
	s_cmp_eq_u32 s51, s48
	s_cselect_b32 s48, s56, s53
	s_cselect_b32 s65, s9, s64
	s_cselect_b32 s64, s8, s49
	s_cselect_b32 s49, s57, s55
	v_lshl_add_u64 v[154:155], s[62:63], 0, v[138:139]
	s_add_i32 m0, s59, 0xc000
	ds_read_b128 v[190:193], v160
	ds_read_b128 v[196:199], v160 offset:1024
	ds_read_b128 v[200:203], v160 offset:2048
	ds_read_b128 v[206:209], v160 offset:3072
	ds_read_b128 v[210:213], v160 offset:4096
	ds_read_b128 v[214:217], v160 offset:5120
	ds_read_b128 v[218:221], v160 offset:6144
	ds_read_b128 v[222:225], v160 offset:7168
	global_load_lds_dwordx4 v[154:155], off
	v_lshl_add_u64 v[154:155], s[62:63], 0, v[140:141]
	s_add_i32 m0, s59, 0xe000
	s_nop 0
	global_load_lds_dwordx4 v[154:155], off
	s_waitcnt lgkmcnt(0)
	s_setprio 1
	v_mfma_f32_16x16x32_bf16 v[126:129], v[150:153], v[190:193], v[126:129]
	v_mfma_f32_16x16x32_bf16 v[122:125], v[166:169], v[190:193], v[122:125]
	v_mfma_f32_16x16x32_bf16 v[110:113], v[150:153], v[200:203], v[110:113]
	v_mfma_f32_16x16x32_bf16 v[106:109], v[166:169], v[200:203], v[106:109]
	v_mfma_f32_16x16x32_bf16 v[94:97], v[150:153], v[210:213], v[94:97]
	v_mfma_f32_16x16x32_bf16 v[90:93], v[166:169], v[210:213], v[90:93]
	v_mfma_f32_16x16x32_bf16 v[78:81], v[150:153], v[218:221], v[78:81]
	v_mfma_f32_16x16x32_bf16 v[74:77], v[166:169], v[218:221], v[74:77]
	v_mfma_f32_16x16x32_bf16 v[126:129], v[162:165], v[196:199], v[126:129]
	v_mfma_f32_16x16x32_bf16 v[122:125], v[170:173], v[196:199], v[122:125]
	v_mfma_f32_16x16x32_bf16 v[110:113], v[162:165], v[206:209], v[110:113]
	v_mfma_f32_16x16x32_bf16 v[106:109], v[170:173], v[206:209], v[106:109]
	v_mfma_f32_16x16x32_bf16 v[94:97], v[162:165], v[214:217], v[94:97]
	v_mfma_f32_16x16x32_bf16 v[90:93], v[170:173], v[214:217], v[90:93]
	v_mfma_f32_16x16x32_bf16 v[78:81], v[162:165], v[222:225], v[78:81]
	v_mfma_f32_16x16x32_bf16 v[74:77], v[170:173], v[222:225], v[74:77]
	v_mfma_f32_16x16x32_bf16 v[118:121], v[174:177], v[190:193], v[118:121]
	v_mfma_f32_16x16x32_bf16 v[114:117], v[182:185], v[190:193], v[114:117]
	v_mfma_f32_16x16x32_bf16 v[102:105], v[174:177], v[200:203], v[102:105]
	v_mfma_f32_16x16x32_bf16 v[98:101], v[182:185], v[200:203], v[98:101]
	v_mfma_f32_16x16x32_bf16 v[86:89], v[174:177], v[210:213], v[86:89]
	v_mfma_f32_16x16x32_bf16 v[82:85], v[182:185], v[210:213], v[82:85]
	v_mfma_f32_16x16x32_bf16 v[70:73], v[174:177], v[218:221], v[70:73]
	v_mfma_f32_16x16x32_bf16 v[66:69], v[182:185], v[218:221], v[66:69]
	v_mfma_f32_16x16x32_bf16 v[118:121], v[178:181], v[196:199], v[118:121]
	v_mfma_f32_16x16x32_bf16 v[114:117], v[186:189], v[196:199], v[114:117]
	v_mfma_f32_16x16x32_bf16 v[102:105], v[178:181], v[206:209], v[102:105]
	v_mfma_f32_16x16x32_bf16 v[98:101], v[186:189], v[206:209], v[98:101]
	v_mfma_f32_16x16x32_bf16 v[86:89], v[178:181], v[214:217], v[86:89]
	v_mfma_f32_16x16x32_bf16 v[82:85], v[186:189], v[214:217], v[82:85]
	v_mfma_f32_16x16x32_bf16 v[70:73], v[178:181], v[222:225], v[70:73]
	v_mfma_f32_16x16x32_bf16 v[66:69], v[186:189], v[222:225], v[66:69]
	s_setprio 0
	s_waitcnt vmcnt(8)
	s_barrier
	s_add_i32 s85, s75, s66
	v_lshl_add_u64 v[154:155], s[48:49], 0, v[132:133]
	s_mov_b32 m0, s85
	ds_read_b128 v[190:193], v160 offset:16384
	ds_read_b128 v[196:199], v160 offset:17408
	ds_read_b128 v[200:203], v160 offset:18432
	ds_read_b128 v[206:209], v160 offset:19456
	ds_read_b128 v[210:213], v160 offset:20480
	ds_read_b128 v[214:217], v160 offset:21504
	ds_read_b128 v[218:221], v160 offset:22528
	ds_read_b128 v[222:225], v160 offset:23552
	global_load_lds_dwordx4 v[154:155], off
	s_add_i32 m0, s85, 0x2000
	s_add_u32 s86, s48, 0x100000
	v_lshl_add_u64 v[226:227], s[48:49], 0, v[136:137]
	s_addc_u32 s87, s49, 0
	s_add_i32 s85, s76, s66
	global_load_lds_dwordx4 v[226:227], off
	v_lshl_add_u64 v[228:229], s[86:87], 0, v[132:133]
	s_mov_b32 m0, s85
	v_lshl_add_u64 v[230:231], s[64:65], 0, v[134:135]
	global_load_lds_dwordx4 v[228:229], off
	v_lshl_add_u64 v[228:229], s[86:87], 0, v[136:137]
	s_add_i32 m0, s85, 0x2000
	s_nop 0
	global_load_lds_dwordx4 v[228:229], off
	v_lshl_add_u64 v[228:229], s[64:65], 0, v[130:131]
	s_mov_b32 m0, s59
	s_nop 0
	global_load_lds_dwordx4 v[228:229], off
	s_mov_b32 m0, s61
	s_nop 0
	global_load_lds_dwordx4 v[230:231], off
	s_waitcnt lgkmcnt(0)
	s_setprio 1
	v_mfma_f32_16x16x32_bf16 v[62:65], v[150:153], v[190:193], v[62:65]
	v_mfma_f32_16x16x32_bf16 v[58:61], v[166:169], v[190:193], v[58:61]
	v_mfma_f32_16x16x32_bf16 v[46:49], v[150:153], v[200:203], v[46:49]
	v_mfma_f32_16x16x32_bf16 v[42:45], v[166:169], v[200:203], v[42:45]
	v_mfma_f32_16x16x32_bf16 v[30:33], v[150:153], v[210:213], v[30:33]
	v_mfma_f32_16x16x32_bf16 v[26:29], v[166:169], v[210:213], v[26:29]
	v_mfma_f32_16x16x32_bf16 v[14:17], v[150:153], v[218:221], v[14:17]
	v_mfma_f32_16x16x32_bf16 v[10:13], v[166:169], v[218:221], v[10:13]
	v_mfma_f32_16x16x32_bf16 v[62:65], v[162:165], v[196:199], v[62:65]
	v_mfma_f32_16x16x32_bf16 v[58:61], v[170:173], v[196:199], v[58:61]
	v_mfma_f32_16x16x32_bf16 v[46:49], v[162:165], v[206:209], v[46:49]
	v_mfma_f32_16x16x32_bf16 v[42:45], v[170:173], v[206:209], v[42:45]
	v_mfma_f32_16x16x32_bf16 v[30:33], v[162:165], v[214:217], v[30:33]
	v_mfma_f32_16x16x32_bf16 v[26:29], v[170:173], v[214:217], v[26:29]
	v_mfma_f32_16x16x32_bf16 v[14:17], v[162:165], v[222:225], v[14:17]
	v_mfma_f32_16x16x32_bf16 v[10:13], v[170:173], v[222:225], v[10:13]
	v_mfma_f32_16x16x32_bf16 v[54:57], v[174:177], v[190:193], v[54:57]
	v_mfma_f32_16x16x32_bf16 v[50:53], v[182:185], v[190:193], v[50:53]
	v_mfma_f32_16x16x32_bf16 v[38:41], v[174:177], v[200:203], v[38:41]
	v_mfma_f32_16x16x32_bf16 v[34:37], v[182:185], v[200:203], v[34:37]
	v_mfma_f32_16x16x32_bf16 v[22:25], v[174:177], v[210:213], v[22:25]
	v_mfma_f32_16x16x32_bf16 v[18:21], v[182:185], v[210:213], v[18:21]
	v_mfma_f32_16x16x32_bf16 v[6:9], v[174:177], v[218:221], v[6:9]
	v_mfma_f32_16x16x32_bf16 v[2:5], v[182:185], v[218:221], v[2:5]
	v_mfma_f32_16x16x32_bf16 v[54:57], v[178:181], v[196:199], v[54:57]
	v_mfma_f32_16x16x32_bf16 v[50:53], v[186:189], v[196:199], v[50:53]
	v_mfma_f32_16x16x32_bf16 v[38:41], v[178:181], v[206:209], v[38:41]
	v_mfma_f32_16x16x32_bf16 v[34:37], v[186:189], v[206:209], v[34:37]
	v_mfma_f32_16x16x32_bf16 v[22:25], v[178:181], v[214:217], v[22:25]
	v_mfma_f32_16x16x32_bf16 v[18:21], v[186:189], v[214:217], v[18:21]
	v_mfma_f32_16x16x32_bf16 v[6:9], v[178:181], v[222:225], v[6:9]
	v_mfma_f32_16x16x32_bf16 v[2:5], v[186:189], v[222:225], v[2:5]
	s_setprio 0
	s_waitcnt vmcnt(8)
	s_barrier
	s_add_i32 s85, 0, 0x18000
	v_add_u32_e32 v161, s85, v156
	s_add_i32 s86, 0, 0x1c000
	ds_read_b128 v[150:153], v161
	ds_read_b128 v[162:165], v161 offset:1024
	ds_read_b128 v[166:169], v161 offset:2048
	ds_read_b128 v[170:173], v161 offset:3072
	v_add_u32_e32 v161, s86, v156
	ds_read_b128 v[174:177], v161
	ds_read_b128 v[178:181], v161 offset:1024
	ds_read_b128 v[182:185], v161 offset:2048
	ds_read_b128 v[186:189], v161 offset:3072
	s_add_u32 s64, s64, 0x100000
	s_addc_u32 s65, s65, 0
	s_mov_b32 m0, s67
	v_lshl_add_u64 v[232:233], s[64:65], 0, v[130:131]
	ds_read_b128 v[190:193], v160 offset:32768
	ds_read_b128 v[196:199], v160 offset:33792
	ds_read_b128 v[200:203], v160 offset:34816
	ds_read_b128 v[206:209], v160 offset:35840
	ds_read_b128 v[210:213], v160 offset:36864
	ds_read_b128 v[214:217], v160 offset:37888
	ds_read_b128 v[218:221], v160 offset:38912
	ds_read_b128 v[222:225], v160 offset:39936
	global_load_lds_dwordx4 v[232:233], off
	v_lshl_add_u64 v[232:233], s[64:65], 0, v[134:135]
	s_mov_b32 m0, s68
	s_nop 0
	global_load_lds_dwordx4 v[232:233], off
	s_waitcnt lgkmcnt(0)
	s_setprio 1
	v_mfma_f32_16x16x32_bf16 v[126:129], v[150:153], v[190:193], v[126:129]
	v_mfma_f32_16x16x32_bf16 v[122:125], v[166:169], v[190:193], v[122:125]
	v_mfma_f32_16x16x32_bf16 v[110:113], v[150:153], v[200:203], v[110:113]
	v_mfma_f32_16x16x32_bf16 v[106:109], v[166:169], v[200:203], v[106:109]
	v_mfma_f32_16x16x32_bf16 v[94:97], v[150:153], v[210:213], v[94:97]
	v_mfma_f32_16x16x32_bf16 v[90:93], v[166:169], v[210:213], v[90:93]
	v_mfma_f32_16x16x32_bf16 v[78:81], v[150:153], v[218:221], v[78:81]
	v_mfma_f32_16x16x32_bf16 v[74:77], v[166:169], v[218:221], v[74:77]
	v_mfma_f32_16x16x32_bf16 v[126:129], v[162:165], v[196:199], v[126:129]
	v_mfma_f32_16x16x32_bf16 v[122:125], v[170:173], v[196:199], v[122:125]
	v_mfma_f32_16x16x32_bf16 v[110:113], v[162:165], v[206:209], v[110:113]
	v_mfma_f32_16x16x32_bf16 v[106:109], v[170:173], v[206:209], v[106:109]
	v_mfma_f32_16x16x32_bf16 v[94:97], v[162:165], v[214:217], v[94:97]
	v_mfma_f32_16x16x32_bf16 v[90:93], v[170:173], v[214:217], v[90:93]
	v_mfma_f32_16x16x32_bf16 v[78:81], v[162:165], v[222:225], v[78:81]
	v_mfma_f32_16x16x32_bf16 v[74:77], v[170:173], v[222:225], v[74:77]
	v_mfma_f32_16x16x32_bf16 v[118:121], v[174:177], v[190:193], v[118:121]
	v_mfma_f32_16x16x32_bf16 v[114:117], v[182:185], v[190:193], v[114:117]
	v_mfma_f32_16x16x32_bf16 v[102:105], v[174:177], v[200:203], v[102:105]
	v_mfma_f32_16x16x32_bf16 v[98:101], v[182:185], v[200:203], v[98:101]
	v_mfma_f32_16x16x32_bf16 v[86:89], v[174:177], v[210:213], v[86:89]
	v_mfma_f32_16x16x32_bf16 v[82:85], v[182:185], v[210:213], v[82:85]
	v_mfma_f32_16x16x32_bf16 v[70:73], v[174:177], v[218:221], v[70:73]
	v_mfma_f32_16x16x32_bf16 v[66:69], v[182:185], v[218:221], v[66:69]
	v_mfma_f32_16x16x32_bf16 v[118:121], v[178:181], v[196:199], v[118:121]
	v_mfma_f32_16x16x32_bf16 v[114:117], v[186:189], v[196:199], v[114:117]
	v_mfma_f32_16x16x32_bf16 v[102:105], v[178:181], v[206:209], v[102:105]
	v_mfma_f32_16x16x32_bf16 v[98:101], v[186:189], v[206:209], v[98:101]
	v_mfma_f32_16x16x32_bf16 v[86:89], v[178:181], v[214:217], v[86:89]
	v_mfma_f32_16x16x32_bf16 v[82:85], v[186:189], v[214:217], v[82:85]
	v_mfma_f32_16x16x32_bf16 v[70:73], v[178:181], v[222:225], v[70:73]
	v_mfma_f32_16x16x32_bf16 v[66:69], v[186:189], v[222:225], v[66:69]
	s_setprio 0
	s_waitcnt vmcnt(8)
	s_barrier
	s_add_i32 s64, s85, s66
	v_lshl_add_u64 v[154:155], v[154:155], 0, s[20:21]
	s_mov_b32 m0, s64
	ds_read_b128 v[190:193], v160 offset:49152
	ds_read_b128 v[196:199], v160 offset:50176
	ds_read_b128 v[200:203], v160 offset:51200
	ds_read_b128 v[206:209], v160 offset:52224
	ds_read_b128 v[210:213], v160 offset:53248
	ds_read_b128 v[214:217], v160 offset:54272
	ds_read_b128 v[218:221], v160 offset:55296
	ds_read_b128 v[222:225], v160 offset:56320
	global_load_lds_dwordx4 v[154:155], off
	s_add_i32 m0, s64, 0x2000
	s_add_u32 s48, s48, 0x100080
	v_lshl_add_u64 v[154:155], v[226:227], 0, s[20:21]
	s_addc_u32 s49, s49, 0
	s_add_i32 s64, s86, s66
	global_load_lds_dwordx4 v[154:155], off
	v_lshl_add_u64 v[154:155], s[48:49], 0, v[132:133]
	s_mov_b32 m0, s64
	s_nop 0
	global_load_lds_dwordx4 v[154:155], off
	v_lshl_add_u64 v[154:155], s[48:49], 0, v[136:137]
	s_add_i32 m0, s64, 0x2000
	s_nop 0
	global_load_lds_dwordx4 v[154:155], off
	v_lshl_add_u64 v[154:155], v[228:229], 0, s[20:21]
	s_mov_b32 m0, s72
	s_nop 0
	global_load_lds_dwordx4 v[154:155], off
	v_lshl_add_u64 v[154:155], v[230:231], 0, s[20:21]
	s_mov_b32 m0, s73
	s_nop 0
	global_load_lds_dwordx4 v[154:155], off
	s_waitcnt lgkmcnt(0)
	s_setprio 1
	v_mfma_f32_16x16x32_bf16 v[62:65], v[150:153], v[190:193], v[62:65]
	v_mfma_f32_16x16x32_bf16 v[58:61], v[166:169], v[190:193], v[58:61]
	v_mfma_f32_16x16x32_bf16 v[46:49], v[150:153], v[200:203], v[46:49]
	v_mfma_f32_16x16x32_bf16 v[42:45], v[166:169], v[200:203], v[42:45]
	v_mfma_f32_16x16x32_bf16 v[30:33], v[150:153], v[210:213], v[30:33]
	v_mfma_f32_16x16x32_bf16 v[26:29], v[166:169], v[210:213], v[26:29]
	v_mfma_f32_16x16x32_bf16 v[14:17], v[150:153], v[218:221], v[14:17]
	v_mfma_f32_16x16x32_bf16 v[10:13], v[166:169], v[218:221], v[10:13]
	v_mfma_f32_16x16x32_bf16 v[62:65], v[162:165], v[196:199], v[62:65]
	v_mfma_f32_16x16x32_bf16 v[58:61], v[170:173], v[196:199], v[58:61]
	v_mfma_f32_16x16x32_bf16 v[46:49], v[162:165], v[206:209], v[46:49]
	v_mfma_f32_16x16x32_bf16 v[42:45], v[170:173], v[206:209], v[42:45]
	v_mfma_f32_16x16x32_bf16 v[30:33], v[162:165], v[214:217], v[30:33]
	v_mfma_f32_16x16x32_bf16 v[26:29], v[170:173], v[214:217], v[26:29]
	v_mfma_f32_16x16x32_bf16 v[14:17], v[162:165], v[222:225], v[14:17]
	v_mfma_f32_16x16x32_bf16 v[10:13], v[170:173], v[222:225], v[10:13]
	v_mfma_f32_16x16x32_bf16 v[54:57], v[174:177], v[190:193], v[54:57]
	v_mfma_f32_16x16x32_bf16 v[50:53], v[182:185], v[190:193], v[50:53]
	v_mfma_f32_16x16x32_bf16 v[38:41], v[174:177], v[200:203], v[38:41]
	v_mfma_f32_16x16x32_bf16 v[34:37], v[182:185], v[200:203], v[34:37]
	v_mfma_f32_16x16x32_bf16 v[22:25], v[174:177], v[210:213], v[22:25]
	v_mfma_f32_16x16x32_bf16 v[18:21], v[182:185], v[210:213], v[18:21]
	v_mfma_f32_16x16x32_bf16 v[6:9], v[174:177], v[218:221], v[6:9]
	v_mfma_f32_16x16x32_bf16 v[2:5], v[182:185], v[218:221], v[2:5]
	v_mfma_f32_16x16x32_bf16 v[54:57], v[178:181], v[196:199], v[54:57]
	v_mfma_f32_16x16x32_bf16 v[50:53], v[186:189], v[196:199], v[50:53]
	v_mfma_f32_16x16x32_bf16 v[38:41], v[178:181], v[206:209], v[38:41]
	v_mfma_f32_16x16x32_bf16 v[34:37], v[186:189], v[206:209], v[34:37]
	v_mfma_f32_16x16x32_bf16 v[22:25], v[178:181], v[214:217], v[22:25]
	v_mfma_f32_16x16x32_bf16 v[18:21], v[186:189], v[214:217], v[18:21]
	v_mfma_f32_16x16x32_bf16 v[6:9], v[178:181], v[222:225], v[6:9]
	v_mfma_f32_16x16x32_bf16 v[2:5], v[186:189], v[222:225], v[2:5]
	s_setprio 0
	s_waitcnt vmcnt(8)
	s_barrier
	s_add_u32 s62, s62, 0x100
	s_addc_u32 s63, s63, 0
	s_add_u32 s53, s53, 0x100
	s_addc_u32 s55, s55, 0
	s_cmp_ge_i32 s84, s83
	s_mov_b32 s48, s84
	s_cbranch_scc0 .Lkt_L_7
	s_branch .Lkt_exit_7
.Lkt_T_7:
	ds_read_b128 v[150:153], v158
	ds_read_b128 v[162:165], v158 offset:1024
	ds_read_b128 v[166:169], v158 offset:2048
	ds_read_b128 v[170:173], v158 offset:3072
	ds_read_b128 v[174:177], v159
	ds_read_b128 v[178:181], v159 offset:1024
	ds_read_b128 v[182:185], v159 offset:2048
	ds_read_b128 v[186:189], v159 offset:3072
	s_add_i32 s84, s48, 2
	s_add_u32 s49, s62, 0xfff00080
	s_addc_u32 s64, s63, -1
	s_cmp_eq_u32 s51, s48
	s_cselect_b32 s48, s56, s53
	s_cselect_b32 s65, s9, s64
	s_cselect_b32 s64, s8, s49
	s_cselect_b32 s49, s57, s55
	v_lshl_add_u64 v[154:155], s[62:63], 0, v[138:139]
	s_add_i32 m0, s59, 0xc000
	ds_read_b128 v[190:193], v160
	ds_read_b128 v[196:199], v160 offset:1024
	ds_read_b128 v[200:203], v160 offset:2048
	ds_read_b128 v[206:209], v160 offset:3072
	ds_read_b128 v[210:213], v160 offset:4096
	ds_read_b128 v[214:217], v160 offset:5120
	ds_read_b128 v[218:221], v160 offset:6144
	ds_read_b128 v[222:225], v160 offset:7168
	global_load_lds_dwordx4 v[154:155], off
	v_lshl_add_u64 v[154:155], s[62:63], 0, v[140:141]
	s_add_i32 m0, s59, 0xe000
	s_nop 0
	global_load_lds_dwordx4 v[154:155], off
	s_waitcnt vmcnt(8)
	s_waitcnt lgkmcnt(0)
	s_barrier
	s_setprio 2
	v_mfma_f32_16x16x32_bf16 v[126:129], v[150:153], v[190:193], v[126:129]
	v_mfma_f32_16x16x32_bf16 v[122:125], v[166:169], v[190:193], v[122:125]
	v_mfma_f32_16x16x32_bf16 v[110:113], v[150:153], v[200:203], v[110:113]
	v_mfma_f32_16x16x32_bf16 v[106:109], v[166:169], v[200:203], v[106:109]
	v_mfma_f32_16x16x32_bf16 v[94:97], v[150:153], v[210:213], v[94:97]
	v_mfma_f32_16x16x32_bf16 v[90:93], v[166:169], v[210:213], v[90:93]
	v_mfma_f32_16x16x32_bf16 v[78:81], v[150:153], v[218:221], v[78:81]
	v_mfma_f32_16x16x32_bf16 v[74:77], v[166:169], v[218:221], v[74:77]
	v_mfma_f32_16x16x32_bf16 v[126:129], v[162:165], v[196:199], v[126:129]
	v_mfma_f32_16x16x32_bf16 v[122:125], v[170:173], v[196:199], v[122:125]
	v_mfma_f32_16x16x32_bf16 v[110:113], v[162:165], v[206:209], v[110:113]
	v_mfma_f32_16x16x32_bf16 v[106:109], v[170:173], v[206:209], v[106:109]
	v_mfma_f32_16x16x32_bf16 v[94:97], v[162:165], v[214:217], v[94:97]
	v_mfma_f32_16x16x32_bf16 v[90:93], v[170:173], v[214:217], v[90:93]
	v_mfma_f32_16x16x32_bf16 v[78:81], v[162:165], v[222:225], v[78:81]
	v_mfma_f32_16x16x32_bf16 v[74:77], v[170:173], v[222:225], v[74:77]
	v_mfma_f32_16x16x32_bf16 v[118:121], v[174:177], v[190:193], v[118:121]
	v_mfma_f32_16x16x32_bf16 v[114:117], v[182:185], v[190:193], v[114:117]
	v_mfma_f32_16x16x32_bf16 v[102:105], v[174:177], v[200:203], v[102:105]
	v_mfma_f32_16x16x32_bf16 v[98:101], v[182:185], v[200:203], v[98:101]
	v_mfma_f32_16x16x32_bf16 v[86:89], v[174:177], v[210:213], v[86:89]
	v_mfma_f32_16x16x32_bf16 v[82:85], v[182:185], v[210:213], v[82:85]
	v_mfma_f32_16x16x32_bf16 v[70:73], v[174:177], v[218:221], v[70:73]
	v_mfma_f32_16x16x32_bf16 v[66:69], v[182:185], v[218:221], v[66:69]
	v_mfma_f32_16x16x32_bf16 v[118:121], v[178:181], v[196:199], v[118:121]
	v_mfma_f32_16x16x32_bf16 v[114:117], v[186:189], v[196:199], v[114:117]
	v_mfma_f32_16x16x32_bf16 v[102:105], v[178:181], v[206:209], v[102:105]
	v_mfma_f32_16x16x32_bf16 v[98:101], v[186:189], v[206:209], v[98:101]
	v_mfma_f32_16x16x32_bf16 v[86:89], v[178:181], v[214:217], v[86:89]
	v_mfma_f32_16x16x32_bf16 v[82:85], v[186:189], v[214:217], v[82:85]
	v_mfma_f32_16x16x32_bf16 v[70:73], v[178:181], v[222:225], v[70:73]
	v_mfma_f32_16x16x32_bf16 v[66:69], v[186:189], v[222:225], v[66:69]
	s_setprio 0
	s_add_i32 s85, s75, s66
	v_lshl_add_u64 v[154:155], s[48:49], 0, v[132:133]
	s_mov_b32 m0, s85
	ds_read_b128 v[190:193], v160 offset:16384
	ds_read_b128 v[196:199], v160 offset:17408
	ds_read_b128 v[200:203], v160 offset:18432
	ds_read_b128 v[206:209], v160 offset:19456
	ds_read_b128 v[210:213], v160 offset:20480
	ds_read_b128 v[214:217], v160 offset:21504
	ds_read_b128 v[218:221], v160 offset:22528
	ds_read_b128 v[222:225], v160 offset:23552
	global_load_lds_dwordx4 v[154:155], off
	s_add_i32 m0, s85, 0x2000
	s_add_u32 s86, s48, 0x100000
	v_lshl_add_u64 v[226:227], s[48:49], 0, v[136:137]
	s_addc_u32 s87, s49, 0
	s_add_i32 s85, s76, s66
	global_load_lds_dwordx4 v[226:227], off
	v_lshl_add_u64 v[228:229], s[86:87], 0, v[132:133]
	s_mov_b32 m0, s85
	v_lshl_add_u64 v[230:231], s[64:65], 0, v[134:135]
	global_load_lds_dwordx4 v[228:229], off
	v_lshl_add_u64 v[228:229], s[86:87], 0, v[136:137]
	s_add_i32 m0, s85, 0x2000
	s_nop 0
	global_load_lds_dwordx4 v[228:229], off
	v_lshl_add_u64 v[228:229], s[64:65], 0, v[130:131]
	s_mov_b32 m0, s59
	s_nop 0
	global_load_lds_dwordx4 v[228:229], off
	s_mov_b32 m0, s61
	s_nop 0
	global_load_lds_dwordx4 v[230:231], off
	s_waitcnt vmcnt(8)
	s_waitcnt lgkmcnt(0)
	s_barrier
	s_setprio 2
	v_mfma_f32_16x16x32_bf16 v[62:65], v[150:153], v[190:193], v[62:65]
	v_mfma_f32_16x16x32_bf16 v[58:61], v[166:169], v[190:193], v[58:61]
	v_mfma_f32_16x16x32_bf16 v[46:49], v[150:153], v[200:203], v[46:49]
	v_mfma_f32_16x16x32_bf16 v[42:45], v[166:169], v[200:203], v[42:45]
	v_mfma_f32_16x16x32_bf16 v[30:33], v[150:153], v[210:213], v[30:33]
	v_mfma_f32_16x16x32_bf16 v[26:29], v[166:169], v[210:213], v[26:29]
	v_mfma_f32_16x16x32_bf16 v[14:17], v[150:153], v[218:221], v[14:17]
	v_mfma_f32_16x16x32_bf16 v[10:13], v[166:169], v[218:221], v[10:13]
	v_mfma_f32_16x16x32_bf16 v[62:65], v[162:165], v[196:199], v[62:65]
	v_mfma_f32_16x16x32_bf16 v[58:61], v[170:173], v[196:199], v[58:61]
	v_mfma_f32_16x16x32_bf16 v[46:49], v[162:165], v[206:209], v[46:49]
	v_mfma_f32_16x16x32_bf16 v[42:45], v[170:173], v[206:209], v[42:45]
	v_mfma_f32_16x16x32_bf16 v[30:33], v[162:165], v[214:217], v[30:33]
	v_mfma_f32_16x16x32_bf16 v[26:29], v[170:173], v[214:217], v[26:29]
	v_mfma_f32_16x16x32_bf16 v[14:17], v[162:165], v[222:225], v[14:17]
	v_mfma_f32_16x16x32_bf16 v[10:13], v[170:173], v[222:225], v[10:13]
	v_mfma_f32_16x16x32_bf16 v[54:57], v[174:177], v[190:193], v[54:57]
	v_mfma_f32_16x16x32_bf16 v[50:53], v[182:185], v[190:193], v[50:53]
	v_mfma_f32_16x16x32_bf16 v[38:41], v[174:177], v[200:203], v[38:41]
	v_mfma_f32_16x16x32_bf16 v[34:37], v[182:185], v[200:203], v[34:37]
	v_mfma_f32_16x16x32_bf16 v[22:25], v[174:177], v[210:213], v[22:25]
	v_mfma_f32_16x16x32_bf16 v[18:21], v[182:185], v[210:213], v[18:21]
	v_mfma_f32_16x16x32_bf16 v[6:9], v[174:177], v[218:221], v[6:9]
	v_mfma_f32_16x16x32_bf16 v[2:5], v[182:185], v[218:221], v[2:5]
	v_mfma_f32_16x16x32_bf16 v[54:57], v[178:181], v[196:199], v[54:57]
	v_mfma_f32_16x16x32_bf16 v[50:53], v[186:189], v[196:199], v[50:53]
	v_mfma_f32_16x16x32_bf16 v[38:41], v[178:181], v[206:209], v[38:41]
	v_mfma_f32_16x16x32_bf16 v[34:37], v[186:189], v[206:209], v[34:37]
	v_mfma_f32_16x16x32_bf16 v[22:25], v[178:181], v[214:217], v[22:25]
	v_mfma_f32_16x16x32_bf16 v[18:21], v[186:189], v[214:217], v[18:21]
	v_mfma_f32_16x16x32_bf16 v[6:9], v[178:181], v[222:225], v[6:9]
	v_mfma_f32_16x16x32_bf16 v[2:5], v[186:189], v[222:225], v[2:5]
	s_setprio 0
	s_add_i32 s85, 0, 0x18000
	v_add_u32_e32 v161, s85, v156
	s_add_i32 s86, 0, 0x1c000
	ds_read_b128 v[150:153], v161
	ds_read_b128 v[162:165], v161 offset:1024
	ds_read_b128 v[166:169], v161 offset:2048
	ds_read_b128 v[170:173], v161 offset:3072
	v_add_u32_e32 v161, s86, v156
	ds_read_b128 v[174:177], v161
	ds_read_b128 v[178:181], v161 offset:1024
	ds_read_b128 v[182:185], v161 offset:2048
	ds_read_b128 v[186:189], v161 offset:3072
	s_add_u32 s64, s64, 0x100000
	s_addc_u32 s65, s65, 0
	s_mov_b32 m0, s67
	v_lshl_add_u64 v[232:233], s[64:65], 0, v[130:131]
	ds_read_b128 v[190:193], v160 offset:32768
	ds_read_b128 v[196:199], v160 offset:33792
	ds_read_b128 v[200:203], v160 offset:34816
	ds_read_b128 v[206:209], v160 offset:35840
	ds_read_b128 v[210:213], v160 offset:36864
	ds_read_b128 v[214:217], v160 offset:37888
	ds_read_b128 v[218:221], v160 offset:38912
	ds_read_b128 v[222:225], v160 offset:39936
	global_load_lds_dwordx4 v[232:233], off
	v_lshl_add_u64 v[232:233], s[64:65], 0, v[134:135]
	s_mov_b32 m0, s68
	s_nop 0
	global_load_lds_dwordx4 v[232:233], off
	s_waitcnt vmcnt(8)
	s_waitcnt lgkmcnt(0)
	s_barrier
	s_setprio 2
	v_mfma_f32_16x16x32_bf16 v[126:129], v[150:153], v[190:193], v[126:129]
	v_mfma_f32_16x16x32_bf16 v[122:125], v[166:169], v[190:193], v[122:125]
	v_mfma_f32_16x16x32_bf16 v[110:113], v[150:153], v[200:203], v[110:113]
	v_mfma_f32_16x16x32_bf16 v[106:109], v[166:169], v[200:203], v[106:109]
	v_mfma_f32_16x16x32_bf16 v[94:97], v[150:153], v[210:213], v[94:97]
	v_mfma_f32_16x16x32_bf16 v[90:93], v[166:169], v[210:213], v[90:93]
	v_mfma_f32_16x16x32_bf16 v[78:81], v[150:153], v[218:221], v[78:81]
	v_mfma_f32_16x16x32_bf16 v[74:77], v[166:169], v[218:221], v[74:77]
	v_mfma_f32_16x16x32_bf16 v[126:129], v[162:165], v[196:199], v[126:129]
	v_mfma_f32_16x16x32_bf16 v[122:125], v[170:173], v[196:199], v[122:125]
	v_mfma_f32_16x16x32_bf16 v[110:113], v[162:165], v[206:209], v[110:113]
	v_mfma_f32_16x16x32_bf16 v[106:109], v[170:173], v[206:209], v[106:109]
	v_mfma_f32_16x16x32_bf16 v[94:97], v[162:165], v[214:217], v[94:97]
	v_mfma_f32_16x16x32_bf16 v[90:93], v[170:173], v[214:217], v[90:93]
	v_mfma_f32_16x16x32_bf16 v[78:81], v[162:165], v[222:225], v[78:81]
	v_mfma_f32_16x16x32_bf16 v[74:77], v[170:173], v[222:225], v[74:77]
	v_mfma_f32_16x16x32_bf16 v[118:121], v[174:177], v[190:193], v[118:121]
	v_mfma_f32_16x16x32_bf16 v[114:117], v[182:185], v[190:193], v[114:117]
	v_mfma_f32_16x16x32_bf16 v[102:105], v[174:177], v[200:203], v[102:105]
	v_mfma_f32_16x16x32_bf16 v[98:101], v[182:185], v[200:203], v[98:101]
	v_mfma_f32_16x16x32_bf16 v[86:89], v[174:177], v[210:213], v[86:89]
	v_mfma_f32_16x16x32_bf16 v[82:85], v[182:185], v[210:213], v[82:85]
	v_mfma_f32_16x16x32_bf16 v[70:73], v[174:177], v[218:221], v[70:73]
	v_mfma_f32_16x16x32_bf16 v[66:69], v[182:185], v[218:221], v[66:69]
	v_mfma_f32_16x16x32_bf16 v[118:121], v[178:181], v[196:199], v[118:121]
	v_mfma_f32_16x16x32_bf16 v[114:117], v[186:189], v[196:199], v[114:117]
	v_mfma_f32_16x16x32_bf16 v[102:105], v[178:181], v[206:209], v[102:105]
	v_mfma_f32_16x16x32_bf16 v[98:101], v[186:189], v[206:209], v[98:101]
	v_mfma_f32_16x16x32_bf16 v[86:89], v[178:181], v[214:217], v[86:89]
	v_mfma_f32_16x16x32_bf16 v[82:85], v[186:189], v[214:217], v[82:85]
	v_mfma_f32_16x16x32_bf16 v[70:73], v[178:181], v[222:225], v[70:73]
	v_mfma_f32_16x16x32_bf16 v[66:69], v[186:189], v[222:225], v[66:69]
	s_setprio 0
	s_add_i32 s64, s85, s66
	v_lshl_add_u64 v[154:155], v[154:155], 0, s[20:21]
	s_mov_b32 m0, s64
	ds_read_b128 v[190:193], v160 offset:49152
	ds_read_b128 v[196:199], v160 offset:50176
	ds_read_b128 v[200:203], v160 offset:51200
	ds_read_b128 v[206:209], v160 offset:52224
	ds_read_b128 v[210:213], v160 offset:53248
	ds_read_b128 v[214:217], v160 offset:54272
	ds_read_b128 v[218:221], v160 offset:55296
	ds_read_b128 v[222:225], v160 offset:56320
	global_load_lds_dwordx4 v[154:155], off
	s_add_i32 m0, s64, 0x2000
	s_add_u32 s48, s48, 0x100080
	v_lshl_add_u64 v[154:155], v[226:227], 0, s[20:21]
	s_addc_u32 s49, s49, 0
	s_add_i32 s64, s86, s66
	global_load_lds_dwordx4 v[154:155], off
	v_lshl_add_u64 v[154:155], s[48:49], 0, v[132:133]
	s_mov_b32 m0, s64
	s_nop 0
	global_load_lds_dwordx4 v[154:155], off
	v_lshl_add_u64 v[154:155], s[48:49], 0, v[136:137]
	s_add_i32 m0, s64, 0x2000
	s_nop 0
	global_load_lds_dwordx4 v[154:155], off
	v_lshl_add_u64 v[154:155], v[228:229], 0, s[20:21]
	s_mov_b32 m0, s72
	s_nop 0
	global_load_lds_dwordx4 v[154:155], off
	v_lshl_add_u64 v[154:155], v[230:231], 0, s[20:21]
	s_mov_b32 m0, s73
	s_nop 0
	global_load_lds_dwordx4 v[154:155], off
	s_waitcnt vmcnt(8)
	s_waitcnt lgkmcnt(0)
	s_barrier
	s_setprio 2
	v_mfma_f32_16x16x32_bf16 v[62:65], v[150:153], v[190:193], v[62:65]
	v_mfma_f32_16x16x32_bf16 v[58:61], v[166:169], v[190:193], v[58:61]
	v_mfma_f32_16x16x32_bf16 v[46:49], v[150:153], v[200:203], v[46:49]
	v_mfma_f32_16x16x32_bf16 v[42:45], v[166:169], v[200:203], v[42:45]
	v_mfma_f32_16x16x32_bf16 v[30:33], v[150:153], v[210:213], v[30:33]
	v_mfma_f32_16x16x32_bf16 v[26:29], v[166:169], v[210:213], v[26:29]
	v_mfma_f32_16x16x32_bf16 v[14:17], v[150:153], v[218:221], v[14:17]
	v_mfma_f32_16x16x32_bf16 v[10:13], v[166:169], v[218:221], v[10:13]
	v_mfma_f32_16x16x32_bf16 v[62:65], v[162:165], v[196:199], v[62:65]
	v_mfma_f32_16x16x32_bf16 v[58:61], v[170:173], v[196:199], v[58:61]
	v_mfma_f32_16x16x32_bf16 v[46:49], v[162:165], v[206:209], v[46:49]
	v_mfma_f32_16x16x32_bf16 v[42:45], v[170:173], v[206:209], v[42:45]
	v_mfma_f32_16x16x32_bf16 v[30:33], v[162:165], v[214:217], v[30:33]
	v_mfma_f32_16x16x32_bf16 v[26:29], v[170:173], v[214:217], v[26:29]
	v_mfma_f32_16x16x32_bf16 v[14:17], v[162:165], v[222:225], v[14:17]
	v_mfma_f32_16x16x32_bf16 v[10:13], v[170:173], v[222:225], v[10:13]
	v_mfma_f32_16x16x32_bf16 v[54:57], v[174:177], v[190:193], v[54:57]
	v_mfma_f32_16x16x32_bf16 v[50:53], v[182:185], v[190:193], v[50:53]
	v_mfma_f32_16x16x32_bf16 v[38:41], v[174:177], v[200:203], v[38:41]
	v_mfma_f32_16x16x32_bf16 v[34:37], v[182:185], v[200:203], v[34:37]
	v_mfma_f32_16x16x32_bf16 v[22:25], v[174:177], v[210:213], v[22:25]
	v_mfma_f32_16x16x32_bf16 v[18:21], v[182:185], v[210:213], v[18:21]
	v_mfma_f32_16x16x32_bf16 v[6:9], v[174:177], v[218:221], v[6:9]
	v_mfma_f32_16x16x32_bf16 v[2:5], v[182:185], v[218:221], v[2:5]
	v_mfma_f32_16x16x32_bf16 v[54:57], v[178:181], v[196:199], v[54:57]
	v_mfma_f32_16x16x32_bf16 v[50:53], v[186:189], v[196:199], v[50:53]
	v_mfma_f32_16x16x32_bf16 v[38:41], v[178:181], v[206:209], v[38:41]
	v_mfma_f32_16x16x32_bf16 v[34:37], v[186:189], v[206:209], v[34:37]
	v_mfma_f32_16x16x32_bf16 v[22:25], v[178:181], v[214:217], v[22:25]
	v_mfma_f32_16x16x32_bf16 v[18:21], v[186:189], v[214:217], v[18:21]
	v_mfma_f32_16x16x32_bf16 v[6:9], v[178:181], v[222:225], v[6:9]
	v_mfma_f32_16x16x32_bf16 v[2:5], v[186:189], v[222:225], v[2:5]
	s_setprio 0
	s_add_u32 s62, s62, 0x100
	s_addc_u32 s63, s63, 0
	s_add_u32 s53, s53, 0x100
	s_addc_u32 s55, s55, 0
	s_cmp_ge_i32 s84, s83
	s_mov_b32 s48, s84
	s_cbranch_scc0 .Lkt_T_7
	s_nop 7

.LBB0_1065:
	s_andn2_b64 vcc, exec, s[14:15]
	s_cbranch_vccnz .LBB0_1041
	s_branch .LBB0_1041

.LBB0_1191:
	s_and_b64 s[6:7], s[6:7], exec
	s_cselect_b32 s60, 16, 8
	s_add_u32 s48, s38, 0x43e00000
	s_addc_u32 s49, s39, 0
	s_add_u32 s50, s38, 0x47e00000
	s_addc_u32 s51, s39, 0
	s_lshl_b32 s6, s12, 5
	s_mov_b64 s[12:13], 0x80
	s_and_b32 s21, s6, 0x60
	s_add_i32 m0, s8, 0x18000
	v_lshl_add_u64 v[8:9], v[8:9], 0, s[12:13]
	s_lshl_b32 s20, s19, 13
	s_lshl_b32 s22, s21, 7
	s_waitcnt vmcnt(2)
	s_barrier
	global_load_lds_dwordx4 v[8:9], off
	v_lshl_add_u64 v[6:7], v[6:7], 0, s[12:13]
	s_add_i32 m0, s8, 0x1a000
	s_add_i32 s52, s8, 0x8000
	s_add_i32 s53, s8, 0xa000
	global_load_lds_dwordx4 v[6:7], off
	v_lshl_add_u64 v[2:3], v[2:3], 0, s[12:13]
	s_mov_b32 m0, s52
	s_add_u32 s6, s34, 0x100080
	global_load_lds_dwordx4 v[2:3], off
	v_lshl_add_u64 v[2:3], v[4:5], 0, s[12:13]
	s_mov_b32 m0, s53
	s_addc_u32 s7, s35, 0
	global_load_lds_dwordx4 v[2:3], off
	s_add_i32 m0, s8, 0x1c000
	v_lshl_add_u64 v[2:3], s[6:7], 0, v[134:135]
	global_load_lds_dwordx4 v[2:3], off
	v_lshl_add_u64 v[2:3], s[6:7], 0, v[132:133]
	s_add_i32 m0, s8, 0x1e000
	v_and_b32_e32 v1, 15, v0
	global_load_lds_dwordx4 v[2:3], off
	v_bfe_u32 v2, v0, 4, 2
	v_lshlrev_b32_e32 v3, 4, v2
	v_lshlrev_b32_e32 v4, 2, v0
	v_lshl_or_b32 v136, s19, 6, v1
	v_lshl_or_b32 v1, v1, 6, v3
	v_and_b32_e32 v4, 32, v4
	v_mov_b32_e32 v137, v135
	v_bitop3_b32 v5, v1, s20, v4 bitop3:0xde
	v_lshlrev_b32_e32 v1, 6, v0
	s_movk_i32 s6, 0x3c0
	v_lshlrev_b64 v[138:139], 11, v[136:137]
	v_lshl_or_b32 v137, v2, 2, s21
	v_lshlrev_b32_e32 v2, 10, v0
	v_and_or_b32 v1, v1, s6, v3
	v_and_b32_e32 v2, 0x60000, v2
	v_lshlrev_b32_e32 v3, 13, v13
	v_or3_b32 v2, v12, v2, v3
	v_add_u32_e32 v148, v2, v11
	v_lshlrev_b32_e32 v2, 6, v10
	s_waitcnt vmcnt(6)
	s_cmpk_lt_u32 s18, 0x100
	v_and_b32_e32 v2, 0xe0000, v2
	v_bitop3_b32 v1, s22, v1, v4 bitop3:0xf6
	s_cselect_b64 s[18:19], -1, 0
	v_or_b32_e32 v140, 16, v136
	v_mov_b32_e32 v141, v135
	v_or_b32_e32 v144, 32, v136
	v_mov_b32_e32 v145, v135
	v_or3_b32 v2, v12, v2, v3
	s_add_i32 s56, 0, 0x10000
	s_add_i32 s57, 0, 0x14000
	v_lshlrev_b64 v[142:143], 11, v[140:141]
	v_lshlrev_b64 v[146:147], 11, v[144:145]
	v_or_b32_e32 v131, 48, v136
	s_ashr_i32 s54, s44, 31
	s_ashr_i32 s55, s2, 31
	v_mov_b32_e32 v149, v135
	v_add_u32_e32 v150, v2, v11
	v_mov_b32_e32 v151, v135
	v_mov_b64_e32 v[152:153], 0x110
	v_mov_b64_e32 v[154:155], 0x10f
	v_add_u32_e32 v141, s56, v1
	v_add_u32_e32 v145, s57, v1
	v_add_u32_e32 v160, 0, v5
	v_mov_b64_e32 v[156:157], 0x100
	s_branch .LBB0_1194

.LBB0_1197:
	s_and_b64 vcc, exec, s[18:19]
	s_cbranch_vccz .Lkt_T_8
.Lkt_L_8:
	ds_read_b128 v[162:165], v141
	ds_read_b128 v[166:169], v141 offset:1024
	ds_read_b128 v[170:173], v141 offset:2048
	ds_read_b128 v[174:177], v141 offset:3072
	ds_read_b128 v[178:181], v145
	ds_read_b128 v[182:185], v145 offset:1024
	ds_read_b128 v[186:189], v145 offset:2048
	ds_read_b128 v[190:193], v145 offset:3072
	s_add_i32 s65, s34, 2
	s_add_u32 s35, s30, 0xfff00080
	s_addc_u32 s40, s31, -1
	s_cmp_eq_u32 s62, s34
	s_cselect_b32 s34, s61, s63
	s_cselect_b32 s41, s21, s40
	s_cselect_b32 s40, s25, s35
	s_cselect_b32 s35, s23, s64
	v_lshl_add_u64 v[158:159], s[30:31], 0, v[148:149]
	s_add_i32 m0, s8, 0xc000
	ds_read_b128 v[196:199], v160
	ds_read_b128 v[200:203], v160 offset:1024
	ds_read_b128 v[206:209], v160 offset:2048
	ds_read_b128 v[210:213], v160 offset:3072
	ds_read_b128 v[214:217], v160 offset:4096
	ds_read_b128 v[218:221], v160 offset:5120
	ds_read_b128 v[222:225], v160 offset:6144
	ds_read_b128 v[226:229], v160 offset:7168
	global_load_lds_dwordx4 v[158:159], off
	v_lshl_add_u64 v[158:159], s[30:31], 0, v[150:151]
	s_add_i32 m0, s8, 0xe000
	s_nop 0
	global_load_lds_dwordx4 v[158:159], off
	s_waitcnt lgkmcnt(0)
	s_setprio 1
	v_mfma_f32_16x16x32_bf16 v[126:129], v[162:165], v[196:199], v[126:129]
	v_mfma_f32_16x16x32_bf16 v[122:125], v[170:173], v[196:199], v[122:125]
	v_mfma_f32_16x16x32_bf16 v[118:121], v[162:165], v[206:209], v[118:121]
	v_mfma_f32_16x16x32_bf16 v[114:117], v[170:173], v[206:209], v[114:117]
	v_mfma_f32_16x16x32_bf16 v[102:105], v[162:165], v[214:217], v[102:105]
	v_mfma_f32_16x16x32_bf16 v[98:101], v[170:173], v[214:217], v[98:101]
	v_mfma_f32_16x16x32_bf16 v[42:45], v[162:165], v[222:225], v[42:45]
	v_mfma_f32_16x16x32_bf16 v[34:37], v[170:173], v[222:225], v[34:37]
	v_mfma_f32_16x16x32_bf16 v[126:129], v[166:169], v[200:203], v[126:129]
	v_mfma_f32_16x16x32_bf16 v[122:125], v[174:177], v[200:203], v[122:125]
	v_mfma_f32_16x16x32_bf16 v[118:121], v[166:169], v[210:213], v[118:121]
	v_mfma_f32_16x16x32_bf16 v[114:117], v[174:177], v[210:213], v[114:117]
	v_mfma_f32_16x16x32_bf16 v[102:105], v[166:169], v[218:221], v[102:105]
	v_mfma_f32_16x16x32_bf16 v[98:101], v[174:177], v[218:221], v[98:101]
	v_mfma_f32_16x16x32_bf16 v[42:45], v[166:169], v[226:229], v[42:45]
	v_mfma_f32_16x16x32_bf16 v[34:37], v[174:177], v[226:229], v[34:37]
	v_mfma_f32_16x16x32_bf16 v[110:113], v[178:181], v[196:199], v[110:113]
	v_mfma_f32_16x16x32_bf16 v[106:109], v[186:189], v[196:199], v[106:109]
	v_mfma_f32_16x16x32_bf16 v[94:97], v[178:181], v[206:209], v[94:97]
	v_mfma_f32_16x16x32_bf16 v[90:93], v[186:189], v[206:209], v[90:93]
	v_mfma_f32_16x16x32_bf16 v[86:89], v[178:181], v[214:217], v[86:89]
	v_mfma_f32_16x16x32_bf16 v[82:85], v[186:189], v[214:217], v[82:85]
	v_mfma_f32_16x16x32_bf16 v[30:33], v[178:181], v[222:225], v[30:33]
	v_mfma_f32_16x16x32_bf16 v[26:29], v[186:189], v[222:225], v[26:29]
	v_mfma_f32_16x16x32_bf16 v[110:113], v[182:185], v[200:203], v[110:113]
	v_mfma_f32_16x16x32_bf16 v[106:109], v[190:193], v[200:203], v[106:109]
	v_mfma_f32_16x16x32_bf16 v[94:97], v[182:185], v[210:213], v[94:97]
	v_mfma_f32_16x16x32_bf16 v[90:93], v[190:193], v[210:213], v[90:93]
	v_mfma_f32_16x16x32_bf16 v[86:89], v[182:185], v[218:221], v[86:89]
	v_mfma_f32_16x16x32_bf16 v[82:85], v[190:193], v[218:221], v[82:85]
	v_mfma_f32_16x16x32_bf16 v[30:33], v[182:185], v[226:229], v[30:33]
	v_mfma_f32_16x16x32_bf16 v[26:29], v[190:193], v[226:229], v[26:29]
	s_setprio 0
	s_waitcnt vmcnt(8)
	s_barrier
	s_add_i32 s66, s56, s42
	v_lshl_add_u64 v[158:159], s[34:35], 0, v[134:135]
	s_mov_b32 m0, s66
	ds_read_b128 v[196:199], v160 offset:16384
	ds_read_b128 v[200:203], v160 offset:17408
	ds_read_b128 v[206:209], v160 offset:18432
	ds_read_b128 v[210:213], v160 offset:19456
	ds_read_b128 v[214:217], v160 offset:20480
	ds_read_b128 v[218:221], v160 offset:21504
	ds_read_b128 v[222:225], v160 offset:22528
	ds_read_b128 v[226:229], v160 offset:23552
	global_load_lds_dwordx4 v[158:159], off
	s_add_i32 m0, s66, 0x2000
	s_add_u32 s66, s34, 0x100000
	v_lshl_add_u64 v[230:231], s[34:35], 0, v[132:133]
	s_addc_u32 s67, s35, 0
	s_add_i32 s68, s57, s42
	global_load_lds_dwordx4 v[230:231], off
	v_lshl_add_u64 v[232:233], s[66:67], 0, v[134:135]
	s_mov_b32 m0, s68
	v_lshl_add_u64 v[234:235], s[40:41], 0, v[132:133]
	global_load_lds_dwordx4 v[232:233], off
	v_lshl_add_u64 v[232:233], s[66:67], 0, v[132:133]
	s_add_i32 m0, s68, 0x2000
	s_nop 0
	global_load_lds_dwordx4 v[232:233], off
	v_lshl_add_u64 v[232:233], s[40:41], 0, v[134:135]
	s_mov_b32 m0, s8
	s_nop 0
	global_load_lds_dwordx4 v[232:233], off
	s_mov_b32 m0, s15
	s_nop 0
	global_load_lds_dwordx4 v[234:235], off
	s_waitcnt lgkmcnt(0)
	s_setprio 1
	v_mfma_f32_16x16x32_bf16 v[78:81], v[162:165], v[196:199], v[78:81]
	v_mfma_f32_16x16x32_bf16 v[74:77], v[170:173], v[196:199], v[74:77]
	v_mfma_f32_16x16x32_bf16 v[70:73], v[162:165], v[206:209], v[70:73]
	v_mfma_f32_16x16x32_bf16 v[66:69], v[170:173], v[206:209], v[66:69]
	v_mfma_f32_16x16x32_bf16 v[54:57], v[162:165], v[214:217], v[54:57]
	v_mfma_f32_16x16x32_bf16 v[50:53], v[170:173], v[214:217], v[50:53]
	v_mfma_f32_16x16x32_bf16 v[14:17], v[162:165], v[222:225], v[14:17]
	v_mfma_f32_16x16x32_bf16 v[10:13], v[170:173], v[222:225], v[10:13]
	v_mfma_f32_16x16x32_bf16 v[78:81], v[166:169], v[200:203], v[78:81]
	v_mfma_f32_16x16x32_bf16 v[74:77], v[174:177], v[200:203], v[74:77]
	v_mfma_f32_16x16x32_bf16 v[70:73], v[166:169], v[210:213], v[70:73]
	v_mfma_f32_16x16x32_bf16 v[66:69], v[174:177], v[210:213], v[66:69]
	v_mfma_f32_16x16x32_bf16 v[54:57], v[166:169], v[218:221], v[54:57]
	v_mfma_f32_16x16x32_bf16 v[50:53], v[174:177], v[218:221], v[50:53]
	v_mfma_f32_16x16x32_bf16 v[14:17], v[166:169], v[226:229], v[14:17]
	v_mfma_f32_16x16x32_bf16 v[10:13], v[174:177], v[226:229], v[10:13]
	v_mfma_f32_16x16x32_bf16 v[62:65], v[178:181], v[196:199], v[62:65]
	v_mfma_f32_16x16x32_bf16 v[58:61], v[186:189], v[196:199], v[58:61]
	v_mfma_f32_16x16x32_bf16 v[46:49], v[178:181], v[206:209], v[46:49]
	v_mfma_f32_16x16x32_bf16 v[38:41], v[186:189], v[206:209], v[38:41]
	v_mfma_f32_16x16x32_bf16 v[22:25], v[178:181], v[214:217], v[22:25]
	v_mfma_f32_16x16x32_bf16 v[18:21], v[186:189], v[214:217], v[18:21]
	v_mfma_f32_16x16x32_bf16 v[6:9], v[178:181], v[222:225], v[6:9]
	v_mfma_f32_16x16x32_bf16 v[2:5], v[186:189], v[222:225], v[2:5]
	v_mfma_f32_16x16x32_bf16 v[62:65], v[182:185], v[200:203], v[62:65]
	v_mfma_f32_16x16x32_bf16 v[58:61], v[190:193], v[200:203], v[58:61]
	v_mfma_f32_16x16x32_bf16 v[46:49], v[182:185], v[210:213], v[46:49]
	v_mfma_f32_16x16x32_bf16 v[38:41], v[190:193], v[210:213], v[38:41]
	v_mfma_f32_16x16x32_bf16 v[22:25], v[182:185], v[218:221], v[22:25]
	v_mfma_f32_16x16x32_bf16 v[18:21], v[190:193], v[218:221], v[18:21]
	v_mfma_f32_16x16x32_bf16 v[6:9], v[182:185], v[226:229], v[6:9]
	v_mfma_f32_16x16x32_bf16 v[2:5], v[190:193], v[226:229], v[2:5]
	s_setprio 0
	s_waitcnt vmcnt(8)
	s_barrier
	s_add_i32 s66, 0, 0x18000
	v_add_u32_e32 v161, s66, v1
	s_add_i32 s67, 0, 0x1c000
	ds_read_b128 v[162:165], v161
	ds_read_b128 v[166:169], v161 offset:1024
	ds_read_b128 v[170:173], v161 offset:2048
	ds_read_b128 v[174:177], v161 offset:3072
	v_add_u32_e32 v161, s67, v1
	ds_read_b128 v[178:181], v161
	ds_read_b128 v[182:185], v161 offset:1024
	ds_read_b128 v[186:189], v161 offset:2048
	ds_read_b128 v[190:193], v161 offset:3072
	s_add_u32 s40, s40, 0x100000
	s_addc_u32 s41, s41, 0
	s_mov_b32 m0, s46
	v_lshl_add_u64 v[236:237], s[40:41], 0, v[134:135]
	ds_read_b128 v[196:199], v160 offset:32768
	ds_read_b128 v[200:203], v160 offset:33792
	ds_read_b128 v[206:209], v160 offset:34816
	ds_read_b128 v[210:213], v160 offset:35840
	ds_read_b128 v[214:217], v160 offset:36864
	ds_read_b128 v[218:221], v160 offset:37888
	ds_read_b128 v[222:225], v160 offset:38912
	ds_read_b128 v[226:229], v160 offset:39936
	global_load_lds_dwordx4 v[236:237], off
	v_lshl_add_u64 v[236:237], s[40:41], 0, v[132:133]
	s_mov_b32 m0, s47
	s_nop 0
	global_load_lds_dwordx4 v[236:237], off
	s_waitcnt lgkmcnt(0)
	s_setprio 1
	v_mfma_f32_16x16x32_bf16 v[126:129], v[162:165], v[196:199], v[126:129]
	v_mfma_f32_16x16x32_bf16 v[122:125], v[170:173], v[196:199], v[122:125]
	v_mfma_f32_16x16x32_bf16 v[118:121], v[162:165], v[206:209], v[118:121]
	v_mfma_f32_16x16x32_bf16 v[114:117], v[170:173], v[206:209], v[114:117]
	v_mfma_f32_16x16x32_bf16 v[102:105], v[162:165], v[214:217], v[102:105]
	v_mfma_f32_16x16x32_bf16 v[98:101], v[170:173], v[214:217], v[98:101]
	v_mfma_f32_16x16x32_bf16 v[42:45], v[162:165], v[222:225], v[42:45]
	v_mfma_f32_16x16x32_bf16 v[34:37], v[170:173], v[222:225], v[34:37]
	v_mfma_f32_16x16x32_bf16 v[126:129], v[166:169], v[200:203], v[126:129]
	v_mfma_f32_16x16x32_bf16 v[122:125], v[174:177], v[200:203], v[122:125]
	v_mfma_f32_16x16x32_bf16 v[118:121], v[166:169], v[210:213], v[118:121]
	v_mfma_f32_16x16x32_bf16 v[114:117], v[174:177], v[210:213], v[114:117]
	v_mfma_f32_16x16x32_bf16 v[102:105], v[166:169], v[218:221], v[102:105]
	v_mfma_f32_16x16x32_bf16 v[98:101], v[174:177], v[218:221], v[98:101]
	v_mfma_f32_16x16x32_bf16 v[42:45], v[166:169], v[226:229], v[42:45]
	v_mfma_f32_16x16x32_bf16 v[34:37], v[174:177], v[226:229], v[34:37]
	v_mfma_f32_16x16x32_bf16 v[110:113], v[178:181], v[196:199], v[110:113]
	v_mfma_f32_16x16x32_bf16 v[106:109], v[186:189], v[196:199], v[106:109]
	v_mfma_f32_16x16x32_bf16 v[94:97], v[178:181], v[206:209], v[94:97]
	v_mfma_f32_16x16x32_bf16 v[90:93], v[186:189], v[206:209], v[90:93]
	v_mfma_f32_16x16x32_bf16 v[86:89], v[178:181], v[214:217], v[86:89]
	v_mfma_f32_16x16x32_bf16 v[82:85], v[186:189], v[214:217], v[82:85]
	v_mfma_f32_16x16x32_bf16 v[30:33], v[178:181], v[222:225], v[30:33]
	v_mfma_f32_16x16x32_bf16 v[26:29], v[186:189], v[222:225], v[26:29]
	v_mfma_f32_16x16x32_bf16 v[110:113], v[182:185], v[200:203], v[110:113]
	v_mfma_f32_16x16x32_bf16 v[106:109], v[190:193], v[200:203], v[106:109]
	v_mfma_f32_16x16x32_bf16 v[94:97], v[182:185], v[210:213], v[94:97]
	v_mfma_f32_16x16x32_bf16 v[90:93], v[190:193], v[210:213], v[90:93]
	v_mfma_f32_16x16x32_bf16 v[86:89], v[182:185], v[218:221], v[86:89]
	v_mfma_f32_16x16x32_bf16 v[82:85], v[190:193], v[218:221], v[82:85]
	v_mfma_f32_16x16x32_bf16 v[30:33], v[182:185], v[226:229], v[30:33]
	v_mfma_f32_16x16x32_bf16 v[26:29], v[190:193], v[226:229], v[26:29]
	s_setprio 0
	s_waitcnt vmcnt(8)
	s_barrier
	s_add_i32 s40, s66, s42
	v_lshl_add_u64 v[158:159], v[158:159], 0, s[12:13]
	s_mov_b32 m0, s40
	ds_read_b128 v[196:199], v160 offset:49152
	ds_read_b128 v[200:203], v160 offset:50176
	ds_read_b128 v[206:209], v160 offset:51200
	ds_read_b128 v[210:213], v160 offset:52224
	ds_read_b128 v[214:217], v160 offset:53248
	ds_read_b128 v[218:221], v160 offset:54272
	ds_read_b128 v[222:225], v160 offset:55296
	ds_read_b128 v[226:229], v160 offset:56320
	global_load_lds_dwordx4 v[158:159], off
	s_add_i32 m0, s40, 0x2000
	s_add_u32 s34, s34, 0x100080
	v_lshl_add_u64 v[158:159], v[230:231], 0, s[12:13]
	s_addc_u32 s35, s35, 0
	s_add_i32 s40, s67, s42
	global_load_lds_dwordx4 v[158:159], off
	v_lshl_add_u64 v[158:159], s[34:35], 0, v[134:135]
	s_mov_b32 m0, s40
	s_nop 0
	global_load_lds_dwordx4 v[158:159], off
	v_lshl_add_u64 v[158:159], s[34:35], 0, v[132:133]
	s_add_i32 m0, s40, 0x2000
	s_nop 0
	global_load_lds_dwordx4 v[158:159], off
	v_lshl_add_u64 v[158:159], v[232:233], 0, s[12:13]
	s_mov_b32 m0, s52
	s_nop 0
	global_load_lds_dwordx4 v[158:159], off
	v_lshl_add_u64 v[158:159], v[234:235], 0, s[12:13]
	s_mov_b32 m0, s53
	s_nop 0
	global_load_lds_dwordx4 v[158:159], off
	s_waitcnt lgkmcnt(0)
	s_setprio 1
	v_mfma_f32_16x16x32_bf16 v[78:81], v[162:165], v[196:199], v[78:81]
	v_mfma_f32_16x16x32_bf16 v[74:77], v[170:173], v[196:199], v[74:77]
	v_mfma_f32_16x16x32_bf16 v[70:73], v[162:165], v[206:209], v[70:73]
	v_mfma_f32_16x16x32_bf16 v[66:69], v[170:173], v[206:209], v[66:69]
	v_mfma_f32_16x16x32_bf16 v[54:57], v[162:165], v[214:217], v[54:57]
	v_mfma_f32_16x16x32_bf16 v[50:53], v[170:173], v[214:217], v[50:53]
	v_mfma_f32_16x16x32_bf16 v[14:17], v[162:165], v[222:225], v[14:17]
	v_mfma_f32_16x16x32_bf16 v[10:13], v[170:173], v[222:225], v[10:13]
	v_mfma_f32_16x16x32_bf16 v[78:81], v[166:169], v[200:203], v[78:81]
	v_mfma_f32_16x16x32_bf16 v[74:77], v[174:177], v[200:203], v[74:77]
	v_mfma_f32_16x16x32_bf16 v[70:73], v[166:169], v[210:213], v[70:73]
	v_mfma_f32_16x16x32_bf16 v[66:69], v[174:177], v[210:213], v[66:69]
	v_mfma_f32_16x16x32_bf16 v[54:57], v[166:169], v[218:221], v[54:57]
	v_mfma_f32_16x16x32_bf16 v[50:53], v[174:177], v[218:221], v[50:53]
	v_mfma_f32_16x16x32_bf16 v[14:17], v[166:169], v[226:229], v[14:17]
	v_mfma_f32_16x16x32_bf16 v[10:13], v[174:177], v[226:229], v[10:13]
	v_mfma_f32_16x16x32_bf16 v[62:65], v[178:181], v[196:199], v[62:65]
	v_mfma_f32_16x16x32_bf16 v[58:61], v[186:189], v[196:199], v[58:61]
	v_mfma_f32_16x16x32_bf16 v[46:49], v[178:181], v[206:209], v[46:49]
	v_mfma_f32_16x16x32_bf16 v[38:41], v[186:189], v[206:209], v[38:41]
	v_mfma_f32_16x16x32_bf16 v[22:25], v[178:181], v[214:217], v[22:25]
	v_mfma_f32_16x16x32_bf16 v[18:21], v[186:189], v[214:217], v[18:21]
	v_mfma_f32_16x16x32_bf16 v[6:9], v[178:181], v[222:225], v[6:9]
	v_mfma_f32_16x16x32_bf16 v[2:5], v[186:189], v[222:225], v[2:5]
	v_mfma_f32_16x16x32_bf16 v[62:65], v[182:185], v[200:203], v[62:65]
	v_mfma_f32_16x16x32_bf16 v[58:61], v[190:193], v[200:203], v[58:61]
	v_mfma_f32_16x16x32_bf16 v[46:49], v[182:185], v[210:213], v[46:49]
	v_mfma_f32_16x16x32_bf16 v[38:41], v[190:193], v[210:213], v[38:41]
	v_mfma_f32_16x16x32_bf16 v[22:25], v[182:185], v[218:221], v[22:25]
	v_mfma_f32_16x16x32_bf16 v[18:21], v[190:193], v[218:221], v[18:21]
	v_mfma_f32_16x16x32_bf16 v[6:9], v[182:185], v[226:229], v[6:9]
	v_mfma_f32_16x16x32_bf16 v[2:5], v[190:193], v[226:229], v[2:5]
	s_setprio 0
	s_waitcnt vmcnt(8)
	s_barrier
	s_add_u32 s30, s30, 0x100
	s_addc_u32 s31, s31, 0
	s_add_u32 s63, s63, 0x100
	s_addc_u32 s64, s64, 0
	s_cmp_ge_i32 s65, s60
	s_mov_b32 s34, s65
	s_cbranch_scc0 .Lkt_L_8
	s_branch .Lkt_exit_8
.Lkt_T_8:
	ds_read_b128 v[162:165], v141
	ds_read_b128 v[166:169], v141 offset:1024
	ds_read_b128 v[170:173], v141 offset:2048
	ds_read_b128 v[174:177], v141 offset:3072
	ds_read_b128 v[178:181], v145
	ds_read_b128 v[182:185], v145 offset:1024
	ds_read_b128 v[186:189], v145 offset:2048
	ds_read_b128 v[190:193], v145 offset:3072
	s_add_i32 s65, s34, 2
	s_add_u32 s35, s30, 0xfff00080
	s_addc_u32 s40, s31, -1
	s_cmp_eq_u32 s62, s34
	s_cselect_b32 s34, s61, s63
	s_cselect_b32 s41, s21, s40
	s_cselect_b32 s40, s25, s35
	s_cselect_b32 s35, s23, s64
	v_lshl_add_u64 v[158:159], s[30:31], 0, v[148:149]
	s_add_i32 m0, s8, 0xc000
	ds_read_b128 v[196:199], v160
	ds_read_b128 v[200:203], v160 offset:1024
	ds_read_b128 v[206:209], v160 offset:2048
	ds_read_b128 v[210:213], v160 offset:3072
	ds_read_b128 v[214:217], v160 offset:4096
	ds_read_b128 v[218:221], v160 offset:5120
	ds_read_b128 v[222:225], v160 offset:6144
	ds_read_b128 v[226:229], v160 offset:7168
	global_load_lds_dwordx4 v[158:159], off
	v_lshl_add_u64 v[158:159], s[30:31], 0, v[150:151]
	s_add_i32 m0, s8, 0xe000
	s_nop 0
	global_load_lds_dwordx4 v[158:159], off
	s_waitcnt vmcnt(8)
	s_waitcnt lgkmcnt(0)
	s_barrier
	s_setprio 2
	v_mfma_f32_16x16x32_bf16 v[126:129], v[162:165], v[196:199], v[126:129]
	v_mfma_f32_16x16x32_bf16 v[122:125], v[170:173], v[196:199], v[122:125]
	v_mfma_f32_16x16x32_bf16 v[118:121], v[162:165], v[206:209], v[118:121]
	v_mfma_f32_16x16x32_bf16 v[114:117], v[170:173], v[206:209], v[114:117]
	v_mfma_f32_16x16x32_bf16 v[102:105], v[162:165], v[214:217], v[102:105]
	v_mfma_f32_16x16x32_bf16 v[98:101], v[170:173], v[214:217], v[98:101]
	v_mfma_f32_16x16x32_bf16 v[42:45], v[162:165], v[222:225], v[42:45]
	v_mfma_f32_16x16x32_bf16 v[34:37], v[170:173], v[222:225], v[34:37]
	v_mfma_f32_16x16x32_bf16 v[126:129], v[166:169], v[200:203], v[126:129]
	v_mfma_f32_16x16x32_bf16 v[122:125], v[174:177], v[200:203], v[122:125]
	v_mfma_f32_16x16x32_bf16 v[118:121], v[166:169], v[210:213], v[118:121]
	v_mfma_f32_16x16x32_bf16 v[114:117], v[174:177], v[210:213], v[114:117]
	v_mfma_f32_16x16x32_bf16 v[102:105], v[166:169], v[218:221], v[102:105]
	v_mfma_f32_16x16x32_bf16 v[98:101], v[174:177], v[218:221], v[98:101]
	v_mfma_f32_16x16x32_bf16 v[42:45], v[166:169], v[226:229], v[42:45]
	v_mfma_f32_16x16x32_bf16 v[34:37], v[174:177], v[226:229], v[34:37]
	v_mfma_f32_16x16x32_bf16 v[110:113], v[178:181], v[196:199], v[110:113]
	v_mfma_f32_16x16x32_bf16 v[106:109], v[186:189], v[196:199], v[106:109]
	v_mfma_f32_16x16x32_bf16 v[94:97], v[178:181], v[206:209], v[94:97]
	v_mfma_f32_16x16x32_bf16 v[90:93], v[186:189], v[206:209], v[90:93]
	v_mfma_f32_16x16x32_bf16 v[86:89], v[178:181], v[214:217], v[86:89]
	v_mfma_f32_16x16x32_bf16 v[82:85], v[186:189], v[214:217], v[82:85]
	v_mfma_f32_16x16x32_bf16 v[30:33], v[178:181], v[222:225], v[30:33]
	v_mfma_f32_16x16x32_bf16 v[26:29], v[186:189], v[222:225], v[26:29]
	v_mfma_f32_16x16x32_bf16 v[110:113], v[182:185], v[200:203], v[110:113]
	v_mfma_f32_16x16x32_bf16 v[106:109], v[190:193], v[200:203], v[106:109]
	v_mfma_f32_16x16x32_bf16 v[94:97], v[182:185], v[210:213], v[94:97]
	v_mfma_f32_16x16x32_bf16 v[90:93], v[190:193], v[210:213], v[90:93]
	v_mfma_f32_16x16x32_bf16 v[86:89], v[182:185], v[218:221], v[86:89]
	v_mfma_f32_16x16x32_bf16 v[82:85], v[190:193], v[218:221], v[82:85]
	v_mfma_f32_16x16x32_bf16 v[30:33], v[182:185], v[226:229], v[30:33]
	v_mfma_f32_16x16x32_bf16 v[26:29], v[190:193], v[226:229], v[26:29]
	s_setprio 0
	s_add_i32 s66, s56, s42
	v_lshl_add_u64 v[158:159], s[34:35], 0, v[134:135]
	s_mov_b32 m0, s66
	ds_read_b128 v[196:199], v160 offset:16384
	ds_read_b128 v[200:203], v160 offset:17408
	ds_read_b128 v[206:209], v160 offset:18432
	ds_read_b128 v[210:213], v160 offset:19456
	ds_read_b128 v[214:217], v160 offset:20480
	ds_read_b128 v[218:221], v160 offset:21504
	ds_read_b128 v[222:225], v160 offset:22528
	ds_read_b128 v[226:229], v160 offset:23552
	global_load_lds_dwordx4 v[158:159], off
	s_add_i32 m0, s66, 0x2000
	s_add_u32 s66, s34, 0x100000
	v_lshl_add_u64 v[230:231], s[34:35], 0, v[132:133]
	s_addc_u32 s67, s35, 0
	s_add_i32 s68, s57, s42
	global_load_lds_dwordx4 v[230:231], off
	v_lshl_add_u64 v[232:233], s[66:67], 0, v[134:135]
	s_mov_b32 m0, s68
	v_lshl_add_u64 v[234:235], s[40:41], 0, v[132:133]
	global_load_lds_dwordx4 v[232:233], off
	v_lshl_add_u64 v[232:233], s[66:67], 0, v[132:133]
	s_add_i32 m0, s68, 0x2000
	s_nop 0
	global_load_lds_dwordx4 v[232:233], off
	v_lshl_add_u64 v[232:233], s[40:41], 0, v[134:135]
	s_mov_b32 m0, s8
	s_nop 0
	global_load_lds_dwordx4 v[232:233], off
	s_mov_b32 m0, s15
	s_nop 0
	global_load_lds_dwordx4 v[234:235], off
	s_waitcnt vmcnt(8)
	s_waitcnt lgkmcnt(0)
	s_barrier
	s_setprio 2
	v_mfma_f32_16x16x32_bf16 v[78:81], v[162:165], v[196:199], v[78:81]
	v_mfma_f32_16x16x32_bf16 v[74:77], v[170:173], v[196:199], v[74:77]
	v_mfma_f32_16x16x32_bf16 v[70:73], v[162:165], v[206:209], v[70:73]
	v_mfma_f32_16x16x32_bf16 v[66:69], v[170:173], v[206:209], v[66:69]
	v_mfma_f32_16x16x32_bf16 v[54:57], v[162:165], v[214:217], v[54:57]
	v_mfma_f32_16x16x32_bf16 v[50:53], v[170:173], v[214:217], v[50:53]
	v_mfma_f32_16x16x32_bf16 v[14:17], v[162:165], v[222:225], v[14:17]
	v_mfma_f32_16x16x32_bf16 v[10:13], v[170:173], v[222:225], v[10:13]
	v_mfma_f32_16x16x32_bf16 v[78:81], v[166:169], v[200:203], v[78:81]
	v_mfma_f32_16x16x32_bf16 v[74:77], v[174:177], v[200:203], v[74:77]
	v_mfma_f32_16x16x32_bf16 v[70:73], v[166:169], v[210:213], v[70:73]
	v_mfma_f32_16x16x32_bf16 v[66:69], v[174:177], v[210:213], v[66:69]
	v_mfma_f32_16x16x32_bf16 v[54:57], v[166:169], v[218:221], v[54:57]
	v_mfma_f32_16x16x32_bf16 v[50:53], v[174:177], v[218:221], v[50:53]
	v_mfma_f32_16x16x32_bf16 v[14:17], v[166:169], v[226:229], v[14:17]
	v_mfma_f32_16x16x32_bf16 v[10:13], v[174:177], v[226:229], v[10:13]
	v_mfma_f32_16x16x32_bf16 v[62:65], v[178:181], v[196:199], v[62:65]
	v_mfma_f32_16x16x32_bf16 v[58:61], v[186:189], v[196:199], v[58:61]
	v_mfma_f32_16x16x32_bf16 v[46:49], v[178:181], v[206:209], v[46:49]
	v_mfma_f32_16x16x32_bf16 v[38:41], v[186:189], v[206:209], v[38:41]
	v_mfma_f32_16x16x32_bf16 v[22:25], v[178:181], v[214:217], v[22:25]
	v_mfma_f32_16x16x32_bf16 v[18:21], v[186:189], v[214:217], v[18:21]
	v_mfma_f32_16x16x32_bf16 v[6:9], v[178:181], v[222:225], v[6:9]
	v_mfma_f32_16x16x32_bf16 v[2:5], v[186:189], v[222:225], v[2:5]
	v_mfma_f32_16x16x32_bf16 v[62:65], v[182:185], v[200:203], v[62:65]
	v_mfma_f32_16x16x32_bf16 v[58:61], v[190:193], v[200:203], v[58:61]
	v_mfma_f32_16x16x32_bf16 v[46:49], v[182:185], v[210:213], v[46:49]
	v_mfma_f32_16x16x32_bf16 v[38:41], v[190:193], v[210:213], v[38:41]
	v_mfma_f32_16x16x32_bf16 v[22:25], v[182:185], v[218:221], v[22:25]
	v_mfma_f32_16x16x32_bf16 v[18:21], v[190:193], v[218:221], v[18:21]
	v_mfma_f32_16x16x32_bf16 v[6:9], v[182:185], v[226:229], v[6:9]
	v_mfma_f32_16x16x32_bf16 v[2:5], v[190:193], v[226:229], v[2:5]
	s_setprio 0
	s_add_i32 s66, 0, 0x18000
	v_add_u32_e32 v161, s66, v1
	s_add_i32 s67, 0, 0x1c000
	ds_read_b128 v[162:165], v161
	ds_read_b128 v[166:169], v161 offset:1024
	ds_read_b128 v[170:173], v161 offset:2048
	ds_read_b128 v[174:177], v161 offset:3072
	v_add_u32_e32 v161, s67, v1
	ds_read_b128 v[178:181], v161
	ds_read_b128 v[182:185], v161 offset:1024
	ds_read_b128 v[186:189], v161 offset:2048
	ds_read_b128 v[190:193], v161 offset:3072
	s_add_u32 s40, s40, 0x100000
	s_addc_u32 s41, s41, 0
	s_mov_b32 m0, s46
	v_lshl_add_u64 v[236:237], s[40:41], 0, v[134:135]
	ds_read_b128 v[196:199], v160 offset:32768
	ds_read_b128 v[200:203], v160 offset:33792
	ds_read_b128 v[206:209], v160 offset:34816
	ds_read_b128 v[210:213], v160 offset:35840
	ds_read_b128 v[214:217], v160 offset:36864
	ds_read_b128 v[218:221], v160 offset:37888
	ds_read_b128 v[222:225], v160 offset:38912
	ds_read_b128 v[226:229], v160 offset:39936
	global_load_lds_dwordx4 v[236:237], off
	v_lshl_add_u64 v[236:237], s[40:41], 0, v[132:133]
	s_mov_b32 m0, s47
	s_nop 0
	global_load_lds_dwordx4 v[236:237], off
	s_waitcnt vmcnt(8)
	s_waitcnt lgkmcnt(0)
	s_barrier
	s_setprio 2
	v_mfma_f32_16x16x32_bf16 v[126:129], v[162:165], v[196:199], v[126:129]
	v_mfma_f32_16x16x32_bf16 v[122:125], v[170:173], v[196:199], v[122:125]
	v_mfma_f32_16x16x32_bf16 v[118:121], v[162:165], v[206:209], v[118:121]
	v_mfma_f32_16x16x32_bf16 v[114:117], v[170:173], v[206:209], v[114:117]
	v_mfma_f32_16x16x32_bf16 v[102:105], v[162:165], v[214:217], v[102:105]
	v_mfma_f32_16x16x32_bf16 v[98:101], v[170:173], v[214:217], v[98:101]
	v_mfma_f32_16x16x32_bf16 v[42:45], v[162:165], v[222:225], v[42:45]
	v_mfma_f32_16x16x32_bf16 v[34:37], v[170:173], v[222:225], v[34:37]
	v_mfma_f32_16x16x32_bf16 v[126:129], v[166:169], v[200:203], v[126:129]
	v_mfma_f32_16x16x32_bf16 v[122:125], v[174:177], v[200:203], v[122:125]
	v_mfma_f32_16x16x32_bf16 v[118:121], v[166:169], v[210:213], v[118:121]
	v_mfma_f32_16x16x32_bf16 v[114:117], v[174:177], v[210:213], v[114:117]
	v_mfma_f32_16x16x32_bf16 v[102:105], v[166:169], v[218:221], v[102:105]
	v_mfma_f32_16x16x32_bf16 v[98:101], v[174:177], v[218:221], v[98:101]
	v_mfma_f32_16x16x32_bf16 v[42:45], v[166:169], v[226:229], v[42:45]
	v_mfma_f32_16x16x32_bf16 v[34:37], v[174:177], v[226:229], v[34:37]
	v_mfma_f32_16x16x32_bf16 v[110:113], v[178:181], v[196:199], v[110:113]
	v_mfma_f32_16x16x32_bf16 v[106:109], v[186:189], v[196:199], v[106:109]
	v_mfma_f32_16x16x32_bf16 v[94:97], v[178:181], v[206:209], v[94:97]
	v_mfma_f32_16x16x32_bf16 v[90:93], v[186:189], v[206:209], v[90:93]
	v_mfma_f32_16x16x32_bf16 v[86:89], v[178:181], v[214:217], v[86:89]
	v_mfma_f32_16x16x32_bf16 v[82:85], v[186:189], v[214:217], v[82:85]
	v_mfma_f32_16x16x32_bf16 v[30:33], v[178:181], v[222:225], v[30:33]
	v_mfma_f32_16x16x32_bf16 v[26:29], v[186:189], v[222:225], v[26:29]
	v_mfma_f32_16x16x32_bf16 v[110:113], v[182:185], v[200:203], v[110:113]
	v_mfma_f32_16x16x32_bf16 v[106:109], v[190:193], v[200:203], v[106:109]
	v_mfma_f32_16x16x32_bf16 v[94:97], v[182:185], v[210:213], v[94:97]
	v_mfma_f32_16x16x32_bf16 v[90:93], v[190:193], v[210:213], v[90:93]
	v_mfma_f32_16x16x32_bf16 v[86:89], v[182:185], v[218:221], v[86:89]
	v_mfma_f32_16x16x32_bf16 v[82:85], v[190:193], v[218:221], v[82:85]
	v_mfma_f32_16x16x32_bf16 v[30:33], v[182:185], v[226:229], v[30:33]
	v_mfma_f32_16x16x32_bf16 v[26:29], v[190:193], v[226:229], v[26:29]
	s_setprio 0
	s_add_i32 s40, s66, s42
	v_lshl_add_u64 v[158:159], v[158:159], 0, s[12:13]
	s_mov_b32 m0, s40
	ds_read_b128 v[196:199], v160 offset:49152
	ds_read_b128 v[200:203], v160 offset:50176
	ds_read_b128 v[206:209], v160 offset:51200
	ds_read_b128 v[210:213], v160 offset:52224
	ds_read_b128 v[214:217], v160 offset:53248
	ds_read_b128 v[218:221], v160 offset:54272
	ds_read_b128 v[222:225], v160 offset:55296
	ds_read_b128 v[226:229], v160 offset:56320
	global_load_lds_dwordx4 v[158:159], off
	s_add_i32 m0, s40, 0x2000
	s_add_u32 s34, s34, 0x100080
	v_lshl_add_u64 v[158:159], v[230:231], 0, s[12:13]
	s_addc_u32 s35, s35, 0
	s_add_i32 s40, s67, s42
	global_load_lds_dwordx4 v[158:159], off
	v_lshl_add_u64 v[158:159], s[34:35], 0, v[134:135]
	s_mov_b32 m0, s40
	s_nop 0
	global_load_lds_dwordx4 v[158:159], off
	v_lshl_add_u64 v[158:159], s[34:35], 0, v[132:133]
	s_add_i32 m0, s40, 0x2000
	s_nop 0
	global_load_lds_dwordx4 v[158:159], off
	v_lshl_add_u64 v[158:159], v[232:233], 0, s[12:13]
	s_mov_b32 m0, s52
	s_nop 0
	global_load_lds_dwordx4 v[158:159], off
	v_lshl_add_u64 v[158:159], v[234:235], 0, s[12:13]
	s_mov_b32 m0, s53
	s_nop 0
	global_load_lds_dwordx4 v[158:159], off
	s_waitcnt vmcnt(8)
	s_waitcnt lgkmcnt(0)
	s_barrier
	s_setprio 2
	v_mfma_f32_16x16x32_bf16 v[78:81], v[162:165], v[196:199], v[78:81]
	v_mfma_f32_16x16x32_bf16 v[74:77], v[170:173], v[196:199], v[74:77]
	v_mfma_f32_16x16x32_bf16 v[70:73], v[162:165], v[206:209], v[70:73]
	v_mfma_f32_16x16x32_bf16 v[66:69], v[170:173], v[206:209], v[66:69]
	v_mfma_f32_16x16x32_bf16 v[54:57], v[162:165], v[214:217], v[54:57]
	v_mfma_f32_16x16x32_bf16 v[50:53], v[170:173], v[214:217], v[50:53]
	v_mfma_f32_16x16x32_bf16 v[14:17], v[162:165], v[222:225], v[14:17]
	v_mfma_f32_16x16x32_bf16 v[10:13], v[170:173], v[222:225], v[10:13]
	v_mfma_f32_16x16x32_bf16 v[78:81], v[166:169], v[200:203], v[78:81]
	v_mfma_f32_16x16x32_bf16 v[74:77], v[174:177], v[200:203], v[74:77]
	v_mfma_f32_16x16x32_bf16 v[70:73], v[166:169], v[210:213], v[70:73]
	v_mfma_f32_16x16x32_bf16 v[66:69], v[174:177], v[210:213], v[66:69]
	v_mfma_f32_16x16x32_bf16 v[54:57], v[166:169], v[218:221], v[54:57]
	v_mfma_f32_16x16x32_bf16 v[50:53], v[174:177], v[218:221], v[50:53]
	v_mfma_f32_16x16x32_bf16 v[14:17], v[166:169], v[226:229], v[14:17]
	v_mfma_f32_16x16x32_bf16 v[10:13], v[174:177], v[226:229], v[10:13]
	v_mfma_f32_16x16x32_bf16 v[62:65], v[178:181], v[196:199], v[62:65]
	v_mfma_f32_16x16x32_bf16 v[58:61], v[186:189], v[196:199], v[58:61]
	v_mfma_f32_16x16x32_bf16 v[46:49], v[178:181], v[206:209], v[46:49]
	v_mfma_f32_16x16x32_bf16 v[38:41], v[186:189], v[206:209], v[38:41]
	v_mfma_f32_16x16x32_bf16 v[22:25], v[178:181], v[214:217], v[22:25]
	v_mfma_f32_16x16x32_bf16 v[18:21], v[186:189], v[214:217], v[18:21]
	v_mfma_f32_16x16x32_bf16 v[6:9], v[178:181], v[222:225], v[6:9]
	v_mfma_f32_16x16x32_bf16 v[2:5], v[186:189], v[222:225], v[2:5]
	v_mfma_f32_16x16x32_bf16 v[62:65], v[182:185], v[200:203], v[62:65]
	v_mfma_f32_16x16x32_bf16 v[58:61], v[190:193], v[200:203], v[58:61]
	v_mfma_f32_16x16x32_bf16 v[46:49], v[182:185], v[210:213], v[46:49]
	v_mfma_f32_16x16x32_bf16 v[38:41], v[190:193], v[210:213], v[38:41]
	v_mfma_f32_16x16x32_bf16 v[22:25], v[182:185], v[218:221], v[22:25]
	v_mfma_f32_16x16x32_bf16 v[18:21], v[190:193], v[218:221], v[18:21]
	v_mfma_f32_16x16x32_bf16 v[6:9], v[182:185], v[226:229], v[6:9]
	v_mfma_f32_16x16x32_bf16 v[2:5], v[190:193], v[226:229], v[2:5]
	s_setprio 0
	s_add_u32 s30, s30, 0x100
	s_addc_u32 s31, s31, 0
	s_add_u32 s63, s63, 0x100
	s_addc_u32 s64, s64, 0
	s_cmp_ge_i32 s65, s60
	s_mov_b32 s34, s65
	s_cbranch_scc0 .Lkt_T_8
	s_nop 7

.LBB0_1205:
	v_ashrrev_i32_e32 v19, 31, v18
	v_lshl_add_u64 v[20:21], v[158:159], 2, s[30:31]
	v_lshlrev_b64 v[18:19], 11, v[18:19]
	v_lshl_add_u64 v[18:19], v[20:21], 0, v[18:19]
	s_andn2_b64 vcc, exec, s[6:7]
	s_mov_b64 s[6:7], -1
	global_store_dwordx4 v[18:19], v[14:17], off
	global_store_dwordx4 v[18:19], v[10:13], off offset:64
	global_store_dwordx4 v[18:19], v[6:9], off offset:512
	global_store_dwordx4 v[18:19], v[2:5], off offset:576
	s_cbranch_vccnz .LBB0_1193
	s_andn2_b64 vcc, exec, s[10:11]
	s_cbranch_vccnz .LBB0_1192
	s_branch .LBB0_1192

.LBB0_1374:
	s_add_u32 s14, s38, 0x31800000
	s_addc_u32 s15, s39, 0
	s_add_u32 s16, s38, 0x39c00000
	s_addc_u32 s17, s39, 0
	s_add_u32 s67, s38, 0x50600000
	s_addc_u32 s68, s39, 0
	s_lshl_b32 s6, s9, 5
	s_mov_b64 s[18:19], 0x80
	s_and_b32 s9, s6, 0x60
	s_add_i32 m0, s57, 0x18000
	v_lshl_add_u64 v[8:9], v[8:9], 0, s[18:19]
	s_lshl_b32 s21, s8, 13
	s_lshl_b32 s22, s9, 7
	s_ashr_i32 s69, s2, 31
	s_waitcnt vmcnt(2)
	s_barrier
	global_load_lds_dwordx4 v[8:9], off
	v_lshl_add_u64 v[6:7], v[6:7], 0, s[18:19]
	s_add_i32 m0, s57, 0x1a000
	s_add_i32 s70, s57, 0x8000
	s_add_i32 s71, s57, 0xa000
	global_load_lds_dwordx4 v[6:7], off
	v_lshl_add_u64 v[2:3], v[2:3], 0, s[18:19]
	s_mov_b32 m0, s70
	s_add_u32 s6, s48, 0x20080
	global_load_lds_dwordx4 v[2:3], off
	v_lshl_add_u64 v[2:3], v[4:5], 0, s[18:19]
	s_mov_b32 m0, s71
	s_addc_u32 s7, s49, 0
	global_load_lds_dwordx4 v[2:3], off
	s_add_i32 m0, s57, 0x1c000
	v_lshl_add_u64 v[2:3], s[6:7], 0, v[134:135]
	global_load_lds_dwordx4 v[2:3], off
	v_lshl_add_u64 v[2:3], s[6:7], 0, v[138:139]
	s_add_i32 m0, s57, 0x1e000
	v_lshlrev_b32_e32 v4, 2, v0
	global_load_lds_dwordx4 v[2:3], off
	v_and_b32_e32 v2, 15, v0
	v_lshlrev_b32_e32 v3, 1, v13
	v_lshlrev_b32_e32 v5, 6, v0
	s_movk_i32 s6, 0x3c0
	v_lshl_or_b32 v1, s8, 6, v2
	v_lshl_or_b32 v2, v2, 6, v3
	v_and_b32_e32 v4, 32, v4
	v_and_or_b32 v3, v5, s6, v3
	v_bitop3_b32 v131, s22, v3, v4 bitop3:0xf6
	v_lshlrev_b32_e32 v3, 7, v0
	v_bitop3_b32 v2, v2, s21, v4 bitop3:0xde
	v_and_b32_e32 v3, 0xc000, v3
	v_lshlrev_b32_e32 v4, 10, v12
	v_or3_b32 v3, v10, v3, v4
	v_add_u32_e32 v140, v3, v11
	v_lshlrev_b32_e32 v3, 3, v14
	s_waitcnt vmcnt(6)
	s_cmpk_lt_u32 s20, 0x100
	v_and_b32_e32 v3, 0x1c000, v3
	s_cselect_b64 s[20:21], -1, 0
	v_or3_b32 v3, v10, v3, v4
	s_add_i32 s73, 0, 0x10000
	s_add_i32 s74, 0, 0x14000
	s_mov_b32 s22, 0xf8040000
	s_mov_b32 s24, 0xf8080000
	s_mov_b32 s26, 0xf80c0000
	s_ashr_i32 s72, s44, 31
	v_or_b32_e32 v158, s9, v13
	v_mov_b32_e32 v141, v135
	v_add_u32_e32 v142, v3, v11
	v_mov_b32_e32 v143, v135
	v_mov_b64_e32 v[144:145], 0x240
	v_mov_b64_e32 v[146:147], 0x23f
	v_add_u32_e32 v159, s73, v131
	v_add_u32_e32 v160, s74, v131
	v_add_u32_e32 v161, 0, v2
	s_brev_b32 s75, 31
	s_mov_b32 s23, -1
	s_mov_b32 s76, 0xf8040000
	s_mov_b32 s25, -1
	s_mov_b32 s77, 0xf8080000
	s_mov_b32 s27, -1
	s_mov_b32 s28, 0x3fb504f3
	s_mov_b64 s[30:31], 0x100000
	s_mov_b64 s[34:35], 0x120000
	s_mov_b64 s[40:41], 0x140000
	s_mov_b64 s[42:43], 0x160000
	v_mov_b64_e32 v[148:149], 0x1ff
	v_mov_b64_e32 v[150:151], 0x200
	s_mov_b32 s78, s11
	s_branch .LBB0_1377

.LBB0_1391:
	s_and_b64 vcc, exec, s[20:21]
	s_cbranch_vccz .Lkt_T_9
.Lkt_L_9:
	ds_read_b128 v[152:155], v159
	ds_read_b128 v[162:165], v159 offset:1024
	ds_read_b128 v[166:169], v159 offset:2048
	ds_read_b128 v[170:173], v159 offset:3072
	ds_read_b128 v[174:177], v160
	ds_read_b128 v[178:181], v160 offset:1024
	ds_read_b128 v[182:185], v160 offset:2048
	ds_read_b128 v[186:189], v160 offset:3072
	s_add_i32 s82, s48, 2
	s_add_u32 s49, s60, 0xfffe0080
	s_addc_u32 s62, s61, -1
	s_cmp_eq_u32 s47, s48
	s_cselect_b32 s48, s54, s51
	s_cselect_b32 s63, s9, s62
	s_cselect_b32 s62, s8, s49
	s_cselect_b32 s49, s55, s53
	v_lshl_add_u64 v[156:157], s[60:61], 0, v[140:141]
	s_add_i32 m0, s57, 0xc000
	ds_read_b128 v[190:193], v161
	ds_read_b128 v[196:199], v161 offset:1024
	ds_read_b128 v[200:203], v161 offset:2048
	ds_read_b128 v[206:209], v161 offset:3072
	ds_read_b128 v[210:213], v161 offset:4096
	ds_read_b128 v[214:217], v161 offset:5120
	ds_read_b128 v[218:221], v161 offset:6144
	ds_read_b128 v[222:225], v161 offset:7168
	global_load_lds_dwordx4 v[156:157], off
	v_lshl_add_u64 v[156:157], s[60:61], 0, v[142:143]
	s_add_i32 m0, s57, 0xe000
	s_nop 0
	global_load_lds_dwordx4 v[156:157], off
	s_waitcnt lgkmcnt(0)
	s_setprio 1
	v_mfma_f32_16x16x32_bf16 v[126:129], v[152:155], v[190:193], v[126:129]
	v_mfma_f32_16x16x32_bf16 v[122:125], v[166:169], v[190:193], v[122:125]
	v_mfma_f32_16x16x32_bf16 v[110:113], v[152:155], v[200:203], v[110:113]
	v_mfma_f32_16x16x32_bf16 v[106:109], v[166:169], v[200:203], v[106:109]
	v_mfma_f32_16x16x32_bf16 v[94:97], v[152:155], v[210:213], v[94:97]
	v_mfma_f32_16x16x32_bf16 v[90:93], v[166:169], v[210:213], v[90:93]
	v_mfma_f32_16x16x32_bf16 v[78:81], v[152:155], v[218:221], v[78:81]
	v_mfma_f32_16x16x32_bf16 v[74:77], v[166:169], v[218:221], v[74:77]
	v_mfma_f32_16x16x32_bf16 v[126:129], v[162:165], v[196:199], v[126:129]
	v_mfma_f32_16x16x32_bf16 v[122:125], v[170:173], v[196:199], v[122:125]
	v_mfma_f32_16x16x32_bf16 v[110:113], v[162:165], v[206:209], v[110:113]
	v_mfma_f32_16x16x32_bf16 v[106:109], v[170:173], v[206:209], v[106:109]
	v_mfma_f32_16x16x32_bf16 v[94:97], v[162:165], v[214:217], v[94:97]
	v_mfma_f32_16x16x32_bf16 v[90:93], v[170:173], v[214:217], v[90:93]
	v_mfma_f32_16x16x32_bf16 v[78:81], v[162:165], v[222:225], v[78:81]
	v_mfma_f32_16x16x32_bf16 v[74:77], v[170:173], v[222:225], v[74:77]
	v_mfma_f32_16x16x32_bf16 v[118:121], v[174:177], v[190:193], v[118:121]
	v_mfma_f32_16x16x32_bf16 v[114:117], v[182:185], v[190:193], v[114:117]
	v_mfma_f32_16x16x32_bf16 v[102:105], v[174:177], v[200:203], v[102:105]
	v_mfma_f32_16x16x32_bf16 v[98:101], v[182:185], v[200:203], v[98:101]
	v_mfma_f32_16x16x32_bf16 v[86:89], v[174:177], v[210:213], v[86:89]
	v_mfma_f32_16x16x32_bf16 v[82:85], v[182:185], v[210:213], v[82:85]
	v_mfma_f32_16x16x32_bf16 v[70:73], v[174:177], v[218:221], v[70:73]
	v_mfma_f32_16x16x32_bf16 v[66:69], v[182:185], v[218:221], v[66:69]
	v_mfma_f32_16x16x32_bf16 v[118:121], v[178:181], v[196:199], v[118:121]
	v_mfma_f32_16x16x32_bf16 v[114:117], v[186:189], v[196:199], v[114:117]
	v_mfma_f32_16x16x32_bf16 v[102:105], v[178:181], v[206:209], v[102:105]
	v_mfma_f32_16x16x32_bf16 v[98:101], v[186:189], v[206:209], v[98:101]
	v_mfma_f32_16x16x32_bf16 v[86:89], v[178:181], v[214:217], v[86:89]
	v_mfma_f32_16x16x32_bf16 v[82:85], v[186:189], v[214:217], v[82:85]
	v_mfma_f32_16x16x32_bf16 v[70:73], v[178:181], v[222:225], v[70:73]
	v_mfma_f32_16x16x32_bf16 v[66:69], v[186:189], v[222:225], v[66:69]
	s_setprio 0
	s_waitcnt vmcnt(8)
	s_barrier
	s_add_i32 s83, s73, s64
	v_lshl_add_u64 v[156:157], s[48:49], 0, v[134:135]
	s_mov_b32 m0, s83
	ds_read_b128 v[190:193], v161 offset:16384
	ds_read_b128 v[196:199], v161 offset:17408
	ds_read_b128 v[200:203], v161 offset:18432
	ds_read_b128 v[206:209], v161 offset:19456
	ds_read_b128 v[210:213], v161 offset:20480
	ds_read_b128 v[214:217], v161 offset:21504
	ds_read_b128 v[218:221], v161 offset:22528
	ds_read_b128 v[222:225], v161 offset:23552
	global_load_lds_dwordx4 v[156:157], off
	s_add_i32 m0, s83, 0x2000
	s_add_u32 s84, s48, 0x20000
	v_lshl_add_u64 v[226:227], s[48:49], 0, v[138:139]
	s_addc_u32 s85, s49, 0
	s_add_i32 s83, s74, s64
	global_load_lds_dwordx4 v[226:227], off
	v_lshl_add_u64 v[228:229], s[84:85], 0, v[134:135]
	s_mov_b32 m0, s83
	v_lshl_add_u64 v[230:231], s[62:63], 0, v[136:137]
	global_load_lds_dwordx4 v[228:229], off
	v_lshl_add_u64 v[228:229], s[84:85], 0, v[138:139]
	s_add_i32 m0, s83, 0x2000
	s_nop 0
	global_load_lds_dwordx4 v[228:229], off
	v_lshl_add_u64 v[228:229], s[62:63], 0, v[132:133]
	s_mov_b32 m0, s57
	s_nop 0
	global_load_lds_dwordx4 v[228:229], off
	s_mov_b32 m0, s59
	s_nop 0
	global_load_lds_dwordx4 v[230:231], off
	s_waitcnt lgkmcnt(0)
	s_setprio 1
	v_mfma_f32_16x16x32_bf16 v[62:65], v[152:155], v[190:193], v[62:65]
	v_mfma_f32_16x16x32_bf16 v[58:61], v[166:169], v[190:193], v[58:61]
	v_mfma_f32_16x16x32_bf16 v[46:49], v[152:155], v[200:203], v[46:49]
	v_mfma_f32_16x16x32_bf16 v[42:45], v[166:169], v[200:203], v[42:45]
	v_mfma_f32_16x16x32_bf16 v[30:33], v[152:155], v[210:213], v[30:33]
	v_mfma_f32_16x16x32_bf16 v[26:29], v[166:169], v[210:213], v[26:29]
	v_mfma_f32_16x16x32_bf16 v[14:17], v[152:155], v[218:221], v[14:17]
	v_mfma_f32_16x16x32_bf16 v[10:13], v[166:169], v[218:221], v[10:13]
	v_mfma_f32_16x16x32_bf16 v[62:65], v[162:165], v[196:199], v[62:65]
	v_mfma_f32_16x16x32_bf16 v[58:61], v[170:173], v[196:199], v[58:61]
	v_mfma_f32_16x16x32_bf16 v[46:49], v[162:165], v[206:209], v[46:49]
	v_mfma_f32_16x16x32_bf16 v[42:45], v[170:173], v[206:209], v[42:45]
	v_mfma_f32_16x16x32_bf16 v[30:33], v[162:165], v[214:217], v[30:33]
	v_mfma_f32_16x16x32_bf16 v[26:29], v[170:173], v[214:217], v[26:29]
	v_mfma_f32_16x16x32_bf16 v[14:17], v[162:165], v[222:225], v[14:17]
	v_mfma_f32_16x16x32_bf16 v[10:13], v[170:173], v[222:225], v[10:13]
	v_mfma_f32_16x16x32_bf16 v[54:57], v[174:177], v[190:193], v[54:57]
	v_mfma_f32_16x16x32_bf16 v[50:53], v[182:185], v[190:193], v[50:53]
	v_mfma_f32_16x16x32_bf16 v[38:41], v[174:177], v[200:203], v[38:41]
	v_mfma_f32_16x16x32_bf16 v[34:37], v[182:185], v[200:203], v[34:37]
	v_mfma_f32_16x16x32_bf16 v[22:25], v[174:177], v[210:213], v[22:25]
	v_mfma_f32_16x16x32_bf16 v[18:21], v[182:185], v[210:213], v[18:21]
	v_mfma_f32_16x16x32_bf16 v[6:9], v[174:177], v[218:221], v[6:9]
	v_mfma_f32_16x16x32_bf16 v[2:5], v[182:185], v[218:221], v[2:5]
	v_mfma_f32_16x16x32_bf16 v[54:57], v[178:181], v[196:199], v[54:57]
	v_mfma_f32_16x16x32_bf16 v[50:53], v[186:189], v[196:199], v[50:53]
	v_mfma_f32_16x16x32_bf16 v[38:41], v[178:181], v[206:209], v[38:41]
	v_mfma_f32_16x16x32_bf16 v[34:37], v[186:189], v[206:209], v[34:37]
	v_mfma_f32_16x16x32_bf16 v[22:25], v[178:181], v[214:217], v[22:25]
	v_mfma_f32_16x16x32_bf16 v[18:21], v[186:189], v[214:217], v[18:21]
	v_mfma_f32_16x16x32_bf16 v[6:9], v[178:181], v[222:225], v[6:9]
	v_mfma_f32_16x16x32_bf16 v[2:5], v[186:189], v[222:225], v[2:5]
	s_setprio 0
	s_waitcnt vmcnt(8)
	s_barrier
	s_add_i32 s83, 0, 0x18000
	s_add_i32 s84, 0, 0x1c000
	v_add_u32_e32 v170, s83, v131
	v_add_u32_e32 v186, s84, v131
	ds_read_b128 v[152:155], v170
	ds_read_b128 v[162:165], v170 offset:1024
	ds_read_b128 v[166:169], v170 offset:2048
	ds_read_b128 v[170:173], v170 offset:3072
	ds_read_b128 v[174:177], v186
	ds_read_b128 v[178:181], v186 offset:1024
	ds_read_b128 v[182:185], v186 offset:2048
	ds_read_b128 v[186:189], v186 offset:3072
	s_add_u32 s62, s62, 0x20000
	s_addc_u32 s63, s63, 0
	s_mov_b32 m0, s65
	v_lshl_add_u64 v[232:233], s[62:63], 0, v[132:133]
	ds_read_b128 v[190:193], v161 offset:32768
	ds_read_b128 v[196:199], v161 offset:33792
	ds_read_b128 v[200:203], v161 offset:34816
	ds_read_b128 v[206:209], v161 offset:35840
	ds_read_b128 v[210:213], v161 offset:36864
	ds_read_b128 v[214:217], v161 offset:37888
	ds_read_b128 v[218:221], v161 offset:38912
	ds_read_b128 v[222:225], v161 offset:39936
	global_load_lds_dwordx4 v[232:233], off
	v_lshl_add_u64 v[232:233], s[62:63], 0, v[136:137]
	s_mov_b32 m0, s66
	s_nop 0
	global_load_lds_dwordx4 v[232:233], off
	s_waitcnt lgkmcnt(0)
	s_setprio 1
	v_mfma_f32_16x16x32_bf16 v[126:129], v[152:155], v[190:193], v[126:129]
	v_mfma_f32_16x16x32_bf16 v[122:125], v[166:169], v[190:193], v[122:125]
	v_mfma_f32_16x16x32_bf16 v[110:113], v[152:155], v[200:203], v[110:113]
	v_mfma_f32_16x16x32_bf16 v[106:109], v[166:169], v[200:203], v[106:109]
	v_mfma_f32_16x16x32_bf16 v[94:97], v[152:155], v[210:213], v[94:97]
	v_mfma_f32_16x16x32_bf16 v[90:93], v[166:169], v[210:213], v[90:93]
	v_mfma_f32_16x16x32_bf16 v[78:81], v[152:155], v[218:221], v[78:81]
	v_mfma_f32_16x16x32_bf16 v[74:77], v[166:169], v[218:221], v[74:77]
	v_mfma_f32_16x16x32_bf16 v[126:129], v[162:165], v[196:199], v[126:129]
	v_mfma_f32_16x16x32_bf16 v[122:125], v[170:173], v[196:199], v[122:125]
	v_mfma_f32_16x16x32_bf16 v[110:113], v[162:165], v[206:209], v[110:113]
	v_mfma_f32_16x16x32_bf16 v[106:109], v[170:173], v[206:209], v[106:109]
	v_mfma_f32_16x16x32_bf16 v[94:97], v[162:165], v[214:217], v[94:97]
	v_mfma_f32_16x16x32_bf16 v[90:93], v[170:173], v[214:217], v[90:93]
	v_mfma_f32_16x16x32_bf16 v[78:81], v[162:165], v[222:225], v[78:81]
	v_mfma_f32_16x16x32_bf16 v[74:77], v[170:173], v[222:225], v[74:77]
	v_mfma_f32_16x16x32_bf16 v[118:121], v[174:177], v[190:193], v[118:121]
	v_mfma_f32_16x16x32_bf16 v[114:117], v[182:185], v[190:193], v[114:117]
	v_mfma_f32_16x16x32_bf16 v[102:105], v[174:177], v[200:203], v[102:105]
	v_mfma_f32_16x16x32_bf16 v[98:101], v[182:185], v[200:203], v[98:101]
	v_mfma_f32_16x16x32_bf16 v[86:89], v[174:177], v[210:213], v[86:89]
	v_mfma_f32_16x16x32_bf16 v[82:85], v[182:185], v[210:213], v[82:85]
	v_mfma_f32_16x16x32_bf16 v[70:73], v[174:177], v[218:221], v[70:73]
	v_mfma_f32_16x16x32_bf16 v[66:69], v[182:185], v[218:221], v[66:69]
	v_mfma_f32_16x16x32_bf16 v[118:121], v[178:181], v[196:199], v[118:121]
	v_mfma_f32_16x16x32_bf16 v[114:117], v[186:189], v[196:199], v[114:117]
	v_mfma_f32_16x16x32_bf16 v[102:105], v[178:181], v[206:209], v[102:105]
	v_mfma_f32_16x16x32_bf16 v[98:101], v[186:189], v[206:209], v[98:101]
	v_mfma_f32_16x16x32_bf16 v[86:89], v[178:181], v[214:217], v[86:89]
	v_mfma_f32_16x16x32_bf16 v[82:85], v[186:189], v[214:217], v[82:85]
	v_mfma_f32_16x16x32_bf16 v[70:73], v[178:181], v[222:225], v[70:73]
	v_mfma_f32_16x16x32_bf16 v[66:69], v[186:189], v[222:225], v[66:69]
	s_setprio 0
	s_waitcnt vmcnt(8)
	s_barrier
	s_add_i32 s62, s83, s64
	v_lshl_add_u64 v[156:157], v[156:157], 0, s[18:19]
	s_mov_b32 m0, s62
	ds_read_b128 v[190:193], v161 offset:49152
	ds_read_b128 v[196:199], v161 offset:50176
	ds_read_b128 v[200:203], v161 offset:51200
	ds_read_b128 v[206:209], v161 offset:52224
	ds_read_b128 v[210:213], v161 offset:53248
	ds_read_b128 v[214:217], v161 offset:54272
	ds_read_b128 v[218:221], v161 offset:55296
	ds_read_b128 v[222:225], v161 offset:56320
	global_load_lds_dwordx4 v[156:157], off
	s_add_i32 m0, s62, 0x2000
	s_add_u32 s48, s48, 0x20080
	v_lshl_add_u64 v[156:157], v[226:227], 0, s[18:19]
	s_addc_u32 s49, s49, 0
	s_add_i32 s62, s84, s64
	global_load_lds_dwordx4 v[156:157], off
	v_lshl_add_u64 v[156:157], s[48:49], 0, v[134:135]
	s_mov_b32 m0, s62
	s_nop 0
	global_load_lds_dwordx4 v[156:157], off
	v_lshl_add_u64 v[156:157], s[48:49], 0, v[138:139]
	s_add_i32 m0, s62, 0x2000
	s_nop 0
	global_load_lds_dwordx4 v[156:157], off
	v_lshl_add_u64 v[156:157], v[228:229], 0, s[18:19]
	s_mov_b32 m0, s70
	s_nop 0
	global_load_lds_dwordx4 v[156:157], off
	v_lshl_add_u64 v[156:157], v[230:231], 0, s[18:19]
	s_mov_b32 m0, s71
	s_nop 0
	global_load_lds_dwordx4 v[156:157], off
	s_waitcnt lgkmcnt(0)
	s_setprio 1
	v_mfma_f32_16x16x32_bf16 v[62:65], v[152:155], v[190:193], v[62:65]
	v_mfma_f32_16x16x32_bf16 v[58:61], v[166:169], v[190:193], v[58:61]
	v_mfma_f32_16x16x32_bf16 v[46:49], v[152:155], v[200:203], v[46:49]
	v_mfma_f32_16x16x32_bf16 v[42:45], v[166:169], v[200:203], v[42:45]
	v_mfma_f32_16x16x32_bf16 v[30:33], v[152:155], v[210:213], v[30:33]
	v_mfma_f32_16x16x32_bf16 v[26:29], v[166:169], v[210:213], v[26:29]
	v_mfma_f32_16x16x32_bf16 v[14:17], v[152:155], v[218:221], v[14:17]
	v_mfma_f32_16x16x32_bf16 v[10:13], v[166:169], v[218:221], v[10:13]
	v_mfma_f32_16x16x32_bf16 v[62:65], v[162:165], v[196:199], v[62:65]
	v_mfma_f32_16x16x32_bf16 v[58:61], v[170:173], v[196:199], v[58:61]
	v_mfma_f32_16x16x32_bf16 v[46:49], v[162:165], v[206:209], v[46:49]
	v_mfma_f32_16x16x32_bf16 v[42:45], v[170:173], v[206:209], v[42:45]
	v_mfma_f32_16x16x32_bf16 v[30:33], v[162:165], v[214:217], v[30:33]
	v_mfma_f32_16x16x32_bf16 v[26:29], v[170:173], v[214:217], v[26:29]
	v_mfma_f32_16x16x32_bf16 v[14:17], v[162:165], v[222:225], v[14:17]
	v_mfma_f32_16x16x32_bf16 v[10:13], v[170:173], v[222:225], v[10:13]
	v_mfma_f32_16x16x32_bf16 v[54:57], v[174:177], v[190:193], v[54:57]
	v_mfma_f32_16x16x32_bf16 v[50:53], v[182:185], v[190:193], v[50:53]
	v_mfma_f32_16x16x32_bf16 v[38:41], v[174:177], v[200:203], v[38:41]
	v_mfma_f32_16x16x32_bf16 v[34:37], v[182:185], v[200:203], v[34:37]
	v_mfma_f32_16x16x32_bf16 v[22:25], v[174:177], v[210:213], v[22:25]
	v_mfma_f32_16x16x32_bf16 v[18:21], v[182:185], v[210:213], v[18:21]
	v_mfma_f32_16x16x32_bf16 v[6:9], v[174:177], v[218:221], v[6:9]
	v_mfma_f32_16x16x32_bf16 v[2:5], v[182:185], v[218:221], v[2:5]
	v_mfma_f32_16x16x32_bf16 v[54:57], v[178:181], v[196:199], v[54:57]
	v_mfma_f32_16x16x32_bf16 v[50:53], v[186:189], v[196:199], v[50:53]
	v_mfma_f32_16x16x32_bf16 v[38:41], v[178:181], v[206:209], v[38:41]
	v_mfma_f32_16x16x32_bf16 v[34:37], v[186:189], v[206:209], v[34:37]
	v_mfma_f32_16x16x32_bf16 v[22:25], v[178:181], v[214:217], v[22:25]
	v_mfma_f32_16x16x32_bf16 v[18:21], v[186:189], v[214:217], v[18:21]
	v_mfma_f32_16x16x32_bf16 v[6:9], v[178:181], v[222:225], v[6:9]
	v_mfma_f32_16x16x32_bf16 v[2:5], v[186:189], v[222:225], v[2:5]
	s_setprio 0
	s_waitcnt vmcnt(8)
	s_barrier
	s_add_u32 s60, s60, 0x100
	s_addc_u32 s61, s61, 0
	s_add_u32 s51, s51, 0x100
	s_addc_u32 s53, s53, 0
	s_cmp_ge_i32 s82, s81
	s_mov_b32 s48, s82
	s_cbranch_scc0 .Lkt_L_9
	s_branch .Lkt_exit_9
.Lkt_T_9:
	ds_read_b128 v[152:155], v159
	ds_read_b128 v[162:165], v159 offset:1024
	ds_read_b128 v[166:169], v159 offset:2048
	ds_read_b128 v[170:173], v159 offset:3072
	ds_read_b128 v[174:177], v160
	ds_read_b128 v[178:181], v160 offset:1024
	ds_read_b128 v[182:185], v160 offset:2048
	ds_read_b128 v[186:189], v160 offset:3072
	s_add_i32 s82, s48, 2
	s_add_u32 s49, s60, 0xfffe0080
	s_addc_u32 s62, s61, -1
	s_cmp_eq_u32 s47, s48
	s_cselect_b32 s48, s54, s51
	s_cselect_b32 s63, s9, s62
	s_cselect_b32 s62, s8, s49
	s_cselect_b32 s49, s55, s53
	v_lshl_add_u64 v[156:157], s[60:61], 0, v[140:141]
	s_add_i32 m0, s57, 0xc000
	ds_read_b128 v[190:193], v161
	ds_read_b128 v[196:199], v161 offset:1024
	ds_read_b128 v[200:203], v161 offset:2048
	ds_read_b128 v[206:209], v161 offset:3072
	ds_read_b128 v[210:213], v161 offset:4096
	ds_read_b128 v[214:217], v161 offset:5120
	ds_read_b128 v[218:221], v161 offset:6144
	ds_read_b128 v[222:225], v161 offset:7168
	global_load_lds_dwordx4 v[156:157], off
	v_lshl_add_u64 v[156:157], s[60:61], 0, v[142:143]
	s_add_i32 m0, s57, 0xe000
	s_nop 0
	global_load_lds_dwordx4 v[156:157], off
	s_waitcnt vmcnt(8)
	s_waitcnt lgkmcnt(0)
	s_barrier
	s_setprio 2
	v_mfma_f32_16x16x32_bf16 v[126:129], v[152:155], v[190:193], v[126:129]
	v_mfma_f32_16x16x32_bf16 v[122:125], v[166:169], v[190:193], v[122:125]
	v_mfma_f32_16x16x32_bf16 v[110:113], v[152:155], v[200:203], v[110:113]
	v_mfma_f32_16x16x32_bf16 v[106:109], v[166:169], v[200:203], v[106:109]
	v_mfma_f32_16x16x32_bf16 v[94:97], v[152:155], v[210:213], v[94:97]
	v_mfma_f32_16x16x32_bf16 v[90:93], v[166:169], v[210:213], v[90:93]
	v_mfma_f32_16x16x32_bf16 v[78:81], v[152:155], v[218:221], v[78:81]
	v_mfma_f32_16x16x32_bf16 v[74:77], v[166:169], v[218:221], v[74:77]
	v_mfma_f32_16x16x32_bf16 v[126:129], v[162:165], v[196:199], v[126:129]
	v_mfma_f32_16x16x32_bf16 v[122:125], v[170:173], v[196:199], v[122:125]
	v_mfma_f32_16x16x32_bf16 v[110:113], v[162:165], v[206:209], v[110:113]
	v_mfma_f32_16x16x32_bf16 v[106:109], v[170:173], v[206:209], v[106:109]
	v_mfma_f32_16x16x32_bf16 v[94:97], v[162:165], v[214:217], v[94:97]
	v_mfma_f32_16x16x32_bf16 v[90:93], v[170:173], v[214:217], v[90:93]
	v_mfma_f32_16x16x32_bf16 v[78:81], v[162:165], v[222:225], v[78:81]
	v_mfma_f32_16x16x32_bf16 v[74:77], v[170:173], v[222:225], v[74:77]
	v_mfma_f32_16x16x32_bf16 v[118:121], v[174:177], v[190:193], v[118:121]
	v_mfma_f32_16x16x32_bf16 v[114:117], v[182:185], v[190:193], v[114:117]
	v_mfma_f32_16x16x32_bf16 v[102:105], v[174:177], v[200:203], v[102:105]
	v_mfma_f32_16x16x32_bf16 v[98:101], v[182:185], v[200:203], v[98:101]
	v_mfma_f32_16x16x32_bf16 v[86:89], v[174:177], v[210:213], v[86:89]
	v_mfma_f32_16x16x32_bf16 v[82:85], v[182:185], v[210:213], v[82:85]
	v_mfma_f32_16x16x32_bf16 v[70:73], v[174:177], v[218:221], v[70:73]
	v_mfma_f32_16x16x32_bf16 v[66:69], v[182:185], v[218:221], v[66:69]
	v_mfma_f32_16x16x32_bf16 v[118:121], v[178:181], v[196:199], v[118:121]
	v_mfma_f32_16x16x32_bf16 v[114:117], v[186:189], v[196:199], v[114:117]
	v_mfma_f32_16x16x32_bf16 v[102:105], v[178:181], v[206:209], v[102:105]
	v_mfma_f32_16x16x32_bf16 v[98:101], v[186:189], v[206:209], v[98:101]
	v_mfma_f32_16x16x32_bf16 v[86:89], v[178:181], v[214:217], v[86:89]
	v_mfma_f32_16x16x32_bf16 v[82:85], v[186:189], v[214:217], v[82:85]
	v_mfma_f32_16x16x32_bf16 v[70:73], v[178:181], v[222:225], v[70:73]
	v_mfma_f32_16x16x32_bf16 v[66:69], v[186:189], v[222:225], v[66:69]
	s_setprio 0
	s_add_i32 s83, s73, s64
	v_lshl_add_u64 v[156:157], s[48:49], 0, v[134:135]
	s_mov_b32 m0, s83
	ds_read_b128 v[190:193], v161 offset:16384
	ds_read_b128 v[196:199], v161 offset:17408
	ds_read_b128 v[200:203], v161 offset:18432
	ds_read_b128 v[206:209], v161 offset:19456
	ds_read_b128 v[210:213], v161 offset:20480
	ds_read_b128 v[214:217], v161 offset:21504
	ds_read_b128 v[218:221], v161 offset:22528
	ds_read_b128 v[222:225], v161 offset:23552
	global_load_lds_dwordx4 v[156:157], off
	s_add_i32 m0, s83, 0x2000
	s_add_u32 s84, s48, 0x20000
	v_lshl_add_u64 v[226:227], s[48:49], 0, v[138:139]
	s_addc_u32 s85, s49, 0
	s_add_i32 s83, s74, s64
	global_load_lds_dwordx4 v[226:227], off
	v_lshl_add_u64 v[228:229], s[84:85], 0, v[134:135]
	s_mov_b32 m0, s83
	v_lshl_add_u64 v[230:231], s[62:63], 0, v[136:137]
	global_load_lds_dwordx4 v[228:229], off
	v_lshl_add_u64 v[228:229], s[84:85], 0, v[138:139]
	s_add_i32 m0, s83, 0x2000
	s_nop 0
	global_load_lds_dwordx4 v[228:229], off
	v_lshl_add_u64 v[228:229], s[62:63], 0, v[132:133]
	s_mov_b32 m0, s57
	s_nop 0
	global_load_lds_dwordx4 v[228:229], off
	s_mov_b32 m0, s59
	s_nop 0
	global_load_lds_dwordx4 v[230:231], off
	s_waitcnt vmcnt(8)
	s_waitcnt lgkmcnt(0)
	s_barrier
	s_setprio 2
	v_mfma_f32_16x16x32_bf16 v[62:65], v[152:155], v[190:193], v[62:65]
	v_mfma_f32_16x16x32_bf16 v[58:61], v[166:169], v[190:193], v[58:61]
	v_mfma_f32_16x16x32_bf16 v[46:49], v[152:155], v[200:203], v[46:49]
	v_mfma_f32_16x16x32_bf16 v[42:45], v[166:169], v[200:203], v[42:45]
	v_mfma_f32_16x16x32_bf16 v[30:33], v[152:155], v[210:213], v[30:33]
	v_mfma_f32_16x16x32_bf16 v[26:29], v[166:169], v[210:213], v[26:29]
	v_mfma_f32_16x16x32_bf16 v[14:17], v[152:155], v[218:221], v[14:17]
	v_mfma_f32_16x16x32_bf16 v[10:13], v[166:169], v[218:221], v[10:13]
	v_mfma_f32_16x16x32_bf16 v[62:65], v[162:165], v[196:199], v[62:65]
	v_mfma_f32_16x16x32_bf16 v[58:61], v[170:173], v[196:199], v[58:61]
	v_mfma_f32_16x16x32_bf16 v[46:49], v[162:165], v[206:209], v[46:49]
	v_mfma_f32_16x16x32_bf16 v[42:45], v[170:173], v[206:209], v[42:45]
	v_mfma_f32_16x16x32_bf16 v[30:33], v[162:165], v[214:217], v[30:33]
	v_mfma_f32_16x16x32_bf16 v[26:29], v[170:173], v[214:217], v[26:29]
	v_mfma_f32_16x16x32_bf16 v[14:17], v[162:165], v[222:225], v[14:17]
	v_mfma_f32_16x16x32_bf16 v[10:13], v[170:173], v[222:225], v[10:13]
	v_mfma_f32_16x16x32_bf16 v[54:57], v[174:177], v[190:193], v[54:57]
	v_mfma_f32_16x16x32_bf16 v[50:53], v[182:185], v[190:193], v[50:53]
	v_mfma_f32_16x16x32_bf16 v[38:41], v[174:177], v[200:203], v[38:41]
	v_mfma_f32_16x16x32_bf16 v[34:37], v[182:185], v[200:203], v[34:37]
	v_mfma_f32_16x16x32_bf16 v[22:25], v[174:177], v[210:213], v[22:25]
	v_mfma_f32_16x16x32_bf16 v[18:21], v[182:185], v[210:213], v[18:21]
	v_mfma_f32_16x16x32_bf16 v[6:9], v[174:177], v[218:221], v[6:9]
	v_mfma_f32_16x16x32_bf16 v[2:5], v[182:185], v[218:221], v[2:5]
	v_mfma_f32_16x16x32_bf16 v[54:57], v[178:181], v[196:199], v[54:57]
	v_mfma_f32_16x16x32_bf16 v[50:53], v[186:189], v[196:199], v[50:53]
	v_mfma_f32_16x16x32_bf16 v[38:41], v[178:181], v[206:209], v[38:41]
	v_mfma_f32_16x16x32_bf16 v[34:37], v[186:189], v[206:209], v[34:37]
	v_mfma_f32_16x16x32_bf16 v[22:25], v[178:181], v[214:217], v[22:25]
	v_mfma_f32_16x16x32_bf16 v[18:21], v[186:189], v[214:217], v[18:21]
	v_mfma_f32_16x16x32_bf16 v[6:9], v[178:181], v[222:225], v[6:9]
	v_mfma_f32_16x16x32_bf16 v[2:5], v[186:189], v[222:225], v[2:5]
	s_setprio 0
	s_add_i32 s83, 0, 0x18000
	s_add_i32 s84, 0, 0x1c000
	v_add_u32_e32 v170, s83, v131
	v_add_u32_e32 v186, s84, v131
	ds_read_b128 v[152:155], v170
	ds_read_b128 v[162:165], v170 offset:1024
	ds_read_b128 v[166:169], v170 offset:2048
	ds_read_b128 v[170:173], v170 offset:3072
	ds_read_b128 v[174:177], v186
	ds_read_b128 v[178:181], v186 offset:1024
	ds_read_b128 v[182:185], v186 offset:2048
	ds_read_b128 v[186:189], v186 offset:3072
	s_add_u32 s62, s62, 0x20000
	s_addc_u32 s63, s63, 0
	s_mov_b32 m0, s65
	v_lshl_add_u64 v[232:233], s[62:63], 0, v[132:133]
	ds_read_b128 v[190:193], v161 offset:32768
	ds_read_b128 v[196:199], v161 offset:33792
	ds_read_b128 v[200:203], v161 offset:34816
	ds_read_b128 v[206:209], v161 offset:35840
	ds_read_b128 v[210:213], v161 offset:36864
	ds_read_b128 v[214:217], v161 offset:37888
	ds_read_b128 v[218:221], v161 offset:38912
	ds_read_b128 v[222:225], v161 offset:39936
	global_load_lds_dwordx4 v[232:233], off
	v_lshl_add_u64 v[232:233], s[62:63], 0, v[136:137]
	s_mov_b32 m0, s66
	s_nop 0
	global_load_lds_dwordx4 v[232:233], off
	s_waitcnt vmcnt(8)
	s_waitcnt lgkmcnt(0)
	s_barrier
	s_setprio 2
	v_mfma_f32_16x16x32_bf16 v[126:129], v[152:155], v[190:193], v[126:129]
	v_mfma_f32_16x16x32_bf16 v[122:125], v[166:169], v[190:193], v[122:125]
	v_mfma_f32_16x16x32_bf16 v[110:113], v[152:155], v[200:203], v[110:113]
	v_mfma_f32_16x16x32_bf16 v[106:109], v[166:169], v[200:203], v[106:109]
	v_mfma_f32_16x16x32_bf16 v[94:97], v[152:155], v[210:213], v[94:97]
	v_mfma_f32_16x16x32_bf16 v[90:93], v[166:169], v[210:213], v[90:93]
	v_mfma_f32_16x16x32_bf16 v[78:81], v[152:155], v[218:221], v[78:81]
	v_mfma_f32_16x16x32_bf16 v[74:77], v[166:169], v[218:221], v[74:77]
	v_mfma_f32_16x16x32_bf16 v[126:129], v[162:165], v[196:199], v[126:129]
	v_mfma_f32_16x16x32_bf16 v[122:125], v[170:173], v[196:199], v[122:125]
	v_mfma_f32_16x16x32_bf16 v[110:113], v[162:165], v[206:209], v[110:113]
	v_mfma_f32_16x16x32_bf16 v[106:109], v[170:173], v[206:209], v[106:109]
	v_mfma_f32_16x16x32_bf16 v[94:97], v[162:165], v[214:217], v[94:97]
	v_mfma_f32_16x16x32_bf16 v[90:93], v[170:173], v[214:217], v[90:93]
	v_mfma_f32_16x16x32_bf16 v[78:81], v[162:165], v[222:225], v[78:81]
	v_mfma_f32_16x16x32_bf16 v[74:77], v[170:173], v[222:225], v[74:77]
	v_mfma_f32_16x16x32_bf16 v[118:121], v[174:177], v[190:193], v[118:121]
	v_mfma_f32_16x16x32_bf16 v[114:117], v[182:185], v[190:193], v[114:117]
	v_mfma_f32_16x16x32_bf16 v[102:105], v[174:177], v[200:203], v[102:105]
	v_mfma_f32_16x16x32_bf16 v[98:101], v[182:185], v[200:203], v[98:101]
	v_mfma_f32_16x16x32_bf16 v[86:89], v[174:177], v[210:213], v[86:89]
	v_mfma_f32_16x16x32_bf16 v[82:85], v[182:185], v[210:213], v[82:85]
	v_mfma_f32_16x16x32_bf16 v[70:73], v[174:177], v[218:221], v[70:73]
	v_mfma_f32_16x16x32_bf16 v[66:69], v[182:185], v[218:221], v[66:69]
	v_mfma_f32_16x16x32_bf16 v[118:121], v[178:181], v[196:199], v[118:121]
	v_mfma_f32_16x16x32_bf16 v[114:117], v[186:189], v[196:199], v[114:117]
	v_mfma_f32_16x16x32_bf16 v[102:105], v[178:181], v[206:209], v[102:105]
	v_mfma_f32_16x16x32_bf16 v[98:101], v[186:189], v[206:209], v[98:101]
	v_mfma_f32_16x16x32_bf16 v[86:89], v[178:181], v[214:217], v[86:89]
	v_mfma_f32_16x16x32_bf16 v[82:85], v[186:189], v[214:217], v[82:85]
	v_mfma_f32_16x16x32_bf16 v[70:73], v[178:181], v[222:225], v[70:73]
	v_mfma_f32_16x16x32_bf16 v[66:69], v[186:189], v[222:225], v[66:69]
	s_setprio 0
	s_add_i32 s62, s83, s64
	v_lshl_add_u64 v[156:157], v[156:157], 0, s[18:19]
	s_mov_b32 m0, s62
	ds_read_b128 v[190:193], v161 offset:49152
	ds_read_b128 v[196:199], v161 offset:50176
	ds_read_b128 v[200:203], v161 offset:51200
	ds_read_b128 v[206:209], v161 offset:52224
	ds_read_b128 v[210:213], v161 offset:53248
	ds_read_b128 v[214:217], v161 offset:54272
	ds_read_b128 v[218:221], v161 offset:55296
	ds_read_b128 v[222:225], v161 offset:56320
	global_load_lds_dwordx4 v[156:157], off
	s_add_i32 m0, s62, 0x2000
	s_add_u32 s48, s48, 0x20080
	v_lshl_add_u64 v[156:157], v[226:227], 0, s[18:19]
	s_addc_u32 s49, s49, 0
	s_add_i32 s62, s84, s64
	global_load_lds_dwordx4 v[156:157], off
	v_lshl_add_u64 v[156:157], s[48:49], 0, v[134:135]
	s_mov_b32 m0, s62
	s_nop 0
	global_load_lds_dwordx4 v[156:157], off
	v_lshl_add_u64 v[156:157], s[48:49], 0, v[138:139]
	s_add_i32 m0, s62, 0x2000
	s_nop 0
	global_load_lds_dwordx4 v[156:157], off
	v_lshl_add_u64 v[156:157], v[228:229], 0, s[18:19]
	s_mov_b32 m0, s70
	s_nop 0
	global_load_lds_dwordx4 v[156:157], off
	v_lshl_add_u64 v[156:157], v[230:231], 0, s[18:19]
	s_mov_b32 m0, s71
	s_nop 0
	global_load_lds_dwordx4 v[156:157], off
	s_waitcnt vmcnt(8)
	s_waitcnt lgkmcnt(0)
	s_barrier
	s_setprio 2
	v_mfma_f32_16x16x32_bf16 v[62:65], v[152:155], v[190:193], v[62:65]
	v_mfma_f32_16x16x32_bf16 v[58:61], v[166:169], v[190:193], v[58:61]
	v_mfma_f32_16x16x32_bf16 v[46:49], v[152:155], v[200:203], v[46:49]
	v_mfma_f32_16x16x32_bf16 v[42:45], v[166:169], v[200:203], v[42:45]
	v_mfma_f32_16x16x32_bf16 v[30:33], v[152:155], v[210:213], v[30:33]
	v_mfma_f32_16x16x32_bf16 v[26:29], v[166:169], v[210:213], v[26:29]
	v_mfma_f32_16x16x32_bf16 v[14:17], v[152:155], v[218:221], v[14:17]
	v_mfma_f32_16x16x32_bf16 v[10:13], v[166:169], v[218:221], v[10:13]
	v_mfma_f32_16x16x32_bf16 v[62:65], v[162:165], v[196:199], v[62:65]
	v_mfma_f32_16x16x32_bf16 v[58:61], v[170:173], v[196:199], v[58:61]
	v_mfma_f32_16x16x32_bf16 v[46:49], v[162:165], v[206:209], v[46:49]
	v_mfma_f32_16x16x32_bf16 v[42:45], v[170:173], v[206:209], v[42:45]
	v_mfma_f32_16x16x32_bf16 v[30:33], v[162:165], v[214:217], v[30:33]
	v_mfma_f32_16x16x32_bf16 v[26:29], v[170:173], v[214:217], v[26:29]
	v_mfma_f32_16x16x32_bf16 v[14:17], v[162:165], v[222:225], v[14:17]
	v_mfma_f32_16x16x32_bf16 v[10:13], v[170:173], v[222:225], v[10:13]
	v_mfma_f32_16x16x32_bf16 v[54:57], v[174:177], v[190:193], v[54:57]
	v_mfma_f32_16x16x32_bf16 v[50:53], v[182:185], v[190:193], v[50:53]
	v_mfma_f32_16x16x32_bf16 v[38:41], v[174:177], v[200:203], v[38:41]
	v_mfma_f32_16x16x32_bf16 v[34:37], v[182:185], v[200:203], v[34:37]
	v_mfma_f32_16x16x32_bf16 v[22:25], v[174:177], v[210:213], v[22:25]
	v_mfma_f32_16x16x32_bf16 v[18:21], v[182:185], v[210:213], v[18:21]
	v_mfma_f32_16x16x32_bf16 v[6:9], v[174:177], v[218:221], v[6:9]
	v_mfma_f32_16x16x32_bf16 v[2:5], v[182:185], v[218:221], v[2:5]
	v_mfma_f32_16x16x32_bf16 v[54:57], v[178:181], v[196:199], v[54:57]
	v_mfma_f32_16x16x32_bf16 v[50:53], v[186:189], v[196:199], v[50:53]
	v_mfma_f32_16x16x32_bf16 v[38:41], v[178:181], v[206:209], v[38:41]
	v_mfma_f32_16x16x32_bf16 v[34:37], v[186:189], v[206:209], v[34:37]
	v_mfma_f32_16x16x32_bf16 v[22:25], v[178:181], v[214:217], v[22:25]
	v_mfma_f32_16x16x32_bf16 v[18:21], v[186:189], v[214:217], v[18:21]
	v_mfma_f32_16x16x32_bf16 v[6:9], v[178:181], v[222:225], v[6:9]
	v_mfma_f32_16x16x32_bf16 v[2:5], v[186:189], v[222:225], v[2:5]
	s_setprio 0
	s_add_u32 s60, s60, 0x100
	s_addc_u32 s61, s61, 0
	s_add_u32 s51, s51, 0x100
	s_addc_u32 s53, s53, 0
	s_cmp_ge_i32 s82, s81
	s_mov_b32 s48, s82
	s_cbranch_scc0 .Lkt_T_9
	s_nop 7

.LBB0_1399:
	s_andn2_b64 vcc, exec, s[12:13]
	s_cbranch_vccnz .LBB0_1375
	s_branch .LBB0_1375

.LBB0_1530:
	s_add_u32 s12, s38, 0x43e00000
	s_addc_u32 s13, s39, 0
	s_add_u32 s57, s38, 0x56600000
	s_addc_u32 s58, s39, 0
	s_lshl_b32 s14, s14, 5
	s_and_b32 s24, s14, 0x60
	s_mov_b64 s[14:15], 0x80
	s_add_i32 m0, s43, 0x18000
	v_lshl_add_u64 v[8:9], v[8:9], 0, s[14:15]
	s_lshl_b32 s20, s17, 13
	s_lshl_b32 s21, s24, 7
	s_waitcnt vmcnt(2)
	s_barrier
	global_load_lds_dwordx4 v[8:9], off
	v_lshl_add_u64 v[6:7], v[6:7], 0, s[14:15]
	s_add_i32 m0, s43, 0x1a000
	s_add_i32 s59, s43, 0x8000
	s_add_i32 s60, s43, 0xa000
	global_load_lds_dwordx4 v[6:7], off
	v_lshl_add_u64 v[2:3], v[2:3], 0, s[14:15]
	s_mov_b32 m0, s59
	s_add_u32 s18, s48, 0x100080
	global_load_lds_dwordx4 v[2:3], off
	v_lshl_add_u64 v[2:3], v[4:5], 0, s[14:15]
	s_mov_b32 m0, s60
	s_addc_u32 s19, s49, 0
	global_load_lds_dwordx4 v[2:3], off
	s_add_i32 m0, s43, 0x1c000
	v_lshl_add_u64 v[2:3], s[18:19], 0, v[134:135]
	global_load_lds_dwordx4 v[2:3], off
	v_lshl_add_u64 v[2:3], s[18:19], 0, v[138:139]
	s_add_i32 m0, s43, 0x1e000
	v_lshlrev_b32_e32 v4, 2, v0
	global_load_lds_dwordx4 v[2:3], off
	v_and_b32_e32 v2, 15, v0
	v_lshl_or_b32 v1, s17, 6, v2
	v_lshlrev_b32_e32 v3, 1, v13
	v_lshlrev_b32_e32 v5, 6, v0
	s_movk_i32 s17, 0x3c0
	v_lshl_or_b32 v2, v2, 6, v3
	v_and_b32_e32 v4, 32, v4
	v_and_or_b32 v3, v5, s17, v3
	v_bitop3_b32 v2, v2, s20, v4 bitop3:0xde
	v_bitop3_b32 v131, s21, v3, v4 bitop3:0xf6
	s_mov_b32 s20, 0x15800
	v_or_b32_e32 v3, 16, v1
	v_mad_u64_u32 v[142:143], s[18:19], v3, s20, 0
	v_or_b32_e32 v3, 32, v1
	v_mad_u64_u32 v[144:145], s[18:19], v3, s20, 0
	v_or_b32_e32 v3, 48, v1
	s_cmpk_lt_u32 s16, 0x100
	v_mad_u64_u32 v[146:147], s[18:19], v3, s20, 0
	v_lshlrev_b32_e32 v3, 10, v0
	s_cselect_b64 s[16:17], -1, 0
	s_ashr_i32 s61, s44, 31
	s_ashr_i32 s62, s2, 31
	v_and_b32_e32 v3, 0x60000, v3
	v_lshlrev_b32_e32 v4, 13, v12
	v_mad_u64_u32 v[140:141], s[18:19], v1, s20, 0
	s_cmpk_gt_i32 s2, 0xbf
	v_or3_b32 v3, v10, v3, v4
	s_cselect_b64 s[18:19], -1, 0
	s_add_i32 s63, s2, 0xfffffcc0
	v_add_u32_e32 v148, v3, v11
	v_lshlrev_b32_e32 v3, 6, v14
	s_waitcnt vmcnt(6)
	s_cmpk_lt_i32 s2, 0x58
	v_and_b32_e32 v3, 0xe0000, v3
	s_cselect_b64 s[20:21], -1, 0
	v_or3_b32 v3, v10, v3, v4
	s_add_i32 s66, 0, 0x10000
	s_add_i32 s67, 0, 0x14000
	s_add_i32 s64, s2, 0x100
	s_add_i32 s22, s2, 0xa00
	v_or_b32_e32 v160, s24, v13
	v_mov_b32_e32 v149, v135
	v_add_u32_e32 v150, v3, v11
	v_mov_b32_e32 v151, v135
	s_movk_i32 s65, 0x159
	v_add_u32_e32 v161, s66, v131
	v_add_u32_e32 v162, s67, v131
	v_add_u32_e32 v163, 0, v2
	s_movk_i32 s68, 0x5600
	v_mov_b64_e32 v[152:153], 0xac0
	v_mov_b64_e32 v[154:155], 0xabf
	s_branch .LBB0_1533

.Lkt_L_10:
	ds_read_b128 v[156:159], v161
	ds_read_b128 v[164:167], v161 offset:1024
	ds_read_b128 v[168:171], v161 offset:2048
	ds_read_b128 v[172:175], v161 offset:3072
	ds_read_b128 v[176:179], v162
	ds_read_b128 v[180:183], v162 offset:1024
	ds_read_b128 v[184:187], v162 offset:2048
	ds_read_b128 v[188:191], v162 offset:3072
	s_add_i32 s76, s48, 2
	s_add_u32 s49, s46, 0xfff00080
	s_addc_u32 s50, s47, -1
	s_cmp_eq_u32 s73, s48
	s_cselect_b32 s48, s29, s74
	s_cselect_b32 s51, s9, s50
	s_cselect_b32 s50, s27, s49
	s_cselect_b32 s49, s25, s75
	v_lshl_add_u64 v[192:193], s[46:47], 0, v[148:149]
	s_add_i32 m0, s43, 0xc000
	ds_read_b128 v[196:199], v163
	ds_read_b128 v[200:203], v163 offset:1024
	ds_read_b128 v[206:209], v163 offset:2048
	ds_read_b128 v[210:213], v163 offset:3072
	ds_read_b128 v[214:217], v163 offset:4096
	ds_read_b128 v[218:221], v163 offset:5120
	ds_read_b128 v[222:225], v163 offset:6144
	ds_read_b128 v[226:229], v163 offset:7168
	global_load_lds_dwordx4 v[192:193], off
	v_lshl_add_u64 v[192:193], s[46:47], 0, v[150:151]
	s_add_i32 m0, s43, 0xe000
	s_nop 0
	global_load_lds_dwordx4 v[192:193], off
	s_waitcnt lgkmcnt(0)
	s_setprio 1
	v_mfma_f32_16x16x32_bf16 v[78:81], v[156:159], v[196:199], v[78:81]
	v_mfma_f32_16x16x32_bf16 v[74:77], v[168:171], v[196:199], v[74:77]
	v_mfma_f32_16x16x32_bf16 v[70:73], v[156:159], v[206:209], v[70:73]
	v_mfma_f32_16x16x32_bf16 v[62:65], v[168:171], v[206:209], v[62:65]
	v_mfma_f32_16x16x32_bf16 v[58:61], v[156:159], v[214:217], v[58:61]
	v_mfma_f32_16x16x32_bf16 v[54:57], v[168:171], v[214:217], v[54:57]
	v_mfma_f32_16x16x32_bf16 v[46:49], v[156:159], v[222:225], v[46:49]
	v_mfma_f32_16x16x32_bf16 v[38:41], v[168:171], v[222:225], v[38:41]
	v_mfma_f32_16x16x32_bf16 v[78:81], v[164:167], v[200:203], v[78:81]
	v_mfma_f32_16x16x32_bf16 v[74:77], v[172:175], v[200:203], v[74:77]
	v_mfma_f32_16x16x32_bf16 v[70:73], v[164:167], v[210:213], v[70:73]
	v_mfma_f32_16x16x32_bf16 v[62:65], v[172:175], v[210:213], v[62:65]
	v_mfma_f32_16x16x32_bf16 v[58:61], v[164:167], v[218:221], v[58:61]
	v_mfma_f32_16x16x32_bf16 v[54:57], v[172:175], v[218:221], v[54:57]
	v_mfma_f32_16x16x32_bf16 v[46:49], v[164:167], v[226:229], v[46:49]
	v_mfma_f32_16x16x32_bf16 v[38:41], v[172:175], v[226:229], v[38:41]
	v_mfma_f32_16x16x32_bf16 v[50:53], v[176:179], v[196:199], v[50:53]
	v_mfma_f32_16x16x32_bf16 v[42:45], v[184:187], v[196:199], v[42:45]
	v_mfma_f32_16x16x32_bf16 v[34:37], v[176:179], v[206:209], v[34:37]
	v_mfma_f32_16x16x32_bf16 v[26:29], v[184:187], v[206:209], v[26:29]
	v_mfma_f32_16x16x32_bf16 v[18:21], v[176:179], v[214:217], v[18:21]
	v_mfma_f32_16x16x32_bf16 v[14:17], v[184:187], v[214:217], v[14:17]
	v_mfma_f32_16x16x32_bf16 v[10:13], v[176:179], v[222:225], v[10:13]
	v_mfma_f32_16x16x32_bf16 v[6:9], v[184:187], v[222:225], v[6:9]
	v_mfma_f32_16x16x32_bf16 v[50:53], v[180:183], v[200:203], v[50:53]
	v_mfma_f32_16x16x32_bf16 v[42:45], v[188:191], v[200:203], v[42:45]
	v_mfma_f32_16x16x32_bf16 v[34:37], v[180:183], v[210:213], v[34:37]
	v_mfma_f32_16x16x32_bf16 v[26:29], v[188:191], v[210:213], v[26:29]
	v_mfma_f32_16x16x32_bf16 v[18:21], v[180:183], v[218:221], v[18:21]
	v_mfma_f32_16x16x32_bf16 v[14:17], v[188:191], v[218:221], v[14:17]
	v_mfma_f32_16x16x32_bf16 v[10:13], v[180:183], v[226:229], v[10:13]
	v_mfma_f32_16x16x32_bf16 v[6:9], v[188:191], v[226:229], v[6:9]
	s_setprio 0
	s_waitcnt vmcnt(8)
	s_barrier
	s_add_i32 s77, s66, s53
	v_lshl_add_u64 v[192:193], s[48:49], 0, v[134:135]
	s_mov_b32 m0, s77
	ds_read_b128 v[196:199], v163 offset:16384
	ds_read_b128 v[200:203], v163 offset:17408
	ds_read_b128 v[206:209], v163 offset:18432
	ds_read_b128 v[210:213], v163 offset:19456
	ds_read_b128 v[214:217], v163 offset:20480
	ds_read_b128 v[218:221], v163 offset:21504
	ds_read_b128 v[222:225], v163 offset:22528
	ds_read_b128 v[226:229], v163 offset:23552
	global_load_lds_dwordx4 v[192:193], off
	s_add_i32 m0, s77, 0x2000
	s_add_u32 s78, s48, 0x100000
	v_lshl_add_u64 v[230:231], s[48:49], 0, v[138:139]
	s_addc_u32 s79, s49, 0
	s_add_i32 s77, s67, s53
	global_load_lds_dwordx4 v[230:231], off
	v_lshl_add_u64 v[232:233], s[78:79], 0, v[134:135]
	s_mov_b32 m0, s77
	v_lshl_add_u64 v[234:235], s[50:51], 0, v[136:137]
	global_load_lds_dwordx4 v[232:233], off
	v_lshl_add_u64 v[232:233], s[78:79], 0, v[138:139]
	s_add_i32 m0, s77, 0x2000
	s_nop 0
	global_load_lds_dwordx4 v[232:233], off
	v_lshl_add_u64 v[232:233], s[50:51], 0, v[132:133]
	s_mov_b32 m0, s43
	s_nop 0
	global_load_lds_dwordx4 v[232:233], off
	s_mov_b32 m0, s54
	s_nop 0
	global_load_lds_dwordx4 v[234:235], off
	s_waitcnt lgkmcnt(0)
	s_setprio 1
	v_mfma_f32_16x16x32_bf16 v[126:129], v[156:159], v[196:199], v[126:129]
	v_mfma_f32_16x16x32_bf16 v[118:121], v[168:171], v[196:199], v[118:121]
	v_mfma_f32_16x16x32_bf16 v[110:113], v[156:159], v[206:209], v[110:113]
	v_mfma_f32_16x16x32_bf16 v[102:105], v[168:171], v[206:209], v[102:105]
	v_mfma_f32_16x16x32_bf16 v[94:97], v[156:159], v[214:217], v[94:97]
	v_mfma_f32_16x16x32_bf16 v[86:89], v[168:171], v[214:217], v[86:89]
	v_mfma_f32_16x16x32_bf16 v[66:69], v[156:159], v[222:225], v[66:69]
	v_mfma_f32_16x16x32_bf16 v[22:25], v[168:171], v[222:225], v[22:25]
	v_mfma_f32_16x16x32_bf16 v[126:129], v[164:167], v[200:203], v[126:129]
	v_mfma_f32_16x16x32_bf16 v[118:121], v[172:175], v[200:203], v[118:121]
	v_mfma_f32_16x16x32_bf16 v[110:113], v[164:167], v[210:213], v[110:113]
	v_mfma_f32_16x16x32_bf16 v[102:105], v[172:175], v[210:213], v[102:105]
	v_mfma_f32_16x16x32_bf16 v[94:97], v[164:167], v[218:221], v[94:97]
	v_mfma_f32_16x16x32_bf16 v[86:89], v[172:175], v[218:221], v[86:89]
	v_mfma_f32_16x16x32_bf16 v[66:69], v[164:167], v[226:229], v[66:69]
	v_mfma_f32_16x16x32_bf16 v[22:25], v[172:175], v[226:229], v[22:25]
	v_mfma_f32_16x16x32_bf16 v[122:125], v[176:179], v[196:199], v[122:125]
	v_mfma_f32_16x16x32_bf16 v[114:117], v[184:187], v[196:199], v[114:117]
	v_mfma_f32_16x16x32_bf16 v[106:109], v[176:179], v[206:209], v[106:109]
	v_mfma_f32_16x16x32_bf16 v[98:101], v[184:187], v[206:209], v[98:101]
	v_mfma_f32_16x16x32_bf16 v[90:93], v[176:179], v[214:217], v[90:93]
	v_mfma_f32_16x16x32_bf16 v[82:85], v[184:187], v[214:217], v[82:85]
	v_mfma_f32_16x16x32_bf16 v[30:33], v[176:179], v[222:225], v[30:33]
	v_mfma_f32_16x16x32_bf16 v[2:5], v[184:187], v[222:225], v[2:5]
	v_mfma_f32_16x16x32_bf16 v[122:125], v[180:183], v[200:203], v[122:125]
	v_mfma_f32_16x16x32_bf16 v[114:117], v[188:191], v[200:203], v[114:117]
	v_mfma_f32_16x16x32_bf16 v[106:109], v[180:183], v[210:213], v[106:109]
	v_mfma_f32_16x16x32_bf16 v[98:101], v[188:191], v[210:213], v[98:101]
	v_mfma_f32_16x16x32_bf16 v[90:93], v[180:183], v[218:221], v[90:93]
	v_mfma_f32_16x16x32_bf16 v[82:85], v[188:191], v[218:221], v[82:85]
	v_mfma_f32_16x16x32_bf16 v[30:33], v[180:183], v[226:229], v[30:33]
	v_mfma_f32_16x16x32_bf16 v[2:5], v[188:191], v[226:229], v[2:5]
	s_setprio 0
	s_waitcnt vmcnt(8)
	s_barrier
	s_add_i32 s77, 0, 0x18000
	s_add_i32 s78, 0, 0x1c000
	v_add_u32_e32 v172, s77, v131
	v_add_u32_e32 v188, s78, v131
	ds_read_b128 v[156:159], v172
	ds_read_b128 v[164:167], v172 offset:1024
	ds_read_b128 v[168:171], v172 offset:2048
	ds_read_b128 v[172:175], v172 offset:3072
	ds_read_b128 v[176:179], v188
	ds_read_b128 v[180:183], v188 offset:1024
	ds_read_b128 v[184:187], v188 offset:2048
	ds_read_b128 v[188:191], v188 offset:3072
	s_add_u32 s50, s50, 0x100000
	s_addc_u32 s51, s51, 0
	s_mov_b32 m0, s55
	v_lshl_add_u64 v[236:237], s[50:51], 0, v[132:133]
	ds_read_b128 v[196:199], v163 offset:32768
	ds_read_b128 v[200:203], v163 offset:33792
	ds_read_b128 v[206:209], v163 offset:34816
	ds_read_b128 v[210:213], v163 offset:35840
	ds_read_b128 v[214:217], v163 offset:36864
	ds_read_b128 v[218:221], v163 offset:37888
	ds_read_b128 v[222:225], v163 offset:38912
	ds_read_b128 v[226:229], v163 offset:39936
	global_load_lds_dwordx4 v[236:237], off
	v_lshl_add_u64 v[236:237], s[50:51], 0, v[136:137]
	s_mov_b32 m0, s56
	s_nop 0
	global_load_lds_dwordx4 v[236:237], off
	s_waitcnt lgkmcnt(0)
	s_setprio 1
	v_mfma_f32_16x16x32_bf16 v[78:81], v[156:159], v[196:199], v[78:81]
	v_mfma_f32_16x16x32_bf16 v[74:77], v[168:171], v[196:199], v[74:77]
	v_mfma_f32_16x16x32_bf16 v[70:73], v[156:159], v[206:209], v[70:73]
	v_mfma_f32_16x16x32_bf16 v[62:65], v[168:171], v[206:209], v[62:65]
	v_mfma_f32_16x16x32_bf16 v[58:61], v[156:159], v[214:217], v[58:61]
	v_mfma_f32_16x16x32_bf16 v[54:57], v[168:171], v[214:217], v[54:57]
	v_mfma_f32_16x16x32_bf16 v[46:49], v[156:159], v[222:225], v[46:49]
	v_mfma_f32_16x16x32_bf16 v[38:41], v[168:171], v[222:225], v[38:41]
	v_mfma_f32_16x16x32_bf16 v[78:81], v[164:167], v[200:203], v[78:81]
	v_mfma_f32_16x16x32_bf16 v[74:77], v[172:175], v[200:203], v[74:77]
	v_mfma_f32_16x16x32_bf16 v[70:73], v[164:167], v[210:213], v[70:73]
	v_mfma_f32_16x16x32_bf16 v[62:65], v[172:175], v[210:213], v[62:65]
	v_mfma_f32_16x16x32_bf16 v[58:61], v[164:167], v[218:221], v[58:61]
	v_mfma_f32_16x16x32_bf16 v[54:57], v[172:175], v[218:221], v[54:57]
	v_mfma_f32_16x16x32_bf16 v[46:49], v[164:167], v[226:229], v[46:49]
	v_mfma_f32_16x16x32_bf16 v[38:41], v[172:175], v[226:229], v[38:41]
	v_mfma_f32_16x16x32_bf16 v[50:53], v[176:179], v[196:199], v[50:53]
	v_mfma_f32_16x16x32_bf16 v[42:45], v[184:187], v[196:199], v[42:45]
	v_mfma_f32_16x16x32_bf16 v[34:37], v[176:179], v[206:209], v[34:37]
	v_mfma_f32_16x16x32_bf16 v[26:29], v[184:187], v[206:209], v[26:29]
	v_mfma_f32_16x16x32_bf16 v[18:21], v[176:179], v[214:217], v[18:21]
	v_mfma_f32_16x16x32_bf16 v[14:17], v[184:187], v[214:217], v[14:17]
	v_mfma_f32_16x16x32_bf16 v[10:13], v[176:179], v[222:225], v[10:13]
	v_mfma_f32_16x16x32_bf16 v[6:9], v[184:187], v[222:225], v[6:9]
	v_mfma_f32_16x16x32_bf16 v[50:53], v[180:183], v[200:203], v[50:53]
	v_mfma_f32_16x16x32_bf16 v[42:45], v[188:191], v[200:203], v[42:45]
	v_mfma_f32_16x16x32_bf16 v[34:37], v[180:183], v[210:213], v[34:37]
	v_mfma_f32_16x16x32_bf16 v[26:29], v[188:191], v[210:213], v[26:29]
	v_mfma_f32_16x16x32_bf16 v[18:21], v[180:183], v[218:221], v[18:21]
	v_mfma_f32_16x16x32_bf16 v[14:17], v[188:191], v[218:221], v[14:17]
	v_mfma_f32_16x16x32_bf16 v[10:13], v[180:183], v[226:229], v[10:13]
	v_mfma_f32_16x16x32_bf16 v[6:9], v[188:191], v[226:229], v[6:9]
	s_setprio 0
	s_waitcnt vmcnt(8)
	s_barrier
	s_add_i32 s50, s77, s53
	v_lshl_add_u64 v[192:193], v[192:193], 0, s[14:15]
	s_mov_b32 m0, s50
	ds_read_b128 v[196:199], v163 offset:49152
	ds_read_b128 v[200:203], v163 offset:50176
	ds_read_b128 v[206:209], v163 offset:51200
	ds_read_b128 v[210:213], v163 offset:52224
	ds_read_b128 v[214:217], v163 offset:53248
	ds_read_b128 v[218:221], v163 offset:54272
	ds_read_b128 v[222:225], v163 offset:55296
	ds_read_b128 v[226:229], v163 offset:56320
	global_load_lds_dwordx4 v[192:193], off
	s_add_i32 m0, s50, 0x2000
	s_add_u32 s48, s48, 0x100080
	v_lshl_add_u64 v[192:193], v[230:231], 0, s[14:15]
	s_addc_u32 s49, s49, 0
	s_add_i32 s50, s78, s53
	global_load_lds_dwordx4 v[192:193], off
	v_lshl_add_u64 v[192:193], s[48:49], 0, v[134:135]
	s_mov_b32 m0, s50
	s_nop 0
	global_load_lds_dwordx4 v[192:193], off
	v_lshl_add_u64 v[192:193], s[48:49], 0, v[138:139]
	s_add_i32 m0, s50, 0x2000
	s_nop 0
	global_load_lds_dwordx4 v[192:193], off
	v_lshl_add_u64 v[192:193], v[232:233], 0, s[14:15]
	s_mov_b32 m0, s59
	s_nop 0
	global_load_lds_dwordx4 v[192:193], off
	v_lshl_add_u64 v[192:193], v[234:235], 0, s[14:15]
	s_mov_b32 m0, s60
	s_nop 0
	global_load_lds_dwordx4 v[192:193], off
	s_waitcnt lgkmcnt(0)
	s_setprio 1
	v_mfma_f32_16x16x32_bf16 v[126:129], v[156:159], v[196:199], v[126:129]
	v_mfma_f32_16x16x32_bf16 v[118:121], v[168:171], v[196:199], v[118:121]
	v_mfma_f32_16x16x32_bf16 v[110:113], v[156:159], v[206:209], v[110:113]
	v_mfma_f32_16x16x32_bf16 v[102:105], v[168:171], v[206:209], v[102:105]
	v_mfma_f32_16x16x32_bf16 v[94:97], v[156:159], v[214:217], v[94:97]
	v_mfma_f32_16x16x32_bf16 v[86:89], v[168:171], v[214:217], v[86:89]
	v_mfma_f32_16x16x32_bf16 v[66:69], v[156:159], v[222:225], v[66:69]
	v_mfma_f32_16x16x32_bf16 v[22:25], v[168:171], v[222:225], v[22:25]
	v_mfma_f32_16x16x32_bf16 v[126:129], v[164:167], v[200:203], v[126:129]
	v_mfma_f32_16x16x32_bf16 v[118:121], v[172:175], v[200:203], v[118:121]
	v_mfma_f32_16x16x32_bf16 v[110:113], v[164:167], v[210:213], v[110:113]
	v_mfma_f32_16x16x32_bf16 v[102:105], v[172:175], v[210:213], v[102:105]
	v_mfma_f32_16x16x32_bf16 v[94:97], v[164:167], v[218:221], v[94:97]
	v_mfma_f32_16x16x32_bf16 v[86:89], v[172:175], v[218:221], v[86:89]
	v_mfma_f32_16x16x32_bf16 v[66:69], v[164:167], v[226:229], v[66:69]
	v_mfma_f32_16x16x32_bf16 v[22:25], v[172:175], v[226:229], v[22:25]
	v_mfma_f32_16x16x32_bf16 v[122:125], v[176:179], v[196:199], v[122:125]
	v_mfma_f32_16x16x32_bf16 v[114:117], v[184:187], v[196:199], v[114:117]
	v_mfma_f32_16x16x32_bf16 v[106:109], v[176:179], v[206:209], v[106:109]
	v_mfma_f32_16x16x32_bf16 v[98:101], v[184:187], v[206:209], v[98:101]
	v_mfma_f32_16x16x32_bf16 v[90:93], v[176:179], v[214:217], v[90:93]
	v_mfma_f32_16x16x32_bf16 v[82:85], v[184:187], v[214:217], v[82:85]
	v_mfma_f32_16x16x32_bf16 v[30:33], v[176:179], v[222:225], v[30:33]
	v_mfma_f32_16x16x32_bf16 v[2:5], v[184:187], v[222:225], v[2:5]
	v_mfma_f32_16x16x32_bf16 v[122:125], v[180:183], v[200:203], v[122:125]
	v_mfma_f32_16x16x32_bf16 v[114:117], v[188:191], v[200:203], v[114:117]
	v_mfma_f32_16x16x32_bf16 v[106:109], v[180:183], v[210:213], v[106:109]
	v_mfma_f32_16x16x32_bf16 v[98:101], v[188:191], v[210:213], v[98:101]
	v_mfma_f32_16x16x32_bf16 v[90:93], v[180:183], v[218:221], v[90:93]
	v_mfma_f32_16x16x32_bf16 v[82:85], v[188:191], v[218:221], v[82:85]
	v_mfma_f32_16x16x32_bf16 v[30:33], v[180:183], v[226:229], v[30:33]
	v_mfma_f32_16x16x32_bf16 v[2:5], v[188:191], v[226:229], v[2:5]
	s_setprio 0
	s_waitcnt vmcnt(8)
	s_barrier
	s_add_u32 s46, s46, 0x100
	s_addc_u32 s47, s47, 0
	s_add_u32 s74, s74, 0x100
	s_addc_u32 s75, s75, 0
	s_cmp_ge_i32 s76, s72
	s_mov_b32 s48, s76
	s_cbranch_scc0 .Lkt_L_10
	s_branch .Lkt_exit_10
.Lkt_T_10:
	ds_read_b128 v[156:159], v161
	ds_read_b128 v[164:167], v161 offset:1024
	ds_read_b128 v[168:171], v161 offset:2048
	ds_read_b128 v[172:175], v161 offset:3072
	ds_read_b128 v[176:179], v162
	ds_read_b128 v[180:183], v162 offset:1024
	ds_read_b128 v[184:187], v162 offset:2048
	ds_read_b128 v[188:191], v162 offset:3072
	s_add_i32 s76, s48, 2
	s_add_u32 s49, s46, 0xfff00080
	s_addc_u32 s50, s47, -1
	s_cmp_eq_u32 s73, s48
	s_cselect_b32 s48, s29, s74
	s_cselect_b32 s51, s9, s50
	s_cselect_b32 s50, s27, s49
	s_cselect_b32 s49, s25, s75
	v_lshl_add_u64 v[192:193], s[46:47], 0, v[148:149]
	s_add_i32 m0, s43, 0xc000
	ds_read_b128 v[196:199], v163
	ds_read_b128 v[200:203], v163 offset:1024
	ds_read_b128 v[206:209], v163 offset:2048
	ds_read_b128 v[210:213], v163 offset:3072
	ds_read_b128 v[214:217], v163 offset:4096
	ds_read_b128 v[218:221], v163 offset:5120
	ds_read_b128 v[222:225], v163 offset:6144
	ds_read_b128 v[226:229], v163 offset:7168
	global_load_lds_dwordx4 v[192:193], off
	v_lshl_add_u64 v[192:193], s[46:47], 0, v[150:151]
	s_add_i32 m0, s43, 0xe000
	s_nop 0
	global_load_lds_dwordx4 v[192:193], off
	s_waitcnt vmcnt(8)
	s_waitcnt lgkmcnt(0)
	s_barrier
	s_setprio 2
	v_mfma_f32_16x16x32_bf16 v[78:81], v[156:159], v[196:199], v[78:81]
	v_mfma_f32_16x16x32_bf16 v[74:77], v[168:171], v[196:199], v[74:77]
	v_mfma_f32_16x16x32_bf16 v[70:73], v[156:159], v[206:209], v[70:73]
	v_mfma_f32_16x16x32_bf16 v[62:65], v[168:171], v[206:209], v[62:65]
	v_mfma_f32_16x16x32_bf16 v[58:61], v[156:159], v[214:217], v[58:61]
	v_mfma_f32_16x16x32_bf16 v[54:57], v[168:171], v[214:217], v[54:57]
	v_mfma_f32_16x16x32_bf16 v[46:49], v[156:159], v[222:225], v[46:49]
	v_mfma_f32_16x16x32_bf16 v[38:41], v[168:171], v[222:225], v[38:41]
	v_mfma_f32_16x16x32_bf16 v[78:81], v[164:167], v[200:203], v[78:81]
	v_mfma_f32_16x16x32_bf16 v[74:77], v[172:175], v[200:203], v[74:77]
	v_mfma_f32_16x16x32_bf16 v[70:73], v[164:167], v[210:213], v[70:73]
	v_mfma_f32_16x16x32_bf16 v[62:65], v[172:175], v[210:213], v[62:65]
	v_mfma_f32_16x16x32_bf16 v[58:61], v[164:167], v[218:221], v[58:61]
	v_mfma_f32_16x16x32_bf16 v[54:57], v[172:175], v[218:221], v[54:57]
	v_mfma_f32_16x16x32_bf16 v[46:49], v[164:167], v[226:229], v[46:49]
	v_mfma_f32_16x16x32_bf16 v[38:41], v[172:175], v[226:229], v[38:41]
	v_mfma_f32_16x16x32_bf16 v[50:53], v[176:179], v[196:199], v[50:53]
	v_mfma_f32_16x16x32_bf16 v[42:45], v[184:187], v[196:199], v[42:45]
	v_mfma_f32_16x16x32_bf16 v[34:37], v[176:179], v[206:209], v[34:37]
	v_mfma_f32_16x16x32_bf16 v[26:29], v[184:187], v[206:209], v[26:29]
	v_mfma_f32_16x16x32_bf16 v[18:21], v[176:179], v[214:217], v[18:21]
	v_mfma_f32_16x16x32_bf16 v[14:17], v[184:187], v[214:217], v[14:17]
	v_mfma_f32_16x16x32_bf16 v[10:13], v[176:179], v[222:225], v[10:13]
	v_mfma_f32_16x16x32_bf16 v[6:9], v[184:187], v[222:225], v[6:9]
	v_mfma_f32_16x16x32_bf16 v[50:53], v[180:183], v[200:203], v[50:53]
	v_mfma_f32_16x16x32_bf16 v[42:45], v[188:191], v[200:203], v[42:45]
	v_mfma_f32_16x16x32_bf16 v[34:37], v[180:183], v[210:213], v[34:37]
	v_mfma_f32_16x16x32_bf16 v[26:29], v[188:191], v[210:213], v[26:29]
	v_mfma_f32_16x16x32_bf16 v[18:21], v[180:183], v[218:221], v[18:21]
	v_mfma_f32_16x16x32_bf16 v[14:17], v[188:191], v[218:221], v[14:17]
	v_mfma_f32_16x16x32_bf16 v[10:13], v[180:183], v[226:229], v[10:13]
	v_mfma_f32_16x16x32_bf16 v[6:9], v[188:191], v[226:229], v[6:9]
	s_setprio 0
	s_add_i32 s77, s66, s53
	v_lshl_add_u64 v[192:193], s[48:49], 0, v[134:135]
	s_mov_b32 m0, s77
	ds_read_b128 v[196:199], v163 offset:16384
	ds_read_b128 v[200:203], v163 offset:17408
	ds_read_b128 v[206:209], v163 offset:18432
	ds_read_b128 v[210:213], v163 offset:19456
	ds_read_b128 v[214:217], v163 offset:20480
	ds_read_b128 v[218:221], v163 offset:21504
	ds_read_b128 v[222:225], v163 offset:22528
	ds_read_b128 v[226:229], v163 offset:23552
	global_load_lds_dwordx4 v[192:193], off
	s_add_i32 m0, s77, 0x2000
	s_add_u32 s78, s48, 0x100000
	v_lshl_add_u64 v[230:231], s[48:49], 0, v[138:139]
	s_addc_u32 s79, s49, 0
	s_add_i32 s77, s67, s53
	global_load_lds_dwordx4 v[230:231], off
	v_lshl_add_u64 v[232:233], s[78:79], 0, v[134:135]
	s_mov_b32 m0, s77
	v_lshl_add_u64 v[234:235], s[50:51], 0, v[136:137]
	global_load_lds_dwordx4 v[232:233], off
	v_lshl_add_u64 v[232:233], s[78:79], 0, v[138:139]
	s_add_i32 m0, s77, 0x2000
	s_nop 0
	global_load_lds_dwordx4 v[232:233], off
	v_lshl_add_u64 v[232:233], s[50:51], 0, v[132:133]
	s_mov_b32 m0, s43
	s_nop 0
	global_load_lds_dwordx4 v[232:233], off
	s_mov_b32 m0, s54
	s_nop 0
	global_load_lds_dwordx4 v[234:235], off
	s_waitcnt vmcnt(8)
	s_waitcnt lgkmcnt(0)
	s_barrier
	s_setprio 2
	v_mfma_f32_16x16x32_bf16 v[126:129], v[156:159], v[196:199], v[126:129]
	v_mfma_f32_16x16x32_bf16 v[118:121], v[168:171], v[196:199], v[118:121]
	v_mfma_f32_16x16x32_bf16 v[110:113], v[156:159], v[206:209], v[110:113]
	v_mfma_f32_16x16x32_bf16 v[102:105], v[168:171], v[206:209], v[102:105]
	v_mfma_f32_16x16x32_bf16 v[94:97], v[156:159], v[214:217], v[94:97]
	v_mfma_f32_16x16x32_bf16 v[86:89], v[168:171], v[214:217], v[86:89]
	v_mfma_f32_16x16x32_bf16 v[66:69], v[156:159], v[222:225], v[66:69]
	v_mfma_f32_16x16x32_bf16 v[22:25], v[168:171], v[222:225], v[22:25]
	v_mfma_f32_16x16x32_bf16 v[126:129], v[164:167], v[200:203], v[126:129]
	v_mfma_f32_16x16x32_bf16 v[118:121], v[172:175], v[200:203], v[118:121]
	v_mfma_f32_16x16x32_bf16 v[110:113], v[164:167], v[210:213], v[110:113]
	v_mfma_f32_16x16x32_bf16 v[102:105], v[172:175], v[210:213], v[102:105]
	v_mfma_f32_16x16x32_bf16 v[94:97], v[164:167], v[218:221], v[94:97]
	v_mfma_f32_16x16x32_bf16 v[86:89], v[172:175], v[218:221], v[86:89]
	v_mfma_f32_16x16x32_bf16 v[66:69], v[164:167], v[226:229], v[66:69]
	v_mfma_f32_16x16x32_bf16 v[22:25], v[172:175], v[226:229], v[22:25]
	v_mfma_f32_16x16x32_bf16 v[122:125], v[176:179], v[196:199], v[122:125]
	v_mfma_f32_16x16x32_bf16 v[114:117], v[184:187], v[196:199], v[114:117]
	v_mfma_f32_16x16x32_bf16 v[106:109], v[176:179], v[206:209], v[106:109]
	v_mfma_f32_16x16x32_bf16 v[98:101], v[184:187], v[206:209], v[98:101]
	v_mfma_f32_16x16x32_bf16 v[90:93], v[176:179], v[214:217], v[90:93]
	v_mfma_f32_16x16x32_bf16 v[82:85], v[184:187], v[214:217], v[82:85]
	v_mfma_f32_16x16x32_bf16 v[30:33], v[176:179], v[222:225], v[30:33]
	v_mfma_f32_16x16x32_bf16 v[2:5], v[184:187], v[222:225], v[2:5]
	v_mfma_f32_16x16x32_bf16 v[122:125], v[180:183], v[200:203], v[122:125]
	v_mfma_f32_16x16x32_bf16 v[114:117], v[188:191], v[200:203], v[114:117]
	v_mfma_f32_16x16x32_bf16 v[106:109], v[180:183], v[210:213], v[106:109]
	v_mfma_f32_16x16x32_bf16 v[98:101], v[188:191], v[210:213], v[98:101]
	v_mfma_f32_16x16x32_bf16 v[90:93], v[180:183], v[218:221], v[90:93]
	v_mfma_f32_16x16x32_bf16 v[82:85], v[188:191], v[218:221], v[82:85]
	v_mfma_f32_16x16x32_bf16 v[30:33], v[180:183], v[226:229], v[30:33]
	v_mfma_f32_16x16x32_bf16 v[2:5], v[188:191], v[226:229], v[2:5]
	s_setprio 0
	s_add_i32 s77, 0, 0x18000
	s_add_i32 s78, 0, 0x1c000
	v_add_u32_e32 v172, s77, v131
	v_add_u32_e32 v188, s78, v131
	ds_read_b128 v[156:159], v172
	ds_read_b128 v[164:167], v172 offset:1024
	ds_read_b128 v[168:171], v172 offset:2048
	ds_read_b128 v[172:175], v172 offset:3072
	ds_read_b128 v[176:179], v188
	ds_read_b128 v[180:183], v188 offset:1024
	ds_read_b128 v[184:187], v188 offset:2048
	ds_read_b128 v[188:191], v188 offset:3072
	s_add_u32 s50, s50, 0x100000
	s_addc_u32 s51, s51, 0
	s_mov_b32 m0, s55
	v_lshl_add_u64 v[236:237], s[50:51], 0, v[132:133]
	ds_read_b128 v[196:199], v163 offset:32768
	ds_read_b128 v[200:203], v163 offset:33792
	ds_read_b128 v[206:209], v163 offset:34816
	ds_read_b128 v[210:213], v163 offset:35840
	ds_read_b128 v[214:217], v163 offset:36864
	ds_read_b128 v[218:221], v163 offset:37888
	ds_read_b128 v[222:225], v163 offset:38912
	ds_read_b128 v[226:229], v163 offset:39936
	global_load_lds_dwordx4 v[236:237], off
	v_lshl_add_u64 v[236:237], s[50:51], 0, v[136:137]
	s_mov_b32 m0, s56
	s_nop 0
	global_load_lds_dwordx4 v[236:237], off
	s_waitcnt vmcnt(8)
	s_waitcnt lgkmcnt(0)
	s_barrier
	s_setprio 2
	v_mfma_f32_16x16x32_bf16 v[78:81], v[156:159], v[196:199], v[78:81]
	v_mfma_f32_16x16x32_bf16 v[74:77], v[168:171], v[196:199], v[74:77]
	v_mfma_f32_16x16x32_bf16 v[70:73], v[156:159], v[206:209], v[70:73]
	v_mfma_f32_16x16x32_bf16 v[62:65], v[168:171], v[206:209], v[62:65]
	v_mfma_f32_16x16x32_bf16 v[58:61], v[156:159], v[214:217], v[58:61]
	v_mfma_f32_16x16x32_bf16 v[54:57], v[168:171], v[214:217], v[54:57]
	v_mfma_f32_16x16x32_bf16 v[46:49], v[156:159], v[222:225], v[46:49]
	v_mfma_f32_16x16x32_bf16 v[38:41], v[168:171], v[222:225], v[38:41]
	v_mfma_f32_16x16x32_bf16 v[78:81], v[164:167], v[200:203], v[78:81]
	v_mfma_f32_16x16x32_bf16 v[74:77], v[172:175], v[200:203], v[74:77]
	v_mfma_f32_16x16x32_bf16 v[70:73], v[164:167], v[210:213], v[70:73]
	v_mfma_f32_16x16x32_bf16 v[62:65], v[172:175], v[210:213], v[62:65]
	v_mfma_f32_16x16x32_bf16 v[58:61], v[164:167], v[218:221], v[58:61]
	v_mfma_f32_16x16x32_bf16 v[54:57], v[172:175], v[218:221], v[54:57]
	v_mfma_f32_16x16x32_bf16 v[46:49], v[164:167], v[226:229], v[46:49]
	v_mfma_f32_16x16x32_bf16 v[38:41], v[172:175], v[226:229], v[38:41]
	v_mfma_f32_16x16x32_bf16 v[50:53], v[176:179], v[196:199], v[50:53]
	v_mfma_f32_16x16x32_bf16 v[42:45], v[184:187], v[196:199], v[42:45]
	v_mfma_f32_16x16x32_bf16 v[34:37], v[176:179], v[206:209], v[34:37]
	v_mfma_f32_16x16x32_bf16 v[26:29], v[184:187], v[206:209], v[26:29]
	v_mfma_f32_16x16x32_bf16 v[18:21], v[176:179], v[214:217], v[18:21]
	v_mfma_f32_16x16x32_bf16 v[14:17], v[184:187], v[214:217], v[14:17]
	v_mfma_f32_16x16x32_bf16 v[10:13], v[176:179], v[222:225], v[10:13]
	v_mfma_f32_16x16x32_bf16 v[6:9], v[184:187], v[222:225], v[6:9]
	v_mfma_f32_16x16x32_bf16 v[50:53], v[180:183], v[200:203], v[50:53]
	v_mfma_f32_16x16x32_bf16 v[42:45], v[188:191], v[200:203], v[42:45]
	v_mfma_f32_16x16x32_bf16 v[34:37], v[180:183], v[210:213], v[34:37]
	v_mfma_f32_16x16x32_bf16 v[26:29], v[188:191], v[210:213], v[26:29]
	v_mfma_f32_16x16x32_bf16 v[18:21], v[180:183], v[218:221], v[18:21]
	v_mfma_f32_16x16x32_bf16 v[14:17], v[188:191], v[218:221], v[14:17]
	v_mfma_f32_16x16x32_bf16 v[10:13], v[180:183], v[226:229], v[10:13]
	v_mfma_f32_16x16x32_bf16 v[6:9], v[188:191], v[226:229], v[6:9]
	s_setprio 0
	s_add_i32 s50, s77, s53
	v_lshl_add_u64 v[192:193], v[192:193], 0, s[14:15]
	s_mov_b32 m0, s50
	ds_read_b128 v[196:199], v163 offset:49152
	ds_read_b128 v[200:203], v163 offset:50176
	ds_read_b128 v[206:209], v163 offset:51200
	ds_read_b128 v[210:213], v163 offset:52224
	ds_read_b128 v[214:217], v163 offset:53248
	ds_read_b128 v[218:221], v163 offset:54272
	ds_read_b128 v[222:225], v163 offset:55296
	ds_read_b128 v[226:229], v163 offset:56320
	global_load_lds_dwordx4 v[192:193], off
	s_add_i32 m0, s50, 0x2000
	s_add_u32 s48, s48, 0x100080
	v_lshl_add_u64 v[192:193], v[230:231], 0, s[14:15]
	s_addc_u32 s49, s49, 0
	s_add_i32 s50, s78, s53
	global_load_lds_dwordx4 v[192:193], off
	v_lshl_add_u64 v[192:193], s[48:49], 0, v[134:135]
	s_mov_b32 m0, s50
	s_nop 0
	global_load_lds_dwordx4 v[192:193], off
	v_lshl_add_u64 v[192:193], s[48:49], 0, v[138:139]
	s_add_i32 m0, s50, 0x2000
	s_nop 0
	global_load_lds_dwordx4 v[192:193], off
	v_lshl_add_u64 v[192:193], v[232:233], 0, s[14:15]
	s_mov_b32 m0, s59
	s_nop 0
	global_load_lds_dwordx4 v[192:193], off
	v_lshl_add_u64 v[192:193], v[234:235], 0, s[14:15]
	s_mov_b32 m0, s60
	s_nop 0
	global_load_lds_dwordx4 v[192:193], off
	s_waitcnt vmcnt(8)
	s_waitcnt lgkmcnt(0)
	s_barrier
	s_setprio 2
	v_mfma_f32_16x16x32_bf16 v[126:129], v[156:159], v[196:199], v[126:129]
	v_mfma_f32_16x16x32_bf16 v[118:121], v[168:171], v[196:199], v[118:121]
	v_mfma_f32_16x16x32_bf16 v[110:113], v[156:159], v[206:209], v[110:113]
	v_mfma_f32_16x16x32_bf16 v[102:105], v[168:171], v[206:209], v[102:105]
	v_mfma_f32_16x16x32_bf16 v[94:97], v[156:159], v[214:217], v[94:97]
	v_mfma_f32_16x16x32_bf16 v[86:89], v[168:171], v[214:217], v[86:89]
	v_mfma_f32_16x16x32_bf16 v[66:69], v[156:159], v[222:225], v[66:69]
	v_mfma_f32_16x16x32_bf16 v[22:25], v[168:171], v[222:225], v[22:25]
	v_mfma_f32_16x16x32_bf16 v[126:129], v[164:167], v[200:203], v[126:129]
	v_mfma_f32_16x16x32_bf16 v[118:121], v[172:175], v[200:203], v[118:121]
	v_mfma_f32_16x16x32_bf16 v[110:113], v[164:167], v[210:213], v[110:113]
	v_mfma_f32_16x16x32_bf16 v[102:105], v[172:175], v[210:213], v[102:105]
	v_mfma_f32_16x16x32_bf16 v[94:97], v[164:167], v[218:221], v[94:97]
	v_mfma_f32_16x16x32_bf16 v[86:89], v[172:175], v[218:221], v[86:89]
	v_mfma_f32_16x16x32_bf16 v[66:69], v[164:167], v[226:229], v[66:69]
	v_mfma_f32_16x16x32_bf16 v[22:25], v[172:175], v[226:229], v[22:25]
	v_mfma_f32_16x16x32_bf16 v[122:125], v[176:179], v[196:199], v[122:125]
	v_mfma_f32_16x16x32_bf16 v[114:117], v[184:187], v[196:199], v[114:117]
	v_mfma_f32_16x16x32_bf16 v[106:109], v[176:179], v[206:209], v[106:109]
	v_mfma_f32_16x16x32_bf16 v[98:101], v[184:187], v[206:209], v[98:101]
	v_mfma_f32_16x16x32_bf16 v[90:93], v[176:179], v[214:217], v[90:93]
	v_mfma_f32_16x16x32_bf16 v[82:85], v[184:187], v[214:217], v[82:85]
	v_mfma_f32_16x16x32_bf16 v[30:33], v[176:179], v[222:225], v[30:33]
	v_mfma_f32_16x16x32_bf16 v[2:5], v[184:187], v[222:225], v[2:5]
	v_mfma_f32_16x16x32_bf16 v[122:125], v[180:183], v[200:203], v[122:125]
	v_mfma_f32_16x16x32_bf16 v[114:117], v[188:191], v[200:203], v[114:117]
	v_mfma_f32_16x16x32_bf16 v[106:109], v[180:183], v[210:213], v[106:109]
	v_mfma_f32_16x16x32_bf16 v[98:101], v[188:191], v[210:213], v[98:101]
	v_mfma_f32_16x16x32_bf16 v[90:93], v[180:183], v[218:221], v[90:93]
	v_mfma_f32_16x16x32_bf16 v[82:85], v[188:191], v[218:221], v[82:85]
	v_mfma_f32_16x16x32_bf16 v[30:33], v[180:183], v[226:229], v[30:33]
	v_mfma_f32_16x16x32_bf16 v[2:5], v[188:191], v[226:229], v[2:5]
	s_setprio 0
	s_add_u32 s46, s46, 0x100
	s_addc_u32 s47, s47, 0
	s_add_u32 s74, s74, 0x100
	s_addc_u32 s75, s75, 0
	s_cmp_ge_i32 s76, s72
	s_mov_b32 s48, s76
	s_cbranch_scc0 .Lkt_T_10
	s_nop 7
.Lkt_exit_10:
	s_and_b64 vcc, exec, s[16:17]
	s_cbranch_vccz .LBB0_1558
	s_cmp_lt_i32 s52, 0
	s_mov_b64 s[46:47], -1
	s_cbranch_scc1 .LBB0_1559

.LBB0_1561:
	s_andn2_b64 vcc, exec, s[10:11]
	s_cbranch_vccnz .LBB0_1531
	s_branch .LBB0_1531

.LBB0_1695:
	s_add_u32 s14, s38, 0x31800000
	s_addc_u32 s15, s39, 0
	s_add_u32 s16, s38, 0x39c00000
	s_addc_u32 s17, s39, 0
	s_add_u32 s61, s38, 0x50600000
	s_addc_u32 s62, s39, 0
	s_lshl_b32 s6, s9, 5
	s_mov_b64 s[18:19], 0x80
	s_and_b32 s9, s6, 0x60
	s_add_i32 m0, s57, 0x18000
	v_lshl_add_u64 v[8:9], v[8:9], 0, s[18:19]
	s_lshl_b32 s21, s8, 13
	s_lshl_b32 s22, s9, 7
	s_ashr_i32 s63, s2, 31
	s_waitcnt vmcnt(2)
	s_barrier
	global_load_lds_dwordx4 v[8:9], off
	v_lshl_add_u64 v[6:7], v[6:7], 0, s[18:19]
	s_add_i32 m0, s57, 0x1a000
	s_add_i32 s64, s57, 0x8000
	s_add_i32 s65, s57, 0xa000
	global_load_lds_dwordx4 v[6:7], off
	v_lshl_add_u64 v[2:3], v[2:3], 0, s[18:19]
	s_mov_b32 m0, s64
	s_add_u32 s6, s48, 0x2b0080
	global_load_lds_dwordx4 v[2:3], off
	v_lshl_add_u64 v[2:3], v[4:5], 0, s[18:19]
	s_mov_b32 m0, s65
	s_addc_u32 s7, s49, 0
	global_load_lds_dwordx4 v[2:3], off
	s_add_i32 m0, s57, 0x1c000
	v_lshl_add_u64 v[2:3], s[6:7], 0, v[134:135]
	global_load_lds_dwordx4 v[2:3], off
	v_lshl_add_u64 v[2:3], s[6:7], 0, v[138:139]
	s_add_i32 m0, s57, 0x1e000
	v_lshlrev_b32_e32 v4, 2, v0
	global_load_lds_dwordx4 v[2:3], off
	v_and_b32_e32 v2, 15, v0
	v_lshlrev_b32_e32 v3, 1, v12
	v_lshlrev_b32_e32 v5, 6, v0
	s_movk_i32 s6, 0x3c0
	v_lshl_or_b32 v131, s8, 6, v2
	v_lshl_or_b32 v2, v2, 6, v3
	v_and_b32_e32 v4, 32, v4
	v_and_or_b32 v3, v5, s6, v3
	v_bitop3_b32 v158, s22, v3, v4 bitop3:0xf6
	s_waitcnt vmcnt(6)
	s_cmpk_lt_u32 s20, 0x100
	v_add_u16_e32 v3, v10, v11
	v_bitop3_b32 v2, v2, s21, v4 bitop3:0xde
	s_cselect_b64 s[20:21], -1, 0
	v_lshrrev_b16_e32 v3, 1, v3
	s_add_i32 s67, 0, 0x10000
	s_add_i32 s68, 0, 0x14000
	s_mov_b32 s22, 0xf8040000
	s_mov_b32 s24, 0xf8080000
	s_mov_b32 s26, 0xf80c0000
	s_ashr_i32 s66, s44, 31
	v_or_b32_e32 v159, s9, v12
	v_add_lshl_u32 v140, v13, v3, 1
	v_mov_b32_e32 v141, v135
	v_add_lshl_u32 v142, v14, v3, 1
	v_mov_b32_e32 v143, v135
	v_mov_b64_e32 v[144:145], 0x300
	v_mov_b64_e32 v[146:147], 0x2ff
	v_add_u32_e32 v160, s67, v158
	v_add_u32_e32 v161, s68, v158
	v_add_u32_e32 v162, 0, v2
	s_brev_b32 s69, 31
	s_mov_b32 s23, -1
	s_mov_b32 s70, 0xf8040000
	s_mov_b32 s25, -1
	s_mov_b32 s71, 0xf8080000
	s_mov_b32 s27, -1
	s_mov_b32 s28, 0x3fb504f3
	s_mov_b64 s[30:31], 0x100000
	s_mov_b64 s[34:35], 0x120000
	s_mov_b64 s[40:41], 0x140000
	s_mov_b64 s[42:43], 0x160000
	v_mov_b64_e32 v[148:149], 0x1ff
	v_mov_b64_e32 v[150:151], 0x200
	s_mov_b32 s72, s11
	s_branch .LBB0_1698

.Lkt_L_11:
	ds_read_b128 v[152:155], v160
	ds_read_b128 v[164:167], v160 offset:1024
	ds_read_b128 v[168:171], v160 offset:2048
	ds_read_b128 v[172:175], v160 offset:3072
	ds_read_b128 v[176:179], v161
	ds_read_b128 v[180:183], v161 offset:1024
	ds_read_b128 v[184:187], v161 offset:2048
	ds_read_b128 v[188:191], v161 offset:3072
	s_add_i32 s82, s48, 2
	s_add_u32 s49, s52, 0xffd50080
	s_addc_u32 s54, s53, -1
	s_cmp_eq_u32 s47, s48
	s_cselect_b32 s48, s50, s80
	s_cselect_b32 s55, s9, s54
	s_cselect_b32 s54, s8, s49
	s_cselect_b32 s49, s51, s81
	v_lshl_add_u64 v[156:157], s[52:53], 0, v[140:141]
	s_add_i32 m0, s57, 0xc000
	ds_read_b128 v[196:199], v162
	ds_read_b128 v[200:203], v162 offset:1024
	ds_read_b128 v[206:209], v162 offset:2048
	ds_read_b128 v[210:213], v162 offset:3072
	ds_read_b128 v[214:217], v162 offset:4096
	ds_read_b128 v[218:221], v162 offset:5120
	ds_read_b128 v[222:225], v162 offset:6144
	ds_read_b128 v[226:229], v162 offset:7168
	global_load_lds_dwordx4 v[156:157], off
	v_lshl_add_u64 v[156:157], s[52:53], 0, v[142:143]
	s_add_i32 m0, s57, 0xe000
	s_nop 0
	global_load_lds_dwordx4 v[156:157], off
	s_waitcnt lgkmcnt(0)
	s_setprio 1
	v_mfma_f32_16x16x32_bf16 v[126:129], v[152:155], v[196:199], v[126:129]
	v_mfma_f32_16x16x32_bf16 v[122:125], v[168:171], v[196:199], v[122:125]
	v_mfma_f32_16x16x32_bf16 v[110:113], v[152:155], v[206:209], v[110:113]
	v_mfma_f32_16x16x32_bf16 v[106:109], v[168:171], v[206:209], v[106:109]
	v_mfma_f32_16x16x32_bf16 v[94:97], v[152:155], v[214:217], v[94:97]
	v_mfma_f32_16x16x32_bf16 v[90:93], v[168:171], v[214:217], v[90:93]
	v_mfma_f32_16x16x32_bf16 v[78:81], v[152:155], v[222:225], v[78:81]
	v_mfma_f32_16x16x32_bf16 v[74:77], v[168:171], v[222:225], v[74:77]
	v_mfma_f32_16x16x32_bf16 v[126:129], v[164:167], v[200:203], v[126:129]
	v_mfma_f32_16x16x32_bf16 v[122:125], v[172:175], v[200:203], v[122:125]
	v_mfma_f32_16x16x32_bf16 v[110:113], v[164:167], v[210:213], v[110:113]
	v_mfma_f32_16x16x32_bf16 v[106:109], v[172:175], v[210:213], v[106:109]
	v_mfma_f32_16x16x32_bf16 v[94:97], v[164:167], v[218:221], v[94:97]
	v_mfma_f32_16x16x32_bf16 v[90:93], v[172:175], v[218:221], v[90:93]
	v_mfma_f32_16x16x32_bf16 v[78:81], v[164:167], v[226:229], v[78:81]
	v_mfma_f32_16x16x32_bf16 v[74:77], v[172:175], v[226:229], v[74:77]
	v_mfma_f32_16x16x32_bf16 v[118:121], v[176:179], v[196:199], v[118:121]
	v_mfma_f32_16x16x32_bf16 v[114:117], v[184:187], v[196:199], v[114:117]
	v_mfma_f32_16x16x32_bf16 v[102:105], v[176:179], v[206:209], v[102:105]
	v_mfma_f32_16x16x32_bf16 v[98:101], v[184:187], v[206:209], v[98:101]
	v_mfma_f32_16x16x32_bf16 v[86:89], v[176:179], v[214:217], v[86:89]
	v_mfma_f32_16x16x32_bf16 v[82:85], v[184:187], v[214:217], v[82:85]
	v_mfma_f32_16x16x32_bf16 v[70:73], v[176:179], v[222:225], v[70:73]
	v_mfma_f32_16x16x32_bf16 v[66:69], v[184:187], v[222:225], v[66:69]
	v_mfma_f32_16x16x32_bf16 v[118:121], v[180:183], v[200:203], v[118:121]
	v_mfma_f32_16x16x32_bf16 v[114:117], v[188:191], v[200:203], v[114:117]
	v_mfma_f32_16x16x32_bf16 v[102:105], v[180:183], v[210:213], v[102:105]
	v_mfma_f32_16x16x32_bf16 v[98:101], v[188:191], v[210:213], v[98:101]
	v_mfma_f32_16x16x32_bf16 v[86:89], v[180:183], v[218:221], v[86:89]
	v_mfma_f32_16x16x32_bf16 v[82:85], v[188:191], v[218:221], v[82:85]
	v_mfma_f32_16x16x32_bf16 v[70:73], v[180:183], v[226:229], v[70:73]
	v_mfma_f32_16x16x32_bf16 v[66:69], v[188:191], v[226:229], v[66:69]
	s_setprio 0
	s_waitcnt vmcnt(8)
	s_barrier
	s_add_i32 s83, s67, s56
	v_lshl_add_u64 v[156:157], s[48:49], 0, v[134:135]
	s_mov_b32 m0, s83
	ds_read_b128 v[196:199], v162 offset:16384
	ds_read_b128 v[200:203], v162 offset:17408
	ds_read_b128 v[206:209], v162 offset:18432
	ds_read_b128 v[210:213], v162 offset:19456
	ds_read_b128 v[214:217], v162 offset:20480
	ds_read_b128 v[218:221], v162 offset:21504
	ds_read_b128 v[222:225], v162 offset:22528
	ds_read_b128 v[226:229], v162 offset:23552
	global_load_lds_dwordx4 v[156:157], off
	s_add_i32 m0, s83, 0x2000
	s_add_u32 s84, s48, 0x2b0000
	v_lshl_add_u64 v[192:193], s[48:49], 0, v[138:139]
	s_addc_u32 s85, s49, 0
	s_add_i32 s83, s68, s56
	global_load_lds_dwordx4 v[192:193], off
	v_lshl_add_u64 v[230:231], s[84:85], 0, v[134:135]
	s_mov_b32 m0, s83
	v_lshl_add_u64 v[232:233], s[54:55], 0, v[136:137]
	global_load_lds_dwordx4 v[230:231], off
	v_lshl_add_u64 v[230:231], s[84:85], 0, v[138:139]
	s_add_i32 m0, s83, 0x2000
	s_nop 0
	global_load_lds_dwordx4 v[230:231], off
	v_lshl_add_u64 v[230:231], s[54:55], 0, v[132:133]
	s_mov_b32 m0, s57
	s_nop 0
	global_load_lds_dwordx4 v[230:231], off
	s_mov_b32 m0, s58
	s_nop 0
	global_load_lds_dwordx4 v[232:233], off
	s_waitcnt lgkmcnt(0)
	s_setprio 1
	v_mfma_f32_16x16x32_bf16 v[62:65], v[152:155], v[196:199], v[62:65]
	v_mfma_f32_16x16x32_bf16 v[58:61], v[168:171], v[196:199], v[58:61]
	v_mfma_f32_16x16x32_bf16 v[46:49], v[152:155], v[206:209], v[46:49]
	v_mfma_f32_16x16x32_bf16 v[42:45], v[168:171], v[206:209], v[42:45]
	v_mfma_f32_16x16x32_bf16 v[30:33], v[152:155], v[214:217], v[30:33]
	v_mfma_f32_16x16x32_bf16 v[26:29], v[168:171], v[214:217], v[26:29]
	v_mfma_f32_16x16x32_bf16 v[14:17], v[152:155], v[222:225], v[14:17]
	v_mfma_f32_16x16x32_bf16 v[10:13], v[168:171], v[222:225], v[10:13]
	v_mfma_f32_16x16x32_bf16 v[62:65], v[164:167], v[200:203], v[62:65]
	v_mfma_f32_16x16x32_bf16 v[58:61], v[172:175], v[200:203], v[58:61]
	v_mfma_f32_16x16x32_bf16 v[46:49], v[164:167], v[210:213], v[46:49]
	v_mfma_f32_16x16x32_bf16 v[42:45], v[172:175], v[210:213], v[42:45]
	v_mfma_f32_16x16x32_bf16 v[30:33], v[164:167], v[218:221], v[30:33]
	v_mfma_f32_16x16x32_bf16 v[26:29], v[172:175], v[218:221], v[26:29]
	v_mfma_f32_16x16x32_bf16 v[14:17], v[164:167], v[226:229], v[14:17]
	v_mfma_f32_16x16x32_bf16 v[10:13], v[172:175], v[226:229], v[10:13]
	v_mfma_f32_16x16x32_bf16 v[54:57], v[176:179], v[196:199], v[54:57]
	v_mfma_f32_16x16x32_bf16 v[50:53], v[184:187], v[196:199], v[50:53]
	v_mfma_f32_16x16x32_bf16 v[38:41], v[176:179], v[206:209], v[38:41]
	v_mfma_f32_16x16x32_bf16 v[34:37], v[184:187], v[206:209], v[34:37]
	v_mfma_f32_16x16x32_bf16 v[22:25], v[176:179], v[214:217], v[22:25]
	v_mfma_f32_16x16x32_bf16 v[18:21], v[184:187], v[214:217], v[18:21]
	v_mfma_f32_16x16x32_bf16 v[6:9], v[176:179], v[222:225], v[6:9]
	v_mfma_f32_16x16x32_bf16 v[2:5], v[184:187], v[222:225], v[2:5]
	v_mfma_f32_16x16x32_bf16 v[54:57], v[180:183], v[200:203], v[54:57]
	v_mfma_f32_16x16x32_bf16 v[50:53], v[188:191], v[200:203], v[50:53]
	v_mfma_f32_16x16x32_bf16 v[38:41], v[180:183], v[210:213], v[38:41]
	v_mfma_f32_16x16x32_bf16 v[34:37], v[188:191], v[210:213], v[34:37]
	v_mfma_f32_16x16x32_bf16 v[22:25], v[180:183], v[218:221], v[22:25]
	v_mfma_f32_16x16x32_bf16 v[18:21], v[188:191], v[218:221], v[18:21]
	v_mfma_f32_16x16x32_bf16 v[6:9], v[180:183], v[226:229], v[6:9]
	v_mfma_f32_16x16x32_bf16 v[2:5], v[188:191], v[226:229], v[2:5]
	s_setprio 0
	s_waitcnt vmcnt(8)
	s_barrier
	s_add_i32 s83, 0, 0x18000
	v_add_u32_e32 v163, s83, v158
	s_add_i32 s84, 0, 0x1c000
	ds_read_b128 v[152:155], v163
	ds_read_b128 v[164:167], v163 offset:1024
	ds_read_b128 v[168:171], v163 offset:2048
	ds_read_b128 v[172:175], v163 offset:3072
	v_add_u32_e32 v163, s84, v158
	ds_read_b128 v[176:179], v163
	ds_read_b128 v[180:183], v163 offset:1024
	ds_read_b128 v[184:187], v163 offset:2048
	ds_read_b128 v[188:191], v163 offset:3072
	s_add_u32 s54, s54, 0x2b0000
	s_addc_u32 s55, s55, 0
	s_mov_b32 m0, s59
	v_lshl_add_u64 v[234:235], s[54:55], 0, v[132:133]
	ds_read_b128 v[196:199], v162 offset:32768
	ds_read_b128 v[200:203], v162 offset:33792
	ds_read_b128 v[206:209], v162 offset:34816
	ds_read_b128 v[210:213], v162 offset:35840
	ds_read_b128 v[214:217], v162 offset:36864
	ds_read_b128 v[218:221], v162 offset:37888
	ds_read_b128 v[222:225], v162 offset:38912
	ds_read_b128 v[226:229], v162 offset:39936
	global_load_lds_dwordx4 v[234:235], off
	v_lshl_add_u64 v[234:235], s[54:55], 0, v[136:137]
	s_mov_b32 m0, s60
	s_nop 0
	global_load_lds_dwordx4 v[234:235], off
	s_waitcnt lgkmcnt(0)
	s_setprio 1
	v_mfma_f32_16x16x32_bf16 v[126:129], v[152:155], v[196:199], v[126:129]
	v_mfma_f32_16x16x32_bf16 v[122:125], v[168:171], v[196:199], v[122:125]
	v_mfma_f32_16x16x32_bf16 v[110:113], v[152:155], v[206:209], v[110:113]
	v_mfma_f32_16x16x32_bf16 v[106:109], v[168:171], v[206:209], v[106:109]
	v_mfma_f32_16x16x32_bf16 v[94:97], v[152:155], v[214:217], v[94:97]
	v_mfma_f32_16x16x32_bf16 v[90:93], v[168:171], v[214:217], v[90:93]
	v_mfma_f32_16x16x32_bf16 v[78:81], v[152:155], v[222:225], v[78:81]
	v_mfma_f32_16x16x32_bf16 v[74:77], v[168:171], v[222:225], v[74:77]
	v_mfma_f32_16x16x32_bf16 v[126:129], v[164:167], v[200:203], v[126:129]
	v_mfma_f32_16x16x32_bf16 v[122:125], v[172:175], v[200:203], v[122:125]
	v_mfma_f32_16x16x32_bf16 v[110:113], v[164:167], v[210:213], v[110:113]
	v_mfma_f32_16x16x32_bf16 v[106:109], v[172:175], v[210:213], v[106:109]
	v_mfma_f32_16x16x32_bf16 v[94:97], v[164:167], v[218:221], v[94:97]
	v_mfma_f32_16x16x32_bf16 v[90:93], v[172:175], v[218:221], v[90:93]
	v_mfma_f32_16x16x32_bf16 v[78:81], v[164:167], v[226:229], v[78:81]
	v_mfma_f32_16x16x32_bf16 v[74:77], v[172:175], v[226:229], v[74:77]
	v_mfma_f32_16x16x32_bf16 v[118:121], v[176:179], v[196:199], v[118:121]
	v_mfma_f32_16x16x32_bf16 v[114:117], v[184:187], v[196:199], v[114:117]
	v_mfma_f32_16x16x32_bf16 v[102:105], v[176:179], v[206:209], v[102:105]
	v_mfma_f32_16x16x32_bf16 v[98:101], v[184:187], v[206:209], v[98:101]
	v_mfma_f32_16x16x32_bf16 v[86:89], v[176:179], v[214:217], v[86:89]
	v_mfma_f32_16x16x32_bf16 v[82:85], v[184:187], v[214:217], v[82:85]
	v_mfma_f32_16x16x32_bf16 v[70:73], v[176:179], v[222:225], v[70:73]
	v_mfma_f32_16x16x32_bf16 v[66:69], v[184:187], v[222:225], v[66:69]
	v_mfma_f32_16x16x32_bf16 v[118:121], v[180:183], v[200:203], v[118:121]
	v_mfma_f32_16x16x32_bf16 v[114:117], v[188:191], v[200:203], v[114:117]
	v_mfma_f32_16x16x32_bf16 v[102:105], v[180:183], v[210:213], v[102:105]
	v_mfma_f32_16x16x32_bf16 v[98:101], v[188:191], v[210:213], v[98:101]
	v_mfma_f32_16x16x32_bf16 v[86:89], v[180:183], v[218:221], v[86:89]
	v_mfma_f32_16x16x32_bf16 v[82:85], v[188:191], v[218:221], v[82:85]
	v_mfma_f32_16x16x32_bf16 v[70:73], v[180:183], v[226:229], v[70:73]
	v_mfma_f32_16x16x32_bf16 v[66:69], v[188:191], v[226:229], v[66:69]
	s_setprio 0
	s_waitcnt vmcnt(8)
	s_barrier
	s_add_i32 s54, s83, s56
	v_lshl_add_u64 v[156:157], v[156:157], 0, s[18:19]
	s_mov_b32 m0, s54
	ds_read_b128 v[196:199], v162 offset:49152
	ds_read_b128 v[200:203], v162 offset:50176
	ds_read_b128 v[206:209], v162 offset:51200
	ds_read_b128 v[210:213], v162 offset:52224
	ds_read_b128 v[214:217], v162 offset:53248
	ds_read_b128 v[218:221], v162 offset:54272
	ds_read_b128 v[222:225], v162 offset:55296
	ds_read_b128 v[226:229], v162 offset:56320
	global_load_lds_dwordx4 v[156:157], off
	s_add_i32 m0, s54, 0x2000
	s_add_u32 s48, s48, 0x2b0080
	v_lshl_add_u64 v[156:157], v[192:193], 0, s[18:19]
	s_addc_u32 s49, s49, 0
	s_add_i32 s54, s84, s56
	global_load_lds_dwordx4 v[156:157], off
	v_lshl_add_u64 v[156:157], s[48:49], 0, v[134:135]
	s_mov_b32 m0, s54
	s_nop 0
	global_load_lds_dwordx4 v[156:157], off
	v_lshl_add_u64 v[156:157], s[48:49], 0, v[138:139]
	s_add_i32 m0, s54, 0x2000
	s_nop 0
	global_load_lds_dwordx4 v[156:157], off
	v_lshl_add_u64 v[156:157], v[230:231], 0, s[18:19]
	s_mov_b32 m0, s64
	s_nop 0
	global_load_lds_dwordx4 v[156:157], off
	v_lshl_add_u64 v[156:157], v[232:233], 0, s[18:19]
	s_mov_b32 m0, s65
	s_nop 0
	global_load_lds_dwordx4 v[156:157], off
	s_waitcnt lgkmcnt(0)
	s_setprio 1
	v_mfma_f32_16x16x32_bf16 v[62:65], v[152:155], v[196:199], v[62:65]
	v_mfma_f32_16x16x32_bf16 v[58:61], v[168:171], v[196:199], v[58:61]
	v_mfma_f32_16x16x32_bf16 v[46:49], v[152:155], v[206:209], v[46:49]
	v_mfma_f32_16x16x32_bf16 v[42:45], v[168:171], v[206:209], v[42:45]
	v_mfma_f32_16x16x32_bf16 v[30:33], v[152:155], v[214:217], v[30:33]
	v_mfma_f32_16x16x32_bf16 v[26:29], v[168:171], v[214:217], v[26:29]
	v_mfma_f32_16x16x32_bf16 v[14:17], v[152:155], v[222:225], v[14:17]
	v_mfma_f32_16x16x32_bf16 v[10:13], v[168:171], v[222:225], v[10:13]
	v_mfma_f32_16x16x32_bf16 v[62:65], v[164:167], v[200:203], v[62:65]
	v_mfma_f32_16x16x32_bf16 v[58:61], v[172:175], v[200:203], v[58:61]
	v_mfma_f32_16x16x32_bf16 v[46:49], v[164:167], v[210:213], v[46:49]
	v_mfma_f32_16x16x32_bf16 v[42:45], v[172:175], v[210:213], v[42:45]
	v_mfma_f32_16x16x32_bf16 v[30:33], v[164:167], v[218:221], v[30:33]
	v_mfma_f32_16x16x32_bf16 v[26:29], v[172:175], v[218:221], v[26:29]
	v_mfma_f32_16x16x32_bf16 v[14:17], v[164:167], v[226:229], v[14:17]
	v_mfma_f32_16x16x32_bf16 v[10:13], v[172:175], v[226:229], v[10:13]
	v_mfma_f32_16x16x32_bf16 v[54:57], v[176:179], v[196:199], v[54:57]
	v_mfma_f32_16x16x32_bf16 v[50:53], v[184:187], v[196:199], v[50:53]
	v_mfma_f32_16x16x32_bf16 v[38:41], v[176:179], v[206:209], v[38:41]
	v_mfma_f32_16x16x32_bf16 v[34:37], v[184:187], v[206:209], v[34:37]
	v_mfma_f32_16x16x32_bf16 v[22:25], v[176:179], v[214:217], v[22:25]
	v_mfma_f32_16x16x32_bf16 v[18:21], v[184:187], v[214:217], v[18:21]
	v_mfma_f32_16x16x32_bf16 v[6:9], v[176:179], v[222:225], v[6:9]
	v_mfma_f32_16x16x32_bf16 v[2:5], v[184:187], v[222:225], v[2:5]
	v_mfma_f32_16x16x32_bf16 v[54:57], v[180:183], v[200:203], v[54:57]
	v_mfma_f32_16x16x32_bf16 v[50:53], v[188:191], v[200:203], v[50:53]
	v_mfma_f32_16x16x32_bf16 v[38:41], v[180:183], v[210:213], v[38:41]
	v_mfma_f32_16x16x32_bf16 v[34:37], v[188:191], v[210:213], v[34:37]
	v_mfma_f32_16x16x32_bf16 v[22:25], v[180:183], v[218:221], v[22:25]
	v_mfma_f32_16x16x32_bf16 v[18:21], v[188:191], v[218:221], v[18:21]
	v_mfma_f32_16x16x32_bf16 v[6:9], v[180:183], v[226:229], v[6:9]
	v_mfma_f32_16x16x32_bf16 v[2:5], v[188:191], v[226:229], v[2:5]
	s_setprio 0
	s_waitcnt vmcnt(8)
	s_barrier
	s_add_u32 s52, s52, 0x100
	s_addc_u32 s53, s53, 0
	s_add_u32 s80, s80, 0x100
	s_addc_u32 s81, s81, 0
	s_cmp_ge_i32 s82, s78
	s_mov_b32 s48, s82
	s_cbranch_scc0 .Lkt_L_11
	s_branch .Lkt_exit_11
.Lkt_T_11:
	ds_read_b128 v[152:155], v160
	ds_read_b128 v[164:167], v160 offset:1024
	ds_read_b128 v[168:171], v160 offset:2048
	ds_read_b128 v[172:175], v160 offset:3072
	ds_read_b128 v[176:179], v161
	ds_read_b128 v[180:183], v161 offset:1024
	ds_read_b128 v[184:187], v161 offset:2048
	ds_read_b128 v[188:191], v161 offset:3072
	s_add_i32 s82, s48, 2
	s_add_u32 s49, s52, 0xffd50080
	s_addc_u32 s54, s53, -1
	s_cmp_eq_u32 s47, s48
	s_cselect_b32 s48, s50, s80
	s_cselect_b32 s55, s9, s54
	s_cselect_b32 s54, s8, s49
	s_cselect_b32 s49, s51, s81
	v_lshl_add_u64 v[156:157], s[52:53], 0, v[140:141]
	s_add_i32 m0, s57, 0xc000
	ds_read_b128 v[196:199], v162
	ds_read_b128 v[200:203], v162 offset:1024
	ds_read_b128 v[206:209], v162 offset:2048
	ds_read_b128 v[210:213], v162 offset:3072
	ds_read_b128 v[214:217], v162 offset:4096
	ds_read_b128 v[218:221], v162 offset:5120
	ds_read_b128 v[222:225], v162 offset:6144
	ds_read_b128 v[226:229], v162 offset:7168
	global_load_lds_dwordx4 v[156:157], off
	v_lshl_add_u64 v[156:157], s[52:53], 0, v[142:143]
	s_add_i32 m0, s57, 0xe000
	s_nop 0
	global_load_lds_dwordx4 v[156:157], off
	s_waitcnt vmcnt(8)
	s_waitcnt lgkmcnt(0)
	s_barrier
	s_setprio 2
	v_mfma_f32_16x16x32_bf16 v[126:129], v[152:155], v[196:199], v[126:129]
	v_mfma_f32_16x16x32_bf16 v[122:125], v[168:171], v[196:199], v[122:125]
	v_mfma_f32_16x16x32_bf16 v[110:113], v[152:155], v[206:209], v[110:113]
	v_mfma_f32_16x16x32_bf16 v[106:109], v[168:171], v[206:209], v[106:109]
	v_mfma_f32_16x16x32_bf16 v[94:97], v[152:155], v[214:217], v[94:97]
	v_mfma_f32_16x16x32_bf16 v[90:93], v[168:171], v[214:217], v[90:93]
	v_mfma_f32_16x16x32_bf16 v[78:81], v[152:155], v[222:225], v[78:81]
	v_mfma_f32_16x16x32_bf16 v[74:77], v[168:171], v[222:225], v[74:77]
	v_mfma_f32_16x16x32_bf16 v[126:129], v[164:167], v[200:203], v[126:129]
	v_mfma_f32_16x16x32_bf16 v[122:125], v[172:175], v[200:203], v[122:125]
	v_mfma_f32_16x16x32_bf16 v[110:113], v[164:167], v[210:213], v[110:113]
	v_mfma_f32_16x16x32_bf16 v[106:109], v[172:175], v[210:213], v[106:109]
	v_mfma_f32_16x16x32_bf16 v[94:97], v[164:167], v[218:221], v[94:97]
	v_mfma_f32_16x16x32_bf16 v[90:93], v[172:175], v[218:221], v[90:93]
	v_mfma_f32_16x16x32_bf16 v[78:81], v[164:167], v[226:229], v[78:81]
	v_mfma_f32_16x16x32_bf16 v[74:77], v[172:175], v[226:229], v[74:77]
	v_mfma_f32_16x16x32_bf16 v[118:121], v[176:179], v[196:199], v[118:121]
	v_mfma_f32_16x16x32_bf16 v[114:117], v[184:187], v[196:199], v[114:117]
	v_mfma_f32_16x16x32_bf16 v[102:105], v[176:179], v[206:209], v[102:105]
	v_mfma_f32_16x16x32_bf16 v[98:101], v[184:187], v[206:209], v[98:101]
	v_mfma_f32_16x16x32_bf16 v[86:89], v[176:179], v[214:217], v[86:89]
	v_mfma_f32_16x16x32_bf16 v[82:85], v[184:187], v[214:217], v[82:85]
	v_mfma_f32_16x16x32_bf16 v[70:73], v[176:179], v[222:225], v[70:73]
	v_mfma_f32_16x16x32_bf16 v[66:69], v[184:187], v[222:225], v[66:69]
	v_mfma_f32_16x16x32_bf16 v[118:121], v[180:183], v[200:203], v[118:121]
	v_mfma_f32_16x16x32_bf16 v[114:117], v[188:191], v[200:203], v[114:117]
	v_mfma_f32_16x16x32_bf16 v[102:105], v[180:183], v[210:213], v[102:105]
	v_mfma_f32_16x16x32_bf16 v[98:101], v[188:191], v[210:213], v[98:101]
	v_mfma_f32_16x16x32_bf16 v[86:89], v[180:183], v[218:221], v[86:89]
	v_mfma_f32_16x16x32_bf16 v[82:85], v[188:191], v[218:221], v[82:85]
	v_mfma_f32_16x16x32_bf16 v[70:73], v[180:183], v[226:229], v[70:73]
	v_mfma_f32_16x16x32_bf16 v[66:69], v[188:191], v[226:229], v[66:69]
	s_setprio 0
	s_add_i32 s83, s67, s56
	v_lshl_add_u64 v[156:157], s[48:49], 0, v[134:135]
	s_mov_b32 m0, s83
	ds_read_b128 v[196:199], v162 offset:16384
	ds_read_b128 v[200:203], v162 offset:17408
	ds_read_b128 v[206:209], v162 offset:18432
	ds_read_b128 v[210:213], v162 offset:19456
	ds_read_b128 v[214:217], v162 offset:20480
	ds_read_b128 v[218:221], v162 offset:21504
	ds_read_b128 v[222:225], v162 offset:22528
	ds_read_b128 v[226:229], v162 offset:23552
	global_load_lds_dwordx4 v[156:157], off
	s_add_i32 m0, s83, 0x2000
	s_add_u32 s84, s48, 0x2b0000
	v_lshl_add_u64 v[192:193], s[48:49], 0, v[138:139]
	s_addc_u32 s85, s49, 0
	s_add_i32 s83, s68, s56
	global_load_lds_dwordx4 v[192:193], off
	v_lshl_add_u64 v[230:231], s[84:85], 0, v[134:135]
	s_mov_b32 m0, s83
	v_lshl_add_u64 v[232:233], s[54:55], 0, v[136:137]
	global_load_lds_dwordx4 v[230:231], off
	v_lshl_add_u64 v[230:231], s[84:85], 0, v[138:139]
	s_add_i32 m0, s83, 0x2000
	s_nop 0
	global_load_lds_dwordx4 v[230:231], off
	v_lshl_add_u64 v[230:231], s[54:55], 0, v[132:133]
	s_mov_b32 m0, s57
	s_nop 0
	global_load_lds_dwordx4 v[230:231], off
	s_mov_b32 m0, s58
	s_nop 0
	global_load_lds_dwordx4 v[232:233], off
	s_waitcnt vmcnt(8)
	s_waitcnt lgkmcnt(0)
	s_barrier
	s_setprio 2
	v_mfma_f32_16x16x32_bf16 v[62:65], v[152:155], v[196:199], v[62:65]
	v_mfma_f32_16x16x32_bf16 v[58:61], v[168:171], v[196:199], v[58:61]
	v_mfma_f32_16x16x32_bf16 v[46:49], v[152:155], v[206:209], v[46:49]
	v_mfma_f32_16x16x32_bf16 v[42:45], v[168:171], v[206:209], v[42:45]
	v_mfma_f32_16x16x32_bf16 v[30:33], v[152:155], v[214:217], v[30:33]
	v_mfma_f32_16x16x32_bf16 v[26:29], v[168:171], v[214:217], v[26:29]
	v_mfma_f32_16x16x32_bf16 v[14:17], v[152:155], v[222:225], v[14:17]
	v_mfma_f32_16x16x32_bf16 v[10:13], v[168:171], v[222:225], v[10:13]
	v_mfma_f32_16x16x32_bf16 v[62:65], v[164:167], v[200:203], v[62:65]
	v_mfma_f32_16x16x32_bf16 v[58:61], v[172:175], v[200:203], v[58:61]
	v_mfma_f32_16x16x32_bf16 v[46:49], v[164:167], v[210:213], v[46:49]
	v_mfma_f32_16x16x32_bf16 v[42:45], v[172:175], v[210:213], v[42:45]
	v_mfma_f32_16x16x32_bf16 v[30:33], v[164:167], v[218:221], v[30:33]
	v_mfma_f32_16x16x32_bf16 v[26:29], v[172:175], v[218:221], v[26:29]
	v_mfma_f32_16x16x32_bf16 v[14:17], v[164:167], v[226:229], v[14:17]
	v_mfma_f32_16x16x32_bf16 v[10:13], v[172:175], v[226:229], v[10:13]
	v_mfma_f32_16x16x32_bf16 v[54:57], v[176:179], v[196:199], v[54:57]
	v_mfma_f32_16x16x32_bf16 v[50:53], v[184:187], v[196:199], v[50:53]
	v_mfma_f32_16x16x32_bf16 v[38:41], v[176:179], v[206:209], v[38:41]
	v_mfma_f32_16x16x32_bf16 v[34:37], v[184:187], v[206:209], v[34:37]
	v_mfma_f32_16x16x32_bf16 v[22:25], v[176:179], v[214:217], v[22:25]
	v_mfma_f32_16x16x32_bf16 v[18:21], v[184:187], v[214:217], v[18:21]
	v_mfma_f32_16x16x32_bf16 v[6:9], v[176:179], v[222:225], v[6:9]
	v_mfma_f32_16x16x32_bf16 v[2:5], v[184:187], v[222:225], v[2:5]
	v_mfma_f32_16x16x32_bf16 v[54:57], v[180:183], v[200:203], v[54:57]
	v_mfma_f32_16x16x32_bf16 v[50:53], v[188:191], v[200:203], v[50:53]
	v_mfma_f32_16x16x32_bf16 v[38:41], v[180:183], v[210:213], v[38:41]
	v_mfma_f32_16x16x32_bf16 v[34:37], v[188:191], v[210:213], v[34:37]
	v_mfma_f32_16x16x32_bf16 v[22:25], v[180:183], v[218:221], v[22:25]
	v_mfma_f32_16x16x32_bf16 v[18:21], v[188:191], v[218:221], v[18:21]
	v_mfma_f32_16x16x32_bf16 v[6:9], v[180:183], v[226:229], v[6:9]
	v_mfma_f32_16x16x32_bf16 v[2:5], v[188:191], v[226:229], v[2:5]
	s_setprio 0
	s_add_i32 s83, 0, 0x18000
	v_add_u32_e32 v163, s83, v158
	s_add_i32 s84, 0, 0x1c000
	ds_read_b128 v[152:155], v163
	ds_read_b128 v[164:167], v163 offset:1024
	ds_read_b128 v[168:171], v163 offset:2048
	ds_read_b128 v[172:175], v163 offset:3072
	v_add_u32_e32 v163, s84, v158
	ds_read_b128 v[176:179], v163
	ds_read_b128 v[180:183], v163 offset:1024
	ds_read_b128 v[184:187], v163 offset:2048
	ds_read_b128 v[188:191], v163 offset:3072
	s_add_u32 s54, s54, 0x2b0000
	s_addc_u32 s55, s55, 0
	s_mov_b32 m0, s59
	v_lshl_add_u64 v[234:235], s[54:55], 0, v[132:133]
	ds_read_b128 v[196:199], v162 offset:32768
	ds_read_b128 v[200:203], v162 offset:33792
	ds_read_b128 v[206:209], v162 offset:34816
	ds_read_b128 v[210:213], v162 offset:35840
	ds_read_b128 v[214:217], v162 offset:36864
	ds_read_b128 v[218:221], v162 offset:37888
	ds_read_b128 v[222:225], v162 offset:38912
	ds_read_b128 v[226:229], v162 offset:39936
	global_load_lds_dwordx4 v[234:235], off
	v_lshl_add_u64 v[234:235], s[54:55], 0, v[136:137]
	s_mov_b32 m0, s60
	s_nop 0
	global_load_lds_dwordx4 v[234:235], off
	s_waitcnt vmcnt(8)
	s_waitcnt lgkmcnt(0)
	s_barrier
	s_setprio 2
	v_mfma_f32_16x16x32_bf16 v[126:129], v[152:155], v[196:199], v[126:129]
	v_mfma_f32_16x16x32_bf16 v[122:125], v[168:171], v[196:199], v[122:125]
	v_mfma_f32_16x16x32_bf16 v[110:113], v[152:155], v[206:209], v[110:113]
	v_mfma_f32_16x16x32_bf16 v[106:109], v[168:171], v[206:209], v[106:109]
	v_mfma_f32_16x16x32_bf16 v[94:97], v[152:155], v[214:217], v[94:97]
	v_mfma_f32_16x16x32_bf16 v[90:93], v[168:171], v[214:217], v[90:93]
	v_mfma_f32_16x16x32_bf16 v[78:81], v[152:155], v[222:225], v[78:81]
	v_mfma_f32_16x16x32_bf16 v[74:77], v[168:171], v[222:225], v[74:77]
	v_mfma_f32_16x16x32_bf16 v[126:129], v[164:167], v[200:203], v[126:129]
	v_mfma_f32_16x16x32_bf16 v[122:125], v[172:175], v[200:203], v[122:125]
	v_mfma_f32_16x16x32_bf16 v[110:113], v[164:167], v[210:213], v[110:113]
	v_mfma_f32_16x16x32_bf16 v[106:109], v[172:175], v[210:213], v[106:109]
	v_mfma_f32_16x16x32_bf16 v[94:97], v[164:167], v[218:221], v[94:97]
	v_mfma_f32_16x16x32_bf16 v[90:93], v[172:175], v[218:221], v[90:93]
	v_mfma_f32_16x16x32_bf16 v[78:81], v[164:167], v[226:229], v[78:81]
	v_mfma_f32_16x16x32_bf16 v[74:77], v[172:175], v[226:229], v[74:77]
	v_mfma_f32_16x16x32_bf16 v[118:121], v[176:179], v[196:199], v[118:121]
	v_mfma_f32_16x16x32_bf16 v[114:117], v[184:187], v[196:199], v[114:117]
	v_mfma_f32_16x16x32_bf16 v[102:105], v[176:179], v[206:209], v[102:105]
	v_mfma_f32_16x16x32_bf16 v[98:101], v[184:187], v[206:209], v[98:101]
	v_mfma_f32_16x16x32_bf16 v[86:89], v[176:179], v[214:217], v[86:89]
	v_mfma_f32_16x16x32_bf16 v[82:85], v[184:187], v[214:217], v[82:85]
	v_mfma_f32_16x16x32_bf16 v[70:73], v[176:179], v[222:225], v[70:73]
	v_mfma_f32_16x16x32_bf16 v[66:69], v[184:187], v[222:225], v[66:69]
	v_mfma_f32_16x16x32_bf16 v[118:121], v[180:183], v[200:203], v[118:121]
	v_mfma_f32_16x16x32_bf16 v[114:117], v[188:191], v[200:203], v[114:117]
	v_mfma_f32_16x16x32_bf16 v[102:105], v[180:183], v[210:213], v[102:105]
	v_mfma_f32_16x16x32_bf16 v[98:101], v[188:191], v[210:213], v[98:101]
	v_mfma_f32_16x16x32_bf16 v[86:89], v[180:183], v[218:221], v[86:89]
	v_mfma_f32_16x16x32_bf16 v[82:85], v[188:191], v[218:221], v[82:85]
	v_mfma_f32_16x16x32_bf16 v[70:73], v[180:183], v[226:229], v[70:73]
	v_mfma_f32_16x16x32_bf16 v[66:69], v[188:191], v[226:229], v[66:69]
	s_setprio 0
	s_add_i32 s54, s83, s56
	v_lshl_add_u64 v[156:157], v[156:157], 0, s[18:19]
	s_mov_b32 m0, s54
	ds_read_b128 v[196:199], v162 offset:49152
	ds_read_b128 v[200:203], v162 offset:50176
	ds_read_b128 v[206:209], v162 offset:51200
	ds_read_b128 v[210:213], v162 offset:52224
	ds_read_b128 v[214:217], v162 offset:53248
	ds_read_b128 v[218:221], v162 offset:54272
	ds_read_b128 v[222:225], v162 offset:55296
	ds_read_b128 v[226:229], v162 offset:56320
	global_load_lds_dwordx4 v[156:157], off
	s_add_i32 m0, s54, 0x2000
	s_add_u32 s48, s48, 0x2b0080
	v_lshl_add_u64 v[156:157], v[192:193], 0, s[18:19]
	s_addc_u32 s49, s49, 0
	s_add_i32 s54, s84, s56
	global_load_lds_dwordx4 v[156:157], off
	v_lshl_add_u64 v[156:157], s[48:49], 0, v[134:135]
	s_mov_b32 m0, s54
	s_nop 0
	global_load_lds_dwordx4 v[156:157], off
	v_lshl_add_u64 v[156:157], s[48:49], 0, v[138:139]
	s_add_i32 m0, s54, 0x2000
	s_nop 0
	global_load_lds_dwordx4 v[156:157], off
	v_lshl_add_u64 v[156:157], v[230:231], 0, s[18:19]
	s_mov_b32 m0, s64
	s_nop 0
	global_load_lds_dwordx4 v[156:157], off
	v_lshl_add_u64 v[156:157], v[232:233], 0, s[18:19]
	s_mov_b32 m0, s65
	s_nop 0
	global_load_lds_dwordx4 v[156:157], off
	s_waitcnt vmcnt(8)
	s_waitcnt lgkmcnt(0)
	s_barrier
	s_setprio 2
	v_mfma_f32_16x16x32_bf16 v[62:65], v[152:155], v[196:199], v[62:65]
	v_mfma_f32_16x16x32_bf16 v[58:61], v[168:171], v[196:199], v[58:61]
	v_mfma_f32_16x16x32_bf16 v[46:49], v[152:155], v[206:209], v[46:49]
	v_mfma_f32_16x16x32_bf16 v[42:45], v[168:171], v[206:209], v[42:45]
	v_mfma_f32_16x16x32_bf16 v[30:33], v[152:155], v[214:217], v[30:33]
	v_mfma_f32_16x16x32_bf16 v[26:29], v[168:171], v[214:217], v[26:29]
	v_mfma_f32_16x16x32_bf16 v[14:17], v[152:155], v[222:225], v[14:17]
	v_mfma_f32_16x16x32_bf16 v[10:13], v[168:171], v[222:225], v[10:13]
	v_mfma_f32_16x16x32_bf16 v[62:65], v[164:167], v[200:203], v[62:65]
	v_mfma_f32_16x16x32_bf16 v[58:61], v[172:175], v[200:203], v[58:61]
	v_mfma_f32_16x16x32_bf16 v[46:49], v[164:167], v[210:213], v[46:49]
	v_mfma_f32_16x16x32_bf16 v[42:45], v[172:175], v[210:213], v[42:45]
	v_mfma_f32_16x16x32_bf16 v[30:33], v[164:167], v[218:221], v[30:33]
	v_mfma_f32_16x16x32_bf16 v[26:29], v[172:175], v[218:221], v[26:29]
	v_mfma_f32_16x16x32_bf16 v[14:17], v[164:167], v[226:229], v[14:17]
	v_mfma_f32_16x16x32_bf16 v[10:13], v[172:175], v[226:229], v[10:13]
	v_mfma_f32_16x16x32_bf16 v[54:57], v[176:179], v[196:199], v[54:57]
	v_mfma_f32_16x16x32_bf16 v[50:53], v[184:187], v[196:199], v[50:53]
	v_mfma_f32_16x16x32_bf16 v[38:41], v[176:179], v[206:209], v[38:41]
	v_mfma_f32_16x16x32_bf16 v[34:37], v[184:187], v[206:209], v[34:37]
	v_mfma_f32_16x16x32_bf16 v[22:25], v[176:179], v[214:217], v[22:25]
	v_mfma_f32_16x16x32_bf16 v[18:21], v[184:187], v[214:217], v[18:21]
	v_mfma_f32_16x16x32_bf16 v[6:9], v[176:179], v[222:225], v[6:9]
	v_mfma_f32_16x16x32_bf16 v[2:5], v[184:187], v[222:225], v[2:5]
	v_mfma_f32_16x16x32_bf16 v[54:57], v[180:183], v[200:203], v[54:57]
	v_mfma_f32_16x16x32_bf16 v[50:53], v[188:191], v[200:203], v[50:53]
	v_mfma_f32_16x16x32_bf16 v[38:41], v[180:183], v[210:213], v[38:41]
	v_mfma_f32_16x16x32_bf16 v[34:37], v[188:191], v[210:213], v[34:37]
	v_mfma_f32_16x16x32_bf16 v[22:25], v[180:183], v[218:221], v[22:25]
	v_mfma_f32_16x16x32_bf16 v[18:21], v[188:191], v[218:221], v[18:21]
	v_mfma_f32_16x16x32_bf16 v[6:9], v[180:183], v[226:229], v[6:9]
	v_mfma_f32_16x16x32_bf16 v[2:5], v[188:191], v[226:229], v[2:5]
	s_setprio 0
	s_add_u32 s52, s52, 0x100
	s_addc_u32 s53, s53, 0
	s_add_u32 s80, s80, 0x100
	s_addc_u32 s81, s81, 0
	s_cmp_ge_i32 s82, s78
	s_mov_b32 s48, s82
	s_cbranch_scc0 .Lkt_T_11
	s_nop 7

.LBB0_1856:
	s_add_u32 s14, s38, 0x43e00000
	s_addc_u32 s15, s39, 0
	s_add_u32 s16, s38, 0x214000
	s_addc_u32 s17, s39, 0
	s_add_u32 s66, s38, 0x54600000
	s_addc_u32 s67, s39, 0
	s_lshl_b32 s7, s7, 5
	s_mov_b64 s[18:19], 0x80
	s_and_b32 s7, s7, 0x60
	s_add_i32 m0, s62, 0x18000
	v_lshl_add_u64 v[8:9], v[8:9], 0, s[18:19]
	s_lshl_b32 s21, s6, 13
	s_lshl_b32 s22, s7, 7
	s_ashr_i32 s68, s2, 31
	s_waitcnt vmcnt(2)
	s_barrier
	global_load_lds_dwordx4 v[8:9], off
	v_lshl_add_u64 v[6:7], v[6:7], 0, s[18:19]
	s_add_i32 m0, s62, 0x1a000
	s_add_i32 s69, s62, 0x8000
	s_add_i32 s70, s62, 0xa000
	global_load_lds_dwordx4 v[6:7], off
	v_lshl_add_u64 v[2:3], v[2:3], 0, s[18:19]
	s_mov_b32 m0, s69
	s_add_u32 s8, s42, 0x100080
	global_load_lds_dwordx4 v[2:3], off
	v_lshl_add_u64 v[2:3], v[4:5], 0, s[18:19]
	s_mov_b32 m0, s70
	s_addc_u32 s9, s43, 0
	global_load_lds_dwordx4 v[2:3], off
	s_add_i32 m0, s62, 0x1c000
	v_lshl_add_u64 v[2:3], s[8:9], 0, v[134:135]
	global_load_lds_dwordx4 v[2:3], off
	v_lshl_add_u64 v[2:3], s[8:9], 0, v[138:139]
	s_add_i32 m0, s62, 0x1e000
	v_lshlrev_b32_e32 v4, 2, v0
	global_load_lds_dwordx4 v[2:3], off
	v_and_b32_e32 v2, 15, v0
	v_lshlrev_b32_e32 v3, 1, v13
	v_lshl_or_b32 v140, s6, 6, v2
	v_lshl_or_b32 v2, v2, 6, v3
	v_and_b32_e32 v4, 32, v4
	v_bitop3_b32 v5, v2, s21, v4 bitop3:0xde
	v_lshlrev_b32_e32 v2, 6, v0
	s_movk_i32 s6, 0x3c0
	v_and_or_b32 v2, v2, s6, v3
	v_bitop3_b32 v131, s22, v2, v4 bitop3:0xf6
	v_or_b32_e32 v2, 16, v140
	v_mov_b32_e32 v3, v135
	v_lshlrev_b64 v[144:145], 16, v[2:3]
	v_or_b32_e32 v2, 32, v140
	v_lshlrev_b64 v[146:147], 16, v[2:3]
	v_or_b32_e32 v2, 48, v140
	v_lshlrev_b64 v[148:149], 16, v[2:3]
	v_lshlrev_b32_e32 v2, 10, v0
	v_and_b32_e32 v2, 0x60000, v2
	v_lshlrev_b32_e32 v3, 13, v12
	v_or3_b32 v2, v10, v2, v3
	v_add_u32_e32 v150, v2, v11
	v_lshlrev_b32_e32 v2, 6, v14
	s_waitcnt vmcnt(6)
	s_cmpk_lt_u32 s20, 0x100
	v_and_b32_e32 v2, 0xe0000, v2
	s_cselect_b64 s[20:21], -1, 0
	v_mov_b32_e32 v141, v135
	v_or3_b32 v2, v10, v2, v3
	s_add_i32 s72, 0, 0x10000
	s_add_i32 s73, 0, 0x14000
	v_lshlrev_b64 v[142:143], 16, v[140:141]
	s_ashr_i32 s71, s44, 31
	v_or_b32_e32 v141, s7, v13
	v_mov_b32_e32 v151, v135
	v_add_u32_e32 v152, v2, v11
	v_mov_b32_e32 v153, v135
	v_mov_b64_e32 v[154:155], 0x900
	v_mov_b64_e32 v[156:157], 0x8ff
	v_add_u32_e32 v168, s72, v131
	v_add_u32_e32 v169, s73, v131
	v_add_u32_e32 v170, 0, v5
	s_mov_b32 s74, 0x800000
	s_mov_b32 s75, 0x3f317217
	s_mov_b32 s76, 0x7f800000
	s_mov_b64 s[22:23], 0x400000
	s_mov_b64 s[24:25], 0x480000
	s_mov_b64 s[26:27], 0x500000
	s_mov_b64 s[28:29], 0x580000
	v_mov_b64_e32 v[158:159], 0x7ff
	v_mov_b64_e32 v[160:161], 0x800
	v_mov_b32_e32 v171, 0x41b17218
	s_mov_b32 s77, s11
	s_branch .LBB0_1859

.Lkt_L_12:
	ds_read_b128 v[162:165], v168
	s_waitcnt vmcnt(0)
	ds_read_b128 v[172:175], v168 offset:1024
	ds_read_b128 v[176:179], v168 offset:2048
	ds_read_b128 v[180:183], v168 offset:3072
	ds_read_b128 v[184:187], v169
	ds_read_b128 v[188:191], v169 offset:1024
	ds_read_b128 v[196:199], v169 offset:2048
	ds_read_b128 v[200:203], v169 offset:3072
	s_add_i32 s55, s42, 2
	s_add_u32 s43, s8, 0xfff00080
	s_addc_u32 s46, s9, -1
	s_cmp_eq_u32 s48, s42
	s_cselect_b32 s42, s41, s49
	s_cselect_b32 s47, s31, s46
	s_cselect_b32 s46, s33, s43
	s_cselect_b32 s43, s35, s53
	v_lshl_add_u64 v[166:167], s[8:9], 0, v[150:151]
	s_add_i32 m0, s62, 0xc000
	ds_read_b128 v[206:209], v170
	ds_read_b128 v[210:213], v170 offset:1024
	ds_read_b128 v[214:217], v170 offset:2048
	ds_read_b128 v[218:221], v170 offset:3072
	ds_read_b128 v[222:225], v170 offset:4096
	ds_read_b128 v[226:229], v170 offset:5120
	ds_read_b128 v[230:233], v170 offset:6144
	ds_read_b128 v[234:237], v170 offset:7168
	global_load_lds_dwordx4 v[166:167], off
	v_lshl_add_u64 v[166:167], s[8:9], 0, v[152:153]
	s_add_i32 m0, s62, 0xe000
	s_nop 0
	global_load_lds_dwordx4 v[166:167], off
	s_waitcnt lgkmcnt(0)
	s_setprio 1
	v_mfma_f32_16x16x32_bf16 v[66:69], v[162:165], v[206:209], v[66:69]
	v_mfma_f32_16x16x32_bf16 v[62:65], v[176:179], v[206:209], v[62:65]
	v_mfma_f32_16x16x32_bf16 v[58:61], v[162:165], v[214:217], v[58:61]
	v_mfma_f32_16x16x32_bf16 v[54:57], v[176:179], v[214:217], v[54:57]
	v_mfma_f32_16x16x32_bf16 v[50:53], v[162:165], v[222:225], v[50:53]
	v_mfma_f32_16x16x32_bf16 v[46:49], v[176:179], v[222:225], v[46:49]
	v_mfma_f32_16x16x32_bf16 v[38:41], v[162:165], v[230:233], v[38:41]
	v_mfma_f32_16x16x32_bf16 v[30:33], v[176:179], v[230:233], v[30:33]
	v_mfma_f32_16x16x32_bf16 v[66:69], v[172:175], v[210:213], v[66:69]
	v_mfma_f32_16x16x32_bf16 v[62:65], v[180:183], v[210:213], v[62:65]
	v_mfma_f32_16x16x32_bf16 v[58:61], v[172:175], v[218:221], v[58:61]
	v_mfma_f32_16x16x32_bf16 v[54:57], v[180:183], v[218:221], v[54:57]
	v_mfma_f32_16x16x32_bf16 v[50:53], v[172:175], v[226:229], v[50:53]
	v_mfma_f32_16x16x32_bf16 v[46:49], v[180:183], v[226:229], v[46:49]
	v_mfma_f32_16x16x32_bf16 v[38:41], v[172:175], v[234:237], v[38:41]
	v_mfma_f32_16x16x32_bf16 v[30:33], v[180:183], v[234:237], v[30:33]
	v_mfma_f32_16x16x32_bf16 v[42:45], v[184:187], v[206:209], v[42:45]
	v_mfma_f32_16x16x32_bf16 v[34:37], v[196:199], v[206:209], v[34:37]
	v_mfma_f32_16x16x32_bf16 v[26:29], v[184:187], v[214:217], v[26:29]
	v_mfma_f32_16x16x32_bf16 v[22:25], v[196:199], v[214:217], v[22:25]
	v_mfma_f32_16x16x32_bf16 v[18:21], v[184:187], v[222:225], v[18:21]
	v_mfma_f32_16x16x32_bf16 v[14:17], v[196:199], v[222:225], v[14:17]
	v_mfma_f32_16x16x32_bf16 v[10:13], v[184:187], v[230:233], v[10:13]
	v_mfma_f32_16x16x32_bf16 v[6:9], v[196:199], v[230:233], v[6:9]
	v_mfma_f32_16x16x32_bf16 v[42:45], v[188:191], v[210:213], v[42:45]
	v_mfma_f32_16x16x32_bf16 v[34:37], v[200:203], v[210:213], v[34:37]
	v_mfma_f32_16x16x32_bf16 v[26:29], v[188:191], v[218:221], v[26:29]
	v_mfma_f32_16x16x32_bf16 v[22:25], v[200:203], v[218:221], v[22:25]
	v_mfma_f32_16x16x32_bf16 v[18:21], v[188:191], v[226:229], v[18:21]
	v_mfma_f32_16x16x32_bf16 v[14:17], v[200:203], v[226:229], v[14:17]
	v_mfma_f32_16x16x32_bf16 v[10:13], v[188:191], v[234:237], v[10:13]
	v_mfma_f32_16x16x32_bf16 v[6:9], v[200:203], v[234:237], v[6:9]
	s_setprio 0
	s_waitcnt vmcnt(8)
	s_barrier
	s_add_i32 s80, s72, s61
	v_lshl_add_u64 v[166:167], s[42:43], 0, v[134:135]
	s_mov_b32 m0, s80
	ds_read_b128 v[206:209], v170 offset:16384
	ds_read_b128 v[210:213], v170 offset:17408
	ds_read_b128 v[214:217], v170 offset:18432
	ds_read_b128 v[218:221], v170 offset:19456
	ds_read_b128 v[222:225], v170 offset:20480
	ds_read_b128 v[226:229], v170 offset:21504
	ds_read_b128 v[230:233], v170 offset:22528
	ds_read_b128 v[234:237], v170 offset:23552
	global_load_lds_dwordx4 v[166:167], off
	s_add_i32 m0, s80, 0x2000
	s_add_u32 s80, s42, 0x100000
	v_lshl_add_u64 v[192:193], s[42:43], 0, v[138:139]
	s_addc_u32 s81, s43, 0
	s_add_i32 s82, s73, s61
	global_load_lds_dwordx4 v[192:193], off
	v_lshl_add_u64 v[238:239], s[80:81], 0, v[134:135]
	s_mov_b32 m0, s82
	v_lshl_add_u64 v[240:241], s[46:47], 0, v[136:137]
	global_load_lds_dwordx4 v[238:239], off
	v_lshl_add_u64 v[238:239], s[80:81], 0, v[138:139]
	s_add_i32 m0, s82, 0x2000
	s_nop 0
	global_load_lds_dwordx4 v[238:239], off
	v_lshl_add_u64 v[238:239], s[46:47], 0, v[132:133]
	s_mov_b32 m0, s62
	s_nop 0
	global_load_lds_dwordx4 v[238:239], off
	s_mov_b32 m0, s63
	s_nop 0
	global_load_lds_dwordx4 v[240:241], off
	s_waitcnt lgkmcnt(0)
	s_setprio 1
	v_mfma_f32_16x16x32_bf16 v[126:129], v[162:165], v[206:209], v[126:129]
	v_mfma_f32_16x16x32_bf16 v[122:125], v[176:179], v[206:209], v[122:125]
	v_mfma_f32_16x16x32_bf16 v[110:113], v[162:165], v[214:217], v[110:113]
	v_mfma_f32_16x16x32_bf16 v[106:109], v[176:179], v[214:217], v[106:109]
	v_mfma_f32_16x16x32_bf16 v[94:97], v[162:165], v[222:225], v[94:97]
	v_mfma_f32_16x16x32_bf16 v[90:93], v[176:179], v[222:225], v[90:93]
	v_mfma_f32_16x16x32_bf16 v[78:81], v[162:165], v[230:233], v[78:81]
	v_mfma_f32_16x16x32_bf16 v[74:77], v[176:179], v[230:233], v[74:77]
	v_mfma_f32_16x16x32_bf16 v[126:129], v[172:175], v[210:213], v[126:129]
	v_mfma_f32_16x16x32_bf16 v[122:125], v[180:183], v[210:213], v[122:125]
	v_mfma_f32_16x16x32_bf16 v[110:113], v[172:175], v[218:221], v[110:113]
	v_mfma_f32_16x16x32_bf16 v[106:109], v[180:183], v[218:221], v[106:109]
	v_mfma_f32_16x16x32_bf16 v[94:97], v[172:175], v[226:229], v[94:97]
	v_mfma_f32_16x16x32_bf16 v[90:93], v[180:183], v[226:229], v[90:93]
	v_mfma_f32_16x16x32_bf16 v[78:81], v[172:175], v[234:237], v[78:81]
	v_mfma_f32_16x16x32_bf16 v[74:77], v[180:183], v[234:237], v[74:77]
	v_mfma_f32_16x16x32_bf16 v[118:121], v[184:187], v[206:209], v[118:121]
	v_mfma_f32_16x16x32_bf16 v[114:117], v[196:199], v[206:209], v[114:117]
	v_mfma_f32_16x16x32_bf16 v[102:105], v[184:187], v[214:217], v[102:105]
	v_mfma_f32_16x16x32_bf16 v[98:101], v[196:199], v[214:217], v[98:101]
	v_mfma_f32_16x16x32_bf16 v[86:89], v[184:187], v[222:225], v[86:89]
	v_mfma_f32_16x16x32_bf16 v[82:85], v[196:199], v[222:225], v[82:85]
	v_mfma_f32_16x16x32_bf16 v[70:73], v[184:187], v[230:233], v[70:73]
	v_mfma_f32_16x16x32_bf16 v[2:5], v[196:199], v[230:233], v[2:5]
	v_mfma_f32_16x16x32_bf16 v[118:121], v[188:191], v[210:213], v[118:121]
	v_mfma_f32_16x16x32_bf16 v[114:117], v[200:203], v[210:213], v[114:117]
	v_mfma_f32_16x16x32_bf16 v[102:105], v[188:191], v[218:221], v[102:105]
	v_mfma_f32_16x16x32_bf16 v[98:101], v[200:203], v[218:221], v[98:101]
	v_mfma_f32_16x16x32_bf16 v[86:89], v[188:191], v[226:229], v[86:89]
	v_mfma_f32_16x16x32_bf16 v[82:85], v[200:203], v[226:229], v[82:85]
	v_mfma_f32_16x16x32_bf16 v[70:73], v[188:191], v[234:237], v[70:73]
	v_mfma_f32_16x16x32_bf16 v[2:5], v[200:203], v[234:237], v[2:5]
	s_setprio 0
	s_waitcnt vmcnt(8)
	s_barrier
	s_add_i32 s80, 0, 0x18000
	s_add_i32 s81, 0, 0x1c000
	v_add_u32_e32 v180, s80, v131
	v_add_u32_e32 v200, s81, v131
	ds_read_b128 v[162:165], v180
	ds_read_b128 v[172:175], v180 offset:1024
	ds_read_b128 v[176:179], v180 offset:2048
	ds_read_b128 v[180:183], v180 offset:3072
	ds_read_b128 v[184:187], v200
	ds_read_b128 v[188:191], v200 offset:1024
	ds_read_b128 v[196:199], v200 offset:2048
	ds_read_b128 v[200:203], v200 offset:3072
	s_add_u32 s46, s46, 0x100000
	s_addc_u32 s47, s47, 0
	s_mov_b32 m0, s64
	v_lshl_add_u64 v[242:243], s[46:47], 0, v[132:133]
	ds_read_b128 v[206:209], v170 offset:32768
	ds_read_b128 v[210:213], v170 offset:33792
	ds_read_b128 v[214:217], v170 offset:34816
	ds_read_b128 v[218:221], v170 offset:35840
	ds_read_b128 v[222:225], v170 offset:36864
	ds_read_b128 v[226:229], v170 offset:37888
	ds_read_b128 v[230:233], v170 offset:38912
	ds_read_b128 v[234:237], v170 offset:39936
	global_load_lds_dwordx4 v[242:243], off
	v_lshl_add_u64 v[242:243], s[46:47], 0, v[136:137]
	s_mov_b32 m0, s65
	s_nop 0
	global_load_lds_dwordx4 v[242:243], off
	s_waitcnt lgkmcnt(0)
	s_setprio 1
	v_mfma_f32_16x16x32_bf16 v[66:69], v[162:165], v[206:209], v[66:69]
	v_mfma_f32_16x16x32_bf16 v[62:65], v[176:179], v[206:209], v[62:65]
	v_mfma_f32_16x16x32_bf16 v[58:61], v[162:165], v[214:217], v[58:61]
	v_mfma_f32_16x16x32_bf16 v[54:57], v[176:179], v[214:217], v[54:57]
	v_mfma_f32_16x16x32_bf16 v[50:53], v[162:165], v[222:225], v[50:53]
	v_mfma_f32_16x16x32_bf16 v[46:49], v[176:179], v[222:225], v[46:49]
	v_mfma_f32_16x16x32_bf16 v[38:41], v[162:165], v[230:233], v[38:41]
	v_mfma_f32_16x16x32_bf16 v[30:33], v[176:179], v[230:233], v[30:33]
	v_mfma_f32_16x16x32_bf16 v[66:69], v[172:175], v[210:213], v[66:69]
	v_mfma_f32_16x16x32_bf16 v[62:65], v[180:183], v[210:213], v[62:65]
	v_mfma_f32_16x16x32_bf16 v[58:61], v[172:175], v[218:221], v[58:61]
	v_mfma_f32_16x16x32_bf16 v[54:57], v[180:183], v[218:221], v[54:57]
	v_mfma_f32_16x16x32_bf16 v[50:53], v[172:175], v[226:229], v[50:53]
	v_mfma_f32_16x16x32_bf16 v[46:49], v[180:183], v[226:229], v[46:49]
	v_mfma_f32_16x16x32_bf16 v[38:41], v[172:175], v[234:237], v[38:41]
	v_mfma_f32_16x16x32_bf16 v[30:33], v[180:183], v[234:237], v[30:33]
	v_mfma_f32_16x16x32_bf16 v[42:45], v[184:187], v[206:209], v[42:45]
	v_mfma_f32_16x16x32_bf16 v[34:37], v[196:199], v[206:209], v[34:37]
	v_mfma_f32_16x16x32_bf16 v[26:29], v[184:187], v[214:217], v[26:29]
	v_mfma_f32_16x16x32_bf16 v[22:25], v[196:199], v[214:217], v[22:25]
	v_mfma_f32_16x16x32_bf16 v[18:21], v[184:187], v[222:225], v[18:21]
	v_mfma_f32_16x16x32_bf16 v[14:17], v[196:199], v[222:225], v[14:17]
	v_mfma_f32_16x16x32_bf16 v[10:13], v[184:187], v[230:233], v[10:13]
	v_mfma_f32_16x16x32_bf16 v[6:9], v[196:199], v[230:233], v[6:9]
	v_mfma_f32_16x16x32_bf16 v[42:45], v[188:191], v[210:213], v[42:45]
	v_mfma_f32_16x16x32_bf16 v[34:37], v[200:203], v[210:213], v[34:37]
	v_mfma_f32_16x16x32_bf16 v[26:29], v[188:191], v[218:221], v[26:29]
	v_mfma_f32_16x16x32_bf16 v[22:25], v[200:203], v[218:221], v[22:25]
	v_mfma_f32_16x16x32_bf16 v[18:21], v[188:191], v[226:229], v[18:21]
	v_mfma_f32_16x16x32_bf16 v[14:17], v[200:203], v[226:229], v[14:17]
	v_mfma_f32_16x16x32_bf16 v[10:13], v[188:191], v[234:237], v[10:13]
	v_mfma_f32_16x16x32_bf16 v[6:9], v[200:203], v[234:237], v[6:9]
	s_setprio 0
	s_waitcnt vmcnt(8)
	s_barrier
	s_add_i32 s46, s80, s61
	v_lshl_add_u64 v[166:167], v[166:167], 0, s[18:19]
	s_mov_b32 m0, s46
	ds_read_b128 v[206:209], v170 offset:49152
	ds_read_b128 v[210:213], v170 offset:50176
	ds_read_b128 v[214:217], v170 offset:51200
	ds_read_b128 v[218:221], v170 offset:52224
	ds_read_b128 v[222:225], v170 offset:53248
	ds_read_b128 v[226:229], v170 offset:54272
	ds_read_b128 v[230:233], v170 offset:55296
	ds_read_b128 v[234:237], v170 offset:56320
	global_load_lds_dwordx4 v[166:167], off
	s_add_i32 m0, s46, 0x2000
	s_add_u32 s42, s42, 0x100080
	v_lshl_add_u64 v[166:167], v[192:193], 0, s[18:19]
	s_addc_u32 s43, s43, 0
	s_add_i32 s46, s81, s61
	global_load_lds_dwordx4 v[166:167], off
	v_lshl_add_u64 v[166:167], s[42:43], 0, v[134:135]
	s_mov_b32 m0, s46
	s_nop 0
	global_load_lds_dwordx4 v[166:167], off
	v_lshl_add_u64 v[166:167], s[42:43], 0, v[138:139]
	s_add_i32 m0, s46, 0x2000
	s_nop 0
	global_load_lds_dwordx4 v[166:167], off
	v_lshl_add_u64 v[166:167], v[238:239], 0, s[18:19]
	s_mov_b32 m0, s69
	s_nop 0
	global_load_lds_dwordx4 v[166:167], off
	v_lshl_add_u64 v[166:167], v[240:241], 0, s[18:19]
	s_mov_b32 m0, s70
	s_nop 0
	global_load_lds_dwordx4 v[166:167], off
	s_waitcnt lgkmcnt(0)
	s_setprio 1
	v_mfma_f32_16x16x32_bf16 v[126:129], v[162:165], v[206:209], v[126:129]
	v_mfma_f32_16x16x32_bf16 v[122:125], v[176:179], v[206:209], v[122:125]
	v_mfma_f32_16x16x32_bf16 v[110:113], v[162:165], v[214:217], v[110:113]
	v_mfma_f32_16x16x32_bf16 v[106:109], v[176:179], v[214:217], v[106:109]
	v_mfma_f32_16x16x32_bf16 v[94:97], v[162:165], v[222:225], v[94:97]
	v_mfma_f32_16x16x32_bf16 v[90:93], v[176:179], v[222:225], v[90:93]
	v_mfma_f32_16x16x32_bf16 v[78:81], v[162:165], v[230:233], v[78:81]
	v_mfma_f32_16x16x32_bf16 v[74:77], v[176:179], v[230:233], v[74:77]
	v_mfma_f32_16x16x32_bf16 v[126:129], v[172:175], v[210:213], v[126:129]
	v_mfma_f32_16x16x32_bf16 v[122:125], v[180:183], v[210:213], v[122:125]
	v_mfma_f32_16x16x32_bf16 v[110:113], v[172:175], v[218:221], v[110:113]
	v_mfma_f32_16x16x32_bf16 v[106:109], v[180:183], v[218:221], v[106:109]
	v_mfma_f32_16x16x32_bf16 v[94:97], v[172:175], v[226:229], v[94:97]
	v_mfma_f32_16x16x32_bf16 v[90:93], v[180:183], v[226:229], v[90:93]
	v_mfma_f32_16x16x32_bf16 v[78:81], v[172:175], v[234:237], v[78:81]
	v_mfma_f32_16x16x32_bf16 v[74:77], v[180:183], v[234:237], v[74:77]
	v_mfma_f32_16x16x32_bf16 v[118:121], v[184:187], v[206:209], v[118:121]
	v_mfma_f32_16x16x32_bf16 v[114:117], v[196:199], v[206:209], v[114:117]
	v_mfma_f32_16x16x32_bf16 v[102:105], v[184:187], v[214:217], v[102:105]
	v_mfma_f32_16x16x32_bf16 v[98:101], v[196:199], v[214:217], v[98:101]
	v_mfma_f32_16x16x32_bf16 v[86:89], v[184:187], v[222:225], v[86:89]
	v_mfma_f32_16x16x32_bf16 v[82:85], v[196:199], v[222:225], v[82:85]
	v_mfma_f32_16x16x32_bf16 v[70:73], v[184:187], v[230:233], v[70:73]
	v_mfma_f32_16x16x32_bf16 v[2:5], v[196:199], v[230:233], v[2:5]
	v_mfma_f32_16x16x32_bf16 v[118:121], v[188:191], v[210:213], v[118:121]
	v_mfma_f32_16x16x32_bf16 v[114:117], v[200:203], v[210:213], v[114:117]
	v_mfma_f32_16x16x32_bf16 v[102:105], v[188:191], v[218:221], v[102:105]
	v_mfma_f32_16x16x32_bf16 v[98:101], v[200:203], v[218:221], v[98:101]
	v_mfma_f32_16x16x32_bf16 v[86:89], v[188:191], v[226:229], v[86:89]
	v_mfma_f32_16x16x32_bf16 v[82:85], v[200:203], v[226:229], v[82:85]
	v_mfma_f32_16x16x32_bf16 v[70:73], v[188:191], v[234:237], v[70:73]
	v_mfma_f32_16x16x32_bf16 v[2:5], v[200:203], v[234:237], v[2:5]
	s_setprio 0
	s_waitcnt vmcnt(8)
	s_barrier
	s_add_u32 s8, s8, 0x100
	s_addc_u32 s9, s9, 0
	s_add_u32 s49, s49, 0x100
	s_addc_u32 s53, s53, 0
	s_cmp_ge_i32 s55, s3
	s_mov_b32 s42, s55
	s_cbranch_scc0 .Lkt_L_12
	s_branch .Lkt_exit_12
.Lkt_T_12:
	ds_read_b128 v[162:165], v168
	s_waitcnt vmcnt(0)
	ds_read_b128 v[172:175], v168 offset:1024
	ds_read_b128 v[176:179], v168 offset:2048
	ds_read_b128 v[180:183], v168 offset:3072
	ds_read_b128 v[184:187], v169
	ds_read_b128 v[188:191], v169 offset:1024
	ds_read_b128 v[196:199], v169 offset:2048
	ds_read_b128 v[200:203], v169 offset:3072
	s_add_i32 s55, s42, 2
	s_add_u32 s43, s8, 0xfff00080
	s_addc_u32 s46, s9, -1
	s_cmp_eq_u32 s48, s42
	s_cselect_b32 s42, s41, s49
	s_cselect_b32 s47, s31, s46
	s_cselect_b32 s46, s33, s43
	s_cselect_b32 s43, s35, s53
	v_lshl_add_u64 v[166:167], s[8:9], 0, v[150:151]
	s_add_i32 m0, s62, 0xc000
	ds_read_b128 v[206:209], v170
	ds_read_b128 v[210:213], v170 offset:1024
	ds_read_b128 v[214:217], v170 offset:2048
	ds_read_b128 v[218:221], v170 offset:3072
	ds_read_b128 v[222:225], v170 offset:4096
	ds_read_b128 v[226:229], v170 offset:5120
	ds_read_b128 v[230:233], v170 offset:6144
	ds_read_b128 v[234:237], v170 offset:7168
	global_load_lds_dwordx4 v[166:167], off
	v_lshl_add_u64 v[166:167], s[8:9], 0, v[152:153]
	s_add_i32 m0, s62, 0xe000
	s_nop 0
	global_load_lds_dwordx4 v[166:167], off
	s_waitcnt vmcnt(8)
	s_waitcnt lgkmcnt(0)
	s_barrier
	s_setprio 2
	v_mfma_f32_16x16x32_bf16 v[66:69], v[162:165], v[206:209], v[66:69]
	v_mfma_f32_16x16x32_bf16 v[62:65], v[176:179], v[206:209], v[62:65]
	v_mfma_f32_16x16x32_bf16 v[58:61], v[162:165], v[214:217], v[58:61]
	v_mfma_f32_16x16x32_bf16 v[54:57], v[176:179], v[214:217], v[54:57]
	v_mfma_f32_16x16x32_bf16 v[50:53], v[162:165], v[222:225], v[50:53]
	v_mfma_f32_16x16x32_bf16 v[46:49], v[176:179], v[222:225], v[46:49]
	v_mfma_f32_16x16x32_bf16 v[38:41], v[162:165], v[230:233], v[38:41]
	v_mfma_f32_16x16x32_bf16 v[30:33], v[176:179], v[230:233], v[30:33]
	v_mfma_f32_16x16x32_bf16 v[66:69], v[172:175], v[210:213], v[66:69]
	v_mfma_f32_16x16x32_bf16 v[62:65], v[180:183], v[210:213], v[62:65]
	v_mfma_f32_16x16x32_bf16 v[58:61], v[172:175], v[218:221], v[58:61]
	v_mfma_f32_16x16x32_bf16 v[54:57], v[180:183], v[218:221], v[54:57]
	v_mfma_f32_16x16x32_bf16 v[50:53], v[172:175], v[226:229], v[50:53]
	v_mfma_f32_16x16x32_bf16 v[46:49], v[180:183], v[226:229], v[46:49]
	v_mfma_f32_16x16x32_bf16 v[38:41], v[172:175], v[234:237], v[38:41]
	v_mfma_f32_16x16x32_bf16 v[30:33], v[180:183], v[234:237], v[30:33]
	v_mfma_f32_16x16x32_bf16 v[42:45], v[184:187], v[206:209], v[42:45]
	v_mfma_f32_16x16x32_bf16 v[34:37], v[196:199], v[206:209], v[34:37]
	v_mfma_f32_16x16x32_bf16 v[26:29], v[184:187], v[214:217], v[26:29]
	v_mfma_f32_16x16x32_bf16 v[22:25], v[196:199], v[214:217], v[22:25]
	v_mfma_f32_16x16x32_bf16 v[18:21], v[184:187], v[222:225], v[18:21]
	v_mfma_f32_16x16x32_bf16 v[14:17], v[196:199], v[222:225], v[14:17]
	v_mfma_f32_16x16x32_bf16 v[10:13], v[184:187], v[230:233], v[10:13]
	v_mfma_f32_16x16x32_bf16 v[6:9], v[196:199], v[230:233], v[6:9]
	v_mfma_f32_16x16x32_bf16 v[42:45], v[188:191], v[210:213], v[42:45]
	v_mfma_f32_16x16x32_bf16 v[34:37], v[200:203], v[210:213], v[34:37]
	v_mfma_f32_16x16x32_bf16 v[26:29], v[188:191], v[218:221], v[26:29]
	v_mfma_f32_16x16x32_bf16 v[22:25], v[200:203], v[218:221], v[22:25]
	v_mfma_f32_16x16x32_bf16 v[18:21], v[188:191], v[226:229], v[18:21]
	v_mfma_f32_16x16x32_bf16 v[14:17], v[200:203], v[226:229], v[14:17]
	v_mfma_f32_16x16x32_bf16 v[10:13], v[188:191], v[234:237], v[10:13]
	v_mfma_f32_16x16x32_bf16 v[6:9], v[200:203], v[234:237], v[6:9]
	s_setprio 0
	s_add_i32 s80, s72, s61
	v_lshl_add_u64 v[166:167], s[42:43], 0, v[134:135]
	s_mov_b32 m0, s80
	ds_read_b128 v[206:209], v170 offset:16384
	ds_read_b128 v[210:213], v170 offset:17408
	ds_read_b128 v[214:217], v170 offset:18432
	ds_read_b128 v[218:221], v170 offset:19456
	ds_read_b128 v[222:225], v170 offset:20480
	ds_read_b128 v[226:229], v170 offset:21504
	ds_read_b128 v[230:233], v170 offset:22528
	ds_read_b128 v[234:237], v170 offset:23552
	global_load_lds_dwordx4 v[166:167], off
	s_add_i32 m0, s80, 0x2000
	s_add_u32 s80, s42, 0x100000
	v_lshl_add_u64 v[192:193], s[42:43], 0, v[138:139]
	s_addc_u32 s81, s43, 0
	s_add_i32 s82, s73, s61
	global_load_lds_dwordx4 v[192:193], off
	v_lshl_add_u64 v[238:239], s[80:81], 0, v[134:135]
	s_mov_b32 m0, s82
	v_lshl_add_u64 v[240:241], s[46:47], 0, v[136:137]
	global_load_lds_dwordx4 v[238:239], off
	v_lshl_add_u64 v[238:239], s[80:81], 0, v[138:139]
	s_add_i32 m0, s82, 0x2000
	s_nop 0
	global_load_lds_dwordx4 v[238:239], off
	v_lshl_add_u64 v[238:239], s[46:47], 0, v[132:133]
	s_mov_b32 m0, s62
	s_nop 0
	global_load_lds_dwordx4 v[238:239], off
	s_mov_b32 m0, s63
	s_nop 0
	global_load_lds_dwordx4 v[240:241], off
	s_waitcnt vmcnt(8)
	s_waitcnt lgkmcnt(0)
	s_barrier
	s_setprio 2
	v_mfma_f32_16x16x32_bf16 v[126:129], v[162:165], v[206:209], v[126:129]
	v_mfma_f32_16x16x32_bf16 v[122:125], v[176:179], v[206:209], v[122:125]
	v_mfma_f32_16x16x32_bf16 v[110:113], v[162:165], v[214:217], v[110:113]
	v_mfma_f32_16x16x32_bf16 v[106:109], v[176:179], v[214:217], v[106:109]
	v_mfma_f32_16x16x32_bf16 v[94:97], v[162:165], v[222:225], v[94:97]
	v_mfma_f32_16x16x32_bf16 v[90:93], v[176:179], v[222:225], v[90:93]
	v_mfma_f32_16x16x32_bf16 v[78:81], v[162:165], v[230:233], v[78:81]
	v_mfma_f32_16x16x32_bf16 v[74:77], v[176:179], v[230:233], v[74:77]
	v_mfma_f32_16x16x32_bf16 v[126:129], v[172:175], v[210:213], v[126:129]
	v_mfma_f32_16x16x32_bf16 v[122:125], v[180:183], v[210:213], v[122:125]
	v_mfma_f32_16x16x32_bf16 v[110:113], v[172:175], v[218:221], v[110:113]
	v_mfma_f32_16x16x32_bf16 v[106:109], v[180:183], v[218:221], v[106:109]
	v_mfma_f32_16x16x32_bf16 v[94:97], v[172:175], v[226:229], v[94:97]
	v_mfma_f32_16x16x32_bf16 v[90:93], v[180:183], v[226:229], v[90:93]
	v_mfma_f32_16x16x32_bf16 v[78:81], v[172:175], v[234:237], v[78:81]
	v_mfma_f32_16x16x32_bf16 v[74:77], v[180:183], v[234:237], v[74:77]
	v_mfma_f32_16x16x32_bf16 v[118:121], v[184:187], v[206:209], v[118:121]
	v_mfma_f32_16x16x32_bf16 v[114:117], v[196:199], v[206:209], v[114:117]
	v_mfma_f32_16x16x32_bf16 v[102:105], v[184:187], v[214:217], v[102:105]
	v_mfma_f32_16x16x32_bf16 v[98:101], v[196:199], v[214:217], v[98:101]
	v_mfma_f32_16x16x32_bf16 v[86:89], v[184:187], v[222:225], v[86:89]
	v_mfma_f32_16x16x32_bf16 v[82:85], v[196:199], v[222:225], v[82:85]
	v_mfma_f32_16x16x32_bf16 v[70:73], v[184:187], v[230:233], v[70:73]
	v_mfma_f32_16x16x32_bf16 v[2:5], v[196:199], v[230:233], v[2:5]
	v_mfma_f32_16x16x32_bf16 v[118:121], v[188:191], v[210:213], v[118:121]
	v_mfma_f32_16x16x32_bf16 v[114:117], v[200:203], v[210:213], v[114:117]
	v_mfma_f32_16x16x32_bf16 v[102:105], v[188:191], v[218:221], v[102:105]
	v_mfma_f32_16x16x32_bf16 v[98:101], v[200:203], v[218:221], v[98:101]
	v_mfma_f32_16x16x32_bf16 v[86:89], v[188:191], v[226:229], v[86:89]
	v_mfma_f32_16x16x32_bf16 v[82:85], v[200:203], v[226:229], v[82:85]
	v_mfma_f32_16x16x32_bf16 v[70:73], v[188:191], v[234:237], v[70:73]
	v_mfma_f32_16x16x32_bf16 v[2:5], v[200:203], v[234:237], v[2:5]
	s_setprio 0
	s_add_i32 s80, 0, 0x18000
	s_add_i32 s81, 0, 0x1c000
	v_add_u32_e32 v180, s80, v131
	v_add_u32_e32 v200, s81, v131
	ds_read_b128 v[162:165], v180
	ds_read_b128 v[172:175], v180 offset:1024
	ds_read_b128 v[176:179], v180 offset:2048
	ds_read_b128 v[180:183], v180 offset:3072
	ds_read_b128 v[184:187], v200
	ds_read_b128 v[188:191], v200 offset:1024
	ds_read_b128 v[196:199], v200 offset:2048
	ds_read_b128 v[200:203], v200 offset:3072
	s_add_u32 s46, s46, 0x100000
	s_addc_u32 s47, s47, 0
	s_mov_b32 m0, s64
	v_lshl_add_u64 v[242:243], s[46:47], 0, v[132:133]
	ds_read_b128 v[206:209], v170 offset:32768
	ds_read_b128 v[210:213], v170 offset:33792
	ds_read_b128 v[214:217], v170 offset:34816
	ds_read_b128 v[218:221], v170 offset:35840
	ds_read_b128 v[222:225], v170 offset:36864
	ds_read_b128 v[226:229], v170 offset:37888
	ds_read_b128 v[230:233], v170 offset:38912
	ds_read_b128 v[234:237], v170 offset:39936
	global_load_lds_dwordx4 v[242:243], off
	v_lshl_add_u64 v[242:243], s[46:47], 0, v[136:137]
	s_mov_b32 m0, s65
	s_nop 0
	global_load_lds_dwordx4 v[242:243], off
	s_waitcnt vmcnt(8)
	s_waitcnt lgkmcnt(0)
	s_barrier
	s_setprio 2
	v_mfma_f32_16x16x32_bf16 v[66:69], v[162:165], v[206:209], v[66:69]
	v_mfma_f32_16x16x32_bf16 v[62:65], v[176:179], v[206:209], v[62:65]
	v_mfma_f32_16x16x32_bf16 v[58:61], v[162:165], v[214:217], v[58:61]
	v_mfma_f32_16x16x32_bf16 v[54:57], v[176:179], v[214:217], v[54:57]
	v_mfma_f32_16x16x32_bf16 v[50:53], v[162:165], v[222:225], v[50:53]
	v_mfma_f32_16x16x32_bf16 v[46:49], v[176:179], v[222:225], v[46:49]
	v_mfma_f32_16x16x32_bf16 v[38:41], v[162:165], v[230:233], v[38:41]
	v_mfma_f32_16x16x32_bf16 v[30:33], v[176:179], v[230:233], v[30:33]
	v_mfma_f32_16x16x32_bf16 v[66:69], v[172:175], v[210:213], v[66:69]
	v_mfma_f32_16x16x32_bf16 v[62:65], v[180:183], v[210:213], v[62:65]
	v_mfma_f32_16x16x32_bf16 v[58:61], v[172:175], v[218:221], v[58:61]
	v_mfma_f32_16x16x32_bf16 v[54:57], v[180:183], v[218:221], v[54:57]
	v_mfma_f32_16x16x32_bf16 v[50:53], v[172:175], v[226:229], v[50:53]
	v_mfma_f32_16x16x32_bf16 v[46:49], v[180:183], v[226:229], v[46:49]
	v_mfma_f32_16x16x32_bf16 v[38:41], v[172:175], v[234:237], v[38:41]
	v_mfma_f32_16x16x32_bf16 v[30:33], v[180:183], v[234:237], v[30:33]
	v_mfma_f32_16x16x32_bf16 v[42:45], v[184:187], v[206:209], v[42:45]
	v_mfma_f32_16x16x32_bf16 v[34:37], v[196:199], v[206:209], v[34:37]
	v_mfma_f32_16x16x32_bf16 v[26:29], v[184:187], v[214:217], v[26:29]
	v_mfma_f32_16x16x32_bf16 v[22:25], v[196:199], v[214:217], v[22:25]
	v_mfma_f32_16x16x32_bf16 v[18:21], v[184:187], v[222:225], v[18:21]
	v_mfma_f32_16x16x32_bf16 v[14:17], v[196:199], v[222:225], v[14:17]
	v_mfma_f32_16x16x32_bf16 v[10:13], v[184:187], v[230:233], v[10:13]
	v_mfma_f32_16x16x32_bf16 v[6:9], v[196:199], v[230:233], v[6:9]
	v_mfma_f32_16x16x32_bf16 v[42:45], v[188:191], v[210:213], v[42:45]
	v_mfma_f32_16x16x32_bf16 v[34:37], v[200:203], v[210:213], v[34:37]
	v_mfma_f32_16x16x32_bf16 v[26:29], v[188:191], v[218:221], v[26:29]
	v_mfma_f32_16x16x32_bf16 v[22:25], v[200:203], v[218:221], v[22:25]
	v_mfma_f32_16x16x32_bf16 v[18:21], v[188:191], v[226:229], v[18:21]
	v_mfma_f32_16x16x32_bf16 v[14:17], v[200:203], v[226:229], v[14:17]
	v_mfma_f32_16x16x32_bf16 v[10:13], v[188:191], v[234:237], v[10:13]
	v_mfma_f32_16x16x32_bf16 v[6:9], v[200:203], v[234:237], v[6:9]
	s_setprio 0
	s_add_i32 s46, s80, s61
	v_lshl_add_u64 v[166:167], v[166:167], 0, s[18:19]
	s_mov_b32 m0, s46
	ds_read_b128 v[206:209], v170 offset:49152
	ds_read_b128 v[210:213], v170 offset:50176
	ds_read_b128 v[214:217], v170 offset:51200
	ds_read_b128 v[218:221], v170 offset:52224
	ds_read_b128 v[222:225], v170 offset:53248
	ds_read_b128 v[226:229], v170 offset:54272
	ds_read_b128 v[230:233], v170 offset:55296
	ds_read_b128 v[234:237], v170 offset:56320
	global_load_lds_dwordx4 v[166:167], off
	s_add_i32 m0, s46, 0x2000
	s_add_u32 s42, s42, 0x100080
	v_lshl_add_u64 v[166:167], v[192:193], 0, s[18:19]
	s_addc_u32 s43, s43, 0
	s_add_i32 s46, s81, s61
	global_load_lds_dwordx4 v[166:167], off
	v_lshl_add_u64 v[166:167], s[42:43], 0, v[134:135]
	s_mov_b32 m0, s46
	s_nop 0
	global_load_lds_dwordx4 v[166:167], off
	v_lshl_add_u64 v[166:167], s[42:43], 0, v[138:139]
	s_add_i32 m0, s46, 0x2000
	s_nop 0
	global_load_lds_dwordx4 v[166:167], off
	v_lshl_add_u64 v[166:167], v[238:239], 0, s[18:19]
	s_mov_b32 m0, s69
	s_nop 0
	global_load_lds_dwordx4 v[166:167], off
	v_lshl_add_u64 v[166:167], v[240:241], 0, s[18:19]
	s_mov_b32 m0, s70
	s_nop 0
	global_load_lds_dwordx4 v[166:167], off
	s_waitcnt vmcnt(8)
	s_waitcnt lgkmcnt(0)
	s_barrier
	s_setprio 2
	v_mfma_f32_16x16x32_bf16 v[126:129], v[162:165], v[206:209], v[126:129]
	v_mfma_f32_16x16x32_bf16 v[122:125], v[176:179], v[206:209], v[122:125]
	v_mfma_f32_16x16x32_bf16 v[110:113], v[162:165], v[214:217], v[110:113]
	v_mfma_f32_16x16x32_bf16 v[106:109], v[176:179], v[214:217], v[106:109]
	v_mfma_f32_16x16x32_bf16 v[94:97], v[162:165], v[222:225], v[94:97]
	v_mfma_f32_16x16x32_bf16 v[90:93], v[176:179], v[222:225], v[90:93]
	v_mfma_f32_16x16x32_bf16 v[78:81], v[162:165], v[230:233], v[78:81]
	v_mfma_f32_16x16x32_bf16 v[74:77], v[176:179], v[230:233], v[74:77]
	v_mfma_f32_16x16x32_bf16 v[126:129], v[172:175], v[210:213], v[126:129]
	v_mfma_f32_16x16x32_bf16 v[122:125], v[180:183], v[210:213], v[122:125]
	v_mfma_f32_16x16x32_bf16 v[110:113], v[172:175], v[218:221], v[110:113]
	v_mfma_f32_16x16x32_bf16 v[106:109], v[180:183], v[218:221], v[106:109]
	v_mfma_f32_16x16x32_bf16 v[94:97], v[172:175], v[226:229], v[94:97]
	v_mfma_f32_16x16x32_bf16 v[90:93], v[180:183], v[226:229], v[90:93]
	v_mfma_f32_16x16x32_bf16 v[78:81], v[172:175], v[234:237], v[78:81]
	v_mfma_f32_16x16x32_bf16 v[74:77], v[180:183], v[234:237], v[74:77]
	v_mfma_f32_16x16x32_bf16 v[118:121], v[184:187], v[206:209], v[118:121]
	v_mfma_f32_16x16x32_bf16 v[114:117], v[196:199], v[206:209], v[114:117]
	v_mfma_f32_16x16x32_bf16 v[102:105], v[184:187], v[214:217], v[102:105]
	v_mfma_f32_16x16x32_bf16 v[98:101], v[196:199], v[214:217], v[98:101]
	v_mfma_f32_16x16x32_bf16 v[86:89], v[184:187], v[222:225], v[86:89]
	v_mfma_f32_16x16x32_bf16 v[82:85], v[196:199], v[222:225], v[82:85]
	v_mfma_f32_16x16x32_bf16 v[70:73], v[184:187], v[230:233], v[70:73]
	v_mfma_f32_16x16x32_bf16 v[2:5], v[196:199], v[230:233], v[2:5]
	v_mfma_f32_16x16x32_bf16 v[118:121], v[188:191], v[210:213], v[118:121]
	v_mfma_f32_16x16x32_bf16 v[114:117], v[200:203], v[210:213], v[114:117]
	v_mfma_f32_16x16x32_bf16 v[102:105], v[188:191], v[218:221], v[102:105]
	v_mfma_f32_16x16x32_bf16 v[98:101], v[200:203], v[218:221], v[98:101]
	v_mfma_f32_16x16x32_bf16 v[86:89], v[188:191], v[226:229], v[86:89]
	v_mfma_f32_16x16x32_bf16 v[82:85], v[200:203], v[226:229], v[82:85]
	v_mfma_f32_16x16x32_bf16 v[70:73], v[188:191], v[234:237], v[70:73]
	v_mfma_f32_16x16x32_bf16 v[2:5], v[200:203], v[234:237], v[2:5]
	s_setprio 0
	s_add_u32 s8, s8, 0x100
	s_addc_u32 s9, s9, 0
	s_add_u32 s49, s49, 0x100
	s_addc_u32 s53, s53, 0
	s_cmp_ge_i32 s55, s3
	s_mov_b32 s42, s55
	s_cbranch_scc0 .Lkt_T_12
	s_nop 7
.Lkt_exit_12:
	s_and_b64 vcc, exec, s[20:21]
	s_cbranch_vccz .LBB0_1874
	v_lshl_or_b32 v162, s40, 8, v141
	s_cmp_lt_i32 s10, 0
	s_mov_b64 s[8:9], -1
	s_cbranch_scc1 .LBB0_1875

.LBB0_3632:
	s_add_u32 s14, s38, 0x31800000
	s_addc_u32 s15, s39, 0
	s_add_u32 s16, s38, 0x39c00000
	s_addc_u32 s17, s39, 0
	s_add_u32 s18, s38, 0x218000
	s_addc_u32 s19, s39, 0
	s_add_u32 s69, s38, 0x50600000
	s_addc_u32 s70, s39, 0
	s_lshl_b32 s4, s7, 5
	s_mov_b64 s[20:21], 0x80
	s_and_b32 s7, s4, 0x60
	s_add_i32 m0, s61, 0x18000
	v_lshl_add_u64 v[8:9], v[8:9], 0, s[20:21]
	s_lshl_b32 s23, s6, 13
	s_lshl_b32 s24, s7, 7
	s_ashr_i32 s71, s2, 31
	s_waitcnt vmcnt(2)
	s_barrier
	global_load_lds_dwordx4 v[8:9], off
	v_lshl_add_u64 v[4:5], v[4:5], 0, s[20:21]
	s_add_i32 m0, s61, 0x1a000
	s_add_i32 s72, s61, 0x8000
	s_add_i32 s73, s61, 0xa000
	global_load_lds_dwordx4 v[4:5], off
	v_lshl_add_u64 v[2:3], v[2:3], 0, s[20:21]
	s_mov_b32 m0, s72
	s_add_u32 s4, s48, 0x100080
	global_load_lds_dwordx4 v[2:3], off
	v_lshl_add_u64 v[2:3], v[6:7], 0, s[20:21]
	s_mov_b32 m0, s73
	s_addc_u32 s5, s49, 0
	global_load_lds_dwordx4 v[2:3], off
	s_add_i32 m0, s61, 0x1c000
	v_lshl_add_u64 v[2:3], s[4:5], 0, v[134:135]
	global_load_lds_dwordx4 v[2:3], off
	v_lshl_add_u64 v[2:3], s[4:5], 0, v[138:139]
	s_add_i32 m0, s61, 0x1e000
	v_lshlrev_b32_e32 v4, 2, v0
	global_load_lds_dwordx4 v[2:3], off
	v_and_b32_e32 v2, 15, v0
	v_lshlrev_b32_e32 v3, 1, v13
	v_lshlrev_b32_e32 v5, 6, v0
	s_movk_i32 s4, 0x3c0
	v_lshl_or_b32 v131, s6, 6, v2
	v_lshl_or_b32 v2, v2, 6, v3
	v_and_b32_e32 v4, 32, v4
	v_and_or_b32 v3, v5, s4, v3
	v_bitop3_b32 v160, s24, v3, v4 bitop3:0xf6
	v_lshlrev_b32_e32 v3, 10, v0
	v_bitop3_b32 v2, v2, s23, v4 bitop3:0xde
	v_and_b32_e32 v3, 0x60000, v3
	v_lshlrev_b32_e32 v4, 13, v12
	v_or3_b32 v3, v10, v3, v4
	v_add_u32_e32 v140, v3, v11
	v_lshlrev_b32_e32 v3, 6, v14
	s_waitcnt vmcnt(6)
	s_cmpk_lt_u32 s22, 0x100
	v_and_b32_e32 v3, 0xe0000, v3
	s_cselect_b64 s[22:23], -1, 0
	v_or3_b32 v3, v10, v3, v4
	s_add_i32 s75, 0, 0x10000
	s_add_i32 s76, 0, 0x14000
	s_brev_b32 s24, 31
	s_mov_b32 s26, 0xf8040000
	s_mov_b32 s28, 0xf8080000
	s_mov_b32 s30, 0xf80c0000
	s_ashr_i32 s74, s44, 31
	v_or_b32_e32 v161, s7, v13
	v_mov_b32_e32 v141, v135
	v_add_u32_e32 v142, v3, v11
	v_mov_b32_e32 v143, v135
	v_mov_b64_e32 v[144:145], 0x300
	v_mov_b64_e32 v[146:147], 0x2ff
	v_add_u32_e32 v162, s75, v160
	v_add_u32_e32 v163, s76, v160
	v_add_u32_e32 v164, 0, v2
	v_mov_b32_e32 v165, 0x358637bd
	s_mov_b32 s77, 0xf800000
	v_mov_b32_e32 v166, 0x260
	s_mov_b32 s25, -1
	s_brev_b32 s78, 31
	s_mov_b32 s27, -1
	s_mov_b32 s79, 0xf8040000
	s_mov_b32 s29, -1
	s_mov_b32 s80, 0xf8080000
	s_mov_b32 s31, -1
	s_mov_b32 s81, 0xf80c0000
	s_mov_b32 s34, 0x3fb504f3
	s_mov_b64 s[40:41], 0x120000
	s_mov_b64 s[42:43], 0x140000
	s_mov_b64 s[46:47], 0x160000
	v_mov_b64_e32 v[148:149], 0x1ff
	v_mov_b64_e32 v[150:151], 0x200
	s_mov_b32 s82, s9
	s_branch .LBB0_3635

.Lkt_L_13:
	ds_read_b128 v[152:155], v162
	ds_read_b128 v[156:159], v162 offset:1024
	ds_read_b128 v[168:171], v162 offset:2048
	ds_read_b128 v[172:175], v162 offset:3072
	ds_read_b128 v[176:179], v163
	ds_read_b128 v[180:183], v163 offset:1024
	ds_read_b128 v[184:187], v163 offset:2048
	ds_read_b128 v[188:191], v163 offset:3072
	s_add_i32 s86, s48, 2
	s_add_u32 s49, s6, 0xfff00080
	s_addc_u32 s64, s7, -1
	s_cmp_eq_u32 s51, s48
	s_cselect_b32 s48, s58, s53
	s_cselect_b32 s65, s57, s64
	s_cselect_b32 s64, s56, s49
	s_cselect_b32 s49, s59, s55
	v_lshl_add_u64 v[192:193], s[6:7], 0, v[140:141]
	s_add_i32 m0, s61, 0xc000
	ds_read_b128 v[196:199], v164
	ds_read_b128 v[200:203], v164 offset:1024
	ds_read_b128 v[206:209], v164 offset:2048
	ds_read_b128 v[210:213], v164 offset:3072
	ds_read_b128 v[214:217], v164 offset:4096
	ds_read_b128 v[218:221], v164 offset:5120
	ds_read_b128 v[222:225], v164 offset:6144
	ds_read_b128 v[226:229], v164 offset:7168
	global_load_lds_dwordx4 v[192:193], off
	v_lshl_add_u64 v[192:193], s[6:7], 0, v[142:143]
	s_add_i32 m0, s61, 0xe000
	s_nop 0
	global_load_lds_dwordx4 v[192:193], off
	s_waitcnt lgkmcnt(0)
	s_setprio 1
	v_mfma_f32_16x16x32_bf16 v[126:129], v[152:155], v[196:199], v[126:129]
	v_mfma_f32_16x16x32_bf16 v[122:125], v[168:171], v[196:199], v[122:125]
	v_mfma_f32_16x16x32_bf16 v[110:113], v[152:155], v[206:209], v[110:113]
	v_mfma_f32_16x16x32_bf16 v[106:109], v[168:171], v[206:209], v[106:109]
	v_mfma_f32_16x16x32_bf16 v[94:97], v[152:155], v[214:217], v[94:97]
	v_mfma_f32_16x16x32_bf16 v[90:93], v[168:171], v[214:217], v[90:93]
	v_mfma_f32_16x16x32_bf16 v[78:81], v[152:155], v[222:225], v[78:81]
	v_mfma_f32_16x16x32_bf16 v[74:77], v[168:171], v[222:225], v[74:77]
	v_mfma_f32_16x16x32_bf16 v[126:129], v[156:159], v[200:203], v[126:129]
	v_mfma_f32_16x16x32_bf16 v[122:125], v[172:175], v[200:203], v[122:125]
	v_mfma_f32_16x16x32_bf16 v[110:113], v[156:159], v[210:213], v[110:113]
	v_mfma_f32_16x16x32_bf16 v[106:109], v[172:175], v[210:213], v[106:109]
	v_mfma_f32_16x16x32_bf16 v[94:97], v[156:159], v[218:221], v[94:97]
	v_mfma_f32_16x16x32_bf16 v[90:93], v[172:175], v[218:221], v[90:93]
	v_mfma_f32_16x16x32_bf16 v[78:81], v[156:159], v[226:229], v[78:81]
	v_mfma_f32_16x16x32_bf16 v[74:77], v[172:175], v[226:229], v[74:77]
	v_mfma_f32_16x16x32_bf16 v[118:121], v[176:179], v[196:199], v[118:121]
	v_mfma_f32_16x16x32_bf16 v[114:117], v[184:187], v[196:199], v[114:117]
	v_mfma_f32_16x16x32_bf16 v[102:105], v[176:179], v[206:209], v[102:105]
	v_mfma_f32_16x16x32_bf16 v[98:101], v[184:187], v[206:209], v[98:101]
	v_mfma_f32_16x16x32_bf16 v[86:89], v[176:179], v[214:217], v[86:89]
	v_mfma_f32_16x16x32_bf16 v[82:85], v[184:187], v[214:217], v[82:85]
	v_mfma_f32_16x16x32_bf16 v[70:73], v[176:179], v[222:225], v[70:73]
	v_mfma_f32_16x16x32_bf16 v[66:69], v[184:187], v[222:225], v[66:69]
	v_mfma_f32_16x16x32_bf16 v[118:121], v[180:183], v[200:203], v[118:121]
	v_mfma_f32_16x16x32_bf16 v[114:117], v[188:191], v[200:203], v[114:117]
	v_mfma_f32_16x16x32_bf16 v[102:105], v[180:183], v[210:213], v[102:105]
	v_mfma_f32_16x16x32_bf16 v[98:101], v[188:191], v[210:213], v[98:101]
	v_mfma_f32_16x16x32_bf16 v[86:89], v[180:183], v[218:221], v[86:89]
	v_mfma_f32_16x16x32_bf16 v[82:85], v[188:191], v[218:221], v[82:85]
	v_mfma_f32_16x16x32_bf16 v[70:73], v[180:183], v[226:229], v[70:73]
	v_mfma_f32_16x16x32_bf16 v[66:69], v[188:191], v[226:229], v[66:69]
	s_setprio 0
	s_waitcnt vmcnt(8)
	s_barrier
	s_add_i32 s87, s75, s66
	v_lshl_add_u64 v[192:193], s[48:49], 0, v[134:135]
	s_mov_b32 m0, s87
	ds_read_b128 v[196:199], v164 offset:16384
	ds_read_b128 v[200:203], v164 offset:17408
	ds_read_b128 v[206:209], v164 offset:18432
	ds_read_b128 v[210:213], v164 offset:19456
	ds_read_b128 v[214:217], v164 offset:20480
	ds_read_b128 v[218:221], v164 offset:21504
	ds_read_b128 v[222:225], v164 offset:22528
	ds_read_b128 v[226:229], v164 offset:23552
	global_load_lds_dwordx4 v[192:193], off
	s_add_i32 m0, s87, 0x2000
	s_add_u32 s88, s48, 0x100000
	v_lshl_add_u64 v[230:231], s[48:49], 0, v[138:139]
	s_addc_u32 s89, s49, 0
	s_add_i32 s87, s76, s66
	global_load_lds_dwordx4 v[230:231], off
	v_lshl_add_u64 v[232:233], s[88:89], 0, v[134:135]
	s_mov_b32 m0, s87
	v_lshl_add_u64 v[234:235], s[64:65], 0, v[136:137]
	global_load_lds_dwordx4 v[232:233], off
	v_lshl_add_u64 v[232:233], s[88:89], 0, v[138:139]
	s_add_i32 m0, s87, 0x2000
	s_nop 0
	global_load_lds_dwordx4 v[232:233], off
	v_lshl_add_u64 v[232:233], s[64:65], 0, v[132:133]
	s_mov_b32 m0, s61
	s_nop 0
	global_load_lds_dwordx4 v[232:233], off
	s_mov_b32 m0, s63
	s_nop 0
	global_load_lds_dwordx4 v[234:235], off
	s_waitcnt lgkmcnt(0)
	s_setprio 1
	v_mfma_f32_16x16x32_bf16 v[62:65], v[152:155], v[196:199], v[62:65]
	v_mfma_f32_16x16x32_bf16 v[58:61], v[168:171], v[196:199], v[58:61]
	v_mfma_f32_16x16x32_bf16 v[46:49], v[152:155], v[206:209], v[46:49]
	v_mfma_f32_16x16x32_bf16 v[42:45], v[168:171], v[206:209], v[42:45]
	v_mfma_f32_16x16x32_bf16 v[30:33], v[152:155], v[214:217], v[30:33]
	v_mfma_f32_16x16x32_bf16 v[26:29], v[168:171], v[214:217], v[26:29]
	v_mfma_f32_16x16x32_bf16 v[14:17], v[152:155], v[222:225], v[14:17]
	v_mfma_f32_16x16x32_bf16 v[10:13], v[168:171], v[222:225], v[10:13]
	v_mfma_f32_16x16x32_bf16 v[62:65], v[156:159], v[200:203], v[62:65]
	v_mfma_f32_16x16x32_bf16 v[58:61], v[172:175], v[200:203], v[58:61]
	v_mfma_f32_16x16x32_bf16 v[46:49], v[156:159], v[210:213], v[46:49]
	v_mfma_f32_16x16x32_bf16 v[42:45], v[172:175], v[210:213], v[42:45]
	v_mfma_f32_16x16x32_bf16 v[30:33], v[156:159], v[218:221], v[30:33]
	v_mfma_f32_16x16x32_bf16 v[26:29], v[172:175], v[218:221], v[26:29]
	v_mfma_f32_16x16x32_bf16 v[14:17], v[156:159], v[226:229], v[14:17]
	v_mfma_f32_16x16x32_bf16 v[10:13], v[172:175], v[226:229], v[10:13]
	v_mfma_f32_16x16x32_bf16 v[54:57], v[176:179], v[196:199], v[54:57]
	v_mfma_f32_16x16x32_bf16 v[50:53], v[184:187], v[196:199], v[50:53]
	v_mfma_f32_16x16x32_bf16 v[38:41], v[176:179], v[206:209], v[38:41]
	v_mfma_f32_16x16x32_bf16 v[34:37], v[184:187], v[206:209], v[34:37]
	v_mfma_f32_16x16x32_bf16 v[22:25], v[176:179], v[214:217], v[22:25]
	v_mfma_f32_16x16x32_bf16 v[18:21], v[184:187], v[214:217], v[18:21]
	v_mfma_f32_16x16x32_bf16 v[6:9], v[176:179], v[222:225], v[6:9]
	v_mfma_f32_16x16x32_bf16 v[2:5], v[184:187], v[222:225], v[2:5]
	v_mfma_f32_16x16x32_bf16 v[54:57], v[180:183], v[200:203], v[54:57]
	v_mfma_f32_16x16x32_bf16 v[50:53], v[188:191], v[200:203], v[50:53]
	v_mfma_f32_16x16x32_bf16 v[38:41], v[180:183], v[210:213], v[38:41]
	v_mfma_f32_16x16x32_bf16 v[34:37], v[188:191], v[210:213], v[34:37]
	v_mfma_f32_16x16x32_bf16 v[22:25], v[180:183], v[218:221], v[22:25]
	v_mfma_f32_16x16x32_bf16 v[18:21], v[188:191], v[218:221], v[18:21]
	v_mfma_f32_16x16x32_bf16 v[6:9], v[180:183], v[226:229], v[6:9]
	v_mfma_f32_16x16x32_bf16 v[2:5], v[188:191], v[226:229], v[2:5]
	s_setprio 0
	s_waitcnt vmcnt(8)
	s_barrier
	s_add_i32 s87, 0, 0x18000
	v_add_u32_e32 v167, s87, v160
	s_add_i32 s88, 0, 0x1c000
	ds_read_b128 v[152:155], v167
	ds_read_b128 v[156:159], v167 offset:1024
	ds_read_b128 v[168:171], v167 offset:2048
	ds_read_b128 v[172:175], v167 offset:3072
	v_add_u32_e32 v167, s88, v160
	ds_read_b128 v[176:179], v167
	ds_read_b128 v[180:183], v167 offset:1024
	ds_read_b128 v[184:187], v167 offset:2048
	ds_read_b128 v[188:191], v167 offset:3072
	s_add_u32 s64, s64, 0x100000
	s_addc_u32 s65, s65, 0
	s_mov_b32 m0, s67
	v_lshl_add_u64 v[236:237], s[64:65], 0, v[132:133]
	ds_read_b128 v[196:199], v164 offset:32768
	ds_read_b128 v[200:203], v164 offset:33792
	ds_read_b128 v[206:209], v164 offset:34816
	ds_read_b128 v[210:213], v164 offset:35840
	ds_read_b128 v[214:217], v164 offset:36864
	ds_read_b128 v[218:221], v164 offset:37888
	ds_read_b128 v[222:225], v164 offset:38912
	ds_read_b128 v[226:229], v164 offset:39936
	global_load_lds_dwordx4 v[236:237], off
	v_lshl_add_u64 v[236:237], s[64:65], 0, v[136:137]
	s_mov_b32 m0, s68
	s_nop 0
	global_load_lds_dwordx4 v[236:237], off
	s_waitcnt lgkmcnt(0)
	s_setprio 1
	v_mfma_f32_16x16x32_bf16 v[126:129], v[152:155], v[196:199], v[126:129]
	v_mfma_f32_16x16x32_bf16 v[122:125], v[168:171], v[196:199], v[122:125]
	v_mfma_f32_16x16x32_bf16 v[110:113], v[152:155], v[206:209], v[110:113]
	v_mfma_f32_16x16x32_bf16 v[106:109], v[168:171], v[206:209], v[106:109]
	v_mfma_f32_16x16x32_bf16 v[94:97], v[152:155], v[214:217], v[94:97]
	v_mfma_f32_16x16x32_bf16 v[90:93], v[168:171], v[214:217], v[90:93]
	v_mfma_f32_16x16x32_bf16 v[78:81], v[152:155], v[222:225], v[78:81]
	v_mfma_f32_16x16x32_bf16 v[74:77], v[168:171], v[222:225], v[74:77]
	v_mfma_f32_16x16x32_bf16 v[126:129], v[156:159], v[200:203], v[126:129]
	v_mfma_f32_16x16x32_bf16 v[122:125], v[172:175], v[200:203], v[122:125]
	v_mfma_f32_16x16x32_bf16 v[110:113], v[156:159], v[210:213], v[110:113]
	v_mfma_f32_16x16x32_bf16 v[106:109], v[172:175], v[210:213], v[106:109]
	v_mfma_f32_16x16x32_bf16 v[94:97], v[156:159], v[218:221], v[94:97]
	v_mfma_f32_16x16x32_bf16 v[90:93], v[172:175], v[218:221], v[90:93]
	v_mfma_f32_16x16x32_bf16 v[78:81], v[156:159], v[226:229], v[78:81]
	v_mfma_f32_16x16x32_bf16 v[74:77], v[172:175], v[226:229], v[74:77]
	v_mfma_f32_16x16x32_bf16 v[118:121], v[176:179], v[196:199], v[118:121]
	v_mfma_f32_16x16x32_bf16 v[114:117], v[184:187], v[196:199], v[114:117]
	v_mfma_f32_16x16x32_bf16 v[102:105], v[176:179], v[206:209], v[102:105]
	v_mfma_f32_16x16x32_bf16 v[98:101], v[184:187], v[206:209], v[98:101]
	v_mfma_f32_16x16x32_bf16 v[86:89], v[176:179], v[214:217], v[86:89]
	v_mfma_f32_16x16x32_bf16 v[82:85], v[184:187], v[214:217], v[82:85]
	v_mfma_f32_16x16x32_bf16 v[70:73], v[176:179], v[222:225], v[70:73]
	v_mfma_f32_16x16x32_bf16 v[66:69], v[184:187], v[222:225], v[66:69]
	v_mfma_f32_16x16x32_bf16 v[118:121], v[180:183], v[200:203], v[118:121]
	v_mfma_f32_16x16x32_bf16 v[114:117], v[188:191], v[200:203], v[114:117]
	v_mfma_f32_16x16x32_bf16 v[102:105], v[180:183], v[210:213], v[102:105]
	v_mfma_f32_16x16x32_bf16 v[98:101], v[188:191], v[210:213], v[98:101]
	v_mfma_f32_16x16x32_bf16 v[86:89], v[180:183], v[218:221], v[86:89]
	v_mfma_f32_16x16x32_bf16 v[82:85], v[188:191], v[218:221], v[82:85]
	v_mfma_f32_16x16x32_bf16 v[70:73], v[180:183], v[226:229], v[70:73]
	v_mfma_f32_16x16x32_bf16 v[66:69], v[188:191], v[226:229], v[66:69]
	s_setprio 0
	s_waitcnt vmcnt(8)
	s_barrier
	s_add_i32 s64, s87, s66
	v_lshl_add_u64 v[192:193], v[192:193], 0, s[20:21]
	s_mov_b32 m0, s64
	ds_read_b128 v[196:199], v164 offset:49152
	ds_read_b128 v[200:203], v164 offset:50176
	ds_read_b128 v[206:209], v164 offset:51200
	ds_read_b128 v[210:213], v164 offset:52224
	ds_read_b128 v[214:217], v164 offset:53248
	ds_read_b128 v[218:221], v164 offset:54272
	ds_read_b128 v[222:225], v164 offset:55296
	ds_read_b128 v[226:229], v164 offset:56320
	global_load_lds_dwordx4 v[192:193], off
	s_add_i32 m0, s64, 0x2000
	s_add_u32 s48, s48, 0x100080
	v_lshl_add_u64 v[192:193], v[230:231], 0, s[20:21]
	s_addc_u32 s49, s49, 0
	s_add_i32 s64, s88, s66
	global_load_lds_dwordx4 v[192:193], off
	v_lshl_add_u64 v[192:193], s[48:49], 0, v[134:135]
	s_mov_b32 m0, s64
	s_nop 0
	global_load_lds_dwordx4 v[192:193], off
	v_lshl_add_u64 v[192:193], s[48:49], 0, v[138:139]
	s_add_i32 m0, s64, 0x2000
	s_nop 0
	global_load_lds_dwordx4 v[192:193], off
	v_lshl_add_u64 v[192:193], v[232:233], 0, s[20:21]
	s_mov_b32 m0, s72
	s_nop 0
	global_load_lds_dwordx4 v[192:193], off
	v_lshl_add_u64 v[192:193], v[234:235], 0, s[20:21]
	s_mov_b32 m0, s73
	s_nop 0
	global_load_lds_dwordx4 v[192:193], off
	s_waitcnt lgkmcnt(0)
	s_setprio 1
	v_mfma_f32_16x16x32_bf16 v[62:65], v[152:155], v[196:199], v[62:65]
	v_mfma_f32_16x16x32_bf16 v[58:61], v[168:171], v[196:199], v[58:61]
	v_mfma_f32_16x16x32_bf16 v[46:49], v[152:155], v[206:209], v[46:49]
	v_mfma_f32_16x16x32_bf16 v[42:45], v[168:171], v[206:209], v[42:45]
	v_mfma_f32_16x16x32_bf16 v[30:33], v[152:155], v[214:217], v[30:33]
	v_mfma_f32_16x16x32_bf16 v[26:29], v[168:171], v[214:217], v[26:29]
	v_mfma_f32_16x16x32_bf16 v[14:17], v[152:155], v[222:225], v[14:17]
	v_mfma_f32_16x16x32_bf16 v[10:13], v[168:171], v[222:225], v[10:13]
	v_mfma_f32_16x16x32_bf16 v[62:65], v[156:159], v[200:203], v[62:65]
	v_mfma_f32_16x16x32_bf16 v[58:61], v[172:175], v[200:203], v[58:61]
	v_mfma_f32_16x16x32_bf16 v[46:49], v[156:159], v[210:213], v[46:49]
	v_mfma_f32_16x16x32_bf16 v[42:45], v[172:175], v[210:213], v[42:45]
	v_mfma_f32_16x16x32_bf16 v[30:33], v[156:159], v[218:221], v[30:33]
	v_mfma_f32_16x16x32_bf16 v[26:29], v[172:175], v[218:221], v[26:29]
	v_mfma_f32_16x16x32_bf16 v[14:17], v[156:159], v[226:229], v[14:17]
	v_mfma_f32_16x16x32_bf16 v[10:13], v[172:175], v[226:229], v[10:13]
	v_mfma_f32_16x16x32_bf16 v[54:57], v[176:179], v[196:199], v[54:57]
	v_mfma_f32_16x16x32_bf16 v[50:53], v[184:187], v[196:199], v[50:53]
	v_mfma_f32_16x16x32_bf16 v[38:41], v[176:179], v[206:209], v[38:41]
	v_mfma_f32_16x16x32_bf16 v[34:37], v[184:187], v[206:209], v[34:37]
	v_mfma_f32_16x16x32_bf16 v[22:25], v[176:179], v[214:217], v[22:25]
	v_mfma_f32_16x16x32_bf16 v[18:21], v[184:187], v[214:217], v[18:21]
	v_mfma_f32_16x16x32_bf16 v[6:9], v[176:179], v[222:225], v[6:9]
	v_mfma_f32_16x16x32_bf16 v[2:5], v[184:187], v[222:225], v[2:5]
	v_mfma_f32_16x16x32_bf16 v[54:57], v[180:183], v[200:203], v[54:57]
	v_mfma_f32_16x16x32_bf16 v[50:53], v[188:191], v[200:203], v[50:53]
	v_mfma_f32_16x16x32_bf16 v[38:41], v[180:183], v[210:213], v[38:41]
	v_mfma_f32_16x16x32_bf16 v[34:37], v[188:191], v[210:213], v[34:37]
	v_mfma_f32_16x16x32_bf16 v[22:25], v[180:183], v[218:221], v[22:25]
	v_mfma_f32_16x16x32_bf16 v[18:21], v[188:191], v[218:221], v[18:21]
	v_mfma_f32_16x16x32_bf16 v[6:9], v[180:183], v[226:229], v[6:9]
	v_mfma_f32_16x16x32_bf16 v[2:5], v[188:191], v[226:229], v[2:5]
	s_setprio 0
	s_waitcnt vmcnt(8)
	s_barrier
	s_add_u32 s6, s6, 0x100
	s_addc_u32 s7, s7, 0
	s_add_u32 s53, s53, 0x100
	s_addc_u32 s55, s55, 0
	s_cmp_ge_i32 s86, s85
	s_mov_b32 s48, s86
	s_cbranch_scc0 .Lkt_L_13
	s_branch .Lkt_exit_13
.Lkt_T_13:
	ds_read_b128 v[152:155], v162
	ds_read_b128 v[156:159], v162 offset:1024
	ds_read_b128 v[168:171], v162 offset:2048
	ds_read_b128 v[172:175], v162 offset:3072
	ds_read_b128 v[176:179], v163
	ds_read_b128 v[180:183], v163 offset:1024
	ds_read_b128 v[184:187], v163 offset:2048
	ds_read_b128 v[188:191], v163 offset:3072
	s_add_i32 s86, s48, 2
	s_add_u32 s49, s6, 0xfff00080
	s_addc_u32 s64, s7, -1
	s_cmp_eq_u32 s51, s48
	s_cselect_b32 s48, s58, s53
	s_cselect_b32 s65, s57, s64
	s_cselect_b32 s64, s56, s49
	s_cselect_b32 s49, s59, s55
	v_lshl_add_u64 v[192:193], s[6:7], 0, v[140:141]
	s_add_i32 m0, s61, 0xc000
	ds_read_b128 v[196:199], v164
	ds_read_b128 v[200:203], v164 offset:1024
	ds_read_b128 v[206:209], v164 offset:2048
	ds_read_b128 v[210:213], v164 offset:3072
	ds_read_b128 v[214:217], v164 offset:4096
	ds_read_b128 v[218:221], v164 offset:5120
	ds_read_b128 v[222:225], v164 offset:6144
	ds_read_b128 v[226:229], v164 offset:7168
	global_load_lds_dwordx4 v[192:193], off
	v_lshl_add_u64 v[192:193], s[6:7], 0, v[142:143]
	s_add_i32 m0, s61, 0xe000
	s_nop 0
	global_load_lds_dwordx4 v[192:193], off
	s_waitcnt vmcnt(8)
	s_waitcnt lgkmcnt(0)
	s_barrier
	s_setprio 2
	v_mfma_f32_16x16x32_bf16 v[126:129], v[152:155], v[196:199], v[126:129]
	v_mfma_f32_16x16x32_bf16 v[122:125], v[168:171], v[196:199], v[122:125]
	v_mfma_f32_16x16x32_bf16 v[110:113], v[152:155], v[206:209], v[110:113]
	v_mfma_f32_16x16x32_bf16 v[106:109], v[168:171], v[206:209], v[106:109]
	v_mfma_f32_16x16x32_bf16 v[94:97], v[152:155], v[214:217], v[94:97]
	v_mfma_f32_16x16x32_bf16 v[90:93], v[168:171], v[214:217], v[90:93]
	v_mfma_f32_16x16x32_bf16 v[78:81], v[152:155], v[222:225], v[78:81]
	v_mfma_f32_16x16x32_bf16 v[74:77], v[168:171], v[222:225], v[74:77]
	v_mfma_f32_16x16x32_bf16 v[126:129], v[156:159], v[200:203], v[126:129]
	v_mfma_f32_16x16x32_bf16 v[122:125], v[172:175], v[200:203], v[122:125]
	v_mfma_f32_16x16x32_bf16 v[110:113], v[156:159], v[210:213], v[110:113]
	v_mfma_f32_16x16x32_bf16 v[106:109], v[172:175], v[210:213], v[106:109]
	v_mfma_f32_16x16x32_bf16 v[94:97], v[156:159], v[218:221], v[94:97]
	v_mfma_f32_16x16x32_bf16 v[90:93], v[172:175], v[218:221], v[90:93]
	v_mfma_f32_16x16x32_bf16 v[78:81], v[156:159], v[226:229], v[78:81]
	v_mfma_f32_16x16x32_bf16 v[74:77], v[172:175], v[226:229], v[74:77]
	v_mfma_f32_16x16x32_bf16 v[118:121], v[176:179], v[196:199], v[118:121]
	v_mfma_f32_16x16x32_bf16 v[114:117], v[184:187], v[196:199], v[114:117]
	v_mfma_f32_16x16x32_bf16 v[102:105], v[176:179], v[206:209], v[102:105]
	v_mfma_f32_16x16x32_bf16 v[98:101], v[184:187], v[206:209], v[98:101]
	v_mfma_f32_16x16x32_bf16 v[86:89], v[176:179], v[214:217], v[86:89]
	v_mfma_f32_16x16x32_bf16 v[82:85], v[184:187], v[214:217], v[82:85]
	v_mfma_f32_16x16x32_bf16 v[70:73], v[176:179], v[222:225], v[70:73]
	v_mfma_f32_16x16x32_bf16 v[66:69], v[184:187], v[222:225], v[66:69]
	v_mfma_f32_16x16x32_bf16 v[118:121], v[180:183], v[200:203], v[118:121]
	v_mfma_f32_16x16x32_bf16 v[114:117], v[188:191], v[200:203], v[114:117]
	v_mfma_f32_16x16x32_bf16 v[102:105], v[180:183], v[210:213], v[102:105]
	v_mfma_f32_16x16x32_bf16 v[98:101], v[188:191], v[210:213], v[98:101]
	v_mfma_f32_16x16x32_bf16 v[86:89], v[180:183], v[218:221], v[86:89]
	v_mfma_f32_16x16x32_bf16 v[82:85], v[188:191], v[218:221], v[82:85]
	v_mfma_f32_16x16x32_bf16 v[70:73], v[180:183], v[226:229], v[70:73]
	v_mfma_f32_16x16x32_bf16 v[66:69], v[188:191], v[226:229], v[66:69]
	s_setprio 0
	s_add_i32 s87, s75, s66
	v_lshl_add_u64 v[192:193], s[48:49], 0, v[134:135]
	s_mov_b32 m0, s87
	ds_read_b128 v[196:199], v164 offset:16384
	ds_read_b128 v[200:203], v164 offset:17408
	ds_read_b128 v[206:209], v164 offset:18432
	ds_read_b128 v[210:213], v164 offset:19456
	ds_read_b128 v[214:217], v164 offset:20480
	ds_read_b128 v[218:221], v164 offset:21504
	ds_read_b128 v[222:225], v164 offset:22528
	ds_read_b128 v[226:229], v164 offset:23552
	global_load_lds_dwordx4 v[192:193], off
	s_add_i32 m0, s87, 0x2000
	s_add_u32 s88, s48, 0x100000
	v_lshl_add_u64 v[230:231], s[48:49], 0, v[138:139]
	s_addc_u32 s89, s49, 0
	s_add_i32 s87, s76, s66
	global_load_lds_dwordx4 v[230:231], off
	v_lshl_add_u64 v[232:233], s[88:89], 0, v[134:135]
	s_mov_b32 m0, s87
	v_lshl_add_u64 v[234:235], s[64:65], 0, v[136:137]
	global_load_lds_dwordx4 v[232:233], off
	v_lshl_add_u64 v[232:233], s[88:89], 0, v[138:139]
	s_add_i32 m0, s87, 0x2000
	s_nop 0
	global_load_lds_dwordx4 v[232:233], off
	v_lshl_add_u64 v[232:233], s[64:65], 0, v[132:133]
	s_mov_b32 m0, s61
	s_nop 0
	global_load_lds_dwordx4 v[232:233], off
	s_mov_b32 m0, s63
	s_nop 0
	global_load_lds_dwordx4 v[234:235], off
	s_waitcnt vmcnt(8)
	s_waitcnt lgkmcnt(0)
	s_barrier
	s_setprio 2
	v_mfma_f32_16x16x32_bf16 v[62:65], v[152:155], v[196:199], v[62:65]
	v_mfma_f32_16x16x32_bf16 v[58:61], v[168:171], v[196:199], v[58:61]
	v_mfma_f32_16x16x32_bf16 v[46:49], v[152:155], v[206:209], v[46:49]
	v_mfma_f32_16x16x32_bf16 v[42:45], v[168:171], v[206:209], v[42:45]
	v_mfma_f32_16x16x32_bf16 v[30:33], v[152:155], v[214:217], v[30:33]
	v_mfma_f32_16x16x32_bf16 v[26:29], v[168:171], v[214:217], v[26:29]
	v_mfma_f32_16x16x32_bf16 v[14:17], v[152:155], v[222:225], v[14:17]
	v_mfma_f32_16x16x32_bf16 v[10:13], v[168:171], v[222:225], v[10:13]
	v_mfma_f32_16x16x32_bf16 v[62:65], v[156:159], v[200:203], v[62:65]
	v_mfma_f32_16x16x32_bf16 v[58:61], v[172:175], v[200:203], v[58:61]
	v_mfma_f32_16x16x32_bf16 v[46:49], v[156:159], v[210:213], v[46:49]
	v_mfma_f32_16x16x32_bf16 v[42:45], v[172:175], v[210:213], v[42:45]
	v_mfma_f32_16x16x32_bf16 v[30:33], v[156:159], v[218:221], v[30:33]
	v_mfma_f32_16x16x32_bf16 v[26:29], v[172:175], v[218:221], v[26:29]
	v_mfma_f32_16x16x32_bf16 v[14:17], v[156:159], v[226:229], v[14:17]
	v_mfma_f32_16x16x32_bf16 v[10:13], v[172:175], v[226:229], v[10:13]
	v_mfma_f32_16x16x32_bf16 v[54:57], v[176:179], v[196:199], v[54:57]
	v_mfma_f32_16x16x32_bf16 v[50:53], v[184:187], v[196:199], v[50:53]
	v_mfma_f32_16x16x32_bf16 v[38:41], v[176:179], v[206:209], v[38:41]
	v_mfma_f32_16x16x32_bf16 v[34:37], v[184:187], v[206:209], v[34:37]
	v_mfma_f32_16x16x32_bf16 v[22:25], v[176:179], v[214:217], v[22:25]
	v_mfma_f32_16x16x32_bf16 v[18:21], v[184:187], v[214:217], v[18:21]
	v_mfma_f32_16x16x32_bf16 v[6:9], v[176:179], v[222:225], v[6:9]
	v_mfma_f32_16x16x32_bf16 v[2:5], v[184:187], v[222:225], v[2:5]
	v_mfma_f32_16x16x32_bf16 v[54:57], v[180:183], v[200:203], v[54:57]
	v_mfma_f32_16x16x32_bf16 v[50:53], v[188:191], v[200:203], v[50:53]
	v_mfma_f32_16x16x32_bf16 v[38:41], v[180:183], v[210:213], v[38:41]
	v_mfma_f32_16x16x32_bf16 v[34:37], v[188:191], v[210:213], v[34:37]
	v_mfma_f32_16x16x32_bf16 v[22:25], v[180:183], v[218:221], v[22:25]
	v_mfma_f32_16x16x32_bf16 v[18:21], v[188:191], v[218:221], v[18:21]
	v_mfma_f32_16x16x32_bf16 v[6:9], v[180:183], v[226:229], v[6:9]
	v_mfma_f32_16x16x32_bf16 v[2:5], v[188:191], v[226:229], v[2:5]
	s_setprio 0
	s_add_i32 s87, 0, 0x18000
	v_add_u32_e32 v167, s87, v160
	s_add_i32 s88, 0, 0x1c000
	ds_read_b128 v[152:155], v167
	ds_read_b128 v[156:159], v167 offset:1024
	ds_read_b128 v[168:171], v167 offset:2048
	ds_read_b128 v[172:175], v167 offset:3072
	v_add_u32_e32 v167, s88, v160
	ds_read_b128 v[176:179], v167
	ds_read_b128 v[180:183], v167 offset:1024
	ds_read_b128 v[184:187], v167 offset:2048
	ds_read_b128 v[188:191], v167 offset:3072
	s_add_u32 s64, s64, 0x100000
	s_addc_u32 s65, s65, 0
	s_mov_b32 m0, s67
	v_lshl_add_u64 v[236:237], s[64:65], 0, v[132:133]
	ds_read_b128 v[196:199], v164 offset:32768
	ds_read_b128 v[200:203], v164 offset:33792
	ds_read_b128 v[206:209], v164 offset:34816
	ds_read_b128 v[210:213], v164 offset:35840
	ds_read_b128 v[214:217], v164 offset:36864
	ds_read_b128 v[218:221], v164 offset:37888
	ds_read_b128 v[222:225], v164 offset:38912
	ds_read_b128 v[226:229], v164 offset:39936
	global_load_lds_dwordx4 v[236:237], off
	v_lshl_add_u64 v[236:237], s[64:65], 0, v[136:137]
	s_mov_b32 m0, s68
	s_nop 0
	global_load_lds_dwordx4 v[236:237], off
	s_waitcnt vmcnt(8)
	s_waitcnt lgkmcnt(0)
	s_barrier
	s_setprio 2
	v_mfma_f32_16x16x32_bf16 v[126:129], v[152:155], v[196:199], v[126:129]
	v_mfma_f32_16x16x32_bf16 v[122:125], v[168:171], v[196:199], v[122:125]
	v_mfma_f32_16x16x32_bf16 v[110:113], v[152:155], v[206:209], v[110:113]
	v_mfma_f32_16x16x32_bf16 v[106:109], v[168:171], v[206:209], v[106:109]
	v_mfma_f32_16x16x32_bf16 v[94:97], v[152:155], v[214:217], v[94:97]
	v_mfma_f32_16x16x32_bf16 v[90:93], v[168:171], v[214:217], v[90:93]
	v_mfma_f32_16x16x32_bf16 v[78:81], v[152:155], v[222:225], v[78:81]
	v_mfma_f32_16x16x32_bf16 v[74:77], v[168:171], v[222:225], v[74:77]
	v_mfma_f32_16x16x32_bf16 v[126:129], v[156:159], v[200:203], v[126:129]
	v_mfma_f32_16x16x32_bf16 v[122:125], v[172:175], v[200:203], v[122:125]
	v_mfma_f32_16x16x32_bf16 v[110:113], v[156:159], v[210:213], v[110:113]
	v_mfma_f32_16x16x32_bf16 v[106:109], v[172:175], v[210:213], v[106:109]
	v_mfma_f32_16x16x32_bf16 v[94:97], v[156:159], v[218:221], v[94:97]
	v_mfma_f32_16x16x32_bf16 v[90:93], v[172:175], v[218:221], v[90:93]
	v_mfma_f32_16x16x32_bf16 v[78:81], v[156:159], v[226:229], v[78:81]
	v_mfma_f32_16x16x32_bf16 v[74:77], v[172:175], v[226:229], v[74:77]
	v_mfma_f32_16x16x32_bf16 v[118:121], v[176:179], v[196:199], v[118:121]
	v_mfma_f32_16x16x32_bf16 v[114:117], v[184:187], v[196:199], v[114:117]
	v_mfma_f32_16x16x32_bf16 v[102:105], v[176:179], v[206:209], v[102:105]
	v_mfma_f32_16x16x32_bf16 v[98:101], v[184:187], v[206:209], v[98:101]
	v_mfma_f32_16x16x32_bf16 v[86:89], v[176:179], v[214:217], v[86:89]
	v_mfma_f32_16x16x32_bf16 v[82:85], v[184:187], v[214:217], v[82:85]
	v_mfma_f32_16x16x32_bf16 v[70:73], v[176:179], v[222:225], v[70:73]
	v_mfma_f32_16x16x32_bf16 v[66:69], v[184:187], v[222:225], v[66:69]
	v_mfma_f32_16x16x32_bf16 v[118:121], v[180:183], v[200:203], v[118:121]
	v_mfma_f32_16x16x32_bf16 v[114:117], v[188:191], v[200:203], v[114:117]
	v_mfma_f32_16x16x32_bf16 v[102:105], v[180:183], v[210:213], v[102:105]
	v_mfma_f32_16x16x32_bf16 v[98:101], v[188:191], v[210:213], v[98:101]
	v_mfma_f32_16x16x32_bf16 v[86:89], v[180:183], v[218:221], v[86:89]
	v_mfma_f32_16x16x32_bf16 v[82:85], v[188:191], v[218:221], v[82:85]
	v_mfma_f32_16x16x32_bf16 v[70:73], v[180:183], v[226:229], v[70:73]
	v_mfma_f32_16x16x32_bf16 v[66:69], v[188:191], v[226:229], v[66:69]
	s_setprio 0
	s_add_i32 s64, s87, s66
	v_lshl_add_u64 v[192:193], v[192:193], 0, s[20:21]
	s_mov_b32 m0, s64
	ds_read_b128 v[196:199], v164 offset:49152
	ds_read_b128 v[200:203], v164 offset:50176
	ds_read_b128 v[206:209], v164 offset:51200
	ds_read_b128 v[210:213], v164 offset:52224
	ds_read_b128 v[214:217], v164 offset:53248
	ds_read_b128 v[218:221], v164 offset:54272
	ds_read_b128 v[222:225], v164 offset:55296
	ds_read_b128 v[226:229], v164 offset:56320
	global_load_lds_dwordx4 v[192:193], off
	s_add_i32 m0, s64, 0x2000
	s_add_u32 s48, s48, 0x100080
	v_lshl_add_u64 v[192:193], v[230:231], 0, s[20:21]
	s_addc_u32 s49, s49, 0
	s_add_i32 s64, s88, s66
	global_load_lds_dwordx4 v[192:193], off
	v_lshl_add_u64 v[192:193], s[48:49], 0, v[134:135]
	s_mov_b32 m0, s64
	s_nop 0
	global_load_lds_dwordx4 v[192:193], off
	v_lshl_add_u64 v[192:193], s[48:49], 0, v[138:139]
	s_add_i32 m0, s64, 0x2000
	s_nop 0
	global_load_lds_dwordx4 v[192:193], off
	v_lshl_add_u64 v[192:193], v[232:233], 0, s[20:21]
	s_mov_b32 m0, s72
	s_nop 0
	global_load_lds_dwordx4 v[192:193], off
	v_lshl_add_u64 v[192:193], v[234:235], 0, s[20:21]
	s_mov_b32 m0, s73
	s_nop 0
	global_load_lds_dwordx4 v[192:193], off
	s_waitcnt vmcnt(8)
	s_waitcnt lgkmcnt(0)
	s_barrier
	s_setprio 2
	v_mfma_f32_16x16x32_bf16 v[62:65], v[152:155], v[196:199], v[62:65]
	v_mfma_f32_16x16x32_bf16 v[58:61], v[168:171], v[196:199], v[58:61]
	v_mfma_f32_16x16x32_bf16 v[46:49], v[152:155], v[206:209], v[46:49]
	v_mfma_f32_16x16x32_bf16 v[42:45], v[168:171], v[206:209], v[42:45]
	v_mfma_f32_16x16x32_bf16 v[30:33], v[152:155], v[214:217], v[30:33]
	v_mfma_f32_16x16x32_bf16 v[26:29], v[168:171], v[214:217], v[26:29]
	v_mfma_f32_16x16x32_bf16 v[14:17], v[152:155], v[222:225], v[14:17]
	v_mfma_f32_16x16x32_bf16 v[10:13], v[168:171], v[222:225], v[10:13]
	v_mfma_f32_16x16x32_bf16 v[62:65], v[156:159], v[200:203], v[62:65]
	v_mfma_f32_16x16x32_bf16 v[58:61], v[172:175], v[200:203], v[58:61]
	v_mfma_f32_16x16x32_bf16 v[46:49], v[156:159], v[210:213], v[46:49]
	v_mfma_f32_16x16x32_bf16 v[42:45], v[172:175], v[210:213], v[42:45]
	v_mfma_f32_16x16x32_bf16 v[30:33], v[156:159], v[218:221], v[30:33]
	v_mfma_f32_16x16x32_bf16 v[26:29], v[172:175], v[218:221], v[26:29]
	v_mfma_f32_16x16x32_bf16 v[14:17], v[156:159], v[226:229], v[14:17]
	v_mfma_f32_16x16x32_bf16 v[10:13], v[172:175], v[226:229], v[10:13]
	v_mfma_f32_16x16x32_bf16 v[54:57], v[176:179], v[196:199], v[54:57]
	v_mfma_f32_16x16x32_bf16 v[50:53], v[184:187], v[196:199], v[50:53]
	v_mfma_f32_16x16x32_bf16 v[38:41], v[176:179], v[206:209], v[38:41]
	v_mfma_f32_16x16x32_bf16 v[34:37], v[184:187], v[206:209], v[34:37]
	v_mfma_f32_16x16x32_bf16 v[22:25], v[176:179], v[214:217], v[22:25]
	v_mfma_f32_16x16x32_bf16 v[18:21], v[184:187], v[214:217], v[18:21]
	v_mfma_f32_16x16x32_bf16 v[6:9], v[176:179], v[222:225], v[6:9]
	v_mfma_f32_16x16x32_bf16 v[2:5], v[184:187], v[222:225], v[2:5]
	v_mfma_f32_16x16x32_bf16 v[54:57], v[180:183], v[200:203], v[54:57]
	v_mfma_f32_16x16x32_bf16 v[50:53], v[188:191], v[200:203], v[50:53]
	v_mfma_f32_16x16x32_bf16 v[38:41], v[180:183], v[210:213], v[38:41]
	v_mfma_f32_16x16x32_bf16 v[34:37], v[188:191], v[210:213], v[34:37]
	v_mfma_f32_16x16x32_bf16 v[22:25], v[180:183], v[218:221], v[22:25]
	v_mfma_f32_16x16x32_bf16 v[18:21], v[188:191], v[218:221], v[18:21]
	v_mfma_f32_16x16x32_bf16 v[6:9], v[180:183], v[226:229], v[6:9]
	v_mfma_f32_16x16x32_bf16 v[2:5], v[188:191], v[226:229], v[2:5]
	s_setprio 0
	s_add_u32 s6, s6, 0x100
	s_addc_u32 s7, s7, 0
	s_add_u32 s53, s53, 0x100
	s_addc_u32 s55, s55, 0
	s_cmp_ge_i32 s86, s85
	s_mov_b32 s48, s86
	s_cbranch_scc0 .Lkt_T_13
	s_nop 7

.LBB0_3783:
	s_and_b64 s[4:5], s[4:5], exec
	s_cselect_b32 s58, 16, 8
	s_add_u32 s46, s38, 0x43e00000
	s_addc_u32 s47, s39, 0
	s_add_u32 s48, s38, 0x47e00000
	s_addc_u32 s49, s39, 0
	s_lshl_b32 s4, s10, 5
	s_mov_b64 s[10:11], 0x80
	s_and_b32 s19, s4, 0x60
	s_add_i32 m0, s6, 0x18000
	v_lshl_add_u64 v[8:9], v[8:9], 0, s[10:11]
	s_lshl_b32 s18, s17, 13
	s_lshl_b32 s20, s19, 7
	s_waitcnt vmcnt(2)
	s_barrier
	global_load_lds_dwordx4 v[8:9], off
	v_lshl_add_u64 v[6:7], v[6:7], 0, s[10:11]
	s_add_i32 m0, s6, 0x1a000
	s_add_i32 s50, s6, 0x8000
	s_add_i32 s51, s6, 0xa000
	global_load_lds_dwordx4 v[6:7], off
	v_lshl_add_u64 v[2:3], v[2:3], 0, s[10:11]
	s_mov_b32 m0, s50
	s_add_u32 s4, s30, 0x100080
	global_load_lds_dwordx4 v[2:3], off
	v_lshl_add_u64 v[2:3], v[4:5], 0, s[10:11]
	s_mov_b32 m0, s51
	s_addc_u32 s5, s31, 0
	global_load_lds_dwordx4 v[2:3], off
	s_add_i32 m0, s6, 0x1c000
	v_lshl_add_u64 v[2:3], s[4:5], 0, v[134:135]
	global_load_lds_dwordx4 v[2:3], off
	v_lshl_add_u64 v[2:3], s[4:5], 0, v[132:133]
	s_add_i32 m0, s6, 0x1e000
	v_lshlrev_b32_e32 v5, 2, v0
	global_load_lds_dwordx4 v[2:3], off
	v_and_b32_e32 v2, 15, v0
	v_bfe_u32 v3, v0, 4, 2
	v_lshl_or_b32 v136, s17, 6, v2
	v_lshlrev_b32_e32 v4, 4, v3
	v_lshlrev_b32_e32 v6, 6, v0
	s_movk_i32 s4, 0x3c0
	v_or_b32_e32 v140, 16, v136
	v_mov_b32_e32 v141, v135
	v_lshl_or_b32 v2, v2, 6, v4
	v_and_b32_e32 v5, 32, v5
	v_and_or_b32 v4, v6, s4, v4
	v_lshlrev_b64 v[142:143], 11, v[140:141]
	v_lshl_or_b32 v141, v3, 2, s19
	v_lshlrev_b32_e32 v3, 10, v0
	v_bitop3_b32 v131, s20, v4, v5 bitop3:0xf6
	v_and_b32_e32 v3, 0x60000, v3
	v_lshlrev_b32_e32 v4, 13, v13
	v_or3_b32 v3, v12, v3, v4
	v_add_u32_e32 v148, v3, v11
	v_lshlrev_b32_e32 v3, 6, v10
	s_waitcnt vmcnt(6)
	s_cmpk_lt_u32 s16, 0x100
	v_and_b32_e32 v3, 0xe0000, v3
	v_bitop3_b32 v2, v2, s18, v5 bitop3:0xde
	s_cselect_b64 s[16:17], -1, 0
	v_mov_b32_e32 v137, v135
	v_or_b32_e32 v144, 32, v136
	v_mov_b32_e32 v145, v135
	v_or3_b32 v3, v12, v3, v4
	s_add_i32 s54, 0, 0x10000
	s_add_i32 s55, 0, 0x14000
	v_lshlrev_b64 v[138:139], 11, v[136:137]
	v_lshlrev_b64 v[146:147], 11, v[144:145]
	v_or_b32_e32 v137, 48, v136
	s_ashr_i32 s52, s44, 31
	s_ashr_i32 s53, s2, 31
	v_mov_b32_e32 v149, v135
	v_add_u32_e32 v150, v3, v11
	v_mov_b32_e32 v151, v135
	v_mov_b64_e32 v[152:153], 0x110
	v_mov_b64_e32 v[154:155], 0x10f
	v_add_u32_e32 v145, s54, v131
	v_add_u32_e32 v160, s55, v131
	v_add_u32_e32 v161, 0, v2
	v_mov_b64_e32 v[156:157], 0x100
	s_branch .LBB0_3786

.Lkt_L_14:
	ds_read_b128 v[162:165], v145
	ds_read_b128 v[166:169], v145 offset:1024
	ds_read_b128 v[170:173], v145 offset:2048
	ds_read_b128 v[174:177], v145 offset:3072
	ds_read_b128 v[178:181], v160
	ds_read_b128 v[182:185], v160 offset:1024
	ds_read_b128 v[186:189], v160 offset:2048
	ds_read_b128 v[190:193], v160 offset:3072
	s_add_i32 s63, s30, 2
	s_add_u32 s31, s28, 0xfff00080
	s_addc_u32 s34, s29, -1
	s_cmp_eq_u32 s60, s30
	s_cselect_b32 s30, s59, s61
	s_cselect_b32 s35, s19, s34
	s_cselect_b32 s34, s23, s31
	s_cselect_b32 s31, s21, s62
	v_lshl_add_u64 v[158:159], s[28:29], 0, v[148:149]
	s_add_i32 m0, s6, 0xc000
	ds_read_b128 v[196:199], v161
	ds_read_b128 v[200:203], v161 offset:1024
	ds_read_b128 v[206:209], v161 offset:2048
	ds_read_b128 v[210:213], v161 offset:3072
	ds_read_b128 v[214:217], v161 offset:4096
	ds_read_b128 v[218:221], v161 offset:5120
	ds_read_b128 v[222:225], v161 offset:6144
	ds_read_b128 v[226:229], v161 offset:7168
	global_load_lds_dwordx4 v[158:159], off
	v_lshl_add_u64 v[158:159], s[28:29], 0, v[150:151]
	s_add_i32 m0, s6, 0xe000
	s_nop 0
	global_load_lds_dwordx4 v[158:159], off
	s_waitcnt lgkmcnt(0)
	s_setprio 1
	v_mfma_f32_16x16x32_bf16 v[126:129], v[162:165], v[196:199], v[126:129]
	v_mfma_f32_16x16x32_bf16 v[122:125], v[170:173], v[196:199], v[122:125]
	v_mfma_f32_16x16x32_bf16 v[118:121], v[162:165], v[206:209], v[118:121]
	v_mfma_f32_16x16x32_bf16 v[114:117], v[170:173], v[206:209], v[114:117]
	v_mfma_f32_16x16x32_bf16 v[102:105], v[162:165], v[214:217], v[102:105]
	v_mfma_f32_16x16x32_bf16 v[98:101], v[170:173], v[214:217], v[98:101]
	v_mfma_f32_16x16x32_bf16 v[42:45], v[162:165], v[222:225], v[42:45]
	v_mfma_f32_16x16x32_bf16 v[34:37], v[170:173], v[222:225], v[34:37]
	v_mfma_f32_16x16x32_bf16 v[126:129], v[166:169], v[200:203], v[126:129]
	v_mfma_f32_16x16x32_bf16 v[122:125], v[174:177], v[200:203], v[122:125]
	v_mfma_f32_16x16x32_bf16 v[118:121], v[166:169], v[210:213], v[118:121]
	v_mfma_f32_16x16x32_bf16 v[114:117], v[174:177], v[210:213], v[114:117]
	v_mfma_f32_16x16x32_bf16 v[102:105], v[166:169], v[218:221], v[102:105]
	v_mfma_f32_16x16x32_bf16 v[98:101], v[174:177], v[218:221], v[98:101]
	v_mfma_f32_16x16x32_bf16 v[42:45], v[166:169], v[226:229], v[42:45]
	v_mfma_f32_16x16x32_bf16 v[34:37], v[174:177], v[226:229], v[34:37]
	v_mfma_f32_16x16x32_bf16 v[110:113], v[178:181], v[196:199], v[110:113]
	v_mfma_f32_16x16x32_bf16 v[106:109], v[186:189], v[196:199], v[106:109]
	v_mfma_f32_16x16x32_bf16 v[94:97], v[178:181], v[206:209], v[94:97]
	v_mfma_f32_16x16x32_bf16 v[90:93], v[186:189], v[206:209], v[90:93]
	v_mfma_f32_16x16x32_bf16 v[86:89], v[178:181], v[214:217], v[86:89]
	v_mfma_f32_16x16x32_bf16 v[82:85], v[186:189], v[214:217], v[82:85]
	v_mfma_f32_16x16x32_bf16 v[30:33], v[178:181], v[222:225], v[30:33]
	v_mfma_f32_16x16x32_bf16 v[26:29], v[186:189], v[222:225], v[26:29]
	v_mfma_f32_16x16x32_bf16 v[110:113], v[182:185], v[200:203], v[110:113]
	v_mfma_f32_16x16x32_bf16 v[106:109], v[190:193], v[200:203], v[106:109]
	v_mfma_f32_16x16x32_bf16 v[94:97], v[182:185], v[210:213], v[94:97]
	v_mfma_f32_16x16x32_bf16 v[90:93], v[190:193], v[210:213], v[90:93]
	v_mfma_f32_16x16x32_bf16 v[86:89], v[182:185], v[218:221], v[86:89]
	v_mfma_f32_16x16x32_bf16 v[82:85], v[190:193], v[218:221], v[82:85]
	v_mfma_f32_16x16x32_bf16 v[30:33], v[182:185], v[226:229], v[30:33]
	v_mfma_f32_16x16x32_bf16 v[26:29], v[190:193], v[226:229], v[26:29]
	s_setprio 0
	s_waitcnt vmcnt(8)
	s_barrier
	s_add_i32 s64, s54, s40
	v_lshl_add_u64 v[158:159], s[30:31], 0, v[134:135]
	s_mov_b32 m0, s64
	ds_read_b128 v[196:199], v161 offset:16384
	ds_read_b128 v[200:203], v161 offset:17408
	ds_read_b128 v[206:209], v161 offset:18432
	ds_read_b128 v[210:213], v161 offset:19456
	ds_read_b128 v[214:217], v161 offset:20480
	ds_read_b128 v[218:221], v161 offset:21504
	ds_read_b128 v[222:225], v161 offset:22528
	ds_read_b128 v[226:229], v161 offset:23552
	global_load_lds_dwordx4 v[158:159], off
	s_add_i32 m0, s64, 0x2000
	s_add_u32 s64, s30, 0x100000
	v_lshl_add_u64 v[230:231], s[30:31], 0, v[132:133]
	s_addc_u32 s65, s31, 0
	s_add_i32 s66, s55, s40
	global_load_lds_dwordx4 v[230:231], off
	v_lshl_add_u64 v[232:233], s[64:65], 0, v[134:135]
	s_mov_b32 m0, s66
	v_lshl_add_u64 v[234:235], s[34:35], 0, v[132:133]
	global_load_lds_dwordx4 v[232:233], off
	v_lshl_add_u64 v[232:233], s[64:65], 0, v[132:133]
	s_add_i32 m0, s66, 0x2000
	s_nop 0
	global_load_lds_dwordx4 v[232:233], off
	v_lshl_add_u64 v[232:233], s[34:35], 0, v[134:135]
	s_mov_b32 m0, s6
	s_nop 0
	global_load_lds_dwordx4 v[232:233], off
	s_mov_b32 m0, s13
	s_nop 0
	global_load_lds_dwordx4 v[234:235], off
	s_waitcnt lgkmcnt(0)
	s_setprio 1
	v_mfma_f32_16x16x32_bf16 v[78:81], v[162:165], v[196:199], v[78:81]
	v_mfma_f32_16x16x32_bf16 v[74:77], v[170:173], v[196:199], v[74:77]
	v_mfma_f32_16x16x32_bf16 v[70:73], v[162:165], v[206:209], v[70:73]
	v_mfma_f32_16x16x32_bf16 v[66:69], v[170:173], v[206:209], v[66:69]
	v_mfma_f32_16x16x32_bf16 v[54:57], v[162:165], v[214:217], v[54:57]
	v_mfma_f32_16x16x32_bf16 v[50:53], v[170:173], v[214:217], v[50:53]
	v_mfma_f32_16x16x32_bf16 v[14:17], v[162:165], v[222:225], v[14:17]
	v_mfma_f32_16x16x32_bf16 v[10:13], v[170:173], v[222:225], v[10:13]
	v_mfma_f32_16x16x32_bf16 v[78:81], v[166:169], v[200:203], v[78:81]
	v_mfma_f32_16x16x32_bf16 v[74:77], v[174:177], v[200:203], v[74:77]
	v_mfma_f32_16x16x32_bf16 v[70:73], v[166:169], v[210:213], v[70:73]
	v_mfma_f32_16x16x32_bf16 v[66:69], v[174:177], v[210:213], v[66:69]
	v_mfma_f32_16x16x32_bf16 v[54:57], v[166:169], v[218:221], v[54:57]
	v_mfma_f32_16x16x32_bf16 v[50:53], v[174:177], v[218:221], v[50:53]
	v_mfma_f32_16x16x32_bf16 v[14:17], v[166:169], v[226:229], v[14:17]
	v_mfma_f32_16x16x32_bf16 v[10:13], v[174:177], v[226:229], v[10:13]
	v_mfma_f32_16x16x32_bf16 v[62:65], v[178:181], v[196:199], v[62:65]
	v_mfma_f32_16x16x32_bf16 v[58:61], v[186:189], v[196:199], v[58:61]
	v_mfma_f32_16x16x32_bf16 v[46:49], v[178:181], v[206:209], v[46:49]
	v_mfma_f32_16x16x32_bf16 v[38:41], v[186:189], v[206:209], v[38:41]
	v_mfma_f32_16x16x32_bf16 v[22:25], v[178:181], v[214:217], v[22:25]
	v_mfma_f32_16x16x32_bf16 v[18:21], v[186:189], v[214:217], v[18:21]
	v_mfma_f32_16x16x32_bf16 v[6:9], v[178:181], v[222:225], v[6:9]
	v_mfma_f32_16x16x32_bf16 v[2:5], v[186:189], v[222:225], v[2:5]
	v_mfma_f32_16x16x32_bf16 v[62:65], v[182:185], v[200:203], v[62:65]
	v_mfma_f32_16x16x32_bf16 v[58:61], v[190:193], v[200:203], v[58:61]
	v_mfma_f32_16x16x32_bf16 v[46:49], v[182:185], v[210:213], v[46:49]
	v_mfma_f32_16x16x32_bf16 v[38:41], v[190:193], v[210:213], v[38:41]
	v_mfma_f32_16x16x32_bf16 v[22:25], v[182:185], v[218:221], v[22:25]
	v_mfma_f32_16x16x32_bf16 v[18:21], v[190:193], v[218:221], v[18:21]
	v_mfma_f32_16x16x32_bf16 v[6:9], v[182:185], v[226:229], v[6:9]
	v_mfma_f32_16x16x32_bf16 v[2:5], v[190:193], v[226:229], v[2:5]
	s_setprio 0
	s_waitcnt vmcnt(8)
	s_barrier
	s_add_i32 s64, 0, 0x18000
	s_add_i32 s65, 0, 0x1c000
	v_add_u32_e32 v174, s64, v131
	v_add_u32_e32 v190, s65, v131
	ds_read_b128 v[162:165], v174
	ds_read_b128 v[166:169], v174 offset:1024
	ds_read_b128 v[170:173], v174 offset:2048
	ds_read_b128 v[174:177], v174 offset:3072
	ds_read_b128 v[178:181], v190
	ds_read_b128 v[182:185], v190 offset:1024
	ds_read_b128 v[186:189], v190 offset:2048
	ds_read_b128 v[190:193], v190 offset:3072
	s_add_u32 s34, s34, 0x100000
	s_addc_u32 s35, s35, 0
	s_mov_b32 m0, s43
	v_lshl_add_u64 v[236:237], s[34:35], 0, v[134:135]
	ds_read_b128 v[196:199], v161 offset:32768
	ds_read_b128 v[200:203], v161 offset:33792
	ds_read_b128 v[206:209], v161 offset:34816
	ds_read_b128 v[210:213], v161 offset:35840
	ds_read_b128 v[214:217], v161 offset:36864
	ds_read_b128 v[218:221], v161 offset:37888
	ds_read_b128 v[222:225], v161 offset:38912
	ds_read_b128 v[226:229], v161 offset:39936
	global_load_lds_dwordx4 v[236:237], off
	v_lshl_add_u64 v[236:237], s[34:35], 0, v[132:133]
	s_mov_b32 m0, s45
	s_nop 0
	global_load_lds_dwordx4 v[236:237], off
	s_waitcnt lgkmcnt(0)
	s_setprio 1
	v_mfma_f32_16x16x32_bf16 v[126:129], v[162:165], v[196:199], v[126:129]
	v_mfma_f32_16x16x32_bf16 v[122:125], v[170:173], v[196:199], v[122:125]
	v_mfma_f32_16x16x32_bf16 v[118:121], v[162:165], v[206:209], v[118:121]
	v_mfma_f32_16x16x32_bf16 v[114:117], v[170:173], v[206:209], v[114:117]
	v_mfma_f32_16x16x32_bf16 v[102:105], v[162:165], v[214:217], v[102:105]
	v_mfma_f32_16x16x32_bf16 v[98:101], v[170:173], v[214:217], v[98:101]
	v_mfma_f32_16x16x32_bf16 v[42:45], v[162:165], v[222:225], v[42:45]
	v_mfma_f32_16x16x32_bf16 v[34:37], v[170:173], v[222:225], v[34:37]
	v_mfma_f32_16x16x32_bf16 v[126:129], v[166:169], v[200:203], v[126:129]
	v_mfma_f32_16x16x32_bf16 v[122:125], v[174:177], v[200:203], v[122:125]
	v_mfma_f32_16x16x32_bf16 v[118:121], v[166:169], v[210:213], v[118:121]
	v_mfma_f32_16x16x32_bf16 v[114:117], v[174:177], v[210:213], v[114:117]
	v_mfma_f32_16x16x32_bf16 v[102:105], v[166:169], v[218:221], v[102:105]
	v_mfma_f32_16x16x32_bf16 v[98:101], v[174:177], v[218:221], v[98:101]
	v_mfma_f32_16x16x32_bf16 v[42:45], v[166:169], v[226:229], v[42:45]
	v_mfma_f32_16x16x32_bf16 v[34:37], v[174:177], v[226:229], v[34:37]
	v_mfma_f32_16x16x32_bf16 v[110:113], v[178:181], v[196:199], v[110:113]
	v_mfma_f32_16x16x32_bf16 v[106:109], v[186:189], v[196:199], v[106:109]
	v_mfma_f32_16x16x32_bf16 v[94:97], v[178:181], v[206:209], v[94:97]
	v_mfma_f32_16x16x32_bf16 v[90:93], v[186:189], v[206:209], v[90:93]
	v_mfma_f32_16x16x32_bf16 v[86:89], v[178:181], v[214:217], v[86:89]
	v_mfma_f32_16x16x32_bf16 v[82:85], v[186:189], v[214:217], v[82:85]
	v_mfma_f32_16x16x32_bf16 v[30:33], v[178:181], v[222:225], v[30:33]
	v_mfma_f32_16x16x32_bf16 v[26:29], v[186:189], v[222:225], v[26:29]
	v_mfma_f32_16x16x32_bf16 v[110:113], v[182:185], v[200:203], v[110:113]
	v_mfma_f32_16x16x32_bf16 v[106:109], v[190:193], v[200:203], v[106:109]
	v_mfma_f32_16x16x32_bf16 v[94:97], v[182:185], v[210:213], v[94:97]
	v_mfma_f32_16x16x32_bf16 v[90:93], v[190:193], v[210:213], v[90:93]
	v_mfma_f32_16x16x32_bf16 v[86:89], v[182:185], v[218:221], v[86:89]
	v_mfma_f32_16x16x32_bf16 v[82:85], v[190:193], v[218:221], v[82:85]
	v_mfma_f32_16x16x32_bf16 v[30:33], v[182:185], v[226:229], v[30:33]
	v_mfma_f32_16x16x32_bf16 v[26:29], v[190:193], v[226:229], v[26:29]
	s_setprio 0
	s_waitcnt vmcnt(8)
	s_barrier
	s_add_i32 s34, s64, s40
	v_lshl_add_u64 v[158:159], v[158:159], 0, s[10:11]
	s_mov_b32 m0, s34
	ds_read_b128 v[196:199], v161 offset:49152
	ds_read_b128 v[200:203], v161 offset:50176
	ds_read_b128 v[206:209], v161 offset:51200
	ds_read_b128 v[210:213], v161 offset:52224
	ds_read_b128 v[214:217], v161 offset:53248
	ds_read_b128 v[218:221], v161 offset:54272
	ds_read_b128 v[222:225], v161 offset:55296
	ds_read_b128 v[226:229], v161 offset:56320
	global_load_lds_dwordx4 v[158:159], off
	s_add_i32 m0, s34, 0x2000
	s_add_u32 s30, s30, 0x100080
	v_lshl_add_u64 v[158:159], v[230:231], 0, s[10:11]
	s_addc_u32 s31, s31, 0
	s_add_i32 s34, s65, s40
	global_load_lds_dwordx4 v[158:159], off
	v_lshl_add_u64 v[158:159], s[30:31], 0, v[134:135]
	s_mov_b32 m0, s34
	s_nop 0
	global_load_lds_dwordx4 v[158:159], off
	v_lshl_add_u64 v[158:159], s[30:31], 0, v[132:133]
	s_add_i32 m0, s34, 0x2000
	s_nop 0
	global_load_lds_dwordx4 v[158:159], off
	v_lshl_add_u64 v[158:159], v[232:233], 0, s[10:11]
	s_mov_b32 m0, s50
	s_nop 0
	global_load_lds_dwordx4 v[158:159], off
	v_lshl_add_u64 v[158:159], v[234:235], 0, s[10:11]
	s_mov_b32 m0, s51
	s_nop 0
	global_load_lds_dwordx4 v[158:159], off
	s_waitcnt lgkmcnt(0)
	s_setprio 1
	v_mfma_f32_16x16x32_bf16 v[78:81], v[162:165], v[196:199], v[78:81]
	v_mfma_f32_16x16x32_bf16 v[74:77], v[170:173], v[196:199], v[74:77]
	v_mfma_f32_16x16x32_bf16 v[70:73], v[162:165], v[206:209], v[70:73]
	v_mfma_f32_16x16x32_bf16 v[66:69], v[170:173], v[206:209], v[66:69]
	v_mfma_f32_16x16x32_bf16 v[54:57], v[162:165], v[214:217], v[54:57]
	v_mfma_f32_16x16x32_bf16 v[50:53], v[170:173], v[214:217], v[50:53]
	v_mfma_f32_16x16x32_bf16 v[14:17], v[162:165], v[222:225], v[14:17]
	v_mfma_f32_16x16x32_bf16 v[10:13], v[170:173], v[222:225], v[10:13]
	v_mfma_f32_16x16x32_bf16 v[78:81], v[166:169], v[200:203], v[78:81]
	v_mfma_f32_16x16x32_bf16 v[74:77], v[174:177], v[200:203], v[74:77]
	v_mfma_f32_16x16x32_bf16 v[70:73], v[166:169], v[210:213], v[70:73]
	v_mfma_f32_16x16x32_bf16 v[66:69], v[174:177], v[210:213], v[66:69]
	v_mfma_f32_16x16x32_bf16 v[54:57], v[166:169], v[218:221], v[54:57]
	v_mfma_f32_16x16x32_bf16 v[50:53], v[174:177], v[218:221], v[50:53]
	v_mfma_f32_16x16x32_bf16 v[14:17], v[166:169], v[226:229], v[14:17]
	v_mfma_f32_16x16x32_bf16 v[10:13], v[174:177], v[226:229], v[10:13]
	v_mfma_f32_16x16x32_bf16 v[62:65], v[178:181], v[196:199], v[62:65]
	v_mfma_f32_16x16x32_bf16 v[58:61], v[186:189], v[196:199], v[58:61]
	v_mfma_f32_16x16x32_bf16 v[46:49], v[178:181], v[206:209], v[46:49]
	v_mfma_f32_16x16x32_bf16 v[38:41], v[186:189], v[206:209], v[38:41]
	v_mfma_f32_16x16x32_bf16 v[22:25], v[178:181], v[214:217], v[22:25]
	v_mfma_f32_16x16x32_bf16 v[18:21], v[186:189], v[214:217], v[18:21]
	v_mfma_f32_16x16x32_bf16 v[6:9], v[178:181], v[222:225], v[6:9]
	v_mfma_f32_16x16x32_bf16 v[2:5], v[186:189], v[222:225], v[2:5]
	v_mfma_f32_16x16x32_bf16 v[62:65], v[182:185], v[200:203], v[62:65]
	v_mfma_f32_16x16x32_bf16 v[58:61], v[190:193], v[200:203], v[58:61]
	v_mfma_f32_16x16x32_bf16 v[46:49], v[182:185], v[210:213], v[46:49]
	v_mfma_f32_16x16x32_bf16 v[38:41], v[190:193], v[210:213], v[38:41]
	v_mfma_f32_16x16x32_bf16 v[22:25], v[182:185], v[218:221], v[22:25]
	v_mfma_f32_16x16x32_bf16 v[18:21], v[190:193], v[218:221], v[18:21]
	v_mfma_f32_16x16x32_bf16 v[6:9], v[182:185], v[226:229], v[6:9]
	v_mfma_f32_16x16x32_bf16 v[2:5], v[190:193], v[226:229], v[2:5]
	s_setprio 0
	s_waitcnt vmcnt(8)
	s_barrier
	s_add_u32 s28, s28, 0x100
	s_addc_u32 s29, s29, 0
	s_add_u32 s61, s61, 0x100
	s_addc_u32 s62, s62, 0
	s_cmp_ge_i32 s63, s58
	s_mov_b32 s30, s63
	s_cbranch_scc0 .Lkt_L_14
	s_branch .Lkt_exit_14
.Lkt_T_14:
	ds_read_b128 v[162:165], v145
	ds_read_b128 v[166:169], v145 offset:1024
	ds_read_b128 v[170:173], v145 offset:2048
	ds_read_b128 v[174:177], v145 offset:3072
	ds_read_b128 v[178:181], v160
	ds_read_b128 v[182:185], v160 offset:1024
	ds_read_b128 v[186:189], v160 offset:2048
	ds_read_b128 v[190:193], v160 offset:3072
	s_add_i32 s63, s30, 2
	s_add_u32 s31, s28, 0xfff00080
	s_addc_u32 s34, s29, -1
	s_cmp_eq_u32 s60, s30
	s_cselect_b32 s30, s59, s61
	s_cselect_b32 s35, s19, s34
	s_cselect_b32 s34, s23, s31
	s_cselect_b32 s31, s21, s62
	v_lshl_add_u64 v[158:159], s[28:29], 0, v[148:149]
	s_add_i32 m0, s6, 0xc000
	ds_read_b128 v[196:199], v161
	ds_read_b128 v[200:203], v161 offset:1024
	ds_read_b128 v[206:209], v161 offset:2048
	ds_read_b128 v[210:213], v161 offset:3072
	ds_read_b128 v[214:217], v161 offset:4096
	ds_read_b128 v[218:221], v161 offset:5120
	ds_read_b128 v[222:225], v161 offset:6144
	ds_read_b128 v[226:229], v161 offset:7168
	global_load_lds_dwordx4 v[158:159], off
	v_lshl_add_u64 v[158:159], s[28:29], 0, v[150:151]
	s_add_i32 m0, s6, 0xe000
	s_nop 0
	global_load_lds_dwordx4 v[158:159], off
	s_waitcnt vmcnt(8)
	s_waitcnt lgkmcnt(0)
	s_barrier
	s_setprio 2
	v_mfma_f32_16x16x32_bf16 v[126:129], v[162:165], v[196:199], v[126:129]
	v_mfma_f32_16x16x32_bf16 v[122:125], v[170:173], v[196:199], v[122:125]
	v_mfma_f32_16x16x32_bf16 v[118:121], v[162:165], v[206:209], v[118:121]
	v_mfma_f32_16x16x32_bf16 v[114:117], v[170:173], v[206:209], v[114:117]
	v_mfma_f32_16x16x32_bf16 v[102:105], v[162:165], v[214:217], v[102:105]
	v_mfma_f32_16x16x32_bf16 v[98:101], v[170:173], v[214:217], v[98:101]
	v_mfma_f32_16x16x32_bf16 v[42:45], v[162:165], v[222:225], v[42:45]
	v_mfma_f32_16x16x32_bf16 v[34:37], v[170:173], v[222:225], v[34:37]
	v_mfma_f32_16x16x32_bf16 v[126:129], v[166:169], v[200:203], v[126:129]
	v_mfma_f32_16x16x32_bf16 v[122:125], v[174:177], v[200:203], v[122:125]
	v_mfma_f32_16x16x32_bf16 v[118:121], v[166:169], v[210:213], v[118:121]
	v_mfma_f32_16x16x32_bf16 v[114:117], v[174:177], v[210:213], v[114:117]
	v_mfma_f32_16x16x32_bf16 v[102:105], v[166:169], v[218:221], v[102:105]
	v_mfma_f32_16x16x32_bf16 v[98:101], v[174:177], v[218:221], v[98:101]
	v_mfma_f32_16x16x32_bf16 v[42:45], v[166:169], v[226:229], v[42:45]
	v_mfma_f32_16x16x32_bf16 v[34:37], v[174:177], v[226:229], v[34:37]
	v_mfma_f32_16x16x32_bf16 v[110:113], v[178:181], v[196:199], v[110:113]
	v_mfma_f32_16x16x32_bf16 v[106:109], v[186:189], v[196:199], v[106:109]
	v_mfma_f32_16x16x32_bf16 v[94:97], v[178:181], v[206:209], v[94:97]
	v_mfma_f32_16x16x32_bf16 v[90:93], v[186:189], v[206:209], v[90:93]
	v_mfma_f32_16x16x32_bf16 v[86:89], v[178:181], v[214:217], v[86:89]
	v_mfma_f32_16x16x32_bf16 v[82:85], v[186:189], v[214:217], v[82:85]
	v_mfma_f32_16x16x32_bf16 v[30:33], v[178:181], v[222:225], v[30:33]
	v_mfma_f32_16x16x32_bf16 v[26:29], v[186:189], v[222:225], v[26:29]
	v_mfma_f32_16x16x32_bf16 v[110:113], v[182:185], v[200:203], v[110:113]
	v_mfma_f32_16x16x32_bf16 v[106:109], v[190:193], v[200:203], v[106:109]
	v_mfma_f32_16x16x32_bf16 v[94:97], v[182:185], v[210:213], v[94:97]
	v_mfma_f32_16x16x32_bf16 v[90:93], v[190:193], v[210:213], v[90:93]
	v_mfma_f32_16x16x32_bf16 v[86:89], v[182:185], v[218:221], v[86:89]
	v_mfma_f32_16x16x32_bf16 v[82:85], v[190:193], v[218:221], v[82:85]
	v_mfma_f32_16x16x32_bf16 v[30:33], v[182:185], v[226:229], v[30:33]
	v_mfma_f32_16x16x32_bf16 v[26:29], v[190:193], v[226:229], v[26:29]
	s_setprio 0
	s_add_i32 s64, s54, s40
	v_lshl_add_u64 v[158:159], s[30:31], 0, v[134:135]
	s_mov_b32 m0, s64
	ds_read_b128 v[196:199], v161 offset:16384
	ds_read_b128 v[200:203], v161 offset:17408
	ds_read_b128 v[206:209], v161 offset:18432
	ds_read_b128 v[210:213], v161 offset:19456
	ds_read_b128 v[214:217], v161 offset:20480
	ds_read_b128 v[218:221], v161 offset:21504
	ds_read_b128 v[222:225], v161 offset:22528
	ds_read_b128 v[226:229], v161 offset:23552
	global_load_lds_dwordx4 v[158:159], off
	s_add_i32 m0, s64, 0x2000
	s_add_u32 s64, s30, 0x100000
	v_lshl_add_u64 v[230:231], s[30:31], 0, v[132:133]
	s_addc_u32 s65, s31, 0
	s_add_i32 s66, s55, s40
	global_load_lds_dwordx4 v[230:231], off
	v_lshl_add_u64 v[232:233], s[64:65], 0, v[134:135]
	s_mov_b32 m0, s66
	v_lshl_add_u64 v[234:235], s[34:35], 0, v[132:133]
	global_load_lds_dwordx4 v[232:233], off
	v_lshl_add_u64 v[232:233], s[64:65], 0, v[132:133]
	s_add_i32 m0, s66, 0x2000
	s_nop 0
	global_load_lds_dwordx4 v[232:233], off
	v_lshl_add_u64 v[232:233], s[34:35], 0, v[134:135]
	s_mov_b32 m0, s6
	s_nop 0
	global_load_lds_dwordx4 v[232:233], off
	s_mov_b32 m0, s13
	s_nop 0
	global_load_lds_dwordx4 v[234:235], off
	s_waitcnt vmcnt(8)
	s_waitcnt lgkmcnt(0)
	s_barrier
	s_setprio 2
	v_mfma_f32_16x16x32_bf16 v[78:81], v[162:165], v[196:199], v[78:81]
	v_mfma_f32_16x16x32_bf16 v[74:77], v[170:173], v[196:199], v[74:77]
	v_mfma_f32_16x16x32_bf16 v[70:73], v[162:165], v[206:209], v[70:73]
	v_mfma_f32_16x16x32_bf16 v[66:69], v[170:173], v[206:209], v[66:69]
	v_mfma_f32_16x16x32_bf16 v[54:57], v[162:165], v[214:217], v[54:57]
	v_mfma_f32_16x16x32_bf16 v[50:53], v[170:173], v[214:217], v[50:53]
	v_mfma_f32_16x16x32_bf16 v[14:17], v[162:165], v[222:225], v[14:17]
	v_mfma_f32_16x16x32_bf16 v[10:13], v[170:173], v[222:225], v[10:13]
	v_mfma_f32_16x16x32_bf16 v[78:81], v[166:169], v[200:203], v[78:81]
	v_mfma_f32_16x16x32_bf16 v[74:77], v[174:177], v[200:203], v[74:77]
	v_mfma_f32_16x16x32_bf16 v[70:73], v[166:169], v[210:213], v[70:73]
	v_mfma_f32_16x16x32_bf16 v[66:69], v[174:177], v[210:213], v[66:69]
	v_mfma_f32_16x16x32_bf16 v[54:57], v[166:169], v[218:221], v[54:57]
	v_mfma_f32_16x16x32_bf16 v[50:53], v[174:177], v[218:221], v[50:53]
	v_mfma_f32_16x16x32_bf16 v[14:17], v[166:169], v[226:229], v[14:17]
	v_mfma_f32_16x16x32_bf16 v[10:13], v[174:177], v[226:229], v[10:13]
	v_mfma_f32_16x16x32_bf16 v[62:65], v[178:181], v[196:199], v[62:65]
	v_mfma_f32_16x16x32_bf16 v[58:61], v[186:189], v[196:199], v[58:61]
	v_mfma_f32_16x16x32_bf16 v[46:49], v[178:181], v[206:209], v[46:49]
	v_mfma_f32_16x16x32_bf16 v[38:41], v[186:189], v[206:209], v[38:41]
	v_mfma_f32_16x16x32_bf16 v[22:25], v[178:181], v[214:217], v[22:25]
	v_mfma_f32_16x16x32_bf16 v[18:21], v[186:189], v[214:217], v[18:21]
	v_mfma_f32_16x16x32_bf16 v[6:9], v[178:181], v[222:225], v[6:9]
	v_mfma_f32_16x16x32_bf16 v[2:5], v[186:189], v[222:225], v[2:5]
	v_mfma_f32_16x16x32_bf16 v[62:65], v[182:185], v[200:203], v[62:65]
	v_mfma_f32_16x16x32_bf16 v[58:61], v[190:193], v[200:203], v[58:61]
	v_mfma_f32_16x16x32_bf16 v[46:49], v[182:185], v[210:213], v[46:49]
	v_mfma_f32_16x16x32_bf16 v[38:41], v[190:193], v[210:213], v[38:41]
	v_mfma_f32_16x16x32_bf16 v[22:25], v[182:185], v[218:221], v[22:25]
	v_mfma_f32_16x16x32_bf16 v[18:21], v[190:193], v[218:221], v[18:21]
	v_mfma_f32_16x16x32_bf16 v[6:9], v[182:185], v[226:229], v[6:9]
	v_mfma_f32_16x16x32_bf16 v[2:5], v[190:193], v[226:229], v[2:5]
	s_setprio 0
	s_add_i32 s64, 0, 0x18000
	s_add_i32 s65, 0, 0x1c000
	v_add_u32_e32 v174, s64, v131
	v_add_u32_e32 v190, s65, v131
	ds_read_b128 v[162:165], v174
	ds_read_b128 v[166:169], v174 offset:1024
	ds_read_b128 v[170:173], v174 offset:2048
	ds_read_b128 v[174:177], v174 offset:3072
	ds_read_b128 v[178:181], v190
	ds_read_b128 v[182:185], v190 offset:1024
	ds_read_b128 v[186:189], v190 offset:2048
	ds_read_b128 v[190:193], v190 offset:3072
	s_add_u32 s34, s34, 0x100000
	s_addc_u32 s35, s35, 0
	s_mov_b32 m0, s43
	v_lshl_add_u64 v[236:237], s[34:35], 0, v[134:135]
	ds_read_b128 v[196:199], v161 offset:32768
	ds_read_b128 v[200:203], v161 offset:33792
	ds_read_b128 v[206:209], v161 offset:34816
	ds_read_b128 v[210:213], v161 offset:35840
	ds_read_b128 v[214:217], v161 offset:36864
	ds_read_b128 v[218:221], v161 offset:37888
	ds_read_b128 v[222:225], v161 offset:38912
	ds_read_b128 v[226:229], v161 offset:39936
	global_load_lds_dwordx4 v[236:237], off
	v_lshl_add_u64 v[236:237], s[34:35], 0, v[132:133]
	s_mov_b32 m0, s45
	s_nop 0
	global_load_lds_dwordx4 v[236:237], off
	s_waitcnt vmcnt(8)
	s_waitcnt lgkmcnt(0)
	s_barrier
	s_setprio 2
	v_mfma_f32_16x16x32_bf16 v[126:129], v[162:165], v[196:199], v[126:129]
	v_mfma_f32_16x16x32_bf16 v[122:125], v[170:173], v[196:199], v[122:125]
	v_mfma_f32_16x16x32_bf16 v[118:121], v[162:165], v[206:209], v[118:121]
	v_mfma_f32_16x16x32_bf16 v[114:117], v[170:173], v[206:209], v[114:117]
	v_mfma_f32_16x16x32_bf16 v[102:105], v[162:165], v[214:217], v[102:105]
	v_mfma_f32_16x16x32_bf16 v[98:101], v[170:173], v[214:217], v[98:101]
	v_mfma_f32_16x16x32_bf16 v[42:45], v[162:165], v[222:225], v[42:45]
	v_mfma_f32_16x16x32_bf16 v[34:37], v[170:173], v[222:225], v[34:37]
	v_mfma_f32_16x16x32_bf16 v[126:129], v[166:169], v[200:203], v[126:129]
	v_mfma_f32_16x16x32_bf16 v[122:125], v[174:177], v[200:203], v[122:125]
	v_mfma_f32_16x16x32_bf16 v[118:121], v[166:169], v[210:213], v[118:121]
	v_mfma_f32_16x16x32_bf16 v[114:117], v[174:177], v[210:213], v[114:117]
	v_mfma_f32_16x16x32_bf16 v[102:105], v[166:169], v[218:221], v[102:105]
	v_mfma_f32_16x16x32_bf16 v[98:101], v[174:177], v[218:221], v[98:101]
	v_mfma_f32_16x16x32_bf16 v[42:45], v[166:169], v[226:229], v[42:45]
	v_mfma_f32_16x16x32_bf16 v[34:37], v[174:177], v[226:229], v[34:37]
	v_mfma_f32_16x16x32_bf16 v[110:113], v[178:181], v[196:199], v[110:113]
	v_mfma_f32_16x16x32_bf16 v[106:109], v[186:189], v[196:199], v[106:109]
	v_mfma_f32_16x16x32_bf16 v[94:97], v[178:181], v[206:209], v[94:97]
	v_mfma_f32_16x16x32_bf16 v[90:93], v[186:189], v[206:209], v[90:93]
	v_mfma_f32_16x16x32_bf16 v[86:89], v[178:181], v[214:217], v[86:89]
	v_mfma_f32_16x16x32_bf16 v[82:85], v[186:189], v[214:217], v[82:85]
	v_mfma_f32_16x16x32_bf16 v[30:33], v[178:181], v[222:225], v[30:33]
	v_mfma_f32_16x16x32_bf16 v[26:29], v[186:189], v[222:225], v[26:29]
	v_mfma_f32_16x16x32_bf16 v[110:113], v[182:185], v[200:203], v[110:113]
	v_mfma_f32_16x16x32_bf16 v[106:109], v[190:193], v[200:203], v[106:109]
	v_mfma_f32_16x16x32_bf16 v[94:97], v[182:185], v[210:213], v[94:97]
	v_mfma_f32_16x16x32_bf16 v[90:93], v[190:193], v[210:213], v[90:93]
	v_mfma_f32_16x16x32_bf16 v[86:89], v[182:185], v[218:221], v[86:89]
	v_mfma_f32_16x16x32_bf16 v[82:85], v[190:193], v[218:221], v[82:85]
	v_mfma_f32_16x16x32_bf16 v[30:33], v[182:185], v[226:229], v[30:33]
	v_mfma_f32_16x16x32_bf16 v[26:29], v[190:193], v[226:229], v[26:29]
	s_setprio 0
	s_add_i32 s34, s64, s40
	v_lshl_add_u64 v[158:159], v[158:159], 0, s[10:11]
	s_mov_b32 m0, s34
	ds_read_b128 v[196:199], v161 offset:49152
	ds_read_b128 v[200:203], v161 offset:50176
	ds_read_b128 v[206:209], v161 offset:51200
	ds_read_b128 v[210:213], v161 offset:52224
	ds_read_b128 v[214:217], v161 offset:53248
	ds_read_b128 v[218:221], v161 offset:54272
	ds_read_b128 v[222:225], v161 offset:55296
	ds_read_b128 v[226:229], v161 offset:56320
	global_load_lds_dwordx4 v[158:159], off
	s_add_i32 m0, s34, 0x2000
	s_add_u32 s30, s30, 0x100080
	v_lshl_add_u64 v[158:159], v[230:231], 0, s[10:11]
	s_addc_u32 s31, s31, 0
	s_add_i32 s34, s65, s40
	global_load_lds_dwordx4 v[158:159], off
	v_lshl_add_u64 v[158:159], s[30:31], 0, v[134:135]
	s_mov_b32 m0, s34
	s_nop 0
	global_load_lds_dwordx4 v[158:159], off
	v_lshl_add_u64 v[158:159], s[30:31], 0, v[132:133]
	s_add_i32 m0, s34, 0x2000
	s_nop 0
	global_load_lds_dwordx4 v[158:159], off
	v_lshl_add_u64 v[158:159], v[232:233], 0, s[10:11]
	s_mov_b32 m0, s50
	s_nop 0
	global_load_lds_dwordx4 v[158:159], off
	v_lshl_add_u64 v[158:159], v[234:235], 0, s[10:11]
	s_mov_b32 m0, s51
	s_nop 0
	global_load_lds_dwordx4 v[158:159], off
	s_waitcnt vmcnt(8)
	s_waitcnt lgkmcnt(0)
	s_barrier
	s_setprio 2
	v_mfma_f32_16x16x32_bf16 v[78:81], v[162:165], v[196:199], v[78:81]
	v_mfma_f32_16x16x32_bf16 v[74:77], v[170:173], v[196:199], v[74:77]
	v_mfma_f32_16x16x32_bf16 v[70:73], v[162:165], v[206:209], v[70:73]
	v_mfma_f32_16x16x32_bf16 v[66:69], v[170:173], v[206:209], v[66:69]
	v_mfma_f32_16x16x32_bf16 v[54:57], v[162:165], v[214:217], v[54:57]
	v_mfma_f32_16x16x32_bf16 v[50:53], v[170:173], v[214:217], v[50:53]
	v_mfma_f32_16x16x32_bf16 v[14:17], v[162:165], v[222:225], v[14:17]
	v_mfma_f32_16x16x32_bf16 v[10:13], v[170:173], v[222:225], v[10:13]
	v_mfma_f32_16x16x32_bf16 v[78:81], v[166:169], v[200:203], v[78:81]
	v_mfma_f32_16x16x32_bf16 v[74:77], v[174:177], v[200:203], v[74:77]
	v_mfma_f32_16x16x32_bf16 v[70:73], v[166:169], v[210:213], v[70:73]
	v_mfma_f32_16x16x32_bf16 v[66:69], v[174:177], v[210:213], v[66:69]
	v_mfma_f32_16x16x32_bf16 v[54:57], v[166:169], v[218:221], v[54:57]
	v_mfma_f32_16x16x32_bf16 v[50:53], v[174:177], v[218:221], v[50:53]
	v_mfma_f32_16x16x32_bf16 v[14:17], v[166:169], v[226:229], v[14:17]
	v_mfma_f32_16x16x32_bf16 v[10:13], v[174:177], v[226:229], v[10:13]
	v_mfma_f32_16x16x32_bf16 v[62:65], v[178:181], v[196:199], v[62:65]
	v_mfma_f32_16x16x32_bf16 v[58:61], v[186:189], v[196:199], v[58:61]
	v_mfma_f32_16x16x32_bf16 v[46:49], v[178:181], v[206:209], v[46:49]
	v_mfma_f32_16x16x32_bf16 v[38:41], v[186:189], v[206:209], v[38:41]
	v_mfma_f32_16x16x32_bf16 v[22:25], v[178:181], v[214:217], v[22:25]
	v_mfma_f32_16x16x32_bf16 v[18:21], v[186:189], v[214:217], v[18:21]
	v_mfma_f32_16x16x32_bf16 v[6:9], v[178:181], v[222:225], v[6:9]
	v_mfma_f32_16x16x32_bf16 v[2:5], v[186:189], v[222:225], v[2:5]
	v_mfma_f32_16x16x32_bf16 v[62:65], v[182:185], v[200:203], v[62:65]
	v_mfma_f32_16x16x32_bf16 v[58:61], v[190:193], v[200:203], v[58:61]
	v_mfma_f32_16x16x32_bf16 v[46:49], v[182:185], v[210:213], v[46:49]
	v_mfma_f32_16x16x32_bf16 v[38:41], v[190:193], v[210:213], v[38:41]
	v_mfma_f32_16x16x32_bf16 v[22:25], v[182:185], v[218:221], v[22:25]
	v_mfma_f32_16x16x32_bf16 v[18:21], v[190:193], v[218:221], v[18:21]
	v_mfma_f32_16x16x32_bf16 v[6:9], v[182:185], v[226:229], v[6:9]
	v_mfma_f32_16x16x32_bf16 v[2:5], v[190:193], v[226:229], v[2:5]
	s_setprio 0
	s_add_u32 s28, s28, 0x100
	s_addc_u32 s29, s29, 0
	s_add_u32 s61, s61, 0x100
	s_addc_u32 s62, s62, 0
	s_cmp_ge_i32 s63, s58
	s_mov_b32 s30, s63
	s_cbranch_scc0 .Lkt_T_14
	s_nop 7

.LBB0_3797:
	v_ashrrev_i32_e32 v19, 31, v18
	v_lshl_add_u64 v[20:21], v[158:159], 2, s[28:29]
	v_lshlrev_b64 v[18:19], 11, v[18:19]
	v_lshl_add_u64 v[18:19], v[20:21], 0, v[18:19]
	s_andn2_b64 vcc, exec, s[4:5]
	s_mov_b64 s[4:5], -1
	global_store_dwordx4 v[18:19], v[14:17], off
	global_store_dwordx4 v[18:19], v[10:13], off offset:64
	global_store_dwordx4 v[18:19], v[6:9], off offset:512
	global_store_dwordx4 v[18:19], v[2:5], off offset:576
	s_cbranch_vccnz .LBB0_3785
	s_andn2_b64 vcc, exec, s[8:9]
	s_cbranch_vccnz .LBB0_3784
	s_branch .LBB0_3784

.LBB0_3966:
	s_add_u32 s10, s38, 0x31800000
	s_addc_u32 s11, s39, 0
	s_add_u32 s12, s38, 0x39c00000
	s_addc_u32 s13, s39, 0
	s_add_u32 s65, s38, 0x50600000
	s_addc_u32 s66, s39, 0
	s_lshl_b32 s0, s5, 5
	s_mov_b64 s[14:15], 0x80
	s_and_b32 s5, s0, 0x60
	s_add_i32 m0, s55, 0x18000
	v_lshl_add_u64 v[8:9], v[8:9], 0, s[14:15]
	s_lshl_b32 s17, s4, 13
	s_lshl_b32 s18, s5, 7
	s_ashr_i32 s67, s2, 31
	s_waitcnt vmcnt(2)
	s_barrier
	global_load_lds_dwordx4 v[8:9], off
	v_lshl_add_u64 v[6:7], v[6:7], 0, s[14:15]
	s_add_i32 m0, s55, 0x1a000
	s_add_i32 s68, s55, 0x8000
	s_add_i32 s69, s55, 0xa000
	global_load_lds_dwordx4 v[6:7], off
	v_lshl_add_u64 v[2:3], v[2:3], 0, s[14:15]
	s_mov_b32 m0, s68
	s_add_u32 s0, s48, 0x20080
	global_load_lds_dwordx4 v[2:3], off
	v_lshl_add_u64 v[2:3], v[4:5], 0, s[14:15]
	s_mov_b32 m0, s69
	s_addc_u32 s1, s49, 0
	global_load_lds_dwordx4 v[2:3], off
	s_add_i32 m0, s55, 0x1c000
	v_lshl_add_u64 v[2:3], s[0:1], 0, v[134:135]
	global_load_lds_dwordx4 v[2:3], off
	v_lshl_add_u64 v[2:3], s[0:1], 0, v[138:139]
	s_add_i32 m0, s55, 0x1e000
	v_lshlrev_b32_e32 v4, 2, v0
	global_load_lds_dwordx4 v[2:3], off
	v_and_b32_e32 v2, 15, v0
	v_lshlrev_b32_e32 v3, 1, v13
	v_lshlrev_b32_e32 v5, 6, v0
	s_movk_i32 s0, 0x3c0
	v_lshl_or_b32 v131, s4, 6, v2
	v_lshl_or_b32 v2, v2, 6, v3
	v_and_b32_e32 v4, 32, v4
	v_and_or_b32 v3, v5, s0, v3
	v_bitop3_b32 v158, s18, v3, v4 bitop3:0xf6
	v_lshlrev_b32_e32 v3, 7, v0
	v_bitop3_b32 v2, v2, s17, v4 bitop3:0xde
	v_and_b32_e32 v3, 0xc000, v3
	v_lshlrev_b32_e32 v4, 10, v12
	v_or3_b32 v3, v10, v3, v4
	v_add_u32_e32 v140, v3, v11
	v_lshlrev_b32_e32 v3, 3, v14
	s_waitcnt vmcnt(6)
	s_cmpk_lt_u32 s16, 0x100
	v_and_b32_e32 v3, 0x1c000, v3
	s_cselect_b64 s[16:17], -1, 0
	v_or3_b32 v3, v10, v3, v4
	s_add_i32 s71, 0, 0x10000
	s_add_i32 s72, 0, 0x14000
	s_brev_b32 s18, 31
	s_mov_b32 s20, 0xf8040000
	s_mov_b32 s22, 0xf8080000
	s_mov_b32 s24, 0xf80c0000
	s_ashr_i32 s70, s44, 31
	v_or_b32_e32 v159, s5, v13
	v_mov_b32_e32 v141, v135
	v_add_u32_e32 v142, v3, v11
	v_mov_b32_e32 v143, v135
	v_mov_b64_e32 v[144:145], 0x240
	v_mov_b64_e32 v[146:147], 0x23f
	v_add_u32_e32 v160, s71, v158
	v_add_u32_e32 v161, s72, v158
	v_add_u32_e32 v162, 0, v2
	s_mov_b32 s19, -1
	s_brev_b32 s73, 31
	s_mov_b32 s21, -1
	s_mov_b32 s74, 0xf8040000
	s_mov_b32 s23, -1
	s_mov_b32 s75, 0xf8080000
	s_mov_b32 s25, -1
	s_mov_b32 s26, 0x3fb504f3
	s_mov_b64 s[28:29], 0x100000
	s_mov_b64 s[30:31], 0x120000
	s_mov_b64 s[34:35], 0x140000
	s_mov_b64 s[40:41], 0x160000
	v_mov_b64_e32 v[148:149], 0x1ff
	v_mov_b64_e32 v[150:151], 0x200
	s_mov_b32 s76, s7
	s_branch .LBB0_3969

.Lkt_L_15:
	ds_read_b128 v[152:155], v160
	ds_read_b128 v[164:167], v160 offset:1024
	ds_read_b128 v[168:171], v160 offset:2048
	ds_read_b128 v[172:175], v160 offset:3072
	ds_read_b128 v[176:179], v161
	ds_read_b128 v[180:183], v161 offset:1024
	ds_read_b128 v[184:187], v161 offset:2048
	ds_read_b128 v[188:191], v161 offset:3072
	s_add_i32 s80, s48, 2
	s_add_u32 s49, s58, 0xfffe0080
	s_addc_u32 s60, s59, -1
	s_cmp_eq_u32 s43, s48
	s_cselect_b32 s48, s52, s47
	s_cselect_b32 s61, s5, s60
	s_cselect_b32 s60, s4, s49
	s_cselect_b32 s49, s53, s51
	v_lshl_add_u64 v[156:157], s[58:59], 0, v[140:141]
	s_add_i32 m0, s55, 0xc000
	ds_read_b128 v[196:199], v162
	ds_read_b128 v[200:203], v162 offset:1024
	ds_read_b128 v[204:207], v162 offset:2048
	ds_read_b128 v[208:211], v162 offset:3072
	ds_read_b128 v[212:215], v162 offset:4096
	ds_read_b128 v[216:219], v162 offset:5120
	ds_read_b128 v[220:223], v162 offset:6144
	ds_read_b128 v[224:227], v162 offset:7168
	global_load_lds_dwordx4 v[156:157], off
	v_lshl_add_u64 v[156:157], s[58:59], 0, v[142:143]
	s_add_i32 m0, s55, 0xe000
	s_nop 0
	global_load_lds_dwordx4 v[156:157], off
	s_waitcnt lgkmcnt(0)
	s_setprio 1
	v_mfma_f32_16x16x32_bf16 v[126:129], v[152:155], v[196:199], v[126:129]
	v_mfma_f32_16x16x32_bf16 v[122:125], v[168:171], v[196:199], v[122:125]
	v_mfma_f32_16x16x32_bf16 v[110:113], v[152:155], v[204:207], v[110:113]
	v_mfma_f32_16x16x32_bf16 v[106:109], v[168:171], v[204:207], v[106:109]
	v_mfma_f32_16x16x32_bf16 v[94:97], v[152:155], v[212:215], v[94:97]
	v_mfma_f32_16x16x32_bf16 v[90:93], v[168:171], v[212:215], v[90:93]
	v_mfma_f32_16x16x32_bf16 v[78:81], v[152:155], v[220:223], v[78:81]
	v_mfma_f32_16x16x32_bf16 v[74:77], v[168:171], v[220:223], v[74:77]
	v_mfma_f32_16x16x32_bf16 v[126:129], v[164:167], v[200:203], v[126:129]
	v_mfma_f32_16x16x32_bf16 v[122:125], v[172:175], v[200:203], v[122:125]
	v_mfma_f32_16x16x32_bf16 v[110:113], v[164:167], v[208:211], v[110:113]
	v_mfma_f32_16x16x32_bf16 v[106:109], v[172:175], v[208:211], v[106:109]
	v_mfma_f32_16x16x32_bf16 v[94:97], v[164:167], v[216:219], v[94:97]
	v_mfma_f32_16x16x32_bf16 v[90:93], v[172:175], v[216:219], v[90:93]
	v_mfma_f32_16x16x32_bf16 v[78:81], v[164:167], v[224:227], v[78:81]
	v_mfma_f32_16x16x32_bf16 v[74:77], v[172:175], v[224:227], v[74:77]
	v_mfma_f32_16x16x32_bf16 v[118:121], v[176:179], v[196:199], v[118:121]
	v_mfma_f32_16x16x32_bf16 v[114:117], v[184:187], v[196:199], v[114:117]
	v_mfma_f32_16x16x32_bf16 v[102:105], v[176:179], v[204:207], v[102:105]
	v_mfma_f32_16x16x32_bf16 v[98:101], v[184:187], v[204:207], v[98:101]
	v_mfma_f32_16x16x32_bf16 v[86:89], v[176:179], v[212:215], v[86:89]
	v_mfma_f32_16x16x32_bf16 v[82:85], v[184:187], v[212:215], v[82:85]
	v_mfma_f32_16x16x32_bf16 v[70:73], v[176:179], v[220:223], v[70:73]
	v_mfma_f32_16x16x32_bf16 v[66:69], v[184:187], v[220:223], v[66:69]
	v_mfma_f32_16x16x32_bf16 v[118:121], v[180:183], v[200:203], v[118:121]
	v_mfma_f32_16x16x32_bf16 v[114:117], v[188:191], v[200:203], v[114:117]
	v_mfma_f32_16x16x32_bf16 v[102:105], v[180:183], v[208:211], v[102:105]
	v_mfma_f32_16x16x32_bf16 v[98:101], v[188:191], v[208:211], v[98:101]
	v_mfma_f32_16x16x32_bf16 v[86:89], v[180:183], v[216:219], v[86:89]
	v_mfma_f32_16x16x32_bf16 v[82:85], v[188:191], v[216:219], v[82:85]
	v_mfma_f32_16x16x32_bf16 v[70:73], v[180:183], v[224:227], v[70:73]
	v_mfma_f32_16x16x32_bf16 v[66:69], v[188:191], v[224:227], v[66:69]
	s_setprio 0
	s_waitcnt vmcnt(8)
	s_barrier
	s_add_i32 s81, s71, s62
	v_lshl_add_u64 v[156:157], s[48:49], 0, v[134:135]
	s_mov_b32 m0, s81
	ds_read_b128 v[196:199], v162 offset:16384
	ds_read_b128 v[200:203], v162 offset:17408
	ds_read_b128 v[204:207], v162 offset:18432
	ds_read_b128 v[208:211], v162 offset:19456
	ds_read_b128 v[212:215], v162 offset:20480
	ds_read_b128 v[216:219], v162 offset:21504
	ds_read_b128 v[220:223], v162 offset:22528
	ds_read_b128 v[224:227], v162 offset:23552
	global_load_lds_dwordx4 v[156:157], off
	s_add_i32 m0, s81, 0x2000
	s_add_u32 s82, s48, 0x20000
	v_lshl_add_u64 v[192:193], s[48:49], 0, v[138:139]
	s_addc_u32 s83, s49, 0
	s_add_i32 s81, s72, s62
	global_load_lds_dwordx4 v[192:193], off
	v_lshl_add_u64 v[228:229], s[82:83], 0, v[134:135]
	s_mov_b32 m0, s81
	v_lshl_add_u64 v[230:231], s[60:61], 0, v[136:137]
	global_load_lds_dwordx4 v[228:229], off
	v_lshl_add_u64 v[228:229], s[82:83], 0, v[138:139]
	s_add_i32 m0, s81, 0x2000
	s_nop 0
	global_load_lds_dwordx4 v[228:229], off
	v_lshl_add_u64 v[228:229], s[60:61], 0, v[132:133]
	s_mov_b32 m0, s55
	s_nop 0
	global_load_lds_dwordx4 v[228:229], off
	s_mov_b32 m0, s57
	s_nop 0
	global_load_lds_dwordx4 v[230:231], off
	s_waitcnt lgkmcnt(0)
	s_setprio 1
	v_mfma_f32_16x16x32_bf16 v[62:65], v[152:155], v[196:199], v[62:65]
	v_mfma_f32_16x16x32_bf16 v[58:61], v[168:171], v[196:199], v[58:61]
	v_mfma_f32_16x16x32_bf16 v[46:49], v[152:155], v[204:207], v[46:49]
	v_mfma_f32_16x16x32_bf16 v[42:45], v[168:171], v[204:207], v[42:45]
	v_mfma_f32_16x16x32_bf16 v[30:33], v[152:155], v[212:215], v[30:33]
	v_mfma_f32_16x16x32_bf16 v[26:29], v[168:171], v[212:215], v[26:29]
	v_mfma_f32_16x16x32_bf16 v[14:17], v[152:155], v[220:223], v[14:17]
	v_mfma_f32_16x16x32_bf16 v[10:13], v[168:171], v[220:223], v[10:13]
	v_mfma_f32_16x16x32_bf16 v[62:65], v[164:167], v[200:203], v[62:65]
	v_mfma_f32_16x16x32_bf16 v[58:61], v[172:175], v[200:203], v[58:61]
	v_mfma_f32_16x16x32_bf16 v[46:49], v[164:167], v[208:211], v[46:49]
	v_mfma_f32_16x16x32_bf16 v[42:45], v[172:175], v[208:211], v[42:45]
	v_mfma_f32_16x16x32_bf16 v[30:33], v[164:167], v[216:219], v[30:33]
	v_mfma_f32_16x16x32_bf16 v[26:29], v[172:175], v[216:219], v[26:29]
	v_mfma_f32_16x16x32_bf16 v[14:17], v[164:167], v[224:227], v[14:17]
	v_mfma_f32_16x16x32_bf16 v[10:13], v[172:175], v[224:227], v[10:13]
	v_mfma_f32_16x16x32_bf16 v[54:57], v[176:179], v[196:199], v[54:57]
	v_mfma_f32_16x16x32_bf16 v[50:53], v[184:187], v[196:199], v[50:53]
	v_mfma_f32_16x16x32_bf16 v[38:41], v[176:179], v[204:207], v[38:41]
	v_mfma_f32_16x16x32_bf16 v[34:37], v[184:187], v[204:207], v[34:37]
	v_mfma_f32_16x16x32_bf16 v[22:25], v[176:179], v[212:215], v[22:25]
	v_mfma_f32_16x16x32_bf16 v[18:21], v[184:187], v[212:215], v[18:21]
	v_mfma_f32_16x16x32_bf16 v[6:9], v[176:179], v[220:223], v[6:9]
	v_mfma_f32_16x16x32_bf16 v[2:5], v[184:187], v[220:223], v[2:5]
	v_mfma_f32_16x16x32_bf16 v[54:57], v[180:183], v[200:203], v[54:57]
	v_mfma_f32_16x16x32_bf16 v[50:53], v[188:191], v[200:203], v[50:53]
	v_mfma_f32_16x16x32_bf16 v[38:41], v[180:183], v[208:211], v[38:41]
	v_mfma_f32_16x16x32_bf16 v[34:37], v[188:191], v[208:211], v[34:37]
	v_mfma_f32_16x16x32_bf16 v[22:25], v[180:183], v[216:219], v[22:25]
	v_mfma_f32_16x16x32_bf16 v[18:21], v[188:191], v[216:219], v[18:21]
	v_mfma_f32_16x16x32_bf16 v[6:9], v[180:183], v[224:227], v[6:9]
	v_mfma_f32_16x16x32_bf16 v[2:5], v[188:191], v[224:227], v[2:5]
	s_setprio 0
	s_waitcnt vmcnt(8)
	s_barrier
	s_add_i32 s81, 0, 0x18000
	v_add_u32_e32 v163, s81, v158
	s_add_i32 s82, 0, 0x1c000
	ds_read_b128 v[152:155], v163
	ds_read_b128 v[164:167], v163 offset:1024
	ds_read_b128 v[168:171], v163 offset:2048
	ds_read_b128 v[172:175], v163 offset:3072
	v_add_u32_e32 v163, s82, v158
	ds_read_b128 v[176:179], v163
	ds_read_b128 v[180:183], v163 offset:1024
	ds_read_b128 v[184:187], v163 offset:2048
	ds_read_b128 v[188:191], v163 offset:3072
	s_add_u32 s60, s60, 0x20000
	s_addc_u32 s61, s61, 0
	s_mov_b32 m0, s63
	v_lshl_add_u64 v[232:233], s[60:61], 0, v[132:133]
	ds_read_b128 v[196:199], v162 offset:32768
	ds_read_b128 v[200:203], v162 offset:33792
	ds_read_b128 v[204:207], v162 offset:34816
	ds_read_b128 v[208:211], v162 offset:35840
	ds_read_b128 v[212:215], v162 offset:36864
	ds_read_b128 v[216:219], v162 offset:37888
	ds_read_b128 v[220:223], v162 offset:38912
	ds_read_b128 v[224:227], v162 offset:39936
	global_load_lds_dwordx4 v[232:233], off
	v_lshl_add_u64 v[232:233], s[60:61], 0, v[136:137]
	s_mov_b32 m0, s64
	s_nop 0
	global_load_lds_dwordx4 v[232:233], off
	s_waitcnt lgkmcnt(0)
	s_setprio 1
	v_mfma_f32_16x16x32_bf16 v[126:129], v[152:155], v[196:199], v[126:129]
	v_mfma_f32_16x16x32_bf16 v[122:125], v[168:171], v[196:199], v[122:125]
	v_mfma_f32_16x16x32_bf16 v[110:113], v[152:155], v[204:207], v[110:113]
	v_mfma_f32_16x16x32_bf16 v[106:109], v[168:171], v[204:207], v[106:109]
	v_mfma_f32_16x16x32_bf16 v[94:97], v[152:155], v[212:215], v[94:97]
	v_mfma_f32_16x16x32_bf16 v[90:93], v[168:171], v[212:215], v[90:93]
	v_mfma_f32_16x16x32_bf16 v[78:81], v[152:155], v[220:223], v[78:81]
	v_mfma_f32_16x16x32_bf16 v[74:77], v[168:171], v[220:223], v[74:77]
	v_mfma_f32_16x16x32_bf16 v[126:129], v[164:167], v[200:203], v[126:129]
	v_mfma_f32_16x16x32_bf16 v[122:125], v[172:175], v[200:203], v[122:125]
	v_mfma_f32_16x16x32_bf16 v[110:113], v[164:167], v[208:211], v[110:113]
	v_mfma_f32_16x16x32_bf16 v[106:109], v[172:175], v[208:211], v[106:109]
	v_mfma_f32_16x16x32_bf16 v[94:97], v[164:167], v[216:219], v[94:97]
	v_mfma_f32_16x16x32_bf16 v[90:93], v[172:175], v[216:219], v[90:93]
	v_mfma_f32_16x16x32_bf16 v[78:81], v[164:167], v[224:227], v[78:81]
	v_mfma_f32_16x16x32_bf16 v[74:77], v[172:175], v[224:227], v[74:77]
	v_mfma_f32_16x16x32_bf16 v[118:121], v[176:179], v[196:199], v[118:121]
	v_mfma_f32_16x16x32_bf16 v[114:117], v[184:187], v[196:199], v[114:117]
	v_mfma_f32_16x16x32_bf16 v[102:105], v[176:179], v[204:207], v[102:105]
	v_mfma_f32_16x16x32_bf16 v[98:101], v[184:187], v[204:207], v[98:101]
	v_mfma_f32_16x16x32_bf16 v[86:89], v[176:179], v[212:215], v[86:89]
	v_mfma_f32_16x16x32_bf16 v[82:85], v[184:187], v[212:215], v[82:85]
	v_mfma_f32_16x16x32_bf16 v[70:73], v[176:179], v[220:223], v[70:73]
	v_mfma_f32_16x16x32_bf16 v[66:69], v[184:187], v[220:223], v[66:69]
	v_mfma_f32_16x16x32_bf16 v[118:121], v[180:183], v[200:203], v[118:121]
	v_mfma_f32_16x16x32_bf16 v[114:117], v[188:191], v[200:203], v[114:117]
	v_mfma_f32_16x16x32_bf16 v[102:105], v[180:183], v[208:211], v[102:105]
	v_mfma_f32_16x16x32_bf16 v[98:101], v[188:191], v[208:211], v[98:101]
	v_mfma_f32_16x16x32_bf16 v[86:89], v[180:183], v[216:219], v[86:89]
	v_mfma_f32_16x16x32_bf16 v[82:85], v[188:191], v[216:219], v[82:85]
	v_mfma_f32_16x16x32_bf16 v[70:73], v[180:183], v[224:227], v[70:73]
	v_mfma_f32_16x16x32_bf16 v[66:69], v[188:191], v[224:227], v[66:69]
	s_setprio 0
	s_waitcnt vmcnt(8)
	s_barrier
	s_add_i32 s60, s81, s62
	v_lshl_add_u64 v[156:157], v[156:157], 0, s[14:15]
	s_mov_b32 m0, s60
	ds_read_b128 v[196:199], v162 offset:49152
	ds_read_b128 v[200:203], v162 offset:50176
	ds_read_b128 v[204:207], v162 offset:51200
	ds_read_b128 v[208:211], v162 offset:52224
	ds_read_b128 v[212:215], v162 offset:53248
	ds_read_b128 v[216:219], v162 offset:54272
	ds_read_b128 v[220:223], v162 offset:55296
	ds_read_b128 v[224:227], v162 offset:56320
	global_load_lds_dwordx4 v[156:157], off
	s_add_i32 m0, s60, 0x2000
	s_add_u32 s48, s48, 0x20080
	v_lshl_add_u64 v[156:157], v[192:193], 0, s[14:15]
	s_addc_u32 s49, s49, 0
	s_add_i32 s60, s82, s62
	global_load_lds_dwordx4 v[156:157], off
	v_lshl_add_u64 v[156:157], s[48:49], 0, v[134:135]
	s_mov_b32 m0, s60
	s_nop 0
	global_load_lds_dwordx4 v[156:157], off
	v_lshl_add_u64 v[156:157], s[48:49], 0, v[138:139]
	s_add_i32 m0, s60, 0x2000
	s_nop 0
	global_load_lds_dwordx4 v[156:157], off
	v_lshl_add_u64 v[156:157], v[228:229], 0, s[14:15]
	s_mov_b32 m0, s68
	s_nop 0
	global_load_lds_dwordx4 v[156:157], off
	v_lshl_add_u64 v[156:157], v[230:231], 0, s[14:15]
	s_mov_b32 m0, s69
	s_nop 0
	global_load_lds_dwordx4 v[156:157], off
	s_waitcnt lgkmcnt(0)
	s_setprio 1
	v_mfma_f32_16x16x32_bf16 v[62:65], v[152:155], v[196:199], v[62:65]
	v_mfma_f32_16x16x32_bf16 v[58:61], v[168:171], v[196:199], v[58:61]
	v_mfma_f32_16x16x32_bf16 v[46:49], v[152:155], v[204:207], v[46:49]
	v_mfma_f32_16x16x32_bf16 v[42:45], v[168:171], v[204:207], v[42:45]
	v_mfma_f32_16x16x32_bf16 v[30:33], v[152:155], v[212:215], v[30:33]
	v_mfma_f32_16x16x32_bf16 v[26:29], v[168:171], v[212:215], v[26:29]
	v_mfma_f32_16x16x32_bf16 v[14:17], v[152:155], v[220:223], v[14:17]
	v_mfma_f32_16x16x32_bf16 v[10:13], v[168:171], v[220:223], v[10:13]
	v_mfma_f32_16x16x32_bf16 v[62:65], v[164:167], v[200:203], v[62:65]
	v_mfma_f32_16x16x32_bf16 v[58:61], v[172:175], v[200:203], v[58:61]
	v_mfma_f32_16x16x32_bf16 v[46:49], v[164:167], v[208:211], v[46:49]
	v_mfma_f32_16x16x32_bf16 v[42:45], v[172:175], v[208:211], v[42:45]
	v_mfma_f32_16x16x32_bf16 v[30:33], v[164:167], v[216:219], v[30:33]
	v_mfma_f32_16x16x32_bf16 v[26:29], v[172:175], v[216:219], v[26:29]
	v_mfma_f32_16x16x32_bf16 v[14:17], v[164:167], v[224:227], v[14:17]
	v_mfma_f32_16x16x32_bf16 v[10:13], v[172:175], v[224:227], v[10:13]
	v_mfma_f32_16x16x32_bf16 v[54:57], v[176:179], v[196:199], v[54:57]
	v_mfma_f32_16x16x32_bf16 v[50:53], v[184:187], v[196:199], v[50:53]
	v_mfma_f32_16x16x32_bf16 v[38:41], v[176:179], v[204:207], v[38:41]
	v_mfma_f32_16x16x32_bf16 v[34:37], v[184:187], v[204:207], v[34:37]
	v_mfma_f32_16x16x32_bf16 v[22:25], v[176:179], v[212:215], v[22:25]
	v_mfma_f32_16x16x32_bf16 v[18:21], v[184:187], v[212:215], v[18:21]
	v_mfma_f32_16x16x32_bf16 v[6:9], v[176:179], v[220:223], v[6:9]
	v_mfma_f32_16x16x32_bf16 v[2:5], v[184:187], v[220:223], v[2:5]
	v_mfma_f32_16x16x32_bf16 v[54:57], v[180:183], v[200:203], v[54:57]
	v_mfma_f32_16x16x32_bf16 v[50:53], v[188:191], v[200:203], v[50:53]
	v_mfma_f32_16x16x32_bf16 v[38:41], v[180:183], v[208:211], v[38:41]
	v_mfma_f32_16x16x32_bf16 v[34:37], v[188:191], v[208:211], v[34:37]
	v_mfma_f32_16x16x32_bf16 v[22:25], v[180:183], v[216:219], v[22:25]
	v_mfma_f32_16x16x32_bf16 v[18:21], v[188:191], v[216:219], v[18:21]
	v_mfma_f32_16x16x32_bf16 v[6:9], v[180:183], v[224:227], v[6:9]
	v_mfma_f32_16x16x32_bf16 v[2:5], v[188:191], v[224:227], v[2:5]
	s_setprio 0
	s_waitcnt vmcnt(8)
	s_barrier
	s_add_u32 s58, s58, 0x100
	s_addc_u32 s59, s59, 0
	s_add_u32 s47, s47, 0x100
	s_addc_u32 s51, s51, 0
	s_cmp_ge_i32 s80, s79
	s_mov_b32 s48, s80
	s_cbranch_scc0 .Lkt_L_15
	s_branch .Lkt_exit_15
.Lkt_T_15:
	ds_read_b128 v[152:155], v160
	ds_read_b128 v[164:167], v160 offset:1024
	ds_read_b128 v[168:171], v160 offset:2048
	ds_read_b128 v[172:175], v160 offset:3072
	ds_read_b128 v[176:179], v161
	ds_read_b128 v[180:183], v161 offset:1024
	ds_read_b128 v[184:187], v161 offset:2048
	ds_read_b128 v[188:191], v161 offset:3072
	s_add_i32 s80, s48, 2
	s_add_u32 s49, s58, 0xfffe0080
	s_addc_u32 s60, s59, -1
	s_cmp_eq_u32 s43, s48
	s_cselect_b32 s48, s52, s47
	s_cselect_b32 s61, s5, s60
	s_cselect_b32 s60, s4, s49
	s_cselect_b32 s49, s53, s51
	v_lshl_add_u64 v[156:157], s[58:59], 0, v[140:141]
	s_add_i32 m0, s55, 0xc000
	ds_read_b128 v[196:199], v162
	ds_read_b128 v[200:203], v162 offset:1024
	ds_read_b128 v[204:207], v162 offset:2048
	ds_read_b128 v[208:211], v162 offset:3072
	ds_read_b128 v[212:215], v162 offset:4096
	ds_read_b128 v[216:219], v162 offset:5120
	ds_read_b128 v[220:223], v162 offset:6144
	ds_read_b128 v[224:227], v162 offset:7168
	global_load_lds_dwordx4 v[156:157], off
	v_lshl_add_u64 v[156:157], s[58:59], 0, v[142:143]
	s_add_i32 m0, s55, 0xe000
	s_nop 0
	global_load_lds_dwordx4 v[156:157], off
	s_waitcnt vmcnt(8)
	s_waitcnt lgkmcnt(0)
	s_barrier
	s_setprio 2
	v_mfma_f32_16x16x32_bf16 v[126:129], v[152:155], v[196:199], v[126:129]
	v_mfma_f32_16x16x32_bf16 v[122:125], v[168:171], v[196:199], v[122:125]
	v_mfma_f32_16x16x32_bf16 v[110:113], v[152:155], v[204:207], v[110:113]
	v_mfma_f32_16x16x32_bf16 v[106:109], v[168:171], v[204:207], v[106:109]
	v_mfma_f32_16x16x32_bf16 v[94:97], v[152:155], v[212:215], v[94:97]
	v_mfma_f32_16x16x32_bf16 v[90:93], v[168:171], v[212:215], v[90:93]
	v_mfma_f32_16x16x32_bf16 v[78:81], v[152:155], v[220:223], v[78:81]
	v_mfma_f32_16x16x32_bf16 v[74:77], v[168:171], v[220:223], v[74:77]
	v_mfma_f32_16x16x32_bf16 v[126:129], v[164:167], v[200:203], v[126:129]
	v_mfma_f32_16x16x32_bf16 v[122:125], v[172:175], v[200:203], v[122:125]
	v_mfma_f32_16x16x32_bf16 v[110:113], v[164:167], v[208:211], v[110:113]
	v_mfma_f32_16x16x32_bf16 v[106:109], v[172:175], v[208:211], v[106:109]
	v_mfma_f32_16x16x32_bf16 v[94:97], v[164:167], v[216:219], v[94:97]
	v_mfma_f32_16x16x32_bf16 v[90:93], v[172:175], v[216:219], v[90:93]
	v_mfma_f32_16x16x32_bf16 v[78:81], v[164:167], v[224:227], v[78:81]
	v_mfma_f32_16x16x32_bf16 v[74:77], v[172:175], v[224:227], v[74:77]
	v_mfma_f32_16x16x32_bf16 v[118:121], v[176:179], v[196:199], v[118:121]
	v_mfma_f32_16x16x32_bf16 v[114:117], v[184:187], v[196:199], v[114:117]
	v_mfma_f32_16x16x32_bf16 v[102:105], v[176:179], v[204:207], v[102:105]
	v_mfma_f32_16x16x32_bf16 v[98:101], v[184:187], v[204:207], v[98:101]
	v_mfma_f32_16x16x32_bf16 v[86:89], v[176:179], v[212:215], v[86:89]
	v_mfma_f32_16x16x32_bf16 v[82:85], v[184:187], v[212:215], v[82:85]
	v_mfma_f32_16x16x32_bf16 v[70:73], v[176:179], v[220:223], v[70:73]
	v_mfma_f32_16x16x32_bf16 v[66:69], v[184:187], v[220:223], v[66:69]
	v_mfma_f32_16x16x32_bf16 v[118:121], v[180:183], v[200:203], v[118:121]
	v_mfma_f32_16x16x32_bf16 v[114:117], v[188:191], v[200:203], v[114:117]
	v_mfma_f32_16x16x32_bf16 v[102:105], v[180:183], v[208:211], v[102:105]
	v_mfma_f32_16x16x32_bf16 v[98:101], v[188:191], v[208:211], v[98:101]
	v_mfma_f32_16x16x32_bf16 v[86:89], v[180:183], v[216:219], v[86:89]
	v_mfma_f32_16x16x32_bf16 v[82:85], v[188:191], v[216:219], v[82:85]
	v_mfma_f32_16x16x32_bf16 v[70:73], v[180:183], v[224:227], v[70:73]
	v_mfma_f32_16x16x32_bf16 v[66:69], v[188:191], v[224:227], v[66:69]
	s_setprio 0
	s_add_i32 s81, s71, s62
	v_lshl_add_u64 v[156:157], s[48:49], 0, v[134:135]
	s_mov_b32 m0, s81
	ds_read_b128 v[196:199], v162 offset:16384
	ds_read_b128 v[200:203], v162 offset:17408
	ds_read_b128 v[204:207], v162 offset:18432
	ds_read_b128 v[208:211], v162 offset:19456
	ds_read_b128 v[212:215], v162 offset:20480
	ds_read_b128 v[216:219], v162 offset:21504
	ds_read_b128 v[220:223], v162 offset:22528
	ds_read_b128 v[224:227], v162 offset:23552
	global_load_lds_dwordx4 v[156:157], off
	s_add_i32 m0, s81, 0x2000
	s_add_u32 s82, s48, 0x20000
	v_lshl_add_u64 v[192:193], s[48:49], 0, v[138:139]
	s_addc_u32 s83, s49, 0
	s_add_i32 s81, s72, s62
	global_load_lds_dwordx4 v[192:193], off
	v_lshl_add_u64 v[228:229], s[82:83], 0, v[134:135]
	s_mov_b32 m0, s81
	v_lshl_add_u64 v[230:231], s[60:61], 0, v[136:137]
	global_load_lds_dwordx4 v[228:229], off
	v_lshl_add_u64 v[228:229], s[82:83], 0, v[138:139]
	s_add_i32 m0, s81, 0x2000
	s_nop 0
	global_load_lds_dwordx4 v[228:229], off
	v_lshl_add_u64 v[228:229], s[60:61], 0, v[132:133]
	s_mov_b32 m0, s55
	s_nop 0
	global_load_lds_dwordx4 v[228:229], off
	s_mov_b32 m0, s57
	s_nop 0
	global_load_lds_dwordx4 v[230:231], off
	s_waitcnt vmcnt(8)
	s_waitcnt lgkmcnt(0)
	s_barrier
	s_setprio 2
	v_mfma_f32_16x16x32_bf16 v[62:65], v[152:155], v[196:199], v[62:65]
	v_mfma_f32_16x16x32_bf16 v[58:61], v[168:171], v[196:199], v[58:61]
	v_mfma_f32_16x16x32_bf16 v[46:49], v[152:155], v[204:207], v[46:49]
	v_mfma_f32_16x16x32_bf16 v[42:45], v[168:171], v[204:207], v[42:45]
	v_mfma_f32_16x16x32_bf16 v[30:33], v[152:155], v[212:215], v[30:33]
	v_mfma_f32_16x16x32_bf16 v[26:29], v[168:171], v[212:215], v[26:29]
	v_mfma_f32_16x16x32_bf16 v[14:17], v[152:155], v[220:223], v[14:17]
	v_mfma_f32_16x16x32_bf16 v[10:13], v[168:171], v[220:223], v[10:13]
	v_mfma_f32_16x16x32_bf16 v[62:65], v[164:167], v[200:203], v[62:65]
	v_mfma_f32_16x16x32_bf16 v[58:61], v[172:175], v[200:203], v[58:61]
	v_mfma_f32_16x16x32_bf16 v[46:49], v[164:167], v[208:211], v[46:49]
	v_mfma_f32_16x16x32_bf16 v[42:45], v[172:175], v[208:211], v[42:45]
	v_mfma_f32_16x16x32_bf16 v[30:33], v[164:167], v[216:219], v[30:33]
	v_mfma_f32_16x16x32_bf16 v[26:29], v[172:175], v[216:219], v[26:29]
	v_mfma_f32_16x16x32_bf16 v[14:17], v[164:167], v[224:227], v[14:17]
	v_mfma_f32_16x16x32_bf16 v[10:13], v[172:175], v[224:227], v[10:13]
	v_mfma_f32_16x16x32_bf16 v[54:57], v[176:179], v[196:199], v[54:57]
	v_mfma_f32_16x16x32_bf16 v[50:53], v[184:187], v[196:199], v[50:53]
	v_mfma_f32_16x16x32_bf16 v[38:41], v[176:179], v[204:207], v[38:41]
	v_mfma_f32_16x16x32_bf16 v[34:37], v[184:187], v[204:207], v[34:37]
	v_mfma_f32_16x16x32_bf16 v[22:25], v[176:179], v[212:215], v[22:25]
	v_mfma_f32_16x16x32_bf16 v[18:21], v[184:187], v[212:215], v[18:21]
	v_mfma_f32_16x16x32_bf16 v[6:9], v[176:179], v[220:223], v[6:9]
	v_mfma_f32_16x16x32_bf16 v[2:5], v[184:187], v[220:223], v[2:5]
	v_mfma_f32_16x16x32_bf16 v[54:57], v[180:183], v[200:203], v[54:57]
	v_mfma_f32_16x16x32_bf16 v[50:53], v[188:191], v[200:203], v[50:53]
	v_mfma_f32_16x16x32_bf16 v[38:41], v[180:183], v[208:211], v[38:41]
	v_mfma_f32_16x16x32_bf16 v[34:37], v[188:191], v[208:211], v[34:37]
	v_mfma_f32_16x16x32_bf16 v[22:25], v[180:183], v[216:219], v[22:25]
	v_mfma_f32_16x16x32_bf16 v[18:21], v[188:191], v[216:219], v[18:21]
	v_mfma_f32_16x16x32_bf16 v[6:9], v[180:183], v[224:227], v[6:9]
	v_mfma_f32_16x16x32_bf16 v[2:5], v[188:191], v[224:227], v[2:5]
	s_setprio 0
	s_add_i32 s81, 0, 0x18000
	v_add_u32_e32 v163, s81, v158
	s_add_i32 s82, 0, 0x1c000
	ds_read_b128 v[152:155], v163
	ds_read_b128 v[164:167], v163 offset:1024
	ds_read_b128 v[168:171], v163 offset:2048
	ds_read_b128 v[172:175], v163 offset:3072
	v_add_u32_e32 v163, s82, v158
	ds_read_b128 v[176:179], v163
	ds_read_b128 v[180:183], v163 offset:1024
	ds_read_b128 v[184:187], v163 offset:2048
	ds_read_b128 v[188:191], v163 offset:3072
	s_add_u32 s60, s60, 0x20000
	s_addc_u32 s61, s61, 0
	s_mov_b32 m0, s63
	v_lshl_add_u64 v[232:233], s[60:61], 0, v[132:133]
	ds_read_b128 v[196:199], v162 offset:32768
	ds_read_b128 v[200:203], v162 offset:33792
	ds_read_b128 v[204:207], v162 offset:34816
	ds_read_b128 v[208:211], v162 offset:35840
	ds_read_b128 v[212:215], v162 offset:36864
	ds_read_b128 v[216:219], v162 offset:37888
	ds_read_b128 v[220:223], v162 offset:38912
	ds_read_b128 v[224:227], v162 offset:39936
	global_load_lds_dwordx4 v[232:233], off
	v_lshl_add_u64 v[232:233], s[60:61], 0, v[136:137]
	s_mov_b32 m0, s64
	s_nop 0
	global_load_lds_dwordx4 v[232:233], off
	s_waitcnt vmcnt(8)
	s_waitcnt lgkmcnt(0)
	s_barrier
	s_setprio 2
	v_mfma_f32_16x16x32_bf16 v[126:129], v[152:155], v[196:199], v[126:129]
	v_mfma_f32_16x16x32_bf16 v[122:125], v[168:171], v[196:199], v[122:125]
	v_mfma_f32_16x16x32_bf16 v[110:113], v[152:155], v[204:207], v[110:113]
	v_mfma_f32_16x16x32_bf16 v[106:109], v[168:171], v[204:207], v[106:109]
	v_mfma_f32_16x16x32_bf16 v[94:97], v[152:155], v[212:215], v[94:97]
	v_mfma_f32_16x16x32_bf16 v[90:93], v[168:171], v[212:215], v[90:93]
	v_mfma_f32_16x16x32_bf16 v[78:81], v[152:155], v[220:223], v[78:81]
	v_mfma_f32_16x16x32_bf16 v[74:77], v[168:171], v[220:223], v[74:77]
	v_mfma_f32_16x16x32_bf16 v[126:129], v[164:167], v[200:203], v[126:129]
	v_mfma_f32_16x16x32_bf16 v[122:125], v[172:175], v[200:203], v[122:125]
	v_mfma_f32_16x16x32_bf16 v[110:113], v[164:167], v[208:211], v[110:113]
	v_mfma_f32_16x16x32_bf16 v[106:109], v[172:175], v[208:211], v[106:109]
	v_mfma_f32_16x16x32_bf16 v[94:97], v[164:167], v[216:219], v[94:97]
	v_mfma_f32_16x16x32_bf16 v[90:93], v[172:175], v[216:219], v[90:93]
	v_mfma_f32_16x16x32_bf16 v[78:81], v[164:167], v[224:227], v[78:81]
	v_mfma_f32_16x16x32_bf16 v[74:77], v[172:175], v[224:227], v[74:77]
	v_mfma_f32_16x16x32_bf16 v[118:121], v[176:179], v[196:199], v[118:121]
	v_mfma_f32_16x16x32_bf16 v[114:117], v[184:187], v[196:199], v[114:117]
	v_mfma_f32_16x16x32_bf16 v[102:105], v[176:179], v[204:207], v[102:105]
	v_mfma_f32_16x16x32_bf16 v[98:101], v[184:187], v[204:207], v[98:101]
	v_mfma_f32_16x16x32_bf16 v[86:89], v[176:179], v[212:215], v[86:89]
	v_mfma_f32_16x16x32_bf16 v[82:85], v[184:187], v[212:215], v[82:85]
	v_mfma_f32_16x16x32_bf16 v[70:73], v[176:179], v[220:223], v[70:73]
	v_mfma_f32_16x16x32_bf16 v[66:69], v[184:187], v[220:223], v[66:69]
	v_mfma_f32_16x16x32_bf16 v[118:121], v[180:183], v[200:203], v[118:121]
	v_mfma_f32_16x16x32_bf16 v[114:117], v[188:191], v[200:203], v[114:117]
	v_mfma_f32_16x16x32_bf16 v[102:105], v[180:183], v[208:211], v[102:105]
	v_mfma_f32_16x16x32_bf16 v[98:101], v[188:191], v[208:211], v[98:101]
	v_mfma_f32_16x16x32_bf16 v[86:89], v[180:183], v[216:219], v[86:89]
	v_mfma_f32_16x16x32_bf16 v[82:85], v[188:191], v[216:219], v[82:85]
	v_mfma_f32_16x16x32_bf16 v[70:73], v[180:183], v[224:227], v[70:73]
	v_mfma_f32_16x16x32_bf16 v[66:69], v[188:191], v[224:227], v[66:69]
	s_setprio 0
	s_add_i32 s60, s81, s62
	v_lshl_add_u64 v[156:157], v[156:157], 0, s[14:15]
	s_mov_b32 m0, s60
	ds_read_b128 v[196:199], v162 offset:49152
	ds_read_b128 v[200:203], v162 offset:50176
	ds_read_b128 v[204:207], v162 offset:51200
	ds_read_b128 v[208:211], v162 offset:52224
	ds_read_b128 v[212:215], v162 offset:53248
	ds_read_b128 v[216:219], v162 offset:54272
	ds_read_b128 v[220:223], v162 offset:55296
	ds_read_b128 v[224:227], v162 offset:56320
	global_load_lds_dwordx4 v[156:157], off
	s_add_i32 m0, s60, 0x2000
	s_add_u32 s48, s48, 0x20080
	v_lshl_add_u64 v[156:157], v[192:193], 0, s[14:15]
	s_addc_u32 s49, s49, 0
	s_add_i32 s60, s82, s62
	global_load_lds_dwordx4 v[156:157], off
	v_lshl_add_u64 v[156:157], s[48:49], 0, v[134:135]
	s_mov_b32 m0, s60
	s_nop 0
	global_load_lds_dwordx4 v[156:157], off
	v_lshl_add_u64 v[156:157], s[48:49], 0, v[138:139]
	s_add_i32 m0, s60, 0x2000
	s_nop 0
	global_load_lds_dwordx4 v[156:157], off
	v_lshl_add_u64 v[156:157], v[228:229], 0, s[14:15]
	s_mov_b32 m0, s68
	s_nop 0
	global_load_lds_dwordx4 v[156:157], off
	v_lshl_add_u64 v[156:157], v[230:231], 0, s[14:15]
	s_mov_b32 m0, s69
	s_nop 0
	global_load_lds_dwordx4 v[156:157], off
	s_waitcnt vmcnt(8)
	s_waitcnt lgkmcnt(0)
	s_barrier
	s_setprio 2
	v_mfma_f32_16x16x32_bf16 v[62:65], v[152:155], v[196:199], v[62:65]
	v_mfma_f32_16x16x32_bf16 v[58:61], v[168:171], v[196:199], v[58:61]
	v_mfma_f32_16x16x32_bf16 v[46:49], v[152:155], v[204:207], v[46:49]
	v_mfma_f32_16x16x32_bf16 v[42:45], v[168:171], v[204:207], v[42:45]
	v_mfma_f32_16x16x32_bf16 v[30:33], v[152:155], v[212:215], v[30:33]
	v_mfma_f32_16x16x32_bf16 v[26:29], v[168:171], v[212:215], v[26:29]
	v_mfma_f32_16x16x32_bf16 v[14:17], v[152:155], v[220:223], v[14:17]
	v_mfma_f32_16x16x32_bf16 v[10:13], v[168:171], v[220:223], v[10:13]
	v_mfma_f32_16x16x32_bf16 v[62:65], v[164:167], v[200:203], v[62:65]
	v_mfma_f32_16x16x32_bf16 v[58:61], v[172:175], v[200:203], v[58:61]
	v_mfma_f32_16x16x32_bf16 v[46:49], v[164:167], v[208:211], v[46:49]
	v_mfma_f32_16x16x32_bf16 v[42:45], v[172:175], v[208:211], v[42:45]
	v_mfma_f32_16x16x32_bf16 v[30:33], v[164:167], v[216:219], v[30:33]
	v_mfma_f32_16x16x32_bf16 v[26:29], v[172:175], v[216:219], v[26:29]
	v_mfma_f32_16x16x32_bf16 v[14:17], v[164:167], v[224:227], v[14:17]
	v_mfma_f32_16x16x32_bf16 v[10:13], v[172:175], v[224:227], v[10:13]
	v_mfma_f32_16x16x32_bf16 v[54:57], v[176:179], v[196:199], v[54:57]
	v_mfma_f32_16x16x32_bf16 v[50:53], v[184:187], v[196:199], v[50:53]
	v_mfma_f32_16x16x32_bf16 v[38:41], v[176:179], v[204:207], v[38:41]
	v_mfma_f32_16x16x32_bf16 v[34:37], v[184:187], v[204:207], v[34:37]
	v_mfma_f32_16x16x32_bf16 v[22:25], v[176:179], v[212:215], v[22:25]
	v_mfma_f32_16x16x32_bf16 v[18:21], v[184:187], v[212:215], v[18:21]
	v_mfma_f32_16x16x32_bf16 v[6:9], v[176:179], v[220:223], v[6:9]
	v_mfma_f32_16x16x32_bf16 v[2:5], v[184:187], v[220:223], v[2:5]
	v_mfma_f32_16x16x32_bf16 v[54:57], v[180:183], v[200:203], v[54:57]
	v_mfma_f32_16x16x32_bf16 v[50:53], v[188:191], v[200:203], v[50:53]
	v_mfma_f32_16x16x32_bf16 v[38:41], v[180:183], v[208:211], v[38:41]
	v_mfma_f32_16x16x32_bf16 v[34:37], v[188:191], v[208:211], v[34:37]
	v_mfma_f32_16x16x32_bf16 v[22:25], v[180:183], v[216:219], v[22:25]
	v_mfma_f32_16x16x32_bf16 v[18:21], v[188:191], v[216:219], v[18:21]
	v_mfma_f32_16x16x32_bf16 v[6:9], v[180:183], v[224:227], v[6:9]
	v_mfma_f32_16x16x32_bf16 v[2:5], v[188:191], v[224:227], v[2:5]
	s_setprio 0
	s_add_u32 s58, s58, 0x100
	s_addc_u32 s59, s59, 0
	s_add_u32 s47, s47, 0x100
	s_addc_u32 s51, s51, 0
	s_cmp_ge_i32 s80, s79
	s_mov_b32 s48, s80
	s_cbranch_scc0 .Lkt_T_15
	s_nop 7

.LBB0_3990:
	v_lshlrev_b64 v[152:153], 12, v[156:157]
	v_lshl_add_u64 v[152:153], v[152:153], 0, v[154:155]
	v_lshlrev_b64 v[152:153], 1, v[152:153]
	v_lshl_add_u64 v[168:169], s[12:13], 0, v[152:153]
	global_load_dwordx4 v[164:167], v[168:169], off
	s_nop 0
	global_load_dwordx4 v[168:171], v[168:169], off offset:256
	v_or_b32_e32 v172, 16, v156
	v_ashrrev_i32_e32 v173, 31, v172
	v_lshlrev_b64 v[172:173], 12, v[172:173]
	v_lshl_add_u64 v[172:173], v[172:173], 0, v[154:155]
	v_lshl_add_u64 v[174:175], s[10:11], 0, v[152:153]
	v_lshlrev_b64 v[172:173], 1, v[172:173]
	v_lshl_add_u64 v[176:177], s[12:13], 0, v[172:173]
	s_waitcnt vmcnt(0)
	v_lshlrev_b32_e32 v178, 16, v164
	v_and_b32_e32 v179, 0xffff0000, v164
	v_lshlrev_b32_e32 v164, 16, v165
	v_and_b32_e32 v165, 0xffff0000, v165
	v_lshlrev_b32_e32 v180, 16, v166
	v_and_b32_e32 v181, 0xffff0000, v166
	v_lshlrev_b32_e32 v166, 16, v167
	v_and_b32_e32 v167, 0xffff0000, v167
	v_lshlrev_b32_e32 v182, 16, v168
	v_and_b32_e32 v183, 0xffff0000, v168
	v_lshlrev_b32_e32 v168, 16, v169
	v_and_b32_e32 v169, 0xffff0000, v169
	v_lshlrev_b32_e32 v184, 16, v170
	v_and_b32_e32 v185, 0xffff0000, v170
	v_lshlrev_b32_e32 v170, 16, v171
	v_and_b32_e32 v171, 0xffff0000, v171
	v_pk_fma_f32 v[126:127], v[178:179], s[26:27], v[126:127] op_sel_hi:[1,0,1]
	v_pk_fma_f32 v[128:129], v[164:165], s[26:27], v[128:129] op_sel_hi:[1,0,1]
	v_pk_fma_f32 v[122:123], v[180:181], s[26:27], v[122:123] op_sel_hi:[1,0,1]
	v_pk_fma_f32 v[124:125], v[166:167], s[26:27], v[124:125] op_sel_hi:[1,0,1]
	v_pk_fma_f32 v[118:119], v[182:183], s[26:27], v[118:119] op_sel_hi:[1,0,1]
	v_pk_fma_f32 v[120:121], v[168:169], s[26:27], v[120:121] op_sel_hi:[1,0,1]
	v_pk_fma_f32 v[164:165], v[184:185], s[26:27], v[114:115] op_sel_hi:[1,0,1]
	v_pk_fma_f32 v[166:167], v[170:171], s[26:27], v[116:117] op_sel_hi:[1,0,1]
	v_cvt_pk_bf16_f32 v114, v126, v127
	v_cvt_pk_bf16_f32 v115, v128, v129
	v_cvt_pk_bf16_f32 v116, v122, v123
	v_cvt_pk_bf16_f32 v117, v124, v125
	v_cvt_pk_bf16_f32 v118, v118, v119
	v_cvt_pk_bf16_f32 v119, v120, v121
	v_cvt_pk_bf16_f32 v120, v164, v165
	v_cvt_pk_bf16_f32 v121, v166, v167
	global_store_dwordx4 v[174:175], v[114:117], off
	global_store_dwordx4 v[174:175], v[118:121], off offset:256
	global_load_dwordx4 v[114:117], v[176:177], off
	s_nop 0
	global_load_dwordx4 v[118:121], v[176:177], off offset:256
	v_or_b32_e32 v122, 32, v156
	v_ashrrev_i32_e32 v123, 31, v122
	v_lshlrev_b64 v[122:123], 12, v[122:123]
	v_lshl_add_u64 v[122:123], v[122:123], 0, v[154:155]
	v_lshlrev_b64 v[122:123], 1, v[122:123]
	v_lshl_add_u64 v[124:125], s[10:11], 0, v[172:173]
	v_lshl_add_u64 v[126:127], s[12:13], 0, v[122:123]
	s_waitcnt vmcnt(1)
	v_lshlrev_b32_e32 v128, 16, v114
	v_and_b32_e32 v129, 0xffff0000, v114
	v_lshlrev_b32_e32 v114, 16, v115
	v_and_b32_e32 v115, 0xffff0000, v115
	v_lshlrev_b32_e32 v164, 16, v116
	v_and_b32_e32 v165, 0xffff0000, v116
	v_lshlrev_b32_e32 v116, 16, v117
	v_and_b32_e32 v117, 0xffff0000, v117
	s_waitcnt vmcnt(0)
	v_lshlrev_b32_e32 v166, 16, v118
	v_and_b32_e32 v167, 0xffff0000, v118
	v_lshlrev_b32_e32 v118, 16, v119
	v_and_b32_e32 v119, 0xffff0000, v119
	v_lshlrev_b32_e32 v168, 16, v120
	v_and_b32_e32 v169, 0xffff0000, v120
	v_lshlrev_b32_e32 v120, 16, v121
	v_and_b32_e32 v121, 0xffff0000, v121
	v_pk_fma_f32 v[110:111], v[128:129], s[26:27], v[110:111] op_sel_hi:[1,0,1]
	v_pk_fma_f32 v[112:113], v[114:115], s[26:27], v[112:113] op_sel_hi:[1,0,1]
	v_pk_fma_f32 v[106:107], v[164:165], s[26:27], v[106:107] op_sel_hi:[1,0,1]
	v_pk_fma_f32 v[108:109], v[116:117], s[26:27], v[108:109] op_sel_hi:[1,0,1]
	v_pk_fma_f32 v[102:103], v[166:167], s[26:27], v[102:103] op_sel_hi:[1,0,1]
	v_pk_fma_f32 v[104:105], v[118:119], s[26:27], v[104:105] op_sel_hi:[1,0,1]
	v_pk_fma_f32 v[114:115], v[168:169], s[26:27], v[98:99] op_sel_hi:[1,0,1]
	v_pk_fma_f32 v[116:117], v[120:121], s[26:27], v[100:101] op_sel_hi:[1,0,1]
	v_cvt_pk_bf16_f32 v98, v110, v111
	v_cvt_pk_bf16_f32 v99, v112, v113
	v_cvt_pk_bf16_f32 v100, v106, v107
	v_cvt_pk_bf16_f32 v101, v108, v109
	v_cvt_pk_bf16_f32 v102, v102, v103
	v_cvt_pk_bf16_f32 v103, v104, v105
	v_cvt_pk_bf16_f32 v104, v114, v115
	v_cvt_pk_bf16_f32 v105, v116, v117
	global_store_dwordx4 v[124:125], v[98:101], off
	global_store_dwordx4 v[124:125], v[102:105], off offset:256
	global_load_dwordx4 v[98:101], v[126:127], off
	s_nop 0
	global_load_dwordx4 v[102:105], v[126:127], off offset:256
	v_or_b32_e32 v106, 48, v156
	v_ashrrev_i32_e32 v107, 31, v106
	v_lshlrev_b64 v[106:107], 12, v[106:107]
	v_lshl_add_u64 v[106:107], v[106:107], 0, v[154:155]
	v_lshlrev_b64 v[106:107], 1, v[106:107]
	v_lshl_add_u64 v[108:109], s[10:11], 0, v[122:123]
	v_lshl_add_u64 v[110:111], s[12:13], 0, v[106:107]
	s_waitcnt vmcnt(1)
	v_lshlrev_b32_e32 v112, 16, v98
	v_and_b32_e32 v113, 0xffff0000, v98
	v_lshlrev_b32_e32 v98, 16, v99
	v_and_b32_e32 v99, 0xffff0000, v99
	v_lshlrev_b32_e32 v114, 16, v100
	v_and_b32_e32 v115, 0xffff0000, v100
	v_lshlrev_b32_e32 v100, 16, v101
	v_and_b32_e32 v101, 0xffff0000, v101
	s_waitcnt vmcnt(0)
	v_lshlrev_b32_e32 v116, 16, v102
	v_and_b32_e32 v117, 0xffff0000, v102
	v_lshlrev_b32_e32 v102, 16, v103
	v_and_b32_e32 v103, 0xffff0000, v103
	v_lshlrev_b32_e32 v118, 16, v104
	v_and_b32_e32 v119, 0xffff0000, v104
	v_lshlrev_b32_e32 v104, 16, v105
	v_and_b32_e32 v105, 0xffff0000, v105
	v_pk_fma_f32 v[94:95], v[112:113], s[26:27], v[94:95] op_sel_hi:[1,0,1]
	v_pk_fma_f32 v[96:97], v[98:99], s[26:27], v[96:97] op_sel_hi:[1,0,1]
	v_pk_fma_f32 v[90:91], v[114:115], s[26:27], v[90:91] op_sel_hi:[1,0,1]
	v_pk_fma_f32 v[92:93], v[100:101], s[26:27], v[92:93] op_sel_hi:[1,0,1]
	v_pk_fma_f32 v[86:87], v[116:117], s[26:27], v[86:87] op_sel_hi:[1,0,1]
	v_pk_fma_f32 v[88:89], v[102:103], s[26:27], v[88:89] op_sel_hi:[1,0,1]
	v_pk_fma_f32 v[98:99], v[118:119], s[26:27], v[82:83] op_sel_hi:[1,0,1]
	v_pk_fma_f32 v[100:101], v[104:105], s[26:27], v[84:85] op_sel_hi:[1,0,1]
	v_cvt_pk_bf16_f32 v82, v94, v95
	v_cvt_pk_bf16_f32 v83, v96, v97
	v_cvt_pk_bf16_f32 v84, v90, v91
	v_cvt_pk_bf16_f32 v85, v92, v93
	v_cvt_pk_bf16_f32 v86, v86, v87
	v_cvt_pk_bf16_f32 v87, v88, v89
	v_cvt_pk_bf16_f32 v88, v98, v99
	v_cvt_pk_bf16_f32 v89, v100, v101
	global_store_dwordx4 v[108:109], v[82:85], off
	global_store_dwordx4 v[108:109], v[86:89], off offset:256
	global_load_dwordx4 v[82:85], v[110:111], off
	s_nop 0
	global_load_dwordx4 v[86:89], v[110:111], off offset:256
	v_lshl_add_u64 v[90:91], v[152:153], 0, s[28:29]
	v_lshl_add_u64 v[94:95], s[10:11], 0, v[106:107]
	v_lshl_add_u64 v[92:93], s[12:13], 0, v[90:91]
	s_waitcnt vmcnt(1)
	v_lshlrev_b32_e32 v96, 16, v82
	v_and_b32_e32 v97, 0xffff0000, v82
	v_lshlrev_b32_e32 v82, 16, v83
	v_and_b32_e32 v83, 0xffff0000, v83
	v_lshlrev_b32_e32 v98, 16, v84
	v_and_b32_e32 v99, 0xffff0000, v84
	v_lshlrev_b32_e32 v84, 16, v85
	v_and_b32_e32 v85, 0xffff0000, v85
	s_waitcnt vmcnt(0)
	v_lshlrev_b32_e32 v100, 16, v86
	v_and_b32_e32 v101, 0xffff0000, v86
	v_lshlrev_b32_e32 v86, 16, v87
	v_and_b32_e32 v87, 0xffff0000, v87
	v_lshlrev_b32_e32 v102, 16, v88
	v_and_b32_e32 v103, 0xffff0000, v88
	v_lshlrev_b32_e32 v88, 16, v89
	v_and_b32_e32 v89, 0xffff0000, v89
	v_pk_fma_f32 v[78:79], v[96:97], s[26:27], v[78:79] op_sel_hi:[1,0,1]
	v_pk_fma_f32 v[80:81], v[82:83], s[26:27], v[80:81] op_sel_hi:[1,0,1]
	v_pk_fma_f32 v[74:75], v[98:99], s[26:27], v[74:75] op_sel_hi:[1,0,1]
	v_pk_fma_f32 v[76:77], v[84:85], s[26:27], v[76:77] op_sel_hi:[1,0,1]
	v_pk_fma_f32 v[70:71], v[100:101], s[26:27], v[70:71] op_sel_hi:[1,0,1]
	v_pk_fma_f32 v[72:73], v[86:87], s[26:27], v[72:73] op_sel_hi:[1,0,1]
	v_pk_fma_f32 v[82:83], v[102:103], s[26:27], v[66:67] op_sel_hi:[1,0,1]
	v_pk_fma_f32 v[84:85], v[88:89], s[26:27], v[68:69] op_sel_hi:[1,0,1]
	v_cvt_pk_bf16_f32 v66, v78, v79
	v_cvt_pk_bf16_f32 v67, v80, v81
	v_cvt_pk_bf16_f32 v68, v74, v75
	v_cvt_pk_bf16_f32 v69, v76, v77
	v_cvt_pk_bf16_f32 v70, v70, v71
	v_cvt_pk_bf16_f32 v71, v72, v73
	v_cvt_pk_bf16_f32 v72, v82, v83
	v_cvt_pk_bf16_f32 v73, v84, v85
	global_store_dwordx4 v[94:95], v[66:69], off
	global_store_dwordx4 v[94:95], v[70:73], off offset:256
	global_load_dwordx4 v[66:69], v[92:93], off
	s_nop 0
	global_load_dwordx4 v[70:73], v[92:93], off offset:256
	v_lshl_add_u64 v[74:75], v[152:153], 0, s[30:31]
	v_lshl_add_u64 v[76:77], s[10:11], 0, v[90:91]
	v_lshl_add_u64 v[78:79], s[12:13], 0, v[74:75]
	s_waitcnt vmcnt(1)
	v_lshlrev_b32_e32 v80, 16, v66
	v_and_b32_e32 v81, 0xffff0000, v66
	v_lshlrev_b32_e32 v66, 16, v67
	v_and_b32_e32 v67, 0xffff0000, v67
	v_lshlrev_b32_e32 v82, 16, v68
	v_and_b32_e32 v83, 0xffff0000, v68
	v_lshlrev_b32_e32 v68, 16, v69
	v_and_b32_e32 v69, 0xffff0000, v69
	s_waitcnt vmcnt(0)
	v_lshlrev_b32_e32 v84, 16, v70
	v_and_b32_e32 v85, 0xffff0000, v70
	v_lshlrev_b32_e32 v70, 16, v71
	v_and_b32_e32 v71, 0xffff0000, v71
	v_lshlrev_b32_e32 v86, 16, v72
	v_and_b32_e32 v87, 0xffff0000, v72
	v_lshlrev_b32_e32 v72, 16, v73
	v_and_b32_e32 v73, 0xffff0000, v73
	v_pk_fma_f32 v[62:63], v[80:81], s[26:27], v[62:63] op_sel_hi:[1,0,1]
	v_pk_fma_f32 v[64:65], v[66:67], s[26:27], v[64:65] op_sel_hi:[1,0,1]
	v_pk_fma_f32 v[58:59], v[82:83], s[26:27], v[58:59] op_sel_hi:[1,0,1]
	v_pk_fma_f32 v[60:61], v[68:69], s[26:27], v[60:61] op_sel_hi:[1,0,1]
	v_pk_fma_f32 v[54:55], v[84:85], s[26:27], v[54:55] op_sel_hi:[1,0,1]
	v_pk_fma_f32 v[56:57], v[70:71], s[26:27], v[56:57] op_sel_hi:[1,0,1]
	v_pk_fma_f32 v[66:67], v[86:87], s[26:27], v[50:51] op_sel_hi:[1,0,1]
	v_pk_fma_f32 v[68:69], v[72:73], s[26:27], v[52:53] op_sel_hi:[1,0,1]
	v_cvt_pk_bf16_f32 v50, v62, v63
	v_cvt_pk_bf16_f32 v51, v64, v65
	v_cvt_pk_bf16_f32 v52, v58, v59
	v_cvt_pk_bf16_f32 v53, v60, v61
	v_cvt_pk_bf16_f32 v54, v54, v55
	v_cvt_pk_bf16_f32 v55, v56, v57
	v_cvt_pk_bf16_f32 v56, v66, v67
	v_cvt_pk_bf16_f32 v57, v68, v69
	global_store_dwordx4 v[76:77], v[50:53], off
	global_store_dwordx4 v[76:77], v[54:57], off offset:256
	global_load_dwordx4 v[50:53], v[78:79], off
	s_nop 0
	global_load_dwordx4 v[54:57], v[78:79], off offset:256
	v_lshl_add_u64 v[58:59], v[152:153], 0, s[34:35]
	v_lshl_add_u64 v[60:61], s[10:11], 0, v[74:75]
	v_lshl_add_u64 v[62:63], s[12:13], 0, v[58:59]
	s_waitcnt vmcnt(1)
	v_lshlrev_b32_e32 v64, 16, v50
	v_and_b32_e32 v65, 0xffff0000, v50
	v_lshlrev_b32_e32 v50, 16, v51
	v_and_b32_e32 v51, 0xffff0000, v51
	v_lshlrev_b32_e32 v66, 16, v52
	v_and_b32_e32 v67, 0xffff0000, v52
	v_lshlrev_b32_e32 v52, 16, v53
	v_and_b32_e32 v53, 0xffff0000, v53
	s_waitcnt vmcnt(0)
	v_lshlrev_b32_e32 v68, 16, v54
	v_and_b32_e32 v69, 0xffff0000, v54
	v_lshlrev_b32_e32 v54, 16, v55
	v_and_b32_e32 v55, 0xffff0000, v55
	v_lshlrev_b32_e32 v70, 16, v56
	v_and_b32_e32 v71, 0xffff0000, v56
	v_lshlrev_b32_e32 v56, 16, v57
	v_and_b32_e32 v57, 0xffff0000, v57
	v_pk_fma_f32 v[46:47], v[64:65], s[26:27], v[46:47] op_sel_hi:[1,0,1]
	v_pk_fma_f32 v[48:49], v[50:51], s[26:27], v[48:49] op_sel_hi:[1,0,1]
	v_pk_fma_f32 v[42:43], v[66:67], s[26:27], v[42:43] op_sel_hi:[1,0,1]
	v_pk_fma_f32 v[44:45], v[52:53], s[26:27], v[44:45] op_sel_hi:[1,0,1]
	v_pk_fma_f32 v[38:39], v[68:69], s[26:27], v[38:39] op_sel_hi:[1,0,1]
	v_pk_fma_f32 v[40:41], v[54:55], s[26:27], v[40:41] op_sel_hi:[1,0,1]
	v_pk_fma_f32 v[50:51], v[70:71], s[26:27], v[34:35] op_sel_hi:[1,0,1]
	v_pk_fma_f32 v[52:53], v[56:57], s[26:27], v[36:37] op_sel_hi:[1,0,1]
	v_cvt_pk_bf16_f32 v34, v46, v47
	v_cvt_pk_bf16_f32 v35, v48, v49
	v_cvt_pk_bf16_f32 v36, v42, v43
	v_cvt_pk_bf16_f32 v37, v44, v45
	v_cvt_pk_bf16_f32 v38, v38, v39
	v_cvt_pk_bf16_f32 v39, v40, v41
	v_cvt_pk_bf16_f32 v40, v50, v51
	v_cvt_pk_bf16_f32 v41, v52, v53
	global_store_dwordx4 v[60:61], v[34:37], off
	global_store_dwordx4 v[60:61], v[38:41], off offset:256
	global_load_dwordx4 v[34:37], v[62:63], off
	s_nop 0
	global_load_dwordx4 v[38:41], v[62:63], off offset:256
	v_lshl_add_u64 v[42:43], v[152:153], 0, s[40:41]
	v_lshl_add_u64 v[44:45], s[10:11], 0, v[58:59]
	v_lshl_add_u64 v[46:47], s[12:13], 0, v[42:43]
	s_waitcnt vmcnt(1)
	v_lshlrev_b32_e32 v48, 16, v34
	v_and_b32_e32 v49, 0xffff0000, v34
	v_lshlrev_b32_e32 v34, 16, v35
	v_and_b32_e32 v35, 0xffff0000, v35
	v_lshlrev_b32_e32 v50, 16, v36
	v_and_b32_e32 v51, 0xffff0000, v36
	v_lshlrev_b32_e32 v36, 16, v37
	v_and_b32_e32 v37, 0xffff0000, v37
	s_waitcnt vmcnt(0)
	v_lshlrev_b32_e32 v52, 16, v38
	v_and_b32_e32 v53, 0xffff0000, v38
	v_lshlrev_b32_e32 v38, 16, v39
	v_and_b32_e32 v39, 0xffff0000, v39
	v_lshlrev_b32_e32 v54, 16, v40
	v_and_b32_e32 v55, 0xffff0000, v40
	v_lshlrev_b32_e32 v40, 16, v41
	v_and_b32_e32 v41, 0xffff0000, v41
	v_pk_fma_f32 v[30:31], v[48:49], s[26:27], v[30:31] op_sel_hi:[1,0,1]
	v_pk_fma_f32 v[32:33], v[34:35], s[26:27], v[32:33] op_sel_hi:[1,0,1]
	v_pk_fma_f32 v[26:27], v[50:51], s[26:27], v[26:27] op_sel_hi:[1,0,1]
	v_pk_fma_f32 v[28:29], v[36:37], s[26:27], v[28:29] op_sel_hi:[1,0,1]
	v_pk_fma_f32 v[22:23], v[52:53], s[26:27], v[22:23] op_sel_hi:[1,0,1]
	v_pk_fma_f32 v[24:25], v[38:39], s[26:27], v[24:25] op_sel_hi:[1,0,1]
	v_pk_fma_f32 v[34:35], v[54:55], s[26:27], v[18:19] op_sel_hi:[1,0,1]
	v_pk_fma_f32 v[36:37], v[40:41], s[26:27], v[20:21] op_sel_hi:[1,0,1]
	v_cvt_pk_bf16_f32 v18, v30, v31
	v_cvt_pk_bf16_f32 v19, v32, v33
	v_cvt_pk_bf16_f32 v20, v26, v27
	v_cvt_pk_bf16_f32 v21, v28, v29
	v_cvt_pk_bf16_f32 v22, v22, v23
	v_cvt_pk_bf16_f32 v23, v24, v25
	v_cvt_pk_bf16_f32 v24, v34, v35
	v_cvt_pk_bf16_f32 v25, v36, v37
	global_store_dwordx4 v[44:45], v[18:21], off
	global_store_dwordx4 v[44:45], v[22:25], off offset:256
	global_load_dwordx4 v[18:21], v[46:47], off
	s_nop 0
	global_load_dwordx4 v[22:25], v[46:47], off offset:256
	v_lshl_add_u64 v[26:27], s[10:11], 0, v[42:43]
	s_waitcnt vmcnt(1)
	v_lshlrev_b32_e32 v28, 16, v18
	v_and_b32_e32 v29, 0xffff0000, v18
	v_lshlrev_b32_e32 v18, 16, v19
	v_and_b32_e32 v19, 0xffff0000, v19
	v_lshlrev_b32_e32 v30, 16, v20
	v_and_b32_e32 v31, 0xffff0000, v20
	v_lshlrev_b32_e32 v20, 16, v21
	v_and_b32_e32 v21, 0xffff0000, v21
	s_waitcnt vmcnt(0)
	v_lshlrev_b32_e32 v32, 16, v22
	v_and_b32_e32 v33, 0xffff0000, v22
	v_lshlrev_b32_e32 v22, 16, v23
	v_and_b32_e32 v23, 0xffff0000, v23
	v_lshlrev_b32_e32 v34, 16, v24
	v_and_b32_e32 v35, 0xffff0000, v24
	v_lshlrev_b32_e32 v24, 16, v25
	v_and_b32_e32 v25, 0xffff0000, v25
	v_pk_fma_f32 v[14:15], v[28:29], s[26:27], v[14:15] op_sel_hi:[1,0,1]
	v_pk_fma_f32 v[16:17], v[18:19], s[26:27], v[16:17] op_sel_hi:[1,0,1]
	v_pk_fma_f32 v[10:11], v[30:31], s[26:27], v[10:11] op_sel_hi:[1,0,1]
	v_pk_fma_f32 v[12:13], v[20:21], s[26:27], v[12:13] op_sel_hi:[1,0,1]
	v_pk_fma_f32 v[6:7], v[32:33], s[26:27], v[6:7] op_sel_hi:[1,0,1]
	v_pk_fma_f32 v[8:9], v[22:23], s[26:27], v[8:9] op_sel_hi:[1,0,1]
	v_pk_fma_f32 v[18:19], v[34:35], s[26:27], v[2:3] op_sel_hi:[1,0,1]
	v_pk_fma_f32 v[20:21], v[24:25], s[26:27], v[4:5] op_sel_hi:[1,0,1]
	v_cvt_pk_bf16_f32 v2, v14, v15
	v_cvt_pk_bf16_f32 v3, v16, v17
	v_cvt_pk_bf16_f32 v4, v10, v11
	v_cvt_pk_bf16_f32 v5, v12, v13
	v_cvt_pk_bf16_f32 v6, v6, v7
	v_cvt_pk_bf16_f32 v7, v8, v9
	v_cvt_pk_bf16_f32 v8, v18, v19
	v_cvt_pk_bf16_f32 v9, v20, v21
	global_store_dwordx4 v[26:27], v[2:5], off
	global_store_dwordx4 v[26:27], v[6:9], off offset:256
	s_and_b64 vcc, exec, s[0:1]
	s_mov_b64 s[0:1], -1
	s_cbranch_vccnz .LBB0_3968
.LBB0_3991:
	s_andn2_b64 vcc, exec, s[8:9]
	s_cbranch_vccnz .LBB0_3967
	s_branch .LBB0_3967
.LBB0_3993:
	s_waitcnt vmcnt(0)
	s_barrier

.LBB0_4122:
	s_add_u32 s8, s38, 0x43e00000
	s_addc_u32 s9, s39, 0
	s_add_u32 s53, s38, 0x56600000
	s_addc_u32 s54, s39, 0
	s_lshl_b32 s10, s10, 5
	s_and_b32 s20, s10, 0x60
	s_mov_b64 s[10:11], 0x80
	s_add_i32 m0, s35, 0x18000
	v_lshl_add_u64 v[8:9], v[8:9], 0, s[10:11]
	s_lshl_b32 s16, s13, 13
	s_lshl_b32 s17, s20, 7
	s_waitcnt vmcnt(2)
	s_barrier
	global_load_lds_dwordx4 v[8:9], off
	v_lshl_add_u64 v[6:7], v[6:7], 0, s[10:11]
	s_add_i32 m0, s35, 0x1a000
	s_add_i32 s55, s35, 0x8000
	s_add_i32 s56, s35, 0xa000
	global_load_lds_dwordx4 v[6:7], off
	v_lshl_add_u64 v[2:3], v[2:3], 0, s[10:11]
	s_mov_b32 m0, s55
	s_add_u32 s14, s42, 0x100080
	global_load_lds_dwordx4 v[2:3], off
	v_lshl_add_u64 v[2:3], v[4:5], 0, s[10:11]
	s_mov_b32 m0, s56
	s_addc_u32 s15, s43, 0
	global_load_lds_dwordx4 v[2:3], off
	s_add_i32 m0, s35, 0x1c000
	v_lshl_add_u64 v[2:3], s[14:15], 0, v[134:135]
	global_load_lds_dwordx4 v[2:3], off
	v_lshl_add_u64 v[2:3], s[14:15], 0, v[138:139]
	s_add_i32 m0, s35, 0x1e000
	v_lshlrev_b32_e32 v4, 2, v0
	global_load_lds_dwordx4 v[2:3], off
	v_and_b32_e32 v2, 15, v0
	v_lshl_or_b32 v131, s13, 6, v2
	v_lshlrev_b32_e32 v3, 1, v13
	v_lshlrev_b32_e32 v5, 6, v0
	s_movk_i32 s13, 0x3c0
	v_lshl_or_b32 v2, v2, 6, v3
	v_and_b32_e32 v4, 32, v4
	v_and_or_b32 v3, v5, s13, v3
	v_bitop3_b32 v2, v2, s16, v4 bitop3:0xde
	v_bitop3_b32 v160, s17, v3, v4 bitop3:0xf6
	s_mov_b32 s16, 0x15800
	v_or_b32_e32 v3, 16, v131
	v_mad_u64_u32 v[142:143], s[14:15], v3, s16, 0
	v_or_b32_e32 v3, 32, v131
	v_mad_u64_u32 v[144:145], s[14:15], v3, s16, 0
	v_or_b32_e32 v3, 48, v131
	s_cmpk_lt_u32 s12, 0x100
	v_mad_u64_u32 v[146:147], s[14:15], v3, s16, 0
	v_lshlrev_b32_e32 v3, 10, v0
	s_cselect_b64 s[12:13], -1, 0
	s_ashr_i32 s57, s44, 31
	s_ashr_i32 s58, s2, 31
	v_and_b32_e32 v3, 0x60000, v3
	v_lshlrev_b32_e32 v4, 13, v12
	v_mad_u64_u32 v[140:141], s[14:15], v131, s16, 0
	s_cmpk_gt_i32 s2, 0xbf
	v_or3_b32 v3, v10, v3, v4
	s_cselect_b64 s[14:15], -1, 0
	s_add_i32 s59, s2, 0xfffffcc0
	v_add_u32_e32 v148, v3, v11
	v_lshlrev_b32_e32 v3, 6, v14
	s_waitcnt vmcnt(6)
	s_cmpk_lt_i32 s2, 0x58
	v_and_b32_e32 v3, 0xe0000, v3
	s_cselect_b64 s[16:17], -1, 0
	v_or3_b32 v3, v10, v3, v4
	s_add_i32 s62, 0, 0x10000
	s_add_i32 s63, 0, 0x14000
	s_add_i32 s60, s2, 0x100
	s_add_i32 s18, s2, 0xa00
	v_or_b32_e32 v161, s20, v13
	v_mov_b32_e32 v149, v135
	v_add_u32_e32 v150, v3, v11
	v_mov_b32_e32 v151, v135
	s_movk_i32 s61, 0x159
	v_add_u32_e32 v162, s62, v160
	v_add_u32_e32 v163, s63, v160
	v_add_u32_e32 v164, 0, v2
	s_movk_i32 s64, 0x5600
	v_mov_b64_e32 v[152:153], 0xac0
	v_mov_b64_e32 v[154:155], 0xabf
	s_branch .LBB0_4125

.Lkt_L_16:
	ds_read_b128 v[156:159], v162
	ds_read_b128 v[166:169], v162 offset:1024
	ds_read_b128 v[170:173], v162 offset:2048
	ds_read_b128 v[174:177], v162 offset:3072
	ds_read_b128 v[178:181], v163
	ds_read_b128 v[182:185], v163 offset:1024
	ds_read_b128 v[186:189], v163 offset:2048
	ds_read_b128 v[190:193], v163 offset:3072
	s_add_i32 s72, s42, 2
	s_add_u32 s43, s40, 0xfff00080
	s_addc_u32 s46, s41, -1
	s_cmp_eq_u32 s69, s42
	s_cselect_b32 s42, s25, s70
	s_cselect_b32 s47, s5, s46
	s_cselect_b32 s46, s23, s43
	s_cselect_b32 s43, s21, s71
	v_lshl_add_u64 v[228:229], s[40:41], 0, v[148:149]
	s_add_i32 m0, s35, 0xc000
	ds_read_b128 v[196:199], v164
	ds_read_b128 v[200:203], v164 offset:1024
	ds_read_b128 v[204:207], v164 offset:2048
	ds_read_b128 v[208:211], v164 offset:3072
	ds_read_b128 v[212:215], v164 offset:4096
	ds_read_b128 v[216:219], v164 offset:5120
	ds_read_b128 v[220:223], v164 offset:6144
	ds_read_b128 v[224:227], v164 offset:7168
	global_load_lds_dwordx4 v[228:229], off
	v_lshl_add_u64 v[228:229], s[40:41], 0, v[150:151]
	s_add_i32 m0, s35, 0xe000
	s_nop 0
	global_load_lds_dwordx4 v[228:229], off
	s_waitcnt lgkmcnt(0)
	s_setprio 1
	v_mfma_f32_16x16x32_bf16 v[78:81], v[156:159], v[196:199], v[78:81]
	v_mfma_f32_16x16x32_bf16 v[74:77], v[170:173], v[196:199], v[74:77]
	v_mfma_f32_16x16x32_bf16 v[70:73], v[156:159], v[204:207], v[70:73]
	v_mfma_f32_16x16x32_bf16 v[62:65], v[170:173], v[204:207], v[62:65]
	v_mfma_f32_16x16x32_bf16 v[58:61], v[156:159], v[212:215], v[58:61]
	v_mfma_f32_16x16x32_bf16 v[54:57], v[170:173], v[212:215], v[54:57]
	v_mfma_f32_16x16x32_bf16 v[46:49], v[156:159], v[220:223], v[46:49]
	v_mfma_f32_16x16x32_bf16 v[38:41], v[170:173], v[220:223], v[38:41]
	v_mfma_f32_16x16x32_bf16 v[78:81], v[166:169], v[200:203], v[78:81]
	v_mfma_f32_16x16x32_bf16 v[74:77], v[174:177], v[200:203], v[74:77]
	v_mfma_f32_16x16x32_bf16 v[70:73], v[166:169], v[208:211], v[70:73]
	v_mfma_f32_16x16x32_bf16 v[62:65], v[174:177], v[208:211], v[62:65]
	v_mfma_f32_16x16x32_bf16 v[58:61], v[166:169], v[216:219], v[58:61]
	v_mfma_f32_16x16x32_bf16 v[54:57], v[174:177], v[216:219], v[54:57]
	v_mfma_f32_16x16x32_bf16 v[46:49], v[166:169], v[224:227], v[46:49]
	v_mfma_f32_16x16x32_bf16 v[38:41], v[174:177], v[224:227], v[38:41]
	v_mfma_f32_16x16x32_bf16 v[50:53], v[178:181], v[196:199], v[50:53]
	v_mfma_f32_16x16x32_bf16 v[42:45], v[186:189], v[196:199], v[42:45]
	v_mfma_f32_16x16x32_bf16 v[34:37], v[178:181], v[204:207], v[34:37]
	v_mfma_f32_16x16x32_bf16 v[26:29], v[186:189], v[204:207], v[26:29]
	v_mfma_f32_16x16x32_bf16 v[18:21], v[178:181], v[212:215], v[18:21]
	v_mfma_f32_16x16x32_bf16 v[14:17], v[186:189], v[212:215], v[14:17]
	v_mfma_f32_16x16x32_bf16 v[10:13], v[178:181], v[220:223], v[10:13]
	v_mfma_f32_16x16x32_bf16 v[6:9], v[186:189], v[220:223], v[6:9]
	v_mfma_f32_16x16x32_bf16 v[50:53], v[182:185], v[200:203], v[50:53]
	v_mfma_f32_16x16x32_bf16 v[42:45], v[190:193], v[200:203], v[42:45]
	v_mfma_f32_16x16x32_bf16 v[34:37], v[182:185], v[208:211], v[34:37]
	v_mfma_f32_16x16x32_bf16 v[26:29], v[190:193], v[208:211], v[26:29]
	v_mfma_f32_16x16x32_bf16 v[18:21], v[182:185], v[216:219], v[18:21]
	v_mfma_f32_16x16x32_bf16 v[14:17], v[190:193], v[216:219], v[14:17]
	v_mfma_f32_16x16x32_bf16 v[10:13], v[182:185], v[224:227], v[10:13]
	v_mfma_f32_16x16x32_bf16 v[6:9], v[190:193], v[224:227], v[6:9]
	s_setprio 0
	s_waitcnt vmcnt(8)
	s_barrier
	s_add_i32 s73, s62, s49
	v_lshl_add_u64 v[228:229], s[42:43], 0, v[134:135]
	s_mov_b32 m0, s73
	ds_read_b128 v[196:199], v164 offset:16384
	ds_read_b128 v[200:203], v164 offset:17408
	ds_read_b128 v[204:207], v164 offset:18432
	ds_read_b128 v[208:211], v164 offset:19456
	ds_read_b128 v[212:215], v164 offset:20480
	ds_read_b128 v[216:219], v164 offset:21504
	ds_read_b128 v[220:223], v164 offset:22528
	ds_read_b128 v[224:227], v164 offset:23552
	global_load_lds_dwordx4 v[228:229], off
	s_add_i32 m0, s73, 0x2000
	s_add_u32 s74, s42, 0x100000
	v_lshl_add_u64 v[230:231], s[42:43], 0, v[138:139]
	s_addc_u32 s75, s43, 0
	s_add_i32 s73, s63, s49
	global_load_lds_dwordx4 v[230:231], off
	v_lshl_add_u64 v[232:233], s[74:75], 0, v[134:135]
	s_mov_b32 m0, s73
	v_lshl_add_u64 v[234:235], s[46:47], 0, v[136:137]
	global_load_lds_dwordx4 v[232:233], off
	v_lshl_add_u64 v[232:233], s[74:75], 0, v[138:139]
	s_add_i32 m0, s73, 0x2000
	s_nop 0
	global_load_lds_dwordx4 v[232:233], off
	v_lshl_add_u64 v[232:233], s[46:47], 0, v[132:133]
	s_mov_b32 m0, s35
	s_nop 0
	global_load_lds_dwordx4 v[232:233], off
	s_mov_b32 m0, s50
	s_nop 0
	global_load_lds_dwordx4 v[234:235], off
	s_waitcnt lgkmcnt(0)
	s_setprio 1
	v_mfma_f32_16x16x32_bf16 v[126:129], v[156:159], v[196:199], v[126:129]
	v_mfma_f32_16x16x32_bf16 v[118:121], v[170:173], v[196:199], v[118:121]
	v_mfma_f32_16x16x32_bf16 v[110:113], v[156:159], v[204:207], v[110:113]
	v_mfma_f32_16x16x32_bf16 v[102:105], v[170:173], v[204:207], v[102:105]
	v_mfma_f32_16x16x32_bf16 v[94:97], v[156:159], v[212:215], v[94:97]
	v_mfma_f32_16x16x32_bf16 v[86:89], v[170:173], v[212:215], v[86:89]
	v_mfma_f32_16x16x32_bf16 v[66:69], v[156:159], v[220:223], v[66:69]
	v_mfma_f32_16x16x32_bf16 v[22:25], v[170:173], v[220:223], v[22:25]
	v_mfma_f32_16x16x32_bf16 v[126:129], v[166:169], v[200:203], v[126:129]
	v_mfma_f32_16x16x32_bf16 v[118:121], v[174:177], v[200:203], v[118:121]
	v_mfma_f32_16x16x32_bf16 v[110:113], v[166:169], v[208:211], v[110:113]
	v_mfma_f32_16x16x32_bf16 v[102:105], v[174:177], v[208:211], v[102:105]
	v_mfma_f32_16x16x32_bf16 v[94:97], v[166:169], v[216:219], v[94:97]
	v_mfma_f32_16x16x32_bf16 v[86:89], v[174:177], v[216:219], v[86:89]
	v_mfma_f32_16x16x32_bf16 v[66:69], v[166:169], v[224:227], v[66:69]
	v_mfma_f32_16x16x32_bf16 v[22:25], v[174:177], v[224:227], v[22:25]
	v_mfma_f32_16x16x32_bf16 v[122:125], v[178:181], v[196:199], v[122:125]
	v_mfma_f32_16x16x32_bf16 v[114:117], v[186:189], v[196:199], v[114:117]
	v_mfma_f32_16x16x32_bf16 v[106:109], v[178:181], v[204:207], v[106:109]
	v_mfma_f32_16x16x32_bf16 v[98:101], v[186:189], v[204:207], v[98:101]
	v_mfma_f32_16x16x32_bf16 v[90:93], v[178:181], v[212:215], v[90:93]
	v_mfma_f32_16x16x32_bf16 v[82:85], v[186:189], v[212:215], v[82:85]
	v_mfma_f32_16x16x32_bf16 v[30:33], v[178:181], v[220:223], v[30:33]
	v_mfma_f32_16x16x32_bf16 v[2:5], v[186:189], v[220:223], v[2:5]
	v_mfma_f32_16x16x32_bf16 v[122:125], v[182:185], v[200:203], v[122:125]
	v_mfma_f32_16x16x32_bf16 v[114:117], v[190:193], v[200:203], v[114:117]
	v_mfma_f32_16x16x32_bf16 v[106:109], v[182:185], v[208:211], v[106:109]
	v_mfma_f32_16x16x32_bf16 v[98:101], v[190:193], v[208:211], v[98:101]
	v_mfma_f32_16x16x32_bf16 v[90:93], v[182:185], v[216:219], v[90:93]
	v_mfma_f32_16x16x32_bf16 v[82:85], v[190:193], v[216:219], v[82:85]
	v_mfma_f32_16x16x32_bf16 v[30:33], v[182:185], v[224:227], v[30:33]
	v_mfma_f32_16x16x32_bf16 v[2:5], v[190:193], v[224:227], v[2:5]
	s_setprio 0
	s_waitcnt vmcnt(8)
	s_barrier
	s_add_i32 s73, 0, 0x18000
	v_add_u32_e32 v165, s73, v160
	s_add_i32 s74, 0, 0x1c000
	ds_read_b128 v[156:159], v165
	ds_read_b128 v[166:169], v165 offset:1024
	ds_read_b128 v[170:173], v165 offset:2048
	ds_read_b128 v[174:177], v165 offset:3072
	v_add_u32_e32 v165, s74, v160
	ds_read_b128 v[178:181], v165
	ds_read_b128 v[182:185], v165 offset:1024
	ds_read_b128 v[186:189], v165 offset:2048
	ds_read_b128 v[190:193], v165 offset:3072
	s_add_u32 s46, s46, 0x100000
	s_addc_u32 s47, s47, 0
	s_mov_b32 m0, s51
	v_lshl_add_u64 v[236:237], s[46:47], 0, v[132:133]
	ds_read_b128 v[196:199], v164 offset:32768
	ds_read_b128 v[200:203], v164 offset:33792
	ds_read_b128 v[204:207], v164 offset:34816
	ds_read_b128 v[208:211], v164 offset:35840
	ds_read_b128 v[212:215], v164 offset:36864
	ds_read_b128 v[216:219], v164 offset:37888
	ds_read_b128 v[220:223], v164 offset:38912
	ds_read_b128 v[224:227], v164 offset:39936
	global_load_lds_dwordx4 v[236:237], off
	v_lshl_add_u64 v[236:237], s[46:47], 0, v[136:137]
	s_mov_b32 m0, s52
	s_nop 0
	global_load_lds_dwordx4 v[236:237], off
	s_waitcnt lgkmcnt(0)
	s_setprio 1
	v_mfma_f32_16x16x32_bf16 v[78:81], v[156:159], v[196:199], v[78:81]
	v_mfma_f32_16x16x32_bf16 v[74:77], v[170:173], v[196:199], v[74:77]
	v_mfma_f32_16x16x32_bf16 v[70:73], v[156:159], v[204:207], v[70:73]
	v_mfma_f32_16x16x32_bf16 v[62:65], v[170:173], v[204:207], v[62:65]
	v_mfma_f32_16x16x32_bf16 v[58:61], v[156:159], v[212:215], v[58:61]
	v_mfma_f32_16x16x32_bf16 v[54:57], v[170:173], v[212:215], v[54:57]
	v_mfma_f32_16x16x32_bf16 v[46:49], v[156:159], v[220:223], v[46:49]
	v_mfma_f32_16x16x32_bf16 v[38:41], v[170:173], v[220:223], v[38:41]
	v_mfma_f32_16x16x32_bf16 v[78:81], v[166:169], v[200:203], v[78:81]
	v_mfma_f32_16x16x32_bf16 v[74:77], v[174:177], v[200:203], v[74:77]
	v_mfma_f32_16x16x32_bf16 v[70:73], v[166:169], v[208:211], v[70:73]
	v_mfma_f32_16x16x32_bf16 v[62:65], v[174:177], v[208:211], v[62:65]
	v_mfma_f32_16x16x32_bf16 v[58:61], v[166:169], v[216:219], v[58:61]
	v_mfma_f32_16x16x32_bf16 v[54:57], v[174:177], v[216:219], v[54:57]
	v_mfma_f32_16x16x32_bf16 v[46:49], v[166:169], v[224:227], v[46:49]
	v_mfma_f32_16x16x32_bf16 v[38:41], v[174:177], v[224:227], v[38:41]
	v_mfma_f32_16x16x32_bf16 v[50:53], v[178:181], v[196:199], v[50:53]
	v_mfma_f32_16x16x32_bf16 v[42:45], v[186:189], v[196:199], v[42:45]
	v_mfma_f32_16x16x32_bf16 v[34:37], v[178:181], v[204:207], v[34:37]
	v_mfma_f32_16x16x32_bf16 v[26:29], v[186:189], v[204:207], v[26:29]
	v_mfma_f32_16x16x32_bf16 v[18:21], v[178:181], v[212:215], v[18:21]
	v_mfma_f32_16x16x32_bf16 v[14:17], v[186:189], v[212:215], v[14:17]
	v_mfma_f32_16x16x32_bf16 v[10:13], v[178:181], v[220:223], v[10:13]
	v_mfma_f32_16x16x32_bf16 v[6:9], v[186:189], v[220:223], v[6:9]
	v_mfma_f32_16x16x32_bf16 v[50:53], v[182:185], v[200:203], v[50:53]
	v_mfma_f32_16x16x32_bf16 v[42:45], v[190:193], v[200:203], v[42:45]
	v_mfma_f32_16x16x32_bf16 v[34:37], v[182:185], v[208:211], v[34:37]
	v_mfma_f32_16x16x32_bf16 v[26:29], v[190:193], v[208:211], v[26:29]
	v_mfma_f32_16x16x32_bf16 v[18:21], v[182:185], v[216:219], v[18:21]
	v_mfma_f32_16x16x32_bf16 v[14:17], v[190:193], v[216:219], v[14:17]
	v_mfma_f32_16x16x32_bf16 v[10:13], v[182:185], v[224:227], v[10:13]
	v_mfma_f32_16x16x32_bf16 v[6:9], v[190:193], v[224:227], v[6:9]
	s_setprio 0
	s_waitcnt vmcnt(8)
	s_barrier
	s_add_i32 s46, s73, s49
	v_lshl_add_u64 v[228:229], v[228:229], 0, s[10:11]
	s_mov_b32 m0, s46
	ds_read_b128 v[196:199], v164 offset:49152
	ds_read_b128 v[200:203], v164 offset:50176
	ds_read_b128 v[204:207], v164 offset:51200
	ds_read_b128 v[208:211], v164 offset:52224
	ds_read_b128 v[212:215], v164 offset:53248
	ds_read_b128 v[216:219], v164 offset:54272
	ds_read_b128 v[220:223], v164 offset:55296
	ds_read_b128 v[224:227], v164 offset:56320
	global_load_lds_dwordx4 v[228:229], off
	s_add_i32 m0, s46, 0x2000
	s_add_u32 s42, s42, 0x100080
	v_lshl_add_u64 v[228:229], v[230:231], 0, s[10:11]
	s_addc_u32 s43, s43, 0
	s_add_i32 s46, s74, s49
	global_load_lds_dwordx4 v[228:229], off
	v_lshl_add_u64 v[228:229], s[42:43], 0, v[134:135]
	s_mov_b32 m0, s46
	s_nop 0
	global_load_lds_dwordx4 v[228:229], off
	v_lshl_add_u64 v[228:229], s[42:43], 0, v[138:139]
	s_add_i32 m0, s46, 0x2000
	s_nop 0
	global_load_lds_dwordx4 v[228:229], off
	v_lshl_add_u64 v[228:229], v[232:233], 0, s[10:11]
	s_mov_b32 m0, s55
	s_nop 0
	global_load_lds_dwordx4 v[228:229], off
	v_lshl_add_u64 v[228:229], v[234:235], 0, s[10:11]
	s_mov_b32 m0, s56
	s_nop 0
	global_load_lds_dwordx4 v[228:229], off
	s_waitcnt lgkmcnt(0)
	s_setprio 1
	v_mfma_f32_16x16x32_bf16 v[126:129], v[156:159], v[196:199], v[126:129]
	v_mfma_f32_16x16x32_bf16 v[118:121], v[170:173], v[196:199], v[118:121]
	v_mfma_f32_16x16x32_bf16 v[110:113], v[156:159], v[204:207], v[110:113]
	v_mfma_f32_16x16x32_bf16 v[102:105], v[170:173], v[204:207], v[102:105]
	v_mfma_f32_16x16x32_bf16 v[94:97], v[156:159], v[212:215], v[94:97]
	v_mfma_f32_16x16x32_bf16 v[86:89], v[170:173], v[212:215], v[86:89]
	v_mfma_f32_16x16x32_bf16 v[66:69], v[156:159], v[220:223], v[66:69]
	v_mfma_f32_16x16x32_bf16 v[22:25], v[170:173], v[220:223], v[22:25]
	v_mfma_f32_16x16x32_bf16 v[126:129], v[166:169], v[200:203], v[126:129]
	v_mfma_f32_16x16x32_bf16 v[118:121], v[174:177], v[200:203], v[118:121]
	v_mfma_f32_16x16x32_bf16 v[110:113], v[166:169], v[208:211], v[110:113]
	v_mfma_f32_16x16x32_bf16 v[102:105], v[174:177], v[208:211], v[102:105]
	v_mfma_f32_16x16x32_bf16 v[94:97], v[166:169], v[216:219], v[94:97]
	v_mfma_f32_16x16x32_bf16 v[86:89], v[174:177], v[216:219], v[86:89]
	v_mfma_f32_16x16x32_bf16 v[66:69], v[166:169], v[224:227], v[66:69]
	v_mfma_f32_16x16x32_bf16 v[22:25], v[174:177], v[224:227], v[22:25]
	v_mfma_f32_16x16x32_bf16 v[122:125], v[178:181], v[196:199], v[122:125]
	v_mfma_f32_16x16x32_bf16 v[114:117], v[186:189], v[196:199], v[114:117]
	v_mfma_f32_16x16x32_bf16 v[106:109], v[178:181], v[204:207], v[106:109]
	v_mfma_f32_16x16x32_bf16 v[98:101], v[186:189], v[204:207], v[98:101]
	v_mfma_f32_16x16x32_bf16 v[90:93], v[178:181], v[212:215], v[90:93]
	v_mfma_f32_16x16x32_bf16 v[82:85], v[186:189], v[212:215], v[82:85]
	v_mfma_f32_16x16x32_bf16 v[30:33], v[178:181], v[220:223], v[30:33]
	v_mfma_f32_16x16x32_bf16 v[2:5], v[186:189], v[220:223], v[2:5]
	v_mfma_f32_16x16x32_bf16 v[122:125], v[182:185], v[200:203], v[122:125]
	v_mfma_f32_16x16x32_bf16 v[114:117], v[190:193], v[200:203], v[114:117]
	v_mfma_f32_16x16x32_bf16 v[106:109], v[182:185], v[208:211], v[106:109]
	v_mfma_f32_16x16x32_bf16 v[98:101], v[190:193], v[208:211], v[98:101]
	v_mfma_f32_16x16x32_bf16 v[90:93], v[182:185], v[216:219], v[90:93]
	v_mfma_f32_16x16x32_bf16 v[82:85], v[190:193], v[216:219], v[82:85]
	v_mfma_f32_16x16x32_bf16 v[30:33], v[182:185], v[224:227], v[30:33]
	v_mfma_f32_16x16x32_bf16 v[2:5], v[190:193], v[224:227], v[2:5]
	s_setprio 0
	s_waitcnt vmcnt(8)
	s_barrier
	s_add_u32 s40, s40, 0x100
	s_addc_u32 s41, s41, 0
	s_add_u32 s70, s70, 0x100
	s_addc_u32 s71, s71, 0
	s_cmp_ge_i32 s72, s68
	s_mov_b32 s42, s72
	s_cbranch_scc0 .Lkt_L_16
	s_branch .Lkt_exit_16
.Lkt_T_16:
	ds_read_b128 v[156:159], v162
	ds_read_b128 v[166:169], v162 offset:1024
	ds_read_b128 v[170:173], v162 offset:2048
	ds_read_b128 v[174:177], v162 offset:3072
	ds_read_b128 v[178:181], v163
	ds_read_b128 v[182:185], v163 offset:1024
	ds_read_b128 v[186:189], v163 offset:2048
	ds_read_b128 v[190:193], v163 offset:3072
	s_add_i32 s72, s42, 2
	s_add_u32 s43, s40, 0xfff00080
	s_addc_u32 s46, s41, -1
	s_cmp_eq_u32 s69, s42
	s_cselect_b32 s42, s25, s70
	s_cselect_b32 s47, s5, s46
	s_cselect_b32 s46, s23, s43
	s_cselect_b32 s43, s21, s71
	v_lshl_add_u64 v[228:229], s[40:41], 0, v[148:149]
	s_add_i32 m0, s35, 0xc000
	ds_read_b128 v[196:199], v164
	ds_read_b128 v[200:203], v164 offset:1024
	ds_read_b128 v[204:207], v164 offset:2048
	ds_read_b128 v[208:211], v164 offset:3072
	ds_read_b128 v[212:215], v164 offset:4096
	ds_read_b128 v[216:219], v164 offset:5120
	ds_read_b128 v[220:223], v164 offset:6144
	ds_read_b128 v[224:227], v164 offset:7168
	global_load_lds_dwordx4 v[228:229], off
	v_lshl_add_u64 v[228:229], s[40:41], 0, v[150:151]
	s_add_i32 m0, s35, 0xe000
	s_nop 0
	global_load_lds_dwordx4 v[228:229], off
	s_waitcnt vmcnt(8)
	s_waitcnt lgkmcnt(0)
	s_barrier
	s_setprio 2
	v_mfma_f32_16x16x32_bf16 v[78:81], v[156:159], v[196:199], v[78:81]
	v_mfma_f32_16x16x32_bf16 v[74:77], v[170:173], v[196:199], v[74:77]
	v_mfma_f32_16x16x32_bf16 v[70:73], v[156:159], v[204:207], v[70:73]
	v_mfma_f32_16x16x32_bf16 v[62:65], v[170:173], v[204:207], v[62:65]
	v_mfma_f32_16x16x32_bf16 v[58:61], v[156:159], v[212:215], v[58:61]
	v_mfma_f32_16x16x32_bf16 v[54:57], v[170:173], v[212:215], v[54:57]
	v_mfma_f32_16x16x32_bf16 v[46:49], v[156:159], v[220:223], v[46:49]
	v_mfma_f32_16x16x32_bf16 v[38:41], v[170:173], v[220:223], v[38:41]
	v_mfma_f32_16x16x32_bf16 v[78:81], v[166:169], v[200:203], v[78:81]
	v_mfma_f32_16x16x32_bf16 v[74:77], v[174:177], v[200:203], v[74:77]
	v_mfma_f32_16x16x32_bf16 v[70:73], v[166:169], v[208:211], v[70:73]
	v_mfma_f32_16x16x32_bf16 v[62:65], v[174:177], v[208:211], v[62:65]
	v_mfma_f32_16x16x32_bf16 v[58:61], v[166:169], v[216:219], v[58:61]
	v_mfma_f32_16x16x32_bf16 v[54:57], v[174:177], v[216:219], v[54:57]
	v_mfma_f32_16x16x32_bf16 v[46:49], v[166:169], v[224:227], v[46:49]
	v_mfma_f32_16x16x32_bf16 v[38:41], v[174:177], v[224:227], v[38:41]
	v_mfma_f32_16x16x32_bf16 v[50:53], v[178:181], v[196:199], v[50:53]
	v_mfma_f32_16x16x32_bf16 v[42:45], v[186:189], v[196:199], v[42:45]
	v_mfma_f32_16x16x32_bf16 v[34:37], v[178:181], v[204:207], v[34:37]
	v_mfma_f32_16x16x32_bf16 v[26:29], v[186:189], v[204:207], v[26:29]
	v_mfma_f32_16x16x32_bf16 v[18:21], v[178:181], v[212:215], v[18:21]
	v_mfma_f32_16x16x32_bf16 v[14:17], v[186:189], v[212:215], v[14:17]
	v_mfma_f32_16x16x32_bf16 v[10:13], v[178:181], v[220:223], v[10:13]
	v_mfma_f32_16x16x32_bf16 v[6:9], v[186:189], v[220:223], v[6:9]
	v_mfma_f32_16x16x32_bf16 v[50:53], v[182:185], v[200:203], v[50:53]
	v_mfma_f32_16x16x32_bf16 v[42:45], v[190:193], v[200:203], v[42:45]
	v_mfma_f32_16x16x32_bf16 v[34:37], v[182:185], v[208:211], v[34:37]
	v_mfma_f32_16x16x32_bf16 v[26:29], v[190:193], v[208:211], v[26:29]
	v_mfma_f32_16x16x32_bf16 v[18:21], v[182:185], v[216:219], v[18:21]
	v_mfma_f32_16x16x32_bf16 v[14:17], v[190:193], v[216:219], v[14:17]
	v_mfma_f32_16x16x32_bf16 v[10:13], v[182:185], v[224:227], v[10:13]
	v_mfma_f32_16x16x32_bf16 v[6:9], v[190:193], v[224:227], v[6:9]
	s_setprio 0
	s_add_i32 s73, s62, s49
	v_lshl_add_u64 v[228:229], s[42:43], 0, v[134:135]
	s_mov_b32 m0, s73
	ds_read_b128 v[196:199], v164 offset:16384
	ds_read_b128 v[200:203], v164 offset:17408
	ds_read_b128 v[204:207], v164 offset:18432
	ds_read_b128 v[208:211], v164 offset:19456
	ds_read_b128 v[212:215], v164 offset:20480
	ds_read_b128 v[216:219], v164 offset:21504
	ds_read_b128 v[220:223], v164 offset:22528
	ds_read_b128 v[224:227], v164 offset:23552
	global_load_lds_dwordx4 v[228:229], off
	s_add_i32 m0, s73, 0x2000
	s_add_u32 s74, s42, 0x100000
	v_lshl_add_u64 v[230:231], s[42:43], 0, v[138:139]
	s_addc_u32 s75, s43, 0
	s_add_i32 s73, s63, s49
	global_load_lds_dwordx4 v[230:231], off
	v_lshl_add_u64 v[232:233], s[74:75], 0, v[134:135]
	s_mov_b32 m0, s73
	v_lshl_add_u64 v[234:235], s[46:47], 0, v[136:137]
	global_load_lds_dwordx4 v[232:233], off
	v_lshl_add_u64 v[232:233], s[74:75], 0, v[138:139]
	s_add_i32 m0, s73, 0x2000
	s_nop 0
	global_load_lds_dwordx4 v[232:233], off
	v_lshl_add_u64 v[232:233], s[46:47], 0, v[132:133]
	s_mov_b32 m0, s35
	s_nop 0
	global_load_lds_dwordx4 v[232:233], off
	s_mov_b32 m0, s50
	s_nop 0
	global_load_lds_dwordx4 v[234:235], off
	s_waitcnt vmcnt(8)
	s_waitcnt lgkmcnt(0)
	s_barrier
	s_setprio 2
	v_mfma_f32_16x16x32_bf16 v[126:129], v[156:159], v[196:199], v[126:129]
	v_mfma_f32_16x16x32_bf16 v[118:121], v[170:173], v[196:199], v[118:121]
	v_mfma_f32_16x16x32_bf16 v[110:113], v[156:159], v[204:207], v[110:113]
	v_mfma_f32_16x16x32_bf16 v[102:105], v[170:173], v[204:207], v[102:105]
	v_mfma_f32_16x16x32_bf16 v[94:97], v[156:159], v[212:215], v[94:97]
	v_mfma_f32_16x16x32_bf16 v[86:89], v[170:173], v[212:215], v[86:89]
	v_mfma_f32_16x16x32_bf16 v[66:69], v[156:159], v[220:223], v[66:69]
	v_mfma_f32_16x16x32_bf16 v[22:25], v[170:173], v[220:223], v[22:25]
	v_mfma_f32_16x16x32_bf16 v[126:129], v[166:169], v[200:203], v[126:129]
	v_mfma_f32_16x16x32_bf16 v[118:121], v[174:177], v[200:203], v[118:121]
	v_mfma_f32_16x16x32_bf16 v[110:113], v[166:169], v[208:211], v[110:113]
	v_mfma_f32_16x16x32_bf16 v[102:105], v[174:177], v[208:211], v[102:105]
	v_mfma_f32_16x16x32_bf16 v[94:97], v[166:169], v[216:219], v[94:97]
	v_mfma_f32_16x16x32_bf16 v[86:89], v[174:177], v[216:219], v[86:89]
	v_mfma_f32_16x16x32_bf16 v[66:69], v[166:169], v[224:227], v[66:69]
	v_mfma_f32_16x16x32_bf16 v[22:25], v[174:177], v[224:227], v[22:25]
	v_mfma_f32_16x16x32_bf16 v[122:125], v[178:181], v[196:199], v[122:125]
	v_mfma_f32_16x16x32_bf16 v[114:117], v[186:189], v[196:199], v[114:117]
	v_mfma_f32_16x16x32_bf16 v[106:109], v[178:181], v[204:207], v[106:109]
	v_mfma_f32_16x16x32_bf16 v[98:101], v[186:189], v[204:207], v[98:101]
	v_mfma_f32_16x16x32_bf16 v[90:93], v[178:181], v[212:215], v[90:93]
	v_mfma_f32_16x16x32_bf16 v[82:85], v[186:189], v[212:215], v[82:85]
	v_mfma_f32_16x16x32_bf16 v[30:33], v[178:181], v[220:223], v[30:33]
	v_mfma_f32_16x16x32_bf16 v[2:5], v[186:189], v[220:223], v[2:5]
	v_mfma_f32_16x16x32_bf16 v[122:125], v[182:185], v[200:203], v[122:125]
	v_mfma_f32_16x16x32_bf16 v[114:117], v[190:193], v[200:203], v[114:117]
	v_mfma_f32_16x16x32_bf16 v[106:109], v[182:185], v[208:211], v[106:109]
	v_mfma_f32_16x16x32_bf16 v[98:101], v[190:193], v[208:211], v[98:101]
	v_mfma_f32_16x16x32_bf16 v[90:93], v[182:185], v[216:219], v[90:93]
	v_mfma_f32_16x16x32_bf16 v[82:85], v[190:193], v[216:219], v[82:85]
	v_mfma_f32_16x16x32_bf16 v[30:33], v[182:185], v[224:227], v[30:33]
	v_mfma_f32_16x16x32_bf16 v[2:5], v[190:193], v[224:227], v[2:5]
	s_setprio 0
	s_add_i32 s73, 0, 0x18000
	v_add_u32_e32 v165, s73, v160
	s_add_i32 s74, 0, 0x1c000
	ds_read_b128 v[156:159], v165
	ds_read_b128 v[166:169], v165 offset:1024
	ds_read_b128 v[170:173], v165 offset:2048
	ds_read_b128 v[174:177], v165 offset:3072
	v_add_u32_e32 v165, s74, v160
	ds_read_b128 v[178:181], v165
	ds_read_b128 v[182:185], v165 offset:1024
	ds_read_b128 v[186:189], v165 offset:2048
	ds_read_b128 v[190:193], v165 offset:3072
	s_add_u32 s46, s46, 0x100000
	s_addc_u32 s47, s47, 0
	s_mov_b32 m0, s51
	v_lshl_add_u64 v[236:237], s[46:47], 0, v[132:133]
	ds_read_b128 v[196:199], v164 offset:32768
	ds_read_b128 v[200:203], v164 offset:33792
	ds_read_b128 v[204:207], v164 offset:34816
	ds_read_b128 v[208:211], v164 offset:35840
	ds_read_b128 v[212:215], v164 offset:36864
	ds_read_b128 v[216:219], v164 offset:37888
	ds_read_b128 v[220:223], v164 offset:38912
	ds_read_b128 v[224:227], v164 offset:39936
	global_load_lds_dwordx4 v[236:237], off
	v_lshl_add_u64 v[236:237], s[46:47], 0, v[136:137]
	s_mov_b32 m0, s52
	s_nop 0
	global_load_lds_dwordx4 v[236:237], off
	s_waitcnt vmcnt(8)
	s_waitcnt lgkmcnt(0)
	s_barrier
	s_setprio 2
	v_mfma_f32_16x16x32_bf16 v[78:81], v[156:159], v[196:199], v[78:81]
	v_mfma_f32_16x16x32_bf16 v[74:77], v[170:173], v[196:199], v[74:77]
	v_mfma_f32_16x16x32_bf16 v[70:73], v[156:159], v[204:207], v[70:73]
	v_mfma_f32_16x16x32_bf16 v[62:65], v[170:173], v[204:207], v[62:65]
	v_mfma_f32_16x16x32_bf16 v[58:61], v[156:159], v[212:215], v[58:61]
	v_mfma_f32_16x16x32_bf16 v[54:57], v[170:173], v[212:215], v[54:57]
	v_mfma_f32_16x16x32_bf16 v[46:49], v[156:159], v[220:223], v[46:49]
	v_mfma_f32_16x16x32_bf16 v[38:41], v[170:173], v[220:223], v[38:41]
	v_mfma_f32_16x16x32_bf16 v[78:81], v[166:169], v[200:203], v[78:81]
	v_mfma_f32_16x16x32_bf16 v[74:77], v[174:177], v[200:203], v[74:77]
	v_mfma_f32_16x16x32_bf16 v[70:73], v[166:169], v[208:211], v[70:73]
	v_mfma_f32_16x16x32_bf16 v[62:65], v[174:177], v[208:211], v[62:65]
	v_mfma_f32_16x16x32_bf16 v[58:61], v[166:169], v[216:219], v[58:61]
	v_mfma_f32_16x16x32_bf16 v[54:57], v[174:177], v[216:219], v[54:57]
	v_mfma_f32_16x16x32_bf16 v[46:49], v[166:169], v[224:227], v[46:49]
	v_mfma_f32_16x16x32_bf16 v[38:41], v[174:177], v[224:227], v[38:41]
	v_mfma_f32_16x16x32_bf16 v[50:53], v[178:181], v[196:199], v[50:53]
	v_mfma_f32_16x16x32_bf16 v[42:45], v[186:189], v[196:199], v[42:45]
	v_mfma_f32_16x16x32_bf16 v[34:37], v[178:181], v[204:207], v[34:37]
	v_mfma_f32_16x16x32_bf16 v[26:29], v[186:189], v[204:207], v[26:29]
	v_mfma_f32_16x16x32_bf16 v[18:21], v[178:181], v[212:215], v[18:21]
	v_mfma_f32_16x16x32_bf16 v[14:17], v[186:189], v[212:215], v[14:17]
	v_mfma_f32_16x16x32_bf16 v[10:13], v[178:181], v[220:223], v[10:13]
	v_mfma_f32_16x16x32_bf16 v[6:9], v[186:189], v[220:223], v[6:9]
	v_mfma_f32_16x16x32_bf16 v[50:53], v[182:185], v[200:203], v[50:53]
	v_mfma_f32_16x16x32_bf16 v[42:45], v[190:193], v[200:203], v[42:45]
	v_mfma_f32_16x16x32_bf16 v[34:37], v[182:185], v[208:211], v[34:37]
	v_mfma_f32_16x16x32_bf16 v[26:29], v[190:193], v[208:211], v[26:29]
	v_mfma_f32_16x16x32_bf16 v[18:21], v[182:185], v[216:219], v[18:21]
	v_mfma_f32_16x16x32_bf16 v[14:17], v[190:193], v[216:219], v[14:17]
	v_mfma_f32_16x16x32_bf16 v[10:13], v[182:185], v[224:227], v[10:13]
	v_mfma_f32_16x16x32_bf16 v[6:9], v[190:193], v[224:227], v[6:9]
	s_setprio 0
	s_add_i32 s46, s73, s49
	v_lshl_add_u64 v[228:229], v[228:229], 0, s[10:11]
	s_mov_b32 m0, s46
	ds_read_b128 v[196:199], v164 offset:49152
	ds_read_b128 v[200:203], v164 offset:50176
	ds_read_b128 v[204:207], v164 offset:51200
	ds_read_b128 v[208:211], v164 offset:52224
	ds_read_b128 v[212:215], v164 offset:53248
	ds_read_b128 v[216:219], v164 offset:54272
	ds_read_b128 v[220:223], v164 offset:55296
	ds_read_b128 v[224:227], v164 offset:56320
	global_load_lds_dwordx4 v[228:229], off
	s_add_i32 m0, s46, 0x2000
	s_add_u32 s42, s42, 0x100080
	v_lshl_add_u64 v[228:229], v[230:231], 0, s[10:11]
	s_addc_u32 s43, s43, 0
	s_add_i32 s46, s74, s49
	global_load_lds_dwordx4 v[228:229], off
	v_lshl_add_u64 v[228:229], s[42:43], 0, v[134:135]
	s_mov_b32 m0, s46
	s_nop 0
	global_load_lds_dwordx4 v[228:229], off
	v_lshl_add_u64 v[228:229], s[42:43], 0, v[138:139]
	s_add_i32 m0, s46, 0x2000
	s_nop 0
	global_load_lds_dwordx4 v[228:229], off
	v_lshl_add_u64 v[228:229], v[232:233], 0, s[10:11]
	s_mov_b32 m0, s55
	s_nop 0
	global_load_lds_dwordx4 v[228:229], off
	v_lshl_add_u64 v[228:229], v[234:235], 0, s[10:11]
	s_mov_b32 m0, s56
	s_nop 0
	global_load_lds_dwordx4 v[228:229], off
	s_waitcnt vmcnt(8)
	s_waitcnt lgkmcnt(0)
	s_barrier
	s_setprio 2
	v_mfma_f32_16x16x32_bf16 v[126:129], v[156:159], v[196:199], v[126:129]
	v_mfma_f32_16x16x32_bf16 v[118:121], v[170:173], v[196:199], v[118:121]
	v_mfma_f32_16x16x32_bf16 v[110:113], v[156:159], v[204:207], v[110:113]
	v_mfma_f32_16x16x32_bf16 v[102:105], v[170:173], v[204:207], v[102:105]
	v_mfma_f32_16x16x32_bf16 v[94:97], v[156:159], v[212:215], v[94:97]
	v_mfma_f32_16x16x32_bf16 v[86:89], v[170:173], v[212:215], v[86:89]
	v_mfma_f32_16x16x32_bf16 v[66:69], v[156:159], v[220:223], v[66:69]
	v_mfma_f32_16x16x32_bf16 v[22:25], v[170:173], v[220:223], v[22:25]
	v_mfma_f32_16x16x32_bf16 v[126:129], v[166:169], v[200:203], v[126:129]
	v_mfma_f32_16x16x32_bf16 v[118:121], v[174:177], v[200:203], v[118:121]
	v_mfma_f32_16x16x32_bf16 v[110:113], v[166:169], v[208:211], v[110:113]
	v_mfma_f32_16x16x32_bf16 v[102:105], v[174:177], v[208:211], v[102:105]
	v_mfma_f32_16x16x32_bf16 v[94:97], v[166:169], v[216:219], v[94:97]
	v_mfma_f32_16x16x32_bf16 v[86:89], v[174:177], v[216:219], v[86:89]
	v_mfma_f32_16x16x32_bf16 v[66:69], v[166:169], v[224:227], v[66:69]
	v_mfma_f32_16x16x32_bf16 v[22:25], v[174:177], v[224:227], v[22:25]
	v_mfma_f32_16x16x32_bf16 v[122:125], v[178:181], v[196:199], v[122:125]
	v_mfma_f32_16x16x32_bf16 v[114:117], v[186:189], v[196:199], v[114:117]
	v_mfma_f32_16x16x32_bf16 v[106:109], v[178:181], v[204:207], v[106:109]
	v_mfma_f32_16x16x32_bf16 v[98:101], v[186:189], v[204:207], v[98:101]
	v_mfma_f32_16x16x32_bf16 v[90:93], v[178:181], v[212:215], v[90:93]
	v_mfma_f32_16x16x32_bf16 v[82:85], v[186:189], v[212:215], v[82:85]
	v_mfma_f32_16x16x32_bf16 v[30:33], v[178:181], v[220:223], v[30:33]
	v_mfma_f32_16x16x32_bf16 v[2:5], v[186:189], v[220:223], v[2:5]
	v_mfma_f32_16x16x32_bf16 v[122:125], v[182:185], v[200:203], v[122:125]
	v_mfma_f32_16x16x32_bf16 v[114:117], v[190:193], v[200:203], v[114:117]
	v_mfma_f32_16x16x32_bf16 v[106:109], v[182:185], v[208:211], v[106:109]
	v_mfma_f32_16x16x32_bf16 v[98:101], v[190:193], v[208:211], v[98:101]
	v_mfma_f32_16x16x32_bf16 v[90:93], v[182:185], v[216:219], v[90:93]
	v_mfma_f32_16x16x32_bf16 v[82:85], v[190:193], v[216:219], v[82:85]
	v_mfma_f32_16x16x32_bf16 v[30:33], v[182:185], v[224:227], v[30:33]
	v_mfma_f32_16x16x32_bf16 v[2:5], v[190:193], v[224:227], v[2:5]
	s_setprio 0
	s_add_u32 s40, s40, 0x100
	s_addc_u32 s41, s41, 0
	s_add_u32 s70, s70, 0x100
	s_addc_u32 s71, s71, 0
	s_cmp_ge_i32 s72, s68
	s_mov_b32 s42, s72
	s_cbranch_scc0 .Lkt_T_16
	s_nop 7
.Lkt_exit_16:
	s_and_b64 vcc, exec, s[12:13]
	s_cbranch_vccz .LBB0_4150
	s_cmp_lt_i32 s48, 0
	s_mov_b64 s[40:41], -1
	s_cbranch_scc1 .LBB0_4151

.LBB0_4153:
	s_andn2_b64 vcc, exec, s[6:7]
	s_cbranch_vccnz .LBB0_4123
	s_branch .LBB0_4123

.LBB0_4287:
	s_add_u32 s10, s38, 0x31800000
	s_addc_u32 s11, s39, 0
	s_add_u32 s12, s38, 0x39c00000
	s_addc_u32 s13, s39, 0
	s_add_u32 s59, s38, 0x50600000
	s_addc_u32 s60, s39, 0
	s_lshl_b32 s0, s5, 5
	s_mov_b64 s[14:15], 0x80
	s_and_b32 s5, s0, 0x60
	s_add_i32 m0, s55, 0x18000
	v_lshl_add_u64 v[8:9], v[8:9], 0, s[14:15]
	s_lshl_b32 s17, s4, 13
	s_lshl_b32 s18, s5, 7
	s_ashr_i32 s61, s2, 31
	s_waitcnt vmcnt(2)
	s_barrier
	global_load_lds_dwordx4 v[8:9], off
	v_lshl_add_u64 v[6:7], v[6:7], 0, s[14:15]
	s_add_i32 m0, s55, 0x1a000
	s_add_i32 s62, s55, 0x8000
	s_add_i32 s63, s55, 0xa000
	global_load_lds_dwordx4 v[6:7], off
	v_lshl_add_u64 v[2:3], v[2:3], 0, s[14:15]
	s_mov_b32 m0, s62
	s_add_u32 s0, s48, 0x2b0080
	global_load_lds_dwordx4 v[2:3], off
	v_lshl_add_u64 v[2:3], v[4:5], 0, s[14:15]
	s_mov_b32 m0, s63
	s_addc_u32 s1, s49, 0
	global_load_lds_dwordx4 v[2:3], off
	s_add_i32 m0, s55, 0x1c000
	v_lshl_add_u64 v[2:3], s[0:1], 0, v[132:133]
	global_load_lds_dwordx4 v[2:3], off
	v_lshl_add_u64 v[2:3], s[0:1], 0, v[136:137]
	s_add_i32 m0, s55, 0x1e000
	v_lshlrev_b32_e32 v4, 2, v0
	global_load_lds_dwordx4 v[2:3], off
	v_and_b32_e32 v2, 15, v0
	v_lshlrev_b32_e32 v3, 1, v11
	v_lshlrev_b32_e32 v0, 6, v0
	s_movk_i32 s0, 0x3c0
	v_and_b32_e32 v4, 32, v4
	v_and_or_b32 v0, v0, s0, v3
	v_lshl_or_b32 v131, s4, 6, v2
	v_lshl_or_b32 v2, v2, 6, v3
	v_bitop3_b32 v156, s18, v0, v4 bitop3:0xf6
	s_waitcnt vmcnt(6)
	s_cmpk_lt_u32 s16, 0x100
	v_add_u16_e32 v0, v1, v10
	v_bitop3_b32 v2, v2, s17, v4 bitop3:0xde
	s_cselect_b64 s[16:17], -1, 0
	v_lshrrev_b16_e32 v0, 1, v0
	s_add_i32 s65, 0, 0x10000
	s_add_i32 s66, 0, 0x14000
	s_brev_b32 s18, 31
	s_mov_b32 s20, 0xf8040000
	s_mov_b32 s22, 0xf8080000
	s_mov_b32 s24, 0xf80c0000
	s_ashr_i32 s64, s44, 31
	v_or_b32_e32 v157, s5, v11
	v_add_lshl_u32 v138, v12, v0, 1
	v_mov_b32_e32 v139, v133
	v_add_lshl_u32 v140, v13, v0, 1
	v_mov_b32_e32 v141, v133
	v_mov_b64_e32 v[142:143], 0x300
	v_mov_b64_e32 v[144:145], 0x2ff
	v_add_u32_e32 v158, s65, v156
	v_add_u32_e32 v159, s66, v156
	v_add_u32_e32 v160, 0, v2
	s_mov_b32 s19, -1
	s_brev_b32 s67, 31
	s_mov_b32 s21, -1
	s_mov_b32 s68, 0xf8040000
	s_mov_b32 s23, -1
	s_mov_b32 s69, 0xf8080000
	s_mov_b32 s25, -1
	s_mov_b32 s26, 0x3fb504f3
	s_mov_b64 s[28:29], 0x100000
	s_mov_b64 s[30:31], 0x120000
	s_mov_b64 s[34:35], 0x140000
	s_mov_b64 s[40:41], 0x160000
	v_mov_b64_e32 v[146:147], 0x1ff
	v_mov_b64_e32 v[148:149], 0x200
	s_mov_b32 s70, s7
	s_branch .LBB0_4290

.Lkt_L_17:
	ds_read_b128 v[150:153], v158
	ds_read_b128 v[162:165], v158 offset:1024
	ds_read_b128 v[166:169], v158 offset:2048
	ds_read_b128 v[170:173], v158 offset:3072
	ds_read_b128 v[174:177], v159
	ds_read_b128 v[178:181], v159 offset:1024
	ds_read_b128 v[182:185], v159 offset:2048
	ds_read_b128 v[186:189], v159 offset:3072
	s_add_i32 s80, s48, 2
	s_add_u32 s49, s50, 0xffd50080
	s_addc_u32 s52, s51, -1
	s_cmp_eq_u32 s43, s48
	s_cselect_b32 s48, s46, s78
	s_cselect_b32 s53, s5, s52
	s_cselect_b32 s52, s4, s49
	s_cselect_b32 s49, s47, s79
	v_lshl_add_u64 v[154:155], s[50:51], 0, v[138:139]
	s_add_i32 m0, s55, 0xc000
	ds_read_b128 v[190:193], v160
	ds_read_b128 v[196:199], v160 offset:1024
	ds_read_b128 v[200:203], v160 offset:2048
	ds_read_b128 v[204:207], v160 offset:3072
	ds_read_b128 v[208:211], v160 offset:4096
	ds_read_b128 v[212:215], v160 offset:5120
	ds_read_b128 v[216:219], v160 offset:6144
	ds_read_b128 v[220:223], v160 offset:7168
	global_load_lds_dwordx4 v[154:155], off
	v_lshl_add_u64 v[154:155], s[50:51], 0, v[140:141]
	s_add_i32 m0, s55, 0xe000
	s_nop 0
	global_load_lds_dwordx4 v[154:155], off
	s_waitcnt lgkmcnt(0)
	s_setprio 1
	v_mfma_f32_16x16x32_bf16 v[124:127], v[150:153], v[190:193], v[124:127]
	v_mfma_f32_16x16x32_bf16 v[120:123], v[166:169], v[190:193], v[120:123]
	v_mfma_f32_16x16x32_bf16 v[108:111], v[150:153], v[200:203], v[108:111]
	v_mfma_f32_16x16x32_bf16 v[104:107], v[166:169], v[200:203], v[104:107]
	v_mfma_f32_16x16x32_bf16 v[92:95], v[150:153], v[208:211], v[92:95]
	v_mfma_f32_16x16x32_bf16 v[88:91], v[166:169], v[208:211], v[88:91]
	v_mfma_f32_16x16x32_bf16 v[76:79], v[150:153], v[216:219], v[76:79]
	v_mfma_f32_16x16x32_bf16 v[72:75], v[166:169], v[216:219], v[72:75]
	v_mfma_f32_16x16x32_bf16 v[124:127], v[162:165], v[196:199], v[124:127]
	v_mfma_f32_16x16x32_bf16 v[120:123], v[170:173], v[196:199], v[120:123]
	v_mfma_f32_16x16x32_bf16 v[108:111], v[162:165], v[204:207], v[108:111]
	v_mfma_f32_16x16x32_bf16 v[104:107], v[170:173], v[204:207], v[104:107]
	v_mfma_f32_16x16x32_bf16 v[92:95], v[162:165], v[212:215], v[92:95]
	v_mfma_f32_16x16x32_bf16 v[88:91], v[170:173], v[212:215], v[88:91]
	v_mfma_f32_16x16x32_bf16 v[76:79], v[162:165], v[220:223], v[76:79]
	v_mfma_f32_16x16x32_bf16 v[72:75], v[170:173], v[220:223], v[72:75]
	v_mfma_f32_16x16x32_bf16 v[116:119], v[174:177], v[190:193], v[116:119]
	v_mfma_f32_16x16x32_bf16 v[112:115], v[182:185], v[190:193], v[112:115]
	v_mfma_f32_16x16x32_bf16 v[100:103], v[174:177], v[200:203], v[100:103]
	v_mfma_f32_16x16x32_bf16 v[96:99], v[182:185], v[200:203], v[96:99]
	v_mfma_f32_16x16x32_bf16 v[84:87], v[174:177], v[208:211], v[84:87]
	v_mfma_f32_16x16x32_bf16 v[80:83], v[182:185], v[208:211], v[80:83]
	v_mfma_f32_16x16x32_bf16 v[68:71], v[174:177], v[216:219], v[68:71]
	v_mfma_f32_16x16x32_bf16 v[64:67], v[182:185], v[216:219], v[64:67]
	v_mfma_f32_16x16x32_bf16 v[116:119], v[178:181], v[196:199], v[116:119]
	v_mfma_f32_16x16x32_bf16 v[112:115], v[186:189], v[196:199], v[112:115]
	v_mfma_f32_16x16x32_bf16 v[100:103], v[178:181], v[204:207], v[100:103]
	v_mfma_f32_16x16x32_bf16 v[96:99], v[186:189], v[204:207], v[96:99]
	v_mfma_f32_16x16x32_bf16 v[84:87], v[178:181], v[212:215], v[84:87]
	v_mfma_f32_16x16x32_bf16 v[80:83], v[186:189], v[212:215], v[80:83]
	v_mfma_f32_16x16x32_bf16 v[68:71], v[178:181], v[220:223], v[68:71]
	v_mfma_f32_16x16x32_bf16 v[64:67], v[186:189], v[220:223], v[64:67]
	s_setprio 0
	s_waitcnt vmcnt(8)
	s_barrier
	s_add_i32 s81, s65, s54
	v_lshl_add_u64 v[154:155], s[48:49], 0, v[132:133]
	s_mov_b32 m0, s81
	ds_read_b128 v[190:193], v160 offset:16384
	ds_read_b128 v[196:199], v160 offset:17408
	ds_read_b128 v[200:203], v160 offset:18432
	ds_read_b128 v[204:207], v160 offset:19456
	ds_read_b128 v[208:211], v160 offset:20480
	ds_read_b128 v[212:215], v160 offset:21504
	ds_read_b128 v[216:219], v160 offset:22528
	ds_read_b128 v[220:223], v160 offset:23552
	global_load_lds_dwordx4 v[154:155], off
	s_add_i32 m0, s81, 0x2000
	s_add_u32 s82, s48, 0x2b0000
	v_lshl_add_u64 v[224:225], s[48:49], 0, v[136:137]
	s_addc_u32 s83, s49, 0
	s_add_i32 s81, s66, s54
	global_load_lds_dwordx4 v[224:225], off
	v_lshl_add_u64 v[226:227], s[82:83], 0, v[132:133]
	s_mov_b32 m0, s81
	v_lshl_add_u64 v[228:229], s[52:53], 0, v[134:135]
	global_load_lds_dwordx4 v[226:227], off
	v_lshl_add_u64 v[226:227], s[82:83], 0, v[136:137]
	s_add_i32 m0, s81, 0x2000
	s_nop 0
	global_load_lds_dwordx4 v[226:227], off
	v_lshl_add_u64 v[226:227], s[52:53], 0, v[128:129]
	s_mov_b32 m0, s55
	s_nop 0
	global_load_lds_dwordx4 v[226:227], off
	s_mov_b32 m0, s56
	s_nop 0
	global_load_lds_dwordx4 v[228:229], off
	s_waitcnt lgkmcnt(0)
	s_setprio 1
	v_mfma_f32_16x16x32_bf16 v[60:63], v[150:153], v[190:193], v[60:63]
	v_mfma_f32_16x16x32_bf16 v[56:59], v[166:169], v[190:193], v[56:59]
	v_mfma_f32_16x16x32_bf16 v[44:47], v[150:153], v[200:203], v[44:47]
	v_mfma_f32_16x16x32_bf16 v[40:43], v[166:169], v[200:203], v[40:43]
	v_mfma_f32_16x16x32_bf16 v[28:31], v[150:153], v[208:211], v[28:31]
	v_mfma_f32_16x16x32_bf16 v[24:27], v[166:169], v[208:211], v[24:27]
	v_mfma_f32_16x16x32_bf16 v[12:15], v[150:153], v[216:219], v[12:15]
	v_mfma_f32_16x16x32_bf16 v[8:11], v[166:169], v[216:219], v[8:11]
	v_mfma_f32_16x16x32_bf16 v[60:63], v[162:165], v[196:199], v[60:63]
	v_mfma_f32_16x16x32_bf16 v[56:59], v[170:173], v[196:199], v[56:59]
	v_mfma_f32_16x16x32_bf16 v[44:47], v[162:165], v[204:207], v[44:47]
	v_mfma_f32_16x16x32_bf16 v[40:43], v[170:173], v[204:207], v[40:43]
	v_mfma_f32_16x16x32_bf16 v[28:31], v[162:165], v[212:215], v[28:31]
	v_mfma_f32_16x16x32_bf16 v[24:27], v[170:173], v[212:215], v[24:27]
	v_mfma_f32_16x16x32_bf16 v[12:15], v[162:165], v[220:223], v[12:15]
	v_mfma_f32_16x16x32_bf16 v[8:11], v[170:173], v[220:223], v[8:11]
	v_mfma_f32_16x16x32_bf16 v[52:55], v[174:177], v[190:193], v[52:55]
	v_mfma_f32_16x16x32_bf16 v[48:51], v[182:185], v[190:193], v[48:51]
	v_mfma_f32_16x16x32_bf16 v[36:39], v[174:177], v[200:203], v[36:39]
	v_mfma_f32_16x16x32_bf16 v[32:35], v[182:185], v[200:203], v[32:35]
	v_mfma_f32_16x16x32_bf16 v[20:23], v[174:177], v[208:211], v[20:23]
	v_mfma_f32_16x16x32_bf16 v[16:19], v[182:185], v[208:211], v[16:19]
	v_mfma_f32_16x16x32_bf16 v[4:7], v[174:177], v[216:219], v[4:7]
	v_mfma_f32_16x16x32_bf16 v[0:3], v[182:185], v[216:219], v[0:3]
	v_mfma_f32_16x16x32_bf16 v[52:55], v[178:181], v[196:199], v[52:55]
	v_mfma_f32_16x16x32_bf16 v[48:51], v[186:189], v[196:199], v[48:51]
	v_mfma_f32_16x16x32_bf16 v[36:39], v[178:181], v[204:207], v[36:39]
	v_mfma_f32_16x16x32_bf16 v[32:35], v[186:189], v[204:207], v[32:35]
	v_mfma_f32_16x16x32_bf16 v[20:23], v[178:181], v[212:215], v[20:23]
	v_mfma_f32_16x16x32_bf16 v[16:19], v[186:189], v[212:215], v[16:19]
	v_mfma_f32_16x16x32_bf16 v[4:7], v[178:181], v[220:223], v[4:7]
	v_mfma_f32_16x16x32_bf16 v[0:3], v[186:189], v[220:223], v[0:3]
	s_setprio 0
	s_waitcnt vmcnt(8)
	s_barrier
	s_add_i32 s81, 0, 0x18000
	v_add_u32_e32 v161, s81, v156
	s_add_i32 s82, 0, 0x1c000
	ds_read_b128 v[150:153], v161
	ds_read_b128 v[162:165], v161 offset:1024
	ds_read_b128 v[166:169], v161 offset:2048
	ds_read_b128 v[170:173], v161 offset:3072
	v_add_u32_e32 v161, s82, v156
	ds_read_b128 v[174:177], v161
	ds_read_b128 v[178:181], v161 offset:1024
	ds_read_b128 v[182:185], v161 offset:2048
	ds_read_b128 v[186:189], v161 offset:3072
	s_add_u32 s52, s52, 0x2b0000
	s_addc_u32 s53, s53, 0
	s_mov_b32 m0, s57
	v_lshl_add_u64 v[230:231], s[52:53], 0, v[128:129]
	ds_read_b128 v[190:193], v160 offset:32768
	ds_read_b128 v[196:199], v160 offset:33792
	ds_read_b128 v[200:203], v160 offset:34816
	ds_read_b128 v[204:207], v160 offset:35840
	ds_read_b128 v[208:211], v160 offset:36864
	ds_read_b128 v[212:215], v160 offset:37888
	ds_read_b128 v[216:219], v160 offset:38912
	ds_read_b128 v[220:223], v160 offset:39936
	global_load_lds_dwordx4 v[230:231], off
	v_lshl_add_u64 v[230:231], s[52:53], 0, v[134:135]
	s_mov_b32 m0, s58
	s_nop 0
	global_load_lds_dwordx4 v[230:231], off
	s_waitcnt lgkmcnt(0)
	s_setprio 1
	v_mfma_f32_16x16x32_bf16 v[124:127], v[150:153], v[190:193], v[124:127]
	v_mfma_f32_16x16x32_bf16 v[120:123], v[166:169], v[190:193], v[120:123]
	v_mfma_f32_16x16x32_bf16 v[108:111], v[150:153], v[200:203], v[108:111]
	v_mfma_f32_16x16x32_bf16 v[104:107], v[166:169], v[200:203], v[104:107]
	v_mfma_f32_16x16x32_bf16 v[92:95], v[150:153], v[208:211], v[92:95]
	v_mfma_f32_16x16x32_bf16 v[88:91], v[166:169], v[208:211], v[88:91]
	v_mfma_f32_16x16x32_bf16 v[76:79], v[150:153], v[216:219], v[76:79]
	v_mfma_f32_16x16x32_bf16 v[72:75], v[166:169], v[216:219], v[72:75]
	v_mfma_f32_16x16x32_bf16 v[124:127], v[162:165], v[196:199], v[124:127]
	v_mfma_f32_16x16x32_bf16 v[120:123], v[170:173], v[196:199], v[120:123]
	v_mfma_f32_16x16x32_bf16 v[108:111], v[162:165], v[204:207], v[108:111]
	v_mfma_f32_16x16x32_bf16 v[104:107], v[170:173], v[204:207], v[104:107]
	v_mfma_f32_16x16x32_bf16 v[92:95], v[162:165], v[212:215], v[92:95]
	v_mfma_f32_16x16x32_bf16 v[88:91], v[170:173], v[212:215], v[88:91]
	v_mfma_f32_16x16x32_bf16 v[76:79], v[162:165], v[220:223], v[76:79]
	v_mfma_f32_16x16x32_bf16 v[72:75], v[170:173], v[220:223], v[72:75]
	v_mfma_f32_16x16x32_bf16 v[116:119], v[174:177], v[190:193], v[116:119]
	v_mfma_f32_16x16x32_bf16 v[112:115], v[182:185], v[190:193], v[112:115]
	v_mfma_f32_16x16x32_bf16 v[100:103], v[174:177], v[200:203], v[100:103]
	v_mfma_f32_16x16x32_bf16 v[96:99], v[182:185], v[200:203], v[96:99]
	v_mfma_f32_16x16x32_bf16 v[84:87], v[174:177], v[208:211], v[84:87]
	v_mfma_f32_16x16x32_bf16 v[80:83], v[182:185], v[208:211], v[80:83]
	v_mfma_f32_16x16x32_bf16 v[68:71], v[174:177], v[216:219], v[68:71]
	v_mfma_f32_16x16x32_bf16 v[64:67], v[182:185], v[216:219], v[64:67]
	v_mfma_f32_16x16x32_bf16 v[116:119], v[178:181], v[196:199], v[116:119]
	v_mfma_f32_16x16x32_bf16 v[112:115], v[186:189], v[196:199], v[112:115]
	v_mfma_f32_16x16x32_bf16 v[100:103], v[178:181], v[204:207], v[100:103]
	v_mfma_f32_16x16x32_bf16 v[96:99], v[186:189], v[204:207], v[96:99]
	v_mfma_f32_16x16x32_bf16 v[84:87], v[178:181], v[212:215], v[84:87]
	v_mfma_f32_16x16x32_bf16 v[80:83], v[186:189], v[212:215], v[80:83]
	v_mfma_f32_16x16x32_bf16 v[68:71], v[178:181], v[220:223], v[68:71]
	v_mfma_f32_16x16x32_bf16 v[64:67], v[186:189], v[220:223], v[64:67]
	s_setprio 0
	s_waitcnt vmcnt(8)
	s_barrier
	s_add_i32 s52, s81, s54
	v_lshl_add_u64 v[154:155], v[154:155], 0, s[14:15]
	s_mov_b32 m0, s52
	ds_read_b128 v[190:193], v160 offset:49152
	ds_read_b128 v[196:199], v160 offset:50176
	ds_read_b128 v[200:203], v160 offset:51200
	ds_read_b128 v[204:207], v160 offset:52224
	ds_read_b128 v[208:211], v160 offset:53248
	ds_read_b128 v[212:215], v160 offset:54272
	ds_read_b128 v[216:219], v160 offset:55296
	ds_read_b128 v[220:223], v160 offset:56320
	global_load_lds_dwordx4 v[154:155], off
	s_add_i32 m0, s52, 0x2000
	s_add_u32 s48, s48, 0x2b0080
	v_lshl_add_u64 v[154:155], v[224:225], 0, s[14:15]
	s_addc_u32 s49, s49, 0
	s_add_i32 s52, s82, s54
	global_load_lds_dwordx4 v[154:155], off
	v_lshl_add_u64 v[154:155], s[48:49], 0, v[132:133]
	s_mov_b32 m0, s52
	s_nop 0
	global_load_lds_dwordx4 v[154:155], off
	v_lshl_add_u64 v[154:155], s[48:49], 0, v[136:137]
	s_add_i32 m0, s52, 0x2000
	s_nop 0
	global_load_lds_dwordx4 v[154:155], off
	v_lshl_add_u64 v[154:155], v[226:227], 0, s[14:15]
	s_mov_b32 m0, s62
	s_nop 0
	global_load_lds_dwordx4 v[154:155], off
	v_lshl_add_u64 v[154:155], v[228:229], 0, s[14:15]
	s_mov_b32 m0, s63
	s_nop 0
	global_load_lds_dwordx4 v[154:155], off
	s_waitcnt lgkmcnt(0)
	s_setprio 1
	v_mfma_f32_16x16x32_bf16 v[60:63], v[150:153], v[190:193], v[60:63]
	v_mfma_f32_16x16x32_bf16 v[56:59], v[166:169], v[190:193], v[56:59]
	v_mfma_f32_16x16x32_bf16 v[44:47], v[150:153], v[200:203], v[44:47]
	v_mfma_f32_16x16x32_bf16 v[40:43], v[166:169], v[200:203], v[40:43]
	v_mfma_f32_16x16x32_bf16 v[28:31], v[150:153], v[208:211], v[28:31]
	v_mfma_f32_16x16x32_bf16 v[24:27], v[166:169], v[208:211], v[24:27]
	v_mfma_f32_16x16x32_bf16 v[12:15], v[150:153], v[216:219], v[12:15]
	v_mfma_f32_16x16x32_bf16 v[8:11], v[166:169], v[216:219], v[8:11]
	v_mfma_f32_16x16x32_bf16 v[60:63], v[162:165], v[196:199], v[60:63]
	v_mfma_f32_16x16x32_bf16 v[56:59], v[170:173], v[196:199], v[56:59]
	v_mfma_f32_16x16x32_bf16 v[44:47], v[162:165], v[204:207], v[44:47]
	v_mfma_f32_16x16x32_bf16 v[40:43], v[170:173], v[204:207], v[40:43]
	v_mfma_f32_16x16x32_bf16 v[28:31], v[162:165], v[212:215], v[28:31]
	v_mfma_f32_16x16x32_bf16 v[24:27], v[170:173], v[212:215], v[24:27]
	v_mfma_f32_16x16x32_bf16 v[12:15], v[162:165], v[220:223], v[12:15]
	v_mfma_f32_16x16x32_bf16 v[8:11], v[170:173], v[220:223], v[8:11]
	v_mfma_f32_16x16x32_bf16 v[52:55], v[174:177], v[190:193], v[52:55]
	v_mfma_f32_16x16x32_bf16 v[48:51], v[182:185], v[190:193], v[48:51]
	v_mfma_f32_16x16x32_bf16 v[36:39], v[174:177], v[200:203], v[36:39]
	v_mfma_f32_16x16x32_bf16 v[32:35], v[182:185], v[200:203], v[32:35]
	v_mfma_f32_16x16x32_bf16 v[20:23], v[174:177], v[208:211], v[20:23]
	v_mfma_f32_16x16x32_bf16 v[16:19], v[182:185], v[208:211], v[16:19]
	v_mfma_f32_16x16x32_bf16 v[4:7], v[174:177], v[216:219], v[4:7]
	v_mfma_f32_16x16x32_bf16 v[0:3], v[182:185], v[216:219], v[0:3]
	v_mfma_f32_16x16x32_bf16 v[52:55], v[178:181], v[196:199], v[52:55]
	v_mfma_f32_16x16x32_bf16 v[48:51], v[186:189], v[196:199], v[48:51]
	v_mfma_f32_16x16x32_bf16 v[36:39], v[178:181], v[204:207], v[36:39]
	v_mfma_f32_16x16x32_bf16 v[32:35], v[186:189], v[204:207], v[32:35]
	v_mfma_f32_16x16x32_bf16 v[20:23], v[178:181], v[212:215], v[20:23]
	v_mfma_f32_16x16x32_bf16 v[16:19], v[186:189], v[212:215], v[16:19]
	v_mfma_f32_16x16x32_bf16 v[4:7], v[178:181], v[220:223], v[4:7]
	v_mfma_f32_16x16x32_bf16 v[0:3], v[186:189], v[220:223], v[0:3]
	s_setprio 0
	s_waitcnt vmcnt(8)
	s_barrier
	s_add_u32 s50, s50, 0x100
	s_addc_u32 s51, s51, 0
	s_add_u32 s78, s78, 0x100
	s_addc_u32 s79, s79, 0
	s_cmp_ge_i32 s80, s76
	s_mov_b32 s48, s80
	s_cbranch_scc0 .Lkt_L_17
	s_branch .Lkt_exit_17
.Lkt_T_17:
	ds_read_b128 v[150:153], v158
	ds_read_b128 v[162:165], v158 offset:1024
	ds_read_b128 v[166:169], v158 offset:2048
	ds_read_b128 v[170:173], v158 offset:3072
	ds_read_b128 v[174:177], v159
	ds_read_b128 v[178:181], v159 offset:1024
	ds_read_b128 v[182:185], v159 offset:2048
	ds_read_b128 v[186:189], v159 offset:3072
	s_add_i32 s80, s48, 2
	s_add_u32 s49, s50, 0xffd50080
	s_addc_u32 s52, s51, -1
	s_cmp_eq_u32 s43, s48
	s_cselect_b32 s48, s46, s78
	s_cselect_b32 s53, s5, s52
	s_cselect_b32 s52, s4, s49
	s_cselect_b32 s49, s47, s79
	v_lshl_add_u64 v[154:155], s[50:51], 0, v[138:139]
	s_add_i32 m0, s55, 0xc000
	ds_read_b128 v[190:193], v160
	ds_read_b128 v[196:199], v160 offset:1024
	ds_read_b128 v[200:203], v160 offset:2048
	ds_read_b128 v[204:207], v160 offset:3072
	ds_read_b128 v[208:211], v160 offset:4096
	ds_read_b128 v[212:215], v160 offset:5120
	ds_read_b128 v[216:219], v160 offset:6144
	ds_read_b128 v[220:223], v160 offset:7168
	global_load_lds_dwordx4 v[154:155], off
	v_lshl_add_u64 v[154:155], s[50:51], 0, v[140:141]
	s_add_i32 m0, s55, 0xe000
	s_nop 0
	global_load_lds_dwordx4 v[154:155], off
	s_waitcnt vmcnt(8)
	s_waitcnt lgkmcnt(0)
	s_barrier
	s_setprio 2
	v_mfma_f32_16x16x32_bf16 v[124:127], v[150:153], v[190:193], v[124:127]
	v_mfma_f32_16x16x32_bf16 v[120:123], v[166:169], v[190:193], v[120:123]
	v_mfma_f32_16x16x32_bf16 v[108:111], v[150:153], v[200:203], v[108:111]
	v_mfma_f32_16x16x32_bf16 v[104:107], v[166:169], v[200:203], v[104:107]
	v_mfma_f32_16x16x32_bf16 v[92:95], v[150:153], v[208:211], v[92:95]
	v_mfma_f32_16x16x32_bf16 v[88:91], v[166:169], v[208:211], v[88:91]
	v_mfma_f32_16x16x32_bf16 v[76:79], v[150:153], v[216:219], v[76:79]
	v_mfma_f32_16x16x32_bf16 v[72:75], v[166:169], v[216:219], v[72:75]
	v_mfma_f32_16x16x32_bf16 v[124:127], v[162:165], v[196:199], v[124:127]
	v_mfma_f32_16x16x32_bf16 v[120:123], v[170:173], v[196:199], v[120:123]
	v_mfma_f32_16x16x32_bf16 v[108:111], v[162:165], v[204:207], v[108:111]
	v_mfma_f32_16x16x32_bf16 v[104:107], v[170:173], v[204:207], v[104:107]
	v_mfma_f32_16x16x32_bf16 v[92:95], v[162:165], v[212:215], v[92:95]
	v_mfma_f32_16x16x32_bf16 v[88:91], v[170:173], v[212:215], v[88:91]
	v_mfma_f32_16x16x32_bf16 v[76:79], v[162:165], v[220:223], v[76:79]
	v_mfma_f32_16x16x32_bf16 v[72:75], v[170:173], v[220:223], v[72:75]
	v_mfma_f32_16x16x32_bf16 v[116:119], v[174:177], v[190:193], v[116:119]
	v_mfma_f32_16x16x32_bf16 v[112:115], v[182:185], v[190:193], v[112:115]
	v_mfma_f32_16x16x32_bf16 v[100:103], v[174:177], v[200:203], v[100:103]
	v_mfma_f32_16x16x32_bf16 v[96:99], v[182:185], v[200:203], v[96:99]
	v_mfma_f32_16x16x32_bf16 v[84:87], v[174:177], v[208:211], v[84:87]
	v_mfma_f32_16x16x32_bf16 v[80:83], v[182:185], v[208:211], v[80:83]
	v_mfma_f32_16x16x32_bf16 v[68:71], v[174:177], v[216:219], v[68:71]
	v_mfma_f32_16x16x32_bf16 v[64:67], v[182:185], v[216:219], v[64:67]
	v_mfma_f32_16x16x32_bf16 v[116:119], v[178:181], v[196:199], v[116:119]
	v_mfma_f32_16x16x32_bf16 v[112:115], v[186:189], v[196:199], v[112:115]
	v_mfma_f32_16x16x32_bf16 v[100:103], v[178:181], v[204:207], v[100:103]
	v_mfma_f32_16x16x32_bf16 v[96:99], v[186:189], v[204:207], v[96:99]
	v_mfma_f32_16x16x32_bf16 v[84:87], v[178:181], v[212:215], v[84:87]
	v_mfma_f32_16x16x32_bf16 v[80:83], v[186:189], v[212:215], v[80:83]
	v_mfma_f32_16x16x32_bf16 v[68:71], v[178:181], v[220:223], v[68:71]
	v_mfma_f32_16x16x32_bf16 v[64:67], v[186:189], v[220:223], v[64:67]
	s_setprio 0
	s_add_i32 s81, s65, s54
	v_lshl_add_u64 v[154:155], s[48:49], 0, v[132:133]
	s_mov_b32 m0, s81
	ds_read_b128 v[190:193], v160 offset:16384
	ds_read_b128 v[196:199], v160 offset:17408
	ds_read_b128 v[200:203], v160 offset:18432
	ds_read_b128 v[204:207], v160 offset:19456
	ds_read_b128 v[208:211], v160 offset:20480
	ds_read_b128 v[212:215], v160 offset:21504
	ds_read_b128 v[216:219], v160 offset:22528
	ds_read_b128 v[220:223], v160 offset:23552
	global_load_lds_dwordx4 v[154:155], off
	s_add_i32 m0, s81, 0x2000
	s_add_u32 s82, s48, 0x2b0000
	v_lshl_add_u64 v[224:225], s[48:49], 0, v[136:137]
	s_addc_u32 s83, s49, 0
	s_add_i32 s81, s66, s54
	global_load_lds_dwordx4 v[224:225], off
	v_lshl_add_u64 v[226:227], s[82:83], 0, v[132:133]
	s_mov_b32 m0, s81
	v_lshl_add_u64 v[228:229], s[52:53], 0, v[134:135]
	global_load_lds_dwordx4 v[226:227], off
	v_lshl_add_u64 v[226:227], s[82:83], 0, v[136:137]
	s_add_i32 m0, s81, 0x2000
	s_nop 0
	global_load_lds_dwordx4 v[226:227], off
	v_lshl_add_u64 v[226:227], s[52:53], 0, v[128:129]
	s_mov_b32 m0, s55
	s_nop 0
	global_load_lds_dwordx4 v[226:227], off
	s_mov_b32 m0, s56
	s_nop 0
	global_load_lds_dwordx4 v[228:229], off
	s_waitcnt vmcnt(8)
	s_waitcnt lgkmcnt(0)
	s_barrier
	s_setprio 2
	v_mfma_f32_16x16x32_bf16 v[60:63], v[150:153], v[190:193], v[60:63]
	v_mfma_f32_16x16x32_bf16 v[56:59], v[166:169], v[190:193], v[56:59]
	v_mfma_f32_16x16x32_bf16 v[44:47], v[150:153], v[200:203], v[44:47]
	v_mfma_f32_16x16x32_bf16 v[40:43], v[166:169], v[200:203], v[40:43]
	v_mfma_f32_16x16x32_bf16 v[28:31], v[150:153], v[208:211], v[28:31]
	v_mfma_f32_16x16x32_bf16 v[24:27], v[166:169], v[208:211], v[24:27]
	v_mfma_f32_16x16x32_bf16 v[12:15], v[150:153], v[216:219], v[12:15]
	v_mfma_f32_16x16x32_bf16 v[8:11], v[166:169], v[216:219], v[8:11]
	v_mfma_f32_16x16x32_bf16 v[60:63], v[162:165], v[196:199], v[60:63]
	v_mfma_f32_16x16x32_bf16 v[56:59], v[170:173], v[196:199], v[56:59]
	v_mfma_f32_16x16x32_bf16 v[44:47], v[162:165], v[204:207], v[44:47]
	v_mfma_f32_16x16x32_bf16 v[40:43], v[170:173], v[204:207], v[40:43]
	v_mfma_f32_16x16x32_bf16 v[28:31], v[162:165], v[212:215], v[28:31]
	v_mfma_f32_16x16x32_bf16 v[24:27], v[170:173], v[212:215], v[24:27]
	v_mfma_f32_16x16x32_bf16 v[12:15], v[162:165], v[220:223], v[12:15]
	v_mfma_f32_16x16x32_bf16 v[8:11], v[170:173], v[220:223], v[8:11]
	v_mfma_f32_16x16x32_bf16 v[52:55], v[174:177], v[190:193], v[52:55]
	v_mfma_f32_16x16x32_bf16 v[48:51], v[182:185], v[190:193], v[48:51]
	v_mfma_f32_16x16x32_bf16 v[36:39], v[174:177], v[200:203], v[36:39]
	v_mfma_f32_16x16x32_bf16 v[32:35], v[182:185], v[200:203], v[32:35]
	v_mfma_f32_16x16x32_bf16 v[20:23], v[174:177], v[208:211], v[20:23]
	v_mfma_f32_16x16x32_bf16 v[16:19], v[182:185], v[208:211], v[16:19]
	v_mfma_f32_16x16x32_bf16 v[4:7], v[174:177], v[216:219], v[4:7]
	v_mfma_f32_16x16x32_bf16 v[0:3], v[182:185], v[216:219], v[0:3]
	v_mfma_f32_16x16x32_bf16 v[52:55], v[178:181], v[196:199], v[52:55]
	v_mfma_f32_16x16x32_bf16 v[48:51], v[186:189], v[196:199], v[48:51]
	v_mfma_f32_16x16x32_bf16 v[36:39], v[178:181], v[204:207], v[36:39]
	v_mfma_f32_16x16x32_bf16 v[32:35], v[186:189], v[204:207], v[32:35]
	v_mfma_f32_16x16x32_bf16 v[20:23], v[178:181], v[212:215], v[20:23]
	v_mfma_f32_16x16x32_bf16 v[16:19], v[186:189], v[212:215], v[16:19]
	v_mfma_f32_16x16x32_bf16 v[4:7], v[178:181], v[220:223], v[4:7]
	v_mfma_f32_16x16x32_bf16 v[0:3], v[186:189], v[220:223], v[0:3]
	s_setprio 0
	s_add_i32 s81, 0, 0x18000
	v_add_u32_e32 v161, s81, v156
	s_add_i32 s82, 0, 0x1c000
	ds_read_b128 v[150:153], v161
	ds_read_b128 v[162:165], v161 offset:1024
	ds_read_b128 v[166:169], v161 offset:2048
	ds_read_b128 v[170:173], v161 offset:3072
	v_add_u32_e32 v161, s82, v156
	ds_read_b128 v[174:177], v161
	ds_read_b128 v[178:181], v161 offset:1024
	ds_read_b128 v[182:185], v161 offset:2048
	ds_read_b128 v[186:189], v161 offset:3072
	s_add_u32 s52, s52, 0x2b0000
	s_addc_u32 s53, s53, 0
	s_mov_b32 m0, s57
	v_lshl_add_u64 v[230:231], s[52:53], 0, v[128:129]
	ds_read_b128 v[190:193], v160 offset:32768
	ds_read_b128 v[196:199], v160 offset:33792
	ds_read_b128 v[200:203], v160 offset:34816
	ds_read_b128 v[204:207], v160 offset:35840
	ds_read_b128 v[208:211], v160 offset:36864
	ds_read_b128 v[212:215], v160 offset:37888
	ds_read_b128 v[216:219], v160 offset:38912
	ds_read_b128 v[220:223], v160 offset:39936
	global_load_lds_dwordx4 v[230:231], off
	v_lshl_add_u64 v[230:231], s[52:53], 0, v[134:135]
	s_mov_b32 m0, s58
	s_nop 0
	global_load_lds_dwordx4 v[230:231], off
	s_waitcnt vmcnt(8)
	s_waitcnt lgkmcnt(0)
	s_barrier
	s_setprio 2
	v_mfma_f32_16x16x32_bf16 v[124:127], v[150:153], v[190:193], v[124:127]
	v_mfma_f32_16x16x32_bf16 v[120:123], v[166:169], v[190:193], v[120:123]
	v_mfma_f32_16x16x32_bf16 v[108:111], v[150:153], v[200:203], v[108:111]
	v_mfma_f32_16x16x32_bf16 v[104:107], v[166:169], v[200:203], v[104:107]
	v_mfma_f32_16x16x32_bf16 v[92:95], v[150:153], v[208:211], v[92:95]
	v_mfma_f32_16x16x32_bf16 v[88:91], v[166:169], v[208:211], v[88:91]
	v_mfma_f32_16x16x32_bf16 v[76:79], v[150:153], v[216:219], v[76:79]
	v_mfma_f32_16x16x32_bf16 v[72:75], v[166:169], v[216:219], v[72:75]
	v_mfma_f32_16x16x32_bf16 v[124:127], v[162:165], v[196:199], v[124:127]
	v_mfma_f32_16x16x32_bf16 v[120:123], v[170:173], v[196:199], v[120:123]
	v_mfma_f32_16x16x32_bf16 v[108:111], v[162:165], v[204:207], v[108:111]
	v_mfma_f32_16x16x32_bf16 v[104:107], v[170:173], v[204:207], v[104:107]
	v_mfma_f32_16x16x32_bf16 v[92:95], v[162:165], v[212:215], v[92:95]
	v_mfma_f32_16x16x32_bf16 v[88:91], v[170:173], v[212:215], v[88:91]
	v_mfma_f32_16x16x32_bf16 v[76:79], v[162:165], v[220:223], v[76:79]
	v_mfma_f32_16x16x32_bf16 v[72:75], v[170:173], v[220:223], v[72:75]
	v_mfma_f32_16x16x32_bf16 v[116:119], v[174:177], v[190:193], v[116:119]
	v_mfma_f32_16x16x32_bf16 v[112:115], v[182:185], v[190:193], v[112:115]
	v_mfma_f32_16x16x32_bf16 v[100:103], v[174:177], v[200:203], v[100:103]
	v_mfma_f32_16x16x32_bf16 v[96:99], v[182:185], v[200:203], v[96:99]
	v_mfma_f32_16x16x32_bf16 v[84:87], v[174:177], v[208:211], v[84:87]
	v_mfma_f32_16x16x32_bf16 v[80:83], v[182:185], v[208:211], v[80:83]
	v_mfma_f32_16x16x32_bf16 v[68:71], v[174:177], v[216:219], v[68:71]
	v_mfma_f32_16x16x32_bf16 v[64:67], v[182:185], v[216:219], v[64:67]
	v_mfma_f32_16x16x32_bf16 v[116:119], v[178:181], v[196:199], v[116:119]
	v_mfma_f32_16x16x32_bf16 v[112:115], v[186:189], v[196:199], v[112:115]
	v_mfma_f32_16x16x32_bf16 v[100:103], v[178:181], v[204:207], v[100:103]
	v_mfma_f32_16x16x32_bf16 v[96:99], v[186:189], v[204:207], v[96:99]
	v_mfma_f32_16x16x32_bf16 v[84:87], v[178:181], v[212:215], v[84:87]
	v_mfma_f32_16x16x32_bf16 v[80:83], v[186:189], v[212:215], v[80:83]
	v_mfma_f32_16x16x32_bf16 v[68:71], v[178:181], v[220:223], v[68:71]
	v_mfma_f32_16x16x32_bf16 v[64:67], v[186:189], v[220:223], v[64:67]
	s_setprio 0
	s_add_i32 s52, s81, s54
	v_lshl_add_u64 v[154:155], v[154:155], 0, s[14:15]
	s_mov_b32 m0, s52
	ds_read_b128 v[190:193], v160 offset:49152
	ds_read_b128 v[196:199], v160 offset:50176
	ds_read_b128 v[200:203], v160 offset:51200
	ds_read_b128 v[204:207], v160 offset:52224
	ds_read_b128 v[208:211], v160 offset:53248
	ds_read_b128 v[212:215], v160 offset:54272
	ds_read_b128 v[216:219], v160 offset:55296
	ds_read_b128 v[220:223], v160 offset:56320
	global_load_lds_dwordx4 v[154:155], off
	s_add_i32 m0, s52, 0x2000
	s_add_u32 s48, s48, 0x2b0080
	v_lshl_add_u64 v[154:155], v[224:225], 0, s[14:15]
	s_addc_u32 s49, s49, 0
	s_add_i32 s52, s82, s54
	global_load_lds_dwordx4 v[154:155], off
	v_lshl_add_u64 v[154:155], s[48:49], 0, v[132:133]
	s_mov_b32 m0, s52
	s_nop 0
	global_load_lds_dwordx4 v[154:155], off
	v_lshl_add_u64 v[154:155], s[48:49], 0, v[136:137]
	s_add_i32 m0, s52, 0x2000
	s_nop 0
	global_load_lds_dwordx4 v[154:155], off
	v_lshl_add_u64 v[154:155], v[226:227], 0, s[14:15]
	s_mov_b32 m0, s62
	s_nop 0
	global_load_lds_dwordx4 v[154:155], off
	v_lshl_add_u64 v[154:155], v[228:229], 0, s[14:15]
	s_mov_b32 m0, s63
	s_nop 0
	global_load_lds_dwordx4 v[154:155], off
	s_waitcnt vmcnt(8)
	s_waitcnt lgkmcnt(0)
	s_barrier
	s_setprio 2
	v_mfma_f32_16x16x32_bf16 v[60:63], v[150:153], v[190:193], v[60:63]
	v_mfma_f32_16x16x32_bf16 v[56:59], v[166:169], v[190:193], v[56:59]
	v_mfma_f32_16x16x32_bf16 v[44:47], v[150:153], v[200:203], v[44:47]
	v_mfma_f32_16x16x32_bf16 v[40:43], v[166:169], v[200:203], v[40:43]
	v_mfma_f32_16x16x32_bf16 v[28:31], v[150:153], v[208:211], v[28:31]
	v_mfma_f32_16x16x32_bf16 v[24:27], v[166:169], v[208:211], v[24:27]
	v_mfma_f32_16x16x32_bf16 v[12:15], v[150:153], v[216:219], v[12:15]
	v_mfma_f32_16x16x32_bf16 v[8:11], v[166:169], v[216:219], v[8:11]
	v_mfma_f32_16x16x32_bf16 v[60:63], v[162:165], v[196:199], v[60:63]
	v_mfma_f32_16x16x32_bf16 v[56:59], v[170:173], v[196:199], v[56:59]
	v_mfma_f32_16x16x32_bf16 v[44:47], v[162:165], v[204:207], v[44:47]
	v_mfma_f32_16x16x32_bf16 v[40:43], v[170:173], v[204:207], v[40:43]
	v_mfma_f32_16x16x32_bf16 v[28:31], v[162:165], v[212:215], v[28:31]
	v_mfma_f32_16x16x32_bf16 v[24:27], v[170:173], v[212:215], v[24:27]
	v_mfma_f32_16x16x32_bf16 v[12:15], v[162:165], v[220:223], v[12:15]
	v_mfma_f32_16x16x32_bf16 v[8:11], v[170:173], v[220:223], v[8:11]
	v_mfma_f32_16x16x32_bf16 v[52:55], v[174:177], v[190:193], v[52:55]
	v_mfma_f32_16x16x32_bf16 v[48:51], v[182:185], v[190:193], v[48:51]
	v_mfma_f32_16x16x32_bf16 v[36:39], v[174:177], v[200:203], v[36:39]
	v_mfma_f32_16x16x32_bf16 v[32:35], v[182:185], v[200:203], v[32:35]
	v_mfma_f32_16x16x32_bf16 v[20:23], v[174:177], v[208:211], v[20:23]
	v_mfma_f32_16x16x32_bf16 v[16:19], v[182:185], v[208:211], v[16:19]
	v_mfma_f32_16x16x32_bf16 v[4:7], v[174:177], v[216:219], v[4:7]
	v_mfma_f32_16x16x32_bf16 v[0:3], v[182:185], v[216:219], v[0:3]
	v_mfma_f32_16x16x32_bf16 v[52:55], v[178:181], v[196:199], v[52:55]
	v_mfma_f32_16x16x32_bf16 v[48:51], v[186:189], v[196:199], v[48:51]
	v_mfma_f32_16x16x32_bf16 v[36:39], v[178:181], v[204:207], v[36:39]
	v_mfma_f32_16x16x32_bf16 v[32:35], v[186:189], v[204:207], v[32:35]
	v_mfma_f32_16x16x32_bf16 v[20:23], v[178:181], v[212:215], v[20:23]
	v_mfma_f32_16x16x32_bf16 v[16:19], v[186:189], v[212:215], v[16:19]
	v_mfma_f32_16x16x32_bf16 v[4:7], v[178:181], v[220:223], v[4:7]
	v_mfma_f32_16x16x32_bf16 v[0:3], v[186:189], v[220:223], v[0:3]
	s_setprio 0
	s_add_u32 s50, s50, 0x100
	s_addc_u32 s51, s51, 0
	s_add_u32 s78, s78, 0x100
	s_addc_u32 s79, s79, 0
	s_cmp_ge_i32 s80, s76
	s_mov_b32 s48, s80
	s_cbranch_scc0 .Lkt_T_17
	s_nop 7

.LBB0_4311:
	v_lshlrev_b64 v[150:151], 12, v[154:155]
	v_lshl_add_u64 v[150:151], v[150:151], 0, v[152:153]
	v_lshlrev_b64 v[150:151], 1, v[150:151]
	v_lshl_add_u64 v[166:167], s[12:13], 0, v[150:151]
	global_load_dwordx4 v[162:165], v[166:167], off
	s_nop 0
	global_load_dwordx4 v[166:169], v[166:167], off offset:256
	v_or_b32_e32 v170, 16, v154
	v_ashrrev_i32_e32 v171, 31, v170
	v_lshlrev_b64 v[170:171], 12, v[170:171]
	v_lshl_add_u64 v[170:171], v[170:171], 0, v[152:153]
	v_lshl_add_u64 v[172:173], s[10:11], 0, v[150:151]
	v_lshlrev_b64 v[170:171], 1, v[170:171]
	v_lshl_add_u64 v[174:175], s[12:13], 0, v[170:171]
	s_waitcnt vmcnt(0)
	v_lshlrev_b32_e32 v176, 16, v162
	v_and_b32_e32 v177, 0xffff0000, v162
	v_lshlrev_b32_e32 v162, 16, v163
	v_and_b32_e32 v163, 0xffff0000, v163
	v_lshlrev_b32_e32 v178, 16, v164
	v_and_b32_e32 v179, 0xffff0000, v164
	v_lshlrev_b32_e32 v164, 16, v165
	v_and_b32_e32 v165, 0xffff0000, v165
	v_lshlrev_b32_e32 v180, 16, v166
	v_and_b32_e32 v181, 0xffff0000, v166
	v_lshlrev_b32_e32 v166, 16, v167
	v_and_b32_e32 v167, 0xffff0000, v167
	v_lshlrev_b32_e32 v182, 16, v168
	v_and_b32_e32 v183, 0xffff0000, v168
	v_lshlrev_b32_e32 v168, 16, v169
	v_and_b32_e32 v169, 0xffff0000, v169
	v_pk_fma_f32 v[124:125], v[176:177], s[26:27], v[124:125] op_sel_hi:[1,0,1]
	v_pk_fma_f32 v[126:127], v[162:163], s[26:27], v[126:127] op_sel_hi:[1,0,1]
	v_pk_fma_f32 v[120:121], v[178:179], s[26:27], v[120:121] op_sel_hi:[1,0,1]
	v_pk_fma_f32 v[122:123], v[164:165], s[26:27], v[122:123] op_sel_hi:[1,0,1]
	v_pk_fma_f32 v[116:117], v[180:181], s[26:27], v[116:117] op_sel_hi:[1,0,1]
	v_pk_fma_f32 v[118:119], v[166:167], s[26:27], v[118:119] op_sel_hi:[1,0,1]
	v_pk_fma_f32 v[162:163], v[182:183], s[26:27], v[112:113] op_sel_hi:[1,0,1]
	v_pk_fma_f32 v[164:165], v[168:169], s[26:27], v[114:115] op_sel_hi:[1,0,1]
	v_cvt_pk_bf16_f32 v112, v124, v125
	v_cvt_pk_bf16_f32 v113, v126, v127
	v_cvt_pk_bf16_f32 v114, v120, v121
	v_cvt_pk_bf16_f32 v115, v122, v123
	v_cvt_pk_bf16_f32 v116, v116, v117
	v_cvt_pk_bf16_f32 v117, v118, v119
	v_cvt_pk_bf16_f32 v118, v162, v163
	v_cvt_pk_bf16_f32 v119, v164, v165
	global_store_dwordx4 v[172:173], v[112:115], off
	global_store_dwordx4 v[172:173], v[116:119], off offset:256
	global_load_dwordx4 v[112:115], v[174:175], off
	s_nop 0
	global_load_dwordx4 v[116:119], v[174:175], off offset:256
	v_or_b32_e32 v120, 32, v154
	v_ashrrev_i32_e32 v121, 31, v120
	v_lshlrev_b64 v[120:121], 12, v[120:121]
	v_lshl_add_u64 v[120:121], v[120:121], 0, v[152:153]
	v_lshlrev_b64 v[120:121], 1, v[120:121]
	v_lshl_add_u64 v[122:123], s[10:11], 0, v[170:171]
	v_lshl_add_u64 v[124:125], s[12:13], 0, v[120:121]
	s_waitcnt vmcnt(1)
	v_lshlrev_b32_e32 v126, 16, v112
	v_and_b32_e32 v127, 0xffff0000, v112
	v_lshlrev_b32_e32 v112, 16, v113
	v_and_b32_e32 v113, 0xffff0000, v113
	v_lshlrev_b32_e32 v162, 16, v114
	v_and_b32_e32 v163, 0xffff0000, v114
	v_lshlrev_b32_e32 v114, 16, v115
	v_and_b32_e32 v115, 0xffff0000, v115
	s_waitcnt vmcnt(0)
	v_lshlrev_b32_e32 v164, 16, v116
	v_and_b32_e32 v165, 0xffff0000, v116
	v_lshlrev_b32_e32 v116, 16, v117
	v_and_b32_e32 v117, 0xffff0000, v117
	v_lshlrev_b32_e32 v166, 16, v118
	v_and_b32_e32 v167, 0xffff0000, v118
	v_lshlrev_b32_e32 v118, 16, v119
	v_and_b32_e32 v119, 0xffff0000, v119
	v_pk_fma_f32 v[108:109], v[126:127], s[26:27], v[108:109] op_sel_hi:[1,0,1]
	v_pk_fma_f32 v[110:111], v[112:113], s[26:27], v[110:111] op_sel_hi:[1,0,1]
	v_pk_fma_f32 v[104:105], v[162:163], s[26:27], v[104:105] op_sel_hi:[1,0,1]
	v_pk_fma_f32 v[106:107], v[114:115], s[26:27], v[106:107] op_sel_hi:[1,0,1]
	v_pk_fma_f32 v[100:101], v[164:165], s[26:27], v[100:101] op_sel_hi:[1,0,1]
	v_pk_fma_f32 v[102:103], v[116:117], s[26:27], v[102:103] op_sel_hi:[1,0,1]
	v_pk_fma_f32 v[112:113], v[166:167], s[26:27], v[96:97] op_sel_hi:[1,0,1]
	v_pk_fma_f32 v[114:115], v[118:119], s[26:27], v[98:99] op_sel_hi:[1,0,1]
	v_cvt_pk_bf16_f32 v96, v108, v109
	v_cvt_pk_bf16_f32 v97, v110, v111
	v_cvt_pk_bf16_f32 v98, v104, v105
	v_cvt_pk_bf16_f32 v99, v106, v107
	v_cvt_pk_bf16_f32 v100, v100, v101
	v_cvt_pk_bf16_f32 v101, v102, v103
	v_cvt_pk_bf16_f32 v102, v112, v113
	v_cvt_pk_bf16_f32 v103, v114, v115
	global_store_dwordx4 v[122:123], v[96:99], off
	global_store_dwordx4 v[122:123], v[100:103], off offset:256
	global_load_dwordx4 v[96:99], v[124:125], off
	s_nop 0
	global_load_dwordx4 v[100:103], v[124:125], off offset:256
	v_or_b32_e32 v104, 48, v154
	v_ashrrev_i32_e32 v105, 31, v104
	v_lshlrev_b64 v[104:105], 12, v[104:105]
	v_lshl_add_u64 v[104:105], v[104:105], 0, v[152:153]
	v_lshlrev_b64 v[104:105], 1, v[104:105]
	v_lshl_add_u64 v[106:107], s[10:11], 0, v[120:121]
	v_lshl_add_u64 v[108:109], s[12:13], 0, v[104:105]
	s_waitcnt vmcnt(1)
	v_lshlrev_b32_e32 v110, 16, v96
	v_and_b32_e32 v111, 0xffff0000, v96
	v_lshlrev_b32_e32 v96, 16, v97
	v_and_b32_e32 v97, 0xffff0000, v97
	v_lshlrev_b32_e32 v112, 16, v98
	v_and_b32_e32 v113, 0xffff0000, v98
	v_lshlrev_b32_e32 v98, 16, v99
	v_and_b32_e32 v99, 0xffff0000, v99
	s_waitcnt vmcnt(0)
	v_lshlrev_b32_e32 v114, 16, v100
	v_and_b32_e32 v115, 0xffff0000, v100
	v_lshlrev_b32_e32 v100, 16, v101
	v_and_b32_e32 v101, 0xffff0000, v101
	v_lshlrev_b32_e32 v116, 16, v102
	v_and_b32_e32 v117, 0xffff0000, v102
	v_lshlrev_b32_e32 v102, 16, v103
	v_and_b32_e32 v103, 0xffff0000, v103
	v_pk_fma_f32 v[92:93], v[110:111], s[26:27], v[92:93] op_sel_hi:[1,0,1]
	v_pk_fma_f32 v[94:95], v[96:97], s[26:27], v[94:95] op_sel_hi:[1,0,1]
	v_pk_fma_f32 v[88:89], v[112:113], s[26:27], v[88:89] op_sel_hi:[1,0,1]
	v_pk_fma_f32 v[90:91], v[98:99], s[26:27], v[90:91] op_sel_hi:[1,0,1]
	v_pk_fma_f32 v[84:85], v[114:115], s[26:27], v[84:85] op_sel_hi:[1,0,1]
	v_pk_fma_f32 v[86:87], v[100:101], s[26:27], v[86:87] op_sel_hi:[1,0,1]
	v_pk_fma_f32 v[96:97], v[116:117], s[26:27], v[80:81] op_sel_hi:[1,0,1]
	v_pk_fma_f32 v[98:99], v[102:103], s[26:27], v[82:83] op_sel_hi:[1,0,1]
	v_cvt_pk_bf16_f32 v80, v92, v93
	v_cvt_pk_bf16_f32 v81, v94, v95
	v_cvt_pk_bf16_f32 v82, v88, v89
	v_cvt_pk_bf16_f32 v83, v90, v91
	v_cvt_pk_bf16_f32 v84, v84, v85
	v_cvt_pk_bf16_f32 v85, v86, v87
	v_cvt_pk_bf16_f32 v86, v96, v97
	v_cvt_pk_bf16_f32 v87, v98, v99
	global_store_dwordx4 v[106:107], v[80:83], off
	global_store_dwordx4 v[106:107], v[84:87], off offset:256
	global_load_dwordx4 v[80:83], v[108:109], off
	s_nop 0
	global_load_dwordx4 v[84:87], v[108:109], off offset:256
	v_lshl_add_u64 v[88:89], v[150:151], 0, s[28:29]
	v_lshl_add_u64 v[92:93], s[10:11], 0, v[104:105]
	v_lshl_add_u64 v[90:91], s[12:13], 0, v[88:89]
	s_waitcnt vmcnt(1)
	v_lshlrev_b32_e32 v94, 16, v80
	v_and_b32_e32 v95, 0xffff0000, v80
	v_lshlrev_b32_e32 v80, 16, v81
	v_and_b32_e32 v81, 0xffff0000, v81
	v_lshlrev_b32_e32 v96, 16, v82
	v_and_b32_e32 v97, 0xffff0000, v82
	v_lshlrev_b32_e32 v82, 16, v83
	v_and_b32_e32 v83, 0xffff0000, v83
	s_waitcnt vmcnt(0)
	v_lshlrev_b32_e32 v98, 16, v84
	v_and_b32_e32 v99, 0xffff0000, v84
	v_lshlrev_b32_e32 v84, 16, v85
	v_and_b32_e32 v85, 0xffff0000, v85
	v_lshlrev_b32_e32 v100, 16, v86
	v_and_b32_e32 v101, 0xffff0000, v86
	v_lshlrev_b32_e32 v86, 16, v87
	v_and_b32_e32 v87, 0xffff0000, v87
	v_pk_fma_f32 v[76:77], v[94:95], s[26:27], v[76:77] op_sel_hi:[1,0,1]
	v_pk_fma_f32 v[78:79], v[80:81], s[26:27], v[78:79] op_sel_hi:[1,0,1]
	v_pk_fma_f32 v[72:73], v[96:97], s[26:27], v[72:73] op_sel_hi:[1,0,1]
	v_pk_fma_f32 v[74:75], v[82:83], s[26:27], v[74:75] op_sel_hi:[1,0,1]
	v_pk_fma_f32 v[68:69], v[98:99], s[26:27], v[68:69] op_sel_hi:[1,0,1]
	v_pk_fma_f32 v[70:71], v[84:85], s[26:27], v[70:71] op_sel_hi:[1,0,1]
	v_pk_fma_f32 v[80:81], v[100:101], s[26:27], v[64:65] op_sel_hi:[1,0,1]
	v_pk_fma_f32 v[82:83], v[86:87], s[26:27], v[66:67] op_sel_hi:[1,0,1]
	v_cvt_pk_bf16_f32 v64, v76, v77
	v_cvt_pk_bf16_f32 v65, v78, v79
	v_cvt_pk_bf16_f32 v66, v72, v73
	v_cvt_pk_bf16_f32 v67, v74, v75
	v_cvt_pk_bf16_f32 v68, v68, v69
	v_cvt_pk_bf16_f32 v69, v70, v71
	v_cvt_pk_bf16_f32 v70, v80, v81
	v_cvt_pk_bf16_f32 v71, v82, v83
	global_store_dwordx4 v[92:93], v[64:67], off
	global_store_dwordx4 v[92:93], v[68:71], off offset:256
	global_load_dwordx4 v[64:67], v[90:91], off
	s_nop 0
	global_load_dwordx4 v[68:71], v[90:91], off offset:256
	v_lshl_add_u64 v[72:73], v[150:151], 0, s[30:31]
	v_lshl_add_u64 v[74:75], s[10:11], 0, v[88:89]
	v_lshl_add_u64 v[76:77], s[12:13], 0, v[72:73]
	s_waitcnt vmcnt(1)
	v_lshlrev_b32_e32 v78, 16, v64
	v_and_b32_e32 v79, 0xffff0000, v64
	v_lshlrev_b32_e32 v64, 16, v65
	v_and_b32_e32 v65, 0xffff0000, v65
	v_lshlrev_b32_e32 v80, 16, v66
	v_and_b32_e32 v81, 0xffff0000, v66
	v_lshlrev_b32_e32 v66, 16, v67
	v_and_b32_e32 v67, 0xffff0000, v67
	s_waitcnt vmcnt(0)
	v_lshlrev_b32_e32 v82, 16, v68
	v_and_b32_e32 v83, 0xffff0000, v68
	v_lshlrev_b32_e32 v68, 16, v69
	v_and_b32_e32 v69, 0xffff0000, v69
	v_lshlrev_b32_e32 v84, 16, v70
	v_and_b32_e32 v85, 0xffff0000, v70
	v_lshlrev_b32_e32 v70, 16, v71
	v_and_b32_e32 v71, 0xffff0000, v71
	v_pk_fma_f32 v[60:61], v[78:79], s[26:27], v[60:61] op_sel_hi:[1,0,1]
	v_pk_fma_f32 v[62:63], v[64:65], s[26:27], v[62:63] op_sel_hi:[1,0,1]
	v_pk_fma_f32 v[56:57], v[80:81], s[26:27], v[56:57] op_sel_hi:[1,0,1]
	v_pk_fma_f32 v[58:59], v[66:67], s[26:27], v[58:59] op_sel_hi:[1,0,1]
	v_pk_fma_f32 v[52:53], v[82:83], s[26:27], v[52:53] op_sel_hi:[1,0,1]
	v_pk_fma_f32 v[54:55], v[68:69], s[26:27], v[54:55] op_sel_hi:[1,0,1]
	v_pk_fma_f32 v[64:65], v[84:85], s[26:27], v[48:49] op_sel_hi:[1,0,1]
	v_pk_fma_f32 v[66:67], v[70:71], s[26:27], v[50:51] op_sel_hi:[1,0,1]
	v_cvt_pk_bf16_f32 v48, v60, v61
	v_cvt_pk_bf16_f32 v49, v62, v63
	v_cvt_pk_bf16_f32 v50, v56, v57
	v_cvt_pk_bf16_f32 v51, v58, v59
	v_cvt_pk_bf16_f32 v52, v52, v53
	v_cvt_pk_bf16_f32 v53, v54, v55
	v_cvt_pk_bf16_f32 v54, v64, v65
	v_cvt_pk_bf16_f32 v55, v66, v67
	global_store_dwordx4 v[74:75], v[48:51], off
	global_store_dwordx4 v[74:75], v[52:55], off offset:256
	global_load_dwordx4 v[48:51], v[76:77], off
	s_nop 0
	global_load_dwordx4 v[52:55], v[76:77], off offset:256
	v_lshl_add_u64 v[56:57], v[150:151], 0, s[34:35]
	v_lshl_add_u64 v[58:59], s[10:11], 0, v[72:73]
	v_lshl_add_u64 v[60:61], s[12:13], 0, v[56:57]
	s_waitcnt vmcnt(1)
	v_lshlrev_b32_e32 v62, 16, v48
	v_and_b32_e32 v63, 0xffff0000, v48
	v_lshlrev_b32_e32 v48, 16, v49
	v_and_b32_e32 v49, 0xffff0000, v49
	v_lshlrev_b32_e32 v64, 16, v50
	v_and_b32_e32 v65, 0xffff0000, v50
	v_lshlrev_b32_e32 v50, 16, v51
	v_and_b32_e32 v51, 0xffff0000, v51
	s_waitcnt vmcnt(0)
	v_lshlrev_b32_e32 v66, 16, v52
	v_and_b32_e32 v67, 0xffff0000, v52
	v_lshlrev_b32_e32 v52, 16, v53
	v_and_b32_e32 v53, 0xffff0000, v53
	v_lshlrev_b32_e32 v68, 16, v54
	v_and_b32_e32 v69, 0xffff0000, v54
	v_lshlrev_b32_e32 v54, 16, v55
	v_and_b32_e32 v55, 0xffff0000, v55
	v_pk_fma_f32 v[44:45], v[62:63], s[26:27], v[44:45] op_sel_hi:[1,0,1]
	v_pk_fma_f32 v[46:47], v[48:49], s[26:27], v[46:47] op_sel_hi:[1,0,1]
	v_pk_fma_f32 v[40:41], v[64:65], s[26:27], v[40:41] op_sel_hi:[1,0,1]
	v_pk_fma_f32 v[42:43], v[50:51], s[26:27], v[42:43] op_sel_hi:[1,0,1]
	v_pk_fma_f32 v[36:37], v[66:67], s[26:27], v[36:37] op_sel_hi:[1,0,1]
	v_pk_fma_f32 v[38:39], v[52:53], s[26:27], v[38:39] op_sel_hi:[1,0,1]
	v_pk_fma_f32 v[48:49], v[68:69], s[26:27], v[32:33] op_sel_hi:[1,0,1]
	v_pk_fma_f32 v[50:51], v[54:55], s[26:27], v[34:35] op_sel_hi:[1,0,1]
	v_cvt_pk_bf16_f32 v32, v44, v45
	v_cvt_pk_bf16_f32 v33, v46, v47
	v_cvt_pk_bf16_f32 v34, v40, v41
	v_cvt_pk_bf16_f32 v35, v42, v43
	v_cvt_pk_bf16_f32 v36, v36, v37
	v_cvt_pk_bf16_f32 v37, v38, v39
	v_cvt_pk_bf16_f32 v38, v48, v49
	v_cvt_pk_bf16_f32 v39, v50, v51
	global_store_dwordx4 v[58:59], v[32:35], off
	global_store_dwordx4 v[58:59], v[36:39], off offset:256
	global_load_dwordx4 v[32:35], v[60:61], off
	s_nop 0
	global_load_dwordx4 v[36:39], v[60:61], off offset:256
	v_lshl_add_u64 v[40:41], v[150:151], 0, s[40:41]
	v_lshl_add_u64 v[42:43], s[10:11], 0, v[56:57]
	v_lshl_add_u64 v[44:45], s[12:13], 0, v[40:41]
	s_waitcnt vmcnt(1)
	v_lshlrev_b32_e32 v46, 16, v32
	v_and_b32_e32 v47, 0xffff0000, v32
	v_lshlrev_b32_e32 v32, 16, v33
	v_and_b32_e32 v33, 0xffff0000, v33
	v_lshlrev_b32_e32 v48, 16, v34
	v_and_b32_e32 v49, 0xffff0000, v34
	v_lshlrev_b32_e32 v34, 16, v35
	v_and_b32_e32 v35, 0xffff0000, v35
	s_waitcnt vmcnt(0)
	v_lshlrev_b32_e32 v50, 16, v36
	v_and_b32_e32 v51, 0xffff0000, v36
	v_lshlrev_b32_e32 v36, 16, v37
	v_and_b32_e32 v37, 0xffff0000, v37
	v_lshlrev_b32_e32 v52, 16, v38
	v_and_b32_e32 v53, 0xffff0000, v38
	v_lshlrev_b32_e32 v38, 16, v39
	v_and_b32_e32 v39, 0xffff0000, v39
	v_pk_fma_f32 v[28:29], v[46:47], s[26:27], v[28:29] op_sel_hi:[1,0,1]
	v_pk_fma_f32 v[30:31], v[32:33], s[26:27], v[30:31] op_sel_hi:[1,0,1]
	v_pk_fma_f32 v[24:25], v[48:49], s[26:27], v[24:25] op_sel_hi:[1,0,1]
	v_pk_fma_f32 v[26:27], v[34:35], s[26:27], v[26:27] op_sel_hi:[1,0,1]
	v_pk_fma_f32 v[20:21], v[50:51], s[26:27], v[20:21] op_sel_hi:[1,0,1]
	v_pk_fma_f32 v[22:23], v[36:37], s[26:27], v[22:23] op_sel_hi:[1,0,1]
	v_pk_fma_f32 v[32:33], v[52:53], s[26:27], v[16:17] op_sel_hi:[1,0,1]
	v_pk_fma_f32 v[34:35], v[38:39], s[26:27], v[18:19] op_sel_hi:[1,0,1]
	v_cvt_pk_bf16_f32 v16, v28, v29
	v_cvt_pk_bf16_f32 v17, v30, v31
	v_cvt_pk_bf16_f32 v18, v24, v25
	v_cvt_pk_bf16_f32 v19, v26, v27
	v_cvt_pk_bf16_f32 v20, v20, v21
	v_cvt_pk_bf16_f32 v21, v22, v23
	v_cvt_pk_bf16_f32 v22, v32, v33
	v_cvt_pk_bf16_f32 v23, v34, v35
	global_store_dwordx4 v[42:43], v[16:19], off
	global_store_dwordx4 v[42:43], v[20:23], off offset:256
	global_load_dwordx4 v[16:19], v[44:45], off
	s_nop 0
	global_load_dwordx4 v[20:23], v[44:45], off offset:256
	v_lshl_add_u64 v[24:25], s[10:11], 0, v[40:41]
	s_waitcnt vmcnt(1)
	v_lshlrev_b32_e32 v26, 16, v16
	v_and_b32_e32 v27, 0xffff0000, v16
	v_lshlrev_b32_e32 v16, 16, v17
	v_and_b32_e32 v17, 0xffff0000, v17
	v_lshlrev_b32_e32 v28, 16, v18
	v_and_b32_e32 v29, 0xffff0000, v18
	v_lshlrev_b32_e32 v18, 16, v19
	v_and_b32_e32 v19, 0xffff0000, v19
	s_waitcnt vmcnt(0)
	v_lshlrev_b32_e32 v30, 16, v20
	v_and_b32_e32 v31, 0xffff0000, v20
	v_lshlrev_b32_e32 v20, 16, v21
	v_and_b32_e32 v21, 0xffff0000, v21
	v_lshlrev_b32_e32 v32, 16, v22
	v_and_b32_e32 v33, 0xffff0000, v22
	v_lshlrev_b32_e32 v22, 16, v23
	v_and_b32_e32 v23, 0xffff0000, v23
	v_pk_fma_f32 v[12:13], v[26:27], s[26:27], v[12:13] op_sel_hi:[1,0,1]
	v_pk_fma_f32 v[14:15], v[16:17], s[26:27], v[14:15] op_sel_hi:[1,0,1]
	v_pk_fma_f32 v[8:9], v[28:29], s[26:27], v[8:9] op_sel_hi:[1,0,1]
	v_pk_fma_f32 v[10:11], v[18:19], s[26:27], v[10:11] op_sel_hi:[1,0,1]
	v_pk_fma_f32 v[4:5], v[30:31], s[26:27], v[4:5] op_sel_hi:[1,0,1]
	v_pk_fma_f32 v[6:7], v[20:21], s[26:27], v[6:7] op_sel_hi:[1,0,1]
	v_pk_fma_f32 v[16:17], v[32:33], s[26:27], v[0:1] op_sel_hi:[1,0,1]
	v_pk_fma_f32 v[18:19], v[22:23], s[26:27], v[2:3] op_sel_hi:[1,0,1]
	v_cvt_pk_bf16_f32 v0, v12, v13
	v_cvt_pk_bf16_f32 v1, v14, v15
	v_cvt_pk_bf16_f32 v2, v8, v9
	v_cvt_pk_bf16_f32 v3, v10, v11
	v_cvt_pk_bf16_f32 v4, v4, v5
	v_cvt_pk_bf16_f32 v5, v6, v7
	v_cvt_pk_bf16_f32 v6, v16, v17
	v_cvt_pk_bf16_f32 v7, v18, v19
	global_store_dwordx4 v[24:25], v[0:3], off
	global_store_dwordx4 v[24:25], v[4:7], off offset:256
	s_and_b64 vcc, exec, s[0:1]
	s_mov_b64 s[0:1], -1
	s_cbranch_vccnz .LBB0_4289
.LBB0_4312:
	s_andn2_b64 vcc, exec, s[8:9]
	s_cbranch_vccnz .LBB0_4288
	s_branch .LBB0_4288
.LBB0_4314:
	s_waitcnt vmcnt(0)
	s_barrier
